# scan step maths in packed f32 (v_pk_mul/fma/add_f32, same per-component operations): hand-generated RWKV-7, mLSTM (both instances) and HGRN2 prompt step sections
# speedup vs baseline: 1.1732x; 1.0251x over previous
.LBB0_341:
	v_mov_b32_e32 v148, v80
	v_mov_b32_e32 v149, v81
	v_mov_b32_e32 v150, v82
	v_mov_b32_e32 v151, v83
	ds_read_b128 v[102:105], v134 offset:4096
	ds_read_b32 v122, v182 offset:20480
	ds_read_b32 v123, v182 offset:20544
	ds_read_b128 v[118:121], v134 offset:12288
	ds_read_b128 v[110:113], v134
	ds_read_b128 v[114:117], v134 offset:8192
	ds_read_b128 v[186:189], v134 offset:16384
	s_waitcnt lgkmcnt(6)
	v_pk_mul_f32 v[190:191], v[84:85], v[102:103]
	v_pk_mul_f32 v[192:193], v[148:149], v[102:103]
	v_pk_fma_f32 v[190:191], v[86:87], v[104:105], v[190:191]
	v_pk_fma_f32 v[192:193], v[150:151], v[104:105], v[192:193]
	v_add_f32_e32 v190, v190, v191
	v_add_f32_e32 v192, v192, v193
	ds_read_b128 v[106:109], v134 offset:4352
	v_add_f32_dpp v190, v190, v190 row_ror:8 row_mask:0xf bank_mask:0xf bound_ctrl:1
	v_add_f32_dpp v192, v192, v192 row_ror:8 row_mask:0xf bank_mask:0xf bound_ctrl:1
	s_waitcnt lgkmcnt(4)
	v_pk_mul_f32 v[194:195], v[122:123], v[118:119] op_sel_hi:[0,1]
	v_add_f32_dpp v190, v190, v190 row_ror:4 row_mask:0xf bank_mask:0xf bound_ctrl:1
	v_add_f32_dpp v192, v192, v192 row_ror:4 row_mask:0xf bank_mask:0xf bound_ctrl:1
	v_pk_mul_f32 v[196:197], v[122:123], v[120:121] op_sel_hi:[0,1]
	v_add_f32_dpp v190, v190, v190 row_ror:2 row_mask:0xf bank_mask:0xf bound_ctrl:1
	v_add_f32_dpp v192, v192, v192 row_ror:2 row_mask:0xf bank_mask:0xf bound_ctrl:1
	v_pk_mul_f32 v[198:199], v[122:123], v[118:119] op_sel:[1,0] op_sel_hi:[1,1]
	v_add_f32_dpp v190, v190, v190 row_ror:1 row_mask:0xf bank_mask:0xf bound_ctrl:1
	v_add_f32_dpp v192, v192, v192 row_ror:1 row_mask:0xf bank_mask:0xf bound_ctrl:1
	v_pk_mul_f32 v[152:153], v[122:123], v[120:121] op_sel:[1,0] op_sel_hi:[1,1]
	ds_read_b32 v122, v182 offset:20608
	ds_read_b32 v123, v182 offset:20672
	ds_read_b128 v[118:121], v134 offset:12544
	s_waitcnt lgkmcnt(5)
	v_pk_fma_f32 v[194:195], v[190:191], v[114:115], v[194:195] op_sel_hi:[0,1,1]
	v_pk_fma_f32 v[198:199], v[192:193], v[114:115], v[198:199] op_sel_hi:[0,1,1]
	v_pk_fma_f32 v[196:197], v[190:191], v[116:117], v[196:197] op_sel_hi:[0,1,1]
	v_pk_fma_f32 v[152:153], v[192:193], v[116:117], v[152:153] op_sel_hi:[0,1,1]
	v_pk_fma_f32 v[84:85], v[84:85], v[110:111], v[194:195]
	v_pk_fma_f32 v[148:149], v[148:149], v[110:111], v[198:199]
	v_pk_fma_f32 v[86:87], v[86:87], v[112:113], v[196:197]
	v_pk_fma_f32 v[150:151], v[150:151], v[112:113], v[152:153]
	ds_read_b128 v[110:113], v134 offset:256
	ds_read_b128 v[114:117], v134 offset:8448
	s_waitcnt lgkmcnt(6)
	v_pk_mul_f32 v[194:195], v[84:85], v[186:187]
	v_pk_mul_f32 v[196:197], v[148:149], v[186:187]
	v_pk_fma_f32 v[194:195], v[86:87], v[188:189], v[194:195]
	v_pk_fma_f32 v[196:197], v[150:151], v[188:189], v[196:197]
	v_add_f32_e32 v194, v194, v195
	v_add_f32_e32 v196, v196, v197
	ds_read_b128 v[186:189], v134 offset:16640
	v_add_f32_dpp v194, v194, v194 row_ror:8 row_mask:0xf bank_mask:0xf bound_ctrl:1
	v_add_f32_dpp v196, v196, v196 row_ror:8 row_mask:0xf bank_mask:0xf bound_ctrl:1
	s_waitcnt lgkmcnt(6)
	v_pk_mul_f32 v[190:191], v[84:85], v[106:107]
	v_pk_mul_f32 v[192:193], v[148:149], v[106:107]
	v_add_f32_dpp v194, v194, v194 row_ror:4 row_mask:0xf bank_mask:0xf bound_ctrl:1
	v_add_f32_dpp v196, v196, v196 row_ror:4 row_mask:0xf bank_mask:0xf bound_ctrl:1
	v_pk_fma_f32 v[190:191], v[86:87], v[108:109], v[190:191]
	v_pk_fma_f32 v[192:193], v[150:151], v[108:109], v[192:193]
	v_add_f32_dpp v194, v194, v194 row_ror:2 row_mask:0xf bank_mask:0xf bound_ctrl:1
	v_add_f32_dpp v196, v196, v196 row_ror:2 row_mask:0xf bank_mask:0xf bound_ctrl:1
	v_add_f32_e32 v190, v190, v191
	v_add_f32_dpp v194, v194, v194 row_ror:1 row_mask:0xf bank_mask:0xf bound_ctrl:1
	v_add_f32_dpp v196, v196, v196 row_ror:1 row_mask:0xf bank_mask:0xf bound_ctrl:1
	v_add_f32_e32 v192, v192, v193
	ds_write_b32 v182, v194 offset:45056
	ds_write_b32 v182, v196 offset:45120
	ds_read_b128 v[102:105], v134 offset:4608
	v_add_f32_dpp v190, v190, v190 row_ror:8 row_mask:0xf bank_mask:0xf bound_ctrl:1
	v_add_f32_dpp v192, v192, v192 row_ror:8 row_mask:0xf bank_mask:0xf bound_ctrl:1
	s_waitcnt lgkmcnt(6)
	v_pk_mul_f32 v[194:195], v[122:123], v[118:119] op_sel_hi:[0,1]
	v_add_f32_dpp v190, v190, v190 row_ror:4 row_mask:0xf bank_mask:0xf bound_ctrl:1
	v_add_f32_dpp v192, v192, v192 row_ror:4 row_mask:0xf bank_mask:0xf bound_ctrl:1
	v_pk_mul_f32 v[196:197], v[122:123], v[120:121] op_sel_hi:[0,1]
	v_add_f32_dpp v190, v190, v190 row_ror:2 row_mask:0xf bank_mask:0xf bound_ctrl:1
	v_add_f32_dpp v192, v192, v192 row_ror:2 row_mask:0xf bank_mask:0xf bound_ctrl:1
	v_pk_mul_f32 v[198:199], v[122:123], v[118:119] op_sel:[1,0] op_sel_hi:[1,1]
	v_add_f32_dpp v190, v190, v190 row_ror:1 row_mask:0xf bank_mask:0xf bound_ctrl:1
	v_add_f32_dpp v192, v192, v192 row_ror:1 row_mask:0xf bank_mask:0xf bound_ctrl:1
	v_pk_mul_f32 v[152:153], v[122:123], v[120:121] op_sel:[1,0] op_sel_hi:[1,1]
	ds_read_b32 v122, v182 offset:20736
	ds_read_b32 v123, v182 offset:20800
	ds_read_b128 v[118:121], v134 offset:12800
	s_waitcnt lgkmcnt(7)
	v_pk_fma_f32 v[194:195], v[190:191], v[114:115], v[194:195] op_sel_hi:[0,1,1]
	v_pk_fma_f32 v[198:199], v[192:193], v[114:115], v[198:199] op_sel_hi:[0,1,1]
	v_pk_fma_f32 v[196:197], v[190:191], v[116:117], v[196:197] op_sel_hi:[0,1,1]
	v_pk_fma_f32 v[152:153], v[192:193], v[116:117], v[152:153] op_sel_hi:[0,1,1]
	v_pk_fma_f32 v[84:85], v[84:85], v[110:111], v[194:195]
	v_pk_fma_f32 v[148:149], v[148:149], v[110:111], v[198:199]
	v_pk_fma_f32 v[86:87], v[86:87], v[112:113], v[196:197]
	v_pk_fma_f32 v[150:151], v[150:151], v[112:113], v[152:153]
	ds_read_b128 v[110:113], v134 offset:512
	ds_read_b128 v[114:117], v134 offset:8704
	s_waitcnt lgkmcnt(8)
	v_pk_mul_f32 v[194:195], v[84:85], v[186:187]
	v_pk_mul_f32 v[196:197], v[148:149], v[186:187]
	v_pk_fma_f32 v[194:195], v[86:87], v[188:189], v[194:195]
	v_pk_fma_f32 v[196:197], v[150:151], v[188:189], v[196:197]
	v_add_f32_e32 v194, v194, v195
	v_add_f32_e32 v196, v196, v197
	ds_read_b128 v[186:189], v134 offset:16896
	v_add_f32_dpp v194, v194, v194 row_ror:8 row_mask:0xf bank_mask:0xf bound_ctrl:1
	v_add_f32_dpp v196, v196, v196 row_ror:8 row_mask:0xf bank_mask:0xf bound_ctrl:1
	s_waitcnt lgkmcnt(6)
	v_pk_mul_f32 v[190:191], v[84:85], v[102:103]
	v_pk_mul_f32 v[192:193], v[148:149], v[102:103]
	v_add_f32_dpp v194, v194, v194 row_ror:4 row_mask:0xf bank_mask:0xf bound_ctrl:1
	v_add_f32_dpp v196, v196, v196 row_ror:4 row_mask:0xf bank_mask:0xf bound_ctrl:1
	v_pk_fma_f32 v[190:191], v[86:87], v[104:105], v[190:191]
	v_pk_fma_f32 v[192:193], v[150:151], v[104:105], v[192:193]
	v_add_f32_dpp v194, v194, v194 row_ror:2 row_mask:0xf bank_mask:0xf bound_ctrl:1
	v_add_f32_dpp v196, v196, v196 row_ror:2 row_mask:0xf bank_mask:0xf bound_ctrl:1
	v_add_f32_e32 v190, v190, v191
	v_add_f32_dpp v194, v194, v194 row_ror:1 row_mask:0xf bank_mask:0xf bound_ctrl:1
	v_add_f32_dpp v196, v196, v196 row_ror:1 row_mask:0xf bank_mask:0xf bound_ctrl:1
	v_add_f32_e32 v192, v192, v193
	ds_write_b32 v182, v194 offset:45184
	ds_write_b32 v182, v196 offset:45248
	ds_read_b128 v[106:109], v134 offset:4864
	v_add_f32_dpp v190, v190, v190 row_ror:8 row_mask:0xf bank_mask:0xf bound_ctrl:1
	v_add_f32_dpp v192, v192, v192 row_ror:8 row_mask:0xf bank_mask:0xf bound_ctrl:1
	s_waitcnt lgkmcnt(6)
	v_pk_mul_f32 v[194:195], v[122:123], v[118:119] op_sel_hi:[0,1]
	v_add_f32_dpp v190, v190, v190 row_ror:4 row_mask:0xf bank_mask:0xf bound_ctrl:1
	v_add_f32_dpp v192, v192, v192 row_ror:4 row_mask:0xf bank_mask:0xf bound_ctrl:1
	v_pk_mul_f32 v[196:197], v[122:123], v[120:121] op_sel_hi:[0,1]
	v_add_f32_dpp v190, v190, v190 row_ror:2 row_mask:0xf bank_mask:0xf bound_ctrl:1
	v_add_f32_dpp v192, v192, v192 row_ror:2 row_mask:0xf bank_mask:0xf bound_ctrl:1
	v_pk_mul_f32 v[198:199], v[122:123], v[118:119] op_sel:[1,0] op_sel_hi:[1,1]
	v_add_f32_dpp v190, v190, v190 row_ror:1 row_mask:0xf bank_mask:0xf bound_ctrl:1
	v_add_f32_dpp v192, v192, v192 row_ror:1 row_mask:0xf bank_mask:0xf bound_ctrl:1
	v_pk_mul_f32 v[152:153], v[122:123], v[120:121] op_sel:[1,0] op_sel_hi:[1,1]
	ds_read_b32 v122, v182 offset:20864
	ds_read_b32 v123, v182 offset:20928
	ds_read_b128 v[118:121], v134 offset:13056
	s_waitcnt lgkmcnt(7)
	v_pk_fma_f32 v[194:195], v[190:191], v[114:115], v[194:195] op_sel_hi:[0,1,1]
	v_pk_fma_f32 v[198:199], v[192:193], v[114:115], v[198:199] op_sel_hi:[0,1,1]
	v_pk_fma_f32 v[196:197], v[190:191], v[116:117], v[196:197] op_sel_hi:[0,1,1]
	v_pk_fma_f32 v[152:153], v[192:193], v[116:117], v[152:153] op_sel_hi:[0,1,1]
	v_pk_fma_f32 v[84:85], v[84:85], v[110:111], v[194:195]
	v_pk_fma_f32 v[148:149], v[148:149], v[110:111], v[198:199]
	v_pk_fma_f32 v[86:87], v[86:87], v[112:113], v[196:197]
	v_pk_fma_f32 v[150:151], v[150:151], v[112:113], v[152:153]
	ds_read_b128 v[110:113], v134 offset:768
	ds_read_b128 v[114:117], v134 offset:8960
	s_waitcnt lgkmcnt(8)
	v_pk_mul_f32 v[194:195], v[84:85], v[186:187]
	v_pk_mul_f32 v[196:197], v[148:149], v[186:187]
	v_pk_fma_f32 v[194:195], v[86:87], v[188:189], v[194:195]
	v_pk_fma_f32 v[196:197], v[150:151], v[188:189], v[196:197]
	v_add_f32_e32 v194, v194, v195
	v_add_f32_e32 v196, v196, v197
	ds_read_b128 v[186:189], v134 offset:17152
	v_add_f32_dpp v194, v194, v194 row_ror:8 row_mask:0xf bank_mask:0xf bound_ctrl:1
	v_add_f32_dpp v196, v196, v196 row_ror:8 row_mask:0xf bank_mask:0xf bound_ctrl:1
	s_waitcnt lgkmcnt(6)
	v_pk_mul_f32 v[190:191], v[84:85], v[106:107]
	v_pk_mul_f32 v[192:193], v[148:149], v[106:107]
	v_add_f32_dpp v194, v194, v194 row_ror:4 row_mask:0xf bank_mask:0xf bound_ctrl:1
	v_add_f32_dpp v196, v196, v196 row_ror:4 row_mask:0xf bank_mask:0xf bound_ctrl:1
	v_pk_fma_f32 v[190:191], v[86:87], v[108:109], v[190:191]
	v_pk_fma_f32 v[192:193], v[150:151], v[108:109], v[192:193]
	v_add_f32_dpp v194, v194, v194 row_ror:2 row_mask:0xf bank_mask:0xf bound_ctrl:1
	v_add_f32_dpp v196, v196, v196 row_ror:2 row_mask:0xf bank_mask:0xf bound_ctrl:1
	v_add_f32_e32 v190, v190, v191
	v_add_f32_dpp v194, v194, v194 row_ror:1 row_mask:0xf bank_mask:0xf bound_ctrl:1
	v_add_f32_dpp v196, v196, v196 row_ror:1 row_mask:0xf bank_mask:0xf bound_ctrl:1
	v_add_f32_e32 v192, v192, v193
	ds_write_b32 v182, v194 offset:45312
	ds_write_b32 v182, v196 offset:45376
	ds_read_b128 v[102:105], v134 offset:5120
	v_add_f32_dpp v190, v190, v190 row_ror:8 row_mask:0xf bank_mask:0xf bound_ctrl:1
	v_add_f32_dpp v192, v192, v192 row_ror:8 row_mask:0xf bank_mask:0xf bound_ctrl:1
	s_waitcnt lgkmcnt(6)
	v_pk_mul_f32 v[194:195], v[122:123], v[118:119] op_sel_hi:[0,1]
	v_add_f32_dpp v190, v190, v190 row_ror:4 row_mask:0xf bank_mask:0xf bound_ctrl:1
	v_add_f32_dpp v192, v192, v192 row_ror:4 row_mask:0xf bank_mask:0xf bound_ctrl:1
	v_pk_mul_f32 v[196:197], v[122:123], v[120:121] op_sel_hi:[0,1]
	v_add_f32_dpp v190, v190, v190 row_ror:2 row_mask:0xf bank_mask:0xf bound_ctrl:1
	v_add_f32_dpp v192, v192, v192 row_ror:2 row_mask:0xf bank_mask:0xf bound_ctrl:1
	v_pk_mul_f32 v[198:199], v[122:123], v[118:119] op_sel:[1,0] op_sel_hi:[1,1]
	v_add_f32_dpp v190, v190, v190 row_ror:1 row_mask:0xf bank_mask:0xf bound_ctrl:1
	v_add_f32_dpp v192, v192, v192 row_ror:1 row_mask:0xf bank_mask:0xf bound_ctrl:1
	v_pk_mul_f32 v[152:153], v[122:123], v[120:121] op_sel:[1,0] op_sel_hi:[1,1]
	ds_read_b32 v122, v182 offset:20992
	ds_read_b32 v123, v182 offset:21056
	ds_read_b128 v[118:121], v134 offset:13312
	s_waitcnt lgkmcnt(7)
	v_pk_fma_f32 v[194:195], v[190:191], v[114:115], v[194:195] op_sel_hi:[0,1,1]
	v_pk_fma_f32 v[198:199], v[192:193], v[114:115], v[198:199] op_sel_hi:[0,1,1]
	v_pk_fma_f32 v[196:197], v[190:191], v[116:117], v[196:197] op_sel_hi:[0,1,1]
	v_pk_fma_f32 v[152:153], v[192:193], v[116:117], v[152:153] op_sel_hi:[0,1,1]
	v_pk_fma_f32 v[84:85], v[84:85], v[110:111], v[194:195]
	v_pk_fma_f32 v[148:149], v[148:149], v[110:111], v[198:199]
	v_pk_fma_f32 v[86:87], v[86:87], v[112:113], v[196:197]
	v_pk_fma_f32 v[150:151], v[150:151], v[112:113], v[152:153]
	ds_read_b128 v[110:113], v134 offset:1024
	ds_read_b128 v[114:117], v134 offset:9216
	s_waitcnt lgkmcnt(8)
	v_pk_mul_f32 v[194:195], v[84:85], v[186:187]
	v_pk_mul_f32 v[196:197], v[148:149], v[186:187]
	v_pk_fma_f32 v[194:195], v[86:87], v[188:189], v[194:195]
	v_pk_fma_f32 v[196:197], v[150:151], v[188:189], v[196:197]
	v_add_f32_e32 v194, v194, v195
	v_add_f32_e32 v196, v196, v197
	ds_read_b128 v[186:189], v134 offset:17408
	v_add_f32_dpp v194, v194, v194 row_ror:8 row_mask:0xf bank_mask:0xf bound_ctrl:1
	v_add_f32_dpp v196, v196, v196 row_ror:8 row_mask:0xf bank_mask:0xf bound_ctrl:1
	s_waitcnt lgkmcnt(6)
	v_pk_mul_f32 v[190:191], v[84:85], v[102:103]
	v_pk_mul_f32 v[192:193], v[148:149], v[102:103]
	v_add_f32_dpp v194, v194, v194 row_ror:4 row_mask:0xf bank_mask:0xf bound_ctrl:1
	v_add_f32_dpp v196, v196, v196 row_ror:4 row_mask:0xf bank_mask:0xf bound_ctrl:1
	v_pk_fma_f32 v[190:191], v[86:87], v[104:105], v[190:191]
	v_pk_fma_f32 v[192:193], v[150:151], v[104:105], v[192:193]
	v_add_f32_dpp v194, v194, v194 row_ror:2 row_mask:0xf bank_mask:0xf bound_ctrl:1
	v_add_f32_dpp v196, v196, v196 row_ror:2 row_mask:0xf bank_mask:0xf bound_ctrl:1
	v_add_f32_e32 v190, v190, v191
	v_add_f32_dpp v194, v194, v194 row_ror:1 row_mask:0xf bank_mask:0xf bound_ctrl:1
	v_add_f32_dpp v196, v196, v196 row_ror:1 row_mask:0xf bank_mask:0xf bound_ctrl:1
	v_add_f32_e32 v192, v192, v193
	ds_write_b32 v182, v194 offset:45440
	ds_write_b32 v182, v196 offset:45504
	ds_read_b128 v[106:109], v134 offset:5376
	v_add_f32_dpp v190, v190, v190 row_ror:8 row_mask:0xf bank_mask:0xf bound_ctrl:1
	v_add_f32_dpp v192, v192, v192 row_ror:8 row_mask:0xf bank_mask:0xf bound_ctrl:1
	s_waitcnt lgkmcnt(6)
	v_pk_mul_f32 v[194:195], v[122:123], v[118:119] op_sel_hi:[0,1]
	v_add_f32_dpp v190, v190, v190 row_ror:4 row_mask:0xf bank_mask:0xf bound_ctrl:1
	v_add_f32_dpp v192, v192, v192 row_ror:4 row_mask:0xf bank_mask:0xf bound_ctrl:1
	v_pk_mul_f32 v[196:197], v[122:123], v[120:121] op_sel_hi:[0,1]
	v_add_f32_dpp v190, v190, v190 row_ror:2 row_mask:0xf bank_mask:0xf bound_ctrl:1
	v_add_f32_dpp v192, v192, v192 row_ror:2 row_mask:0xf bank_mask:0xf bound_ctrl:1
	v_pk_mul_f32 v[198:199], v[122:123], v[118:119] op_sel:[1,0] op_sel_hi:[1,1]
	v_add_f32_dpp v190, v190, v190 row_ror:1 row_mask:0xf bank_mask:0xf bound_ctrl:1
	v_add_f32_dpp v192, v192, v192 row_ror:1 row_mask:0xf bank_mask:0xf bound_ctrl:1
	v_pk_mul_f32 v[152:153], v[122:123], v[120:121] op_sel:[1,0] op_sel_hi:[1,1]
	ds_read_b32 v122, v182 offset:21120
	ds_read_b32 v123, v182 offset:21184
	ds_read_b128 v[118:121], v134 offset:13568
	s_waitcnt lgkmcnt(7)
	v_pk_fma_f32 v[194:195], v[190:191], v[114:115], v[194:195] op_sel_hi:[0,1,1]
	v_pk_fma_f32 v[198:199], v[192:193], v[114:115], v[198:199] op_sel_hi:[0,1,1]
	v_pk_fma_f32 v[196:197], v[190:191], v[116:117], v[196:197] op_sel_hi:[0,1,1]
	v_pk_fma_f32 v[152:153], v[192:193], v[116:117], v[152:153] op_sel_hi:[0,1,1]
	v_pk_fma_f32 v[84:85], v[84:85], v[110:111], v[194:195]
	v_pk_fma_f32 v[148:149], v[148:149], v[110:111], v[198:199]
	v_pk_fma_f32 v[86:87], v[86:87], v[112:113], v[196:197]
	v_pk_fma_f32 v[150:151], v[150:151], v[112:113], v[152:153]
	ds_read_b128 v[110:113], v134 offset:1280
	ds_read_b128 v[114:117], v134 offset:9472
	s_waitcnt lgkmcnt(8)
	v_pk_mul_f32 v[194:195], v[84:85], v[186:187]
	v_pk_mul_f32 v[196:197], v[148:149], v[186:187]
	v_pk_fma_f32 v[194:195], v[86:87], v[188:189], v[194:195]
	v_pk_fma_f32 v[196:197], v[150:151], v[188:189], v[196:197]
	v_add_f32_e32 v194, v194, v195
	v_add_f32_e32 v196, v196, v197
	ds_read_b128 v[186:189], v134 offset:17664
	v_add_f32_dpp v194, v194, v194 row_ror:8 row_mask:0xf bank_mask:0xf bound_ctrl:1
	v_add_f32_dpp v196, v196, v196 row_ror:8 row_mask:0xf bank_mask:0xf bound_ctrl:1
	s_waitcnt lgkmcnt(6)
	v_pk_mul_f32 v[190:191], v[84:85], v[106:107]
	v_pk_mul_f32 v[192:193], v[148:149], v[106:107]
	v_add_f32_dpp v194, v194, v194 row_ror:4 row_mask:0xf bank_mask:0xf bound_ctrl:1
	v_add_f32_dpp v196, v196, v196 row_ror:4 row_mask:0xf bank_mask:0xf bound_ctrl:1
	v_pk_fma_f32 v[190:191], v[86:87], v[108:109], v[190:191]
	v_pk_fma_f32 v[192:193], v[150:151], v[108:109], v[192:193]
	v_add_f32_dpp v194, v194, v194 row_ror:2 row_mask:0xf bank_mask:0xf bound_ctrl:1
	v_add_f32_dpp v196, v196, v196 row_ror:2 row_mask:0xf bank_mask:0xf bound_ctrl:1
	v_add_f32_e32 v190, v190, v191
	v_add_f32_dpp v194, v194, v194 row_ror:1 row_mask:0xf bank_mask:0xf bound_ctrl:1
	v_add_f32_dpp v196, v196, v196 row_ror:1 row_mask:0xf bank_mask:0xf bound_ctrl:1
	v_add_f32_e32 v192, v192, v193
	ds_write_b32 v182, v194 offset:45568
	ds_write_b32 v182, v196 offset:45632
	ds_read_b128 v[102:105], v134 offset:5632
	v_add_f32_dpp v190, v190, v190 row_ror:8 row_mask:0xf bank_mask:0xf bound_ctrl:1
	v_add_f32_dpp v192, v192, v192 row_ror:8 row_mask:0xf bank_mask:0xf bound_ctrl:1
	s_waitcnt lgkmcnt(6)
	v_pk_mul_f32 v[194:195], v[122:123], v[118:119] op_sel_hi:[0,1]
	v_add_f32_dpp v190, v190, v190 row_ror:4 row_mask:0xf bank_mask:0xf bound_ctrl:1
	v_add_f32_dpp v192, v192, v192 row_ror:4 row_mask:0xf bank_mask:0xf bound_ctrl:1
	v_pk_mul_f32 v[196:197], v[122:123], v[120:121] op_sel_hi:[0,1]
	v_add_f32_dpp v190, v190, v190 row_ror:2 row_mask:0xf bank_mask:0xf bound_ctrl:1
	v_add_f32_dpp v192, v192, v192 row_ror:2 row_mask:0xf bank_mask:0xf bound_ctrl:1
	v_pk_mul_f32 v[198:199], v[122:123], v[118:119] op_sel:[1,0] op_sel_hi:[1,1]
	v_add_f32_dpp v190, v190, v190 row_ror:1 row_mask:0xf bank_mask:0xf bound_ctrl:1
	v_add_f32_dpp v192, v192, v192 row_ror:1 row_mask:0xf bank_mask:0xf bound_ctrl:1
	v_pk_mul_f32 v[152:153], v[122:123], v[120:121] op_sel:[1,0] op_sel_hi:[1,1]
	ds_read_b32 v122, v182 offset:21248
	ds_read_b32 v123, v182 offset:21312
	ds_read_b128 v[118:121], v134 offset:13824
	s_waitcnt lgkmcnt(7)
	v_pk_fma_f32 v[194:195], v[190:191], v[114:115], v[194:195] op_sel_hi:[0,1,1]
	v_pk_fma_f32 v[198:199], v[192:193], v[114:115], v[198:199] op_sel_hi:[0,1,1]
	v_pk_fma_f32 v[196:197], v[190:191], v[116:117], v[196:197] op_sel_hi:[0,1,1]
	v_pk_fma_f32 v[152:153], v[192:193], v[116:117], v[152:153] op_sel_hi:[0,1,1]
	v_pk_fma_f32 v[84:85], v[84:85], v[110:111], v[194:195]
	v_pk_fma_f32 v[148:149], v[148:149], v[110:111], v[198:199]
	v_pk_fma_f32 v[86:87], v[86:87], v[112:113], v[196:197]
	v_pk_fma_f32 v[150:151], v[150:151], v[112:113], v[152:153]
	ds_read_b128 v[110:113], v134 offset:1536
	ds_read_b128 v[114:117], v134 offset:9728
	s_waitcnt lgkmcnt(8)
	v_pk_mul_f32 v[194:195], v[84:85], v[186:187]
	v_pk_mul_f32 v[196:197], v[148:149], v[186:187]
	v_pk_fma_f32 v[194:195], v[86:87], v[188:189], v[194:195]
	v_pk_fma_f32 v[196:197], v[150:151], v[188:189], v[196:197]
	v_add_f32_e32 v194, v194, v195
	v_add_f32_e32 v196, v196, v197
	ds_read_b128 v[186:189], v134 offset:17920
	v_add_f32_dpp v194, v194, v194 row_ror:8 row_mask:0xf bank_mask:0xf bound_ctrl:1
	v_add_f32_dpp v196, v196, v196 row_ror:8 row_mask:0xf bank_mask:0xf bound_ctrl:1
	s_waitcnt lgkmcnt(6)
	v_pk_mul_f32 v[190:191], v[84:85], v[102:103]
	v_pk_mul_f32 v[192:193], v[148:149], v[102:103]
	v_add_f32_dpp v194, v194, v194 row_ror:4 row_mask:0xf bank_mask:0xf bound_ctrl:1
	v_add_f32_dpp v196, v196, v196 row_ror:4 row_mask:0xf bank_mask:0xf bound_ctrl:1
	v_pk_fma_f32 v[190:191], v[86:87], v[104:105], v[190:191]
	v_pk_fma_f32 v[192:193], v[150:151], v[104:105], v[192:193]
	v_add_f32_dpp v194, v194, v194 row_ror:2 row_mask:0xf bank_mask:0xf bound_ctrl:1
	v_add_f32_dpp v196, v196, v196 row_ror:2 row_mask:0xf bank_mask:0xf bound_ctrl:1
	v_add_f32_e32 v190, v190, v191
	v_add_f32_dpp v194, v194, v194 row_ror:1 row_mask:0xf bank_mask:0xf bound_ctrl:1
	v_add_f32_dpp v196, v196, v196 row_ror:1 row_mask:0xf bank_mask:0xf bound_ctrl:1
	v_add_f32_e32 v192, v192, v193
	ds_write_b32 v182, v194 offset:45696
	ds_write_b32 v182, v196 offset:45760
	ds_read_b128 v[106:109], v134 offset:5888
	v_add_f32_dpp v190, v190, v190 row_ror:8 row_mask:0xf bank_mask:0xf bound_ctrl:1
	v_add_f32_dpp v192, v192, v192 row_ror:8 row_mask:0xf bank_mask:0xf bound_ctrl:1
	s_waitcnt lgkmcnt(6)
	v_pk_mul_f32 v[194:195], v[122:123], v[118:119] op_sel_hi:[0,1]
	v_add_f32_dpp v190, v190, v190 row_ror:4 row_mask:0xf bank_mask:0xf bound_ctrl:1
	v_add_f32_dpp v192, v192, v192 row_ror:4 row_mask:0xf bank_mask:0xf bound_ctrl:1
	v_pk_mul_f32 v[196:197], v[122:123], v[120:121] op_sel_hi:[0,1]
	v_add_f32_dpp v190, v190, v190 row_ror:2 row_mask:0xf bank_mask:0xf bound_ctrl:1
	v_add_f32_dpp v192, v192, v192 row_ror:2 row_mask:0xf bank_mask:0xf bound_ctrl:1
	v_pk_mul_f32 v[198:199], v[122:123], v[118:119] op_sel:[1,0] op_sel_hi:[1,1]
	v_add_f32_dpp v190, v190, v190 row_ror:1 row_mask:0xf bank_mask:0xf bound_ctrl:1
	v_add_f32_dpp v192, v192, v192 row_ror:1 row_mask:0xf bank_mask:0xf bound_ctrl:1
	v_pk_mul_f32 v[152:153], v[122:123], v[120:121] op_sel:[1,0] op_sel_hi:[1,1]
	ds_read_b32 v122, v182 offset:21376
	ds_read_b32 v123, v182 offset:21440
	ds_read_b128 v[118:121], v134 offset:14080
	s_waitcnt lgkmcnt(7)
	v_pk_fma_f32 v[194:195], v[190:191], v[114:115], v[194:195] op_sel_hi:[0,1,1]
	v_pk_fma_f32 v[198:199], v[192:193], v[114:115], v[198:199] op_sel_hi:[0,1,1]
	v_pk_fma_f32 v[196:197], v[190:191], v[116:117], v[196:197] op_sel_hi:[0,1,1]
	v_pk_fma_f32 v[152:153], v[192:193], v[116:117], v[152:153] op_sel_hi:[0,1,1]
	v_pk_fma_f32 v[84:85], v[84:85], v[110:111], v[194:195]
	v_pk_fma_f32 v[148:149], v[148:149], v[110:111], v[198:199]
	v_pk_fma_f32 v[86:87], v[86:87], v[112:113], v[196:197]
	v_pk_fma_f32 v[150:151], v[150:151], v[112:113], v[152:153]
	ds_read_b128 v[110:113], v134 offset:1792
	ds_read_b128 v[114:117], v134 offset:9984
	s_waitcnt lgkmcnt(8)
	v_pk_mul_f32 v[194:195], v[84:85], v[186:187]
	v_pk_mul_f32 v[196:197], v[148:149], v[186:187]
	v_pk_fma_f32 v[194:195], v[86:87], v[188:189], v[194:195]
	v_pk_fma_f32 v[196:197], v[150:151], v[188:189], v[196:197]
	v_add_f32_e32 v194, v194, v195
	v_add_f32_e32 v196, v196, v197
	ds_read_b128 v[186:189], v134 offset:18176
	v_add_f32_dpp v194, v194, v194 row_ror:8 row_mask:0xf bank_mask:0xf bound_ctrl:1
	v_add_f32_dpp v196, v196, v196 row_ror:8 row_mask:0xf bank_mask:0xf bound_ctrl:1
	s_waitcnt lgkmcnt(6)
	v_pk_mul_f32 v[190:191], v[84:85], v[106:107]
	v_pk_mul_f32 v[192:193], v[148:149], v[106:107]
	v_add_f32_dpp v194, v194, v194 row_ror:4 row_mask:0xf bank_mask:0xf bound_ctrl:1
	v_add_f32_dpp v196, v196, v196 row_ror:4 row_mask:0xf bank_mask:0xf bound_ctrl:1
	v_pk_fma_f32 v[190:191], v[86:87], v[108:109], v[190:191]
	v_pk_fma_f32 v[192:193], v[150:151], v[108:109], v[192:193]
	v_add_f32_dpp v194, v194, v194 row_ror:2 row_mask:0xf bank_mask:0xf bound_ctrl:1
	v_add_f32_dpp v196, v196, v196 row_ror:2 row_mask:0xf bank_mask:0xf bound_ctrl:1
	v_add_f32_e32 v190, v190, v191
	v_add_f32_dpp v194, v194, v194 row_ror:1 row_mask:0xf bank_mask:0xf bound_ctrl:1
	v_add_f32_dpp v196, v196, v196 row_ror:1 row_mask:0xf bank_mask:0xf bound_ctrl:1
	v_add_f32_e32 v192, v192, v193
	ds_write_b32 v182, v194 offset:45824
	ds_write_b32 v182, v196 offset:45888
	ds_read_b128 v[102:105], v134 offset:6144
	v_add_f32_dpp v190, v190, v190 row_ror:8 row_mask:0xf bank_mask:0xf bound_ctrl:1
	v_add_f32_dpp v192, v192, v192 row_ror:8 row_mask:0xf bank_mask:0xf bound_ctrl:1
	s_waitcnt lgkmcnt(6)
	v_pk_mul_f32 v[194:195], v[122:123], v[118:119] op_sel_hi:[0,1]
	v_add_f32_dpp v190, v190, v190 row_ror:4 row_mask:0xf bank_mask:0xf bound_ctrl:1
	v_add_f32_dpp v192, v192, v192 row_ror:4 row_mask:0xf bank_mask:0xf bound_ctrl:1
	v_pk_mul_f32 v[196:197], v[122:123], v[120:121] op_sel_hi:[0,1]
	v_add_f32_dpp v190, v190, v190 row_ror:2 row_mask:0xf bank_mask:0xf bound_ctrl:1
	v_add_f32_dpp v192, v192, v192 row_ror:2 row_mask:0xf bank_mask:0xf bound_ctrl:1
	v_pk_mul_f32 v[198:199], v[122:123], v[118:119] op_sel:[1,0] op_sel_hi:[1,1]
	v_add_f32_dpp v190, v190, v190 row_ror:1 row_mask:0xf bank_mask:0xf bound_ctrl:1
	v_add_f32_dpp v192, v192, v192 row_ror:1 row_mask:0xf bank_mask:0xf bound_ctrl:1
	v_pk_mul_f32 v[152:153], v[122:123], v[120:121] op_sel:[1,0] op_sel_hi:[1,1]
	ds_read_b32 v122, v182 offset:21504
	ds_read_b32 v123, v182 offset:21568
	ds_read_b128 v[118:121], v134 offset:14336
	s_waitcnt lgkmcnt(7)
	v_pk_fma_f32 v[194:195], v[190:191], v[114:115], v[194:195] op_sel_hi:[0,1,1]
	v_pk_fma_f32 v[198:199], v[192:193], v[114:115], v[198:199] op_sel_hi:[0,1,1]
	v_pk_fma_f32 v[196:197], v[190:191], v[116:117], v[196:197] op_sel_hi:[0,1,1]
	v_pk_fma_f32 v[152:153], v[192:193], v[116:117], v[152:153] op_sel_hi:[0,1,1]
	v_pk_fma_f32 v[84:85], v[84:85], v[110:111], v[194:195]
	v_pk_fma_f32 v[148:149], v[148:149], v[110:111], v[198:199]
	v_pk_fma_f32 v[86:87], v[86:87], v[112:113], v[196:197]
	v_pk_fma_f32 v[150:151], v[150:151], v[112:113], v[152:153]
	ds_read_b128 v[110:113], v134 offset:2048
	ds_read_b128 v[114:117], v134 offset:10240
	s_waitcnt lgkmcnt(8)
	v_pk_mul_f32 v[194:195], v[84:85], v[186:187]
	v_pk_mul_f32 v[196:197], v[148:149], v[186:187]
	v_pk_fma_f32 v[194:195], v[86:87], v[188:189], v[194:195]
	v_pk_fma_f32 v[196:197], v[150:151], v[188:189], v[196:197]
	v_add_f32_e32 v194, v194, v195
	v_add_f32_e32 v196, v196, v197
	ds_read_b128 v[186:189], v134 offset:18432
	v_add_f32_dpp v194, v194, v194 row_ror:8 row_mask:0xf bank_mask:0xf bound_ctrl:1
	v_add_f32_dpp v196, v196, v196 row_ror:8 row_mask:0xf bank_mask:0xf bound_ctrl:1
	s_waitcnt lgkmcnt(6)
	v_pk_mul_f32 v[190:191], v[84:85], v[102:103]
	v_pk_mul_f32 v[192:193], v[148:149], v[102:103]
	v_add_f32_dpp v194, v194, v194 row_ror:4 row_mask:0xf bank_mask:0xf bound_ctrl:1
	v_add_f32_dpp v196, v196, v196 row_ror:4 row_mask:0xf bank_mask:0xf bound_ctrl:1
	v_pk_fma_f32 v[190:191], v[86:87], v[104:105], v[190:191]
	v_pk_fma_f32 v[192:193], v[150:151], v[104:105], v[192:193]
	v_add_f32_dpp v194, v194, v194 row_ror:2 row_mask:0xf bank_mask:0xf bound_ctrl:1
	v_add_f32_dpp v196, v196, v196 row_ror:2 row_mask:0xf bank_mask:0xf bound_ctrl:1
	v_add_f32_e32 v190, v190, v191
	v_add_f32_dpp v194, v194, v194 row_ror:1 row_mask:0xf bank_mask:0xf bound_ctrl:1
	v_add_f32_dpp v196, v196, v196 row_ror:1 row_mask:0xf bank_mask:0xf bound_ctrl:1
	v_add_f32_e32 v192, v192, v193
	ds_write_b32 v182, v194 offset:45952
	ds_write_b32 v182, v196 offset:46016
	ds_read_b128 v[106:109], v134 offset:6400
	v_add_f32_dpp v190, v190, v190 row_ror:8 row_mask:0xf bank_mask:0xf bound_ctrl:1
	v_add_f32_dpp v192, v192, v192 row_ror:8 row_mask:0xf bank_mask:0xf bound_ctrl:1
	s_waitcnt lgkmcnt(6)
	v_pk_mul_f32 v[194:195], v[122:123], v[118:119] op_sel_hi:[0,1]
	v_add_f32_dpp v190, v190, v190 row_ror:4 row_mask:0xf bank_mask:0xf bound_ctrl:1
	v_add_f32_dpp v192, v192, v192 row_ror:4 row_mask:0xf bank_mask:0xf bound_ctrl:1
	v_pk_mul_f32 v[196:197], v[122:123], v[120:121] op_sel_hi:[0,1]
	v_add_f32_dpp v190, v190, v190 row_ror:2 row_mask:0xf bank_mask:0xf bound_ctrl:1
	v_add_f32_dpp v192, v192, v192 row_ror:2 row_mask:0xf bank_mask:0xf bound_ctrl:1
	v_pk_mul_f32 v[198:199], v[122:123], v[118:119] op_sel:[1,0] op_sel_hi:[1,1]
	v_add_f32_dpp v190, v190, v190 row_ror:1 row_mask:0xf bank_mask:0xf bound_ctrl:1
	v_add_f32_dpp v192, v192, v192 row_ror:1 row_mask:0xf bank_mask:0xf bound_ctrl:1
	v_pk_mul_f32 v[152:153], v[122:123], v[120:121] op_sel:[1,0] op_sel_hi:[1,1]
	ds_read_b32 v122, v182 offset:21632
	ds_read_b32 v123, v182 offset:21696
	ds_read_b128 v[118:121], v134 offset:14592
	s_waitcnt lgkmcnt(7)
	v_pk_fma_f32 v[194:195], v[190:191], v[114:115], v[194:195] op_sel_hi:[0,1,1]
	v_pk_fma_f32 v[198:199], v[192:193], v[114:115], v[198:199] op_sel_hi:[0,1,1]
	v_pk_fma_f32 v[196:197], v[190:191], v[116:117], v[196:197] op_sel_hi:[0,1,1]
	v_pk_fma_f32 v[152:153], v[192:193], v[116:117], v[152:153] op_sel_hi:[0,1,1]
	v_pk_fma_f32 v[84:85], v[84:85], v[110:111], v[194:195]
	v_pk_fma_f32 v[148:149], v[148:149], v[110:111], v[198:199]
	v_pk_fma_f32 v[86:87], v[86:87], v[112:113], v[196:197]
	v_pk_fma_f32 v[150:151], v[150:151], v[112:113], v[152:153]
	ds_read_b128 v[110:113], v134 offset:2304
	ds_read_b128 v[114:117], v134 offset:10496
	s_waitcnt lgkmcnt(8)
	v_pk_mul_f32 v[194:195], v[84:85], v[186:187]
	v_pk_mul_f32 v[196:197], v[148:149], v[186:187]
	v_pk_fma_f32 v[194:195], v[86:87], v[188:189], v[194:195]
	v_pk_fma_f32 v[196:197], v[150:151], v[188:189], v[196:197]
	v_add_f32_e32 v194, v194, v195
	v_add_f32_e32 v196, v196, v197
	ds_read_b128 v[186:189], v134 offset:18688
	v_add_f32_dpp v194, v194, v194 row_ror:8 row_mask:0xf bank_mask:0xf bound_ctrl:1
	v_add_f32_dpp v196, v196, v196 row_ror:8 row_mask:0xf bank_mask:0xf bound_ctrl:1
	s_waitcnt lgkmcnt(6)
	v_pk_mul_f32 v[190:191], v[84:85], v[106:107]
	v_pk_mul_f32 v[192:193], v[148:149], v[106:107]
	v_add_f32_dpp v194, v194, v194 row_ror:4 row_mask:0xf bank_mask:0xf bound_ctrl:1
	v_add_f32_dpp v196, v196, v196 row_ror:4 row_mask:0xf bank_mask:0xf bound_ctrl:1
	v_pk_fma_f32 v[190:191], v[86:87], v[108:109], v[190:191]
	v_pk_fma_f32 v[192:193], v[150:151], v[108:109], v[192:193]
	v_add_f32_dpp v194, v194, v194 row_ror:2 row_mask:0xf bank_mask:0xf bound_ctrl:1
	v_add_f32_dpp v196, v196, v196 row_ror:2 row_mask:0xf bank_mask:0xf bound_ctrl:1
	v_add_f32_e32 v190, v190, v191
	v_add_f32_dpp v194, v194, v194 row_ror:1 row_mask:0xf bank_mask:0xf bound_ctrl:1
	v_add_f32_dpp v196, v196, v196 row_ror:1 row_mask:0xf bank_mask:0xf bound_ctrl:1
	v_add_f32_e32 v192, v192, v193
	ds_write_b32 v182, v194 offset:46080
	ds_write_b32 v182, v196 offset:46144
	ds_read_b128 v[102:105], v134 offset:6656
	v_add_f32_dpp v190, v190, v190 row_ror:8 row_mask:0xf bank_mask:0xf bound_ctrl:1
	v_add_f32_dpp v192, v192, v192 row_ror:8 row_mask:0xf bank_mask:0xf bound_ctrl:1
	s_waitcnt lgkmcnt(6)
	v_pk_mul_f32 v[194:195], v[122:123], v[118:119] op_sel_hi:[0,1]
	v_add_f32_dpp v190, v190, v190 row_ror:4 row_mask:0xf bank_mask:0xf bound_ctrl:1
	v_add_f32_dpp v192, v192, v192 row_ror:4 row_mask:0xf bank_mask:0xf bound_ctrl:1
	v_pk_mul_f32 v[196:197], v[122:123], v[120:121] op_sel_hi:[0,1]
	v_add_f32_dpp v190, v190, v190 row_ror:2 row_mask:0xf bank_mask:0xf bound_ctrl:1
	v_add_f32_dpp v192, v192, v192 row_ror:2 row_mask:0xf bank_mask:0xf bound_ctrl:1
	v_pk_mul_f32 v[198:199], v[122:123], v[118:119] op_sel:[1,0] op_sel_hi:[1,1]
	v_add_f32_dpp v190, v190, v190 row_ror:1 row_mask:0xf bank_mask:0xf bound_ctrl:1
	v_add_f32_dpp v192, v192, v192 row_ror:1 row_mask:0xf bank_mask:0xf bound_ctrl:1
	v_pk_mul_f32 v[152:153], v[122:123], v[120:121] op_sel:[1,0] op_sel_hi:[1,1]
	ds_read_b32 v122, v182 offset:21760
	ds_read_b32 v123, v182 offset:21824
	ds_read_b128 v[118:121], v134 offset:14848
	s_waitcnt lgkmcnt(7)
	v_pk_fma_f32 v[194:195], v[190:191], v[114:115], v[194:195] op_sel_hi:[0,1,1]
	v_pk_fma_f32 v[198:199], v[192:193], v[114:115], v[198:199] op_sel_hi:[0,1,1]
	v_pk_fma_f32 v[196:197], v[190:191], v[116:117], v[196:197] op_sel_hi:[0,1,1]
	v_pk_fma_f32 v[152:153], v[192:193], v[116:117], v[152:153] op_sel_hi:[0,1,1]
	v_pk_fma_f32 v[84:85], v[84:85], v[110:111], v[194:195]
	v_pk_fma_f32 v[148:149], v[148:149], v[110:111], v[198:199]
	v_pk_fma_f32 v[86:87], v[86:87], v[112:113], v[196:197]
	v_pk_fma_f32 v[150:151], v[150:151], v[112:113], v[152:153]
	ds_read_b128 v[110:113], v134 offset:2560
	ds_read_b128 v[114:117], v134 offset:10752
	s_waitcnt lgkmcnt(8)
	v_pk_mul_f32 v[194:195], v[84:85], v[186:187]
	v_pk_mul_f32 v[196:197], v[148:149], v[186:187]
	v_pk_fma_f32 v[194:195], v[86:87], v[188:189], v[194:195]
	v_pk_fma_f32 v[196:197], v[150:151], v[188:189], v[196:197]
	v_add_f32_e32 v194, v194, v195
	v_add_f32_e32 v196, v196, v197
	ds_read_b128 v[186:189], v134 offset:18944
	v_add_f32_dpp v194, v194, v194 row_ror:8 row_mask:0xf bank_mask:0xf bound_ctrl:1
	v_add_f32_dpp v196, v196, v196 row_ror:8 row_mask:0xf bank_mask:0xf bound_ctrl:1
	s_waitcnt lgkmcnt(6)
	v_pk_mul_f32 v[190:191], v[84:85], v[102:103]
	v_pk_mul_f32 v[192:193], v[148:149], v[102:103]
	v_add_f32_dpp v194, v194, v194 row_ror:4 row_mask:0xf bank_mask:0xf bound_ctrl:1
	v_add_f32_dpp v196, v196, v196 row_ror:4 row_mask:0xf bank_mask:0xf bound_ctrl:1
	v_pk_fma_f32 v[190:191], v[86:87], v[104:105], v[190:191]
	v_pk_fma_f32 v[192:193], v[150:151], v[104:105], v[192:193]
	v_add_f32_dpp v194, v194, v194 row_ror:2 row_mask:0xf bank_mask:0xf bound_ctrl:1
	v_add_f32_dpp v196, v196, v196 row_ror:2 row_mask:0xf bank_mask:0xf bound_ctrl:1
	v_add_f32_e32 v190, v190, v191
	v_add_f32_dpp v194, v194, v194 row_ror:1 row_mask:0xf bank_mask:0xf bound_ctrl:1
	v_add_f32_dpp v196, v196, v196 row_ror:1 row_mask:0xf bank_mask:0xf bound_ctrl:1
	v_add_f32_e32 v192, v192, v193
	ds_write_b32 v182, v194 offset:46208
	ds_write_b32 v182, v196 offset:46272
	ds_read_b128 v[106:109], v134 offset:6912
	v_add_f32_dpp v190, v190, v190 row_ror:8 row_mask:0xf bank_mask:0xf bound_ctrl:1
	v_add_f32_dpp v192, v192, v192 row_ror:8 row_mask:0xf bank_mask:0xf bound_ctrl:1
	s_waitcnt lgkmcnt(6)
	v_pk_mul_f32 v[194:195], v[122:123], v[118:119] op_sel_hi:[0,1]
	v_add_f32_dpp v190, v190, v190 row_ror:4 row_mask:0xf bank_mask:0xf bound_ctrl:1
	v_add_f32_dpp v192, v192, v192 row_ror:4 row_mask:0xf bank_mask:0xf bound_ctrl:1
	v_pk_mul_f32 v[196:197], v[122:123], v[120:121] op_sel_hi:[0,1]
	v_add_f32_dpp v190, v190, v190 row_ror:2 row_mask:0xf bank_mask:0xf bound_ctrl:1
	v_add_f32_dpp v192, v192, v192 row_ror:2 row_mask:0xf bank_mask:0xf bound_ctrl:1
	v_pk_mul_f32 v[198:199], v[122:123], v[118:119] op_sel:[1,0] op_sel_hi:[1,1]
	v_add_f32_dpp v190, v190, v190 row_ror:1 row_mask:0xf bank_mask:0xf bound_ctrl:1
	v_add_f32_dpp v192, v192, v192 row_ror:1 row_mask:0xf bank_mask:0xf bound_ctrl:1
	v_pk_mul_f32 v[152:153], v[122:123], v[120:121] op_sel:[1,0] op_sel_hi:[1,1]
	ds_read_b32 v122, v182 offset:21888
	ds_read_b32 v123, v182 offset:21952
	ds_read_b128 v[118:121], v134 offset:15104
	s_waitcnt lgkmcnt(7)
	v_pk_fma_f32 v[194:195], v[190:191], v[114:115], v[194:195] op_sel_hi:[0,1,1]
	v_pk_fma_f32 v[198:199], v[192:193], v[114:115], v[198:199] op_sel_hi:[0,1,1]
	v_pk_fma_f32 v[196:197], v[190:191], v[116:117], v[196:197] op_sel_hi:[0,1,1]
	v_pk_fma_f32 v[152:153], v[192:193], v[116:117], v[152:153] op_sel_hi:[0,1,1]
	v_pk_fma_f32 v[84:85], v[84:85], v[110:111], v[194:195]
	v_pk_fma_f32 v[148:149], v[148:149], v[110:111], v[198:199]
	v_pk_fma_f32 v[86:87], v[86:87], v[112:113], v[196:197]
	v_pk_fma_f32 v[150:151], v[150:151], v[112:113], v[152:153]
	ds_read_b128 v[110:113], v134 offset:2816
	ds_read_b128 v[114:117], v134 offset:11008
	s_waitcnt lgkmcnt(8)
	v_pk_mul_f32 v[194:195], v[84:85], v[186:187]
	v_pk_mul_f32 v[196:197], v[148:149], v[186:187]
	v_pk_fma_f32 v[194:195], v[86:87], v[188:189], v[194:195]
	v_pk_fma_f32 v[196:197], v[150:151], v[188:189], v[196:197]
	v_add_f32_e32 v194, v194, v195
	v_add_f32_e32 v196, v196, v197
	ds_read_b128 v[186:189], v134 offset:19200
	v_add_f32_dpp v194, v194, v194 row_ror:8 row_mask:0xf bank_mask:0xf bound_ctrl:1
	v_add_f32_dpp v196, v196, v196 row_ror:8 row_mask:0xf bank_mask:0xf bound_ctrl:1
	s_waitcnt lgkmcnt(6)
	v_pk_mul_f32 v[190:191], v[84:85], v[106:107]
	v_pk_mul_f32 v[192:193], v[148:149], v[106:107]
	v_add_f32_dpp v194, v194, v194 row_ror:4 row_mask:0xf bank_mask:0xf bound_ctrl:1
	v_add_f32_dpp v196, v196, v196 row_ror:4 row_mask:0xf bank_mask:0xf bound_ctrl:1
	v_pk_fma_f32 v[190:191], v[86:87], v[108:109], v[190:191]
	v_pk_fma_f32 v[192:193], v[150:151], v[108:109], v[192:193]
	v_add_f32_dpp v194, v194, v194 row_ror:2 row_mask:0xf bank_mask:0xf bound_ctrl:1
	v_add_f32_dpp v196, v196, v196 row_ror:2 row_mask:0xf bank_mask:0xf bound_ctrl:1
	v_add_f32_e32 v190, v190, v191
	v_add_f32_dpp v194, v194, v194 row_ror:1 row_mask:0xf bank_mask:0xf bound_ctrl:1
	v_add_f32_dpp v196, v196, v196 row_ror:1 row_mask:0xf bank_mask:0xf bound_ctrl:1
	v_add_f32_e32 v192, v192, v193
	ds_write_b32 v182, v194 offset:46336
	ds_write_b32 v182, v196 offset:46400
	ds_read_b128 v[102:105], v134 offset:7168
	v_add_f32_dpp v190, v190, v190 row_ror:8 row_mask:0xf bank_mask:0xf bound_ctrl:1
	v_add_f32_dpp v192, v192, v192 row_ror:8 row_mask:0xf bank_mask:0xf bound_ctrl:1
	s_waitcnt lgkmcnt(6)
	v_pk_mul_f32 v[194:195], v[122:123], v[118:119] op_sel_hi:[0,1]
	v_add_f32_dpp v190, v190, v190 row_ror:4 row_mask:0xf bank_mask:0xf bound_ctrl:1
	v_add_f32_dpp v192, v192, v192 row_ror:4 row_mask:0xf bank_mask:0xf bound_ctrl:1
	v_pk_mul_f32 v[196:197], v[122:123], v[120:121] op_sel_hi:[0,1]
	v_add_f32_dpp v190, v190, v190 row_ror:2 row_mask:0xf bank_mask:0xf bound_ctrl:1
	v_add_f32_dpp v192, v192, v192 row_ror:2 row_mask:0xf bank_mask:0xf bound_ctrl:1
	v_pk_mul_f32 v[198:199], v[122:123], v[118:119] op_sel:[1,0] op_sel_hi:[1,1]
	v_add_f32_dpp v190, v190, v190 row_ror:1 row_mask:0xf bank_mask:0xf bound_ctrl:1
	v_add_f32_dpp v192, v192, v192 row_ror:1 row_mask:0xf bank_mask:0xf bound_ctrl:1
	v_pk_mul_f32 v[152:153], v[122:123], v[120:121] op_sel:[1,0] op_sel_hi:[1,1]
	ds_read_b32 v122, v182 offset:22016
	ds_read_b32 v123, v182 offset:22080
	ds_read_b128 v[118:121], v134 offset:15360
	s_waitcnt lgkmcnt(7)
	v_pk_fma_f32 v[194:195], v[190:191], v[114:115], v[194:195] op_sel_hi:[0,1,1]
	v_pk_fma_f32 v[198:199], v[192:193], v[114:115], v[198:199] op_sel_hi:[0,1,1]
	v_pk_fma_f32 v[196:197], v[190:191], v[116:117], v[196:197] op_sel_hi:[0,1,1]
	v_pk_fma_f32 v[152:153], v[192:193], v[116:117], v[152:153] op_sel_hi:[0,1,1]
	v_pk_fma_f32 v[84:85], v[84:85], v[110:111], v[194:195]
	v_pk_fma_f32 v[148:149], v[148:149], v[110:111], v[198:199]
	v_pk_fma_f32 v[86:87], v[86:87], v[112:113], v[196:197]
	v_pk_fma_f32 v[150:151], v[150:151], v[112:113], v[152:153]
	ds_read_b128 v[110:113], v134 offset:3072
	ds_read_b128 v[114:117], v134 offset:11264
	s_waitcnt lgkmcnt(8)
	v_pk_mul_f32 v[194:195], v[84:85], v[186:187]
	v_pk_mul_f32 v[196:197], v[148:149], v[186:187]
	v_pk_fma_f32 v[194:195], v[86:87], v[188:189], v[194:195]
	v_pk_fma_f32 v[196:197], v[150:151], v[188:189], v[196:197]
	v_add_f32_e32 v194, v194, v195
	v_add_f32_e32 v196, v196, v197
	ds_read_b128 v[186:189], v134 offset:19456
	v_add_f32_dpp v194, v194, v194 row_ror:8 row_mask:0xf bank_mask:0xf bound_ctrl:1
	v_add_f32_dpp v196, v196, v196 row_ror:8 row_mask:0xf bank_mask:0xf bound_ctrl:1
	s_waitcnt lgkmcnt(6)
	v_pk_mul_f32 v[190:191], v[84:85], v[102:103]
	v_pk_mul_f32 v[192:193], v[148:149], v[102:103]
	v_add_f32_dpp v194, v194, v194 row_ror:4 row_mask:0xf bank_mask:0xf bound_ctrl:1
	v_add_f32_dpp v196, v196, v196 row_ror:4 row_mask:0xf bank_mask:0xf bound_ctrl:1
	v_pk_fma_f32 v[190:191], v[86:87], v[104:105], v[190:191]
	v_pk_fma_f32 v[192:193], v[150:151], v[104:105], v[192:193]
	v_add_f32_dpp v194, v194, v194 row_ror:2 row_mask:0xf bank_mask:0xf bound_ctrl:1
	v_add_f32_dpp v196, v196, v196 row_ror:2 row_mask:0xf bank_mask:0xf bound_ctrl:1
	v_add_f32_e32 v190, v190, v191
	v_add_f32_dpp v194, v194, v194 row_ror:1 row_mask:0xf bank_mask:0xf bound_ctrl:1
	v_add_f32_dpp v196, v196, v196 row_ror:1 row_mask:0xf bank_mask:0xf bound_ctrl:1
	v_add_f32_e32 v192, v192, v193
	ds_write_b32 v182, v194 offset:46464
	ds_write_b32 v182, v196 offset:46528
	ds_read_b128 v[106:109], v134 offset:7424
	v_add_f32_dpp v190, v190, v190 row_ror:8 row_mask:0xf bank_mask:0xf bound_ctrl:1
	v_add_f32_dpp v192, v192, v192 row_ror:8 row_mask:0xf bank_mask:0xf bound_ctrl:1
	s_waitcnt lgkmcnt(6)
	v_pk_mul_f32 v[194:195], v[122:123], v[118:119] op_sel_hi:[0,1]
	v_add_f32_dpp v190, v190, v190 row_ror:4 row_mask:0xf bank_mask:0xf bound_ctrl:1
	v_add_f32_dpp v192, v192, v192 row_ror:4 row_mask:0xf bank_mask:0xf bound_ctrl:1
	v_pk_mul_f32 v[196:197], v[122:123], v[120:121] op_sel_hi:[0,1]
	v_add_f32_dpp v190, v190, v190 row_ror:2 row_mask:0xf bank_mask:0xf bound_ctrl:1
	v_add_f32_dpp v192, v192, v192 row_ror:2 row_mask:0xf bank_mask:0xf bound_ctrl:1
	v_pk_mul_f32 v[198:199], v[122:123], v[118:119] op_sel:[1,0] op_sel_hi:[1,1]
	v_add_f32_dpp v190, v190, v190 row_ror:1 row_mask:0xf bank_mask:0xf bound_ctrl:1
	v_add_f32_dpp v192, v192, v192 row_ror:1 row_mask:0xf bank_mask:0xf bound_ctrl:1
	v_pk_mul_f32 v[152:153], v[122:123], v[120:121] op_sel:[1,0] op_sel_hi:[1,1]
	ds_read_b32 v122, v182 offset:22144
	ds_read_b32 v123, v182 offset:22208
	ds_read_b128 v[118:121], v134 offset:15616
	s_waitcnt lgkmcnt(7)
	v_pk_fma_f32 v[194:195], v[190:191], v[114:115], v[194:195] op_sel_hi:[0,1,1]
	v_pk_fma_f32 v[198:199], v[192:193], v[114:115], v[198:199] op_sel_hi:[0,1,1]
	v_pk_fma_f32 v[196:197], v[190:191], v[116:117], v[196:197] op_sel_hi:[0,1,1]
	v_pk_fma_f32 v[152:153], v[192:193], v[116:117], v[152:153] op_sel_hi:[0,1,1]
	v_pk_fma_f32 v[84:85], v[84:85], v[110:111], v[194:195]
	v_pk_fma_f32 v[148:149], v[148:149], v[110:111], v[198:199]
	v_pk_fma_f32 v[86:87], v[86:87], v[112:113], v[196:197]
	v_pk_fma_f32 v[150:151], v[150:151], v[112:113], v[152:153]
	ds_read_b128 v[110:113], v134 offset:3328
	ds_read_b128 v[114:117], v134 offset:11520
	s_waitcnt lgkmcnt(8)
	v_pk_mul_f32 v[194:195], v[84:85], v[186:187]
	v_pk_mul_f32 v[196:197], v[148:149], v[186:187]
	v_pk_fma_f32 v[194:195], v[86:87], v[188:189], v[194:195]
	v_pk_fma_f32 v[196:197], v[150:151], v[188:189], v[196:197]
	v_add_f32_e32 v194, v194, v195
	v_add_f32_e32 v196, v196, v197
	ds_read_b128 v[186:189], v134 offset:19712
	v_add_f32_dpp v194, v194, v194 row_ror:8 row_mask:0xf bank_mask:0xf bound_ctrl:1
	v_add_f32_dpp v196, v196, v196 row_ror:8 row_mask:0xf bank_mask:0xf bound_ctrl:1
	s_waitcnt lgkmcnt(6)
	v_pk_mul_f32 v[190:191], v[84:85], v[106:107]
	v_pk_mul_f32 v[192:193], v[148:149], v[106:107]
	v_add_f32_dpp v194, v194, v194 row_ror:4 row_mask:0xf bank_mask:0xf bound_ctrl:1
	v_add_f32_dpp v196, v196, v196 row_ror:4 row_mask:0xf bank_mask:0xf bound_ctrl:1
	v_pk_fma_f32 v[190:191], v[86:87], v[108:109], v[190:191]
	v_pk_fma_f32 v[192:193], v[150:151], v[108:109], v[192:193]
	v_add_f32_dpp v194, v194, v194 row_ror:2 row_mask:0xf bank_mask:0xf bound_ctrl:1
	v_add_f32_dpp v196, v196, v196 row_ror:2 row_mask:0xf bank_mask:0xf bound_ctrl:1
	v_add_f32_e32 v190, v190, v191
	v_add_f32_dpp v194, v194, v194 row_ror:1 row_mask:0xf bank_mask:0xf bound_ctrl:1
	v_add_f32_dpp v196, v196, v196 row_ror:1 row_mask:0xf bank_mask:0xf bound_ctrl:1
	v_add_f32_e32 v192, v192, v193
	ds_write_b32 v182, v194 offset:46592
	ds_write_b32 v182, v196 offset:46656
	ds_read_b128 v[102:105], v134 offset:7680
	v_add_f32_dpp v190, v190, v190 row_ror:8 row_mask:0xf bank_mask:0xf bound_ctrl:1
	v_add_f32_dpp v192, v192, v192 row_ror:8 row_mask:0xf bank_mask:0xf bound_ctrl:1
	s_waitcnt lgkmcnt(6)
	v_pk_mul_f32 v[194:195], v[122:123], v[118:119] op_sel_hi:[0,1]
	v_add_f32_dpp v190, v190, v190 row_ror:4 row_mask:0xf bank_mask:0xf bound_ctrl:1
	v_add_f32_dpp v192, v192, v192 row_ror:4 row_mask:0xf bank_mask:0xf bound_ctrl:1
	v_pk_mul_f32 v[196:197], v[122:123], v[120:121] op_sel_hi:[0,1]
	v_add_f32_dpp v190, v190, v190 row_ror:2 row_mask:0xf bank_mask:0xf bound_ctrl:1
	v_add_f32_dpp v192, v192, v192 row_ror:2 row_mask:0xf bank_mask:0xf bound_ctrl:1
	v_pk_mul_f32 v[198:199], v[122:123], v[118:119] op_sel:[1,0] op_sel_hi:[1,1]
	v_add_f32_dpp v190, v190, v190 row_ror:1 row_mask:0xf bank_mask:0xf bound_ctrl:1
	v_add_f32_dpp v192, v192, v192 row_ror:1 row_mask:0xf bank_mask:0xf bound_ctrl:1
	v_pk_mul_f32 v[152:153], v[122:123], v[120:121] op_sel:[1,0] op_sel_hi:[1,1]
	ds_read_b32 v122, v182 offset:22272
	ds_read_b32 v123, v182 offset:22336
	ds_read_b128 v[118:121], v134 offset:15872
	s_waitcnt lgkmcnt(7)
	v_pk_fma_f32 v[194:195], v[190:191], v[114:115], v[194:195] op_sel_hi:[0,1,1]
	v_pk_fma_f32 v[198:199], v[192:193], v[114:115], v[198:199] op_sel_hi:[0,1,1]
	v_pk_fma_f32 v[196:197], v[190:191], v[116:117], v[196:197] op_sel_hi:[0,1,1]
	v_pk_fma_f32 v[152:153], v[192:193], v[116:117], v[152:153] op_sel_hi:[0,1,1]
	v_pk_fma_f32 v[84:85], v[84:85], v[110:111], v[194:195]
	v_pk_fma_f32 v[148:149], v[148:149], v[110:111], v[198:199]
	v_pk_fma_f32 v[86:87], v[86:87], v[112:113], v[196:197]
	v_pk_fma_f32 v[150:151], v[150:151], v[112:113], v[152:153]
	ds_read_b128 v[110:113], v134 offset:3584
	ds_read_b128 v[114:117], v134 offset:11776
	s_waitcnt lgkmcnt(8)
	v_pk_mul_f32 v[194:195], v[84:85], v[186:187]
	v_pk_mul_f32 v[196:197], v[148:149], v[186:187]
	v_pk_fma_f32 v[194:195], v[86:87], v[188:189], v[194:195]
	v_pk_fma_f32 v[196:197], v[150:151], v[188:189], v[196:197]
	v_add_f32_e32 v194, v194, v195
	v_add_f32_e32 v196, v196, v197
	ds_read_b128 v[186:189], v134 offset:19968
	v_add_f32_dpp v194, v194, v194 row_ror:8 row_mask:0xf bank_mask:0xf bound_ctrl:1
	v_add_f32_dpp v196, v196, v196 row_ror:8 row_mask:0xf bank_mask:0xf bound_ctrl:1
	s_waitcnt lgkmcnt(6)
	v_pk_mul_f32 v[190:191], v[84:85], v[102:103]
	v_pk_mul_f32 v[192:193], v[148:149], v[102:103]
	v_add_f32_dpp v194, v194, v194 row_ror:4 row_mask:0xf bank_mask:0xf bound_ctrl:1
	v_add_f32_dpp v196, v196, v196 row_ror:4 row_mask:0xf bank_mask:0xf bound_ctrl:1
	v_pk_fma_f32 v[190:191], v[86:87], v[104:105], v[190:191]
	v_pk_fma_f32 v[192:193], v[150:151], v[104:105], v[192:193]
	v_add_f32_dpp v194, v194, v194 row_ror:2 row_mask:0xf bank_mask:0xf bound_ctrl:1
	v_add_f32_dpp v196, v196, v196 row_ror:2 row_mask:0xf bank_mask:0xf bound_ctrl:1
	v_add_f32_e32 v190, v190, v191
	v_add_f32_dpp v194, v194, v194 row_ror:1 row_mask:0xf bank_mask:0xf bound_ctrl:1
	v_add_f32_dpp v196, v196, v196 row_ror:1 row_mask:0xf bank_mask:0xf bound_ctrl:1
	v_add_f32_e32 v192, v192, v193
	ds_write_b32 v182, v194 offset:46720
	ds_write_b32 v182, v196 offset:46784
	ds_read_b128 v[106:109], v134 offset:7936
	v_add_f32_dpp v190, v190, v190 row_ror:8 row_mask:0xf bank_mask:0xf bound_ctrl:1
	v_add_f32_dpp v192, v192, v192 row_ror:8 row_mask:0xf bank_mask:0xf bound_ctrl:1
	s_waitcnt lgkmcnt(6)
	v_pk_mul_f32 v[194:195], v[122:123], v[118:119] op_sel_hi:[0,1]
	v_add_f32_dpp v190, v190, v190 row_ror:4 row_mask:0xf bank_mask:0xf bound_ctrl:1
	v_add_f32_dpp v192, v192, v192 row_ror:4 row_mask:0xf bank_mask:0xf bound_ctrl:1
	v_pk_mul_f32 v[196:197], v[122:123], v[120:121] op_sel_hi:[0,1]
	v_add_f32_dpp v190, v190, v190 row_ror:2 row_mask:0xf bank_mask:0xf bound_ctrl:1
	v_add_f32_dpp v192, v192, v192 row_ror:2 row_mask:0xf bank_mask:0xf bound_ctrl:1
	v_pk_mul_f32 v[198:199], v[122:123], v[118:119] op_sel:[1,0] op_sel_hi:[1,1]
	v_add_f32_dpp v190, v190, v190 row_ror:1 row_mask:0xf bank_mask:0xf bound_ctrl:1
	v_add_f32_dpp v192, v192, v192 row_ror:1 row_mask:0xf bank_mask:0xf bound_ctrl:1
	v_pk_mul_f32 v[152:153], v[122:123], v[120:121] op_sel:[1,0] op_sel_hi:[1,1]
	ds_read_b32 v122, v182 offset:22400
	ds_read_b32 v123, v182 offset:22464
	ds_read_b128 v[118:121], v134 offset:16128
	s_waitcnt lgkmcnt(7)
	v_pk_fma_f32 v[194:195], v[190:191], v[114:115], v[194:195] op_sel_hi:[0,1,1]
	v_pk_fma_f32 v[198:199], v[192:193], v[114:115], v[198:199] op_sel_hi:[0,1,1]
	v_pk_fma_f32 v[196:197], v[190:191], v[116:117], v[196:197] op_sel_hi:[0,1,1]
	v_pk_fma_f32 v[152:153], v[192:193], v[116:117], v[152:153] op_sel_hi:[0,1,1]
	v_pk_fma_f32 v[84:85], v[84:85], v[110:111], v[194:195]
	v_pk_fma_f32 v[148:149], v[148:149], v[110:111], v[198:199]
	v_pk_fma_f32 v[86:87], v[86:87], v[112:113], v[196:197]
	v_pk_fma_f32 v[150:151], v[150:151], v[112:113], v[152:153]
	ds_read_b128 v[110:113], v134 offset:3840
	ds_read_b128 v[114:117], v134 offset:12032
	s_waitcnt lgkmcnt(8)
	v_pk_mul_f32 v[194:195], v[84:85], v[186:187]
	v_pk_mul_f32 v[196:197], v[148:149], v[186:187]
	v_pk_fma_f32 v[194:195], v[86:87], v[188:189], v[194:195]
	v_pk_fma_f32 v[196:197], v[150:151], v[188:189], v[196:197]
	v_add_f32_e32 v194, v194, v195
	v_add_f32_e32 v196, v196, v197
	ds_read_b128 v[186:189], v134 offset:20224
	v_add_f32_dpp v194, v194, v194 row_ror:8 row_mask:0xf bank_mask:0xf bound_ctrl:1
	v_add_f32_dpp v196, v196, v196 row_ror:8 row_mask:0xf bank_mask:0xf bound_ctrl:1
	s_waitcnt lgkmcnt(6)
	v_pk_mul_f32 v[190:191], v[84:85], v[106:107]
	v_pk_mul_f32 v[192:193], v[148:149], v[106:107]
	v_add_f32_dpp v194, v194, v194 row_ror:4 row_mask:0xf bank_mask:0xf bound_ctrl:1
	v_add_f32_dpp v196, v196, v196 row_ror:4 row_mask:0xf bank_mask:0xf bound_ctrl:1
	v_pk_fma_f32 v[190:191], v[86:87], v[108:109], v[190:191]
	v_pk_fma_f32 v[192:193], v[150:151], v[108:109], v[192:193]
	v_add_f32_dpp v194, v194, v194 row_ror:2 row_mask:0xf bank_mask:0xf bound_ctrl:1
	v_add_f32_dpp v196, v196, v196 row_ror:2 row_mask:0xf bank_mask:0xf bound_ctrl:1
	v_add_f32_e32 v190, v190, v191
	v_add_f32_dpp v194, v194, v194 row_ror:1 row_mask:0xf bank_mask:0xf bound_ctrl:1
	v_add_f32_dpp v196, v196, v196 row_ror:1 row_mask:0xf bank_mask:0xf bound_ctrl:1
	v_add_f32_e32 v192, v192, v193
	ds_write_b32 v182, v194 offset:46848
	ds_write_b32 v182, v196 offset:46912
	v_add_f32_dpp v190, v190, v190 row_ror:8 row_mask:0xf bank_mask:0xf bound_ctrl:1
	v_add_f32_dpp v192, v192, v192 row_ror:8 row_mask:0xf bank_mask:0xf bound_ctrl:1
	s_waitcnt lgkmcnt(5)
	v_pk_mul_f32 v[194:195], v[122:123], v[118:119] op_sel_hi:[0,1]
	v_add_f32_dpp v190, v190, v190 row_ror:4 row_mask:0xf bank_mask:0xf bound_ctrl:1
	v_add_f32_dpp v192, v192, v192 row_ror:4 row_mask:0xf bank_mask:0xf bound_ctrl:1
	v_pk_mul_f32 v[196:197], v[122:123], v[120:121] op_sel_hi:[0,1]
	v_add_f32_dpp v190, v190, v190 row_ror:2 row_mask:0xf bank_mask:0xf bound_ctrl:1
	v_add_f32_dpp v192, v192, v192 row_ror:2 row_mask:0xf bank_mask:0xf bound_ctrl:1
	v_pk_mul_f32 v[198:199], v[122:123], v[118:119] op_sel:[1,0] op_sel_hi:[1,1]
	v_add_f32_dpp v190, v190, v190 row_ror:1 row_mask:0xf bank_mask:0xf bound_ctrl:1
	v_add_f32_dpp v192, v192, v192 row_ror:1 row_mask:0xf bank_mask:0xf bound_ctrl:1
	v_pk_mul_f32 v[152:153], v[122:123], v[120:121] op_sel:[1,0] op_sel_hi:[1,1]
	s_waitcnt lgkmcnt(3)
	v_pk_fma_f32 v[194:195], v[190:191], v[114:115], v[194:195] op_sel_hi:[0,1,1]
	v_pk_fma_f32 v[198:199], v[192:193], v[114:115], v[198:199] op_sel_hi:[0,1,1]
	v_pk_fma_f32 v[196:197], v[190:191], v[116:117], v[196:197] op_sel_hi:[0,1,1]
	v_pk_fma_f32 v[152:153], v[192:193], v[116:117], v[152:153] op_sel_hi:[0,1,1]
	v_pk_fma_f32 v[84:85], v[84:85], v[110:111], v[194:195]
	v_pk_fma_f32 v[148:149], v[148:149], v[110:111], v[198:199]
	v_pk_fma_f32 v[86:87], v[86:87], v[112:113], v[196:197]
	v_pk_fma_f32 v[150:151], v[150:151], v[112:113], v[152:153]
	s_waitcnt lgkmcnt(2)
	v_pk_mul_f32 v[194:195], v[84:85], v[186:187]
	v_pk_mul_f32 v[196:197], v[148:149], v[186:187]
	v_pk_fma_f32 v[194:195], v[86:87], v[188:189], v[194:195]
	v_pk_fma_f32 v[196:197], v[150:151], v[188:189], v[196:197]
	v_add_f32_e32 v194, v194, v195
	v_add_f32_e32 v196, v196, v197
	s_nop 0
	v_add_f32_dpp v194, v194, v194 row_ror:8 row_mask:0xf bank_mask:0xf bound_ctrl:1
	v_add_f32_dpp v196, v196, v196 row_ror:8 row_mask:0xf bank_mask:0xf bound_ctrl:1
	s_nop 0
	v_add_f32_dpp v194, v194, v194 row_ror:4 row_mask:0xf bank_mask:0xf bound_ctrl:1
	v_add_f32_dpp v196, v196, v196 row_ror:4 row_mask:0xf bank_mask:0xf bound_ctrl:1
	s_nop 0
	v_add_f32_dpp v194, v194, v194 row_ror:2 row_mask:0xf bank_mask:0xf bound_ctrl:1
	v_add_f32_dpp v196, v196, v196 row_ror:2 row_mask:0xf bank_mask:0xf bound_ctrl:1
	s_nop 0
	v_add_f32_dpp v194, v194, v194 row_ror:1 row_mask:0xf bank_mask:0xf bound_ctrl:1
	v_add_f32_dpp v196, v196, v196 row_ror:1 row_mask:0xf bank_mask:0xf bound_ctrl:1
	ds_write_b32 v182, v194 offset:46976
	ds_write_b32 v182, v196 offset:47040
	s_and_saveexec_b64 s[8:9], s[38:39]
	s_cbranch_execz .LBB0_375
	v_add_f32_e32 v88, v0, v44
	v_min_f32_e32 v92, 0, v88
	v_mul_f32_e64 v88, |v88|, s62
	v_exp_f32_e32 v88, v88
	v_add_f32_e32 v89, v1, v45
	v_add_f32_e32 v90, v2, v46
	v_add_f32_e32 v91, v3, v47
	v_add_f32_e32 v88, 1.0, v88
	v_cmp_gt_f32_e32 vcc, s5, v88
	s_mov_b32 s4, 0xf800000
	v_add_f32_e32 v80, v4, v28
	v_cndmask_b32_e64 v93, 0, 32, vcc
	v_ldexp_f32 v88, v88, v93
	v_log_f32_e32 v88, v88
	v_mul_f32_e32 v80, 0xbfb8aa3b, v80
	v_exp_f32_e32 v82, v80
	v_add_f32_e32 v80, v5, v29
	v_mul_f32_e32 v93, 0x3f317217, v88
	v_fma_f32 v93, v88, s76, -v93
	v_fmac_f32_e32 v93, 0x3377d1cf, v88
	v_fmac_f32_e32 v93, 0x3f317217, v88
	v_cmp_lt_f32_e64 s[42:43], |v88|, s77
	v_mul_f32_e32 v80, 0xbfb8aa3b, v80
	v_exp_f32_e32 v83, v80
	v_cndmask_b32_e64 v88, v88, v93, s[42:43]
	v_cndmask_b32_e32 v93, 0, v171, vcc
	v_sub_f32_e32 v88, v88, v93
	v_sub_f32_e32 v88, v92, v88
	v_min_f32_e32 v92, 0, v89
	v_mul_f32_e64 v89, |v89|, s62
	v_exp_f32_e32 v89, v89
	v_add_f32_e32 v88, -0.5, v88
	v_mul_f32_e32 v88, 0x3fb8aa3b, v88
	v_exp_f32_e32 v88, v88
	v_add_f32_e32 v89, 1.0, v89
	v_cmp_gt_f32_e32 vcc, s5, v89
	v_pk_add_f32 v[82:83], v[82:83], 1.0 op_sel_hi:[1,0]
	v_mul_f32_e32 v88, 0xbfb8aa3b, v88
	v_cndmask_b32_e64 v93, 0, 32, vcc
	v_ldexp_f32 v89, v89, v93
	v_log_f32_e32 v89, v89
	v_exp_f32_e32 v88, v88
	v_add_f32_e32 v80, v6, v30
	v_add_f32_e32 v81, v7, v31
	v_mul_f32_e32 v93, 0x3f317217, v89
	v_fma_f32 v93, v89, s76, -v93
	v_fmac_f32_e32 v93, 0x3377d1cf, v89
	v_fmac_f32_e32 v93, 0x3f317217, v89
	v_cmp_lt_f32_e64 s[42:43], |v89|, s77
	v_mul_f32_e32 v80, 0xbfb8aa3b, v80
	v_mul_f32_e32 v81, 0xbfb8aa3b, v81
	v_cndmask_b32_e64 v89, v89, v93, s[42:43]
	v_cndmask_b32_e32 v93, 0, v171, vcc
	v_sub_f32_e32 v89, v89, v93
	v_sub_f32_e32 v89, v92, v89
	v_min_f32_e32 v92, 0, v90
	v_mul_f32_e64 v90, |v90|, s62
	v_exp_f32_e32 v90, v90
	v_add_f32_e32 v89, -0.5, v89
	v_mul_f32_e32 v89, 0x3fb8aa3b, v89
	v_exp_f32_e32 v89, v89
	v_add_f32_e32 v90, 1.0, v90
	v_cmp_gt_f32_e32 vcc, s5, v90
	v_exp_f32_e32 v80, v80
	v_mul_f32_e32 v89, 0xbfb8aa3b, v89
	v_cndmask_b32_e64 v93, 0, 32, vcc
	v_ldexp_f32 v90, v90, v93
	v_log_f32_e32 v90, v90
	v_exp_f32_e32 v89, v89
	v_exp_f32_e32 v81, v81
	v_mul_f32_e32 v93, 0x3f317217, v90
	v_fma_f32 v93, v90, s76, -v93
	v_fmac_f32_e32 v93, 0x3377d1cf, v90
	v_fmac_f32_e32 v93, 0x3f317217, v90
	v_cmp_lt_f32_e64 s[42:43], |v90|, s77
	v_pk_add_f32 v[80:81], v[80:81], 1.0 op_sel_hi:[1,0]
	s_nop 0
	v_cndmask_b32_e64 v90, v90, v93, s[42:43]
	v_cndmask_b32_e32 v93, 0, v171, vcc
	v_sub_f32_e32 v90, v90, v93
	v_sub_f32_e32 v90, v92, v90
	v_min_f32_e32 v92, 0, v91
	v_mul_f32_e64 v91, |v91|, s62
	v_exp_f32_e32 v91, v91
	v_add_f32_e32 v90, -0.5, v90
	v_mul_f32_e32 v90, 0x3fb8aa3b, v90
	v_exp_f32_e32 v90, v90
	v_add_f32_e32 v91, 1.0, v91
	v_cmp_gt_f32_e32 vcc, s5, v91
	v_mul_f32_e32 v90, 0xbfb8aa3b, v90
	s_nop 0
	v_cndmask_b32_e64 v93, 0, 32, vcc
	v_ldexp_f32 v91, v91, v93
	v_log_f32_e32 v91, v91
	v_exp_f32_e32 v90, v90
	v_mul_f32_e32 v93, 0x3f317217, v91
	v_fma_f32 v93, v91, s76, -v93
	v_fmac_f32_e32 v93, 0x3377d1cf, v91
	v_fmac_f32_e32 v93, 0x3f317217, v91
	v_cmp_lt_f32_e64 s[42:43], |v91|, s77
	s_nop 1
	v_cndmask_b32_e64 v91, v91, v93, s[42:43]
	v_cndmask_b32_e32 v93, 0, v171, vcc
	v_sub_f32_e32 v91, v91, v93
	v_sub_f32_e32 v91, v92, v91
	v_add_f32_e32 v91, -0.5, v91
	v_mul_f32_e32 v91, 0x3fb8aa3b, v91
	v_exp_f32_e32 v91, v91
	v_pk_mul_f32 v[92:93], v[10:11], v[42:43]
	v_mul_f32_e32 v91, 0xbfb8aa3b, v91
	v_exp_f32_e32 v91, v91
	v_pk_mul_f32 v[94:95], v[92:93], v[92:93]
	ds_write_b128 v181, v[88:91] offset:22528
	v_pk_mul_f32 v[88:89], v[8:9], v[40:41]
	v_pk_mul_f32 v[90:91], v[88:89], v[88:89]
	v_add_f32_e32 v90, v91, v90
	v_add_f32_e32 v90, v94, v90
	v_add_f32_e32 v90, v95, v90
	s_nop 1
	v_add_f32_dpp v90, v90, v90 row_ror:8 row_mask:0xf bank_mask:0xf bound_ctrl:1
	s_nop 1
	v_add_f32_dpp v90, v90, v90 row_ror:4 row_mask:0xf bank_mask:0xf bound_ctrl:1
	s_nop 1
	v_add_f32_dpp v90, v90, v90 row_ror:2 row_mask:0xf bank_mask:0xf bound_ctrl:1
	s_nop 1
	v_add_f32_dpp v90, v90, v90 row_ror:1 row_mask:0xf bank_mask:0xf bound_ctrl:1
	v_cmp_gt_f32_e32 vcc, s4, v90
	v_mul_f32_e32 v91, 0x4f800000, v90
	s_nop 0
	v_cndmask_b32_e32 v90, v90, v91, vcc
	v_sqrt_f32_e32 v91, v90
	s_nop 0
	v_add_u32_e32 v94, -1, v91
	v_fma_f32 v95, -v94, v91, v90
	v_cmp_ge_f32_e64 s[42:43], 0, v95
	v_add_u32_e32 v95, 1, v91
	s_nop 0
	v_cndmask_b32_e64 v94, v91, v94, s[42:43]
	v_fma_f32 v91, -v95, v91, v90
	v_cmp_lt_f32_e64 s[42:43], 0, v91
	s_nop 1
	v_cndmask_b32_e64 v91, v94, v95, s[42:43]
	v_mul_f32_e32 v94, 0x37800000, v91
	v_cndmask_b32_e32 v91, v91, v94, vcc
	v_cmp_class_f32_e32 vcc, v90, v160
	s_nop 1
	v_cndmask_b32_e32 v90, v91, v90, vcc
	v_max_f32_e32 v90, 0x2b8cbccc, v90
	v_div_scale_f32 v91, s[22:23], v90, v90, 1.0
	v_rcp_f32_e32 v94, v91
	s_nop 0
	v_fma_f32 v95, -v91, v94, 1.0
	v_fmac_f32_e32 v94, v95, v94
	v_div_scale_f32 v95, vcc, 1.0, v90, 1.0
	v_mul_f32_e32 v100, v95, v94
	v_fma_f32 v101, -v91, v100, v95
	v_fmac_f32_e32 v100, v101, v94
	v_fma_f32 v91, -v91, v100, v95
	v_div_fmas_f32 v91, v91, v94, v100
	v_div_fixup_f32 v90, v91, v90, 1.0
	v_pk_mul_f32 v[94:95], v[88:89], v[90:91] op_sel_hi:[1,0]
	v_pk_mul_f32 v[92:93], v[92:93], v[90:91] op_sel_hi:[1,0]
	v_xor_b32_e32 v89, 0x80000000, v95
	v_xor_b32_e32 v88, 0x80000000, v94
	v_xor_b32_e32 v91, 0x80000000, v93
	v_xor_b32_e32 v90, 0x80000000, v92
	ds_write_b128 v181, v[88:91] offset:26624
	v_div_scale_f32 v88, s[22:23], v83, v83, 1.0
	v_rcp_f32_e32 v89, v88
	s_nop 0
	v_fma_f32 v90, -v88, v89, 1.0
	v_fmac_f32_e32 v89, v90, v89
	v_div_scale_f32 v90, vcc, 1.0, v83, 1.0
	v_mul_f32_e32 v91, v90, v89
	v_fma_f32 v100, -v88, v91, v90
	v_fmac_f32_e32 v91, v100, v89
	v_fma_f32 v88, -v88, v91, v90
	v_div_fmas_f32 v88, v88, v89, v91
	v_div_fixup_f32 v83, v88, v83, 1.0
	v_div_scale_f32 v88, s[22:23], v82, v82, 1.0
	v_rcp_f32_e32 v89, v88
	s_nop 0
	v_fma_f32 v90, -v88, v89, 1.0
	v_fmac_f32_e32 v89, v90, v89
	v_div_scale_f32 v90, vcc, 1.0, v82, 1.0
	v_mul_f32_e32 v91, v90, v89
	v_fma_f32 v100, -v88, v91, v90
	v_fmac_f32_e32 v91, v100, v89
	v_fma_f32 v88, -v88, v91, v90
	v_div_scale_f32 v90, s[22:23], v81, v81, 1.0
	v_div_fmas_f32 v88, v88, v89, v91
	v_rcp_f32_e32 v91, v90
	v_div_fixup_f32 v82, v88, v82, 1.0
	v_pk_mul_f32 v[88:89], v[82:83], v[94:95]
	v_fma_f32 v94, -v90, v91, 1.0
	v_fmac_f32_e32 v91, v94, v91
	v_div_scale_f32 v94, vcc, 1.0, v81, 1.0
	v_mul_f32_e32 v95, v94, v91
	v_fma_f32 v100, -v90, v95, v94
	v_fmac_f32_e32 v95, v100, v91
	v_fma_f32 v90, -v90, v95, v94
	v_div_fmas_f32 v90, v90, v91, v95
	v_div_fixup_f32 v95, v90, v81, 1.0
	v_div_scale_f32 v81, s[22:23], v80, v80, 1.0
	v_rcp_f32_e32 v90, v81
	s_nop 0
	v_fma_f32 v91, -v81, v90, 1.0
	v_fmac_f32_e32 v90, v91, v90
	v_div_scale_f32 v91, vcc, 1.0, v80, 1.0
	v_mul_f32_e32 v94, v91, v90
	v_fma_f32 v100, -v81, v94, v91
	v_fmac_f32_e32 v94, v100, v90
	v_fma_f32 v81, -v81, v94, v91
	v_div_fmas_f32 v81, v81, v90, v94
	v_div_fixup_f32 v94, v81, v80, 1.0
	v_pk_add_f32 v[80:81], v[82:83], -1.0 op_sel_hi:[1,0]
	v_pk_add_f32 v[82:83], v[94:95], -1.0 op_sel_hi:[1,0]
	v_pk_fma_f32 v[80:81], v[12:13], v[80:81], 1.0 op_sel_hi:[1,1,0]
	v_pk_fma_f32 v[82:83], v[14:15], v[82:83], 1.0 op_sel_hi:[1,1,0]
	v_pk_mul_f32 v[90:91], v[94:95], v[92:93]
	v_pk_mul_f32 v[80:81], v[40:41], v[80:81]
	v_pk_mul_f32 v[82:83], v[42:43], v[82:83]
	ds_write_b128 v181, v[88:91] offset:30720
	ds_write_b128 v181, v[80:83] offset:34816
	ds_write_b128 v181, v[16:19] offset:38912

.LBB0_381:
	ds_read2st64_b32 v[80:81], v179 offset0:176 offset1:180
	v_ashrrev_i32_e32 v127, 31, v126
	v_lshlrev_b64 v[82:83], 13, v[126:127]
	v_ashrrev_i32_e32 v125, 31, v124
	v_lshl_add_u64 v[82:83], v[144:145], 0, v[82:83]
	s_waitcnt lgkmcnt(0)
	global_store_dword v[82:83], v80, off
	v_lshlrev_b64 v[82:83], 13, v[124:125]
	v_lshl_add_u64 v[82:83], v[144:145], 0, v[82:83]
	global_store_dword v[82:83], v81, off
	ds_read_b128 v[102:105], v134 offset:26624
	ds_read_b32 v122, v182 offset:43008
	ds_read_b32 v123, v182 offset:43072
	ds_read_b128 v[118:121], v134 offset:34816
	ds_read_b128 v[110:113], v134 offset:22528
	ds_read_b128 v[114:117], v134 offset:30720
	ds_read_b128 v[186:189], v134 offset:38912
	s_waitcnt lgkmcnt(6)
	v_pk_mul_f32 v[190:191], v[84:85], v[102:103]
	v_pk_mul_f32 v[192:193], v[148:149], v[102:103]
	v_pk_fma_f32 v[190:191], v[86:87], v[104:105], v[190:191]
	v_pk_fma_f32 v[192:193], v[150:151], v[104:105], v[192:193]
	v_add_f32_e32 v190, v190, v191
	v_add_f32_e32 v192, v192, v193
	ds_read_b128 v[106:109], v134 offset:26880
	v_add_f32_dpp v190, v190, v190 row_ror:8 row_mask:0xf bank_mask:0xf bound_ctrl:1
	v_add_f32_dpp v192, v192, v192 row_ror:8 row_mask:0xf bank_mask:0xf bound_ctrl:1
	s_waitcnt lgkmcnt(4)
	v_pk_mul_f32 v[194:195], v[122:123], v[118:119] op_sel_hi:[0,1]
	v_add_f32_dpp v190, v190, v190 row_ror:4 row_mask:0xf bank_mask:0xf bound_ctrl:1
	v_add_f32_dpp v192, v192, v192 row_ror:4 row_mask:0xf bank_mask:0xf bound_ctrl:1
	v_pk_mul_f32 v[196:197], v[122:123], v[120:121] op_sel_hi:[0,1]
	v_add_f32_dpp v190, v190, v190 row_ror:2 row_mask:0xf bank_mask:0xf bound_ctrl:1
	v_add_f32_dpp v192, v192, v192 row_ror:2 row_mask:0xf bank_mask:0xf bound_ctrl:1
	v_pk_mul_f32 v[198:199], v[122:123], v[118:119] op_sel:[1,0] op_sel_hi:[1,1]
	v_add_f32_dpp v190, v190, v190 row_ror:1 row_mask:0xf bank_mask:0xf bound_ctrl:1
	v_add_f32_dpp v192, v192, v192 row_ror:1 row_mask:0xf bank_mask:0xf bound_ctrl:1
	v_pk_mul_f32 v[152:153], v[122:123], v[120:121] op_sel:[1,0] op_sel_hi:[1,1]
	ds_read_b32 v122, v182 offset:43136
	ds_read_b32 v123, v182 offset:43200
	ds_read_b128 v[118:121], v134 offset:35072
	s_waitcnt lgkmcnt(5)
	v_pk_fma_f32 v[194:195], v[190:191], v[114:115], v[194:195] op_sel_hi:[0,1,1]
	v_pk_fma_f32 v[198:199], v[192:193], v[114:115], v[198:199] op_sel_hi:[0,1,1]
	v_pk_fma_f32 v[196:197], v[190:191], v[116:117], v[196:197] op_sel_hi:[0,1,1]
	v_pk_fma_f32 v[152:153], v[192:193], v[116:117], v[152:153] op_sel_hi:[0,1,1]
	v_pk_fma_f32 v[84:85], v[84:85], v[110:111], v[194:195]
	v_pk_fma_f32 v[148:149], v[148:149], v[110:111], v[198:199]
	v_pk_fma_f32 v[86:87], v[86:87], v[112:113], v[196:197]
	v_pk_fma_f32 v[150:151], v[150:151], v[112:113], v[152:153]
	ds_read_b128 v[110:113], v134 offset:22784
	ds_read_b128 v[114:117], v134 offset:30976
	s_waitcnt lgkmcnt(6)
	v_pk_mul_f32 v[194:195], v[84:85], v[186:187]
	v_pk_mul_f32 v[196:197], v[148:149], v[186:187]
	v_pk_fma_f32 v[194:195], v[86:87], v[188:189], v[194:195]
	v_pk_fma_f32 v[196:197], v[150:151], v[188:189], v[196:197]
	v_add_f32_e32 v194, v194, v195
	v_add_f32_e32 v196, v196, v197
	ds_read_b128 v[186:189], v134 offset:39168
	v_add_f32_dpp v194, v194, v194 row_ror:8 row_mask:0xf bank_mask:0xf bound_ctrl:1
	v_add_f32_dpp v196, v196, v196 row_ror:8 row_mask:0xf bank_mask:0xf bound_ctrl:1
	s_waitcnt lgkmcnt(6)
	v_pk_mul_f32 v[190:191], v[84:85], v[106:107]
	v_pk_mul_f32 v[192:193], v[148:149], v[106:107]
	v_add_f32_dpp v194, v194, v194 row_ror:4 row_mask:0xf bank_mask:0xf bound_ctrl:1
	v_add_f32_dpp v196, v196, v196 row_ror:4 row_mask:0xf bank_mask:0xf bound_ctrl:1
	v_pk_fma_f32 v[190:191], v[86:87], v[108:109], v[190:191]
	v_pk_fma_f32 v[192:193], v[150:151], v[108:109], v[192:193]
	v_add_f32_dpp v194, v194, v194 row_ror:2 row_mask:0xf bank_mask:0xf bound_ctrl:1
	v_add_f32_dpp v196, v196, v196 row_ror:2 row_mask:0xf bank_mask:0xf bound_ctrl:1
	v_add_f32_e32 v190, v190, v191
	v_add_f32_dpp v194, v194, v194 row_ror:1 row_mask:0xf bank_mask:0xf bound_ctrl:1
	v_add_f32_dpp v196, v196, v196 row_ror:1 row_mask:0xf bank_mask:0xf bound_ctrl:1
	v_add_f32_e32 v192, v192, v193
	ds_write_b32 v182, v194 offset:47104
	ds_write_b32 v182, v196 offset:47168
	ds_read_b128 v[102:105], v134 offset:27136
	v_add_f32_dpp v190, v190, v190 row_ror:8 row_mask:0xf bank_mask:0xf bound_ctrl:1
	v_add_f32_dpp v192, v192, v192 row_ror:8 row_mask:0xf bank_mask:0xf bound_ctrl:1
	s_waitcnt lgkmcnt(6)
	v_pk_mul_f32 v[194:195], v[122:123], v[118:119] op_sel_hi:[0,1]
	v_add_f32_dpp v190, v190, v190 row_ror:4 row_mask:0xf bank_mask:0xf bound_ctrl:1
	v_add_f32_dpp v192, v192, v192 row_ror:4 row_mask:0xf bank_mask:0xf bound_ctrl:1
	v_pk_mul_f32 v[196:197], v[122:123], v[120:121] op_sel_hi:[0,1]
	v_add_f32_dpp v190, v190, v190 row_ror:2 row_mask:0xf bank_mask:0xf bound_ctrl:1
	v_add_f32_dpp v192, v192, v192 row_ror:2 row_mask:0xf bank_mask:0xf bound_ctrl:1
	v_pk_mul_f32 v[198:199], v[122:123], v[118:119] op_sel:[1,0] op_sel_hi:[1,1]
	v_add_f32_dpp v190, v190, v190 row_ror:1 row_mask:0xf bank_mask:0xf bound_ctrl:1
	v_add_f32_dpp v192, v192, v192 row_ror:1 row_mask:0xf bank_mask:0xf bound_ctrl:1
	v_pk_mul_f32 v[152:153], v[122:123], v[120:121] op_sel:[1,0] op_sel_hi:[1,1]
	ds_read_b32 v122, v182 offset:43264
	ds_read_b32 v123, v182 offset:43328
	ds_read_b128 v[118:121], v134 offset:35328
	s_waitcnt lgkmcnt(7)
	v_pk_fma_f32 v[194:195], v[190:191], v[114:115], v[194:195] op_sel_hi:[0,1,1]
	v_pk_fma_f32 v[198:199], v[192:193], v[114:115], v[198:199] op_sel_hi:[0,1,1]
	v_pk_fma_f32 v[196:197], v[190:191], v[116:117], v[196:197] op_sel_hi:[0,1,1]
	v_pk_fma_f32 v[152:153], v[192:193], v[116:117], v[152:153] op_sel_hi:[0,1,1]
	v_pk_fma_f32 v[84:85], v[84:85], v[110:111], v[194:195]
	v_pk_fma_f32 v[148:149], v[148:149], v[110:111], v[198:199]
	v_pk_fma_f32 v[86:87], v[86:87], v[112:113], v[196:197]
	v_pk_fma_f32 v[150:151], v[150:151], v[112:113], v[152:153]
	ds_read_b128 v[110:113], v134 offset:23040
	ds_read_b128 v[114:117], v134 offset:31232
	s_waitcnt lgkmcnt(8)
	v_pk_mul_f32 v[194:195], v[84:85], v[186:187]
	v_pk_mul_f32 v[196:197], v[148:149], v[186:187]
	v_pk_fma_f32 v[194:195], v[86:87], v[188:189], v[194:195]
	v_pk_fma_f32 v[196:197], v[150:151], v[188:189], v[196:197]
	v_add_f32_e32 v194, v194, v195
	v_add_f32_e32 v196, v196, v197
	ds_read_b128 v[186:189], v134 offset:39424
	v_add_f32_dpp v194, v194, v194 row_ror:8 row_mask:0xf bank_mask:0xf bound_ctrl:1
	v_add_f32_dpp v196, v196, v196 row_ror:8 row_mask:0xf bank_mask:0xf bound_ctrl:1
	s_waitcnt lgkmcnt(6)
	v_pk_mul_f32 v[190:191], v[84:85], v[102:103]
	v_pk_mul_f32 v[192:193], v[148:149], v[102:103]
	v_add_f32_dpp v194, v194, v194 row_ror:4 row_mask:0xf bank_mask:0xf bound_ctrl:1
	v_add_f32_dpp v196, v196, v196 row_ror:4 row_mask:0xf bank_mask:0xf bound_ctrl:1
	v_pk_fma_f32 v[190:191], v[86:87], v[104:105], v[190:191]
	v_pk_fma_f32 v[192:193], v[150:151], v[104:105], v[192:193]
	v_add_f32_dpp v194, v194, v194 row_ror:2 row_mask:0xf bank_mask:0xf bound_ctrl:1
	v_add_f32_dpp v196, v196, v196 row_ror:2 row_mask:0xf bank_mask:0xf bound_ctrl:1
	v_add_f32_e32 v190, v190, v191
	v_add_f32_dpp v194, v194, v194 row_ror:1 row_mask:0xf bank_mask:0xf bound_ctrl:1
	v_add_f32_dpp v196, v196, v196 row_ror:1 row_mask:0xf bank_mask:0xf bound_ctrl:1
	v_add_f32_e32 v192, v192, v193
	ds_write_b32 v182, v194 offset:47232
	ds_write_b32 v182, v196 offset:47296
	ds_read_b128 v[106:109], v134 offset:27392
	v_add_f32_dpp v190, v190, v190 row_ror:8 row_mask:0xf bank_mask:0xf bound_ctrl:1
	v_add_f32_dpp v192, v192, v192 row_ror:8 row_mask:0xf bank_mask:0xf bound_ctrl:1
	s_waitcnt lgkmcnt(6)
	v_pk_mul_f32 v[194:195], v[122:123], v[118:119] op_sel_hi:[0,1]
	v_add_f32_dpp v190, v190, v190 row_ror:4 row_mask:0xf bank_mask:0xf bound_ctrl:1
	v_add_f32_dpp v192, v192, v192 row_ror:4 row_mask:0xf bank_mask:0xf bound_ctrl:1
	v_pk_mul_f32 v[196:197], v[122:123], v[120:121] op_sel_hi:[0,1]
	v_add_f32_dpp v190, v190, v190 row_ror:2 row_mask:0xf bank_mask:0xf bound_ctrl:1
	v_add_f32_dpp v192, v192, v192 row_ror:2 row_mask:0xf bank_mask:0xf bound_ctrl:1
	v_pk_mul_f32 v[198:199], v[122:123], v[118:119] op_sel:[1,0] op_sel_hi:[1,1]
	v_add_f32_dpp v190, v190, v190 row_ror:1 row_mask:0xf bank_mask:0xf bound_ctrl:1
	v_add_f32_dpp v192, v192, v192 row_ror:1 row_mask:0xf bank_mask:0xf bound_ctrl:1
	v_pk_mul_f32 v[152:153], v[122:123], v[120:121] op_sel:[1,0] op_sel_hi:[1,1]
	ds_read_b32 v122, v182 offset:43392
	ds_read_b32 v123, v182 offset:43456
	ds_read_b128 v[118:121], v134 offset:35584
	s_waitcnt lgkmcnt(7)
	v_pk_fma_f32 v[194:195], v[190:191], v[114:115], v[194:195] op_sel_hi:[0,1,1]
	v_pk_fma_f32 v[198:199], v[192:193], v[114:115], v[198:199] op_sel_hi:[0,1,1]
	v_pk_fma_f32 v[196:197], v[190:191], v[116:117], v[196:197] op_sel_hi:[0,1,1]
	v_pk_fma_f32 v[152:153], v[192:193], v[116:117], v[152:153] op_sel_hi:[0,1,1]
	v_pk_fma_f32 v[84:85], v[84:85], v[110:111], v[194:195]
	v_pk_fma_f32 v[148:149], v[148:149], v[110:111], v[198:199]
	v_pk_fma_f32 v[86:87], v[86:87], v[112:113], v[196:197]
	v_pk_fma_f32 v[150:151], v[150:151], v[112:113], v[152:153]
	ds_read_b128 v[110:113], v134 offset:23296
	ds_read_b128 v[114:117], v134 offset:31488
	s_waitcnt lgkmcnt(8)
	v_pk_mul_f32 v[194:195], v[84:85], v[186:187]
	v_pk_mul_f32 v[196:197], v[148:149], v[186:187]
	v_pk_fma_f32 v[194:195], v[86:87], v[188:189], v[194:195]
	v_pk_fma_f32 v[196:197], v[150:151], v[188:189], v[196:197]
	v_add_f32_e32 v194, v194, v195
	v_add_f32_e32 v196, v196, v197
	ds_read_b128 v[186:189], v134 offset:39680
	v_add_f32_dpp v194, v194, v194 row_ror:8 row_mask:0xf bank_mask:0xf bound_ctrl:1
	v_add_f32_dpp v196, v196, v196 row_ror:8 row_mask:0xf bank_mask:0xf bound_ctrl:1
	s_waitcnt lgkmcnt(6)
	v_pk_mul_f32 v[190:191], v[84:85], v[106:107]
	v_pk_mul_f32 v[192:193], v[148:149], v[106:107]
	v_add_f32_dpp v194, v194, v194 row_ror:4 row_mask:0xf bank_mask:0xf bound_ctrl:1
	v_add_f32_dpp v196, v196, v196 row_ror:4 row_mask:0xf bank_mask:0xf bound_ctrl:1
	v_pk_fma_f32 v[190:191], v[86:87], v[108:109], v[190:191]
	v_pk_fma_f32 v[192:193], v[150:151], v[108:109], v[192:193]
	v_add_f32_dpp v194, v194, v194 row_ror:2 row_mask:0xf bank_mask:0xf bound_ctrl:1
	v_add_f32_dpp v196, v196, v196 row_ror:2 row_mask:0xf bank_mask:0xf bound_ctrl:1
	v_add_f32_e32 v190, v190, v191
	v_add_f32_dpp v194, v194, v194 row_ror:1 row_mask:0xf bank_mask:0xf bound_ctrl:1
	v_add_f32_dpp v196, v196, v196 row_ror:1 row_mask:0xf bank_mask:0xf bound_ctrl:1
	v_add_f32_e32 v192, v192, v193
	ds_write_b32 v182, v194 offset:47360
	ds_write_b32 v182, v196 offset:47424
	ds_read_b128 v[102:105], v134 offset:27648
	v_add_f32_dpp v190, v190, v190 row_ror:8 row_mask:0xf bank_mask:0xf bound_ctrl:1
	v_add_f32_dpp v192, v192, v192 row_ror:8 row_mask:0xf bank_mask:0xf bound_ctrl:1
	s_waitcnt lgkmcnt(6)
	v_pk_mul_f32 v[194:195], v[122:123], v[118:119] op_sel_hi:[0,1]
	v_add_f32_dpp v190, v190, v190 row_ror:4 row_mask:0xf bank_mask:0xf bound_ctrl:1
	v_add_f32_dpp v192, v192, v192 row_ror:4 row_mask:0xf bank_mask:0xf bound_ctrl:1
	v_pk_mul_f32 v[196:197], v[122:123], v[120:121] op_sel_hi:[0,1]
	v_add_f32_dpp v190, v190, v190 row_ror:2 row_mask:0xf bank_mask:0xf bound_ctrl:1
	v_add_f32_dpp v192, v192, v192 row_ror:2 row_mask:0xf bank_mask:0xf bound_ctrl:1
	v_pk_mul_f32 v[198:199], v[122:123], v[118:119] op_sel:[1,0] op_sel_hi:[1,1]
	v_add_f32_dpp v190, v190, v190 row_ror:1 row_mask:0xf bank_mask:0xf bound_ctrl:1
	v_add_f32_dpp v192, v192, v192 row_ror:1 row_mask:0xf bank_mask:0xf bound_ctrl:1
	v_pk_mul_f32 v[152:153], v[122:123], v[120:121] op_sel:[1,0] op_sel_hi:[1,1]
	ds_read_b32 v122, v182 offset:43520
	ds_read_b32 v123, v182 offset:43584
	ds_read_b128 v[118:121], v134 offset:35840
	s_waitcnt lgkmcnt(7)
	v_pk_fma_f32 v[194:195], v[190:191], v[114:115], v[194:195] op_sel_hi:[0,1,1]
	v_pk_fma_f32 v[198:199], v[192:193], v[114:115], v[198:199] op_sel_hi:[0,1,1]
	v_pk_fma_f32 v[196:197], v[190:191], v[116:117], v[196:197] op_sel_hi:[0,1,1]
	v_pk_fma_f32 v[152:153], v[192:193], v[116:117], v[152:153] op_sel_hi:[0,1,1]
	v_pk_fma_f32 v[84:85], v[84:85], v[110:111], v[194:195]
	v_pk_fma_f32 v[148:149], v[148:149], v[110:111], v[198:199]
	v_pk_fma_f32 v[86:87], v[86:87], v[112:113], v[196:197]
	v_pk_fma_f32 v[150:151], v[150:151], v[112:113], v[152:153]
	ds_read_b128 v[110:113], v134 offset:23552
	ds_read_b128 v[114:117], v134 offset:31744
	s_waitcnt lgkmcnt(8)
	v_pk_mul_f32 v[194:195], v[84:85], v[186:187]
	v_pk_mul_f32 v[196:197], v[148:149], v[186:187]
	v_pk_fma_f32 v[194:195], v[86:87], v[188:189], v[194:195]
	v_pk_fma_f32 v[196:197], v[150:151], v[188:189], v[196:197]
	v_add_f32_e32 v194, v194, v195
	v_add_f32_e32 v196, v196, v197
	ds_read_b128 v[186:189], v134 offset:39936
	v_add_f32_dpp v194, v194, v194 row_ror:8 row_mask:0xf bank_mask:0xf bound_ctrl:1
	v_add_f32_dpp v196, v196, v196 row_ror:8 row_mask:0xf bank_mask:0xf bound_ctrl:1
	s_waitcnt lgkmcnt(6)
	v_pk_mul_f32 v[190:191], v[84:85], v[102:103]
	v_pk_mul_f32 v[192:193], v[148:149], v[102:103]
	v_add_f32_dpp v194, v194, v194 row_ror:4 row_mask:0xf bank_mask:0xf bound_ctrl:1
	v_add_f32_dpp v196, v196, v196 row_ror:4 row_mask:0xf bank_mask:0xf bound_ctrl:1
	v_pk_fma_f32 v[190:191], v[86:87], v[104:105], v[190:191]
	v_pk_fma_f32 v[192:193], v[150:151], v[104:105], v[192:193]
	v_add_f32_dpp v194, v194, v194 row_ror:2 row_mask:0xf bank_mask:0xf bound_ctrl:1
	v_add_f32_dpp v196, v196, v196 row_ror:2 row_mask:0xf bank_mask:0xf bound_ctrl:1
	v_add_f32_e32 v190, v190, v191
	v_add_f32_dpp v194, v194, v194 row_ror:1 row_mask:0xf bank_mask:0xf bound_ctrl:1
	v_add_f32_dpp v196, v196, v196 row_ror:1 row_mask:0xf bank_mask:0xf bound_ctrl:1
	v_add_f32_e32 v192, v192, v193
	ds_write_b32 v182, v194 offset:47488
	ds_write_b32 v182, v196 offset:47552
	ds_read_b128 v[106:109], v134 offset:27904
	v_add_f32_dpp v190, v190, v190 row_ror:8 row_mask:0xf bank_mask:0xf bound_ctrl:1
	v_add_f32_dpp v192, v192, v192 row_ror:8 row_mask:0xf bank_mask:0xf bound_ctrl:1
	s_waitcnt lgkmcnt(6)
	v_pk_mul_f32 v[194:195], v[122:123], v[118:119] op_sel_hi:[0,1]
	v_add_f32_dpp v190, v190, v190 row_ror:4 row_mask:0xf bank_mask:0xf bound_ctrl:1
	v_add_f32_dpp v192, v192, v192 row_ror:4 row_mask:0xf bank_mask:0xf bound_ctrl:1
	v_pk_mul_f32 v[196:197], v[122:123], v[120:121] op_sel_hi:[0,1]
	v_add_f32_dpp v190, v190, v190 row_ror:2 row_mask:0xf bank_mask:0xf bound_ctrl:1
	v_add_f32_dpp v192, v192, v192 row_ror:2 row_mask:0xf bank_mask:0xf bound_ctrl:1
	v_pk_mul_f32 v[198:199], v[122:123], v[118:119] op_sel:[1,0] op_sel_hi:[1,1]
	v_add_f32_dpp v190, v190, v190 row_ror:1 row_mask:0xf bank_mask:0xf bound_ctrl:1
	v_add_f32_dpp v192, v192, v192 row_ror:1 row_mask:0xf bank_mask:0xf bound_ctrl:1
	v_pk_mul_f32 v[152:153], v[122:123], v[120:121] op_sel:[1,0] op_sel_hi:[1,1]
	ds_read_b32 v122, v182 offset:43648
	ds_read_b32 v123, v182 offset:43712
	ds_read_b128 v[118:121], v134 offset:36096
	s_waitcnt lgkmcnt(7)
	v_pk_fma_f32 v[194:195], v[190:191], v[114:115], v[194:195] op_sel_hi:[0,1,1]
	v_pk_fma_f32 v[198:199], v[192:193], v[114:115], v[198:199] op_sel_hi:[0,1,1]
	v_pk_fma_f32 v[196:197], v[190:191], v[116:117], v[196:197] op_sel_hi:[0,1,1]
	v_pk_fma_f32 v[152:153], v[192:193], v[116:117], v[152:153] op_sel_hi:[0,1,1]
	v_pk_fma_f32 v[84:85], v[84:85], v[110:111], v[194:195]
	v_pk_fma_f32 v[148:149], v[148:149], v[110:111], v[198:199]
	v_pk_fma_f32 v[86:87], v[86:87], v[112:113], v[196:197]
	v_pk_fma_f32 v[150:151], v[150:151], v[112:113], v[152:153]
	ds_read_b128 v[110:113], v134 offset:23808
	ds_read_b128 v[114:117], v134 offset:32000
	s_waitcnt lgkmcnt(8)
	v_pk_mul_f32 v[194:195], v[84:85], v[186:187]
	v_pk_mul_f32 v[196:197], v[148:149], v[186:187]
	v_pk_fma_f32 v[194:195], v[86:87], v[188:189], v[194:195]
	v_pk_fma_f32 v[196:197], v[150:151], v[188:189], v[196:197]
	v_add_f32_e32 v194, v194, v195
	v_add_f32_e32 v196, v196, v197
	ds_read_b128 v[186:189], v134 offset:40192
	v_add_f32_dpp v194, v194, v194 row_ror:8 row_mask:0xf bank_mask:0xf bound_ctrl:1
	v_add_f32_dpp v196, v196, v196 row_ror:8 row_mask:0xf bank_mask:0xf bound_ctrl:1
	s_waitcnt lgkmcnt(6)
	v_pk_mul_f32 v[190:191], v[84:85], v[106:107]
	v_pk_mul_f32 v[192:193], v[148:149], v[106:107]
	v_add_f32_dpp v194, v194, v194 row_ror:4 row_mask:0xf bank_mask:0xf bound_ctrl:1
	v_add_f32_dpp v196, v196, v196 row_ror:4 row_mask:0xf bank_mask:0xf bound_ctrl:1
	v_pk_fma_f32 v[190:191], v[86:87], v[108:109], v[190:191]
	v_pk_fma_f32 v[192:193], v[150:151], v[108:109], v[192:193]
	v_add_f32_dpp v194, v194, v194 row_ror:2 row_mask:0xf bank_mask:0xf bound_ctrl:1
	v_add_f32_dpp v196, v196, v196 row_ror:2 row_mask:0xf bank_mask:0xf bound_ctrl:1
	v_add_f32_e32 v190, v190, v191
	v_add_f32_dpp v194, v194, v194 row_ror:1 row_mask:0xf bank_mask:0xf bound_ctrl:1
	v_add_f32_dpp v196, v196, v196 row_ror:1 row_mask:0xf bank_mask:0xf bound_ctrl:1
	v_add_f32_e32 v192, v192, v193
	ds_write_b32 v182, v194 offset:47616
	ds_write_b32 v182, v196 offset:47680
	ds_read_b128 v[102:105], v134 offset:28160
	v_add_f32_dpp v190, v190, v190 row_ror:8 row_mask:0xf bank_mask:0xf bound_ctrl:1
	v_add_f32_dpp v192, v192, v192 row_ror:8 row_mask:0xf bank_mask:0xf bound_ctrl:1
	s_waitcnt lgkmcnt(6)
	v_pk_mul_f32 v[194:195], v[122:123], v[118:119] op_sel_hi:[0,1]
	v_add_f32_dpp v190, v190, v190 row_ror:4 row_mask:0xf bank_mask:0xf bound_ctrl:1
	v_add_f32_dpp v192, v192, v192 row_ror:4 row_mask:0xf bank_mask:0xf bound_ctrl:1
	v_pk_mul_f32 v[196:197], v[122:123], v[120:121] op_sel_hi:[0,1]
	v_add_f32_dpp v190, v190, v190 row_ror:2 row_mask:0xf bank_mask:0xf bound_ctrl:1
	v_add_f32_dpp v192, v192, v192 row_ror:2 row_mask:0xf bank_mask:0xf bound_ctrl:1
	v_pk_mul_f32 v[198:199], v[122:123], v[118:119] op_sel:[1,0] op_sel_hi:[1,1]
	v_add_f32_dpp v190, v190, v190 row_ror:1 row_mask:0xf bank_mask:0xf bound_ctrl:1
	v_add_f32_dpp v192, v192, v192 row_ror:1 row_mask:0xf bank_mask:0xf bound_ctrl:1
	v_pk_mul_f32 v[152:153], v[122:123], v[120:121] op_sel:[1,0] op_sel_hi:[1,1]
	ds_read_b32 v122, v182 offset:43776
	ds_read_b32 v123, v182 offset:43840
	ds_read_b128 v[118:121], v134 offset:36352
	s_waitcnt lgkmcnt(7)
	v_pk_fma_f32 v[194:195], v[190:191], v[114:115], v[194:195] op_sel_hi:[0,1,1]
	v_pk_fma_f32 v[198:199], v[192:193], v[114:115], v[198:199] op_sel_hi:[0,1,1]
	v_pk_fma_f32 v[196:197], v[190:191], v[116:117], v[196:197] op_sel_hi:[0,1,1]
	v_pk_fma_f32 v[152:153], v[192:193], v[116:117], v[152:153] op_sel_hi:[0,1,1]
	v_pk_fma_f32 v[84:85], v[84:85], v[110:111], v[194:195]
	v_pk_fma_f32 v[148:149], v[148:149], v[110:111], v[198:199]
	v_pk_fma_f32 v[86:87], v[86:87], v[112:113], v[196:197]
	v_pk_fma_f32 v[150:151], v[150:151], v[112:113], v[152:153]
	ds_read_b128 v[110:113], v134 offset:24064
	ds_read_b128 v[114:117], v134 offset:32256
	s_waitcnt lgkmcnt(8)
	v_pk_mul_f32 v[194:195], v[84:85], v[186:187]
	v_pk_mul_f32 v[196:197], v[148:149], v[186:187]
	v_pk_fma_f32 v[194:195], v[86:87], v[188:189], v[194:195]
	v_pk_fma_f32 v[196:197], v[150:151], v[188:189], v[196:197]
	v_add_f32_e32 v194, v194, v195
	v_add_f32_e32 v196, v196, v197
	ds_read_b128 v[186:189], v134 offset:40448
	v_add_f32_dpp v194, v194, v194 row_ror:8 row_mask:0xf bank_mask:0xf bound_ctrl:1
	v_add_f32_dpp v196, v196, v196 row_ror:8 row_mask:0xf bank_mask:0xf bound_ctrl:1
	s_waitcnt lgkmcnt(6)
	v_pk_mul_f32 v[190:191], v[84:85], v[102:103]
	v_pk_mul_f32 v[192:193], v[148:149], v[102:103]
	v_add_f32_dpp v194, v194, v194 row_ror:4 row_mask:0xf bank_mask:0xf bound_ctrl:1
	v_add_f32_dpp v196, v196, v196 row_ror:4 row_mask:0xf bank_mask:0xf bound_ctrl:1
	v_pk_fma_f32 v[190:191], v[86:87], v[104:105], v[190:191]
	v_pk_fma_f32 v[192:193], v[150:151], v[104:105], v[192:193]
	v_add_f32_dpp v194, v194, v194 row_ror:2 row_mask:0xf bank_mask:0xf bound_ctrl:1
	v_add_f32_dpp v196, v196, v196 row_ror:2 row_mask:0xf bank_mask:0xf bound_ctrl:1
	v_add_f32_e32 v190, v190, v191
	v_add_f32_dpp v194, v194, v194 row_ror:1 row_mask:0xf bank_mask:0xf bound_ctrl:1
	v_add_f32_dpp v196, v196, v196 row_ror:1 row_mask:0xf bank_mask:0xf bound_ctrl:1
	v_add_f32_e32 v192, v192, v193
	ds_write_b32 v182, v194 offset:47744
	ds_write_b32 v182, v196 offset:47808
	ds_read_b128 v[106:109], v134 offset:28416
	v_add_f32_dpp v190, v190, v190 row_ror:8 row_mask:0xf bank_mask:0xf bound_ctrl:1
	v_add_f32_dpp v192, v192, v192 row_ror:8 row_mask:0xf bank_mask:0xf bound_ctrl:1
	s_waitcnt lgkmcnt(6)
	v_pk_mul_f32 v[194:195], v[122:123], v[118:119] op_sel_hi:[0,1]
	v_add_f32_dpp v190, v190, v190 row_ror:4 row_mask:0xf bank_mask:0xf bound_ctrl:1
	v_add_f32_dpp v192, v192, v192 row_ror:4 row_mask:0xf bank_mask:0xf bound_ctrl:1
	v_pk_mul_f32 v[196:197], v[122:123], v[120:121] op_sel_hi:[0,1]
	v_add_f32_dpp v190, v190, v190 row_ror:2 row_mask:0xf bank_mask:0xf bound_ctrl:1
	v_add_f32_dpp v192, v192, v192 row_ror:2 row_mask:0xf bank_mask:0xf bound_ctrl:1
	v_pk_mul_f32 v[198:199], v[122:123], v[118:119] op_sel:[1,0] op_sel_hi:[1,1]
	v_add_f32_dpp v190, v190, v190 row_ror:1 row_mask:0xf bank_mask:0xf bound_ctrl:1
	v_add_f32_dpp v192, v192, v192 row_ror:1 row_mask:0xf bank_mask:0xf bound_ctrl:1
	v_pk_mul_f32 v[152:153], v[122:123], v[120:121] op_sel:[1,0] op_sel_hi:[1,1]
	ds_read_b32 v122, v182 offset:43904
	ds_read_b32 v123, v182 offset:43968
	ds_read_b128 v[118:121], v134 offset:36608
	s_waitcnt lgkmcnt(7)
	v_pk_fma_f32 v[194:195], v[190:191], v[114:115], v[194:195] op_sel_hi:[0,1,1]
	v_pk_fma_f32 v[198:199], v[192:193], v[114:115], v[198:199] op_sel_hi:[0,1,1]
	v_pk_fma_f32 v[196:197], v[190:191], v[116:117], v[196:197] op_sel_hi:[0,1,1]
	v_pk_fma_f32 v[152:153], v[192:193], v[116:117], v[152:153] op_sel_hi:[0,1,1]
	v_pk_fma_f32 v[84:85], v[84:85], v[110:111], v[194:195]
	v_pk_fma_f32 v[148:149], v[148:149], v[110:111], v[198:199]
	v_pk_fma_f32 v[86:87], v[86:87], v[112:113], v[196:197]
	v_pk_fma_f32 v[150:151], v[150:151], v[112:113], v[152:153]
	ds_read_b128 v[110:113], v134 offset:24320
	ds_read_b128 v[114:117], v134 offset:32512
	s_waitcnt lgkmcnt(8)
	v_pk_mul_f32 v[194:195], v[84:85], v[186:187]
	v_pk_mul_f32 v[196:197], v[148:149], v[186:187]
	v_pk_fma_f32 v[194:195], v[86:87], v[188:189], v[194:195]
	v_pk_fma_f32 v[196:197], v[150:151], v[188:189], v[196:197]
	v_add_f32_e32 v194, v194, v195
	v_add_f32_e32 v196, v196, v197
	ds_read_b128 v[186:189], v134 offset:40704
	v_add_f32_dpp v194, v194, v194 row_ror:8 row_mask:0xf bank_mask:0xf bound_ctrl:1
	v_add_f32_dpp v196, v196, v196 row_ror:8 row_mask:0xf bank_mask:0xf bound_ctrl:1
	s_waitcnt lgkmcnt(6)
	v_pk_mul_f32 v[190:191], v[84:85], v[106:107]
	v_pk_mul_f32 v[192:193], v[148:149], v[106:107]
	v_add_f32_dpp v194, v194, v194 row_ror:4 row_mask:0xf bank_mask:0xf bound_ctrl:1
	v_add_f32_dpp v196, v196, v196 row_ror:4 row_mask:0xf bank_mask:0xf bound_ctrl:1
	v_pk_fma_f32 v[190:191], v[86:87], v[108:109], v[190:191]
	v_pk_fma_f32 v[192:193], v[150:151], v[108:109], v[192:193]
	v_add_f32_dpp v194, v194, v194 row_ror:2 row_mask:0xf bank_mask:0xf bound_ctrl:1
	v_add_f32_dpp v196, v196, v196 row_ror:2 row_mask:0xf bank_mask:0xf bound_ctrl:1
	v_add_f32_e32 v190, v190, v191
	v_add_f32_dpp v194, v194, v194 row_ror:1 row_mask:0xf bank_mask:0xf bound_ctrl:1
	v_add_f32_dpp v196, v196, v196 row_ror:1 row_mask:0xf bank_mask:0xf bound_ctrl:1
	v_add_f32_e32 v192, v192, v193
	ds_write_b32 v182, v194 offset:47872
	ds_write_b32 v182, v196 offset:47936
	ds_read_b128 v[102:105], v134 offset:28672
	v_add_f32_dpp v190, v190, v190 row_ror:8 row_mask:0xf bank_mask:0xf bound_ctrl:1
	v_add_f32_dpp v192, v192, v192 row_ror:8 row_mask:0xf bank_mask:0xf bound_ctrl:1
	s_waitcnt lgkmcnt(6)
	v_pk_mul_f32 v[194:195], v[122:123], v[118:119] op_sel_hi:[0,1]
	v_add_f32_dpp v190, v190, v190 row_ror:4 row_mask:0xf bank_mask:0xf bound_ctrl:1
	v_add_f32_dpp v192, v192, v192 row_ror:4 row_mask:0xf bank_mask:0xf bound_ctrl:1
	v_pk_mul_f32 v[196:197], v[122:123], v[120:121] op_sel_hi:[0,1]
	v_add_f32_dpp v190, v190, v190 row_ror:2 row_mask:0xf bank_mask:0xf bound_ctrl:1
	v_add_f32_dpp v192, v192, v192 row_ror:2 row_mask:0xf bank_mask:0xf bound_ctrl:1
	v_pk_mul_f32 v[198:199], v[122:123], v[118:119] op_sel:[1,0] op_sel_hi:[1,1]
	v_add_f32_dpp v190, v190, v190 row_ror:1 row_mask:0xf bank_mask:0xf bound_ctrl:1
	v_add_f32_dpp v192, v192, v192 row_ror:1 row_mask:0xf bank_mask:0xf bound_ctrl:1
	v_pk_mul_f32 v[152:153], v[122:123], v[120:121] op_sel:[1,0] op_sel_hi:[1,1]
	ds_read_b32 v122, v182 offset:44032
	ds_read_b32 v123, v182 offset:44096
	ds_read_b128 v[118:121], v134 offset:36864
	s_waitcnt lgkmcnt(7)
	v_pk_fma_f32 v[194:195], v[190:191], v[114:115], v[194:195] op_sel_hi:[0,1,1]
	v_pk_fma_f32 v[198:199], v[192:193], v[114:115], v[198:199] op_sel_hi:[0,1,1]
	v_pk_fma_f32 v[196:197], v[190:191], v[116:117], v[196:197] op_sel_hi:[0,1,1]
	v_pk_fma_f32 v[152:153], v[192:193], v[116:117], v[152:153] op_sel_hi:[0,1,1]
	v_pk_fma_f32 v[84:85], v[84:85], v[110:111], v[194:195]
	v_pk_fma_f32 v[148:149], v[148:149], v[110:111], v[198:199]
	v_pk_fma_f32 v[86:87], v[86:87], v[112:113], v[196:197]
	v_pk_fma_f32 v[150:151], v[150:151], v[112:113], v[152:153]
	ds_read_b128 v[110:113], v134 offset:24576
	ds_read_b128 v[114:117], v134 offset:32768
	s_waitcnt lgkmcnt(8)
	v_pk_mul_f32 v[194:195], v[84:85], v[186:187]
	v_pk_mul_f32 v[196:197], v[148:149], v[186:187]
	v_pk_fma_f32 v[194:195], v[86:87], v[188:189], v[194:195]
	v_pk_fma_f32 v[196:197], v[150:151], v[188:189], v[196:197]
	v_add_f32_e32 v194, v194, v195
	v_add_f32_e32 v196, v196, v197
	ds_read_b128 v[186:189], v134 offset:40960
	v_add_f32_dpp v194, v194, v194 row_ror:8 row_mask:0xf bank_mask:0xf bound_ctrl:1
	v_add_f32_dpp v196, v196, v196 row_ror:8 row_mask:0xf bank_mask:0xf bound_ctrl:1
	s_waitcnt lgkmcnt(6)
	v_pk_mul_f32 v[190:191], v[84:85], v[102:103]
	v_pk_mul_f32 v[192:193], v[148:149], v[102:103]
	v_add_f32_dpp v194, v194, v194 row_ror:4 row_mask:0xf bank_mask:0xf bound_ctrl:1
	v_add_f32_dpp v196, v196, v196 row_ror:4 row_mask:0xf bank_mask:0xf bound_ctrl:1
	v_pk_fma_f32 v[190:191], v[86:87], v[104:105], v[190:191]
	v_pk_fma_f32 v[192:193], v[150:151], v[104:105], v[192:193]
	v_add_f32_dpp v194, v194, v194 row_ror:2 row_mask:0xf bank_mask:0xf bound_ctrl:1
	v_add_f32_dpp v196, v196, v196 row_ror:2 row_mask:0xf bank_mask:0xf bound_ctrl:1
	v_add_f32_e32 v190, v190, v191
	v_add_f32_dpp v194, v194, v194 row_ror:1 row_mask:0xf bank_mask:0xf bound_ctrl:1
	v_add_f32_dpp v196, v196, v196 row_ror:1 row_mask:0xf bank_mask:0xf bound_ctrl:1
	v_add_f32_e32 v192, v192, v193
	ds_write_b32 v182, v194 offset:48000
	ds_write_b32 v182, v196 offset:48064
	ds_read_b128 v[106:109], v134 offset:28928
	v_add_f32_dpp v190, v190, v190 row_ror:8 row_mask:0xf bank_mask:0xf bound_ctrl:1
	v_add_f32_dpp v192, v192, v192 row_ror:8 row_mask:0xf bank_mask:0xf bound_ctrl:1
	s_waitcnt lgkmcnt(6)
	v_pk_mul_f32 v[194:195], v[122:123], v[118:119] op_sel_hi:[0,1]
	v_add_f32_dpp v190, v190, v190 row_ror:4 row_mask:0xf bank_mask:0xf bound_ctrl:1
	v_add_f32_dpp v192, v192, v192 row_ror:4 row_mask:0xf bank_mask:0xf bound_ctrl:1
	v_pk_mul_f32 v[196:197], v[122:123], v[120:121] op_sel_hi:[0,1]
	v_add_f32_dpp v190, v190, v190 row_ror:2 row_mask:0xf bank_mask:0xf bound_ctrl:1
	v_add_f32_dpp v192, v192, v192 row_ror:2 row_mask:0xf bank_mask:0xf bound_ctrl:1
	v_pk_mul_f32 v[198:199], v[122:123], v[118:119] op_sel:[1,0] op_sel_hi:[1,1]
	v_add_f32_dpp v190, v190, v190 row_ror:1 row_mask:0xf bank_mask:0xf bound_ctrl:1
	v_add_f32_dpp v192, v192, v192 row_ror:1 row_mask:0xf bank_mask:0xf bound_ctrl:1
	v_pk_mul_f32 v[152:153], v[122:123], v[120:121] op_sel:[1,0] op_sel_hi:[1,1]
	ds_read_b32 v122, v182 offset:44160
	ds_read_b32 v123, v182 offset:44224
	ds_read_b128 v[118:121], v134 offset:37120
	s_waitcnt lgkmcnt(7)
	v_pk_fma_f32 v[194:195], v[190:191], v[114:115], v[194:195] op_sel_hi:[0,1,1]
	v_pk_fma_f32 v[198:199], v[192:193], v[114:115], v[198:199] op_sel_hi:[0,1,1]
	v_pk_fma_f32 v[196:197], v[190:191], v[116:117], v[196:197] op_sel_hi:[0,1,1]
	v_pk_fma_f32 v[152:153], v[192:193], v[116:117], v[152:153] op_sel_hi:[0,1,1]
	v_pk_fma_f32 v[84:85], v[84:85], v[110:111], v[194:195]
	v_pk_fma_f32 v[148:149], v[148:149], v[110:111], v[198:199]
	v_pk_fma_f32 v[86:87], v[86:87], v[112:113], v[196:197]
	v_pk_fma_f32 v[150:151], v[150:151], v[112:113], v[152:153]
	ds_read_b128 v[110:113], v134 offset:24832
	ds_read_b128 v[114:117], v134 offset:33024
	s_waitcnt lgkmcnt(8)
	v_pk_mul_f32 v[194:195], v[84:85], v[186:187]
	v_pk_mul_f32 v[196:197], v[148:149], v[186:187]
	v_pk_fma_f32 v[194:195], v[86:87], v[188:189], v[194:195]
	v_pk_fma_f32 v[196:197], v[150:151], v[188:189], v[196:197]
	v_add_f32_e32 v194, v194, v195
	v_add_f32_e32 v196, v196, v197
	ds_read_b128 v[186:189], v134 offset:41216
	v_add_f32_dpp v194, v194, v194 row_ror:8 row_mask:0xf bank_mask:0xf bound_ctrl:1
	v_add_f32_dpp v196, v196, v196 row_ror:8 row_mask:0xf bank_mask:0xf bound_ctrl:1
	s_waitcnt lgkmcnt(6)
	v_pk_mul_f32 v[190:191], v[84:85], v[106:107]
	v_pk_mul_f32 v[192:193], v[148:149], v[106:107]
	v_add_f32_dpp v194, v194, v194 row_ror:4 row_mask:0xf bank_mask:0xf bound_ctrl:1
	v_add_f32_dpp v196, v196, v196 row_ror:4 row_mask:0xf bank_mask:0xf bound_ctrl:1
	v_pk_fma_f32 v[190:191], v[86:87], v[108:109], v[190:191]
	v_pk_fma_f32 v[192:193], v[150:151], v[108:109], v[192:193]
	v_add_f32_dpp v194, v194, v194 row_ror:2 row_mask:0xf bank_mask:0xf bound_ctrl:1
	v_add_f32_dpp v196, v196, v196 row_ror:2 row_mask:0xf bank_mask:0xf bound_ctrl:1
	v_add_f32_e32 v190, v190, v191
	v_add_f32_dpp v194, v194, v194 row_ror:1 row_mask:0xf bank_mask:0xf bound_ctrl:1
	v_add_f32_dpp v196, v196, v196 row_ror:1 row_mask:0xf bank_mask:0xf bound_ctrl:1
	v_add_f32_e32 v192, v192, v193
	ds_write_b32 v182, v194 offset:48128
	ds_write_b32 v182, v196 offset:48192
	ds_read_b128 v[102:105], v134 offset:29184
	v_add_f32_dpp v190, v190, v190 row_ror:8 row_mask:0xf bank_mask:0xf bound_ctrl:1
	v_add_f32_dpp v192, v192, v192 row_ror:8 row_mask:0xf bank_mask:0xf bound_ctrl:1
	s_waitcnt lgkmcnt(6)
	v_pk_mul_f32 v[194:195], v[122:123], v[118:119] op_sel_hi:[0,1]
	v_add_f32_dpp v190, v190, v190 row_ror:4 row_mask:0xf bank_mask:0xf bound_ctrl:1
	v_add_f32_dpp v192, v192, v192 row_ror:4 row_mask:0xf bank_mask:0xf bound_ctrl:1
	v_pk_mul_f32 v[196:197], v[122:123], v[120:121] op_sel_hi:[0,1]
	v_add_f32_dpp v190, v190, v190 row_ror:2 row_mask:0xf bank_mask:0xf bound_ctrl:1
	v_add_f32_dpp v192, v192, v192 row_ror:2 row_mask:0xf bank_mask:0xf bound_ctrl:1
	v_pk_mul_f32 v[198:199], v[122:123], v[118:119] op_sel:[1,0] op_sel_hi:[1,1]
	v_add_f32_dpp v190, v190, v190 row_ror:1 row_mask:0xf bank_mask:0xf bound_ctrl:1
	v_add_f32_dpp v192, v192, v192 row_ror:1 row_mask:0xf bank_mask:0xf bound_ctrl:1
	v_pk_mul_f32 v[152:153], v[122:123], v[120:121] op_sel:[1,0] op_sel_hi:[1,1]
	ds_read_b32 v122, v182 offset:44288
	ds_read_b32 v123, v182 offset:44352
	ds_read_b128 v[118:121], v134 offset:37376
	s_waitcnt lgkmcnt(7)
	v_pk_fma_f32 v[194:195], v[190:191], v[114:115], v[194:195] op_sel_hi:[0,1,1]
	v_pk_fma_f32 v[198:199], v[192:193], v[114:115], v[198:199] op_sel_hi:[0,1,1]
	v_pk_fma_f32 v[196:197], v[190:191], v[116:117], v[196:197] op_sel_hi:[0,1,1]
	v_pk_fma_f32 v[152:153], v[192:193], v[116:117], v[152:153] op_sel_hi:[0,1,1]
	v_pk_fma_f32 v[84:85], v[84:85], v[110:111], v[194:195]
	v_pk_fma_f32 v[148:149], v[148:149], v[110:111], v[198:199]
	v_pk_fma_f32 v[86:87], v[86:87], v[112:113], v[196:197]
	v_pk_fma_f32 v[150:151], v[150:151], v[112:113], v[152:153]
	ds_read_b128 v[110:113], v134 offset:25088
	ds_read_b128 v[114:117], v134 offset:33280
	s_waitcnt lgkmcnt(8)
	v_pk_mul_f32 v[194:195], v[84:85], v[186:187]
	v_pk_mul_f32 v[196:197], v[148:149], v[186:187]
	v_pk_fma_f32 v[194:195], v[86:87], v[188:189], v[194:195]
	v_pk_fma_f32 v[196:197], v[150:151], v[188:189], v[196:197]
	v_add_f32_e32 v194, v194, v195
	v_add_f32_e32 v196, v196, v197
	ds_read_b128 v[186:189], v134 offset:41472
	v_add_f32_dpp v194, v194, v194 row_ror:8 row_mask:0xf bank_mask:0xf bound_ctrl:1
	v_add_f32_dpp v196, v196, v196 row_ror:8 row_mask:0xf bank_mask:0xf bound_ctrl:1
	s_waitcnt lgkmcnt(6)
	v_pk_mul_f32 v[190:191], v[84:85], v[102:103]
	v_pk_mul_f32 v[192:193], v[148:149], v[102:103]
	v_add_f32_dpp v194, v194, v194 row_ror:4 row_mask:0xf bank_mask:0xf bound_ctrl:1
	v_add_f32_dpp v196, v196, v196 row_ror:4 row_mask:0xf bank_mask:0xf bound_ctrl:1
	v_pk_fma_f32 v[190:191], v[86:87], v[104:105], v[190:191]
	v_pk_fma_f32 v[192:193], v[150:151], v[104:105], v[192:193]
	v_add_f32_dpp v194, v194, v194 row_ror:2 row_mask:0xf bank_mask:0xf bound_ctrl:1
	v_add_f32_dpp v196, v196, v196 row_ror:2 row_mask:0xf bank_mask:0xf bound_ctrl:1
	v_add_f32_e32 v190, v190, v191
	v_add_f32_dpp v194, v194, v194 row_ror:1 row_mask:0xf bank_mask:0xf bound_ctrl:1
	v_add_f32_dpp v196, v196, v196 row_ror:1 row_mask:0xf bank_mask:0xf bound_ctrl:1
	v_add_f32_e32 v192, v192, v193
	ds_write_b32 v182, v194 offset:48256
	ds_write_b32 v182, v196 offset:48320
	ds_read_b128 v[106:109], v134 offset:29440
	v_add_f32_dpp v190, v190, v190 row_ror:8 row_mask:0xf bank_mask:0xf bound_ctrl:1
	v_add_f32_dpp v192, v192, v192 row_ror:8 row_mask:0xf bank_mask:0xf bound_ctrl:1
	s_waitcnt lgkmcnt(6)
	v_pk_mul_f32 v[194:195], v[122:123], v[118:119] op_sel_hi:[0,1]
	v_add_f32_dpp v190, v190, v190 row_ror:4 row_mask:0xf bank_mask:0xf bound_ctrl:1
	v_add_f32_dpp v192, v192, v192 row_ror:4 row_mask:0xf bank_mask:0xf bound_ctrl:1
	v_pk_mul_f32 v[196:197], v[122:123], v[120:121] op_sel_hi:[0,1]
	v_add_f32_dpp v190, v190, v190 row_ror:2 row_mask:0xf bank_mask:0xf bound_ctrl:1
	v_add_f32_dpp v192, v192, v192 row_ror:2 row_mask:0xf bank_mask:0xf bound_ctrl:1
	v_pk_mul_f32 v[198:199], v[122:123], v[118:119] op_sel:[1,0] op_sel_hi:[1,1]
	v_add_f32_dpp v190, v190, v190 row_ror:1 row_mask:0xf bank_mask:0xf bound_ctrl:1
	v_add_f32_dpp v192, v192, v192 row_ror:1 row_mask:0xf bank_mask:0xf bound_ctrl:1
	v_pk_mul_f32 v[152:153], v[122:123], v[120:121] op_sel:[1,0] op_sel_hi:[1,1]
	ds_read_b32 v122, v182 offset:44416
	ds_read_b32 v123, v182 offset:44480
	ds_read_b128 v[118:121], v134 offset:37632
	s_waitcnt lgkmcnt(7)
	v_pk_fma_f32 v[194:195], v[190:191], v[114:115], v[194:195] op_sel_hi:[0,1,1]
	v_pk_fma_f32 v[198:199], v[192:193], v[114:115], v[198:199] op_sel_hi:[0,1,1]
	v_pk_fma_f32 v[196:197], v[190:191], v[116:117], v[196:197] op_sel_hi:[0,1,1]
	v_pk_fma_f32 v[152:153], v[192:193], v[116:117], v[152:153] op_sel_hi:[0,1,1]
	v_pk_fma_f32 v[84:85], v[84:85], v[110:111], v[194:195]
	v_pk_fma_f32 v[148:149], v[148:149], v[110:111], v[198:199]
	v_pk_fma_f32 v[86:87], v[86:87], v[112:113], v[196:197]
	v_pk_fma_f32 v[150:151], v[150:151], v[112:113], v[152:153]
	ds_read_b128 v[110:113], v134 offset:25344
	ds_read_b128 v[114:117], v134 offset:33536
	s_waitcnt lgkmcnt(8)
	v_pk_mul_f32 v[194:195], v[84:85], v[186:187]
	v_pk_mul_f32 v[196:197], v[148:149], v[186:187]
	v_pk_fma_f32 v[194:195], v[86:87], v[188:189], v[194:195]
	v_pk_fma_f32 v[196:197], v[150:151], v[188:189], v[196:197]
	v_add_f32_e32 v194, v194, v195
	v_add_f32_e32 v196, v196, v197
	ds_read_b128 v[186:189], v134 offset:41728
	v_add_f32_dpp v194, v194, v194 row_ror:8 row_mask:0xf bank_mask:0xf bound_ctrl:1
	v_add_f32_dpp v196, v196, v196 row_ror:8 row_mask:0xf bank_mask:0xf bound_ctrl:1
	s_waitcnt lgkmcnt(6)
	v_pk_mul_f32 v[190:191], v[84:85], v[106:107]
	v_pk_mul_f32 v[192:193], v[148:149], v[106:107]
	v_add_f32_dpp v194, v194, v194 row_ror:4 row_mask:0xf bank_mask:0xf bound_ctrl:1
	v_add_f32_dpp v196, v196, v196 row_ror:4 row_mask:0xf bank_mask:0xf bound_ctrl:1
	v_pk_fma_f32 v[190:191], v[86:87], v[108:109], v[190:191]
	v_pk_fma_f32 v[192:193], v[150:151], v[108:109], v[192:193]
	v_add_f32_dpp v194, v194, v194 row_ror:2 row_mask:0xf bank_mask:0xf bound_ctrl:1
	v_add_f32_dpp v196, v196, v196 row_ror:2 row_mask:0xf bank_mask:0xf bound_ctrl:1
	v_add_f32_e32 v190, v190, v191
	v_add_f32_dpp v194, v194, v194 row_ror:1 row_mask:0xf bank_mask:0xf bound_ctrl:1
	v_add_f32_dpp v196, v196, v196 row_ror:1 row_mask:0xf bank_mask:0xf bound_ctrl:1
	v_add_f32_e32 v192, v192, v193
	ds_write_b32 v182, v194 offset:48384
	ds_write_b32 v182, v196 offset:48448
	ds_read_b128 v[102:105], v134 offset:29696
	v_add_f32_dpp v190, v190, v190 row_ror:8 row_mask:0xf bank_mask:0xf bound_ctrl:1
	v_add_f32_dpp v192, v192, v192 row_ror:8 row_mask:0xf bank_mask:0xf bound_ctrl:1
	s_waitcnt lgkmcnt(6)
	v_pk_mul_f32 v[194:195], v[122:123], v[118:119] op_sel_hi:[0,1]
	v_add_f32_dpp v190, v190, v190 row_ror:4 row_mask:0xf bank_mask:0xf bound_ctrl:1
	v_add_f32_dpp v192, v192, v192 row_ror:4 row_mask:0xf bank_mask:0xf bound_ctrl:1
	v_pk_mul_f32 v[196:197], v[122:123], v[120:121] op_sel_hi:[0,1]
	v_add_f32_dpp v190, v190, v190 row_ror:2 row_mask:0xf bank_mask:0xf bound_ctrl:1
	v_add_f32_dpp v192, v192, v192 row_ror:2 row_mask:0xf bank_mask:0xf bound_ctrl:1
	v_pk_mul_f32 v[198:199], v[122:123], v[118:119] op_sel:[1,0] op_sel_hi:[1,1]
	v_add_f32_dpp v190, v190, v190 row_ror:1 row_mask:0xf bank_mask:0xf bound_ctrl:1
	v_add_f32_dpp v192, v192, v192 row_ror:1 row_mask:0xf bank_mask:0xf bound_ctrl:1
	v_pk_mul_f32 v[152:153], v[122:123], v[120:121] op_sel:[1,0] op_sel_hi:[1,1]
	ds_read_b32 v122, v182 offset:44544
	ds_read_b32 v123, v182 offset:44608
	ds_read_b128 v[118:121], v134 offset:37888
	s_waitcnt lgkmcnt(7)
	v_pk_fma_f32 v[194:195], v[190:191], v[114:115], v[194:195] op_sel_hi:[0,1,1]
	v_pk_fma_f32 v[198:199], v[192:193], v[114:115], v[198:199] op_sel_hi:[0,1,1]
	v_pk_fma_f32 v[196:197], v[190:191], v[116:117], v[196:197] op_sel_hi:[0,1,1]
	v_pk_fma_f32 v[152:153], v[192:193], v[116:117], v[152:153] op_sel_hi:[0,1,1]
	v_pk_fma_f32 v[84:85], v[84:85], v[110:111], v[194:195]
	v_pk_fma_f32 v[148:149], v[148:149], v[110:111], v[198:199]
	v_pk_fma_f32 v[86:87], v[86:87], v[112:113], v[196:197]
	v_pk_fma_f32 v[150:151], v[150:151], v[112:113], v[152:153]
	ds_read_b128 v[110:113], v134 offset:25600
	ds_read_b128 v[114:117], v134 offset:33792
	s_waitcnt lgkmcnt(8)
	v_pk_mul_f32 v[194:195], v[84:85], v[186:187]
	v_pk_mul_f32 v[196:197], v[148:149], v[186:187]
	v_pk_fma_f32 v[194:195], v[86:87], v[188:189], v[194:195]
	v_pk_fma_f32 v[196:197], v[150:151], v[188:189], v[196:197]
	v_add_f32_e32 v194, v194, v195
	v_add_f32_e32 v196, v196, v197
	ds_read_b128 v[186:189], v134 offset:41984
	v_add_f32_dpp v194, v194, v194 row_ror:8 row_mask:0xf bank_mask:0xf bound_ctrl:1
	v_add_f32_dpp v196, v196, v196 row_ror:8 row_mask:0xf bank_mask:0xf bound_ctrl:1
	s_waitcnt lgkmcnt(6)
	v_pk_mul_f32 v[190:191], v[84:85], v[102:103]
	v_pk_mul_f32 v[192:193], v[148:149], v[102:103]
	v_add_f32_dpp v194, v194, v194 row_ror:4 row_mask:0xf bank_mask:0xf bound_ctrl:1
	v_add_f32_dpp v196, v196, v196 row_ror:4 row_mask:0xf bank_mask:0xf bound_ctrl:1
	v_pk_fma_f32 v[190:191], v[86:87], v[104:105], v[190:191]
	v_pk_fma_f32 v[192:193], v[150:151], v[104:105], v[192:193]
	v_add_f32_dpp v194, v194, v194 row_ror:2 row_mask:0xf bank_mask:0xf bound_ctrl:1
	v_add_f32_dpp v196, v196, v196 row_ror:2 row_mask:0xf bank_mask:0xf bound_ctrl:1
	v_add_f32_e32 v190, v190, v191
	v_add_f32_dpp v194, v194, v194 row_ror:1 row_mask:0xf bank_mask:0xf bound_ctrl:1
	v_add_f32_dpp v196, v196, v196 row_ror:1 row_mask:0xf bank_mask:0xf bound_ctrl:1
	v_add_f32_e32 v192, v192, v193
	ds_write_b32 v182, v194 offset:48512
	ds_write_b32 v182, v196 offset:48576
	ds_read_b128 v[106:109], v134 offset:29952
	v_add_f32_dpp v190, v190, v190 row_ror:8 row_mask:0xf bank_mask:0xf bound_ctrl:1
	v_add_f32_dpp v192, v192, v192 row_ror:8 row_mask:0xf bank_mask:0xf bound_ctrl:1
	s_waitcnt lgkmcnt(6)
	v_pk_mul_f32 v[194:195], v[122:123], v[118:119] op_sel_hi:[0,1]
	v_add_f32_dpp v190, v190, v190 row_ror:4 row_mask:0xf bank_mask:0xf bound_ctrl:1
	v_add_f32_dpp v192, v192, v192 row_ror:4 row_mask:0xf bank_mask:0xf bound_ctrl:1
	v_pk_mul_f32 v[196:197], v[122:123], v[120:121] op_sel_hi:[0,1]
	v_add_f32_dpp v190, v190, v190 row_ror:2 row_mask:0xf bank_mask:0xf bound_ctrl:1
	v_add_f32_dpp v192, v192, v192 row_ror:2 row_mask:0xf bank_mask:0xf bound_ctrl:1
	v_pk_mul_f32 v[198:199], v[122:123], v[118:119] op_sel:[1,0] op_sel_hi:[1,1]
	v_add_f32_dpp v190, v190, v190 row_ror:1 row_mask:0xf bank_mask:0xf bound_ctrl:1
	v_add_f32_dpp v192, v192, v192 row_ror:1 row_mask:0xf bank_mask:0xf bound_ctrl:1
	v_pk_mul_f32 v[152:153], v[122:123], v[120:121] op_sel:[1,0] op_sel_hi:[1,1]
	ds_read_b32 v122, v182 offset:44672
	ds_read_b32 v123, v182 offset:44736
	ds_read_b128 v[118:121], v134 offset:38144
	s_waitcnt lgkmcnt(7)
	v_pk_fma_f32 v[194:195], v[190:191], v[114:115], v[194:195] op_sel_hi:[0,1,1]
	v_pk_fma_f32 v[198:199], v[192:193], v[114:115], v[198:199] op_sel_hi:[0,1,1]
	v_pk_fma_f32 v[196:197], v[190:191], v[116:117], v[196:197] op_sel_hi:[0,1,1]
	v_pk_fma_f32 v[152:153], v[192:193], v[116:117], v[152:153] op_sel_hi:[0,1,1]
	v_pk_fma_f32 v[84:85], v[84:85], v[110:111], v[194:195]
	v_pk_fma_f32 v[148:149], v[148:149], v[110:111], v[198:199]
	v_pk_fma_f32 v[86:87], v[86:87], v[112:113], v[196:197]
	v_pk_fma_f32 v[150:151], v[150:151], v[112:113], v[152:153]
	ds_read_b128 v[110:113], v134 offset:25856
	ds_read_b128 v[114:117], v134 offset:34048
	s_waitcnt lgkmcnt(8)
	v_pk_mul_f32 v[194:195], v[84:85], v[186:187]
	v_pk_mul_f32 v[196:197], v[148:149], v[186:187]
	v_pk_fma_f32 v[194:195], v[86:87], v[188:189], v[194:195]
	v_pk_fma_f32 v[196:197], v[150:151], v[188:189], v[196:197]
	v_add_f32_e32 v194, v194, v195
	v_add_f32_e32 v196, v196, v197
	ds_read_b128 v[186:189], v134 offset:42240
	v_add_f32_dpp v194, v194, v194 row_ror:8 row_mask:0xf bank_mask:0xf bound_ctrl:1
	v_add_f32_dpp v196, v196, v196 row_ror:8 row_mask:0xf bank_mask:0xf bound_ctrl:1
	s_waitcnt lgkmcnt(6)
	v_pk_mul_f32 v[190:191], v[84:85], v[106:107]
	v_pk_mul_f32 v[192:193], v[148:149], v[106:107]
	v_add_f32_dpp v194, v194, v194 row_ror:4 row_mask:0xf bank_mask:0xf bound_ctrl:1
	v_add_f32_dpp v196, v196, v196 row_ror:4 row_mask:0xf bank_mask:0xf bound_ctrl:1
	v_pk_fma_f32 v[190:191], v[86:87], v[108:109], v[190:191]
	v_pk_fma_f32 v[192:193], v[150:151], v[108:109], v[192:193]
	v_add_f32_dpp v194, v194, v194 row_ror:2 row_mask:0xf bank_mask:0xf bound_ctrl:1
	v_add_f32_dpp v196, v196, v196 row_ror:2 row_mask:0xf bank_mask:0xf bound_ctrl:1
	v_add_f32_e32 v190, v190, v191
	v_add_f32_dpp v194, v194, v194 row_ror:1 row_mask:0xf bank_mask:0xf bound_ctrl:1
	v_add_f32_dpp v196, v196, v196 row_ror:1 row_mask:0xf bank_mask:0xf bound_ctrl:1
	v_add_f32_e32 v192, v192, v193
	ds_write_b32 v182, v194 offset:48640
	ds_write_b32 v182, v196 offset:48704
	ds_read_b128 v[102:105], v134 offset:30208
	v_add_f32_dpp v190, v190, v190 row_ror:8 row_mask:0xf bank_mask:0xf bound_ctrl:1
	v_add_f32_dpp v192, v192, v192 row_ror:8 row_mask:0xf bank_mask:0xf bound_ctrl:1
	s_waitcnt lgkmcnt(6)
	v_pk_mul_f32 v[194:195], v[122:123], v[118:119] op_sel_hi:[0,1]
	v_add_f32_dpp v190, v190, v190 row_ror:4 row_mask:0xf bank_mask:0xf bound_ctrl:1
	v_add_f32_dpp v192, v192, v192 row_ror:4 row_mask:0xf bank_mask:0xf bound_ctrl:1
	v_pk_mul_f32 v[196:197], v[122:123], v[120:121] op_sel_hi:[0,1]
	v_add_f32_dpp v190, v190, v190 row_ror:2 row_mask:0xf bank_mask:0xf bound_ctrl:1
	v_add_f32_dpp v192, v192, v192 row_ror:2 row_mask:0xf bank_mask:0xf bound_ctrl:1
	v_pk_mul_f32 v[198:199], v[122:123], v[118:119] op_sel:[1,0] op_sel_hi:[1,1]
	v_add_f32_dpp v190, v190, v190 row_ror:1 row_mask:0xf bank_mask:0xf bound_ctrl:1
	v_add_f32_dpp v192, v192, v192 row_ror:1 row_mask:0xf bank_mask:0xf bound_ctrl:1
	v_pk_mul_f32 v[152:153], v[122:123], v[120:121] op_sel:[1,0] op_sel_hi:[1,1]
	ds_read_b32 v122, v182 offset:44800
	ds_read_b32 v123, v182 offset:44864
	ds_read_b128 v[118:121], v134 offset:38400
	s_waitcnt lgkmcnt(7)
	v_pk_fma_f32 v[194:195], v[190:191], v[114:115], v[194:195] op_sel_hi:[0,1,1]
	v_pk_fma_f32 v[198:199], v[192:193], v[114:115], v[198:199] op_sel_hi:[0,1,1]
	v_pk_fma_f32 v[196:197], v[190:191], v[116:117], v[196:197] op_sel_hi:[0,1,1]
	v_pk_fma_f32 v[152:153], v[192:193], v[116:117], v[152:153] op_sel_hi:[0,1,1]
	v_pk_fma_f32 v[84:85], v[84:85], v[110:111], v[194:195]
	v_pk_fma_f32 v[148:149], v[148:149], v[110:111], v[198:199]
	v_pk_fma_f32 v[86:87], v[86:87], v[112:113], v[196:197]
	v_pk_fma_f32 v[150:151], v[150:151], v[112:113], v[152:153]
	ds_read_b128 v[110:113], v134 offset:26112
	ds_read_b128 v[114:117], v134 offset:34304
	s_waitcnt lgkmcnt(8)
	v_pk_mul_f32 v[194:195], v[84:85], v[186:187]
	v_pk_mul_f32 v[196:197], v[148:149], v[186:187]
	v_pk_fma_f32 v[194:195], v[86:87], v[188:189], v[194:195]
	v_pk_fma_f32 v[196:197], v[150:151], v[188:189], v[196:197]
	v_add_f32_e32 v194, v194, v195
	v_add_f32_e32 v196, v196, v197
	ds_read_b128 v[186:189], v134 offset:42496
	v_add_f32_dpp v194, v194, v194 row_ror:8 row_mask:0xf bank_mask:0xf bound_ctrl:1
	v_add_f32_dpp v196, v196, v196 row_ror:8 row_mask:0xf bank_mask:0xf bound_ctrl:1
	s_waitcnt lgkmcnt(6)
	v_pk_mul_f32 v[190:191], v[84:85], v[102:103]
	v_pk_mul_f32 v[192:193], v[148:149], v[102:103]
	v_add_f32_dpp v194, v194, v194 row_ror:4 row_mask:0xf bank_mask:0xf bound_ctrl:1
	v_add_f32_dpp v196, v196, v196 row_ror:4 row_mask:0xf bank_mask:0xf bound_ctrl:1
	v_pk_fma_f32 v[190:191], v[86:87], v[104:105], v[190:191]
	v_pk_fma_f32 v[192:193], v[150:151], v[104:105], v[192:193]
	v_add_f32_dpp v194, v194, v194 row_ror:2 row_mask:0xf bank_mask:0xf bound_ctrl:1
	v_add_f32_dpp v196, v196, v196 row_ror:2 row_mask:0xf bank_mask:0xf bound_ctrl:1
	v_add_f32_e32 v190, v190, v191
	v_add_f32_dpp v194, v194, v194 row_ror:1 row_mask:0xf bank_mask:0xf bound_ctrl:1
	v_add_f32_dpp v196, v196, v196 row_ror:1 row_mask:0xf bank_mask:0xf bound_ctrl:1
	v_add_f32_e32 v192, v192, v193
	ds_write_b32 v182, v194 offset:48768
	ds_write_b32 v182, v196 offset:48832
	ds_read_b128 v[106:109], v134 offset:30464
	v_add_f32_dpp v190, v190, v190 row_ror:8 row_mask:0xf bank_mask:0xf bound_ctrl:1
	v_add_f32_dpp v192, v192, v192 row_ror:8 row_mask:0xf bank_mask:0xf bound_ctrl:1
	s_waitcnt lgkmcnt(6)
	v_pk_mul_f32 v[194:195], v[122:123], v[118:119] op_sel_hi:[0,1]
	v_add_f32_dpp v190, v190, v190 row_ror:4 row_mask:0xf bank_mask:0xf bound_ctrl:1
	v_add_f32_dpp v192, v192, v192 row_ror:4 row_mask:0xf bank_mask:0xf bound_ctrl:1
	v_pk_mul_f32 v[196:197], v[122:123], v[120:121] op_sel_hi:[0,1]
	v_add_f32_dpp v190, v190, v190 row_ror:2 row_mask:0xf bank_mask:0xf bound_ctrl:1
	v_add_f32_dpp v192, v192, v192 row_ror:2 row_mask:0xf bank_mask:0xf bound_ctrl:1
	v_pk_mul_f32 v[198:199], v[122:123], v[118:119] op_sel:[1,0] op_sel_hi:[1,1]
	v_add_f32_dpp v190, v190, v190 row_ror:1 row_mask:0xf bank_mask:0xf bound_ctrl:1
	v_add_f32_dpp v192, v192, v192 row_ror:1 row_mask:0xf bank_mask:0xf bound_ctrl:1
	v_pk_mul_f32 v[152:153], v[122:123], v[120:121] op_sel:[1,0] op_sel_hi:[1,1]
	ds_read_b32 v122, v182 offset:44928
	ds_read_b32 v123, v182 offset:44992
	ds_read_b128 v[118:121], v134 offset:38656
	s_waitcnt lgkmcnt(7)
	v_pk_fma_f32 v[194:195], v[190:191], v[114:115], v[194:195] op_sel_hi:[0,1,1]
	v_pk_fma_f32 v[198:199], v[192:193], v[114:115], v[198:199] op_sel_hi:[0,1,1]
	v_pk_fma_f32 v[196:197], v[190:191], v[116:117], v[196:197] op_sel_hi:[0,1,1]
	v_pk_fma_f32 v[152:153], v[192:193], v[116:117], v[152:153] op_sel_hi:[0,1,1]
	v_pk_fma_f32 v[84:85], v[84:85], v[110:111], v[194:195]
	v_pk_fma_f32 v[148:149], v[148:149], v[110:111], v[198:199]
	v_pk_fma_f32 v[86:87], v[86:87], v[112:113], v[196:197]
	v_pk_fma_f32 v[150:151], v[150:151], v[112:113], v[152:153]
	ds_read_b128 v[110:113], v134 offset:26368
	ds_read_b128 v[114:117], v134 offset:34560
	s_waitcnt lgkmcnt(8)
	v_pk_mul_f32 v[194:195], v[84:85], v[186:187]
	v_pk_mul_f32 v[196:197], v[148:149], v[186:187]
	v_pk_fma_f32 v[194:195], v[86:87], v[188:189], v[194:195]
	v_pk_fma_f32 v[196:197], v[150:151], v[188:189], v[196:197]
	v_add_f32_e32 v194, v194, v195
	v_add_f32_e32 v196, v196, v197
	ds_read_b128 v[186:189], v134 offset:42752
	v_add_f32_dpp v194, v194, v194 row_ror:8 row_mask:0xf bank_mask:0xf bound_ctrl:1
	v_add_f32_dpp v196, v196, v196 row_ror:8 row_mask:0xf bank_mask:0xf bound_ctrl:1
	s_waitcnt lgkmcnt(6)
	v_pk_mul_f32 v[190:191], v[84:85], v[106:107]
	v_pk_mul_f32 v[192:193], v[148:149], v[106:107]
	v_add_f32_dpp v194, v194, v194 row_ror:4 row_mask:0xf bank_mask:0xf bound_ctrl:1
	v_add_f32_dpp v196, v196, v196 row_ror:4 row_mask:0xf bank_mask:0xf bound_ctrl:1
	v_pk_fma_f32 v[190:191], v[86:87], v[108:109], v[190:191]
	v_pk_fma_f32 v[192:193], v[150:151], v[108:109], v[192:193]
	v_add_f32_dpp v194, v194, v194 row_ror:2 row_mask:0xf bank_mask:0xf bound_ctrl:1
	v_add_f32_dpp v196, v196, v196 row_ror:2 row_mask:0xf bank_mask:0xf bound_ctrl:1
	v_add_f32_e32 v190, v190, v191
	v_add_f32_dpp v194, v194, v194 row_ror:1 row_mask:0xf bank_mask:0xf bound_ctrl:1
	v_add_f32_dpp v196, v196, v196 row_ror:1 row_mask:0xf bank_mask:0xf bound_ctrl:1
	v_add_f32_e32 v192, v192, v193
	ds_write_b32 v182, v194 offset:48896
	ds_write_b32 v182, v196 offset:48960
	v_add_f32_dpp v190, v190, v190 row_ror:8 row_mask:0xf bank_mask:0xf bound_ctrl:1
	v_add_f32_dpp v192, v192, v192 row_ror:8 row_mask:0xf bank_mask:0xf bound_ctrl:1
	s_waitcnt lgkmcnt(5)
	v_pk_mul_f32 v[194:195], v[122:123], v[118:119] op_sel_hi:[0,1]
	v_add_f32_dpp v190, v190, v190 row_ror:4 row_mask:0xf bank_mask:0xf bound_ctrl:1
	v_add_f32_dpp v192, v192, v192 row_ror:4 row_mask:0xf bank_mask:0xf bound_ctrl:1
	v_pk_mul_f32 v[196:197], v[122:123], v[120:121] op_sel_hi:[0,1]
	v_add_f32_dpp v190, v190, v190 row_ror:2 row_mask:0xf bank_mask:0xf bound_ctrl:1
	v_add_f32_dpp v192, v192, v192 row_ror:2 row_mask:0xf bank_mask:0xf bound_ctrl:1
	v_pk_mul_f32 v[198:199], v[122:123], v[118:119] op_sel:[1,0] op_sel_hi:[1,1]
	v_add_f32_dpp v190, v190, v190 row_ror:1 row_mask:0xf bank_mask:0xf bound_ctrl:1
	v_add_f32_dpp v192, v192, v192 row_ror:1 row_mask:0xf bank_mask:0xf bound_ctrl:1
	v_pk_mul_f32 v[152:153], v[122:123], v[120:121] op_sel:[1,0] op_sel_hi:[1,1]
	s_waitcnt lgkmcnt(3)
	v_pk_fma_f32 v[194:195], v[190:191], v[114:115], v[194:195] op_sel_hi:[0,1,1]
	v_pk_fma_f32 v[198:199], v[192:193], v[114:115], v[198:199] op_sel_hi:[0,1,1]
	v_pk_fma_f32 v[196:197], v[190:191], v[116:117], v[196:197] op_sel_hi:[0,1,1]
	v_pk_fma_f32 v[152:153], v[192:193], v[116:117], v[152:153] op_sel_hi:[0,1,1]
	v_pk_fma_f32 v[84:85], v[84:85], v[110:111], v[194:195]
	v_pk_fma_f32 v[148:149], v[148:149], v[110:111], v[198:199]
	v_pk_fma_f32 v[86:87], v[86:87], v[112:113], v[196:197]
	v_pk_fma_f32 v[150:151], v[150:151], v[112:113], v[152:153]
	s_waitcnt lgkmcnt(2)
	v_pk_mul_f32 v[194:195], v[84:85], v[186:187]
	v_pk_mul_f32 v[196:197], v[148:149], v[186:187]
	v_pk_fma_f32 v[194:195], v[86:87], v[188:189], v[194:195]
	v_pk_fma_f32 v[196:197], v[150:151], v[188:189], v[196:197]
	v_add_f32_e32 v194, v194, v195
	v_add_f32_e32 v196, v196, v197
	s_nop 0
	v_add_f32_dpp v194, v194, v194 row_ror:8 row_mask:0xf bank_mask:0xf bound_ctrl:1
	v_add_f32_dpp v196, v196, v196 row_ror:8 row_mask:0xf bank_mask:0xf bound_ctrl:1
	s_nop 0
	v_add_f32_dpp v194, v194, v194 row_ror:4 row_mask:0xf bank_mask:0xf bound_ctrl:1
	v_add_f32_dpp v196, v196, v196 row_ror:4 row_mask:0xf bank_mask:0xf bound_ctrl:1
	s_nop 0
	v_add_f32_dpp v194, v194, v194 row_ror:2 row_mask:0xf bank_mask:0xf bound_ctrl:1
	v_add_f32_dpp v196, v196, v196 row_ror:2 row_mask:0xf bank_mask:0xf bound_ctrl:1
	s_nop 0
	v_add_f32_dpp v194, v194, v194 row_ror:1 row_mask:0xf bank_mask:0xf bound_ctrl:1
	v_add_f32_dpp v196, v196, v196 row_ror:1 row_mask:0xf bank_mask:0xf bound_ctrl:1
	ds_write_b32 v182, v194 offset:49024
	ds_write_b32 v182, v196 offset:49088
	s_and_saveexec_b64 s[8:9], s[38:39]
	s_cbranch_execz .LBB0_415
	v_add_f32_e32 v88, v0, v64
	v_min_f32_e32 v92, 0, v88
	v_mul_f32_e64 v88, |v88|, s62
	v_exp_f32_e32 v88, v88
	v_add_f32_e32 v89, v1, v65
	v_add_f32_e32 v90, v2, v66
	v_add_f32_e32 v91, v3, v67
	v_add_f32_e32 v88, 1.0, v88
	v_cmp_gt_f32_e32 vcc, s5, v88
	s_mov_b32 s4, 0xf800000
	v_add_f32_e32 v80, v4, v60
	v_cndmask_b32_e64 v93, 0, 32, vcc
	v_ldexp_f32 v88, v88, v93
	v_log_f32_e32 v88, v88
	v_mul_f32_e32 v80, 0xbfb8aa3b, v80
	v_exp_f32_e32 v82, v80
	v_add_f32_e32 v80, v5, v61
	v_mul_f32_e32 v93, 0x3f317217, v88
	v_fma_f32 v93, v88, s76, -v93
	v_fmac_f32_e32 v93, 0x3377d1cf, v88
	v_fmac_f32_e32 v93, 0x3f317217, v88
	v_cmp_lt_f32_e64 s[42:43], |v88|, s77
	v_mul_f32_e32 v80, 0xbfb8aa3b, v80
	v_exp_f32_e32 v83, v80
	v_cndmask_b32_e64 v88, v88, v93, s[42:43]
	v_cndmask_b32_e32 v93, 0, v171, vcc
	v_sub_f32_e32 v88, v88, v93
	v_sub_f32_e32 v88, v92, v88
	v_min_f32_e32 v92, 0, v89
	v_mul_f32_e64 v89, |v89|, s62
	v_exp_f32_e32 v89, v89
	v_add_f32_e32 v88, -0.5, v88
	v_mul_f32_e32 v88, 0x3fb8aa3b, v88
	v_exp_f32_e32 v88, v88
	v_add_f32_e32 v89, 1.0, v89
	v_cmp_gt_f32_e32 vcc, s5, v89
	v_pk_add_f32 v[82:83], v[82:83], 1.0 op_sel_hi:[1,0]
	v_mul_f32_e32 v88, 0xbfb8aa3b, v88
	v_cndmask_b32_e64 v93, 0, 32, vcc
	v_ldexp_f32 v89, v89, v93
	v_log_f32_e32 v89, v89
	v_exp_f32_e32 v88, v88
	v_add_f32_e32 v80, v6, v62
	v_add_f32_e32 v81, v7, v63
	v_mul_f32_e32 v93, 0x3f317217, v89
	v_fma_f32 v93, v89, s76, -v93
	v_fmac_f32_e32 v93, 0x3377d1cf, v89
	v_fmac_f32_e32 v93, 0x3f317217, v89
	v_cmp_lt_f32_e64 s[42:43], |v89|, s77
	v_mul_f32_e32 v80, 0xbfb8aa3b, v80
	v_mul_f32_e32 v81, 0xbfb8aa3b, v81
	v_cndmask_b32_e64 v89, v89, v93, s[42:43]
	v_cndmask_b32_e32 v93, 0, v171, vcc
	v_sub_f32_e32 v89, v89, v93
	v_sub_f32_e32 v89, v92, v89
	v_min_f32_e32 v92, 0, v90
	v_mul_f32_e64 v90, |v90|, s62
	v_exp_f32_e32 v90, v90
	v_add_f32_e32 v89, -0.5, v89
	v_mul_f32_e32 v89, 0x3fb8aa3b, v89
	v_exp_f32_e32 v89, v89
	v_add_f32_e32 v90, 1.0, v90
	v_cmp_gt_f32_e32 vcc, s5, v90
	v_exp_f32_e32 v80, v80
	v_mul_f32_e32 v89, 0xbfb8aa3b, v89
	v_cndmask_b32_e64 v93, 0, 32, vcc
	v_ldexp_f32 v90, v90, v93
	v_log_f32_e32 v90, v90
	v_exp_f32_e32 v89, v89
	v_exp_f32_e32 v81, v81
	v_mul_f32_e32 v93, 0x3f317217, v90
	v_fma_f32 v93, v90, s76, -v93
	v_fmac_f32_e32 v93, 0x3377d1cf, v90
	v_fmac_f32_e32 v93, 0x3f317217, v90
	v_cmp_lt_f32_e64 s[42:43], |v90|, s77
	v_pk_add_f32 v[80:81], v[80:81], 1.0 op_sel_hi:[1,0]
	s_nop 0
	v_cndmask_b32_e64 v90, v90, v93, s[42:43]
	v_cndmask_b32_e32 v93, 0, v171, vcc
	v_sub_f32_e32 v90, v90, v93
	v_sub_f32_e32 v90, v92, v90
	v_min_f32_e32 v92, 0, v91
	v_mul_f32_e64 v91, |v91|, s62
	v_exp_f32_e32 v91, v91
	v_add_f32_e32 v90, -0.5, v90
	v_mul_f32_e32 v90, 0x3fb8aa3b, v90
	v_exp_f32_e32 v90, v90
	v_add_f32_e32 v91, 1.0, v91
	v_cmp_gt_f32_e32 vcc, s5, v91
	v_mul_f32_e32 v90, 0xbfb8aa3b, v90
	s_nop 0
	v_cndmask_b32_e64 v93, 0, 32, vcc
	v_ldexp_f32 v91, v91, v93
	v_log_f32_e32 v91, v91
	v_exp_f32_e32 v90, v90
	v_mul_f32_e32 v93, 0x3f317217, v91
	v_fma_f32 v93, v91, s76, -v93
	v_fmac_f32_e32 v93, 0x3377d1cf, v91
	v_fmac_f32_e32 v93, 0x3f317217, v91
	v_cmp_lt_f32_e64 s[42:43], |v91|, s77
	s_nop 1
	v_cndmask_b32_e64 v91, v91, v93, s[42:43]
	v_cndmask_b32_e32 v93, 0, v171, vcc
	v_sub_f32_e32 v91, v91, v93
	v_sub_f32_e32 v91, v92, v91
	v_add_f32_e32 v91, -0.5, v91
	v_mul_f32_e32 v91, 0x3fb8aa3b, v91
	v_exp_f32_e32 v91, v91
	v_pk_mul_f32 v[92:93], v[10:11], v[58:59]
	v_mul_f32_e32 v91, 0xbfb8aa3b, v91
	v_exp_f32_e32 v91, v91
	v_pk_mul_f32 v[94:95], v[92:93], v[92:93]
	ds_write_b128 v181, v[88:91]
	v_pk_mul_f32 v[88:89], v[8:9], v[56:57]
	v_pk_mul_f32 v[90:91], v[88:89], v[88:89]
	v_add_f32_e32 v90, v91, v90
	v_add_f32_e32 v90, v94, v90
	v_add_f32_e32 v90, v95, v90
	s_nop 1
	v_add_f32_dpp v90, v90, v90 row_ror:8 row_mask:0xf bank_mask:0xf bound_ctrl:1
	s_nop 1
	v_add_f32_dpp v90, v90, v90 row_ror:4 row_mask:0xf bank_mask:0xf bound_ctrl:1
	s_nop 1
	v_add_f32_dpp v90, v90, v90 row_ror:2 row_mask:0xf bank_mask:0xf bound_ctrl:1
	s_nop 1
	v_add_f32_dpp v90, v90, v90 row_ror:1 row_mask:0xf bank_mask:0xf bound_ctrl:1
	v_cmp_gt_f32_e32 vcc, s4, v90
	v_mul_f32_e32 v91, 0x4f800000, v90
	s_nop 0
	v_cndmask_b32_e32 v90, v90, v91, vcc
	v_sqrt_f32_e32 v91, v90
	s_nop 0
	v_add_u32_e32 v94, -1, v91
	v_fma_f32 v95, -v94, v91, v90
	v_cmp_ge_f32_e64 s[42:43], 0, v95
	v_add_u32_e32 v95, 1, v91
	s_nop 0
	v_cndmask_b32_e64 v94, v91, v94, s[42:43]
	v_fma_f32 v91, -v95, v91, v90
	v_cmp_lt_f32_e64 s[42:43], 0, v91
	s_nop 1
	v_cndmask_b32_e64 v91, v94, v95, s[42:43]
	v_mul_f32_e32 v94, 0x37800000, v91
	v_cndmask_b32_e32 v91, v91, v94, vcc
	v_cmp_class_f32_e32 vcc, v90, v160
	s_nop 1
	v_cndmask_b32_e32 v90, v91, v90, vcc
	v_max_f32_e32 v90, 0x2b8cbccc, v90
	v_div_scale_f32 v91, s[22:23], v90, v90, 1.0
	v_rcp_f32_e32 v94, v91
	s_nop 0
	v_fma_f32 v95, -v91, v94, 1.0
	v_fmac_f32_e32 v94, v95, v94
	v_div_scale_f32 v95, vcc, 1.0, v90, 1.0
	v_mul_f32_e32 v100, v95, v94
	v_fma_f32 v101, -v91, v100, v95
	v_fmac_f32_e32 v100, v101, v94
	v_fma_f32 v91, -v91, v100, v95
	v_div_fmas_f32 v91, v91, v94, v100
	v_div_fixup_f32 v90, v91, v90, 1.0
	v_pk_mul_f32 v[94:95], v[88:89], v[90:91] op_sel_hi:[1,0]
	v_pk_mul_f32 v[92:93], v[92:93], v[90:91] op_sel_hi:[1,0]
	v_xor_b32_e32 v89, 0x80000000, v95
	v_xor_b32_e32 v88, 0x80000000, v94
	v_xor_b32_e32 v91, 0x80000000, v93
	v_xor_b32_e32 v90, 0x80000000, v92
	ds_write_b128 v181, v[88:91] offset:4096
	v_div_scale_f32 v88, s[22:23], v83, v83, 1.0
	v_rcp_f32_e32 v89, v88
	s_nop 0
	v_fma_f32 v90, -v88, v89, 1.0
	v_fmac_f32_e32 v89, v90, v89
	v_div_scale_f32 v90, vcc, 1.0, v83, 1.0
	v_mul_f32_e32 v91, v90, v89
	v_fma_f32 v100, -v88, v91, v90
	v_fmac_f32_e32 v91, v100, v89
	v_fma_f32 v88, -v88, v91, v90
	v_div_fmas_f32 v88, v88, v89, v91
	v_div_fixup_f32 v83, v88, v83, 1.0
	v_div_scale_f32 v88, s[22:23], v82, v82, 1.0
	v_rcp_f32_e32 v89, v88
	s_nop 0
	v_fma_f32 v90, -v88, v89, 1.0
	v_fmac_f32_e32 v89, v90, v89
	v_div_scale_f32 v90, vcc, 1.0, v82, 1.0
	v_mul_f32_e32 v91, v90, v89
	v_fma_f32 v100, -v88, v91, v90
	v_fmac_f32_e32 v91, v100, v89
	v_fma_f32 v88, -v88, v91, v90
	v_div_scale_f32 v90, s[22:23], v81, v81, 1.0
	v_div_fmas_f32 v88, v88, v89, v91
	v_rcp_f32_e32 v91, v90
	v_div_fixup_f32 v82, v88, v82, 1.0
	v_pk_mul_f32 v[88:89], v[82:83], v[94:95]
	v_fma_f32 v94, -v90, v91, 1.0
	v_fmac_f32_e32 v91, v94, v91
	v_div_scale_f32 v94, vcc, 1.0, v81, 1.0
	v_mul_f32_e32 v95, v94, v91
	v_fma_f32 v100, -v90, v95, v94
	v_fmac_f32_e32 v95, v100, v91
	v_fma_f32 v90, -v90, v95, v94
	v_div_fmas_f32 v90, v90, v91, v95
	v_div_fixup_f32 v95, v90, v81, 1.0
	v_div_scale_f32 v81, s[22:23], v80, v80, 1.0
	v_rcp_f32_e32 v90, v81
	s_nop 0
	v_fma_f32 v91, -v81, v90, 1.0
	v_fmac_f32_e32 v90, v91, v90
	v_div_scale_f32 v91, vcc, 1.0, v80, 1.0
	v_mul_f32_e32 v94, v91, v90
	v_fma_f32 v100, -v81, v94, v91
	v_fmac_f32_e32 v94, v100, v90
	v_fma_f32 v81, -v81, v94, v91
	v_div_fmas_f32 v81, v81, v90, v94
	v_div_fixup_f32 v94, v81, v80, 1.0
	v_pk_add_f32 v[80:81], v[82:83], -1.0 op_sel_hi:[1,0]
	v_pk_add_f32 v[82:83], v[94:95], -1.0 op_sel_hi:[1,0]
	v_pk_fma_f32 v[80:81], v[12:13], v[80:81], 1.0 op_sel_hi:[1,1,0]
	v_pk_fma_f32 v[82:83], v[14:15], v[82:83], 1.0 op_sel_hi:[1,1,0]
	v_pk_mul_f32 v[90:91], v[94:95], v[92:93]
	v_pk_mul_f32 v[80:81], v[56:57], v[80:81]
	v_pk_mul_f32 v[82:83], v[58:59], v[82:83]
	ds_write_b128 v181, v[88:91] offset:8192
	ds_write_b128 v181, v[80:83] offset:12288
	ds_write_b128 v181, v[52:55] offset:16384

.LBB0_419:
	ds_read2st64_b32 v[80:81], v179 offset0:184 offset1:188
	v_add_u32_e32 v82, 16, v126
	v_ashrrev_i32_e32 v83, 31, v82
	v_lshlrev_b64 v[82:83], 13, v[82:83]
	v_lshl_add_u64 v[82:83], v[144:145], 0, v[82:83]
	s_waitcnt lgkmcnt(0)
	global_store_dword v[82:83], v80, off
	v_add_u32_e32 v82, 16, v124
	v_ashrrev_i32_e32 v83, 31, v82
	v_lshlrev_b64 v[82:83], 13, v[82:83]
	v_lshl_add_u64 v[82:83], v[144:145], 0, v[82:83]
	global_store_dword v[82:83], v81, off
	ds_read_b128 v[102:105], v134 offset:4096
	ds_read_b32 v122, v182 offset:20480
	ds_read_b32 v123, v182 offset:20544
	ds_read_b128 v[118:121], v134 offset:12288
	ds_read_b128 v[110:113], v134
	ds_read_b128 v[114:117], v134 offset:8192
	ds_read_b128 v[186:189], v134 offset:16384
	s_waitcnt lgkmcnt(6)
	v_pk_mul_f32 v[190:191], v[84:85], v[102:103]
	v_pk_mul_f32 v[192:193], v[148:149], v[102:103]
	v_pk_fma_f32 v[190:191], v[86:87], v[104:105], v[190:191]
	v_pk_fma_f32 v[192:193], v[150:151], v[104:105], v[192:193]
	v_add_f32_e32 v190, v190, v191
	v_add_f32_e32 v192, v192, v193
	ds_read_b128 v[106:109], v134 offset:4352
	v_add_f32_dpp v190, v190, v190 row_ror:8 row_mask:0xf bank_mask:0xf bound_ctrl:1
	v_add_f32_dpp v192, v192, v192 row_ror:8 row_mask:0xf bank_mask:0xf bound_ctrl:1
	s_waitcnt lgkmcnt(4)
	v_pk_mul_f32 v[194:195], v[122:123], v[118:119] op_sel_hi:[0,1]
	v_add_f32_dpp v190, v190, v190 row_ror:4 row_mask:0xf bank_mask:0xf bound_ctrl:1
	v_add_f32_dpp v192, v192, v192 row_ror:4 row_mask:0xf bank_mask:0xf bound_ctrl:1
	v_pk_mul_f32 v[196:197], v[122:123], v[120:121] op_sel_hi:[0,1]
	v_add_f32_dpp v190, v190, v190 row_ror:2 row_mask:0xf bank_mask:0xf bound_ctrl:1
	v_add_f32_dpp v192, v192, v192 row_ror:2 row_mask:0xf bank_mask:0xf bound_ctrl:1
	v_pk_mul_f32 v[198:199], v[122:123], v[118:119] op_sel:[1,0] op_sel_hi:[1,1]
	v_add_f32_dpp v190, v190, v190 row_ror:1 row_mask:0xf bank_mask:0xf bound_ctrl:1
	v_add_f32_dpp v192, v192, v192 row_ror:1 row_mask:0xf bank_mask:0xf bound_ctrl:1
	v_pk_mul_f32 v[152:153], v[122:123], v[120:121] op_sel:[1,0] op_sel_hi:[1,1]
	ds_read_b32 v122, v182 offset:20608
	ds_read_b32 v123, v182 offset:20672
	ds_read_b128 v[118:121], v134 offset:12544
	s_waitcnt lgkmcnt(5)
	v_pk_fma_f32 v[194:195], v[190:191], v[114:115], v[194:195] op_sel_hi:[0,1,1]
	v_pk_fma_f32 v[198:199], v[192:193], v[114:115], v[198:199] op_sel_hi:[0,1,1]
	v_pk_fma_f32 v[196:197], v[190:191], v[116:117], v[196:197] op_sel_hi:[0,1,1]
	v_pk_fma_f32 v[152:153], v[192:193], v[116:117], v[152:153] op_sel_hi:[0,1,1]
	v_pk_fma_f32 v[84:85], v[84:85], v[110:111], v[194:195]
	v_pk_fma_f32 v[148:149], v[148:149], v[110:111], v[198:199]
	v_pk_fma_f32 v[86:87], v[86:87], v[112:113], v[196:197]
	v_pk_fma_f32 v[150:151], v[150:151], v[112:113], v[152:153]
	ds_read_b128 v[110:113], v134 offset:256
	ds_read_b128 v[114:117], v134 offset:8448
	s_waitcnt lgkmcnt(6)
	v_pk_mul_f32 v[194:195], v[84:85], v[186:187]
	v_pk_mul_f32 v[196:197], v[148:149], v[186:187]
	v_pk_fma_f32 v[194:195], v[86:87], v[188:189], v[194:195]
	v_pk_fma_f32 v[196:197], v[150:151], v[188:189], v[196:197]
	v_add_f32_e32 v194, v194, v195
	v_add_f32_e32 v196, v196, v197
	ds_read_b128 v[186:189], v134 offset:16640
	v_add_f32_dpp v194, v194, v194 row_ror:8 row_mask:0xf bank_mask:0xf bound_ctrl:1
	v_add_f32_dpp v196, v196, v196 row_ror:8 row_mask:0xf bank_mask:0xf bound_ctrl:1
	s_waitcnt lgkmcnt(6)
	v_pk_mul_f32 v[190:191], v[84:85], v[106:107]
	v_pk_mul_f32 v[192:193], v[148:149], v[106:107]
	v_add_f32_dpp v194, v194, v194 row_ror:4 row_mask:0xf bank_mask:0xf bound_ctrl:1
	v_add_f32_dpp v196, v196, v196 row_ror:4 row_mask:0xf bank_mask:0xf bound_ctrl:1
	v_pk_fma_f32 v[190:191], v[86:87], v[108:109], v[190:191]
	v_pk_fma_f32 v[192:193], v[150:151], v[108:109], v[192:193]
	v_add_f32_dpp v194, v194, v194 row_ror:2 row_mask:0xf bank_mask:0xf bound_ctrl:1
	v_add_f32_dpp v196, v196, v196 row_ror:2 row_mask:0xf bank_mask:0xf bound_ctrl:1
	v_add_f32_e32 v190, v190, v191
	v_add_f32_dpp v194, v194, v194 row_ror:1 row_mask:0xf bank_mask:0xf bound_ctrl:1
	v_add_f32_dpp v196, v196, v196 row_ror:1 row_mask:0xf bank_mask:0xf bound_ctrl:1
	v_add_f32_e32 v192, v192, v193
	ds_write_b32 v182, v194 offset:45056
	ds_write_b32 v182, v196 offset:45120
	ds_read_b128 v[102:105], v134 offset:4608
	v_add_f32_dpp v190, v190, v190 row_ror:8 row_mask:0xf bank_mask:0xf bound_ctrl:1
	v_add_f32_dpp v192, v192, v192 row_ror:8 row_mask:0xf bank_mask:0xf bound_ctrl:1
	s_waitcnt lgkmcnt(6)
	v_pk_mul_f32 v[194:195], v[122:123], v[118:119] op_sel_hi:[0,1]
	v_add_f32_dpp v190, v190, v190 row_ror:4 row_mask:0xf bank_mask:0xf bound_ctrl:1
	v_add_f32_dpp v192, v192, v192 row_ror:4 row_mask:0xf bank_mask:0xf bound_ctrl:1
	v_pk_mul_f32 v[196:197], v[122:123], v[120:121] op_sel_hi:[0,1]
	v_add_f32_dpp v190, v190, v190 row_ror:2 row_mask:0xf bank_mask:0xf bound_ctrl:1
	v_add_f32_dpp v192, v192, v192 row_ror:2 row_mask:0xf bank_mask:0xf bound_ctrl:1
	v_pk_mul_f32 v[198:199], v[122:123], v[118:119] op_sel:[1,0] op_sel_hi:[1,1]
	v_add_f32_dpp v190, v190, v190 row_ror:1 row_mask:0xf bank_mask:0xf bound_ctrl:1
	v_add_f32_dpp v192, v192, v192 row_ror:1 row_mask:0xf bank_mask:0xf bound_ctrl:1
	v_pk_mul_f32 v[152:153], v[122:123], v[120:121] op_sel:[1,0] op_sel_hi:[1,1]
	ds_read_b32 v122, v182 offset:20736
	ds_read_b32 v123, v182 offset:20800
	ds_read_b128 v[118:121], v134 offset:12800
	s_waitcnt lgkmcnt(7)
	v_pk_fma_f32 v[194:195], v[190:191], v[114:115], v[194:195] op_sel_hi:[0,1,1]
	v_pk_fma_f32 v[198:199], v[192:193], v[114:115], v[198:199] op_sel_hi:[0,1,1]
	v_pk_fma_f32 v[196:197], v[190:191], v[116:117], v[196:197] op_sel_hi:[0,1,1]
	v_pk_fma_f32 v[152:153], v[192:193], v[116:117], v[152:153] op_sel_hi:[0,1,1]
	v_pk_fma_f32 v[84:85], v[84:85], v[110:111], v[194:195]
	v_pk_fma_f32 v[148:149], v[148:149], v[110:111], v[198:199]
	v_pk_fma_f32 v[86:87], v[86:87], v[112:113], v[196:197]
	v_pk_fma_f32 v[150:151], v[150:151], v[112:113], v[152:153]
	ds_read_b128 v[110:113], v134 offset:512
	ds_read_b128 v[114:117], v134 offset:8704
	s_waitcnt lgkmcnt(8)
	v_pk_mul_f32 v[194:195], v[84:85], v[186:187]
	v_pk_mul_f32 v[196:197], v[148:149], v[186:187]
	v_pk_fma_f32 v[194:195], v[86:87], v[188:189], v[194:195]
	v_pk_fma_f32 v[196:197], v[150:151], v[188:189], v[196:197]
	v_add_f32_e32 v194, v194, v195
	v_add_f32_e32 v196, v196, v197
	ds_read_b128 v[186:189], v134 offset:16896
	v_add_f32_dpp v194, v194, v194 row_ror:8 row_mask:0xf bank_mask:0xf bound_ctrl:1
	v_add_f32_dpp v196, v196, v196 row_ror:8 row_mask:0xf bank_mask:0xf bound_ctrl:1
	s_waitcnt lgkmcnt(6)
	v_pk_mul_f32 v[190:191], v[84:85], v[102:103]
	v_pk_mul_f32 v[192:193], v[148:149], v[102:103]
	v_add_f32_dpp v194, v194, v194 row_ror:4 row_mask:0xf bank_mask:0xf bound_ctrl:1
	v_add_f32_dpp v196, v196, v196 row_ror:4 row_mask:0xf bank_mask:0xf bound_ctrl:1
	v_pk_fma_f32 v[190:191], v[86:87], v[104:105], v[190:191]
	v_pk_fma_f32 v[192:193], v[150:151], v[104:105], v[192:193]
	v_add_f32_dpp v194, v194, v194 row_ror:2 row_mask:0xf bank_mask:0xf bound_ctrl:1
	v_add_f32_dpp v196, v196, v196 row_ror:2 row_mask:0xf bank_mask:0xf bound_ctrl:1
	v_add_f32_e32 v190, v190, v191
	v_add_f32_dpp v194, v194, v194 row_ror:1 row_mask:0xf bank_mask:0xf bound_ctrl:1
	v_add_f32_dpp v196, v196, v196 row_ror:1 row_mask:0xf bank_mask:0xf bound_ctrl:1
	v_add_f32_e32 v192, v192, v193
	ds_write_b32 v182, v194 offset:45184
	ds_write_b32 v182, v196 offset:45248
	ds_read_b128 v[106:109], v134 offset:4864
	v_add_f32_dpp v190, v190, v190 row_ror:8 row_mask:0xf bank_mask:0xf bound_ctrl:1
	v_add_f32_dpp v192, v192, v192 row_ror:8 row_mask:0xf bank_mask:0xf bound_ctrl:1
	s_waitcnt lgkmcnt(6)
	v_pk_mul_f32 v[194:195], v[122:123], v[118:119] op_sel_hi:[0,1]
	v_add_f32_dpp v190, v190, v190 row_ror:4 row_mask:0xf bank_mask:0xf bound_ctrl:1
	v_add_f32_dpp v192, v192, v192 row_ror:4 row_mask:0xf bank_mask:0xf bound_ctrl:1
	v_pk_mul_f32 v[196:197], v[122:123], v[120:121] op_sel_hi:[0,1]
	v_add_f32_dpp v190, v190, v190 row_ror:2 row_mask:0xf bank_mask:0xf bound_ctrl:1
	v_add_f32_dpp v192, v192, v192 row_ror:2 row_mask:0xf bank_mask:0xf bound_ctrl:1
	v_pk_mul_f32 v[198:199], v[122:123], v[118:119] op_sel:[1,0] op_sel_hi:[1,1]
	v_add_f32_dpp v190, v190, v190 row_ror:1 row_mask:0xf bank_mask:0xf bound_ctrl:1
	v_add_f32_dpp v192, v192, v192 row_ror:1 row_mask:0xf bank_mask:0xf bound_ctrl:1
	v_pk_mul_f32 v[152:153], v[122:123], v[120:121] op_sel:[1,0] op_sel_hi:[1,1]
	ds_read_b32 v122, v182 offset:20864
	ds_read_b32 v123, v182 offset:20928
	ds_read_b128 v[118:121], v134 offset:13056
	s_waitcnt lgkmcnt(7)
	v_pk_fma_f32 v[194:195], v[190:191], v[114:115], v[194:195] op_sel_hi:[0,1,1]
	v_pk_fma_f32 v[198:199], v[192:193], v[114:115], v[198:199] op_sel_hi:[0,1,1]
	v_pk_fma_f32 v[196:197], v[190:191], v[116:117], v[196:197] op_sel_hi:[0,1,1]
	v_pk_fma_f32 v[152:153], v[192:193], v[116:117], v[152:153] op_sel_hi:[0,1,1]
	v_pk_fma_f32 v[84:85], v[84:85], v[110:111], v[194:195]
	v_pk_fma_f32 v[148:149], v[148:149], v[110:111], v[198:199]
	v_pk_fma_f32 v[86:87], v[86:87], v[112:113], v[196:197]
	v_pk_fma_f32 v[150:151], v[150:151], v[112:113], v[152:153]
	ds_read_b128 v[110:113], v134 offset:768
	ds_read_b128 v[114:117], v134 offset:8960
	s_waitcnt lgkmcnt(8)
	v_pk_mul_f32 v[194:195], v[84:85], v[186:187]
	v_pk_mul_f32 v[196:197], v[148:149], v[186:187]
	v_pk_fma_f32 v[194:195], v[86:87], v[188:189], v[194:195]
	v_pk_fma_f32 v[196:197], v[150:151], v[188:189], v[196:197]
	v_add_f32_e32 v194, v194, v195
	v_add_f32_e32 v196, v196, v197
	ds_read_b128 v[186:189], v134 offset:17152
	v_add_f32_dpp v194, v194, v194 row_ror:8 row_mask:0xf bank_mask:0xf bound_ctrl:1
	v_add_f32_dpp v196, v196, v196 row_ror:8 row_mask:0xf bank_mask:0xf bound_ctrl:1
	s_waitcnt lgkmcnt(6)
	v_pk_mul_f32 v[190:191], v[84:85], v[106:107]
	v_pk_mul_f32 v[192:193], v[148:149], v[106:107]
	v_add_f32_dpp v194, v194, v194 row_ror:4 row_mask:0xf bank_mask:0xf bound_ctrl:1
	v_add_f32_dpp v196, v196, v196 row_ror:4 row_mask:0xf bank_mask:0xf bound_ctrl:1
	v_pk_fma_f32 v[190:191], v[86:87], v[108:109], v[190:191]
	v_pk_fma_f32 v[192:193], v[150:151], v[108:109], v[192:193]
	v_add_f32_dpp v194, v194, v194 row_ror:2 row_mask:0xf bank_mask:0xf bound_ctrl:1
	v_add_f32_dpp v196, v196, v196 row_ror:2 row_mask:0xf bank_mask:0xf bound_ctrl:1
	v_add_f32_e32 v190, v190, v191
	v_add_f32_dpp v194, v194, v194 row_ror:1 row_mask:0xf bank_mask:0xf bound_ctrl:1
	v_add_f32_dpp v196, v196, v196 row_ror:1 row_mask:0xf bank_mask:0xf bound_ctrl:1
	v_add_f32_e32 v192, v192, v193
	ds_write_b32 v182, v194 offset:45312
	ds_write_b32 v182, v196 offset:45376
	ds_read_b128 v[102:105], v134 offset:5120
	v_add_f32_dpp v190, v190, v190 row_ror:8 row_mask:0xf bank_mask:0xf bound_ctrl:1
	v_add_f32_dpp v192, v192, v192 row_ror:8 row_mask:0xf bank_mask:0xf bound_ctrl:1
	s_waitcnt lgkmcnt(6)
	v_pk_mul_f32 v[194:195], v[122:123], v[118:119] op_sel_hi:[0,1]
	v_add_f32_dpp v190, v190, v190 row_ror:4 row_mask:0xf bank_mask:0xf bound_ctrl:1
	v_add_f32_dpp v192, v192, v192 row_ror:4 row_mask:0xf bank_mask:0xf bound_ctrl:1
	v_pk_mul_f32 v[196:197], v[122:123], v[120:121] op_sel_hi:[0,1]
	v_add_f32_dpp v190, v190, v190 row_ror:2 row_mask:0xf bank_mask:0xf bound_ctrl:1
	v_add_f32_dpp v192, v192, v192 row_ror:2 row_mask:0xf bank_mask:0xf bound_ctrl:1
	v_pk_mul_f32 v[198:199], v[122:123], v[118:119] op_sel:[1,0] op_sel_hi:[1,1]
	v_add_f32_dpp v190, v190, v190 row_ror:1 row_mask:0xf bank_mask:0xf bound_ctrl:1
	v_add_f32_dpp v192, v192, v192 row_ror:1 row_mask:0xf bank_mask:0xf bound_ctrl:1
	v_pk_mul_f32 v[152:153], v[122:123], v[120:121] op_sel:[1,0] op_sel_hi:[1,1]
	ds_read_b32 v122, v182 offset:20992
	ds_read_b32 v123, v182 offset:21056
	ds_read_b128 v[118:121], v134 offset:13312
	s_waitcnt lgkmcnt(7)
	v_pk_fma_f32 v[194:195], v[190:191], v[114:115], v[194:195] op_sel_hi:[0,1,1]
	v_pk_fma_f32 v[198:199], v[192:193], v[114:115], v[198:199] op_sel_hi:[0,1,1]
	v_pk_fma_f32 v[196:197], v[190:191], v[116:117], v[196:197] op_sel_hi:[0,1,1]
	v_pk_fma_f32 v[152:153], v[192:193], v[116:117], v[152:153] op_sel_hi:[0,1,1]
	v_pk_fma_f32 v[84:85], v[84:85], v[110:111], v[194:195]
	v_pk_fma_f32 v[148:149], v[148:149], v[110:111], v[198:199]
	v_pk_fma_f32 v[86:87], v[86:87], v[112:113], v[196:197]
	v_pk_fma_f32 v[150:151], v[150:151], v[112:113], v[152:153]
	ds_read_b128 v[110:113], v134 offset:1024
	ds_read_b128 v[114:117], v134 offset:9216
	s_waitcnt lgkmcnt(8)
	v_pk_mul_f32 v[194:195], v[84:85], v[186:187]
	v_pk_mul_f32 v[196:197], v[148:149], v[186:187]
	v_pk_fma_f32 v[194:195], v[86:87], v[188:189], v[194:195]
	v_pk_fma_f32 v[196:197], v[150:151], v[188:189], v[196:197]
	v_add_f32_e32 v194, v194, v195
	v_add_f32_e32 v196, v196, v197
	ds_read_b128 v[186:189], v134 offset:17408
	v_add_f32_dpp v194, v194, v194 row_ror:8 row_mask:0xf bank_mask:0xf bound_ctrl:1
	v_add_f32_dpp v196, v196, v196 row_ror:8 row_mask:0xf bank_mask:0xf bound_ctrl:1
	s_waitcnt lgkmcnt(6)
	v_pk_mul_f32 v[190:191], v[84:85], v[102:103]
	v_pk_mul_f32 v[192:193], v[148:149], v[102:103]
	v_add_f32_dpp v194, v194, v194 row_ror:4 row_mask:0xf bank_mask:0xf bound_ctrl:1
	v_add_f32_dpp v196, v196, v196 row_ror:4 row_mask:0xf bank_mask:0xf bound_ctrl:1
	v_pk_fma_f32 v[190:191], v[86:87], v[104:105], v[190:191]
	v_pk_fma_f32 v[192:193], v[150:151], v[104:105], v[192:193]
	v_add_f32_dpp v194, v194, v194 row_ror:2 row_mask:0xf bank_mask:0xf bound_ctrl:1
	v_add_f32_dpp v196, v196, v196 row_ror:2 row_mask:0xf bank_mask:0xf bound_ctrl:1
	v_add_f32_e32 v190, v190, v191
	v_add_f32_dpp v194, v194, v194 row_ror:1 row_mask:0xf bank_mask:0xf bound_ctrl:1
	v_add_f32_dpp v196, v196, v196 row_ror:1 row_mask:0xf bank_mask:0xf bound_ctrl:1
	v_add_f32_e32 v192, v192, v193
	ds_write_b32 v182, v194 offset:45440
	ds_write_b32 v182, v196 offset:45504
	ds_read_b128 v[106:109], v134 offset:5376
	v_add_f32_dpp v190, v190, v190 row_ror:8 row_mask:0xf bank_mask:0xf bound_ctrl:1
	v_add_f32_dpp v192, v192, v192 row_ror:8 row_mask:0xf bank_mask:0xf bound_ctrl:1
	s_waitcnt lgkmcnt(6)
	v_pk_mul_f32 v[194:195], v[122:123], v[118:119] op_sel_hi:[0,1]
	v_add_f32_dpp v190, v190, v190 row_ror:4 row_mask:0xf bank_mask:0xf bound_ctrl:1
	v_add_f32_dpp v192, v192, v192 row_ror:4 row_mask:0xf bank_mask:0xf bound_ctrl:1
	v_pk_mul_f32 v[196:197], v[122:123], v[120:121] op_sel_hi:[0,1]
	v_add_f32_dpp v190, v190, v190 row_ror:2 row_mask:0xf bank_mask:0xf bound_ctrl:1
	v_add_f32_dpp v192, v192, v192 row_ror:2 row_mask:0xf bank_mask:0xf bound_ctrl:1
	v_pk_mul_f32 v[198:199], v[122:123], v[118:119] op_sel:[1,0] op_sel_hi:[1,1]
	v_add_f32_dpp v190, v190, v190 row_ror:1 row_mask:0xf bank_mask:0xf bound_ctrl:1
	v_add_f32_dpp v192, v192, v192 row_ror:1 row_mask:0xf bank_mask:0xf bound_ctrl:1
	v_pk_mul_f32 v[152:153], v[122:123], v[120:121] op_sel:[1,0] op_sel_hi:[1,1]
	ds_read_b32 v122, v182 offset:21120
	ds_read_b32 v123, v182 offset:21184
	ds_read_b128 v[118:121], v134 offset:13568
	s_waitcnt lgkmcnt(7)
	v_pk_fma_f32 v[194:195], v[190:191], v[114:115], v[194:195] op_sel_hi:[0,1,1]
	v_pk_fma_f32 v[198:199], v[192:193], v[114:115], v[198:199] op_sel_hi:[0,1,1]
	v_pk_fma_f32 v[196:197], v[190:191], v[116:117], v[196:197] op_sel_hi:[0,1,1]
	v_pk_fma_f32 v[152:153], v[192:193], v[116:117], v[152:153] op_sel_hi:[0,1,1]
	v_pk_fma_f32 v[84:85], v[84:85], v[110:111], v[194:195]
	v_pk_fma_f32 v[148:149], v[148:149], v[110:111], v[198:199]
	v_pk_fma_f32 v[86:87], v[86:87], v[112:113], v[196:197]
	v_pk_fma_f32 v[150:151], v[150:151], v[112:113], v[152:153]
	ds_read_b128 v[110:113], v134 offset:1280
	ds_read_b128 v[114:117], v134 offset:9472
	s_waitcnt lgkmcnt(8)
	v_pk_mul_f32 v[194:195], v[84:85], v[186:187]
	v_pk_mul_f32 v[196:197], v[148:149], v[186:187]
	v_pk_fma_f32 v[194:195], v[86:87], v[188:189], v[194:195]
	v_pk_fma_f32 v[196:197], v[150:151], v[188:189], v[196:197]
	v_add_f32_e32 v194, v194, v195
	v_add_f32_e32 v196, v196, v197
	ds_read_b128 v[186:189], v134 offset:17664
	v_add_f32_dpp v194, v194, v194 row_ror:8 row_mask:0xf bank_mask:0xf bound_ctrl:1
	v_add_f32_dpp v196, v196, v196 row_ror:8 row_mask:0xf bank_mask:0xf bound_ctrl:1
	s_waitcnt lgkmcnt(6)
	v_pk_mul_f32 v[190:191], v[84:85], v[106:107]
	v_pk_mul_f32 v[192:193], v[148:149], v[106:107]
	v_add_f32_dpp v194, v194, v194 row_ror:4 row_mask:0xf bank_mask:0xf bound_ctrl:1
	v_add_f32_dpp v196, v196, v196 row_ror:4 row_mask:0xf bank_mask:0xf bound_ctrl:1
	v_pk_fma_f32 v[190:191], v[86:87], v[108:109], v[190:191]
	v_pk_fma_f32 v[192:193], v[150:151], v[108:109], v[192:193]
	v_add_f32_dpp v194, v194, v194 row_ror:2 row_mask:0xf bank_mask:0xf bound_ctrl:1
	v_add_f32_dpp v196, v196, v196 row_ror:2 row_mask:0xf bank_mask:0xf bound_ctrl:1
	v_add_f32_e32 v190, v190, v191
	v_add_f32_dpp v194, v194, v194 row_ror:1 row_mask:0xf bank_mask:0xf bound_ctrl:1
	v_add_f32_dpp v196, v196, v196 row_ror:1 row_mask:0xf bank_mask:0xf bound_ctrl:1
	v_add_f32_e32 v192, v192, v193
	ds_write_b32 v182, v194 offset:45568
	ds_write_b32 v182, v196 offset:45632
	ds_read_b128 v[102:105], v134 offset:5632
	v_add_f32_dpp v190, v190, v190 row_ror:8 row_mask:0xf bank_mask:0xf bound_ctrl:1
	v_add_f32_dpp v192, v192, v192 row_ror:8 row_mask:0xf bank_mask:0xf bound_ctrl:1
	s_waitcnt lgkmcnt(6)
	v_pk_mul_f32 v[194:195], v[122:123], v[118:119] op_sel_hi:[0,1]
	v_add_f32_dpp v190, v190, v190 row_ror:4 row_mask:0xf bank_mask:0xf bound_ctrl:1
	v_add_f32_dpp v192, v192, v192 row_ror:4 row_mask:0xf bank_mask:0xf bound_ctrl:1
	v_pk_mul_f32 v[196:197], v[122:123], v[120:121] op_sel_hi:[0,1]
	v_add_f32_dpp v190, v190, v190 row_ror:2 row_mask:0xf bank_mask:0xf bound_ctrl:1
	v_add_f32_dpp v192, v192, v192 row_ror:2 row_mask:0xf bank_mask:0xf bound_ctrl:1
	v_pk_mul_f32 v[198:199], v[122:123], v[118:119] op_sel:[1,0] op_sel_hi:[1,1]
	v_add_f32_dpp v190, v190, v190 row_ror:1 row_mask:0xf bank_mask:0xf bound_ctrl:1
	v_add_f32_dpp v192, v192, v192 row_ror:1 row_mask:0xf bank_mask:0xf bound_ctrl:1
	v_pk_mul_f32 v[152:153], v[122:123], v[120:121] op_sel:[1,0] op_sel_hi:[1,1]
	ds_read_b32 v122, v182 offset:21248
	ds_read_b32 v123, v182 offset:21312
	ds_read_b128 v[118:121], v134 offset:13824
	s_waitcnt lgkmcnt(7)
	v_pk_fma_f32 v[194:195], v[190:191], v[114:115], v[194:195] op_sel_hi:[0,1,1]
	v_pk_fma_f32 v[198:199], v[192:193], v[114:115], v[198:199] op_sel_hi:[0,1,1]
	v_pk_fma_f32 v[196:197], v[190:191], v[116:117], v[196:197] op_sel_hi:[0,1,1]
	v_pk_fma_f32 v[152:153], v[192:193], v[116:117], v[152:153] op_sel_hi:[0,1,1]
	v_pk_fma_f32 v[84:85], v[84:85], v[110:111], v[194:195]
	v_pk_fma_f32 v[148:149], v[148:149], v[110:111], v[198:199]
	v_pk_fma_f32 v[86:87], v[86:87], v[112:113], v[196:197]
	v_pk_fma_f32 v[150:151], v[150:151], v[112:113], v[152:153]
	ds_read_b128 v[110:113], v134 offset:1536
	ds_read_b128 v[114:117], v134 offset:9728
	s_waitcnt lgkmcnt(8)
	v_pk_mul_f32 v[194:195], v[84:85], v[186:187]
	v_pk_mul_f32 v[196:197], v[148:149], v[186:187]
	v_pk_fma_f32 v[194:195], v[86:87], v[188:189], v[194:195]
	v_pk_fma_f32 v[196:197], v[150:151], v[188:189], v[196:197]
	v_add_f32_e32 v194, v194, v195
	v_add_f32_e32 v196, v196, v197
	ds_read_b128 v[186:189], v134 offset:17920
	v_add_f32_dpp v194, v194, v194 row_ror:8 row_mask:0xf bank_mask:0xf bound_ctrl:1
	v_add_f32_dpp v196, v196, v196 row_ror:8 row_mask:0xf bank_mask:0xf bound_ctrl:1
	s_waitcnt lgkmcnt(6)
	v_pk_mul_f32 v[190:191], v[84:85], v[102:103]
	v_pk_mul_f32 v[192:193], v[148:149], v[102:103]
	v_add_f32_dpp v194, v194, v194 row_ror:4 row_mask:0xf bank_mask:0xf bound_ctrl:1
	v_add_f32_dpp v196, v196, v196 row_ror:4 row_mask:0xf bank_mask:0xf bound_ctrl:1
	v_pk_fma_f32 v[190:191], v[86:87], v[104:105], v[190:191]
	v_pk_fma_f32 v[192:193], v[150:151], v[104:105], v[192:193]
	v_add_f32_dpp v194, v194, v194 row_ror:2 row_mask:0xf bank_mask:0xf bound_ctrl:1
	v_add_f32_dpp v196, v196, v196 row_ror:2 row_mask:0xf bank_mask:0xf bound_ctrl:1
	v_add_f32_e32 v190, v190, v191
	v_add_f32_dpp v194, v194, v194 row_ror:1 row_mask:0xf bank_mask:0xf bound_ctrl:1
	v_add_f32_dpp v196, v196, v196 row_ror:1 row_mask:0xf bank_mask:0xf bound_ctrl:1
	v_add_f32_e32 v192, v192, v193
	ds_write_b32 v182, v194 offset:45696
	ds_write_b32 v182, v196 offset:45760
	ds_read_b128 v[106:109], v134 offset:5888
	v_add_f32_dpp v190, v190, v190 row_ror:8 row_mask:0xf bank_mask:0xf bound_ctrl:1
	v_add_f32_dpp v192, v192, v192 row_ror:8 row_mask:0xf bank_mask:0xf bound_ctrl:1
	s_waitcnt lgkmcnt(6)
	v_pk_mul_f32 v[194:195], v[122:123], v[118:119] op_sel_hi:[0,1]
	v_add_f32_dpp v190, v190, v190 row_ror:4 row_mask:0xf bank_mask:0xf bound_ctrl:1
	v_add_f32_dpp v192, v192, v192 row_ror:4 row_mask:0xf bank_mask:0xf bound_ctrl:1
	v_pk_mul_f32 v[196:197], v[122:123], v[120:121] op_sel_hi:[0,1]
	v_add_f32_dpp v190, v190, v190 row_ror:2 row_mask:0xf bank_mask:0xf bound_ctrl:1
	v_add_f32_dpp v192, v192, v192 row_ror:2 row_mask:0xf bank_mask:0xf bound_ctrl:1
	v_pk_mul_f32 v[198:199], v[122:123], v[118:119] op_sel:[1,0] op_sel_hi:[1,1]
	v_add_f32_dpp v190, v190, v190 row_ror:1 row_mask:0xf bank_mask:0xf bound_ctrl:1
	v_add_f32_dpp v192, v192, v192 row_ror:1 row_mask:0xf bank_mask:0xf bound_ctrl:1
	v_pk_mul_f32 v[152:153], v[122:123], v[120:121] op_sel:[1,0] op_sel_hi:[1,1]
	ds_read_b32 v122, v182 offset:21376
	ds_read_b32 v123, v182 offset:21440
	ds_read_b128 v[118:121], v134 offset:14080
	s_waitcnt lgkmcnt(7)
	v_pk_fma_f32 v[194:195], v[190:191], v[114:115], v[194:195] op_sel_hi:[0,1,1]
	v_pk_fma_f32 v[198:199], v[192:193], v[114:115], v[198:199] op_sel_hi:[0,1,1]
	v_pk_fma_f32 v[196:197], v[190:191], v[116:117], v[196:197] op_sel_hi:[0,1,1]
	v_pk_fma_f32 v[152:153], v[192:193], v[116:117], v[152:153] op_sel_hi:[0,1,1]
	v_pk_fma_f32 v[84:85], v[84:85], v[110:111], v[194:195]
	v_pk_fma_f32 v[148:149], v[148:149], v[110:111], v[198:199]
	v_pk_fma_f32 v[86:87], v[86:87], v[112:113], v[196:197]
	v_pk_fma_f32 v[150:151], v[150:151], v[112:113], v[152:153]
	ds_read_b128 v[110:113], v134 offset:1792
	ds_read_b128 v[114:117], v134 offset:9984
	s_waitcnt lgkmcnt(8)
	v_pk_mul_f32 v[194:195], v[84:85], v[186:187]
	v_pk_mul_f32 v[196:197], v[148:149], v[186:187]
	v_pk_fma_f32 v[194:195], v[86:87], v[188:189], v[194:195]
	v_pk_fma_f32 v[196:197], v[150:151], v[188:189], v[196:197]
	v_add_f32_e32 v194, v194, v195
	v_add_f32_e32 v196, v196, v197
	ds_read_b128 v[186:189], v134 offset:18176
	v_add_f32_dpp v194, v194, v194 row_ror:8 row_mask:0xf bank_mask:0xf bound_ctrl:1
	v_add_f32_dpp v196, v196, v196 row_ror:8 row_mask:0xf bank_mask:0xf bound_ctrl:1
	s_waitcnt lgkmcnt(6)
	v_pk_mul_f32 v[190:191], v[84:85], v[106:107]
	v_pk_mul_f32 v[192:193], v[148:149], v[106:107]
	v_add_f32_dpp v194, v194, v194 row_ror:4 row_mask:0xf bank_mask:0xf bound_ctrl:1
	v_add_f32_dpp v196, v196, v196 row_ror:4 row_mask:0xf bank_mask:0xf bound_ctrl:1
	v_pk_fma_f32 v[190:191], v[86:87], v[108:109], v[190:191]
	v_pk_fma_f32 v[192:193], v[150:151], v[108:109], v[192:193]
	v_add_f32_dpp v194, v194, v194 row_ror:2 row_mask:0xf bank_mask:0xf bound_ctrl:1
	v_add_f32_dpp v196, v196, v196 row_ror:2 row_mask:0xf bank_mask:0xf bound_ctrl:1
	v_add_f32_e32 v190, v190, v191
	v_add_f32_dpp v194, v194, v194 row_ror:1 row_mask:0xf bank_mask:0xf bound_ctrl:1
	v_add_f32_dpp v196, v196, v196 row_ror:1 row_mask:0xf bank_mask:0xf bound_ctrl:1
	v_add_f32_e32 v192, v192, v193
	ds_write_b32 v182, v194 offset:45824
	ds_write_b32 v182, v196 offset:45888
	ds_read_b128 v[102:105], v134 offset:6144
	v_add_f32_dpp v190, v190, v190 row_ror:8 row_mask:0xf bank_mask:0xf bound_ctrl:1
	v_add_f32_dpp v192, v192, v192 row_ror:8 row_mask:0xf bank_mask:0xf bound_ctrl:1
	s_waitcnt lgkmcnt(6)
	v_pk_mul_f32 v[194:195], v[122:123], v[118:119] op_sel_hi:[0,1]
	v_add_f32_dpp v190, v190, v190 row_ror:4 row_mask:0xf bank_mask:0xf bound_ctrl:1
	v_add_f32_dpp v192, v192, v192 row_ror:4 row_mask:0xf bank_mask:0xf bound_ctrl:1
	v_pk_mul_f32 v[196:197], v[122:123], v[120:121] op_sel_hi:[0,1]
	v_add_f32_dpp v190, v190, v190 row_ror:2 row_mask:0xf bank_mask:0xf bound_ctrl:1
	v_add_f32_dpp v192, v192, v192 row_ror:2 row_mask:0xf bank_mask:0xf bound_ctrl:1
	v_pk_mul_f32 v[198:199], v[122:123], v[118:119] op_sel:[1,0] op_sel_hi:[1,1]
	v_add_f32_dpp v190, v190, v190 row_ror:1 row_mask:0xf bank_mask:0xf bound_ctrl:1
	v_add_f32_dpp v192, v192, v192 row_ror:1 row_mask:0xf bank_mask:0xf bound_ctrl:1
	v_pk_mul_f32 v[152:153], v[122:123], v[120:121] op_sel:[1,0] op_sel_hi:[1,1]
	ds_read_b32 v122, v182 offset:21504
	ds_read_b32 v123, v182 offset:21568
	ds_read_b128 v[118:121], v134 offset:14336
	s_waitcnt lgkmcnt(7)
	v_pk_fma_f32 v[194:195], v[190:191], v[114:115], v[194:195] op_sel_hi:[0,1,1]
	v_pk_fma_f32 v[198:199], v[192:193], v[114:115], v[198:199] op_sel_hi:[0,1,1]
	v_pk_fma_f32 v[196:197], v[190:191], v[116:117], v[196:197] op_sel_hi:[0,1,1]
	v_pk_fma_f32 v[152:153], v[192:193], v[116:117], v[152:153] op_sel_hi:[0,1,1]
	v_pk_fma_f32 v[84:85], v[84:85], v[110:111], v[194:195]
	v_pk_fma_f32 v[148:149], v[148:149], v[110:111], v[198:199]
	v_pk_fma_f32 v[86:87], v[86:87], v[112:113], v[196:197]
	v_pk_fma_f32 v[150:151], v[150:151], v[112:113], v[152:153]
	ds_read_b128 v[110:113], v134 offset:2048
	ds_read_b128 v[114:117], v134 offset:10240
	s_waitcnt lgkmcnt(8)
	v_pk_mul_f32 v[194:195], v[84:85], v[186:187]
	v_pk_mul_f32 v[196:197], v[148:149], v[186:187]
	v_pk_fma_f32 v[194:195], v[86:87], v[188:189], v[194:195]
	v_pk_fma_f32 v[196:197], v[150:151], v[188:189], v[196:197]
	v_add_f32_e32 v194, v194, v195
	v_add_f32_e32 v196, v196, v197
	ds_read_b128 v[186:189], v134 offset:18432
	v_add_f32_dpp v194, v194, v194 row_ror:8 row_mask:0xf bank_mask:0xf bound_ctrl:1
	v_add_f32_dpp v196, v196, v196 row_ror:8 row_mask:0xf bank_mask:0xf bound_ctrl:1
	s_waitcnt lgkmcnt(6)
	v_pk_mul_f32 v[190:191], v[84:85], v[102:103]
	v_pk_mul_f32 v[192:193], v[148:149], v[102:103]
	v_add_f32_dpp v194, v194, v194 row_ror:4 row_mask:0xf bank_mask:0xf bound_ctrl:1
	v_add_f32_dpp v196, v196, v196 row_ror:4 row_mask:0xf bank_mask:0xf bound_ctrl:1
	v_pk_fma_f32 v[190:191], v[86:87], v[104:105], v[190:191]
	v_pk_fma_f32 v[192:193], v[150:151], v[104:105], v[192:193]
	v_add_f32_dpp v194, v194, v194 row_ror:2 row_mask:0xf bank_mask:0xf bound_ctrl:1
	v_add_f32_dpp v196, v196, v196 row_ror:2 row_mask:0xf bank_mask:0xf bound_ctrl:1
	v_add_f32_e32 v190, v190, v191
	v_add_f32_dpp v194, v194, v194 row_ror:1 row_mask:0xf bank_mask:0xf bound_ctrl:1
	v_add_f32_dpp v196, v196, v196 row_ror:1 row_mask:0xf bank_mask:0xf bound_ctrl:1
	v_add_f32_e32 v192, v192, v193
	ds_write_b32 v182, v194 offset:45952
	ds_write_b32 v182, v196 offset:46016
	ds_read_b128 v[106:109], v134 offset:6400
	v_add_f32_dpp v190, v190, v190 row_ror:8 row_mask:0xf bank_mask:0xf bound_ctrl:1
	v_add_f32_dpp v192, v192, v192 row_ror:8 row_mask:0xf bank_mask:0xf bound_ctrl:1
	s_waitcnt lgkmcnt(6)
	v_pk_mul_f32 v[194:195], v[122:123], v[118:119] op_sel_hi:[0,1]
	v_add_f32_dpp v190, v190, v190 row_ror:4 row_mask:0xf bank_mask:0xf bound_ctrl:1
	v_add_f32_dpp v192, v192, v192 row_ror:4 row_mask:0xf bank_mask:0xf bound_ctrl:1
	v_pk_mul_f32 v[196:197], v[122:123], v[120:121] op_sel_hi:[0,1]
	v_add_f32_dpp v190, v190, v190 row_ror:2 row_mask:0xf bank_mask:0xf bound_ctrl:1
	v_add_f32_dpp v192, v192, v192 row_ror:2 row_mask:0xf bank_mask:0xf bound_ctrl:1
	v_pk_mul_f32 v[198:199], v[122:123], v[118:119] op_sel:[1,0] op_sel_hi:[1,1]
	v_add_f32_dpp v190, v190, v190 row_ror:1 row_mask:0xf bank_mask:0xf bound_ctrl:1
	v_add_f32_dpp v192, v192, v192 row_ror:1 row_mask:0xf bank_mask:0xf bound_ctrl:1
	v_pk_mul_f32 v[152:153], v[122:123], v[120:121] op_sel:[1,0] op_sel_hi:[1,1]
	ds_read_b32 v122, v182 offset:21632
	ds_read_b32 v123, v182 offset:21696
	ds_read_b128 v[118:121], v134 offset:14592
	s_waitcnt lgkmcnt(7)
	v_pk_fma_f32 v[194:195], v[190:191], v[114:115], v[194:195] op_sel_hi:[0,1,1]
	v_pk_fma_f32 v[198:199], v[192:193], v[114:115], v[198:199] op_sel_hi:[0,1,1]
	v_pk_fma_f32 v[196:197], v[190:191], v[116:117], v[196:197] op_sel_hi:[0,1,1]
	v_pk_fma_f32 v[152:153], v[192:193], v[116:117], v[152:153] op_sel_hi:[0,1,1]
	v_pk_fma_f32 v[84:85], v[84:85], v[110:111], v[194:195]
	v_pk_fma_f32 v[148:149], v[148:149], v[110:111], v[198:199]
	v_pk_fma_f32 v[86:87], v[86:87], v[112:113], v[196:197]
	v_pk_fma_f32 v[150:151], v[150:151], v[112:113], v[152:153]
	ds_read_b128 v[110:113], v134 offset:2304
	ds_read_b128 v[114:117], v134 offset:10496
	s_waitcnt lgkmcnt(8)
	v_pk_mul_f32 v[194:195], v[84:85], v[186:187]
	v_pk_mul_f32 v[196:197], v[148:149], v[186:187]
	v_pk_fma_f32 v[194:195], v[86:87], v[188:189], v[194:195]
	v_pk_fma_f32 v[196:197], v[150:151], v[188:189], v[196:197]
	v_add_f32_e32 v194, v194, v195
	v_add_f32_e32 v196, v196, v197
	ds_read_b128 v[186:189], v134 offset:18688
	v_add_f32_dpp v194, v194, v194 row_ror:8 row_mask:0xf bank_mask:0xf bound_ctrl:1
	v_add_f32_dpp v196, v196, v196 row_ror:8 row_mask:0xf bank_mask:0xf bound_ctrl:1
	s_waitcnt lgkmcnt(6)
	v_pk_mul_f32 v[190:191], v[84:85], v[106:107]
	v_pk_mul_f32 v[192:193], v[148:149], v[106:107]
	v_add_f32_dpp v194, v194, v194 row_ror:4 row_mask:0xf bank_mask:0xf bound_ctrl:1
	v_add_f32_dpp v196, v196, v196 row_ror:4 row_mask:0xf bank_mask:0xf bound_ctrl:1
	v_pk_fma_f32 v[190:191], v[86:87], v[108:109], v[190:191]
	v_pk_fma_f32 v[192:193], v[150:151], v[108:109], v[192:193]
	v_add_f32_dpp v194, v194, v194 row_ror:2 row_mask:0xf bank_mask:0xf bound_ctrl:1
	v_add_f32_dpp v196, v196, v196 row_ror:2 row_mask:0xf bank_mask:0xf bound_ctrl:1
	v_add_f32_e32 v190, v190, v191
	v_add_f32_dpp v194, v194, v194 row_ror:1 row_mask:0xf bank_mask:0xf bound_ctrl:1
	v_add_f32_dpp v196, v196, v196 row_ror:1 row_mask:0xf bank_mask:0xf bound_ctrl:1
	v_add_f32_e32 v192, v192, v193
	ds_write_b32 v182, v194 offset:46080
	ds_write_b32 v182, v196 offset:46144
	ds_read_b128 v[102:105], v134 offset:6656
	v_add_f32_dpp v190, v190, v190 row_ror:8 row_mask:0xf bank_mask:0xf bound_ctrl:1
	v_add_f32_dpp v192, v192, v192 row_ror:8 row_mask:0xf bank_mask:0xf bound_ctrl:1
	s_waitcnt lgkmcnt(6)
	v_pk_mul_f32 v[194:195], v[122:123], v[118:119] op_sel_hi:[0,1]
	v_add_f32_dpp v190, v190, v190 row_ror:4 row_mask:0xf bank_mask:0xf bound_ctrl:1
	v_add_f32_dpp v192, v192, v192 row_ror:4 row_mask:0xf bank_mask:0xf bound_ctrl:1
	v_pk_mul_f32 v[196:197], v[122:123], v[120:121] op_sel_hi:[0,1]
	v_add_f32_dpp v190, v190, v190 row_ror:2 row_mask:0xf bank_mask:0xf bound_ctrl:1
	v_add_f32_dpp v192, v192, v192 row_ror:2 row_mask:0xf bank_mask:0xf bound_ctrl:1
	v_pk_mul_f32 v[198:199], v[122:123], v[118:119] op_sel:[1,0] op_sel_hi:[1,1]
	v_add_f32_dpp v190, v190, v190 row_ror:1 row_mask:0xf bank_mask:0xf bound_ctrl:1
	v_add_f32_dpp v192, v192, v192 row_ror:1 row_mask:0xf bank_mask:0xf bound_ctrl:1
	v_pk_mul_f32 v[152:153], v[122:123], v[120:121] op_sel:[1,0] op_sel_hi:[1,1]
	ds_read_b32 v122, v182 offset:21760
	ds_read_b32 v123, v182 offset:21824
	ds_read_b128 v[118:121], v134 offset:14848
	s_waitcnt lgkmcnt(7)
	v_pk_fma_f32 v[194:195], v[190:191], v[114:115], v[194:195] op_sel_hi:[0,1,1]
	v_pk_fma_f32 v[198:199], v[192:193], v[114:115], v[198:199] op_sel_hi:[0,1,1]
	v_pk_fma_f32 v[196:197], v[190:191], v[116:117], v[196:197] op_sel_hi:[0,1,1]
	v_pk_fma_f32 v[152:153], v[192:193], v[116:117], v[152:153] op_sel_hi:[0,1,1]
	v_pk_fma_f32 v[84:85], v[84:85], v[110:111], v[194:195]
	v_pk_fma_f32 v[148:149], v[148:149], v[110:111], v[198:199]
	v_pk_fma_f32 v[86:87], v[86:87], v[112:113], v[196:197]
	v_pk_fma_f32 v[150:151], v[150:151], v[112:113], v[152:153]
	ds_read_b128 v[110:113], v134 offset:2560
	ds_read_b128 v[114:117], v134 offset:10752
	s_waitcnt lgkmcnt(8)
	v_pk_mul_f32 v[194:195], v[84:85], v[186:187]
	v_pk_mul_f32 v[196:197], v[148:149], v[186:187]
	v_pk_fma_f32 v[194:195], v[86:87], v[188:189], v[194:195]
	v_pk_fma_f32 v[196:197], v[150:151], v[188:189], v[196:197]
	v_add_f32_e32 v194, v194, v195
	v_add_f32_e32 v196, v196, v197
	ds_read_b128 v[186:189], v134 offset:18944
	v_add_f32_dpp v194, v194, v194 row_ror:8 row_mask:0xf bank_mask:0xf bound_ctrl:1
	v_add_f32_dpp v196, v196, v196 row_ror:8 row_mask:0xf bank_mask:0xf bound_ctrl:1
	s_waitcnt lgkmcnt(6)
	v_pk_mul_f32 v[190:191], v[84:85], v[102:103]
	v_pk_mul_f32 v[192:193], v[148:149], v[102:103]
	v_add_f32_dpp v194, v194, v194 row_ror:4 row_mask:0xf bank_mask:0xf bound_ctrl:1
	v_add_f32_dpp v196, v196, v196 row_ror:4 row_mask:0xf bank_mask:0xf bound_ctrl:1
	v_pk_fma_f32 v[190:191], v[86:87], v[104:105], v[190:191]
	v_pk_fma_f32 v[192:193], v[150:151], v[104:105], v[192:193]
	v_add_f32_dpp v194, v194, v194 row_ror:2 row_mask:0xf bank_mask:0xf bound_ctrl:1
	v_add_f32_dpp v196, v196, v196 row_ror:2 row_mask:0xf bank_mask:0xf bound_ctrl:1
	v_add_f32_e32 v190, v190, v191
	v_add_f32_dpp v194, v194, v194 row_ror:1 row_mask:0xf bank_mask:0xf bound_ctrl:1
	v_add_f32_dpp v196, v196, v196 row_ror:1 row_mask:0xf bank_mask:0xf bound_ctrl:1
	v_add_f32_e32 v192, v192, v193
	ds_write_b32 v182, v194 offset:46208
	ds_write_b32 v182, v196 offset:46272
	ds_read_b128 v[106:109], v134 offset:6912
	v_add_f32_dpp v190, v190, v190 row_ror:8 row_mask:0xf bank_mask:0xf bound_ctrl:1
	v_add_f32_dpp v192, v192, v192 row_ror:8 row_mask:0xf bank_mask:0xf bound_ctrl:1
	s_waitcnt lgkmcnt(6)
	v_pk_mul_f32 v[194:195], v[122:123], v[118:119] op_sel_hi:[0,1]
	v_add_f32_dpp v190, v190, v190 row_ror:4 row_mask:0xf bank_mask:0xf bound_ctrl:1
	v_add_f32_dpp v192, v192, v192 row_ror:4 row_mask:0xf bank_mask:0xf bound_ctrl:1
	v_pk_mul_f32 v[196:197], v[122:123], v[120:121] op_sel_hi:[0,1]
	v_add_f32_dpp v190, v190, v190 row_ror:2 row_mask:0xf bank_mask:0xf bound_ctrl:1
	v_add_f32_dpp v192, v192, v192 row_ror:2 row_mask:0xf bank_mask:0xf bound_ctrl:1
	v_pk_mul_f32 v[198:199], v[122:123], v[118:119] op_sel:[1,0] op_sel_hi:[1,1]
	v_add_f32_dpp v190, v190, v190 row_ror:1 row_mask:0xf bank_mask:0xf bound_ctrl:1
	v_add_f32_dpp v192, v192, v192 row_ror:1 row_mask:0xf bank_mask:0xf bound_ctrl:1
	v_pk_mul_f32 v[152:153], v[122:123], v[120:121] op_sel:[1,0] op_sel_hi:[1,1]
	ds_read_b32 v122, v182 offset:21888
	ds_read_b32 v123, v182 offset:21952
	ds_read_b128 v[118:121], v134 offset:15104
	s_waitcnt lgkmcnt(7)
	v_pk_fma_f32 v[194:195], v[190:191], v[114:115], v[194:195] op_sel_hi:[0,1,1]
	v_pk_fma_f32 v[198:199], v[192:193], v[114:115], v[198:199] op_sel_hi:[0,1,1]
	v_pk_fma_f32 v[196:197], v[190:191], v[116:117], v[196:197] op_sel_hi:[0,1,1]
	v_pk_fma_f32 v[152:153], v[192:193], v[116:117], v[152:153] op_sel_hi:[0,1,1]
	v_pk_fma_f32 v[84:85], v[84:85], v[110:111], v[194:195]
	v_pk_fma_f32 v[148:149], v[148:149], v[110:111], v[198:199]
	v_pk_fma_f32 v[86:87], v[86:87], v[112:113], v[196:197]
	v_pk_fma_f32 v[150:151], v[150:151], v[112:113], v[152:153]
	ds_read_b128 v[110:113], v134 offset:2816
	ds_read_b128 v[114:117], v134 offset:11008
	s_waitcnt lgkmcnt(8)
	v_pk_mul_f32 v[194:195], v[84:85], v[186:187]
	v_pk_mul_f32 v[196:197], v[148:149], v[186:187]
	v_pk_fma_f32 v[194:195], v[86:87], v[188:189], v[194:195]
	v_pk_fma_f32 v[196:197], v[150:151], v[188:189], v[196:197]
	v_add_f32_e32 v194, v194, v195
	v_add_f32_e32 v196, v196, v197
	ds_read_b128 v[186:189], v134 offset:19200
	v_add_f32_dpp v194, v194, v194 row_ror:8 row_mask:0xf bank_mask:0xf bound_ctrl:1
	v_add_f32_dpp v196, v196, v196 row_ror:8 row_mask:0xf bank_mask:0xf bound_ctrl:1
	s_waitcnt lgkmcnt(6)
	v_pk_mul_f32 v[190:191], v[84:85], v[106:107]
	v_pk_mul_f32 v[192:193], v[148:149], v[106:107]
	v_add_f32_dpp v194, v194, v194 row_ror:4 row_mask:0xf bank_mask:0xf bound_ctrl:1
	v_add_f32_dpp v196, v196, v196 row_ror:4 row_mask:0xf bank_mask:0xf bound_ctrl:1
	v_pk_fma_f32 v[190:191], v[86:87], v[108:109], v[190:191]
	v_pk_fma_f32 v[192:193], v[150:151], v[108:109], v[192:193]
	v_add_f32_dpp v194, v194, v194 row_ror:2 row_mask:0xf bank_mask:0xf bound_ctrl:1
	v_add_f32_dpp v196, v196, v196 row_ror:2 row_mask:0xf bank_mask:0xf bound_ctrl:1
	v_add_f32_e32 v190, v190, v191
	v_add_f32_dpp v194, v194, v194 row_ror:1 row_mask:0xf bank_mask:0xf bound_ctrl:1
	v_add_f32_dpp v196, v196, v196 row_ror:1 row_mask:0xf bank_mask:0xf bound_ctrl:1
	v_add_f32_e32 v192, v192, v193
	ds_write_b32 v182, v194 offset:46336
	ds_write_b32 v182, v196 offset:46400
	ds_read_b128 v[102:105], v134 offset:7168
	v_add_f32_dpp v190, v190, v190 row_ror:8 row_mask:0xf bank_mask:0xf bound_ctrl:1
	v_add_f32_dpp v192, v192, v192 row_ror:8 row_mask:0xf bank_mask:0xf bound_ctrl:1
	s_waitcnt lgkmcnt(6)
	v_pk_mul_f32 v[194:195], v[122:123], v[118:119] op_sel_hi:[0,1]
	v_add_f32_dpp v190, v190, v190 row_ror:4 row_mask:0xf bank_mask:0xf bound_ctrl:1
	v_add_f32_dpp v192, v192, v192 row_ror:4 row_mask:0xf bank_mask:0xf bound_ctrl:1
	v_pk_mul_f32 v[196:197], v[122:123], v[120:121] op_sel_hi:[0,1]
	v_add_f32_dpp v190, v190, v190 row_ror:2 row_mask:0xf bank_mask:0xf bound_ctrl:1
	v_add_f32_dpp v192, v192, v192 row_ror:2 row_mask:0xf bank_mask:0xf bound_ctrl:1
	v_pk_mul_f32 v[198:199], v[122:123], v[118:119] op_sel:[1,0] op_sel_hi:[1,1]
	v_add_f32_dpp v190, v190, v190 row_ror:1 row_mask:0xf bank_mask:0xf bound_ctrl:1
	v_add_f32_dpp v192, v192, v192 row_ror:1 row_mask:0xf bank_mask:0xf bound_ctrl:1
	v_pk_mul_f32 v[152:153], v[122:123], v[120:121] op_sel:[1,0] op_sel_hi:[1,1]
	ds_read_b32 v122, v182 offset:22016
	ds_read_b32 v123, v182 offset:22080
	ds_read_b128 v[118:121], v134 offset:15360
	s_waitcnt lgkmcnt(7)
	v_pk_fma_f32 v[194:195], v[190:191], v[114:115], v[194:195] op_sel_hi:[0,1,1]
	v_pk_fma_f32 v[198:199], v[192:193], v[114:115], v[198:199] op_sel_hi:[0,1,1]
	v_pk_fma_f32 v[196:197], v[190:191], v[116:117], v[196:197] op_sel_hi:[0,1,1]
	v_pk_fma_f32 v[152:153], v[192:193], v[116:117], v[152:153] op_sel_hi:[0,1,1]
	v_pk_fma_f32 v[84:85], v[84:85], v[110:111], v[194:195]
	v_pk_fma_f32 v[148:149], v[148:149], v[110:111], v[198:199]
	v_pk_fma_f32 v[86:87], v[86:87], v[112:113], v[196:197]
	v_pk_fma_f32 v[150:151], v[150:151], v[112:113], v[152:153]
	ds_read_b128 v[110:113], v134 offset:3072
	ds_read_b128 v[114:117], v134 offset:11264
	s_waitcnt lgkmcnt(8)
	v_pk_mul_f32 v[194:195], v[84:85], v[186:187]
	v_pk_mul_f32 v[196:197], v[148:149], v[186:187]
	v_pk_fma_f32 v[194:195], v[86:87], v[188:189], v[194:195]
	v_pk_fma_f32 v[196:197], v[150:151], v[188:189], v[196:197]
	v_add_f32_e32 v194, v194, v195
	v_add_f32_e32 v196, v196, v197
	ds_read_b128 v[186:189], v134 offset:19456
	v_add_f32_dpp v194, v194, v194 row_ror:8 row_mask:0xf bank_mask:0xf bound_ctrl:1
	v_add_f32_dpp v196, v196, v196 row_ror:8 row_mask:0xf bank_mask:0xf bound_ctrl:1
	s_waitcnt lgkmcnt(6)
	v_pk_mul_f32 v[190:191], v[84:85], v[102:103]
	v_pk_mul_f32 v[192:193], v[148:149], v[102:103]
	v_add_f32_dpp v194, v194, v194 row_ror:4 row_mask:0xf bank_mask:0xf bound_ctrl:1
	v_add_f32_dpp v196, v196, v196 row_ror:4 row_mask:0xf bank_mask:0xf bound_ctrl:1
	v_pk_fma_f32 v[190:191], v[86:87], v[104:105], v[190:191]
	v_pk_fma_f32 v[192:193], v[150:151], v[104:105], v[192:193]
	v_add_f32_dpp v194, v194, v194 row_ror:2 row_mask:0xf bank_mask:0xf bound_ctrl:1
	v_add_f32_dpp v196, v196, v196 row_ror:2 row_mask:0xf bank_mask:0xf bound_ctrl:1
	v_add_f32_e32 v190, v190, v191
	v_add_f32_dpp v194, v194, v194 row_ror:1 row_mask:0xf bank_mask:0xf bound_ctrl:1
	v_add_f32_dpp v196, v196, v196 row_ror:1 row_mask:0xf bank_mask:0xf bound_ctrl:1
	v_add_f32_e32 v192, v192, v193
	ds_write_b32 v182, v194 offset:46464
	ds_write_b32 v182, v196 offset:46528
	ds_read_b128 v[106:109], v134 offset:7424
	v_add_f32_dpp v190, v190, v190 row_ror:8 row_mask:0xf bank_mask:0xf bound_ctrl:1
	v_add_f32_dpp v192, v192, v192 row_ror:8 row_mask:0xf bank_mask:0xf bound_ctrl:1
	s_waitcnt lgkmcnt(6)
	v_pk_mul_f32 v[194:195], v[122:123], v[118:119] op_sel_hi:[0,1]
	v_add_f32_dpp v190, v190, v190 row_ror:4 row_mask:0xf bank_mask:0xf bound_ctrl:1
	v_add_f32_dpp v192, v192, v192 row_ror:4 row_mask:0xf bank_mask:0xf bound_ctrl:1
	v_pk_mul_f32 v[196:197], v[122:123], v[120:121] op_sel_hi:[0,1]
	v_add_f32_dpp v190, v190, v190 row_ror:2 row_mask:0xf bank_mask:0xf bound_ctrl:1
	v_add_f32_dpp v192, v192, v192 row_ror:2 row_mask:0xf bank_mask:0xf bound_ctrl:1
	v_pk_mul_f32 v[198:199], v[122:123], v[118:119] op_sel:[1,0] op_sel_hi:[1,1]
	v_add_f32_dpp v190, v190, v190 row_ror:1 row_mask:0xf bank_mask:0xf bound_ctrl:1
	v_add_f32_dpp v192, v192, v192 row_ror:1 row_mask:0xf bank_mask:0xf bound_ctrl:1
	v_pk_mul_f32 v[152:153], v[122:123], v[120:121] op_sel:[1,0] op_sel_hi:[1,1]
	ds_read_b32 v122, v182 offset:22144
	ds_read_b32 v123, v182 offset:22208
	ds_read_b128 v[118:121], v134 offset:15616
	s_waitcnt lgkmcnt(7)
	v_pk_fma_f32 v[194:195], v[190:191], v[114:115], v[194:195] op_sel_hi:[0,1,1]
	v_pk_fma_f32 v[198:199], v[192:193], v[114:115], v[198:199] op_sel_hi:[0,1,1]
	v_pk_fma_f32 v[196:197], v[190:191], v[116:117], v[196:197] op_sel_hi:[0,1,1]
	v_pk_fma_f32 v[152:153], v[192:193], v[116:117], v[152:153] op_sel_hi:[0,1,1]
	v_pk_fma_f32 v[84:85], v[84:85], v[110:111], v[194:195]
	v_pk_fma_f32 v[148:149], v[148:149], v[110:111], v[198:199]
	v_pk_fma_f32 v[86:87], v[86:87], v[112:113], v[196:197]
	v_pk_fma_f32 v[150:151], v[150:151], v[112:113], v[152:153]
	ds_read_b128 v[110:113], v134 offset:3328
	ds_read_b128 v[114:117], v134 offset:11520
	s_waitcnt lgkmcnt(8)
	v_pk_mul_f32 v[194:195], v[84:85], v[186:187]
	v_pk_mul_f32 v[196:197], v[148:149], v[186:187]
	v_pk_fma_f32 v[194:195], v[86:87], v[188:189], v[194:195]
	v_pk_fma_f32 v[196:197], v[150:151], v[188:189], v[196:197]
	v_add_f32_e32 v194, v194, v195
	v_add_f32_e32 v196, v196, v197
	ds_read_b128 v[186:189], v134 offset:19712
	v_add_f32_dpp v194, v194, v194 row_ror:8 row_mask:0xf bank_mask:0xf bound_ctrl:1
	v_add_f32_dpp v196, v196, v196 row_ror:8 row_mask:0xf bank_mask:0xf bound_ctrl:1
	s_waitcnt lgkmcnt(6)
	v_pk_mul_f32 v[190:191], v[84:85], v[106:107]
	v_pk_mul_f32 v[192:193], v[148:149], v[106:107]
	v_add_f32_dpp v194, v194, v194 row_ror:4 row_mask:0xf bank_mask:0xf bound_ctrl:1
	v_add_f32_dpp v196, v196, v196 row_ror:4 row_mask:0xf bank_mask:0xf bound_ctrl:1
	v_pk_fma_f32 v[190:191], v[86:87], v[108:109], v[190:191]
	v_pk_fma_f32 v[192:193], v[150:151], v[108:109], v[192:193]
	v_add_f32_dpp v194, v194, v194 row_ror:2 row_mask:0xf bank_mask:0xf bound_ctrl:1
	v_add_f32_dpp v196, v196, v196 row_ror:2 row_mask:0xf bank_mask:0xf bound_ctrl:1
	v_add_f32_e32 v190, v190, v191
	v_add_f32_dpp v194, v194, v194 row_ror:1 row_mask:0xf bank_mask:0xf bound_ctrl:1
	v_add_f32_dpp v196, v196, v196 row_ror:1 row_mask:0xf bank_mask:0xf bound_ctrl:1
	v_add_f32_e32 v192, v192, v193
	ds_write_b32 v182, v194 offset:46592
	ds_write_b32 v182, v196 offset:46656
	ds_read_b128 v[102:105], v134 offset:7680
	v_add_f32_dpp v190, v190, v190 row_ror:8 row_mask:0xf bank_mask:0xf bound_ctrl:1
	v_add_f32_dpp v192, v192, v192 row_ror:8 row_mask:0xf bank_mask:0xf bound_ctrl:1
	s_waitcnt lgkmcnt(6)
	v_pk_mul_f32 v[194:195], v[122:123], v[118:119] op_sel_hi:[0,1]
	v_add_f32_dpp v190, v190, v190 row_ror:4 row_mask:0xf bank_mask:0xf bound_ctrl:1
	v_add_f32_dpp v192, v192, v192 row_ror:4 row_mask:0xf bank_mask:0xf bound_ctrl:1
	v_pk_mul_f32 v[196:197], v[122:123], v[120:121] op_sel_hi:[0,1]
	v_add_f32_dpp v190, v190, v190 row_ror:2 row_mask:0xf bank_mask:0xf bound_ctrl:1
	v_add_f32_dpp v192, v192, v192 row_ror:2 row_mask:0xf bank_mask:0xf bound_ctrl:1
	v_pk_mul_f32 v[198:199], v[122:123], v[118:119] op_sel:[1,0] op_sel_hi:[1,1]
	v_add_f32_dpp v190, v190, v190 row_ror:1 row_mask:0xf bank_mask:0xf bound_ctrl:1
	v_add_f32_dpp v192, v192, v192 row_ror:1 row_mask:0xf bank_mask:0xf bound_ctrl:1
	v_pk_mul_f32 v[152:153], v[122:123], v[120:121] op_sel:[1,0] op_sel_hi:[1,1]
	ds_read_b32 v122, v182 offset:22272
	ds_read_b32 v123, v182 offset:22336
	ds_read_b128 v[118:121], v134 offset:15872
	s_waitcnt lgkmcnt(7)
	v_pk_fma_f32 v[194:195], v[190:191], v[114:115], v[194:195] op_sel_hi:[0,1,1]
	v_pk_fma_f32 v[198:199], v[192:193], v[114:115], v[198:199] op_sel_hi:[0,1,1]
	v_pk_fma_f32 v[196:197], v[190:191], v[116:117], v[196:197] op_sel_hi:[0,1,1]
	v_pk_fma_f32 v[152:153], v[192:193], v[116:117], v[152:153] op_sel_hi:[0,1,1]
	v_pk_fma_f32 v[84:85], v[84:85], v[110:111], v[194:195]
	v_pk_fma_f32 v[148:149], v[148:149], v[110:111], v[198:199]
	v_pk_fma_f32 v[86:87], v[86:87], v[112:113], v[196:197]
	v_pk_fma_f32 v[150:151], v[150:151], v[112:113], v[152:153]
	ds_read_b128 v[110:113], v134 offset:3584
	ds_read_b128 v[114:117], v134 offset:11776
	s_waitcnt lgkmcnt(8)
	v_pk_mul_f32 v[194:195], v[84:85], v[186:187]
	v_pk_mul_f32 v[196:197], v[148:149], v[186:187]
	v_pk_fma_f32 v[194:195], v[86:87], v[188:189], v[194:195]
	v_pk_fma_f32 v[196:197], v[150:151], v[188:189], v[196:197]
	v_add_f32_e32 v194, v194, v195
	v_add_f32_e32 v196, v196, v197
	ds_read_b128 v[186:189], v134 offset:19968
	v_add_f32_dpp v194, v194, v194 row_ror:8 row_mask:0xf bank_mask:0xf bound_ctrl:1
	v_add_f32_dpp v196, v196, v196 row_ror:8 row_mask:0xf bank_mask:0xf bound_ctrl:1
	s_waitcnt lgkmcnt(6)
	v_pk_mul_f32 v[190:191], v[84:85], v[102:103]
	v_pk_mul_f32 v[192:193], v[148:149], v[102:103]
	v_add_f32_dpp v194, v194, v194 row_ror:4 row_mask:0xf bank_mask:0xf bound_ctrl:1
	v_add_f32_dpp v196, v196, v196 row_ror:4 row_mask:0xf bank_mask:0xf bound_ctrl:1
	v_pk_fma_f32 v[190:191], v[86:87], v[104:105], v[190:191]
	v_pk_fma_f32 v[192:193], v[150:151], v[104:105], v[192:193]
	v_add_f32_dpp v194, v194, v194 row_ror:2 row_mask:0xf bank_mask:0xf bound_ctrl:1
	v_add_f32_dpp v196, v196, v196 row_ror:2 row_mask:0xf bank_mask:0xf bound_ctrl:1
	v_add_f32_e32 v190, v190, v191
	v_add_f32_dpp v194, v194, v194 row_ror:1 row_mask:0xf bank_mask:0xf bound_ctrl:1
	v_add_f32_dpp v196, v196, v196 row_ror:1 row_mask:0xf bank_mask:0xf bound_ctrl:1
	v_add_f32_e32 v192, v192, v193
	ds_write_b32 v182, v194 offset:46720
	ds_write_b32 v182, v196 offset:46784
	ds_read_b128 v[106:109], v134 offset:7936
	v_add_f32_dpp v190, v190, v190 row_ror:8 row_mask:0xf bank_mask:0xf bound_ctrl:1
	v_add_f32_dpp v192, v192, v192 row_ror:8 row_mask:0xf bank_mask:0xf bound_ctrl:1
	s_waitcnt lgkmcnt(6)
	v_pk_mul_f32 v[194:195], v[122:123], v[118:119] op_sel_hi:[0,1]
	v_add_f32_dpp v190, v190, v190 row_ror:4 row_mask:0xf bank_mask:0xf bound_ctrl:1
	v_add_f32_dpp v192, v192, v192 row_ror:4 row_mask:0xf bank_mask:0xf bound_ctrl:1
	v_pk_mul_f32 v[196:197], v[122:123], v[120:121] op_sel_hi:[0,1]
	v_add_f32_dpp v190, v190, v190 row_ror:2 row_mask:0xf bank_mask:0xf bound_ctrl:1
	v_add_f32_dpp v192, v192, v192 row_ror:2 row_mask:0xf bank_mask:0xf bound_ctrl:1
	v_pk_mul_f32 v[198:199], v[122:123], v[118:119] op_sel:[1,0] op_sel_hi:[1,1]
	v_add_f32_dpp v190, v190, v190 row_ror:1 row_mask:0xf bank_mask:0xf bound_ctrl:1
	v_add_f32_dpp v192, v192, v192 row_ror:1 row_mask:0xf bank_mask:0xf bound_ctrl:1
	v_pk_mul_f32 v[152:153], v[122:123], v[120:121] op_sel:[1,0] op_sel_hi:[1,1]
	ds_read_b32 v122, v182 offset:22400
	ds_read_b32 v123, v182 offset:22464
	ds_read_b128 v[118:121], v134 offset:16128
	s_waitcnt lgkmcnt(7)
	v_pk_fma_f32 v[194:195], v[190:191], v[114:115], v[194:195] op_sel_hi:[0,1,1]
	v_pk_fma_f32 v[198:199], v[192:193], v[114:115], v[198:199] op_sel_hi:[0,1,1]
	v_pk_fma_f32 v[196:197], v[190:191], v[116:117], v[196:197] op_sel_hi:[0,1,1]
	v_pk_fma_f32 v[152:153], v[192:193], v[116:117], v[152:153] op_sel_hi:[0,1,1]
	v_pk_fma_f32 v[84:85], v[84:85], v[110:111], v[194:195]
	v_pk_fma_f32 v[148:149], v[148:149], v[110:111], v[198:199]
	v_pk_fma_f32 v[86:87], v[86:87], v[112:113], v[196:197]
	v_pk_fma_f32 v[150:151], v[150:151], v[112:113], v[152:153]
	ds_read_b128 v[110:113], v134 offset:3840
	ds_read_b128 v[114:117], v134 offset:12032
	s_waitcnt lgkmcnt(8)
	v_pk_mul_f32 v[194:195], v[84:85], v[186:187]
	v_pk_mul_f32 v[196:197], v[148:149], v[186:187]
	v_pk_fma_f32 v[194:195], v[86:87], v[188:189], v[194:195]
	v_pk_fma_f32 v[196:197], v[150:151], v[188:189], v[196:197]
	v_add_f32_e32 v194, v194, v195
	v_add_f32_e32 v196, v196, v197
	ds_read_b128 v[186:189], v134 offset:20224
	v_add_f32_dpp v194, v194, v194 row_ror:8 row_mask:0xf bank_mask:0xf bound_ctrl:1
	v_add_f32_dpp v196, v196, v196 row_ror:8 row_mask:0xf bank_mask:0xf bound_ctrl:1
	s_waitcnt lgkmcnt(6)
	v_pk_mul_f32 v[190:191], v[84:85], v[106:107]
	v_pk_mul_f32 v[192:193], v[148:149], v[106:107]
	v_add_f32_dpp v194, v194, v194 row_ror:4 row_mask:0xf bank_mask:0xf bound_ctrl:1
	v_add_f32_dpp v196, v196, v196 row_ror:4 row_mask:0xf bank_mask:0xf bound_ctrl:1
	v_pk_fma_f32 v[190:191], v[86:87], v[108:109], v[190:191]
	v_pk_fma_f32 v[192:193], v[150:151], v[108:109], v[192:193]
	v_add_f32_dpp v194, v194, v194 row_ror:2 row_mask:0xf bank_mask:0xf bound_ctrl:1
	v_add_f32_dpp v196, v196, v196 row_ror:2 row_mask:0xf bank_mask:0xf bound_ctrl:1
	v_add_f32_e32 v190, v190, v191
	v_add_f32_dpp v194, v194, v194 row_ror:1 row_mask:0xf bank_mask:0xf bound_ctrl:1
	v_add_f32_dpp v196, v196, v196 row_ror:1 row_mask:0xf bank_mask:0xf bound_ctrl:1
	v_add_f32_e32 v192, v192, v193
	ds_write_b32 v182, v194 offset:46848
	ds_write_b32 v182, v196 offset:46912
	v_add_f32_dpp v190, v190, v190 row_ror:8 row_mask:0xf bank_mask:0xf bound_ctrl:1
	v_add_f32_dpp v192, v192, v192 row_ror:8 row_mask:0xf bank_mask:0xf bound_ctrl:1
	s_waitcnt lgkmcnt(5)
	v_pk_mul_f32 v[194:195], v[122:123], v[118:119] op_sel_hi:[0,1]
	v_add_f32_dpp v190, v190, v190 row_ror:4 row_mask:0xf bank_mask:0xf bound_ctrl:1
	v_add_f32_dpp v192, v192, v192 row_ror:4 row_mask:0xf bank_mask:0xf bound_ctrl:1
	v_pk_mul_f32 v[196:197], v[122:123], v[120:121] op_sel_hi:[0,1]
	v_add_f32_dpp v190, v190, v190 row_ror:2 row_mask:0xf bank_mask:0xf bound_ctrl:1
	v_add_f32_dpp v192, v192, v192 row_ror:2 row_mask:0xf bank_mask:0xf bound_ctrl:1
	v_pk_mul_f32 v[198:199], v[122:123], v[118:119] op_sel:[1,0] op_sel_hi:[1,1]
	v_add_f32_dpp v190, v190, v190 row_ror:1 row_mask:0xf bank_mask:0xf bound_ctrl:1
	v_add_f32_dpp v192, v192, v192 row_ror:1 row_mask:0xf bank_mask:0xf bound_ctrl:1
	v_pk_mul_f32 v[152:153], v[122:123], v[120:121] op_sel:[1,0] op_sel_hi:[1,1]
	s_waitcnt lgkmcnt(3)
	v_pk_fma_f32 v[194:195], v[190:191], v[114:115], v[194:195] op_sel_hi:[0,1,1]
	v_pk_fma_f32 v[198:199], v[192:193], v[114:115], v[198:199] op_sel_hi:[0,1,1]
	v_pk_fma_f32 v[196:197], v[190:191], v[116:117], v[196:197] op_sel_hi:[0,1,1]
	v_pk_fma_f32 v[152:153], v[192:193], v[116:117], v[152:153] op_sel_hi:[0,1,1]
	v_pk_fma_f32 v[84:85], v[84:85], v[110:111], v[194:195]
	v_pk_fma_f32 v[148:149], v[148:149], v[110:111], v[198:199]
	v_pk_fma_f32 v[86:87], v[86:87], v[112:113], v[196:197]
	v_pk_fma_f32 v[150:151], v[150:151], v[112:113], v[152:153]
	s_waitcnt lgkmcnt(2)
	v_pk_mul_f32 v[194:195], v[84:85], v[186:187]
	v_pk_mul_f32 v[196:197], v[148:149], v[186:187]
	v_pk_fma_f32 v[194:195], v[86:87], v[188:189], v[194:195]
	v_pk_fma_f32 v[196:197], v[150:151], v[188:189], v[196:197]
	v_add_f32_e32 v194, v194, v195
	v_add_f32_e32 v196, v196, v197
	s_nop 0
	v_add_f32_dpp v194, v194, v194 row_ror:8 row_mask:0xf bank_mask:0xf bound_ctrl:1
	v_add_f32_dpp v196, v196, v196 row_ror:8 row_mask:0xf bank_mask:0xf bound_ctrl:1
	s_nop 0
	v_add_f32_dpp v194, v194, v194 row_ror:4 row_mask:0xf bank_mask:0xf bound_ctrl:1
	v_add_f32_dpp v196, v196, v196 row_ror:4 row_mask:0xf bank_mask:0xf bound_ctrl:1
	s_nop 0
	v_add_f32_dpp v194, v194, v194 row_ror:2 row_mask:0xf bank_mask:0xf bound_ctrl:1
	v_add_f32_dpp v196, v196, v196 row_ror:2 row_mask:0xf bank_mask:0xf bound_ctrl:1
	s_nop 0
	v_add_f32_dpp v194, v194, v194 row_ror:1 row_mask:0xf bank_mask:0xf bound_ctrl:1
	v_add_f32_dpp v196, v196, v196 row_ror:1 row_mask:0xf bank_mask:0xf bound_ctrl:1
	ds_write_b32 v182, v194 offset:46976
	ds_write_b32 v182, v196 offset:47040
	s_and_saveexec_b64 s[8:9], s[38:39]
	s_cbranch_execz .LBB0_453
	v_add_f32_e32 v88, v0, v76
	v_min_f32_e32 v92, 0, v88
	v_mul_f32_e64 v88, |v88|, s62
	v_exp_f32_e32 v88, v88
	v_add_f32_e32 v89, v1, v77
	v_add_f32_e32 v90, v2, v78
	v_add_f32_e32 v91, v3, v79
	v_add_f32_e32 v88, 1.0, v88
	v_cmp_gt_f32_e32 vcc, s5, v88
	s_mov_b32 s4, 0xf800000
	v_add_f32_e32 v80, v4, v72
	v_cndmask_b32_e64 v93, 0, 32, vcc
	v_ldexp_f32 v88, v88, v93
	v_log_f32_e32 v88, v88
	v_mul_f32_e32 v80, 0xbfb8aa3b, v80
	v_exp_f32_e32 v82, v80
	v_add_f32_e32 v80, v5, v73
	v_mul_f32_e32 v93, 0x3f317217, v88
	v_fma_f32 v93, v88, s76, -v93
	v_fmac_f32_e32 v93, 0x3377d1cf, v88
	v_fmac_f32_e32 v93, 0x3f317217, v88
	v_cmp_lt_f32_e64 s[42:43], |v88|, s77
	v_mul_f32_e32 v80, 0xbfb8aa3b, v80
	v_exp_f32_e32 v83, v80
	v_cndmask_b32_e64 v88, v88, v93, s[42:43]
	v_cndmask_b32_e32 v93, 0, v171, vcc
	v_sub_f32_e32 v88, v88, v93
	v_sub_f32_e32 v88, v92, v88
	v_min_f32_e32 v92, 0, v89
	v_mul_f32_e64 v89, |v89|, s62
	v_exp_f32_e32 v89, v89
	v_add_f32_e32 v88, -0.5, v88
	v_mul_f32_e32 v88, 0x3fb8aa3b, v88
	v_exp_f32_e32 v88, v88
	v_add_f32_e32 v89, 1.0, v89
	v_cmp_gt_f32_e32 vcc, s5, v89
	v_pk_add_f32 v[82:83], v[82:83], 1.0 op_sel_hi:[1,0]
	v_mul_f32_e32 v88, 0xbfb8aa3b, v88
	v_cndmask_b32_e64 v93, 0, 32, vcc
	v_ldexp_f32 v89, v89, v93
	v_log_f32_e32 v89, v89
	v_exp_f32_e32 v88, v88
	v_add_f32_e32 v80, v6, v74
	v_add_f32_e32 v81, v7, v75
	v_mul_f32_e32 v93, 0x3f317217, v89
	v_fma_f32 v93, v89, s76, -v93
	v_fmac_f32_e32 v93, 0x3377d1cf, v89
	v_fmac_f32_e32 v93, 0x3f317217, v89
	v_cmp_lt_f32_e64 s[42:43], |v89|, s77
	v_mul_f32_e32 v80, 0xbfb8aa3b, v80
	v_mul_f32_e32 v81, 0xbfb8aa3b, v81
	v_cndmask_b32_e64 v89, v89, v93, s[42:43]
	v_cndmask_b32_e32 v93, 0, v171, vcc
	v_sub_f32_e32 v89, v89, v93
	v_sub_f32_e32 v89, v92, v89
	v_min_f32_e32 v92, 0, v90
	v_mul_f32_e64 v90, |v90|, s62
	v_exp_f32_e32 v90, v90
	v_add_f32_e32 v89, -0.5, v89
	v_mul_f32_e32 v89, 0x3fb8aa3b, v89
	v_exp_f32_e32 v89, v89
	v_add_f32_e32 v90, 1.0, v90
	v_cmp_gt_f32_e32 vcc, s5, v90
	v_exp_f32_e32 v80, v80
	v_mul_f32_e32 v89, 0xbfb8aa3b, v89
	v_cndmask_b32_e64 v93, 0, 32, vcc
	v_ldexp_f32 v90, v90, v93
	v_log_f32_e32 v90, v90
	v_exp_f32_e32 v89, v89
	v_exp_f32_e32 v81, v81
	v_mul_f32_e32 v93, 0x3f317217, v90
	v_fma_f32 v93, v90, s76, -v93
	v_fmac_f32_e32 v93, 0x3377d1cf, v90
	v_fmac_f32_e32 v93, 0x3f317217, v90
	v_cmp_lt_f32_e64 s[42:43], |v90|, s77
	v_pk_add_f32 v[80:81], v[80:81], 1.0 op_sel_hi:[1,0]
	s_nop 0
	v_cndmask_b32_e64 v90, v90, v93, s[42:43]
	v_cndmask_b32_e32 v93, 0, v171, vcc
	v_sub_f32_e32 v90, v90, v93
	v_sub_f32_e32 v90, v92, v90
	v_min_f32_e32 v92, 0, v91
	v_mul_f32_e64 v91, |v91|, s62
	v_exp_f32_e32 v91, v91
	v_add_f32_e32 v90, -0.5, v90
	v_mul_f32_e32 v90, 0x3fb8aa3b, v90
	v_exp_f32_e32 v90, v90
	v_add_f32_e32 v91, 1.0, v91
	v_cmp_gt_f32_e32 vcc, s5, v91
	v_mul_f32_e32 v90, 0xbfb8aa3b, v90
	s_nop 0
	v_cndmask_b32_e64 v93, 0, 32, vcc
	v_ldexp_f32 v91, v91, v93
	v_log_f32_e32 v91, v91
	v_exp_f32_e32 v90, v90
	v_mul_f32_e32 v93, 0x3f317217, v91
	v_fma_f32 v93, v91, s76, -v93
	v_fmac_f32_e32 v93, 0x3377d1cf, v91
	v_fmac_f32_e32 v93, 0x3f317217, v91
	v_cmp_lt_f32_e64 s[42:43], |v91|, s77
	s_nop 1
	v_cndmask_b32_e64 v91, v91, v93, s[42:43]
	v_cndmask_b32_e32 v93, 0, v171, vcc
	v_sub_f32_e32 v91, v91, v93
	v_sub_f32_e32 v91, v92, v91
	v_add_f32_e32 v91, -0.5, v91
	v_mul_f32_e32 v91, 0x3fb8aa3b, v91
	v_exp_f32_e32 v91, v91
	v_pk_mul_f32 v[92:93], v[10:11], v[70:71]
	v_mul_f32_e32 v91, 0xbfb8aa3b, v91
	v_exp_f32_e32 v91, v91
	v_pk_mul_f32 v[94:95], v[92:93], v[92:93]
	ds_write_b128 v181, v[88:91] offset:22528
	v_pk_mul_f32 v[88:89], v[8:9], v[68:69]
	v_pk_mul_f32 v[90:91], v[88:89], v[88:89]
	v_add_f32_e32 v90, v91, v90
	v_add_f32_e32 v90, v94, v90
	v_add_f32_e32 v90, v95, v90
	s_nop 1
	v_add_f32_dpp v90, v90, v90 row_ror:8 row_mask:0xf bank_mask:0xf bound_ctrl:1
	s_nop 1
	v_add_f32_dpp v90, v90, v90 row_ror:4 row_mask:0xf bank_mask:0xf bound_ctrl:1
	s_nop 1
	v_add_f32_dpp v90, v90, v90 row_ror:2 row_mask:0xf bank_mask:0xf bound_ctrl:1
	s_nop 1
	v_add_f32_dpp v90, v90, v90 row_ror:1 row_mask:0xf bank_mask:0xf bound_ctrl:1
	v_cmp_gt_f32_e32 vcc, s4, v90
	v_mul_f32_e32 v91, 0x4f800000, v90
	s_nop 0
	v_cndmask_b32_e32 v90, v90, v91, vcc
	v_sqrt_f32_e32 v91, v90
	s_nop 0
	v_add_u32_e32 v94, -1, v91
	v_fma_f32 v95, -v94, v91, v90
	v_cmp_ge_f32_e64 s[42:43], 0, v95
	v_add_u32_e32 v95, 1, v91
	s_nop 0
	v_cndmask_b32_e64 v94, v91, v94, s[42:43]
	v_fma_f32 v91, -v95, v91, v90
	v_cmp_lt_f32_e64 s[42:43], 0, v91
	s_nop 1
	v_cndmask_b32_e64 v91, v94, v95, s[42:43]
	v_mul_f32_e32 v94, 0x37800000, v91
	v_cndmask_b32_e32 v91, v91, v94, vcc
	v_cmp_class_f32_e32 vcc, v90, v160
	s_nop 1
	v_cndmask_b32_e32 v90, v91, v90, vcc
	v_max_f32_e32 v90, 0x2b8cbccc, v90
	v_div_scale_f32 v91, s[22:23], v90, v90, 1.0
	v_rcp_f32_e32 v94, v91
	s_nop 0
	v_fma_f32 v95, -v91, v94, 1.0
	v_fmac_f32_e32 v94, v95, v94
	v_div_scale_f32 v95, vcc, 1.0, v90, 1.0
	v_mul_f32_e32 v100, v95, v94
	v_fma_f32 v101, -v91, v100, v95
	v_fmac_f32_e32 v100, v101, v94
	v_fma_f32 v91, -v91, v100, v95
	v_div_fmas_f32 v91, v91, v94, v100
	v_div_fixup_f32 v90, v91, v90, 1.0
	v_pk_mul_f32 v[94:95], v[88:89], v[90:91] op_sel_hi:[1,0]
	v_pk_mul_f32 v[92:93], v[92:93], v[90:91] op_sel_hi:[1,0]
	v_xor_b32_e32 v89, 0x80000000, v95
	v_xor_b32_e32 v88, 0x80000000, v94
	v_xor_b32_e32 v91, 0x80000000, v93
	v_xor_b32_e32 v90, 0x80000000, v92
	ds_write_b128 v181, v[88:91] offset:26624
	v_div_scale_f32 v88, s[22:23], v83, v83, 1.0
	v_rcp_f32_e32 v89, v88
	s_nop 0
	v_fma_f32 v90, -v88, v89, 1.0
	v_fmac_f32_e32 v89, v90, v89
	v_div_scale_f32 v90, vcc, 1.0, v83, 1.0
	v_mul_f32_e32 v91, v90, v89
	v_fma_f32 v100, -v88, v91, v90
	v_fmac_f32_e32 v91, v100, v89
	v_fma_f32 v88, -v88, v91, v90
	v_div_fmas_f32 v88, v88, v89, v91
	v_div_fixup_f32 v83, v88, v83, 1.0
	v_div_scale_f32 v88, s[22:23], v82, v82, 1.0
	v_rcp_f32_e32 v89, v88
	s_nop 0
	v_fma_f32 v90, -v88, v89, 1.0
	v_fmac_f32_e32 v89, v90, v89
	v_div_scale_f32 v90, vcc, 1.0, v82, 1.0
	v_mul_f32_e32 v91, v90, v89
	v_fma_f32 v100, -v88, v91, v90
	v_fmac_f32_e32 v91, v100, v89
	v_fma_f32 v88, -v88, v91, v90
	v_div_scale_f32 v90, s[22:23], v81, v81, 1.0
	v_div_fmas_f32 v88, v88, v89, v91
	v_rcp_f32_e32 v91, v90
	v_div_fixup_f32 v82, v88, v82, 1.0
	v_pk_mul_f32 v[88:89], v[82:83], v[94:95]
	v_fma_f32 v94, -v90, v91, 1.0
	v_fmac_f32_e32 v91, v94, v91
	v_div_scale_f32 v94, vcc, 1.0, v81, 1.0
	v_mul_f32_e32 v95, v94, v91
	v_fma_f32 v100, -v90, v95, v94
	v_fmac_f32_e32 v95, v100, v91
	v_fma_f32 v90, -v90, v95, v94
	v_div_fmas_f32 v90, v90, v91, v95
	v_div_fixup_f32 v95, v90, v81, 1.0
	v_div_scale_f32 v81, s[22:23], v80, v80, 1.0
	v_rcp_f32_e32 v90, v81
	s_nop 0
	v_fma_f32 v91, -v81, v90, 1.0
	v_fmac_f32_e32 v90, v91, v90
	v_div_scale_f32 v91, vcc, 1.0, v80, 1.0
	v_mul_f32_e32 v94, v91, v90
	v_fma_f32 v100, -v81, v94, v91
	v_fmac_f32_e32 v94, v100, v90
	v_fma_f32 v81, -v81, v94, v91
	v_div_fmas_f32 v81, v81, v90, v94
	v_div_fixup_f32 v94, v81, v80, 1.0
	v_pk_add_f32 v[80:81], v[82:83], -1.0 op_sel_hi:[1,0]
	v_pk_add_f32 v[82:83], v[94:95], -1.0 op_sel_hi:[1,0]
	v_pk_fma_f32 v[80:81], v[12:13], v[80:81], 1.0 op_sel_hi:[1,1,0]
	v_pk_fma_f32 v[82:83], v[14:15], v[82:83], 1.0 op_sel_hi:[1,1,0]
	v_pk_mul_f32 v[90:91], v[94:95], v[92:93]
	v_pk_mul_f32 v[80:81], v[68:69], v[80:81]
	v_pk_mul_f32 v[82:83], v[70:71], v[82:83]
	ds_write_b128 v181, v[88:91] offset:30720
	ds_write_b128 v181, v[80:83] offset:34816
	ds_write_b128 v181, v[48:51] offset:38912

.LBB0_457:
	ds_read2st64_b32 v[80:81], v179 offset0:176 offset1:180
	v_add_u32_e32 v82, 32, v126
	v_ashrrev_i32_e32 v83, 31, v82
	v_lshlrev_b64 v[82:83], 13, v[82:83]
	v_lshl_add_u64 v[82:83], v[144:145], 0, v[82:83]
	s_waitcnt lgkmcnt(0)
	global_store_dword v[82:83], v80, off
	v_add_u32_e32 v82, 32, v124
	v_ashrrev_i32_e32 v83, 31, v82
	v_lshlrev_b64 v[82:83], 13, v[82:83]
	v_lshl_add_u64 v[82:83], v[144:145], 0, v[82:83]
	global_store_dword v[82:83], v81, off
	ds_read_b128 v[102:105], v134 offset:26624
	ds_read_b32 v122, v182 offset:43008
	ds_read_b32 v123, v182 offset:43072
	ds_read_b128 v[118:121], v134 offset:34816
	ds_read_b128 v[110:113], v134 offset:22528
	ds_read_b128 v[114:117], v134 offset:30720
	ds_read_b128 v[186:189], v134 offset:38912
	s_waitcnt lgkmcnt(6)
	v_pk_mul_f32 v[190:191], v[84:85], v[102:103]
	v_pk_mul_f32 v[192:193], v[148:149], v[102:103]
	v_pk_fma_f32 v[190:191], v[86:87], v[104:105], v[190:191]
	v_pk_fma_f32 v[192:193], v[150:151], v[104:105], v[192:193]
	v_add_f32_e32 v190, v190, v191
	v_add_f32_e32 v192, v192, v193
	ds_read_b128 v[106:109], v134 offset:26880
	v_add_f32_dpp v190, v190, v190 row_ror:8 row_mask:0xf bank_mask:0xf bound_ctrl:1
	v_add_f32_dpp v192, v192, v192 row_ror:8 row_mask:0xf bank_mask:0xf bound_ctrl:1
	s_waitcnt lgkmcnt(4)
	v_pk_mul_f32 v[194:195], v[122:123], v[118:119] op_sel_hi:[0,1]
	v_add_f32_dpp v190, v190, v190 row_ror:4 row_mask:0xf bank_mask:0xf bound_ctrl:1
	v_add_f32_dpp v192, v192, v192 row_ror:4 row_mask:0xf bank_mask:0xf bound_ctrl:1
	v_pk_mul_f32 v[196:197], v[122:123], v[120:121] op_sel_hi:[0,1]
	v_add_f32_dpp v190, v190, v190 row_ror:2 row_mask:0xf bank_mask:0xf bound_ctrl:1
	v_add_f32_dpp v192, v192, v192 row_ror:2 row_mask:0xf bank_mask:0xf bound_ctrl:1
	v_pk_mul_f32 v[198:199], v[122:123], v[118:119] op_sel:[1,0] op_sel_hi:[1,1]
	v_add_f32_dpp v190, v190, v190 row_ror:1 row_mask:0xf bank_mask:0xf bound_ctrl:1
	v_add_f32_dpp v192, v192, v192 row_ror:1 row_mask:0xf bank_mask:0xf bound_ctrl:1
	v_pk_mul_f32 v[152:153], v[122:123], v[120:121] op_sel:[1,0] op_sel_hi:[1,1]
	ds_read_b32 v122, v182 offset:43136
	ds_read_b32 v123, v182 offset:43200
	ds_read_b128 v[118:121], v134 offset:35072
	s_waitcnt lgkmcnt(5)
	v_pk_fma_f32 v[194:195], v[190:191], v[114:115], v[194:195] op_sel_hi:[0,1,1]
	v_pk_fma_f32 v[198:199], v[192:193], v[114:115], v[198:199] op_sel_hi:[0,1,1]
	v_pk_fma_f32 v[196:197], v[190:191], v[116:117], v[196:197] op_sel_hi:[0,1,1]
	v_pk_fma_f32 v[152:153], v[192:193], v[116:117], v[152:153] op_sel_hi:[0,1,1]
	v_pk_fma_f32 v[84:85], v[84:85], v[110:111], v[194:195]
	v_pk_fma_f32 v[148:149], v[148:149], v[110:111], v[198:199]
	v_pk_fma_f32 v[86:87], v[86:87], v[112:113], v[196:197]
	v_pk_fma_f32 v[150:151], v[150:151], v[112:113], v[152:153]
	ds_read_b128 v[110:113], v134 offset:22784
	ds_read_b128 v[114:117], v134 offset:30976
	s_waitcnt lgkmcnt(6)
	v_pk_mul_f32 v[194:195], v[84:85], v[186:187]
	v_pk_mul_f32 v[196:197], v[148:149], v[186:187]
	v_pk_fma_f32 v[194:195], v[86:87], v[188:189], v[194:195]
	v_pk_fma_f32 v[196:197], v[150:151], v[188:189], v[196:197]
	v_add_f32_e32 v194, v194, v195
	v_add_f32_e32 v196, v196, v197
	ds_read_b128 v[186:189], v134 offset:39168
	v_add_f32_dpp v194, v194, v194 row_ror:8 row_mask:0xf bank_mask:0xf bound_ctrl:1
	v_add_f32_dpp v196, v196, v196 row_ror:8 row_mask:0xf bank_mask:0xf bound_ctrl:1
	s_waitcnt lgkmcnt(6)
	v_pk_mul_f32 v[190:191], v[84:85], v[106:107]
	v_pk_mul_f32 v[192:193], v[148:149], v[106:107]
	v_add_f32_dpp v194, v194, v194 row_ror:4 row_mask:0xf bank_mask:0xf bound_ctrl:1
	v_add_f32_dpp v196, v196, v196 row_ror:4 row_mask:0xf bank_mask:0xf bound_ctrl:1
	v_pk_fma_f32 v[190:191], v[86:87], v[108:109], v[190:191]
	v_pk_fma_f32 v[192:193], v[150:151], v[108:109], v[192:193]
	v_add_f32_dpp v194, v194, v194 row_ror:2 row_mask:0xf bank_mask:0xf bound_ctrl:1
	v_add_f32_dpp v196, v196, v196 row_ror:2 row_mask:0xf bank_mask:0xf bound_ctrl:1
	v_add_f32_e32 v190, v190, v191
	v_add_f32_dpp v194, v194, v194 row_ror:1 row_mask:0xf bank_mask:0xf bound_ctrl:1
	v_add_f32_dpp v196, v196, v196 row_ror:1 row_mask:0xf bank_mask:0xf bound_ctrl:1
	v_add_f32_e32 v192, v192, v193
	ds_write_b32 v182, v194 offset:47104
	ds_write_b32 v182, v196 offset:47168
	ds_read_b128 v[102:105], v134 offset:27136
	v_add_f32_dpp v190, v190, v190 row_ror:8 row_mask:0xf bank_mask:0xf bound_ctrl:1
	v_add_f32_dpp v192, v192, v192 row_ror:8 row_mask:0xf bank_mask:0xf bound_ctrl:1
	s_waitcnt lgkmcnt(6)
	v_pk_mul_f32 v[194:195], v[122:123], v[118:119] op_sel_hi:[0,1]
	v_add_f32_dpp v190, v190, v190 row_ror:4 row_mask:0xf bank_mask:0xf bound_ctrl:1
	v_add_f32_dpp v192, v192, v192 row_ror:4 row_mask:0xf bank_mask:0xf bound_ctrl:1
	v_pk_mul_f32 v[196:197], v[122:123], v[120:121] op_sel_hi:[0,1]
	v_add_f32_dpp v190, v190, v190 row_ror:2 row_mask:0xf bank_mask:0xf bound_ctrl:1
	v_add_f32_dpp v192, v192, v192 row_ror:2 row_mask:0xf bank_mask:0xf bound_ctrl:1
	v_pk_mul_f32 v[198:199], v[122:123], v[118:119] op_sel:[1,0] op_sel_hi:[1,1]
	v_add_f32_dpp v190, v190, v190 row_ror:1 row_mask:0xf bank_mask:0xf bound_ctrl:1
	v_add_f32_dpp v192, v192, v192 row_ror:1 row_mask:0xf bank_mask:0xf bound_ctrl:1
	v_pk_mul_f32 v[152:153], v[122:123], v[120:121] op_sel:[1,0] op_sel_hi:[1,1]
	ds_read_b32 v122, v182 offset:43264
	ds_read_b32 v123, v182 offset:43328
	ds_read_b128 v[118:121], v134 offset:35328
	s_waitcnt lgkmcnt(7)
	v_pk_fma_f32 v[194:195], v[190:191], v[114:115], v[194:195] op_sel_hi:[0,1,1]
	v_pk_fma_f32 v[198:199], v[192:193], v[114:115], v[198:199] op_sel_hi:[0,1,1]
	v_pk_fma_f32 v[196:197], v[190:191], v[116:117], v[196:197] op_sel_hi:[0,1,1]
	v_pk_fma_f32 v[152:153], v[192:193], v[116:117], v[152:153] op_sel_hi:[0,1,1]
	v_pk_fma_f32 v[84:85], v[84:85], v[110:111], v[194:195]
	v_pk_fma_f32 v[148:149], v[148:149], v[110:111], v[198:199]
	v_pk_fma_f32 v[86:87], v[86:87], v[112:113], v[196:197]
	v_pk_fma_f32 v[150:151], v[150:151], v[112:113], v[152:153]
	ds_read_b128 v[110:113], v134 offset:23040
	ds_read_b128 v[114:117], v134 offset:31232
	s_waitcnt lgkmcnt(8)
	v_pk_mul_f32 v[194:195], v[84:85], v[186:187]
	v_pk_mul_f32 v[196:197], v[148:149], v[186:187]
	v_pk_fma_f32 v[194:195], v[86:87], v[188:189], v[194:195]
	v_pk_fma_f32 v[196:197], v[150:151], v[188:189], v[196:197]
	v_add_f32_e32 v194, v194, v195
	v_add_f32_e32 v196, v196, v197
	ds_read_b128 v[186:189], v134 offset:39424
	v_add_f32_dpp v194, v194, v194 row_ror:8 row_mask:0xf bank_mask:0xf bound_ctrl:1
	v_add_f32_dpp v196, v196, v196 row_ror:8 row_mask:0xf bank_mask:0xf bound_ctrl:1
	s_waitcnt lgkmcnt(6)
	v_pk_mul_f32 v[190:191], v[84:85], v[102:103]
	v_pk_mul_f32 v[192:193], v[148:149], v[102:103]
	v_add_f32_dpp v194, v194, v194 row_ror:4 row_mask:0xf bank_mask:0xf bound_ctrl:1
	v_add_f32_dpp v196, v196, v196 row_ror:4 row_mask:0xf bank_mask:0xf bound_ctrl:1
	v_pk_fma_f32 v[190:191], v[86:87], v[104:105], v[190:191]
	v_pk_fma_f32 v[192:193], v[150:151], v[104:105], v[192:193]
	v_add_f32_dpp v194, v194, v194 row_ror:2 row_mask:0xf bank_mask:0xf bound_ctrl:1
	v_add_f32_dpp v196, v196, v196 row_ror:2 row_mask:0xf bank_mask:0xf bound_ctrl:1
	v_add_f32_e32 v190, v190, v191
	v_add_f32_dpp v194, v194, v194 row_ror:1 row_mask:0xf bank_mask:0xf bound_ctrl:1
	v_add_f32_dpp v196, v196, v196 row_ror:1 row_mask:0xf bank_mask:0xf bound_ctrl:1
	v_add_f32_e32 v192, v192, v193
	ds_write_b32 v182, v194 offset:47232
	ds_write_b32 v182, v196 offset:47296
	ds_read_b128 v[106:109], v134 offset:27392
	v_add_f32_dpp v190, v190, v190 row_ror:8 row_mask:0xf bank_mask:0xf bound_ctrl:1
	v_add_f32_dpp v192, v192, v192 row_ror:8 row_mask:0xf bank_mask:0xf bound_ctrl:1
	s_waitcnt lgkmcnt(6)
	v_pk_mul_f32 v[194:195], v[122:123], v[118:119] op_sel_hi:[0,1]
	v_add_f32_dpp v190, v190, v190 row_ror:4 row_mask:0xf bank_mask:0xf bound_ctrl:1
	v_add_f32_dpp v192, v192, v192 row_ror:4 row_mask:0xf bank_mask:0xf bound_ctrl:1
	v_pk_mul_f32 v[196:197], v[122:123], v[120:121] op_sel_hi:[0,1]
	v_add_f32_dpp v190, v190, v190 row_ror:2 row_mask:0xf bank_mask:0xf bound_ctrl:1
	v_add_f32_dpp v192, v192, v192 row_ror:2 row_mask:0xf bank_mask:0xf bound_ctrl:1
	v_pk_mul_f32 v[198:199], v[122:123], v[118:119] op_sel:[1,0] op_sel_hi:[1,1]
	v_add_f32_dpp v190, v190, v190 row_ror:1 row_mask:0xf bank_mask:0xf bound_ctrl:1
	v_add_f32_dpp v192, v192, v192 row_ror:1 row_mask:0xf bank_mask:0xf bound_ctrl:1
	v_pk_mul_f32 v[152:153], v[122:123], v[120:121] op_sel:[1,0] op_sel_hi:[1,1]
	ds_read_b32 v122, v182 offset:43392
	ds_read_b32 v123, v182 offset:43456
	ds_read_b128 v[118:121], v134 offset:35584
	s_waitcnt lgkmcnt(7)
	v_pk_fma_f32 v[194:195], v[190:191], v[114:115], v[194:195] op_sel_hi:[0,1,1]
	v_pk_fma_f32 v[198:199], v[192:193], v[114:115], v[198:199] op_sel_hi:[0,1,1]
	v_pk_fma_f32 v[196:197], v[190:191], v[116:117], v[196:197] op_sel_hi:[0,1,1]
	v_pk_fma_f32 v[152:153], v[192:193], v[116:117], v[152:153] op_sel_hi:[0,1,1]
	v_pk_fma_f32 v[84:85], v[84:85], v[110:111], v[194:195]
	v_pk_fma_f32 v[148:149], v[148:149], v[110:111], v[198:199]
	v_pk_fma_f32 v[86:87], v[86:87], v[112:113], v[196:197]
	v_pk_fma_f32 v[150:151], v[150:151], v[112:113], v[152:153]
	ds_read_b128 v[110:113], v134 offset:23296
	ds_read_b128 v[114:117], v134 offset:31488
	s_waitcnt lgkmcnt(8)
	v_pk_mul_f32 v[194:195], v[84:85], v[186:187]
	v_pk_mul_f32 v[196:197], v[148:149], v[186:187]
	v_pk_fma_f32 v[194:195], v[86:87], v[188:189], v[194:195]
	v_pk_fma_f32 v[196:197], v[150:151], v[188:189], v[196:197]
	v_add_f32_e32 v194, v194, v195
	v_add_f32_e32 v196, v196, v197
	ds_read_b128 v[186:189], v134 offset:39680
	v_add_f32_dpp v194, v194, v194 row_ror:8 row_mask:0xf bank_mask:0xf bound_ctrl:1
	v_add_f32_dpp v196, v196, v196 row_ror:8 row_mask:0xf bank_mask:0xf bound_ctrl:1
	s_waitcnt lgkmcnt(6)
	v_pk_mul_f32 v[190:191], v[84:85], v[106:107]
	v_pk_mul_f32 v[192:193], v[148:149], v[106:107]
	v_add_f32_dpp v194, v194, v194 row_ror:4 row_mask:0xf bank_mask:0xf bound_ctrl:1
	v_add_f32_dpp v196, v196, v196 row_ror:4 row_mask:0xf bank_mask:0xf bound_ctrl:1
	v_pk_fma_f32 v[190:191], v[86:87], v[108:109], v[190:191]
	v_pk_fma_f32 v[192:193], v[150:151], v[108:109], v[192:193]
	v_add_f32_dpp v194, v194, v194 row_ror:2 row_mask:0xf bank_mask:0xf bound_ctrl:1
	v_add_f32_dpp v196, v196, v196 row_ror:2 row_mask:0xf bank_mask:0xf bound_ctrl:1
	v_add_f32_e32 v190, v190, v191
	v_add_f32_dpp v194, v194, v194 row_ror:1 row_mask:0xf bank_mask:0xf bound_ctrl:1
	v_add_f32_dpp v196, v196, v196 row_ror:1 row_mask:0xf bank_mask:0xf bound_ctrl:1
	v_add_f32_e32 v192, v192, v193
	ds_write_b32 v182, v194 offset:47360
	ds_write_b32 v182, v196 offset:47424
	ds_read_b128 v[102:105], v134 offset:27648
	v_add_f32_dpp v190, v190, v190 row_ror:8 row_mask:0xf bank_mask:0xf bound_ctrl:1
	v_add_f32_dpp v192, v192, v192 row_ror:8 row_mask:0xf bank_mask:0xf bound_ctrl:1
	s_waitcnt lgkmcnt(6)
	v_pk_mul_f32 v[194:195], v[122:123], v[118:119] op_sel_hi:[0,1]
	v_add_f32_dpp v190, v190, v190 row_ror:4 row_mask:0xf bank_mask:0xf bound_ctrl:1
	v_add_f32_dpp v192, v192, v192 row_ror:4 row_mask:0xf bank_mask:0xf bound_ctrl:1
	v_pk_mul_f32 v[196:197], v[122:123], v[120:121] op_sel_hi:[0,1]
	v_add_f32_dpp v190, v190, v190 row_ror:2 row_mask:0xf bank_mask:0xf bound_ctrl:1
	v_add_f32_dpp v192, v192, v192 row_ror:2 row_mask:0xf bank_mask:0xf bound_ctrl:1
	v_pk_mul_f32 v[198:199], v[122:123], v[118:119] op_sel:[1,0] op_sel_hi:[1,1]
	v_add_f32_dpp v190, v190, v190 row_ror:1 row_mask:0xf bank_mask:0xf bound_ctrl:1
	v_add_f32_dpp v192, v192, v192 row_ror:1 row_mask:0xf bank_mask:0xf bound_ctrl:1
	v_pk_mul_f32 v[152:153], v[122:123], v[120:121] op_sel:[1,0] op_sel_hi:[1,1]
	ds_read_b32 v122, v182 offset:43520
	ds_read_b32 v123, v182 offset:43584
	ds_read_b128 v[118:121], v134 offset:35840
	s_waitcnt lgkmcnt(7)
	v_pk_fma_f32 v[194:195], v[190:191], v[114:115], v[194:195] op_sel_hi:[0,1,1]
	v_pk_fma_f32 v[198:199], v[192:193], v[114:115], v[198:199] op_sel_hi:[0,1,1]
	v_pk_fma_f32 v[196:197], v[190:191], v[116:117], v[196:197] op_sel_hi:[0,1,1]
	v_pk_fma_f32 v[152:153], v[192:193], v[116:117], v[152:153] op_sel_hi:[0,1,1]
	v_pk_fma_f32 v[84:85], v[84:85], v[110:111], v[194:195]
	v_pk_fma_f32 v[148:149], v[148:149], v[110:111], v[198:199]
	v_pk_fma_f32 v[86:87], v[86:87], v[112:113], v[196:197]
	v_pk_fma_f32 v[150:151], v[150:151], v[112:113], v[152:153]
	ds_read_b128 v[110:113], v134 offset:23552
	ds_read_b128 v[114:117], v134 offset:31744
	s_waitcnt lgkmcnt(8)
	v_pk_mul_f32 v[194:195], v[84:85], v[186:187]
	v_pk_mul_f32 v[196:197], v[148:149], v[186:187]
	v_pk_fma_f32 v[194:195], v[86:87], v[188:189], v[194:195]
	v_pk_fma_f32 v[196:197], v[150:151], v[188:189], v[196:197]
	v_add_f32_e32 v194, v194, v195
	v_add_f32_e32 v196, v196, v197
	ds_read_b128 v[186:189], v134 offset:39936
	v_add_f32_dpp v194, v194, v194 row_ror:8 row_mask:0xf bank_mask:0xf bound_ctrl:1
	v_add_f32_dpp v196, v196, v196 row_ror:8 row_mask:0xf bank_mask:0xf bound_ctrl:1
	s_waitcnt lgkmcnt(6)
	v_pk_mul_f32 v[190:191], v[84:85], v[102:103]
	v_pk_mul_f32 v[192:193], v[148:149], v[102:103]
	v_add_f32_dpp v194, v194, v194 row_ror:4 row_mask:0xf bank_mask:0xf bound_ctrl:1
	v_add_f32_dpp v196, v196, v196 row_ror:4 row_mask:0xf bank_mask:0xf bound_ctrl:1
	v_pk_fma_f32 v[190:191], v[86:87], v[104:105], v[190:191]
	v_pk_fma_f32 v[192:193], v[150:151], v[104:105], v[192:193]
	v_add_f32_dpp v194, v194, v194 row_ror:2 row_mask:0xf bank_mask:0xf bound_ctrl:1
	v_add_f32_dpp v196, v196, v196 row_ror:2 row_mask:0xf bank_mask:0xf bound_ctrl:1
	v_add_f32_e32 v190, v190, v191
	v_add_f32_dpp v194, v194, v194 row_ror:1 row_mask:0xf bank_mask:0xf bound_ctrl:1
	v_add_f32_dpp v196, v196, v196 row_ror:1 row_mask:0xf bank_mask:0xf bound_ctrl:1
	v_add_f32_e32 v192, v192, v193
	ds_write_b32 v182, v194 offset:47488
	ds_write_b32 v182, v196 offset:47552
	ds_read_b128 v[106:109], v134 offset:27904
	v_add_f32_dpp v190, v190, v190 row_ror:8 row_mask:0xf bank_mask:0xf bound_ctrl:1
	v_add_f32_dpp v192, v192, v192 row_ror:8 row_mask:0xf bank_mask:0xf bound_ctrl:1
	s_waitcnt lgkmcnt(6)
	v_pk_mul_f32 v[194:195], v[122:123], v[118:119] op_sel_hi:[0,1]
	v_add_f32_dpp v190, v190, v190 row_ror:4 row_mask:0xf bank_mask:0xf bound_ctrl:1
	v_add_f32_dpp v192, v192, v192 row_ror:4 row_mask:0xf bank_mask:0xf bound_ctrl:1
	v_pk_mul_f32 v[196:197], v[122:123], v[120:121] op_sel_hi:[0,1]
	v_add_f32_dpp v190, v190, v190 row_ror:2 row_mask:0xf bank_mask:0xf bound_ctrl:1
	v_add_f32_dpp v192, v192, v192 row_ror:2 row_mask:0xf bank_mask:0xf bound_ctrl:1
	v_pk_mul_f32 v[198:199], v[122:123], v[118:119] op_sel:[1,0] op_sel_hi:[1,1]
	v_add_f32_dpp v190, v190, v190 row_ror:1 row_mask:0xf bank_mask:0xf bound_ctrl:1
	v_add_f32_dpp v192, v192, v192 row_ror:1 row_mask:0xf bank_mask:0xf bound_ctrl:1
	v_pk_mul_f32 v[152:153], v[122:123], v[120:121] op_sel:[1,0] op_sel_hi:[1,1]
	ds_read_b32 v122, v182 offset:43648
	ds_read_b32 v123, v182 offset:43712
	ds_read_b128 v[118:121], v134 offset:36096
	s_waitcnt lgkmcnt(7)
	v_pk_fma_f32 v[194:195], v[190:191], v[114:115], v[194:195] op_sel_hi:[0,1,1]
	v_pk_fma_f32 v[198:199], v[192:193], v[114:115], v[198:199] op_sel_hi:[0,1,1]
	v_pk_fma_f32 v[196:197], v[190:191], v[116:117], v[196:197] op_sel_hi:[0,1,1]
	v_pk_fma_f32 v[152:153], v[192:193], v[116:117], v[152:153] op_sel_hi:[0,1,1]
	v_pk_fma_f32 v[84:85], v[84:85], v[110:111], v[194:195]
	v_pk_fma_f32 v[148:149], v[148:149], v[110:111], v[198:199]
	v_pk_fma_f32 v[86:87], v[86:87], v[112:113], v[196:197]
	v_pk_fma_f32 v[150:151], v[150:151], v[112:113], v[152:153]
	ds_read_b128 v[110:113], v134 offset:23808
	ds_read_b128 v[114:117], v134 offset:32000
	s_waitcnt lgkmcnt(8)
	v_pk_mul_f32 v[194:195], v[84:85], v[186:187]
	v_pk_mul_f32 v[196:197], v[148:149], v[186:187]
	v_pk_fma_f32 v[194:195], v[86:87], v[188:189], v[194:195]
	v_pk_fma_f32 v[196:197], v[150:151], v[188:189], v[196:197]
	v_add_f32_e32 v194, v194, v195
	v_add_f32_e32 v196, v196, v197
	ds_read_b128 v[186:189], v134 offset:40192
	v_add_f32_dpp v194, v194, v194 row_ror:8 row_mask:0xf bank_mask:0xf bound_ctrl:1
	v_add_f32_dpp v196, v196, v196 row_ror:8 row_mask:0xf bank_mask:0xf bound_ctrl:1
	s_waitcnt lgkmcnt(6)
	v_pk_mul_f32 v[190:191], v[84:85], v[106:107]
	v_pk_mul_f32 v[192:193], v[148:149], v[106:107]
	v_add_f32_dpp v194, v194, v194 row_ror:4 row_mask:0xf bank_mask:0xf bound_ctrl:1
	v_add_f32_dpp v196, v196, v196 row_ror:4 row_mask:0xf bank_mask:0xf bound_ctrl:1
	v_pk_fma_f32 v[190:191], v[86:87], v[108:109], v[190:191]
	v_pk_fma_f32 v[192:193], v[150:151], v[108:109], v[192:193]
	v_add_f32_dpp v194, v194, v194 row_ror:2 row_mask:0xf bank_mask:0xf bound_ctrl:1
	v_add_f32_dpp v196, v196, v196 row_ror:2 row_mask:0xf bank_mask:0xf bound_ctrl:1
	v_add_f32_e32 v190, v190, v191
	v_add_f32_dpp v194, v194, v194 row_ror:1 row_mask:0xf bank_mask:0xf bound_ctrl:1
	v_add_f32_dpp v196, v196, v196 row_ror:1 row_mask:0xf bank_mask:0xf bound_ctrl:1
	v_add_f32_e32 v192, v192, v193
	ds_write_b32 v182, v194 offset:47616
	ds_write_b32 v182, v196 offset:47680
	ds_read_b128 v[102:105], v134 offset:28160
	v_add_f32_dpp v190, v190, v190 row_ror:8 row_mask:0xf bank_mask:0xf bound_ctrl:1
	v_add_f32_dpp v192, v192, v192 row_ror:8 row_mask:0xf bank_mask:0xf bound_ctrl:1
	s_waitcnt lgkmcnt(6)
	v_pk_mul_f32 v[194:195], v[122:123], v[118:119] op_sel_hi:[0,1]
	v_add_f32_dpp v190, v190, v190 row_ror:4 row_mask:0xf bank_mask:0xf bound_ctrl:1
	v_add_f32_dpp v192, v192, v192 row_ror:4 row_mask:0xf bank_mask:0xf bound_ctrl:1
	v_pk_mul_f32 v[196:197], v[122:123], v[120:121] op_sel_hi:[0,1]
	v_add_f32_dpp v190, v190, v190 row_ror:2 row_mask:0xf bank_mask:0xf bound_ctrl:1
	v_add_f32_dpp v192, v192, v192 row_ror:2 row_mask:0xf bank_mask:0xf bound_ctrl:1
	v_pk_mul_f32 v[198:199], v[122:123], v[118:119] op_sel:[1,0] op_sel_hi:[1,1]
	v_add_f32_dpp v190, v190, v190 row_ror:1 row_mask:0xf bank_mask:0xf bound_ctrl:1
	v_add_f32_dpp v192, v192, v192 row_ror:1 row_mask:0xf bank_mask:0xf bound_ctrl:1
	v_pk_mul_f32 v[152:153], v[122:123], v[120:121] op_sel:[1,0] op_sel_hi:[1,1]
	ds_read_b32 v122, v182 offset:43776
	ds_read_b32 v123, v182 offset:43840
	ds_read_b128 v[118:121], v134 offset:36352
	s_waitcnt lgkmcnt(7)
	v_pk_fma_f32 v[194:195], v[190:191], v[114:115], v[194:195] op_sel_hi:[0,1,1]
	v_pk_fma_f32 v[198:199], v[192:193], v[114:115], v[198:199] op_sel_hi:[0,1,1]
	v_pk_fma_f32 v[196:197], v[190:191], v[116:117], v[196:197] op_sel_hi:[0,1,1]
	v_pk_fma_f32 v[152:153], v[192:193], v[116:117], v[152:153] op_sel_hi:[0,1,1]
	v_pk_fma_f32 v[84:85], v[84:85], v[110:111], v[194:195]
	v_pk_fma_f32 v[148:149], v[148:149], v[110:111], v[198:199]
	v_pk_fma_f32 v[86:87], v[86:87], v[112:113], v[196:197]
	v_pk_fma_f32 v[150:151], v[150:151], v[112:113], v[152:153]
	ds_read_b128 v[110:113], v134 offset:24064
	ds_read_b128 v[114:117], v134 offset:32256
	s_waitcnt lgkmcnt(8)
	v_pk_mul_f32 v[194:195], v[84:85], v[186:187]
	v_pk_mul_f32 v[196:197], v[148:149], v[186:187]
	v_pk_fma_f32 v[194:195], v[86:87], v[188:189], v[194:195]
	v_pk_fma_f32 v[196:197], v[150:151], v[188:189], v[196:197]
	v_add_f32_e32 v194, v194, v195
	v_add_f32_e32 v196, v196, v197
	ds_read_b128 v[186:189], v134 offset:40448
	v_add_f32_dpp v194, v194, v194 row_ror:8 row_mask:0xf bank_mask:0xf bound_ctrl:1
	v_add_f32_dpp v196, v196, v196 row_ror:8 row_mask:0xf bank_mask:0xf bound_ctrl:1
	s_waitcnt lgkmcnt(6)
	v_pk_mul_f32 v[190:191], v[84:85], v[102:103]
	v_pk_mul_f32 v[192:193], v[148:149], v[102:103]
	v_add_f32_dpp v194, v194, v194 row_ror:4 row_mask:0xf bank_mask:0xf bound_ctrl:1
	v_add_f32_dpp v196, v196, v196 row_ror:4 row_mask:0xf bank_mask:0xf bound_ctrl:1
	v_pk_fma_f32 v[190:191], v[86:87], v[104:105], v[190:191]
	v_pk_fma_f32 v[192:193], v[150:151], v[104:105], v[192:193]
	v_add_f32_dpp v194, v194, v194 row_ror:2 row_mask:0xf bank_mask:0xf bound_ctrl:1
	v_add_f32_dpp v196, v196, v196 row_ror:2 row_mask:0xf bank_mask:0xf bound_ctrl:1
	v_add_f32_e32 v190, v190, v191
	v_add_f32_dpp v194, v194, v194 row_ror:1 row_mask:0xf bank_mask:0xf bound_ctrl:1
	v_add_f32_dpp v196, v196, v196 row_ror:1 row_mask:0xf bank_mask:0xf bound_ctrl:1
	v_add_f32_e32 v192, v192, v193
	ds_write_b32 v182, v194 offset:47744
	ds_write_b32 v182, v196 offset:47808
	ds_read_b128 v[106:109], v134 offset:28416
	v_add_f32_dpp v190, v190, v190 row_ror:8 row_mask:0xf bank_mask:0xf bound_ctrl:1
	v_add_f32_dpp v192, v192, v192 row_ror:8 row_mask:0xf bank_mask:0xf bound_ctrl:1
	s_waitcnt lgkmcnt(6)
	v_pk_mul_f32 v[194:195], v[122:123], v[118:119] op_sel_hi:[0,1]
	v_add_f32_dpp v190, v190, v190 row_ror:4 row_mask:0xf bank_mask:0xf bound_ctrl:1
	v_add_f32_dpp v192, v192, v192 row_ror:4 row_mask:0xf bank_mask:0xf bound_ctrl:1
	v_pk_mul_f32 v[196:197], v[122:123], v[120:121] op_sel_hi:[0,1]
	v_add_f32_dpp v190, v190, v190 row_ror:2 row_mask:0xf bank_mask:0xf bound_ctrl:1
	v_add_f32_dpp v192, v192, v192 row_ror:2 row_mask:0xf bank_mask:0xf bound_ctrl:1
	v_pk_mul_f32 v[198:199], v[122:123], v[118:119] op_sel:[1,0] op_sel_hi:[1,1]
	v_add_f32_dpp v190, v190, v190 row_ror:1 row_mask:0xf bank_mask:0xf bound_ctrl:1
	v_add_f32_dpp v192, v192, v192 row_ror:1 row_mask:0xf bank_mask:0xf bound_ctrl:1
	v_pk_mul_f32 v[152:153], v[122:123], v[120:121] op_sel:[1,0] op_sel_hi:[1,1]
	ds_read_b32 v122, v182 offset:43904
	ds_read_b32 v123, v182 offset:43968
	ds_read_b128 v[118:121], v134 offset:36608
	s_waitcnt lgkmcnt(7)
	v_pk_fma_f32 v[194:195], v[190:191], v[114:115], v[194:195] op_sel_hi:[0,1,1]
	v_pk_fma_f32 v[198:199], v[192:193], v[114:115], v[198:199] op_sel_hi:[0,1,1]
	v_pk_fma_f32 v[196:197], v[190:191], v[116:117], v[196:197] op_sel_hi:[0,1,1]
	v_pk_fma_f32 v[152:153], v[192:193], v[116:117], v[152:153] op_sel_hi:[0,1,1]
	v_pk_fma_f32 v[84:85], v[84:85], v[110:111], v[194:195]
	v_pk_fma_f32 v[148:149], v[148:149], v[110:111], v[198:199]
	v_pk_fma_f32 v[86:87], v[86:87], v[112:113], v[196:197]
	v_pk_fma_f32 v[150:151], v[150:151], v[112:113], v[152:153]
	ds_read_b128 v[110:113], v134 offset:24320
	ds_read_b128 v[114:117], v134 offset:32512
	s_waitcnt lgkmcnt(8)
	v_pk_mul_f32 v[194:195], v[84:85], v[186:187]
	v_pk_mul_f32 v[196:197], v[148:149], v[186:187]
	v_pk_fma_f32 v[194:195], v[86:87], v[188:189], v[194:195]
	v_pk_fma_f32 v[196:197], v[150:151], v[188:189], v[196:197]
	v_add_f32_e32 v194, v194, v195
	v_add_f32_e32 v196, v196, v197
	ds_read_b128 v[186:189], v134 offset:40704
	v_add_f32_dpp v194, v194, v194 row_ror:8 row_mask:0xf bank_mask:0xf bound_ctrl:1
	v_add_f32_dpp v196, v196, v196 row_ror:8 row_mask:0xf bank_mask:0xf bound_ctrl:1
	s_waitcnt lgkmcnt(6)
	v_pk_mul_f32 v[190:191], v[84:85], v[106:107]
	v_pk_mul_f32 v[192:193], v[148:149], v[106:107]
	v_add_f32_dpp v194, v194, v194 row_ror:4 row_mask:0xf bank_mask:0xf bound_ctrl:1
	v_add_f32_dpp v196, v196, v196 row_ror:4 row_mask:0xf bank_mask:0xf bound_ctrl:1
	v_pk_fma_f32 v[190:191], v[86:87], v[108:109], v[190:191]
	v_pk_fma_f32 v[192:193], v[150:151], v[108:109], v[192:193]
	v_add_f32_dpp v194, v194, v194 row_ror:2 row_mask:0xf bank_mask:0xf bound_ctrl:1
	v_add_f32_dpp v196, v196, v196 row_ror:2 row_mask:0xf bank_mask:0xf bound_ctrl:1
	v_add_f32_e32 v190, v190, v191
	v_add_f32_dpp v194, v194, v194 row_ror:1 row_mask:0xf bank_mask:0xf bound_ctrl:1
	v_add_f32_dpp v196, v196, v196 row_ror:1 row_mask:0xf bank_mask:0xf bound_ctrl:1
	v_add_f32_e32 v192, v192, v193
	ds_write_b32 v182, v194 offset:47872
	ds_write_b32 v182, v196 offset:47936
	ds_read_b128 v[102:105], v134 offset:28672
	v_add_f32_dpp v190, v190, v190 row_ror:8 row_mask:0xf bank_mask:0xf bound_ctrl:1
	v_add_f32_dpp v192, v192, v192 row_ror:8 row_mask:0xf bank_mask:0xf bound_ctrl:1
	s_waitcnt lgkmcnt(6)
	v_pk_mul_f32 v[194:195], v[122:123], v[118:119] op_sel_hi:[0,1]
	v_add_f32_dpp v190, v190, v190 row_ror:4 row_mask:0xf bank_mask:0xf bound_ctrl:1
	v_add_f32_dpp v192, v192, v192 row_ror:4 row_mask:0xf bank_mask:0xf bound_ctrl:1
	v_pk_mul_f32 v[196:197], v[122:123], v[120:121] op_sel_hi:[0,1]
	v_add_f32_dpp v190, v190, v190 row_ror:2 row_mask:0xf bank_mask:0xf bound_ctrl:1
	v_add_f32_dpp v192, v192, v192 row_ror:2 row_mask:0xf bank_mask:0xf bound_ctrl:1
	v_pk_mul_f32 v[198:199], v[122:123], v[118:119] op_sel:[1,0] op_sel_hi:[1,1]
	v_add_f32_dpp v190, v190, v190 row_ror:1 row_mask:0xf bank_mask:0xf bound_ctrl:1
	v_add_f32_dpp v192, v192, v192 row_ror:1 row_mask:0xf bank_mask:0xf bound_ctrl:1
	v_pk_mul_f32 v[152:153], v[122:123], v[120:121] op_sel:[1,0] op_sel_hi:[1,1]
	ds_read_b32 v122, v182 offset:44032
	ds_read_b32 v123, v182 offset:44096
	ds_read_b128 v[118:121], v134 offset:36864
	s_waitcnt lgkmcnt(7)
	v_pk_fma_f32 v[194:195], v[190:191], v[114:115], v[194:195] op_sel_hi:[0,1,1]
	v_pk_fma_f32 v[198:199], v[192:193], v[114:115], v[198:199] op_sel_hi:[0,1,1]
	v_pk_fma_f32 v[196:197], v[190:191], v[116:117], v[196:197] op_sel_hi:[0,1,1]
	v_pk_fma_f32 v[152:153], v[192:193], v[116:117], v[152:153] op_sel_hi:[0,1,1]
	v_pk_fma_f32 v[84:85], v[84:85], v[110:111], v[194:195]
	v_pk_fma_f32 v[148:149], v[148:149], v[110:111], v[198:199]
	v_pk_fma_f32 v[86:87], v[86:87], v[112:113], v[196:197]
	v_pk_fma_f32 v[150:151], v[150:151], v[112:113], v[152:153]
	ds_read_b128 v[110:113], v134 offset:24576
	ds_read_b128 v[114:117], v134 offset:32768
	s_waitcnt lgkmcnt(8)
	v_pk_mul_f32 v[194:195], v[84:85], v[186:187]
	v_pk_mul_f32 v[196:197], v[148:149], v[186:187]
	v_pk_fma_f32 v[194:195], v[86:87], v[188:189], v[194:195]
	v_pk_fma_f32 v[196:197], v[150:151], v[188:189], v[196:197]
	v_add_f32_e32 v194, v194, v195
	v_add_f32_e32 v196, v196, v197
	ds_read_b128 v[186:189], v134 offset:40960
	v_add_f32_dpp v194, v194, v194 row_ror:8 row_mask:0xf bank_mask:0xf bound_ctrl:1
	v_add_f32_dpp v196, v196, v196 row_ror:8 row_mask:0xf bank_mask:0xf bound_ctrl:1
	s_waitcnt lgkmcnt(6)
	v_pk_mul_f32 v[190:191], v[84:85], v[102:103]
	v_pk_mul_f32 v[192:193], v[148:149], v[102:103]
	v_add_f32_dpp v194, v194, v194 row_ror:4 row_mask:0xf bank_mask:0xf bound_ctrl:1
	v_add_f32_dpp v196, v196, v196 row_ror:4 row_mask:0xf bank_mask:0xf bound_ctrl:1
	v_pk_fma_f32 v[190:191], v[86:87], v[104:105], v[190:191]
	v_pk_fma_f32 v[192:193], v[150:151], v[104:105], v[192:193]
	v_add_f32_dpp v194, v194, v194 row_ror:2 row_mask:0xf bank_mask:0xf bound_ctrl:1
	v_add_f32_dpp v196, v196, v196 row_ror:2 row_mask:0xf bank_mask:0xf bound_ctrl:1
	v_add_f32_e32 v190, v190, v191
	v_add_f32_dpp v194, v194, v194 row_ror:1 row_mask:0xf bank_mask:0xf bound_ctrl:1
	v_add_f32_dpp v196, v196, v196 row_ror:1 row_mask:0xf bank_mask:0xf bound_ctrl:1
	v_add_f32_e32 v192, v192, v193
	ds_write_b32 v182, v194 offset:48000
	ds_write_b32 v182, v196 offset:48064
	ds_read_b128 v[106:109], v134 offset:28928
	v_add_f32_dpp v190, v190, v190 row_ror:8 row_mask:0xf bank_mask:0xf bound_ctrl:1
	v_add_f32_dpp v192, v192, v192 row_ror:8 row_mask:0xf bank_mask:0xf bound_ctrl:1
	s_waitcnt lgkmcnt(6)
	v_pk_mul_f32 v[194:195], v[122:123], v[118:119] op_sel_hi:[0,1]
	v_add_f32_dpp v190, v190, v190 row_ror:4 row_mask:0xf bank_mask:0xf bound_ctrl:1
	v_add_f32_dpp v192, v192, v192 row_ror:4 row_mask:0xf bank_mask:0xf bound_ctrl:1
	v_pk_mul_f32 v[196:197], v[122:123], v[120:121] op_sel_hi:[0,1]
	v_add_f32_dpp v190, v190, v190 row_ror:2 row_mask:0xf bank_mask:0xf bound_ctrl:1
	v_add_f32_dpp v192, v192, v192 row_ror:2 row_mask:0xf bank_mask:0xf bound_ctrl:1
	v_pk_mul_f32 v[198:199], v[122:123], v[118:119] op_sel:[1,0] op_sel_hi:[1,1]
	v_add_f32_dpp v190, v190, v190 row_ror:1 row_mask:0xf bank_mask:0xf bound_ctrl:1
	v_add_f32_dpp v192, v192, v192 row_ror:1 row_mask:0xf bank_mask:0xf bound_ctrl:1
	v_pk_mul_f32 v[152:153], v[122:123], v[120:121] op_sel:[1,0] op_sel_hi:[1,1]
	ds_read_b32 v122, v182 offset:44160
	ds_read_b32 v123, v182 offset:44224
	ds_read_b128 v[118:121], v134 offset:37120
	s_waitcnt lgkmcnt(7)
	v_pk_fma_f32 v[194:195], v[190:191], v[114:115], v[194:195] op_sel_hi:[0,1,1]
	v_pk_fma_f32 v[198:199], v[192:193], v[114:115], v[198:199] op_sel_hi:[0,1,1]
	v_pk_fma_f32 v[196:197], v[190:191], v[116:117], v[196:197] op_sel_hi:[0,1,1]
	v_pk_fma_f32 v[152:153], v[192:193], v[116:117], v[152:153] op_sel_hi:[0,1,1]
	v_pk_fma_f32 v[84:85], v[84:85], v[110:111], v[194:195]
	v_pk_fma_f32 v[148:149], v[148:149], v[110:111], v[198:199]
	v_pk_fma_f32 v[86:87], v[86:87], v[112:113], v[196:197]
	v_pk_fma_f32 v[150:151], v[150:151], v[112:113], v[152:153]
	ds_read_b128 v[110:113], v134 offset:24832
	ds_read_b128 v[114:117], v134 offset:33024
	s_waitcnt lgkmcnt(8)
	v_pk_mul_f32 v[194:195], v[84:85], v[186:187]
	v_pk_mul_f32 v[196:197], v[148:149], v[186:187]
	v_pk_fma_f32 v[194:195], v[86:87], v[188:189], v[194:195]
	v_pk_fma_f32 v[196:197], v[150:151], v[188:189], v[196:197]
	v_add_f32_e32 v194, v194, v195
	v_add_f32_e32 v196, v196, v197
	ds_read_b128 v[186:189], v134 offset:41216
	v_add_f32_dpp v194, v194, v194 row_ror:8 row_mask:0xf bank_mask:0xf bound_ctrl:1
	v_add_f32_dpp v196, v196, v196 row_ror:8 row_mask:0xf bank_mask:0xf bound_ctrl:1
	s_waitcnt lgkmcnt(6)
	v_pk_mul_f32 v[190:191], v[84:85], v[106:107]
	v_pk_mul_f32 v[192:193], v[148:149], v[106:107]
	v_add_f32_dpp v194, v194, v194 row_ror:4 row_mask:0xf bank_mask:0xf bound_ctrl:1
	v_add_f32_dpp v196, v196, v196 row_ror:4 row_mask:0xf bank_mask:0xf bound_ctrl:1
	v_pk_fma_f32 v[190:191], v[86:87], v[108:109], v[190:191]
	v_pk_fma_f32 v[192:193], v[150:151], v[108:109], v[192:193]
	v_add_f32_dpp v194, v194, v194 row_ror:2 row_mask:0xf bank_mask:0xf bound_ctrl:1
	v_add_f32_dpp v196, v196, v196 row_ror:2 row_mask:0xf bank_mask:0xf bound_ctrl:1
	v_add_f32_e32 v190, v190, v191
	v_add_f32_dpp v194, v194, v194 row_ror:1 row_mask:0xf bank_mask:0xf bound_ctrl:1
	v_add_f32_dpp v196, v196, v196 row_ror:1 row_mask:0xf bank_mask:0xf bound_ctrl:1
	v_add_f32_e32 v192, v192, v193
	ds_write_b32 v182, v194 offset:48128
	ds_write_b32 v182, v196 offset:48192
	ds_read_b128 v[102:105], v134 offset:29184
	v_add_f32_dpp v190, v190, v190 row_ror:8 row_mask:0xf bank_mask:0xf bound_ctrl:1
	v_add_f32_dpp v192, v192, v192 row_ror:8 row_mask:0xf bank_mask:0xf bound_ctrl:1
	s_waitcnt lgkmcnt(6)
	v_pk_mul_f32 v[194:195], v[122:123], v[118:119] op_sel_hi:[0,1]
	v_add_f32_dpp v190, v190, v190 row_ror:4 row_mask:0xf bank_mask:0xf bound_ctrl:1
	v_add_f32_dpp v192, v192, v192 row_ror:4 row_mask:0xf bank_mask:0xf bound_ctrl:1
	v_pk_mul_f32 v[196:197], v[122:123], v[120:121] op_sel_hi:[0,1]
	v_add_f32_dpp v190, v190, v190 row_ror:2 row_mask:0xf bank_mask:0xf bound_ctrl:1
	v_add_f32_dpp v192, v192, v192 row_ror:2 row_mask:0xf bank_mask:0xf bound_ctrl:1
	v_pk_mul_f32 v[198:199], v[122:123], v[118:119] op_sel:[1,0] op_sel_hi:[1,1]
	v_add_f32_dpp v190, v190, v190 row_ror:1 row_mask:0xf bank_mask:0xf bound_ctrl:1
	v_add_f32_dpp v192, v192, v192 row_ror:1 row_mask:0xf bank_mask:0xf bound_ctrl:1
	v_pk_mul_f32 v[152:153], v[122:123], v[120:121] op_sel:[1,0] op_sel_hi:[1,1]
	ds_read_b32 v122, v182 offset:44288
	ds_read_b32 v123, v182 offset:44352
	ds_read_b128 v[118:121], v134 offset:37376
	s_waitcnt lgkmcnt(7)
	v_pk_fma_f32 v[194:195], v[190:191], v[114:115], v[194:195] op_sel_hi:[0,1,1]
	v_pk_fma_f32 v[198:199], v[192:193], v[114:115], v[198:199] op_sel_hi:[0,1,1]
	v_pk_fma_f32 v[196:197], v[190:191], v[116:117], v[196:197] op_sel_hi:[0,1,1]
	v_pk_fma_f32 v[152:153], v[192:193], v[116:117], v[152:153] op_sel_hi:[0,1,1]
	v_pk_fma_f32 v[84:85], v[84:85], v[110:111], v[194:195]
	v_pk_fma_f32 v[148:149], v[148:149], v[110:111], v[198:199]
	v_pk_fma_f32 v[86:87], v[86:87], v[112:113], v[196:197]
	v_pk_fma_f32 v[150:151], v[150:151], v[112:113], v[152:153]
	ds_read_b128 v[110:113], v134 offset:25088
	ds_read_b128 v[114:117], v134 offset:33280
	s_waitcnt lgkmcnt(8)
	v_pk_mul_f32 v[194:195], v[84:85], v[186:187]
	v_pk_mul_f32 v[196:197], v[148:149], v[186:187]
	v_pk_fma_f32 v[194:195], v[86:87], v[188:189], v[194:195]
	v_pk_fma_f32 v[196:197], v[150:151], v[188:189], v[196:197]
	v_add_f32_e32 v194, v194, v195
	v_add_f32_e32 v196, v196, v197
	ds_read_b128 v[186:189], v134 offset:41472
	v_add_f32_dpp v194, v194, v194 row_ror:8 row_mask:0xf bank_mask:0xf bound_ctrl:1
	v_add_f32_dpp v196, v196, v196 row_ror:8 row_mask:0xf bank_mask:0xf bound_ctrl:1
	s_waitcnt lgkmcnt(6)
	v_pk_mul_f32 v[190:191], v[84:85], v[102:103]
	v_pk_mul_f32 v[192:193], v[148:149], v[102:103]
	v_add_f32_dpp v194, v194, v194 row_ror:4 row_mask:0xf bank_mask:0xf bound_ctrl:1
	v_add_f32_dpp v196, v196, v196 row_ror:4 row_mask:0xf bank_mask:0xf bound_ctrl:1
	v_pk_fma_f32 v[190:191], v[86:87], v[104:105], v[190:191]
	v_pk_fma_f32 v[192:193], v[150:151], v[104:105], v[192:193]
	v_add_f32_dpp v194, v194, v194 row_ror:2 row_mask:0xf bank_mask:0xf bound_ctrl:1
	v_add_f32_dpp v196, v196, v196 row_ror:2 row_mask:0xf bank_mask:0xf bound_ctrl:1
	v_add_f32_e32 v190, v190, v191
	v_add_f32_dpp v194, v194, v194 row_ror:1 row_mask:0xf bank_mask:0xf bound_ctrl:1
	v_add_f32_dpp v196, v196, v196 row_ror:1 row_mask:0xf bank_mask:0xf bound_ctrl:1
	v_add_f32_e32 v192, v192, v193
	ds_write_b32 v182, v194 offset:48256
	ds_write_b32 v182, v196 offset:48320
	ds_read_b128 v[106:109], v134 offset:29440
	v_add_f32_dpp v190, v190, v190 row_ror:8 row_mask:0xf bank_mask:0xf bound_ctrl:1
	v_add_f32_dpp v192, v192, v192 row_ror:8 row_mask:0xf bank_mask:0xf bound_ctrl:1
	s_waitcnt lgkmcnt(6)
	v_pk_mul_f32 v[194:195], v[122:123], v[118:119] op_sel_hi:[0,1]
	v_add_f32_dpp v190, v190, v190 row_ror:4 row_mask:0xf bank_mask:0xf bound_ctrl:1
	v_add_f32_dpp v192, v192, v192 row_ror:4 row_mask:0xf bank_mask:0xf bound_ctrl:1
	v_pk_mul_f32 v[196:197], v[122:123], v[120:121] op_sel_hi:[0,1]
	v_add_f32_dpp v190, v190, v190 row_ror:2 row_mask:0xf bank_mask:0xf bound_ctrl:1
	v_add_f32_dpp v192, v192, v192 row_ror:2 row_mask:0xf bank_mask:0xf bound_ctrl:1
	v_pk_mul_f32 v[198:199], v[122:123], v[118:119] op_sel:[1,0] op_sel_hi:[1,1]
	v_add_f32_dpp v190, v190, v190 row_ror:1 row_mask:0xf bank_mask:0xf bound_ctrl:1
	v_add_f32_dpp v192, v192, v192 row_ror:1 row_mask:0xf bank_mask:0xf bound_ctrl:1
	v_pk_mul_f32 v[152:153], v[122:123], v[120:121] op_sel:[1,0] op_sel_hi:[1,1]
	ds_read_b32 v122, v182 offset:44416
	ds_read_b32 v123, v182 offset:44480
	ds_read_b128 v[118:121], v134 offset:37632
	s_waitcnt lgkmcnt(7)
	v_pk_fma_f32 v[194:195], v[190:191], v[114:115], v[194:195] op_sel_hi:[0,1,1]
	v_pk_fma_f32 v[198:199], v[192:193], v[114:115], v[198:199] op_sel_hi:[0,1,1]
	v_pk_fma_f32 v[196:197], v[190:191], v[116:117], v[196:197] op_sel_hi:[0,1,1]
	v_pk_fma_f32 v[152:153], v[192:193], v[116:117], v[152:153] op_sel_hi:[0,1,1]
	v_pk_fma_f32 v[84:85], v[84:85], v[110:111], v[194:195]
	v_pk_fma_f32 v[148:149], v[148:149], v[110:111], v[198:199]
	v_pk_fma_f32 v[86:87], v[86:87], v[112:113], v[196:197]
	v_pk_fma_f32 v[150:151], v[150:151], v[112:113], v[152:153]
	ds_read_b128 v[110:113], v134 offset:25344
	ds_read_b128 v[114:117], v134 offset:33536
	s_waitcnt lgkmcnt(8)
	v_pk_mul_f32 v[194:195], v[84:85], v[186:187]
	v_pk_mul_f32 v[196:197], v[148:149], v[186:187]
	v_pk_fma_f32 v[194:195], v[86:87], v[188:189], v[194:195]
	v_pk_fma_f32 v[196:197], v[150:151], v[188:189], v[196:197]
	v_add_f32_e32 v194, v194, v195
	v_add_f32_e32 v196, v196, v197
	ds_read_b128 v[186:189], v134 offset:41728
	v_add_f32_dpp v194, v194, v194 row_ror:8 row_mask:0xf bank_mask:0xf bound_ctrl:1
	v_add_f32_dpp v196, v196, v196 row_ror:8 row_mask:0xf bank_mask:0xf bound_ctrl:1
	s_waitcnt lgkmcnt(6)
	v_pk_mul_f32 v[190:191], v[84:85], v[106:107]
	v_pk_mul_f32 v[192:193], v[148:149], v[106:107]
	v_add_f32_dpp v194, v194, v194 row_ror:4 row_mask:0xf bank_mask:0xf bound_ctrl:1
	v_add_f32_dpp v196, v196, v196 row_ror:4 row_mask:0xf bank_mask:0xf bound_ctrl:1
	v_pk_fma_f32 v[190:191], v[86:87], v[108:109], v[190:191]
	v_pk_fma_f32 v[192:193], v[150:151], v[108:109], v[192:193]
	v_add_f32_dpp v194, v194, v194 row_ror:2 row_mask:0xf bank_mask:0xf bound_ctrl:1
	v_add_f32_dpp v196, v196, v196 row_ror:2 row_mask:0xf bank_mask:0xf bound_ctrl:1
	v_add_f32_e32 v190, v190, v191
	v_add_f32_dpp v194, v194, v194 row_ror:1 row_mask:0xf bank_mask:0xf bound_ctrl:1
	v_add_f32_dpp v196, v196, v196 row_ror:1 row_mask:0xf bank_mask:0xf bound_ctrl:1
	v_add_f32_e32 v192, v192, v193
	ds_write_b32 v182, v194 offset:48384
	ds_write_b32 v182, v196 offset:48448
	ds_read_b128 v[102:105], v134 offset:29696
	v_add_f32_dpp v190, v190, v190 row_ror:8 row_mask:0xf bank_mask:0xf bound_ctrl:1
	v_add_f32_dpp v192, v192, v192 row_ror:8 row_mask:0xf bank_mask:0xf bound_ctrl:1
	s_waitcnt lgkmcnt(6)
	v_pk_mul_f32 v[194:195], v[122:123], v[118:119] op_sel_hi:[0,1]
	v_add_f32_dpp v190, v190, v190 row_ror:4 row_mask:0xf bank_mask:0xf bound_ctrl:1
	v_add_f32_dpp v192, v192, v192 row_ror:4 row_mask:0xf bank_mask:0xf bound_ctrl:1
	v_pk_mul_f32 v[196:197], v[122:123], v[120:121] op_sel_hi:[0,1]
	v_add_f32_dpp v190, v190, v190 row_ror:2 row_mask:0xf bank_mask:0xf bound_ctrl:1
	v_add_f32_dpp v192, v192, v192 row_ror:2 row_mask:0xf bank_mask:0xf bound_ctrl:1
	v_pk_mul_f32 v[198:199], v[122:123], v[118:119] op_sel:[1,0] op_sel_hi:[1,1]
	v_add_f32_dpp v190, v190, v190 row_ror:1 row_mask:0xf bank_mask:0xf bound_ctrl:1
	v_add_f32_dpp v192, v192, v192 row_ror:1 row_mask:0xf bank_mask:0xf bound_ctrl:1
	v_pk_mul_f32 v[152:153], v[122:123], v[120:121] op_sel:[1,0] op_sel_hi:[1,1]
	ds_read_b32 v122, v182 offset:44544
	ds_read_b32 v123, v182 offset:44608
	ds_read_b128 v[118:121], v134 offset:37888
	s_waitcnt lgkmcnt(7)
	v_pk_fma_f32 v[194:195], v[190:191], v[114:115], v[194:195] op_sel_hi:[0,1,1]
	v_pk_fma_f32 v[198:199], v[192:193], v[114:115], v[198:199] op_sel_hi:[0,1,1]
	v_pk_fma_f32 v[196:197], v[190:191], v[116:117], v[196:197] op_sel_hi:[0,1,1]
	v_pk_fma_f32 v[152:153], v[192:193], v[116:117], v[152:153] op_sel_hi:[0,1,1]
	v_pk_fma_f32 v[84:85], v[84:85], v[110:111], v[194:195]
	v_pk_fma_f32 v[148:149], v[148:149], v[110:111], v[198:199]
	v_pk_fma_f32 v[86:87], v[86:87], v[112:113], v[196:197]
	v_pk_fma_f32 v[150:151], v[150:151], v[112:113], v[152:153]
	ds_read_b128 v[110:113], v134 offset:25600
	ds_read_b128 v[114:117], v134 offset:33792
	s_waitcnt lgkmcnt(8)
	v_pk_mul_f32 v[194:195], v[84:85], v[186:187]
	v_pk_mul_f32 v[196:197], v[148:149], v[186:187]
	v_pk_fma_f32 v[194:195], v[86:87], v[188:189], v[194:195]
	v_pk_fma_f32 v[196:197], v[150:151], v[188:189], v[196:197]
	v_add_f32_e32 v194, v194, v195
	v_add_f32_e32 v196, v196, v197
	ds_read_b128 v[186:189], v134 offset:41984
	v_add_f32_dpp v194, v194, v194 row_ror:8 row_mask:0xf bank_mask:0xf bound_ctrl:1
	v_add_f32_dpp v196, v196, v196 row_ror:8 row_mask:0xf bank_mask:0xf bound_ctrl:1
	s_waitcnt lgkmcnt(6)
	v_pk_mul_f32 v[190:191], v[84:85], v[102:103]
	v_pk_mul_f32 v[192:193], v[148:149], v[102:103]
	v_add_f32_dpp v194, v194, v194 row_ror:4 row_mask:0xf bank_mask:0xf bound_ctrl:1
	v_add_f32_dpp v196, v196, v196 row_ror:4 row_mask:0xf bank_mask:0xf bound_ctrl:1
	v_pk_fma_f32 v[190:191], v[86:87], v[104:105], v[190:191]
	v_pk_fma_f32 v[192:193], v[150:151], v[104:105], v[192:193]
	v_add_f32_dpp v194, v194, v194 row_ror:2 row_mask:0xf bank_mask:0xf bound_ctrl:1
	v_add_f32_dpp v196, v196, v196 row_ror:2 row_mask:0xf bank_mask:0xf bound_ctrl:1
	v_add_f32_e32 v190, v190, v191
	v_add_f32_dpp v194, v194, v194 row_ror:1 row_mask:0xf bank_mask:0xf bound_ctrl:1
	v_add_f32_dpp v196, v196, v196 row_ror:1 row_mask:0xf bank_mask:0xf bound_ctrl:1
	v_add_f32_e32 v192, v192, v193
	ds_write_b32 v182, v194 offset:48512
	ds_write_b32 v182, v196 offset:48576
	ds_read_b128 v[106:109], v134 offset:29952
	v_add_f32_dpp v190, v190, v190 row_ror:8 row_mask:0xf bank_mask:0xf bound_ctrl:1
	v_add_f32_dpp v192, v192, v192 row_ror:8 row_mask:0xf bank_mask:0xf bound_ctrl:1
	s_waitcnt lgkmcnt(6)
	v_pk_mul_f32 v[194:195], v[122:123], v[118:119] op_sel_hi:[0,1]
	v_add_f32_dpp v190, v190, v190 row_ror:4 row_mask:0xf bank_mask:0xf bound_ctrl:1
	v_add_f32_dpp v192, v192, v192 row_ror:4 row_mask:0xf bank_mask:0xf bound_ctrl:1
	v_pk_mul_f32 v[196:197], v[122:123], v[120:121] op_sel_hi:[0,1]
	v_add_f32_dpp v190, v190, v190 row_ror:2 row_mask:0xf bank_mask:0xf bound_ctrl:1
	v_add_f32_dpp v192, v192, v192 row_ror:2 row_mask:0xf bank_mask:0xf bound_ctrl:1
	v_pk_mul_f32 v[198:199], v[122:123], v[118:119] op_sel:[1,0] op_sel_hi:[1,1]
	v_add_f32_dpp v190, v190, v190 row_ror:1 row_mask:0xf bank_mask:0xf bound_ctrl:1
	v_add_f32_dpp v192, v192, v192 row_ror:1 row_mask:0xf bank_mask:0xf bound_ctrl:1
	v_pk_mul_f32 v[152:153], v[122:123], v[120:121] op_sel:[1,0] op_sel_hi:[1,1]
	ds_read_b32 v122, v182 offset:44672
	ds_read_b32 v123, v182 offset:44736
	ds_read_b128 v[118:121], v134 offset:38144
	s_waitcnt lgkmcnt(7)
	v_pk_fma_f32 v[194:195], v[190:191], v[114:115], v[194:195] op_sel_hi:[0,1,1]
	v_pk_fma_f32 v[198:199], v[192:193], v[114:115], v[198:199] op_sel_hi:[0,1,1]
	v_pk_fma_f32 v[196:197], v[190:191], v[116:117], v[196:197] op_sel_hi:[0,1,1]
	v_pk_fma_f32 v[152:153], v[192:193], v[116:117], v[152:153] op_sel_hi:[0,1,1]
	v_pk_fma_f32 v[84:85], v[84:85], v[110:111], v[194:195]
	v_pk_fma_f32 v[148:149], v[148:149], v[110:111], v[198:199]
	v_pk_fma_f32 v[86:87], v[86:87], v[112:113], v[196:197]
	v_pk_fma_f32 v[150:151], v[150:151], v[112:113], v[152:153]
	ds_read_b128 v[110:113], v134 offset:25856
	ds_read_b128 v[114:117], v134 offset:34048
	s_waitcnt lgkmcnt(8)
	v_pk_mul_f32 v[194:195], v[84:85], v[186:187]
	v_pk_mul_f32 v[196:197], v[148:149], v[186:187]
	v_pk_fma_f32 v[194:195], v[86:87], v[188:189], v[194:195]
	v_pk_fma_f32 v[196:197], v[150:151], v[188:189], v[196:197]
	v_add_f32_e32 v194, v194, v195
	v_add_f32_e32 v196, v196, v197
	ds_read_b128 v[186:189], v134 offset:42240
	v_add_f32_dpp v194, v194, v194 row_ror:8 row_mask:0xf bank_mask:0xf bound_ctrl:1
	v_add_f32_dpp v196, v196, v196 row_ror:8 row_mask:0xf bank_mask:0xf bound_ctrl:1
	s_waitcnt lgkmcnt(6)
	v_pk_mul_f32 v[190:191], v[84:85], v[106:107]
	v_pk_mul_f32 v[192:193], v[148:149], v[106:107]
	v_add_f32_dpp v194, v194, v194 row_ror:4 row_mask:0xf bank_mask:0xf bound_ctrl:1
	v_add_f32_dpp v196, v196, v196 row_ror:4 row_mask:0xf bank_mask:0xf bound_ctrl:1
	v_pk_fma_f32 v[190:191], v[86:87], v[108:109], v[190:191]
	v_pk_fma_f32 v[192:193], v[150:151], v[108:109], v[192:193]
	v_add_f32_dpp v194, v194, v194 row_ror:2 row_mask:0xf bank_mask:0xf bound_ctrl:1
	v_add_f32_dpp v196, v196, v196 row_ror:2 row_mask:0xf bank_mask:0xf bound_ctrl:1
	v_add_f32_e32 v190, v190, v191
	v_add_f32_dpp v194, v194, v194 row_ror:1 row_mask:0xf bank_mask:0xf bound_ctrl:1
	v_add_f32_dpp v196, v196, v196 row_ror:1 row_mask:0xf bank_mask:0xf bound_ctrl:1
	v_add_f32_e32 v192, v192, v193
	ds_write_b32 v182, v194 offset:48640
	ds_write_b32 v182, v196 offset:48704
	ds_read_b128 v[102:105], v134 offset:30208
	v_add_f32_dpp v190, v190, v190 row_ror:8 row_mask:0xf bank_mask:0xf bound_ctrl:1
	v_add_f32_dpp v192, v192, v192 row_ror:8 row_mask:0xf bank_mask:0xf bound_ctrl:1
	s_waitcnt lgkmcnt(6)
	v_pk_mul_f32 v[194:195], v[122:123], v[118:119] op_sel_hi:[0,1]
	v_add_f32_dpp v190, v190, v190 row_ror:4 row_mask:0xf bank_mask:0xf bound_ctrl:1
	v_add_f32_dpp v192, v192, v192 row_ror:4 row_mask:0xf bank_mask:0xf bound_ctrl:1
	v_pk_mul_f32 v[196:197], v[122:123], v[120:121] op_sel_hi:[0,1]
	v_add_f32_dpp v190, v190, v190 row_ror:2 row_mask:0xf bank_mask:0xf bound_ctrl:1
	v_add_f32_dpp v192, v192, v192 row_ror:2 row_mask:0xf bank_mask:0xf bound_ctrl:1
	v_pk_mul_f32 v[198:199], v[122:123], v[118:119] op_sel:[1,0] op_sel_hi:[1,1]
	v_add_f32_dpp v190, v190, v190 row_ror:1 row_mask:0xf bank_mask:0xf bound_ctrl:1
	v_add_f32_dpp v192, v192, v192 row_ror:1 row_mask:0xf bank_mask:0xf bound_ctrl:1
	v_pk_mul_f32 v[152:153], v[122:123], v[120:121] op_sel:[1,0] op_sel_hi:[1,1]
	ds_read_b32 v122, v182 offset:44800
	ds_read_b32 v123, v182 offset:44864
	ds_read_b128 v[118:121], v134 offset:38400
	s_waitcnt lgkmcnt(7)
	v_pk_fma_f32 v[194:195], v[190:191], v[114:115], v[194:195] op_sel_hi:[0,1,1]
	v_pk_fma_f32 v[198:199], v[192:193], v[114:115], v[198:199] op_sel_hi:[0,1,1]
	v_pk_fma_f32 v[196:197], v[190:191], v[116:117], v[196:197] op_sel_hi:[0,1,1]
	v_pk_fma_f32 v[152:153], v[192:193], v[116:117], v[152:153] op_sel_hi:[0,1,1]
	v_pk_fma_f32 v[84:85], v[84:85], v[110:111], v[194:195]
	v_pk_fma_f32 v[148:149], v[148:149], v[110:111], v[198:199]
	v_pk_fma_f32 v[86:87], v[86:87], v[112:113], v[196:197]
	v_pk_fma_f32 v[150:151], v[150:151], v[112:113], v[152:153]
	ds_read_b128 v[110:113], v134 offset:26112
	ds_read_b128 v[114:117], v134 offset:34304
	s_waitcnt lgkmcnt(8)
	v_pk_mul_f32 v[194:195], v[84:85], v[186:187]
	v_pk_mul_f32 v[196:197], v[148:149], v[186:187]
	v_pk_fma_f32 v[194:195], v[86:87], v[188:189], v[194:195]
	v_pk_fma_f32 v[196:197], v[150:151], v[188:189], v[196:197]
	v_add_f32_e32 v194, v194, v195
	v_add_f32_e32 v196, v196, v197
	ds_read_b128 v[186:189], v134 offset:42496
	v_add_f32_dpp v194, v194, v194 row_ror:8 row_mask:0xf bank_mask:0xf bound_ctrl:1
	v_add_f32_dpp v196, v196, v196 row_ror:8 row_mask:0xf bank_mask:0xf bound_ctrl:1
	s_waitcnt lgkmcnt(6)
	v_pk_mul_f32 v[190:191], v[84:85], v[102:103]
	v_pk_mul_f32 v[192:193], v[148:149], v[102:103]
	v_add_f32_dpp v194, v194, v194 row_ror:4 row_mask:0xf bank_mask:0xf bound_ctrl:1
	v_add_f32_dpp v196, v196, v196 row_ror:4 row_mask:0xf bank_mask:0xf bound_ctrl:1
	v_pk_fma_f32 v[190:191], v[86:87], v[104:105], v[190:191]
	v_pk_fma_f32 v[192:193], v[150:151], v[104:105], v[192:193]
	v_add_f32_dpp v194, v194, v194 row_ror:2 row_mask:0xf bank_mask:0xf bound_ctrl:1
	v_add_f32_dpp v196, v196, v196 row_ror:2 row_mask:0xf bank_mask:0xf bound_ctrl:1
	v_add_f32_e32 v190, v190, v191
	v_add_f32_dpp v194, v194, v194 row_ror:1 row_mask:0xf bank_mask:0xf bound_ctrl:1
	v_add_f32_dpp v196, v196, v196 row_ror:1 row_mask:0xf bank_mask:0xf bound_ctrl:1
	v_add_f32_e32 v192, v192, v193
	ds_write_b32 v182, v194 offset:48768
	ds_write_b32 v182, v196 offset:48832
	ds_read_b128 v[106:109], v134 offset:30464
	v_add_f32_dpp v190, v190, v190 row_ror:8 row_mask:0xf bank_mask:0xf bound_ctrl:1
	v_add_f32_dpp v192, v192, v192 row_ror:8 row_mask:0xf bank_mask:0xf bound_ctrl:1
	s_waitcnt lgkmcnt(6)
	v_pk_mul_f32 v[194:195], v[122:123], v[118:119] op_sel_hi:[0,1]
	v_add_f32_dpp v190, v190, v190 row_ror:4 row_mask:0xf bank_mask:0xf bound_ctrl:1
	v_add_f32_dpp v192, v192, v192 row_ror:4 row_mask:0xf bank_mask:0xf bound_ctrl:1
	v_pk_mul_f32 v[196:197], v[122:123], v[120:121] op_sel_hi:[0,1]
	v_add_f32_dpp v190, v190, v190 row_ror:2 row_mask:0xf bank_mask:0xf bound_ctrl:1
	v_add_f32_dpp v192, v192, v192 row_ror:2 row_mask:0xf bank_mask:0xf bound_ctrl:1
	v_pk_mul_f32 v[198:199], v[122:123], v[118:119] op_sel:[1,0] op_sel_hi:[1,1]
	v_add_f32_dpp v190, v190, v190 row_ror:1 row_mask:0xf bank_mask:0xf bound_ctrl:1
	v_add_f32_dpp v192, v192, v192 row_ror:1 row_mask:0xf bank_mask:0xf bound_ctrl:1
	v_pk_mul_f32 v[152:153], v[122:123], v[120:121] op_sel:[1,0] op_sel_hi:[1,1]
	ds_read_b32 v122, v182 offset:44928
	ds_read_b32 v123, v182 offset:44992
	ds_read_b128 v[118:121], v134 offset:38656
	s_waitcnt lgkmcnt(7)
	v_pk_fma_f32 v[194:195], v[190:191], v[114:115], v[194:195] op_sel_hi:[0,1,1]
	v_pk_fma_f32 v[198:199], v[192:193], v[114:115], v[198:199] op_sel_hi:[0,1,1]
	v_pk_fma_f32 v[196:197], v[190:191], v[116:117], v[196:197] op_sel_hi:[0,1,1]
	v_pk_fma_f32 v[152:153], v[192:193], v[116:117], v[152:153] op_sel_hi:[0,1,1]
	v_pk_fma_f32 v[84:85], v[84:85], v[110:111], v[194:195]
	v_pk_fma_f32 v[148:149], v[148:149], v[110:111], v[198:199]
	v_pk_fma_f32 v[86:87], v[86:87], v[112:113], v[196:197]
	v_pk_fma_f32 v[150:151], v[150:151], v[112:113], v[152:153]
	ds_read_b128 v[110:113], v134 offset:26368
	ds_read_b128 v[114:117], v134 offset:34560
	s_waitcnt lgkmcnt(8)
	v_pk_mul_f32 v[194:195], v[84:85], v[186:187]
	v_pk_mul_f32 v[196:197], v[148:149], v[186:187]
	v_pk_fma_f32 v[194:195], v[86:87], v[188:189], v[194:195]
	v_pk_fma_f32 v[196:197], v[150:151], v[188:189], v[196:197]
	v_add_f32_e32 v194, v194, v195
	v_add_f32_e32 v196, v196, v197
	ds_read_b128 v[186:189], v134 offset:42752
	v_add_f32_dpp v194, v194, v194 row_ror:8 row_mask:0xf bank_mask:0xf bound_ctrl:1
	v_add_f32_dpp v196, v196, v196 row_ror:8 row_mask:0xf bank_mask:0xf bound_ctrl:1
	s_waitcnt lgkmcnt(6)
	v_pk_mul_f32 v[190:191], v[84:85], v[106:107]
	v_pk_mul_f32 v[192:193], v[148:149], v[106:107]
	v_add_f32_dpp v194, v194, v194 row_ror:4 row_mask:0xf bank_mask:0xf bound_ctrl:1
	v_add_f32_dpp v196, v196, v196 row_ror:4 row_mask:0xf bank_mask:0xf bound_ctrl:1
	v_pk_fma_f32 v[190:191], v[86:87], v[108:109], v[190:191]
	v_pk_fma_f32 v[192:193], v[150:151], v[108:109], v[192:193]
	v_add_f32_dpp v194, v194, v194 row_ror:2 row_mask:0xf bank_mask:0xf bound_ctrl:1
	v_add_f32_dpp v196, v196, v196 row_ror:2 row_mask:0xf bank_mask:0xf bound_ctrl:1
	v_add_f32_e32 v190, v190, v191
	v_add_f32_dpp v194, v194, v194 row_ror:1 row_mask:0xf bank_mask:0xf bound_ctrl:1
	v_add_f32_dpp v196, v196, v196 row_ror:1 row_mask:0xf bank_mask:0xf bound_ctrl:1
	v_add_f32_e32 v192, v192, v193
	ds_write_b32 v182, v194 offset:48896
	ds_write_b32 v182, v196 offset:48960
	v_add_f32_dpp v190, v190, v190 row_ror:8 row_mask:0xf bank_mask:0xf bound_ctrl:1
	v_add_f32_dpp v192, v192, v192 row_ror:8 row_mask:0xf bank_mask:0xf bound_ctrl:1
	s_waitcnt lgkmcnt(5)
	v_pk_mul_f32 v[194:195], v[122:123], v[118:119] op_sel_hi:[0,1]
	v_add_f32_dpp v190, v190, v190 row_ror:4 row_mask:0xf bank_mask:0xf bound_ctrl:1
	v_add_f32_dpp v192, v192, v192 row_ror:4 row_mask:0xf bank_mask:0xf bound_ctrl:1
	v_pk_mul_f32 v[196:197], v[122:123], v[120:121] op_sel_hi:[0,1]
	v_add_f32_dpp v190, v190, v190 row_ror:2 row_mask:0xf bank_mask:0xf bound_ctrl:1
	v_add_f32_dpp v192, v192, v192 row_ror:2 row_mask:0xf bank_mask:0xf bound_ctrl:1
	v_pk_mul_f32 v[198:199], v[122:123], v[118:119] op_sel:[1,0] op_sel_hi:[1,1]
	v_add_f32_dpp v190, v190, v190 row_ror:1 row_mask:0xf bank_mask:0xf bound_ctrl:1
	v_add_f32_dpp v192, v192, v192 row_ror:1 row_mask:0xf bank_mask:0xf bound_ctrl:1
	v_pk_mul_f32 v[152:153], v[122:123], v[120:121] op_sel:[1,0] op_sel_hi:[1,1]
	s_waitcnt lgkmcnt(3)
	v_pk_fma_f32 v[194:195], v[190:191], v[114:115], v[194:195] op_sel_hi:[0,1,1]
	v_pk_fma_f32 v[198:199], v[192:193], v[114:115], v[198:199] op_sel_hi:[0,1,1]
	v_pk_fma_f32 v[196:197], v[190:191], v[116:117], v[196:197] op_sel_hi:[0,1,1]
	v_pk_fma_f32 v[152:153], v[192:193], v[116:117], v[152:153] op_sel_hi:[0,1,1]
	v_pk_fma_f32 v[84:85], v[84:85], v[110:111], v[194:195]
	v_pk_fma_f32 v[148:149], v[148:149], v[110:111], v[198:199]
	v_pk_fma_f32 v[86:87], v[86:87], v[112:113], v[196:197]
	v_pk_fma_f32 v[150:151], v[150:151], v[112:113], v[152:153]
	s_waitcnt lgkmcnt(2)
	v_pk_mul_f32 v[194:195], v[84:85], v[186:187]
	v_pk_mul_f32 v[196:197], v[148:149], v[186:187]
	v_pk_fma_f32 v[194:195], v[86:87], v[188:189], v[194:195]
	v_pk_fma_f32 v[196:197], v[150:151], v[188:189], v[196:197]
	v_add_f32_e32 v194, v194, v195
	v_add_f32_e32 v196, v196, v197
	s_nop 0
	v_add_f32_dpp v194, v194, v194 row_ror:8 row_mask:0xf bank_mask:0xf bound_ctrl:1
	v_add_f32_dpp v196, v196, v196 row_ror:8 row_mask:0xf bank_mask:0xf bound_ctrl:1
	s_nop 0
	v_add_f32_dpp v194, v194, v194 row_ror:4 row_mask:0xf bank_mask:0xf bound_ctrl:1
	v_add_f32_dpp v196, v196, v196 row_ror:4 row_mask:0xf bank_mask:0xf bound_ctrl:1
	s_nop 0
	v_add_f32_dpp v194, v194, v194 row_ror:2 row_mask:0xf bank_mask:0xf bound_ctrl:1
	v_add_f32_dpp v196, v196, v196 row_ror:2 row_mask:0xf bank_mask:0xf bound_ctrl:1
	s_nop 0
	v_add_f32_dpp v194, v194, v194 row_ror:1 row_mask:0xf bank_mask:0xf bound_ctrl:1
	v_add_f32_dpp v196, v196, v196 row_ror:1 row_mask:0xf bank_mask:0xf bound_ctrl:1
	ds_write_b32 v182, v194 offset:49024
	ds_write_b32 v182, v196 offset:49088
	v_mov_b32_e32 v80, v148
	v_mov_b32_e32 v81, v149
	v_mov_b32_e32 v82, v150
	v_mov_b32_e32 v83, v151
	s_branch .LBB0_332

.LBB0_1156:
	s_or_b64 exec, exec, s[8:9]
	s_waitcnt lgkmcnt(0)
	s_barrier
	v_mov_b32_e32 v196, v88
	v_mov_b32_e32 v197, v89
	v_mov_b32_e32 v198, v90
	v_mov_b32_e32 v199, v100
	v_mov_b32_e32 v200, v91
	v_mov_b32_e32 v201, v101
	v_mov_b32_e32 v202, v102
	v_mov_b32_e32 v203, v104
	v_mov_b32_e32 v204, v103
	v_mov_b32_e32 v205, v105
	v_mov_b32_e32 v206, v106
	v_mov_b32_e32 v207, v109
	v_mov_b32_e32 v208, v107
	v_mov_b32_e32 v209, v110
	v_mov_b32_e32 v210, v108
	v_mov_b32_e32 v211, v111
	v_mov_b32_e32 v214, 0
	v_mov_b32_e32 v215, 0
	ds_read_b128 v[80:83], v194 offset:8192
	ds_read_b128 v[84:87], v194 offset:8448
	ds_read_b128 v[88:91], v194 offset:8704
	ds_read_b128 v[92:95], v194 offset:8960
	ds_read_b32 v134, v140 offset:35136
	ds_read_b32 v135, v190 offset:16384
	ds_read_b32 v132, v140 offset:35072
	ds_read_b128 v[64:67], v194
	ds_read_b128 v[68:71], v194 offset:256
	ds_read_b128 v[72:75], v194 offset:512
	ds_read_b128 v[76:79], v194 offset:768
	ds_read_b128 v[112:115], v194 offset:9216
	ds_read_b128 v[116:119], v194 offset:9472
	ds_read_b128 v[120:123], v194 offset:9728
	ds_read_b128 v[124:127], v194 offset:9984
	ds_read_b32 v156, v140 offset:35140
	ds_read_b32 v157, v190 offset:16448
	ds_read_b32 v154, v140 offset:35076
	ds_read_b128 v[96:99], v194 offset:1024
	ds_read_b128 v[100:103], v194 offset:1280
	ds_read_b128 v[104:107], v194 offset:1536
	ds_read_b128 v[108:111], v194 offset:1792
	s_waitcnt lgkmcnt(15)
	v_mul_f32_e32 v133, v134, v135
	v_pk_mul_f32 v[80:81], v[80:81], v[132:133] op_sel:[0,1] op_sel_hi:[1,1]
	v_pk_mul_f32 v[82:83], v[82:83], v[132:133] op_sel:[0,1] op_sel_hi:[1,1]
	v_pk_mul_f32 v[84:85], v[84:85], v[132:133] op_sel:[0,1] op_sel_hi:[1,1]
	v_pk_mul_f32 v[86:87], v[86:87], v[132:133] op_sel:[0,1] op_sel_hi:[1,1]
	v_pk_mul_f32 v[88:89], v[88:89], v[132:133] op_sel:[0,1] op_sel_hi:[1,1]
	v_pk_mul_f32 v[90:91], v[90:91], v[132:133] op_sel:[0,1] op_sel_hi:[1,1]
	v_pk_mul_f32 v[92:93], v[92:93], v[132:133] op_sel:[0,1] op_sel_hi:[1,1]
	v_pk_mul_f32 v[94:95], v[94:95], v[132:133] op_sel:[0,1] op_sel_hi:[1,1]
	v_pk_fma_f32 v[196:197], v[132:133], v[196:197], v[80:81] op_sel_hi:[0,1,1]
	v_pk_fma_f32 v[198:199], v[132:133], v[198:199], v[82:83] op_sel_hi:[0,1,1]
	v_pk_fma_f32 v[200:201], v[132:133], v[200:201], v[84:85] op_sel_hi:[0,1,1]
	v_pk_fma_f32 v[202:203], v[132:133], v[202:203], v[86:87] op_sel_hi:[0,1,1]
	v_pk_fma_f32 v[204:205], v[132:133], v[204:205], v[88:89] op_sel_hi:[0,1,1]
	v_pk_fma_f32 v[206:207], v[132:133], v[206:207], v[90:91] op_sel_hi:[0,1,1]
	v_pk_fma_f32 v[208:209], v[132:133], v[208:209], v[92:93] op_sel_hi:[0,1,1]
	v_pk_fma_f32 v[210:211], v[132:133], v[210:211], v[94:95] op_sel_hi:[0,1,1]
	s_waitcnt lgkmcnt(14)
	v_pk_fma_f32 v[128:129], v[64:65], v[196:197], v[214:215]
	v_pk_fma_f32 v[130:131], v[66:67], v[198:199], v[214:215]
	s_waitcnt lgkmcnt(13)
	v_pk_fma_f32 v[128:129], v[68:69], v[200:201], v[128:129]
	v_pk_fma_f32 v[130:131], v[70:71], v[202:203], v[130:131]
	s_waitcnt lgkmcnt(12)
	v_pk_fma_f32 v[128:129], v[72:73], v[204:205], v[128:129]
	v_pk_fma_f32 v[130:131], v[74:75], v[206:207], v[130:131]
	s_waitcnt lgkmcnt(11)
	v_pk_fma_f32 v[128:129], v[76:77], v[208:209], v[128:129]
	v_pk_fma_f32 v[130:131], v[78:79], v[210:211], v[130:131]
	v_add_f32_e32 v128, v128, v129
	v_add_f32_e32 v130, v130, v131
	v_add_f32_e32 v212, v128, v130
	ds_read_b128 v[80:83], v194 offset:10240
	ds_read_b128 v[84:87], v194 offset:10496
	ds_read_b128 v[88:91], v194 offset:10752
	ds_read_b128 v[92:95], v194 offset:11008
	ds_read_b32 v134, v140 offset:35144
	ds_read_b32 v135, v190 offset:16512
	ds_read_b32 v132, v140 offset:35080
	ds_read_b128 v[64:67], v194 offset:2048
	ds_read_b128 v[68:71], v194 offset:2304
	ds_read_b128 v[72:75], v194 offset:2560
	ds_read_b128 v[76:79], v194 offset:2816
	s_waitcnt lgkmcnt(15)
	v_mul_f32_e32 v155, v156, v157
	v_pk_mul_f32 v[112:113], v[112:113], v[154:155] op_sel:[0,1] op_sel_hi:[1,1]
	v_add_f32_dpp v212, v212, v212 row_ror:8 row_mask:0xf bank_mask:0xf bound_ctrl:1
	v_pk_mul_f32 v[114:115], v[114:115], v[154:155] op_sel:[0,1] op_sel_hi:[1,1]
	v_pk_mul_f32 v[116:117], v[116:117], v[154:155] op_sel:[0,1] op_sel_hi:[1,1]
	v_add_f32_dpp v212, v212, v212 row_ror:4 row_mask:0xf bank_mask:0xf bound_ctrl:1
	v_pk_mul_f32 v[118:119], v[118:119], v[154:155] op_sel:[0,1] op_sel_hi:[1,1]
	v_pk_mul_f32 v[120:121], v[120:121], v[154:155] op_sel:[0,1] op_sel_hi:[1,1]
	v_add_f32_dpp v212, v212, v212 row_ror:2 row_mask:0xf bank_mask:0xf bound_ctrl:1
	v_pk_mul_f32 v[122:123], v[122:123], v[154:155] op_sel:[0,1] op_sel_hi:[1,1]
	v_pk_mul_f32 v[124:125], v[124:125], v[154:155] op_sel:[0,1] op_sel_hi:[1,1]
	v_add_f32_dpp v212, v212, v212 row_ror:1 row_mask:0xf bank_mask:0xf bound_ctrl:1
	v_pk_mul_f32 v[126:127], v[126:127], v[154:155] op_sel:[0,1] op_sel_hi:[1,1]
	v_pk_fma_f32 v[196:197], v[154:155], v[196:197], v[112:113] op_sel_hi:[0,1,1]
	ds_write_b32 v190, v212 offset:34048
	v_pk_fma_f32 v[198:199], v[154:155], v[198:199], v[114:115] op_sel_hi:[0,1,1]
	v_pk_fma_f32 v[200:201], v[154:155], v[200:201], v[116:117] op_sel_hi:[0,1,1]
	v_pk_fma_f32 v[202:203], v[154:155], v[202:203], v[118:119] op_sel_hi:[0,1,1]
	v_pk_fma_f32 v[204:205], v[154:155], v[204:205], v[120:121] op_sel_hi:[0,1,1]
	v_pk_fma_f32 v[206:207], v[154:155], v[206:207], v[122:123] op_sel_hi:[0,1,1]
	v_pk_fma_f32 v[208:209], v[154:155], v[208:209], v[124:125] op_sel_hi:[0,1,1]
	v_pk_fma_f32 v[210:211], v[154:155], v[210:211], v[126:127] op_sel_hi:[0,1,1]
	s_waitcnt lgkmcnt(15)
	v_pk_fma_f32 v[128:129], v[96:97], v[196:197], v[214:215]
	v_pk_fma_f32 v[130:131], v[98:99], v[198:199], v[214:215]
	s_waitcnt lgkmcnt(14)
	v_pk_fma_f32 v[128:129], v[100:101], v[200:201], v[128:129]
	v_pk_fma_f32 v[130:131], v[102:103], v[202:203], v[130:131]
	s_waitcnt lgkmcnt(13)
	v_pk_fma_f32 v[128:129], v[104:105], v[204:205], v[128:129]
	v_pk_fma_f32 v[130:131], v[106:107], v[206:207], v[130:131]
	s_waitcnt lgkmcnt(12)
	v_pk_fma_f32 v[128:129], v[108:109], v[208:209], v[128:129]
	v_pk_fma_f32 v[130:131], v[110:111], v[210:211], v[130:131]
	v_add_f32_e32 v128, v128, v129
	v_add_f32_e32 v130, v130, v131
	v_add_f32_e32 v213, v128, v130
	ds_read_b128 v[112:115], v194 offset:11264
	ds_read_b128 v[116:119], v194 offset:11520
	ds_read_b128 v[120:123], v194 offset:11776
	ds_read_b128 v[124:127], v194 offset:12032
	ds_read_b32 v156, v140 offset:35148
	ds_read_b32 v157, v190 offset:16576
	ds_read_b32 v154, v140 offset:35084
	ds_read_b128 v[96:99], v194 offset:3072
	ds_read_b128 v[100:103], v194 offset:3328
	ds_read_b128 v[104:107], v194 offset:3584
	ds_read_b128 v[108:111], v194 offset:3840
	s_waitcnt lgkmcnt(15)
	v_mul_f32_e32 v133, v134, v135
	v_pk_mul_f32 v[80:81], v[80:81], v[132:133] op_sel:[0,1] op_sel_hi:[1,1]
	v_add_f32_dpp v213, v213, v213 row_ror:8 row_mask:0xf bank_mask:0xf bound_ctrl:1
	v_pk_mul_f32 v[82:83], v[82:83], v[132:133] op_sel:[0,1] op_sel_hi:[1,1]
	v_pk_mul_f32 v[84:85], v[84:85], v[132:133] op_sel:[0,1] op_sel_hi:[1,1]
	v_add_f32_dpp v213, v213, v213 row_ror:4 row_mask:0xf bank_mask:0xf bound_ctrl:1
	v_pk_mul_f32 v[86:87], v[86:87], v[132:133] op_sel:[0,1] op_sel_hi:[1,1]
	v_pk_mul_f32 v[88:89], v[88:89], v[132:133] op_sel:[0,1] op_sel_hi:[1,1]
	v_add_f32_dpp v213, v213, v213 row_ror:2 row_mask:0xf bank_mask:0xf bound_ctrl:1
	v_pk_mul_f32 v[90:91], v[90:91], v[132:133] op_sel:[0,1] op_sel_hi:[1,1]
	v_pk_mul_f32 v[92:93], v[92:93], v[132:133] op_sel:[0,1] op_sel_hi:[1,1]
	v_add_f32_dpp v213, v213, v213 row_ror:1 row_mask:0xf bank_mask:0xf bound_ctrl:1
	v_pk_mul_f32 v[94:95], v[94:95], v[132:133] op_sel:[0,1] op_sel_hi:[1,1]
	v_pk_fma_f32 v[196:197], v[132:133], v[196:197], v[80:81] op_sel_hi:[0,1,1]
	ds_write_b32 v190, v213 offset:34112
	v_pk_fma_f32 v[198:199], v[132:133], v[198:199], v[82:83] op_sel_hi:[0,1,1]
	v_pk_fma_f32 v[200:201], v[132:133], v[200:201], v[84:85] op_sel_hi:[0,1,1]
	v_pk_fma_f32 v[202:203], v[132:133], v[202:203], v[86:87] op_sel_hi:[0,1,1]
	v_pk_fma_f32 v[204:205], v[132:133], v[204:205], v[88:89] op_sel_hi:[0,1,1]
	v_pk_fma_f32 v[206:207], v[132:133], v[206:207], v[90:91] op_sel_hi:[0,1,1]
	v_pk_fma_f32 v[208:209], v[132:133], v[208:209], v[92:93] op_sel_hi:[0,1,1]
	v_pk_fma_f32 v[210:211], v[132:133], v[210:211], v[94:95] op_sel_hi:[0,1,1]
	s_waitcnt lgkmcnt(15)
	v_pk_fma_f32 v[128:129], v[64:65], v[196:197], v[214:215]
	v_pk_fma_f32 v[130:131], v[66:67], v[198:199], v[214:215]
	v_pk_fma_f32 v[128:129], v[68:69], v[200:201], v[128:129]
	v_pk_fma_f32 v[130:131], v[70:71], v[202:203], v[130:131]
	s_waitcnt lgkmcnt(14)
	v_pk_fma_f32 v[128:129], v[72:73], v[204:205], v[128:129]
	v_pk_fma_f32 v[130:131], v[74:75], v[206:207], v[130:131]
	s_waitcnt lgkmcnt(13)
	v_pk_fma_f32 v[128:129], v[76:77], v[208:209], v[128:129]
	v_pk_fma_f32 v[130:131], v[78:79], v[210:211], v[130:131]
	v_add_f32_e32 v128, v128, v129
	v_add_f32_e32 v130, v130, v131
	v_add_f32_e32 v212, v128, v130
	ds_read_b128 v[80:83], v194 offset:12288
	ds_read_b128 v[84:87], v194 offset:12544
	ds_read_b128 v[88:91], v194 offset:12800
	ds_read_b128 v[92:95], v194 offset:13056
	ds_read_b32 v134, v140 offset:35152
	ds_read_b32 v135, v190 offset:16640
	ds_read_b32 v132, v140 offset:35088
	ds_read_b128 v[64:67], v194 offset:4096
	ds_read_b128 v[68:71], v194 offset:4352
	ds_read_b128 v[72:75], v194 offset:4608
	ds_read_b128 v[76:79], v194 offset:4864
	s_waitcnt lgkmcnt(15)
	v_mul_f32_e32 v155, v156, v157
	v_pk_mul_f32 v[112:113], v[112:113], v[154:155] op_sel:[0,1] op_sel_hi:[1,1]
	v_add_f32_dpp v212, v212, v212 row_ror:8 row_mask:0xf bank_mask:0xf bound_ctrl:1
	v_pk_mul_f32 v[114:115], v[114:115], v[154:155] op_sel:[0,1] op_sel_hi:[1,1]
	v_pk_mul_f32 v[116:117], v[116:117], v[154:155] op_sel:[0,1] op_sel_hi:[1,1]
	v_add_f32_dpp v212, v212, v212 row_ror:4 row_mask:0xf bank_mask:0xf bound_ctrl:1
	v_pk_mul_f32 v[118:119], v[118:119], v[154:155] op_sel:[0,1] op_sel_hi:[1,1]
	v_pk_mul_f32 v[120:121], v[120:121], v[154:155] op_sel:[0,1] op_sel_hi:[1,1]
	v_add_f32_dpp v212, v212, v212 row_ror:2 row_mask:0xf bank_mask:0xf bound_ctrl:1
	v_pk_mul_f32 v[122:123], v[122:123], v[154:155] op_sel:[0,1] op_sel_hi:[1,1]
	v_pk_mul_f32 v[124:125], v[124:125], v[154:155] op_sel:[0,1] op_sel_hi:[1,1]
	v_add_f32_dpp v212, v212, v212 row_ror:1 row_mask:0xf bank_mask:0xf bound_ctrl:1
	v_pk_mul_f32 v[126:127], v[126:127], v[154:155] op_sel:[0,1] op_sel_hi:[1,1]
	v_pk_fma_f32 v[196:197], v[154:155], v[196:197], v[112:113] op_sel_hi:[0,1,1]
	ds_write_b32 v190, v212 offset:34176
	v_pk_fma_f32 v[198:199], v[154:155], v[198:199], v[114:115] op_sel_hi:[0,1,1]
	v_pk_fma_f32 v[200:201], v[154:155], v[200:201], v[116:117] op_sel_hi:[0,1,1]
	v_pk_fma_f32 v[202:203], v[154:155], v[202:203], v[118:119] op_sel_hi:[0,1,1]
	v_pk_fma_f32 v[204:205], v[154:155], v[204:205], v[120:121] op_sel_hi:[0,1,1]
	v_pk_fma_f32 v[206:207], v[154:155], v[206:207], v[122:123] op_sel_hi:[0,1,1]
	v_pk_fma_f32 v[208:209], v[154:155], v[208:209], v[124:125] op_sel_hi:[0,1,1]
	v_pk_fma_f32 v[210:211], v[154:155], v[210:211], v[126:127] op_sel_hi:[0,1,1]
	s_waitcnt lgkmcnt(15)
	v_pk_fma_f32 v[128:129], v[96:97], v[196:197], v[214:215]
	v_pk_fma_f32 v[130:131], v[98:99], v[198:199], v[214:215]
	v_pk_fma_f32 v[128:129], v[100:101], v[200:201], v[128:129]
	v_pk_fma_f32 v[130:131], v[102:103], v[202:203], v[130:131]
	s_waitcnt lgkmcnt(14)
	v_pk_fma_f32 v[128:129], v[104:105], v[204:205], v[128:129]
	v_pk_fma_f32 v[130:131], v[106:107], v[206:207], v[130:131]
	s_waitcnt lgkmcnt(13)
	v_pk_fma_f32 v[128:129], v[108:109], v[208:209], v[128:129]
	v_pk_fma_f32 v[130:131], v[110:111], v[210:211], v[130:131]
	v_add_f32_e32 v128, v128, v129
	v_add_f32_e32 v130, v130, v131
	v_add_f32_e32 v213, v128, v130
	ds_read_b128 v[112:115], v194 offset:13312
	ds_read_b128 v[116:119], v194 offset:13568
	ds_read_b128 v[120:123], v194 offset:13824
	ds_read_b128 v[124:127], v194 offset:14080
	ds_read_b32 v156, v140 offset:35156
	ds_read_b32 v157, v190 offset:16704
	ds_read_b32 v154, v140 offset:35092
	ds_read_b128 v[96:99], v194 offset:5120
	ds_read_b128 v[100:103], v194 offset:5376
	ds_read_b128 v[104:107], v194 offset:5632
	ds_read_b128 v[108:111], v194 offset:5888
	s_waitcnt lgkmcnt(15)
	v_mul_f32_e32 v133, v134, v135
	v_pk_mul_f32 v[80:81], v[80:81], v[132:133] op_sel:[0,1] op_sel_hi:[1,1]
	v_add_f32_dpp v213, v213, v213 row_ror:8 row_mask:0xf bank_mask:0xf bound_ctrl:1
	v_pk_mul_f32 v[82:83], v[82:83], v[132:133] op_sel:[0,1] op_sel_hi:[1,1]
	v_pk_mul_f32 v[84:85], v[84:85], v[132:133] op_sel:[0,1] op_sel_hi:[1,1]
	v_add_f32_dpp v213, v213, v213 row_ror:4 row_mask:0xf bank_mask:0xf bound_ctrl:1
	v_pk_mul_f32 v[86:87], v[86:87], v[132:133] op_sel:[0,1] op_sel_hi:[1,1]
	v_pk_mul_f32 v[88:89], v[88:89], v[132:133] op_sel:[0,1] op_sel_hi:[1,1]
	v_add_f32_dpp v213, v213, v213 row_ror:2 row_mask:0xf bank_mask:0xf bound_ctrl:1
	v_pk_mul_f32 v[90:91], v[90:91], v[132:133] op_sel:[0,1] op_sel_hi:[1,1]
	v_pk_mul_f32 v[92:93], v[92:93], v[132:133] op_sel:[0,1] op_sel_hi:[1,1]
	v_add_f32_dpp v213, v213, v213 row_ror:1 row_mask:0xf bank_mask:0xf bound_ctrl:1
	v_pk_mul_f32 v[94:95], v[94:95], v[132:133] op_sel:[0,1] op_sel_hi:[1,1]
	v_pk_fma_f32 v[196:197], v[132:133], v[196:197], v[80:81] op_sel_hi:[0,1,1]
	ds_write_b32 v190, v213 offset:34240
	v_pk_fma_f32 v[198:199], v[132:133], v[198:199], v[82:83] op_sel_hi:[0,1,1]
	v_pk_fma_f32 v[200:201], v[132:133], v[200:201], v[84:85] op_sel_hi:[0,1,1]
	v_pk_fma_f32 v[202:203], v[132:133], v[202:203], v[86:87] op_sel_hi:[0,1,1]
	v_pk_fma_f32 v[204:205], v[132:133], v[204:205], v[88:89] op_sel_hi:[0,1,1]
	v_pk_fma_f32 v[206:207], v[132:133], v[206:207], v[90:91] op_sel_hi:[0,1,1]
	v_pk_fma_f32 v[208:209], v[132:133], v[208:209], v[92:93] op_sel_hi:[0,1,1]
	v_pk_fma_f32 v[210:211], v[132:133], v[210:211], v[94:95] op_sel_hi:[0,1,1]
	s_waitcnt lgkmcnt(15)
	v_pk_fma_f32 v[128:129], v[64:65], v[196:197], v[214:215]
	v_pk_fma_f32 v[130:131], v[66:67], v[198:199], v[214:215]
	v_pk_fma_f32 v[128:129], v[68:69], v[200:201], v[128:129]
	v_pk_fma_f32 v[130:131], v[70:71], v[202:203], v[130:131]
	s_waitcnt lgkmcnt(14)
	v_pk_fma_f32 v[128:129], v[72:73], v[204:205], v[128:129]
	v_pk_fma_f32 v[130:131], v[74:75], v[206:207], v[130:131]
	s_waitcnt lgkmcnt(13)
	v_pk_fma_f32 v[128:129], v[76:77], v[208:209], v[128:129]
	v_pk_fma_f32 v[130:131], v[78:79], v[210:211], v[130:131]
	v_add_f32_e32 v128, v128, v129
	v_add_f32_e32 v130, v130, v131
	v_add_f32_e32 v212, v128, v130
	ds_read_b128 v[80:83], v194 offset:14336
	ds_read_b128 v[84:87], v194 offset:14592
	ds_read_b128 v[88:91], v194 offset:14848
	ds_read_b128 v[92:95], v194 offset:15104
	ds_read_b32 v134, v140 offset:35160
	ds_read_b32 v135, v190 offset:16768
	ds_read_b32 v132, v140 offset:35096
	ds_read_b128 v[64:67], v194 offset:6144
	ds_read_b128 v[68:71], v194 offset:6400
	ds_read_b128 v[72:75], v194 offset:6656
	ds_read_b128 v[76:79], v194 offset:6912
	s_waitcnt lgkmcnt(15)
	v_mul_f32_e32 v155, v156, v157
	v_pk_mul_f32 v[112:113], v[112:113], v[154:155] op_sel:[0,1] op_sel_hi:[1,1]
	v_add_f32_dpp v212, v212, v212 row_ror:8 row_mask:0xf bank_mask:0xf bound_ctrl:1
	v_pk_mul_f32 v[114:115], v[114:115], v[154:155] op_sel:[0,1] op_sel_hi:[1,1]
	v_pk_mul_f32 v[116:117], v[116:117], v[154:155] op_sel:[0,1] op_sel_hi:[1,1]
	v_add_f32_dpp v212, v212, v212 row_ror:4 row_mask:0xf bank_mask:0xf bound_ctrl:1
	v_pk_mul_f32 v[118:119], v[118:119], v[154:155] op_sel:[0,1] op_sel_hi:[1,1]
	v_pk_mul_f32 v[120:121], v[120:121], v[154:155] op_sel:[0,1] op_sel_hi:[1,1]
	v_add_f32_dpp v212, v212, v212 row_ror:2 row_mask:0xf bank_mask:0xf bound_ctrl:1
	v_pk_mul_f32 v[122:123], v[122:123], v[154:155] op_sel:[0,1] op_sel_hi:[1,1]
	v_pk_mul_f32 v[124:125], v[124:125], v[154:155] op_sel:[0,1] op_sel_hi:[1,1]
	v_add_f32_dpp v212, v212, v212 row_ror:1 row_mask:0xf bank_mask:0xf bound_ctrl:1
	v_pk_mul_f32 v[126:127], v[126:127], v[154:155] op_sel:[0,1] op_sel_hi:[1,1]
	v_pk_fma_f32 v[196:197], v[154:155], v[196:197], v[112:113] op_sel_hi:[0,1,1]
	ds_write_b32 v190, v212 offset:34304
	v_pk_fma_f32 v[198:199], v[154:155], v[198:199], v[114:115] op_sel_hi:[0,1,1]
	v_pk_fma_f32 v[200:201], v[154:155], v[200:201], v[116:117] op_sel_hi:[0,1,1]
	v_pk_fma_f32 v[202:203], v[154:155], v[202:203], v[118:119] op_sel_hi:[0,1,1]
	v_pk_fma_f32 v[204:205], v[154:155], v[204:205], v[120:121] op_sel_hi:[0,1,1]
	v_pk_fma_f32 v[206:207], v[154:155], v[206:207], v[122:123] op_sel_hi:[0,1,1]
	v_pk_fma_f32 v[208:209], v[154:155], v[208:209], v[124:125] op_sel_hi:[0,1,1]
	v_pk_fma_f32 v[210:211], v[154:155], v[210:211], v[126:127] op_sel_hi:[0,1,1]
	s_waitcnt lgkmcnt(15)
	v_pk_fma_f32 v[128:129], v[96:97], v[196:197], v[214:215]
	v_pk_fma_f32 v[130:131], v[98:99], v[198:199], v[214:215]
	v_pk_fma_f32 v[128:129], v[100:101], v[200:201], v[128:129]
	v_pk_fma_f32 v[130:131], v[102:103], v[202:203], v[130:131]
	s_waitcnt lgkmcnt(14)
	v_pk_fma_f32 v[128:129], v[104:105], v[204:205], v[128:129]
	v_pk_fma_f32 v[130:131], v[106:107], v[206:207], v[130:131]
	s_waitcnt lgkmcnt(13)
	v_pk_fma_f32 v[128:129], v[108:109], v[208:209], v[128:129]
	v_pk_fma_f32 v[130:131], v[110:111], v[210:211], v[130:131]
	v_add_f32_e32 v128, v128, v129
	v_add_f32_e32 v130, v130, v131
	v_add_f32_e32 v213, v128, v130
	ds_read_b128 v[112:115], v194 offset:15360
	ds_read_b128 v[116:119], v194 offset:15616
	ds_read_b128 v[120:123], v194 offset:15872
	ds_read_b128 v[124:127], v194 offset:16128
	ds_read_b32 v156, v140 offset:35164
	ds_read_b32 v157, v190 offset:16832
	ds_read_b32 v154, v140 offset:35100
	ds_read_b128 v[96:99], v194 offset:7168
	ds_read_b128 v[100:103], v194 offset:7424
	ds_read_b128 v[104:107], v194 offset:7680
	ds_read_b128 v[108:111], v194 offset:7936
	s_waitcnt lgkmcnt(15)
	v_mul_f32_e32 v133, v134, v135
	v_pk_mul_f32 v[80:81], v[80:81], v[132:133] op_sel:[0,1] op_sel_hi:[1,1]
	v_add_f32_dpp v213, v213, v213 row_ror:8 row_mask:0xf bank_mask:0xf bound_ctrl:1
	v_pk_mul_f32 v[82:83], v[82:83], v[132:133] op_sel:[0,1] op_sel_hi:[1,1]
	v_pk_mul_f32 v[84:85], v[84:85], v[132:133] op_sel:[0,1] op_sel_hi:[1,1]
	v_add_f32_dpp v213, v213, v213 row_ror:4 row_mask:0xf bank_mask:0xf bound_ctrl:1
	v_pk_mul_f32 v[86:87], v[86:87], v[132:133] op_sel:[0,1] op_sel_hi:[1,1]
	v_pk_mul_f32 v[88:89], v[88:89], v[132:133] op_sel:[0,1] op_sel_hi:[1,1]
	v_add_f32_dpp v213, v213, v213 row_ror:2 row_mask:0xf bank_mask:0xf bound_ctrl:1
	v_pk_mul_f32 v[90:91], v[90:91], v[132:133] op_sel:[0,1] op_sel_hi:[1,1]
	v_pk_mul_f32 v[92:93], v[92:93], v[132:133] op_sel:[0,1] op_sel_hi:[1,1]
	v_add_f32_dpp v213, v213, v213 row_ror:1 row_mask:0xf bank_mask:0xf bound_ctrl:1
	v_pk_mul_f32 v[94:95], v[94:95], v[132:133] op_sel:[0,1] op_sel_hi:[1,1]
	v_pk_fma_f32 v[196:197], v[132:133], v[196:197], v[80:81] op_sel_hi:[0,1,1]
	ds_write_b32 v190, v213 offset:34368
	v_pk_fma_f32 v[198:199], v[132:133], v[198:199], v[82:83] op_sel_hi:[0,1,1]
	v_pk_fma_f32 v[200:201], v[132:133], v[200:201], v[84:85] op_sel_hi:[0,1,1]
	v_pk_fma_f32 v[202:203], v[132:133], v[202:203], v[86:87] op_sel_hi:[0,1,1]
	v_pk_fma_f32 v[204:205], v[132:133], v[204:205], v[88:89] op_sel_hi:[0,1,1]
	v_pk_fma_f32 v[206:207], v[132:133], v[206:207], v[90:91] op_sel_hi:[0,1,1]
	v_pk_fma_f32 v[208:209], v[132:133], v[208:209], v[92:93] op_sel_hi:[0,1,1]
	v_pk_fma_f32 v[210:211], v[132:133], v[210:211], v[94:95] op_sel_hi:[0,1,1]
	s_waitcnt lgkmcnt(15)
	v_pk_fma_f32 v[128:129], v[64:65], v[196:197], v[214:215]
	v_pk_fma_f32 v[130:131], v[66:67], v[198:199], v[214:215]
	v_pk_fma_f32 v[128:129], v[68:69], v[200:201], v[128:129]
	v_pk_fma_f32 v[130:131], v[70:71], v[202:203], v[130:131]
	s_waitcnt lgkmcnt(14)
	v_pk_fma_f32 v[128:129], v[72:73], v[204:205], v[128:129]
	v_pk_fma_f32 v[130:131], v[74:75], v[206:207], v[130:131]
	s_waitcnt lgkmcnt(13)
	v_pk_fma_f32 v[128:129], v[76:77], v[208:209], v[128:129]
	v_pk_fma_f32 v[130:131], v[78:79], v[210:211], v[130:131]
	v_add_f32_e32 v128, v128, v129
	v_add_f32_e32 v130, v130, v131
	v_add_f32_e32 v212, v128, v130
	s_waitcnt lgkmcnt(6)
	v_mul_f32_e32 v155, v156, v157
	v_pk_mul_f32 v[112:113], v[112:113], v[154:155] op_sel:[0,1] op_sel_hi:[1,1]
	v_add_f32_dpp v212, v212, v212 row_ror:8 row_mask:0xf bank_mask:0xf bound_ctrl:1
	v_pk_mul_f32 v[114:115], v[114:115], v[154:155] op_sel:[0,1] op_sel_hi:[1,1]
	v_pk_mul_f32 v[116:117], v[116:117], v[154:155] op_sel:[0,1] op_sel_hi:[1,1]
	v_add_f32_dpp v212, v212, v212 row_ror:4 row_mask:0xf bank_mask:0xf bound_ctrl:1
	v_pk_mul_f32 v[118:119], v[118:119], v[154:155] op_sel:[0,1] op_sel_hi:[1,1]
	v_pk_mul_f32 v[120:121], v[120:121], v[154:155] op_sel:[0,1] op_sel_hi:[1,1]
	v_add_f32_dpp v212, v212, v212 row_ror:2 row_mask:0xf bank_mask:0xf bound_ctrl:1
	v_pk_mul_f32 v[122:123], v[122:123], v[154:155] op_sel:[0,1] op_sel_hi:[1,1]
	v_pk_mul_f32 v[124:125], v[124:125], v[154:155] op_sel:[0,1] op_sel_hi:[1,1]
	v_add_f32_dpp v212, v212, v212 row_ror:1 row_mask:0xf bank_mask:0xf bound_ctrl:1
	v_pk_mul_f32 v[126:127], v[126:127], v[154:155] op_sel:[0,1] op_sel_hi:[1,1]
	s_waitcnt lgkmcnt(5)
	v_pk_fma_f32 v[196:197], v[154:155], v[196:197], v[112:113] op_sel_hi:[0,1,1]
	ds_write_b32 v190, v212 offset:34432
	v_pk_fma_f32 v[198:199], v[154:155], v[198:199], v[114:115] op_sel_hi:[0,1,1]
	v_pk_fma_f32 v[200:201], v[154:155], v[200:201], v[116:117] op_sel_hi:[0,1,1]
	v_pk_fma_f32 v[202:203], v[154:155], v[202:203], v[118:119] op_sel_hi:[0,1,1]
	v_pk_fma_f32 v[204:205], v[154:155], v[204:205], v[120:121] op_sel_hi:[0,1,1]
	v_pk_fma_f32 v[206:207], v[154:155], v[206:207], v[122:123] op_sel_hi:[0,1,1]
	v_pk_fma_f32 v[208:209], v[154:155], v[208:209], v[124:125] op_sel_hi:[0,1,1]
	v_pk_fma_f32 v[210:211], v[154:155], v[210:211], v[126:127] op_sel_hi:[0,1,1]
	s_waitcnt lgkmcnt(5)
	v_pk_fma_f32 v[128:129], v[96:97], v[196:197], v[214:215]
	v_pk_fma_f32 v[130:131], v[98:99], v[198:199], v[214:215]
	s_waitcnt lgkmcnt(4)
	v_pk_fma_f32 v[128:129], v[100:101], v[200:201], v[128:129]
	v_pk_fma_f32 v[130:131], v[102:103], v[202:203], v[130:131]
	s_waitcnt lgkmcnt(3)
	v_pk_fma_f32 v[128:129], v[104:105], v[204:205], v[128:129]
	v_pk_fma_f32 v[130:131], v[106:107], v[206:207], v[130:131]
	s_waitcnt lgkmcnt(2)
	v_pk_fma_f32 v[128:129], v[108:109], v[208:209], v[128:129]
	v_pk_fma_f32 v[130:131], v[110:111], v[210:211], v[130:131]
	v_add_f32_e32 v128, v128, v129
	v_add_f32_e32 v130, v130, v131
	v_add_f32_e32 v213, v128, v130
	s_nop 1
	v_add_f32_dpp v213, v213, v213 row_ror:8 row_mask:0xf bank_mask:0xf bound_ctrl:1
	s_nop 1
	v_add_f32_dpp v213, v213, v213 row_ror:4 row_mask:0xf bank_mask:0xf bound_ctrl:1
	s_nop 1
	v_add_f32_dpp v213, v213, v213 row_ror:2 row_mask:0xf bank_mask:0xf bound_ctrl:1
	s_nop 1
	v_add_f32_dpp v213, v213, v213 row_ror:1 row_mask:0xf bank_mask:0xf bound_ctrl:1
	ds_write_b32 v190, v213 offset:34496
	s_waitcnt vmcnt(11)
	ds_write_b128 v188, v[16:19] offset:17024
	s_waitcnt vmcnt(9)
	ds_write_b128 v191, v[24:27] offset:17024
	ds_write_b128 v188, v[20:23] offset:25216
	s_waitcnt vmcnt(8)
	ds_write_b128 v191, v[28:31] offset:25216
	s_and_saveexec_b64 s[8:9], s[40:41]
	ds_write_b32 v145, v183 offset:33408
	s_or_b64 exec, exec, s[8:9]
	s_and_saveexec_b64 s[8:9], s[42:43]
	s_cbranch_execz .LBB0_1176
	v_add_f32_e32 v64, v178, v185
	v_mul_f32_e64 v65, |v64|, s62
	v_exp_f32_e32 v65, v65
	v_min_f32_e32 v64, 0, v64
	v_add_f32_e32 v65, 1.0, v65
	v_cmp_gt_f32_e32 vcc, s5, v65
	s_nop 1
	v_cndmask_b32_e64 v66, 0, 32, vcc
	v_ldexp_f32 v65, v65, v66
	v_log_f32_e32 v65, v65
	v_cndmask_b32_e32 v67, 0, v171, vcc
	v_add_f32_e32 v66, v147, v184
	v_mul_f32_e32 v68, 0x3f317217, v65
	v_fma_f32 v68, v65, s76, -v68
	v_fmac_f32_e32 v68, 0x3377d1cf, v65
	v_fmac_f32_e32 v68, 0x3f317217, v65
	v_cmp_lt_f32_e64 vcc, |v65|, s77
	s_nop 1
	v_cndmask_b32_e32 v65, v65, v68, vcc
	v_sub_f32_e32 v65, v65, v67
	v_sub_f32_e32 v64, v64, v65
	v_add_u32_e32 v65, 0x8400, v145
	ds_write2_b32 v65, v66, v64 offset0:32 offset1:48

.LBB0_1189:
	s_or_b64 exec, exec, s[8:9]
	s_waitcnt lgkmcnt(0)
	s_barrier
	v_mov_b32_e32 v214, 0
	v_mov_b32_e32 v215, 0
	ds_read_b128 v[80:83], v194 offset:25216
	ds_read_b128 v[84:87], v194 offset:25472
	ds_read_b128 v[88:91], v194 offset:25728
	ds_read_b128 v[92:95], v194 offset:25984
	ds_read_b32 v134, v140 offset:35136
	ds_read_b32 v135, v190 offset:33408
	ds_read_b32 v132, v140 offset:35072
	ds_read_b128 v[64:67], v194 offset:17024
	ds_read_b128 v[68:71], v194 offset:17280
	ds_read_b128 v[72:75], v194 offset:17536
	ds_read_b128 v[76:79], v194 offset:17792
	ds_read_b128 v[112:115], v194 offset:26240
	ds_read_b128 v[116:119], v194 offset:26496
	ds_read_b128 v[120:123], v194 offset:26752
	ds_read_b128 v[124:127], v194 offset:27008
	ds_read_b32 v156, v140 offset:35140
	ds_read_b32 v157, v190 offset:33472
	ds_read_b32 v154, v140 offset:35076
	ds_read_b128 v[96:99], v194 offset:18048
	ds_read_b128 v[100:103], v194 offset:18304
	ds_read_b128 v[104:107], v194 offset:18560
	ds_read_b128 v[108:111], v194 offset:18816
	s_waitcnt lgkmcnt(15)
	v_mul_f32_e32 v133, v134, v135
	v_pk_mul_f32 v[80:81], v[80:81], v[132:133] op_sel:[0,1] op_sel_hi:[1,1]
	v_pk_mul_f32 v[82:83], v[82:83], v[132:133] op_sel:[0,1] op_sel_hi:[1,1]
	v_pk_mul_f32 v[84:85], v[84:85], v[132:133] op_sel:[0,1] op_sel_hi:[1,1]
	v_pk_mul_f32 v[86:87], v[86:87], v[132:133] op_sel:[0,1] op_sel_hi:[1,1]
	v_pk_mul_f32 v[88:89], v[88:89], v[132:133] op_sel:[0,1] op_sel_hi:[1,1]
	v_pk_mul_f32 v[90:91], v[90:91], v[132:133] op_sel:[0,1] op_sel_hi:[1,1]
	v_pk_mul_f32 v[92:93], v[92:93], v[132:133] op_sel:[0,1] op_sel_hi:[1,1]
	v_pk_mul_f32 v[94:95], v[94:95], v[132:133] op_sel:[0,1] op_sel_hi:[1,1]
	v_pk_fma_f32 v[196:197], v[132:133], v[196:197], v[80:81] op_sel_hi:[0,1,1]
	v_pk_fma_f32 v[198:199], v[132:133], v[198:199], v[82:83] op_sel_hi:[0,1,1]
	v_pk_fma_f32 v[200:201], v[132:133], v[200:201], v[84:85] op_sel_hi:[0,1,1]
	v_pk_fma_f32 v[202:203], v[132:133], v[202:203], v[86:87] op_sel_hi:[0,1,1]
	v_pk_fma_f32 v[204:205], v[132:133], v[204:205], v[88:89] op_sel_hi:[0,1,1]
	v_pk_fma_f32 v[206:207], v[132:133], v[206:207], v[90:91] op_sel_hi:[0,1,1]
	v_pk_fma_f32 v[208:209], v[132:133], v[208:209], v[92:93] op_sel_hi:[0,1,1]
	v_pk_fma_f32 v[210:211], v[132:133], v[210:211], v[94:95] op_sel_hi:[0,1,1]
	s_waitcnt lgkmcnt(14)
	v_pk_fma_f32 v[128:129], v[64:65], v[196:197], v[214:215]
	v_pk_fma_f32 v[130:131], v[66:67], v[198:199], v[214:215]
	s_waitcnt lgkmcnt(13)
	v_pk_fma_f32 v[128:129], v[68:69], v[200:201], v[128:129]
	v_pk_fma_f32 v[130:131], v[70:71], v[202:203], v[130:131]
	s_waitcnt lgkmcnt(12)
	v_pk_fma_f32 v[128:129], v[72:73], v[204:205], v[128:129]
	v_pk_fma_f32 v[130:131], v[74:75], v[206:207], v[130:131]
	s_waitcnt lgkmcnt(11)
	v_pk_fma_f32 v[128:129], v[76:77], v[208:209], v[128:129]
	v_pk_fma_f32 v[130:131], v[78:79], v[210:211], v[130:131]
	v_add_f32_e32 v128, v128, v129
	v_add_f32_e32 v130, v130, v131
	v_add_f32_e32 v212, v128, v130
	ds_read_b128 v[80:83], v194 offset:27264
	ds_read_b128 v[84:87], v194 offset:27520
	ds_read_b128 v[88:91], v194 offset:27776
	ds_read_b128 v[92:95], v194 offset:28032
	ds_read_b32 v134, v140 offset:35144
	ds_read_b32 v135, v190 offset:33536
	ds_read_b32 v132, v140 offset:35080
	ds_read_b128 v[64:67], v194 offset:19072
	ds_read_b128 v[68:71], v194 offset:19328
	ds_read_b128 v[72:75], v194 offset:19584
	ds_read_b128 v[76:79], v194 offset:19840
	s_waitcnt lgkmcnt(15)
	v_mul_f32_e32 v155, v156, v157
	v_pk_mul_f32 v[112:113], v[112:113], v[154:155] op_sel:[0,1] op_sel_hi:[1,1]
	v_add_f32_dpp v212, v212, v212 row_ror:8 row_mask:0xf bank_mask:0xf bound_ctrl:1
	v_pk_mul_f32 v[114:115], v[114:115], v[154:155] op_sel:[0,1] op_sel_hi:[1,1]
	v_pk_mul_f32 v[116:117], v[116:117], v[154:155] op_sel:[0,1] op_sel_hi:[1,1]
	v_add_f32_dpp v212, v212, v212 row_ror:4 row_mask:0xf bank_mask:0xf bound_ctrl:1
	v_pk_mul_f32 v[118:119], v[118:119], v[154:155] op_sel:[0,1] op_sel_hi:[1,1]
	v_pk_mul_f32 v[120:121], v[120:121], v[154:155] op_sel:[0,1] op_sel_hi:[1,1]
	v_add_f32_dpp v212, v212, v212 row_ror:2 row_mask:0xf bank_mask:0xf bound_ctrl:1
	v_pk_mul_f32 v[122:123], v[122:123], v[154:155] op_sel:[0,1] op_sel_hi:[1,1]
	v_pk_mul_f32 v[124:125], v[124:125], v[154:155] op_sel:[0,1] op_sel_hi:[1,1]
	v_add_f32_dpp v212, v212, v212 row_ror:1 row_mask:0xf bank_mask:0xf bound_ctrl:1
	v_pk_mul_f32 v[126:127], v[126:127], v[154:155] op_sel:[0,1] op_sel_hi:[1,1]
	v_pk_fma_f32 v[196:197], v[154:155], v[196:197], v[112:113] op_sel_hi:[0,1,1]
	ds_write_b32 v190, v212 offset:34560
	v_pk_fma_f32 v[198:199], v[154:155], v[198:199], v[114:115] op_sel_hi:[0,1,1]
	v_pk_fma_f32 v[200:201], v[154:155], v[200:201], v[116:117] op_sel_hi:[0,1,1]
	v_pk_fma_f32 v[202:203], v[154:155], v[202:203], v[118:119] op_sel_hi:[0,1,1]
	v_pk_fma_f32 v[204:205], v[154:155], v[204:205], v[120:121] op_sel_hi:[0,1,1]
	v_pk_fma_f32 v[206:207], v[154:155], v[206:207], v[122:123] op_sel_hi:[0,1,1]
	v_pk_fma_f32 v[208:209], v[154:155], v[208:209], v[124:125] op_sel_hi:[0,1,1]
	v_pk_fma_f32 v[210:211], v[154:155], v[210:211], v[126:127] op_sel_hi:[0,1,1]
	s_waitcnt lgkmcnt(15)
	v_pk_fma_f32 v[128:129], v[96:97], v[196:197], v[214:215]
	v_pk_fma_f32 v[130:131], v[98:99], v[198:199], v[214:215]
	s_waitcnt lgkmcnt(14)
	v_pk_fma_f32 v[128:129], v[100:101], v[200:201], v[128:129]
	v_pk_fma_f32 v[130:131], v[102:103], v[202:203], v[130:131]
	s_waitcnt lgkmcnt(13)
	v_pk_fma_f32 v[128:129], v[104:105], v[204:205], v[128:129]
	v_pk_fma_f32 v[130:131], v[106:107], v[206:207], v[130:131]
	s_waitcnt lgkmcnt(12)
	v_pk_fma_f32 v[128:129], v[108:109], v[208:209], v[128:129]
	v_pk_fma_f32 v[130:131], v[110:111], v[210:211], v[130:131]
	v_add_f32_e32 v128, v128, v129
	v_add_f32_e32 v130, v130, v131
	v_add_f32_e32 v213, v128, v130
	ds_read_b128 v[112:115], v194 offset:28288
	ds_read_b128 v[116:119], v194 offset:28544
	ds_read_b128 v[120:123], v194 offset:28800
	ds_read_b128 v[124:127], v194 offset:29056
	ds_read_b32 v156, v140 offset:35148
	ds_read_b32 v157, v190 offset:33600
	ds_read_b32 v154, v140 offset:35084
	ds_read_b128 v[96:99], v194 offset:20096
	ds_read_b128 v[100:103], v194 offset:20352
	ds_read_b128 v[104:107], v194 offset:20608
	ds_read_b128 v[108:111], v194 offset:20864
	s_waitcnt lgkmcnt(15)
	v_mul_f32_e32 v133, v134, v135
	v_pk_mul_f32 v[80:81], v[80:81], v[132:133] op_sel:[0,1] op_sel_hi:[1,1]
	v_add_f32_dpp v213, v213, v213 row_ror:8 row_mask:0xf bank_mask:0xf bound_ctrl:1
	v_pk_mul_f32 v[82:83], v[82:83], v[132:133] op_sel:[0,1] op_sel_hi:[1,1]
	v_pk_mul_f32 v[84:85], v[84:85], v[132:133] op_sel:[0,1] op_sel_hi:[1,1]
	v_add_f32_dpp v213, v213, v213 row_ror:4 row_mask:0xf bank_mask:0xf bound_ctrl:1
	v_pk_mul_f32 v[86:87], v[86:87], v[132:133] op_sel:[0,1] op_sel_hi:[1,1]
	v_pk_mul_f32 v[88:89], v[88:89], v[132:133] op_sel:[0,1] op_sel_hi:[1,1]
	v_add_f32_dpp v213, v213, v213 row_ror:2 row_mask:0xf bank_mask:0xf bound_ctrl:1
	v_pk_mul_f32 v[90:91], v[90:91], v[132:133] op_sel:[0,1] op_sel_hi:[1,1]
	v_pk_mul_f32 v[92:93], v[92:93], v[132:133] op_sel:[0,1] op_sel_hi:[1,1]
	v_add_f32_dpp v213, v213, v213 row_ror:1 row_mask:0xf bank_mask:0xf bound_ctrl:1
	v_pk_mul_f32 v[94:95], v[94:95], v[132:133] op_sel:[0,1] op_sel_hi:[1,1]
	v_pk_fma_f32 v[196:197], v[132:133], v[196:197], v[80:81] op_sel_hi:[0,1,1]
	ds_write_b32 v190, v213 offset:34624
	v_pk_fma_f32 v[198:199], v[132:133], v[198:199], v[82:83] op_sel_hi:[0,1,1]
	v_pk_fma_f32 v[200:201], v[132:133], v[200:201], v[84:85] op_sel_hi:[0,1,1]
	v_pk_fma_f32 v[202:203], v[132:133], v[202:203], v[86:87] op_sel_hi:[0,1,1]
	v_pk_fma_f32 v[204:205], v[132:133], v[204:205], v[88:89] op_sel_hi:[0,1,1]
	v_pk_fma_f32 v[206:207], v[132:133], v[206:207], v[90:91] op_sel_hi:[0,1,1]
	v_pk_fma_f32 v[208:209], v[132:133], v[208:209], v[92:93] op_sel_hi:[0,1,1]
	v_pk_fma_f32 v[210:211], v[132:133], v[210:211], v[94:95] op_sel_hi:[0,1,1]
	s_waitcnt lgkmcnt(15)
	v_pk_fma_f32 v[128:129], v[64:65], v[196:197], v[214:215]
	v_pk_fma_f32 v[130:131], v[66:67], v[198:199], v[214:215]
	v_pk_fma_f32 v[128:129], v[68:69], v[200:201], v[128:129]
	v_pk_fma_f32 v[130:131], v[70:71], v[202:203], v[130:131]
	s_waitcnt lgkmcnt(14)
	v_pk_fma_f32 v[128:129], v[72:73], v[204:205], v[128:129]
	v_pk_fma_f32 v[130:131], v[74:75], v[206:207], v[130:131]
	s_waitcnt lgkmcnt(13)
	v_pk_fma_f32 v[128:129], v[76:77], v[208:209], v[128:129]
	v_pk_fma_f32 v[130:131], v[78:79], v[210:211], v[130:131]
	v_add_f32_e32 v128, v128, v129
	v_add_f32_e32 v130, v130, v131
	v_add_f32_e32 v212, v128, v130
	ds_read_b128 v[80:83], v194 offset:29312
	ds_read_b128 v[84:87], v194 offset:29568
	ds_read_b128 v[88:91], v194 offset:29824
	ds_read_b128 v[92:95], v194 offset:30080
	ds_read_b32 v134, v140 offset:35152
	ds_read_b32 v135, v190 offset:33664
	ds_read_b32 v132, v140 offset:35088
	ds_read_b128 v[64:67], v194 offset:21120
	ds_read_b128 v[68:71], v194 offset:21376
	ds_read_b128 v[72:75], v194 offset:21632
	ds_read_b128 v[76:79], v194 offset:21888
	s_waitcnt lgkmcnt(15)
	v_mul_f32_e32 v155, v156, v157
	v_pk_mul_f32 v[112:113], v[112:113], v[154:155] op_sel:[0,1] op_sel_hi:[1,1]
	v_add_f32_dpp v212, v212, v212 row_ror:8 row_mask:0xf bank_mask:0xf bound_ctrl:1
	v_pk_mul_f32 v[114:115], v[114:115], v[154:155] op_sel:[0,1] op_sel_hi:[1,1]
	v_pk_mul_f32 v[116:117], v[116:117], v[154:155] op_sel:[0,1] op_sel_hi:[1,1]
	v_add_f32_dpp v212, v212, v212 row_ror:4 row_mask:0xf bank_mask:0xf bound_ctrl:1
	v_pk_mul_f32 v[118:119], v[118:119], v[154:155] op_sel:[0,1] op_sel_hi:[1,1]
	v_pk_mul_f32 v[120:121], v[120:121], v[154:155] op_sel:[0,1] op_sel_hi:[1,1]
	v_add_f32_dpp v212, v212, v212 row_ror:2 row_mask:0xf bank_mask:0xf bound_ctrl:1
	v_pk_mul_f32 v[122:123], v[122:123], v[154:155] op_sel:[0,1] op_sel_hi:[1,1]
	v_pk_mul_f32 v[124:125], v[124:125], v[154:155] op_sel:[0,1] op_sel_hi:[1,1]
	v_add_f32_dpp v212, v212, v212 row_ror:1 row_mask:0xf bank_mask:0xf bound_ctrl:1
	v_pk_mul_f32 v[126:127], v[126:127], v[154:155] op_sel:[0,1] op_sel_hi:[1,1]
	v_pk_fma_f32 v[196:197], v[154:155], v[196:197], v[112:113] op_sel_hi:[0,1,1]
	ds_write_b32 v190, v212 offset:34688
	v_pk_fma_f32 v[198:199], v[154:155], v[198:199], v[114:115] op_sel_hi:[0,1,1]
	v_pk_fma_f32 v[200:201], v[154:155], v[200:201], v[116:117] op_sel_hi:[0,1,1]
	v_pk_fma_f32 v[202:203], v[154:155], v[202:203], v[118:119] op_sel_hi:[0,1,1]
	v_pk_fma_f32 v[204:205], v[154:155], v[204:205], v[120:121] op_sel_hi:[0,1,1]
	v_pk_fma_f32 v[206:207], v[154:155], v[206:207], v[122:123] op_sel_hi:[0,1,1]
	v_pk_fma_f32 v[208:209], v[154:155], v[208:209], v[124:125] op_sel_hi:[0,1,1]
	v_pk_fma_f32 v[210:211], v[154:155], v[210:211], v[126:127] op_sel_hi:[0,1,1]
	s_waitcnt lgkmcnt(15)
	v_pk_fma_f32 v[128:129], v[96:97], v[196:197], v[214:215]
	v_pk_fma_f32 v[130:131], v[98:99], v[198:199], v[214:215]
	v_pk_fma_f32 v[128:129], v[100:101], v[200:201], v[128:129]
	v_pk_fma_f32 v[130:131], v[102:103], v[202:203], v[130:131]
	s_waitcnt lgkmcnt(14)
	v_pk_fma_f32 v[128:129], v[104:105], v[204:205], v[128:129]
	v_pk_fma_f32 v[130:131], v[106:107], v[206:207], v[130:131]
	s_waitcnt lgkmcnt(13)
	v_pk_fma_f32 v[128:129], v[108:109], v[208:209], v[128:129]
	v_pk_fma_f32 v[130:131], v[110:111], v[210:211], v[130:131]
	v_add_f32_e32 v128, v128, v129
	v_add_f32_e32 v130, v130, v131
	v_add_f32_e32 v213, v128, v130
	ds_read_b128 v[112:115], v194 offset:30336
	ds_read_b128 v[116:119], v194 offset:30592
	ds_read_b128 v[120:123], v194 offset:30848
	ds_read_b128 v[124:127], v194 offset:31104
	ds_read_b32 v156, v140 offset:35156
	ds_read_b32 v157, v190 offset:33728
	ds_read_b32 v154, v140 offset:35092
	ds_read_b128 v[96:99], v194 offset:22144
	ds_read_b128 v[100:103], v194 offset:22400
	ds_read_b128 v[104:107], v194 offset:22656
	ds_read_b128 v[108:111], v194 offset:22912
	s_waitcnt lgkmcnt(15)
	v_mul_f32_e32 v133, v134, v135
	v_pk_mul_f32 v[80:81], v[80:81], v[132:133] op_sel:[0,1] op_sel_hi:[1,1]
	v_add_f32_dpp v213, v213, v213 row_ror:8 row_mask:0xf bank_mask:0xf bound_ctrl:1
	v_pk_mul_f32 v[82:83], v[82:83], v[132:133] op_sel:[0,1] op_sel_hi:[1,1]
	v_pk_mul_f32 v[84:85], v[84:85], v[132:133] op_sel:[0,1] op_sel_hi:[1,1]
	v_add_f32_dpp v213, v213, v213 row_ror:4 row_mask:0xf bank_mask:0xf bound_ctrl:1
	v_pk_mul_f32 v[86:87], v[86:87], v[132:133] op_sel:[0,1] op_sel_hi:[1,1]
	v_pk_mul_f32 v[88:89], v[88:89], v[132:133] op_sel:[0,1] op_sel_hi:[1,1]
	v_add_f32_dpp v213, v213, v213 row_ror:2 row_mask:0xf bank_mask:0xf bound_ctrl:1
	v_pk_mul_f32 v[90:91], v[90:91], v[132:133] op_sel:[0,1] op_sel_hi:[1,1]
	v_pk_mul_f32 v[92:93], v[92:93], v[132:133] op_sel:[0,1] op_sel_hi:[1,1]
	v_add_f32_dpp v213, v213, v213 row_ror:1 row_mask:0xf bank_mask:0xf bound_ctrl:1
	v_pk_mul_f32 v[94:95], v[94:95], v[132:133] op_sel:[0,1] op_sel_hi:[1,1]
	v_pk_fma_f32 v[196:197], v[132:133], v[196:197], v[80:81] op_sel_hi:[0,1,1]
	ds_write_b32 v190, v213 offset:34752
	v_pk_fma_f32 v[198:199], v[132:133], v[198:199], v[82:83] op_sel_hi:[0,1,1]
	v_pk_fma_f32 v[200:201], v[132:133], v[200:201], v[84:85] op_sel_hi:[0,1,1]
	v_pk_fma_f32 v[202:203], v[132:133], v[202:203], v[86:87] op_sel_hi:[0,1,1]
	v_pk_fma_f32 v[204:205], v[132:133], v[204:205], v[88:89] op_sel_hi:[0,1,1]
	v_pk_fma_f32 v[206:207], v[132:133], v[206:207], v[90:91] op_sel_hi:[0,1,1]
	v_pk_fma_f32 v[208:209], v[132:133], v[208:209], v[92:93] op_sel_hi:[0,1,1]
	v_pk_fma_f32 v[210:211], v[132:133], v[210:211], v[94:95] op_sel_hi:[0,1,1]
	s_waitcnt lgkmcnt(15)
	v_pk_fma_f32 v[128:129], v[64:65], v[196:197], v[214:215]
	v_pk_fma_f32 v[130:131], v[66:67], v[198:199], v[214:215]
	v_pk_fma_f32 v[128:129], v[68:69], v[200:201], v[128:129]
	v_pk_fma_f32 v[130:131], v[70:71], v[202:203], v[130:131]
	s_waitcnt lgkmcnt(14)
	v_pk_fma_f32 v[128:129], v[72:73], v[204:205], v[128:129]
	v_pk_fma_f32 v[130:131], v[74:75], v[206:207], v[130:131]
	s_waitcnt lgkmcnt(13)
	v_pk_fma_f32 v[128:129], v[76:77], v[208:209], v[128:129]
	v_pk_fma_f32 v[130:131], v[78:79], v[210:211], v[130:131]
	v_add_f32_e32 v128, v128, v129
	v_add_f32_e32 v130, v130, v131
	v_add_f32_e32 v212, v128, v130
	ds_read_b128 v[80:83], v194 offset:31360
	ds_read_b128 v[84:87], v194 offset:31616
	ds_read_b128 v[88:91], v194 offset:31872
	ds_read_b128 v[92:95], v194 offset:32128
	ds_read_b32 v134, v140 offset:35160
	ds_read_b32 v135, v190 offset:33792
	ds_read_b32 v132, v140 offset:35096
	ds_read_b128 v[64:67], v194 offset:23168
	ds_read_b128 v[68:71], v194 offset:23424
	ds_read_b128 v[72:75], v194 offset:23680
	ds_read_b128 v[76:79], v194 offset:23936
	s_waitcnt lgkmcnt(15)
	v_mul_f32_e32 v155, v156, v157
	v_pk_mul_f32 v[112:113], v[112:113], v[154:155] op_sel:[0,1] op_sel_hi:[1,1]
	v_add_f32_dpp v212, v212, v212 row_ror:8 row_mask:0xf bank_mask:0xf bound_ctrl:1
	v_pk_mul_f32 v[114:115], v[114:115], v[154:155] op_sel:[0,1] op_sel_hi:[1,1]
	v_pk_mul_f32 v[116:117], v[116:117], v[154:155] op_sel:[0,1] op_sel_hi:[1,1]
	v_add_f32_dpp v212, v212, v212 row_ror:4 row_mask:0xf bank_mask:0xf bound_ctrl:1
	v_pk_mul_f32 v[118:119], v[118:119], v[154:155] op_sel:[0,1] op_sel_hi:[1,1]
	v_pk_mul_f32 v[120:121], v[120:121], v[154:155] op_sel:[0,1] op_sel_hi:[1,1]
	v_add_f32_dpp v212, v212, v212 row_ror:2 row_mask:0xf bank_mask:0xf bound_ctrl:1
	v_pk_mul_f32 v[122:123], v[122:123], v[154:155] op_sel:[0,1] op_sel_hi:[1,1]
	v_pk_mul_f32 v[124:125], v[124:125], v[154:155] op_sel:[0,1] op_sel_hi:[1,1]
	v_add_f32_dpp v212, v212, v212 row_ror:1 row_mask:0xf bank_mask:0xf bound_ctrl:1
	v_pk_mul_f32 v[126:127], v[126:127], v[154:155] op_sel:[0,1] op_sel_hi:[1,1]
	v_pk_fma_f32 v[196:197], v[154:155], v[196:197], v[112:113] op_sel_hi:[0,1,1]
	ds_write_b32 v190, v212 offset:34816
	v_pk_fma_f32 v[198:199], v[154:155], v[198:199], v[114:115] op_sel_hi:[0,1,1]
	v_pk_fma_f32 v[200:201], v[154:155], v[200:201], v[116:117] op_sel_hi:[0,1,1]
	v_pk_fma_f32 v[202:203], v[154:155], v[202:203], v[118:119] op_sel_hi:[0,1,1]
	v_pk_fma_f32 v[204:205], v[154:155], v[204:205], v[120:121] op_sel_hi:[0,1,1]
	v_pk_fma_f32 v[206:207], v[154:155], v[206:207], v[122:123] op_sel_hi:[0,1,1]
	v_pk_fma_f32 v[208:209], v[154:155], v[208:209], v[124:125] op_sel_hi:[0,1,1]
	v_pk_fma_f32 v[210:211], v[154:155], v[210:211], v[126:127] op_sel_hi:[0,1,1]
	s_waitcnt lgkmcnt(15)
	v_pk_fma_f32 v[128:129], v[96:97], v[196:197], v[214:215]
	v_pk_fma_f32 v[130:131], v[98:99], v[198:199], v[214:215]
	v_pk_fma_f32 v[128:129], v[100:101], v[200:201], v[128:129]
	v_pk_fma_f32 v[130:131], v[102:103], v[202:203], v[130:131]
	s_waitcnt lgkmcnt(14)
	v_pk_fma_f32 v[128:129], v[104:105], v[204:205], v[128:129]
	v_pk_fma_f32 v[130:131], v[106:107], v[206:207], v[130:131]
	s_waitcnt lgkmcnt(13)
	v_pk_fma_f32 v[128:129], v[108:109], v[208:209], v[128:129]
	v_pk_fma_f32 v[130:131], v[110:111], v[210:211], v[130:131]
	v_add_f32_e32 v128, v128, v129
	v_add_f32_e32 v130, v130, v131
	v_add_f32_e32 v213, v128, v130
	ds_read_b128 v[112:115], v194 offset:32384
	ds_read_b128 v[116:119], v194 offset:32640
	ds_read_b128 v[120:123], v194 offset:32896
	ds_read_b128 v[124:127], v194 offset:33152
	ds_read_b32 v156, v140 offset:35164
	ds_read_b32 v157, v190 offset:33856
	ds_read_b32 v154, v140 offset:35100
	ds_read_b128 v[96:99], v194 offset:24192
	ds_read_b128 v[100:103], v194 offset:24448
	ds_read_b128 v[104:107], v194 offset:24704
	ds_read_b128 v[108:111], v194 offset:24960
	s_waitcnt lgkmcnt(15)
	v_mul_f32_e32 v133, v134, v135
	v_pk_mul_f32 v[80:81], v[80:81], v[132:133] op_sel:[0,1] op_sel_hi:[1,1]
	v_add_f32_dpp v213, v213, v213 row_ror:8 row_mask:0xf bank_mask:0xf bound_ctrl:1
	v_pk_mul_f32 v[82:83], v[82:83], v[132:133] op_sel:[0,1] op_sel_hi:[1,1]
	v_pk_mul_f32 v[84:85], v[84:85], v[132:133] op_sel:[0,1] op_sel_hi:[1,1]
	v_add_f32_dpp v213, v213, v213 row_ror:4 row_mask:0xf bank_mask:0xf bound_ctrl:1
	v_pk_mul_f32 v[86:87], v[86:87], v[132:133] op_sel:[0,1] op_sel_hi:[1,1]
	v_pk_mul_f32 v[88:89], v[88:89], v[132:133] op_sel:[0,1] op_sel_hi:[1,1]
	v_add_f32_dpp v213, v213, v213 row_ror:2 row_mask:0xf bank_mask:0xf bound_ctrl:1
	v_pk_mul_f32 v[90:91], v[90:91], v[132:133] op_sel:[0,1] op_sel_hi:[1,1]
	v_pk_mul_f32 v[92:93], v[92:93], v[132:133] op_sel:[0,1] op_sel_hi:[1,1]
	v_add_f32_dpp v213, v213, v213 row_ror:1 row_mask:0xf bank_mask:0xf bound_ctrl:1
	v_pk_mul_f32 v[94:95], v[94:95], v[132:133] op_sel:[0,1] op_sel_hi:[1,1]
	v_pk_fma_f32 v[196:197], v[132:133], v[196:197], v[80:81] op_sel_hi:[0,1,1]
	ds_write_b32 v190, v213 offset:34880
	v_pk_fma_f32 v[198:199], v[132:133], v[198:199], v[82:83] op_sel_hi:[0,1,1]
	v_pk_fma_f32 v[200:201], v[132:133], v[200:201], v[84:85] op_sel_hi:[0,1,1]
	v_pk_fma_f32 v[202:203], v[132:133], v[202:203], v[86:87] op_sel_hi:[0,1,1]
	v_pk_fma_f32 v[204:205], v[132:133], v[204:205], v[88:89] op_sel_hi:[0,1,1]
	v_pk_fma_f32 v[206:207], v[132:133], v[206:207], v[90:91] op_sel_hi:[0,1,1]
	v_pk_fma_f32 v[208:209], v[132:133], v[208:209], v[92:93] op_sel_hi:[0,1,1]
	v_pk_fma_f32 v[210:211], v[132:133], v[210:211], v[94:95] op_sel_hi:[0,1,1]
	s_waitcnt lgkmcnt(15)
	v_pk_fma_f32 v[128:129], v[64:65], v[196:197], v[214:215]
	v_pk_fma_f32 v[130:131], v[66:67], v[198:199], v[214:215]
	v_pk_fma_f32 v[128:129], v[68:69], v[200:201], v[128:129]
	v_pk_fma_f32 v[130:131], v[70:71], v[202:203], v[130:131]
	s_waitcnt lgkmcnt(14)
	v_pk_fma_f32 v[128:129], v[72:73], v[204:205], v[128:129]
	v_pk_fma_f32 v[130:131], v[74:75], v[206:207], v[130:131]
	s_waitcnt lgkmcnt(13)
	v_pk_fma_f32 v[128:129], v[76:77], v[208:209], v[128:129]
	v_pk_fma_f32 v[130:131], v[78:79], v[210:211], v[130:131]
	v_add_f32_e32 v128, v128, v129
	v_add_f32_e32 v130, v130, v131
	v_add_f32_e32 v212, v128, v130
	s_waitcnt lgkmcnt(6)
	v_mul_f32_e32 v155, v156, v157
	v_pk_mul_f32 v[112:113], v[112:113], v[154:155] op_sel:[0,1] op_sel_hi:[1,1]
	v_add_f32_dpp v212, v212, v212 row_ror:8 row_mask:0xf bank_mask:0xf bound_ctrl:1
	v_pk_mul_f32 v[114:115], v[114:115], v[154:155] op_sel:[0,1] op_sel_hi:[1,1]
	v_pk_mul_f32 v[116:117], v[116:117], v[154:155] op_sel:[0,1] op_sel_hi:[1,1]
	v_add_f32_dpp v212, v212, v212 row_ror:4 row_mask:0xf bank_mask:0xf bound_ctrl:1
	v_pk_mul_f32 v[118:119], v[118:119], v[154:155] op_sel:[0,1] op_sel_hi:[1,1]
	v_pk_mul_f32 v[120:121], v[120:121], v[154:155] op_sel:[0,1] op_sel_hi:[1,1]
	v_add_f32_dpp v212, v212, v212 row_ror:2 row_mask:0xf bank_mask:0xf bound_ctrl:1
	v_pk_mul_f32 v[122:123], v[122:123], v[154:155] op_sel:[0,1] op_sel_hi:[1,1]
	v_pk_mul_f32 v[124:125], v[124:125], v[154:155] op_sel:[0,1] op_sel_hi:[1,1]
	v_add_f32_dpp v212, v212, v212 row_ror:1 row_mask:0xf bank_mask:0xf bound_ctrl:1
	v_pk_mul_f32 v[126:127], v[126:127], v[154:155] op_sel:[0,1] op_sel_hi:[1,1]
	s_waitcnt lgkmcnt(5)
	v_pk_fma_f32 v[196:197], v[154:155], v[196:197], v[112:113] op_sel_hi:[0,1,1]
	ds_write_b32 v190, v212 offset:34944
	v_pk_fma_f32 v[198:199], v[154:155], v[198:199], v[114:115] op_sel_hi:[0,1,1]
	v_pk_fma_f32 v[200:201], v[154:155], v[200:201], v[116:117] op_sel_hi:[0,1,1]
	v_pk_fma_f32 v[202:203], v[154:155], v[202:203], v[118:119] op_sel_hi:[0,1,1]
	v_pk_fma_f32 v[204:205], v[154:155], v[204:205], v[120:121] op_sel_hi:[0,1,1]
	v_pk_fma_f32 v[206:207], v[154:155], v[206:207], v[122:123] op_sel_hi:[0,1,1]
	v_pk_fma_f32 v[208:209], v[154:155], v[208:209], v[124:125] op_sel_hi:[0,1,1]
	v_pk_fma_f32 v[210:211], v[154:155], v[210:211], v[126:127] op_sel_hi:[0,1,1]
	s_waitcnt lgkmcnt(5)
	v_pk_fma_f32 v[128:129], v[96:97], v[196:197], v[214:215]
	v_pk_fma_f32 v[130:131], v[98:99], v[198:199], v[214:215]
	s_waitcnt lgkmcnt(4)
	v_pk_fma_f32 v[128:129], v[100:101], v[200:201], v[128:129]
	v_pk_fma_f32 v[130:131], v[102:103], v[202:203], v[130:131]
	s_waitcnt lgkmcnt(3)
	v_pk_fma_f32 v[128:129], v[104:105], v[204:205], v[128:129]
	v_pk_fma_f32 v[130:131], v[106:107], v[206:207], v[130:131]
	s_waitcnt lgkmcnt(2)
	v_pk_fma_f32 v[128:129], v[108:109], v[208:209], v[128:129]
	v_pk_fma_f32 v[130:131], v[110:111], v[210:211], v[130:131]
	v_add_f32_e32 v128, v128, v129
	v_add_f32_e32 v130, v130, v131
	v_add_f32_e32 v213, v128, v130
	s_nop 1
	v_add_f32_dpp v213, v213, v213 row_ror:8 row_mask:0xf bank_mask:0xf bound_ctrl:1
	s_nop 1
	v_add_f32_dpp v213, v213, v213 row_ror:4 row_mask:0xf bank_mask:0xf bound_ctrl:1
	s_nop 1
	v_add_f32_dpp v213, v213, v213 row_ror:2 row_mask:0xf bank_mask:0xf bound_ctrl:1
	s_nop 1
	v_add_f32_dpp v213, v213, v213 row_ror:1 row_mask:0xf bank_mask:0xf bound_ctrl:1
	ds_write_b32 v190, v213 offset:35008
	s_waitcnt vmcnt(7)
	ds_write_b128 v188, v[32:35]
	s_waitcnt vmcnt(5)
	ds_write_b128 v191, v[40:43]
	ds_write_b128 v188, v[36:39] offset:8192
	s_waitcnt vmcnt(4)
	ds_write_b128 v191, v[44:47] offset:8192
	s_and_saveexec_b64 s[8:9], s[40:41]
	ds_write_b32 v145, v186 offset:16384
	s_or_b64 exec, exec, s[8:9]
	s_and_saveexec_b64 s[8:9], s[42:43]
	s_cbranch_execz .LBB0_1209
	v_add_f32_e32 v64, v178, v189
	v_mul_f32_e64 v65, |v64|, s62
	v_exp_f32_e32 v65, v65
	v_min_f32_e32 v64, 0, v64
	v_add_f32_e32 v65, 1.0, v65
	v_cmp_gt_f32_e32 vcc, s5, v65
	s_nop 1
	v_cndmask_b32_e64 v66, 0, 32, vcc
	v_ldexp_f32 v65, v65, v66
	v_log_f32_e32 v65, v65
	v_cndmask_b32_e32 v67, 0, v171, vcc
	v_add_f32_e32 v66, v147, v187
	v_mul_f32_e32 v68, 0x3f317217, v65
	v_fma_f32 v68, v65, s76, -v68
	v_fmac_f32_e32 v68, 0x3377d1cf, v65
	v_fmac_f32_e32 v68, 0x3f317217, v65
	v_cmp_lt_f32_e64 vcc, |v65|, s77
	s_nop 1
	v_cndmask_b32_e32 v65, v65, v68, vcc
	v_sub_f32_e32 v65, v65, v67
	v_sub_f32_e32 v64, v64, v65
	v_add_u32_e32 v65, 0x4000, v145
	ds_write2_b32 v65, v66, v64 offset0:128 offset1:144

.LBB0_1222:
	s_or_b64 exec, exec, s[8:9]
	s_waitcnt lgkmcnt(0)
	s_barrier
	v_mov_b32_e32 v214, 0
	v_mov_b32_e32 v215, 0
	ds_read_b128 v[80:83], v194 offset:8192
	ds_read_b128 v[84:87], v194 offset:8448
	ds_read_b128 v[88:91], v194 offset:8704
	ds_read_b128 v[92:95], v194 offset:8960
	ds_read_b32 v134, v140 offset:35136
	ds_read_b32 v135, v190 offset:16384
	ds_read_b32 v132, v140 offset:35072
	ds_read_b128 v[64:67], v194
	ds_read_b128 v[68:71], v194 offset:256
	ds_read_b128 v[72:75], v194 offset:512
	ds_read_b128 v[76:79], v194 offset:768
	ds_read_b128 v[112:115], v194 offset:9216
	ds_read_b128 v[116:119], v194 offset:9472
	ds_read_b128 v[120:123], v194 offset:9728
	ds_read_b128 v[124:127], v194 offset:9984
	ds_read_b32 v156, v140 offset:35140
	ds_read_b32 v157, v190 offset:16448
	ds_read_b32 v154, v140 offset:35076
	ds_read_b128 v[96:99], v194 offset:1024
	ds_read_b128 v[100:103], v194 offset:1280
	ds_read_b128 v[104:107], v194 offset:1536
	ds_read_b128 v[108:111], v194 offset:1792
	s_waitcnt lgkmcnt(15)
	v_mul_f32_e32 v133, v134, v135
	v_pk_mul_f32 v[80:81], v[80:81], v[132:133] op_sel:[0,1] op_sel_hi:[1,1]
	v_pk_mul_f32 v[82:83], v[82:83], v[132:133] op_sel:[0,1] op_sel_hi:[1,1]
	v_pk_mul_f32 v[84:85], v[84:85], v[132:133] op_sel:[0,1] op_sel_hi:[1,1]
	v_pk_mul_f32 v[86:87], v[86:87], v[132:133] op_sel:[0,1] op_sel_hi:[1,1]
	v_pk_mul_f32 v[88:89], v[88:89], v[132:133] op_sel:[0,1] op_sel_hi:[1,1]
	v_pk_mul_f32 v[90:91], v[90:91], v[132:133] op_sel:[0,1] op_sel_hi:[1,1]
	v_pk_mul_f32 v[92:93], v[92:93], v[132:133] op_sel:[0,1] op_sel_hi:[1,1]
	v_pk_mul_f32 v[94:95], v[94:95], v[132:133] op_sel:[0,1] op_sel_hi:[1,1]
	v_pk_fma_f32 v[196:197], v[132:133], v[196:197], v[80:81] op_sel_hi:[0,1,1]
	v_pk_fma_f32 v[198:199], v[132:133], v[198:199], v[82:83] op_sel_hi:[0,1,1]
	v_pk_fma_f32 v[200:201], v[132:133], v[200:201], v[84:85] op_sel_hi:[0,1,1]
	v_pk_fma_f32 v[202:203], v[132:133], v[202:203], v[86:87] op_sel_hi:[0,1,1]
	v_pk_fma_f32 v[204:205], v[132:133], v[204:205], v[88:89] op_sel_hi:[0,1,1]
	v_pk_fma_f32 v[206:207], v[132:133], v[206:207], v[90:91] op_sel_hi:[0,1,1]
	v_pk_fma_f32 v[208:209], v[132:133], v[208:209], v[92:93] op_sel_hi:[0,1,1]
	v_pk_fma_f32 v[210:211], v[132:133], v[210:211], v[94:95] op_sel_hi:[0,1,1]
	s_waitcnt lgkmcnt(14)
	v_pk_fma_f32 v[128:129], v[64:65], v[196:197], v[214:215]
	v_pk_fma_f32 v[130:131], v[66:67], v[198:199], v[214:215]
	s_waitcnt lgkmcnt(13)
	v_pk_fma_f32 v[128:129], v[68:69], v[200:201], v[128:129]
	v_pk_fma_f32 v[130:131], v[70:71], v[202:203], v[130:131]
	s_waitcnt lgkmcnt(12)
	v_pk_fma_f32 v[128:129], v[72:73], v[204:205], v[128:129]
	v_pk_fma_f32 v[130:131], v[74:75], v[206:207], v[130:131]
	s_waitcnt lgkmcnt(11)
	v_pk_fma_f32 v[128:129], v[76:77], v[208:209], v[128:129]
	v_pk_fma_f32 v[130:131], v[78:79], v[210:211], v[130:131]
	v_add_f32_e32 v128, v128, v129
	v_add_f32_e32 v130, v130, v131
	v_add_f32_e32 v212, v128, v130
	ds_read_b128 v[80:83], v194 offset:10240
	ds_read_b128 v[84:87], v194 offset:10496
	ds_read_b128 v[88:91], v194 offset:10752
	ds_read_b128 v[92:95], v194 offset:11008
	ds_read_b32 v134, v140 offset:35144
	ds_read_b32 v135, v190 offset:16512
	ds_read_b32 v132, v140 offset:35080
	ds_read_b128 v[64:67], v194 offset:2048
	ds_read_b128 v[68:71], v194 offset:2304
	ds_read_b128 v[72:75], v194 offset:2560
	ds_read_b128 v[76:79], v194 offset:2816
	s_waitcnt lgkmcnt(15)
	v_mul_f32_e32 v155, v156, v157
	v_pk_mul_f32 v[112:113], v[112:113], v[154:155] op_sel:[0,1] op_sel_hi:[1,1]
	v_add_f32_dpp v212, v212, v212 row_ror:8 row_mask:0xf bank_mask:0xf bound_ctrl:1
	v_pk_mul_f32 v[114:115], v[114:115], v[154:155] op_sel:[0,1] op_sel_hi:[1,1]
	v_pk_mul_f32 v[116:117], v[116:117], v[154:155] op_sel:[0,1] op_sel_hi:[1,1]
	v_add_f32_dpp v212, v212, v212 row_ror:4 row_mask:0xf bank_mask:0xf bound_ctrl:1
	v_pk_mul_f32 v[118:119], v[118:119], v[154:155] op_sel:[0,1] op_sel_hi:[1,1]
	v_pk_mul_f32 v[120:121], v[120:121], v[154:155] op_sel:[0,1] op_sel_hi:[1,1]
	v_add_f32_dpp v212, v212, v212 row_ror:2 row_mask:0xf bank_mask:0xf bound_ctrl:1
	v_pk_mul_f32 v[122:123], v[122:123], v[154:155] op_sel:[0,1] op_sel_hi:[1,1]
	v_pk_mul_f32 v[124:125], v[124:125], v[154:155] op_sel:[0,1] op_sel_hi:[1,1]
	v_add_f32_dpp v212, v212, v212 row_ror:1 row_mask:0xf bank_mask:0xf bound_ctrl:1
	v_pk_mul_f32 v[126:127], v[126:127], v[154:155] op_sel:[0,1] op_sel_hi:[1,1]
	v_pk_fma_f32 v[196:197], v[154:155], v[196:197], v[112:113] op_sel_hi:[0,1,1]
	ds_write_b32 v190, v212 offset:34048
	v_pk_fma_f32 v[198:199], v[154:155], v[198:199], v[114:115] op_sel_hi:[0,1,1]
	v_pk_fma_f32 v[200:201], v[154:155], v[200:201], v[116:117] op_sel_hi:[0,1,1]
	v_pk_fma_f32 v[202:203], v[154:155], v[202:203], v[118:119] op_sel_hi:[0,1,1]
	v_pk_fma_f32 v[204:205], v[154:155], v[204:205], v[120:121] op_sel_hi:[0,1,1]
	v_pk_fma_f32 v[206:207], v[154:155], v[206:207], v[122:123] op_sel_hi:[0,1,1]
	v_pk_fma_f32 v[208:209], v[154:155], v[208:209], v[124:125] op_sel_hi:[0,1,1]
	v_pk_fma_f32 v[210:211], v[154:155], v[210:211], v[126:127] op_sel_hi:[0,1,1]
	s_waitcnt lgkmcnt(15)
	v_pk_fma_f32 v[128:129], v[96:97], v[196:197], v[214:215]
	v_pk_fma_f32 v[130:131], v[98:99], v[198:199], v[214:215]
	s_waitcnt lgkmcnt(14)
	v_pk_fma_f32 v[128:129], v[100:101], v[200:201], v[128:129]
	v_pk_fma_f32 v[130:131], v[102:103], v[202:203], v[130:131]
	s_waitcnt lgkmcnt(13)
	v_pk_fma_f32 v[128:129], v[104:105], v[204:205], v[128:129]
	v_pk_fma_f32 v[130:131], v[106:107], v[206:207], v[130:131]
	s_waitcnt lgkmcnt(12)
	v_pk_fma_f32 v[128:129], v[108:109], v[208:209], v[128:129]
	v_pk_fma_f32 v[130:131], v[110:111], v[210:211], v[130:131]
	v_add_f32_e32 v128, v128, v129
	v_add_f32_e32 v130, v130, v131
	v_add_f32_e32 v213, v128, v130
	ds_read_b128 v[112:115], v194 offset:11264
	ds_read_b128 v[116:119], v194 offset:11520
	ds_read_b128 v[120:123], v194 offset:11776
	ds_read_b128 v[124:127], v194 offset:12032
	ds_read_b32 v156, v140 offset:35148
	ds_read_b32 v157, v190 offset:16576
	ds_read_b32 v154, v140 offset:35084
	ds_read_b128 v[96:99], v194 offset:3072
	ds_read_b128 v[100:103], v194 offset:3328
	ds_read_b128 v[104:107], v194 offset:3584
	ds_read_b128 v[108:111], v194 offset:3840
	s_waitcnt lgkmcnt(15)
	v_mul_f32_e32 v133, v134, v135
	v_pk_mul_f32 v[80:81], v[80:81], v[132:133] op_sel:[0,1] op_sel_hi:[1,1]
	v_add_f32_dpp v213, v213, v213 row_ror:8 row_mask:0xf bank_mask:0xf bound_ctrl:1
	v_pk_mul_f32 v[82:83], v[82:83], v[132:133] op_sel:[0,1] op_sel_hi:[1,1]
	v_pk_mul_f32 v[84:85], v[84:85], v[132:133] op_sel:[0,1] op_sel_hi:[1,1]
	v_add_f32_dpp v213, v213, v213 row_ror:4 row_mask:0xf bank_mask:0xf bound_ctrl:1
	v_pk_mul_f32 v[86:87], v[86:87], v[132:133] op_sel:[0,1] op_sel_hi:[1,1]
	v_pk_mul_f32 v[88:89], v[88:89], v[132:133] op_sel:[0,1] op_sel_hi:[1,1]
	v_add_f32_dpp v213, v213, v213 row_ror:2 row_mask:0xf bank_mask:0xf bound_ctrl:1
	v_pk_mul_f32 v[90:91], v[90:91], v[132:133] op_sel:[0,1] op_sel_hi:[1,1]
	v_pk_mul_f32 v[92:93], v[92:93], v[132:133] op_sel:[0,1] op_sel_hi:[1,1]
	v_add_f32_dpp v213, v213, v213 row_ror:1 row_mask:0xf bank_mask:0xf bound_ctrl:1
	v_pk_mul_f32 v[94:95], v[94:95], v[132:133] op_sel:[0,1] op_sel_hi:[1,1]
	v_pk_fma_f32 v[196:197], v[132:133], v[196:197], v[80:81] op_sel_hi:[0,1,1]
	ds_write_b32 v190, v213 offset:34112
	v_pk_fma_f32 v[198:199], v[132:133], v[198:199], v[82:83] op_sel_hi:[0,1,1]
	v_pk_fma_f32 v[200:201], v[132:133], v[200:201], v[84:85] op_sel_hi:[0,1,1]
	v_pk_fma_f32 v[202:203], v[132:133], v[202:203], v[86:87] op_sel_hi:[0,1,1]
	v_pk_fma_f32 v[204:205], v[132:133], v[204:205], v[88:89] op_sel_hi:[0,1,1]
	v_pk_fma_f32 v[206:207], v[132:133], v[206:207], v[90:91] op_sel_hi:[0,1,1]
	v_pk_fma_f32 v[208:209], v[132:133], v[208:209], v[92:93] op_sel_hi:[0,1,1]
	v_pk_fma_f32 v[210:211], v[132:133], v[210:211], v[94:95] op_sel_hi:[0,1,1]
	s_waitcnt lgkmcnt(15)
	v_pk_fma_f32 v[128:129], v[64:65], v[196:197], v[214:215]
	v_pk_fma_f32 v[130:131], v[66:67], v[198:199], v[214:215]
	v_pk_fma_f32 v[128:129], v[68:69], v[200:201], v[128:129]
	v_pk_fma_f32 v[130:131], v[70:71], v[202:203], v[130:131]
	s_waitcnt lgkmcnt(14)
	v_pk_fma_f32 v[128:129], v[72:73], v[204:205], v[128:129]
	v_pk_fma_f32 v[130:131], v[74:75], v[206:207], v[130:131]
	s_waitcnt lgkmcnt(13)
	v_pk_fma_f32 v[128:129], v[76:77], v[208:209], v[128:129]
	v_pk_fma_f32 v[130:131], v[78:79], v[210:211], v[130:131]
	v_add_f32_e32 v128, v128, v129
	v_add_f32_e32 v130, v130, v131
	v_add_f32_e32 v212, v128, v130
	ds_read_b128 v[80:83], v194 offset:12288
	ds_read_b128 v[84:87], v194 offset:12544
	ds_read_b128 v[88:91], v194 offset:12800
	ds_read_b128 v[92:95], v194 offset:13056
	ds_read_b32 v134, v140 offset:35152
	ds_read_b32 v135, v190 offset:16640
	ds_read_b32 v132, v140 offset:35088
	ds_read_b128 v[64:67], v194 offset:4096
	ds_read_b128 v[68:71], v194 offset:4352
	ds_read_b128 v[72:75], v194 offset:4608
	ds_read_b128 v[76:79], v194 offset:4864
	s_waitcnt lgkmcnt(15)
	v_mul_f32_e32 v155, v156, v157
	v_pk_mul_f32 v[112:113], v[112:113], v[154:155] op_sel:[0,1] op_sel_hi:[1,1]
	v_add_f32_dpp v212, v212, v212 row_ror:8 row_mask:0xf bank_mask:0xf bound_ctrl:1
	v_pk_mul_f32 v[114:115], v[114:115], v[154:155] op_sel:[0,1] op_sel_hi:[1,1]
	v_pk_mul_f32 v[116:117], v[116:117], v[154:155] op_sel:[0,1] op_sel_hi:[1,1]
	v_add_f32_dpp v212, v212, v212 row_ror:4 row_mask:0xf bank_mask:0xf bound_ctrl:1
	v_pk_mul_f32 v[118:119], v[118:119], v[154:155] op_sel:[0,1] op_sel_hi:[1,1]
	v_pk_mul_f32 v[120:121], v[120:121], v[154:155] op_sel:[0,1] op_sel_hi:[1,1]
	v_add_f32_dpp v212, v212, v212 row_ror:2 row_mask:0xf bank_mask:0xf bound_ctrl:1
	v_pk_mul_f32 v[122:123], v[122:123], v[154:155] op_sel:[0,1] op_sel_hi:[1,1]
	v_pk_mul_f32 v[124:125], v[124:125], v[154:155] op_sel:[0,1] op_sel_hi:[1,1]
	v_add_f32_dpp v212, v212, v212 row_ror:1 row_mask:0xf bank_mask:0xf bound_ctrl:1
	v_pk_mul_f32 v[126:127], v[126:127], v[154:155] op_sel:[0,1] op_sel_hi:[1,1]
	v_pk_fma_f32 v[196:197], v[154:155], v[196:197], v[112:113] op_sel_hi:[0,1,1]
	ds_write_b32 v190, v212 offset:34176
	v_pk_fma_f32 v[198:199], v[154:155], v[198:199], v[114:115] op_sel_hi:[0,1,1]
	v_pk_fma_f32 v[200:201], v[154:155], v[200:201], v[116:117] op_sel_hi:[0,1,1]
	v_pk_fma_f32 v[202:203], v[154:155], v[202:203], v[118:119] op_sel_hi:[0,1,1]
	v_pk_fma_f32 v[204:205], v[154:155], v[204:205], v[120:121] op_sel_hi:[0,1,1]
	v_pk_fma_f32 v[206:207], v[154:155], v[206:207], v[122:123] op_sel_hi:[0,1,1]
	v_pk_fma_f32 v[208:209], v[154:155], v[208:209], v[124:125] op_sel_hi:[0,1,1]
	v_pk_fma_f32 v[210:211], v[154:155], v[210:211], v[126:127] op_sel_hi:[0,1,1]
	s_waitcnt lgkmcnt(15)
	v_pk_fma_f32 v[128:129], v[96:97], v[196:197], v[214:215]
	v_pk_fma_f32 v[130:131], v[98:99], v[198:199], v[214:215]
	v_pk_fma_f32 v[128:129], v[100:101], v[200:201], v[128:129]
	v_pk_fma_f32 v[130:131], v[102:103], v[202:203], v[130:131]
	s_waitcnt lgkmcnt(14)
	v_pk_fma_f32 v[128:129], v[104:105], v[204:205], v[128:129]
	v_pk_fma_f32 v[130:131], v[106:107], v[206:207], v[130:131]
	s_waitcnt lgkmcnt(13)
	v_pk_fma_f32 v[128:129], v[108:109], v[208:209], v[128:129]
	v_pk_fma_f32 v[130:131], v[110:111], v[210:211], v[130:131]
	v_add_f32_e32 v128, v128, v129
	v_add_f32_e32 v130, v130, v131
	v_add_f32_e32 v213, v128, v130
	ds_read_b128 v[112:115], v194 offset:13312
	ds_read_b128 v[116:119], v194 offset:13568
	ds_read_b128 v[120:123], v194 offset:13824
	ds_read_b128 v[124:127], v194 offset:14080
	ds_read_b32 v156, v140 offset:35156
	ds_read_b32 v157, v190 offset:16704
	ds_read_b32 v154, v140 offset:35092
	ds_read_b128 v[96:99], v194 offset:5120
	ds_read_b128 v[100:103], v194 offset:5376
	ds_read_b128 v[104:107], v194 offset:5632
	ds_read_b128 v[108:111], v194 offset:5888
	s_waitcnt lgkmcnt(15)
	v_mul_f32_e32 v133, v134, v135
	v_pk_mul_f32 v[80:81], v[80:81], v[132:133] op_sel:[0,1] op_sel_hi:[1,1]
	v_add_f32_dpp v213, v213, v213 row_ror:8 row_mask:0xf bank_mask:0xf bound_ctrl:1
	v_pk_mul_f32 v[82:83], v[82:83], v[132:133] op_sel:[0,1] op_sel_hi:[1,1]
	v_pk_mul_f32 v[84:85], v[84:85], v[132:133] op_sel:[0,1] op_sel_hi:[1,1]
	v_add_f32_dpp v213, v213, v213 row_ror:4 row_mask:0xf bank_mask:0xf bound_ctrl:1
	v_pk_mul_f32 v[86:87], v[86:87], v[132:133] op_sel:[0,1] op_sel_hi:[1,1]
	v_pk_mul_f32 v[88:89], v[88:89], v[132:133] op_sel:[0,1] op_sel_hi:[1,1]
	v_add_f32_dpp v213, v213, v213 row_ror:2 row_mask:0xf bank_mask:0xf bound_ctrl:1
	v_pk_mul_f32 v[90:91], v[90:91], v[132:133] op_sel:[0,1] op_sel_hi:[1,1]
	v_pk_mul_f32 v[92:93], v[92:93], v[132:133] op_sel:[0,1] op_sel_hi:[1,1]
	v_add_f32_dpp v213, v213, v213 row_ror:1 row_mask:0xf bank_mask:0xf bound_ctrl:1
	v_pk_mul_f32 v[94:95], v[94:95], v[132:133] op_sel:[0,1] op_sel_hi:[1,1]
	v_pk_fma_f32 v[196:197], v[132:133], v[196:197], v[80:81] op_sel_hi:[0,1,1]
	ds_write_b32 v190, v213 offset:34240
	v_pk_fma_f32 v[198:199], v[132:133], v[198:199], v[82:83] op_sel_hi:[0,1,1]
	v_pk_fma_f32 v[200:201], v[132:133], v[200:201], v[84:85] op_sel_hi:[0,1,1]
	v_pk_fma_f32 v[202:203], v[132:133], v[202:203], v[86:87] op_sel_hi:[0,1,1]
	v_pk_fma_f32 v[204:205], v[132:133], v[204:205], v[88:89] op_sel_hi:[0,1,1]
	v_pk_fma_f32 v[206:207], v[132:133], v[206:207], v[90:91] op_sel_hi:[0,1,1]
	v_pk_fma_f32 v[208:209], v[132:133], v[208:209], v[92:93] op_sel_hi:[0,1,1]
	v_pk_fma_f32 v[210:211], v[132:133], v[210:211], v[94:95] op_sel_hi:[0,1,1]
	s_waitcnt lgkmcnt(15)
	v_pk_fma_f32 v[128:129], v[64:65], v[196:197], v[214:215]
	v_pk_fma_f32 v[130:131], v[66:67], v[198:199], v[214:215]
	v_pk_fma_f32 v[128:129], v[68:69], v[200:201], v[128:129]
	v_pk_fma_f32 v[130:131], v[70:71], v[202:203], v[130:131]
	s_waitcnt lgkmcnt(14)
	v_pk_fma_f32 v[128:129], v[72:73], v[204:205], v[128:129]
	v_pk_fma_f32 v[130:131], v[74:75], v[206:207], v[130:131]
	s_waitcnt lgkmcnt(13)
	v_pk_fma_f32 v[128:129], v[76:77], v[208:209], v[128:129]
	v_pk_fma_f32 v[130:131], v[78:79], v[210:211], v[130:131]
	v_add_f32_e32 v128, v128, v129
	v_add_f32_e32 v130, v130, v131
	v_add_f32_e32 v212, v128, v130
	ds_read_b128 v[80:83], v194 offset:14336
	ds_read_b128 v[84:87], v194 offset:14592
	ds_read_b128 v[88:91], v194 offset:14848
	ds_read_b128 v[92:95], v194 offset:15104
	ds_read_b32 v134, v140 offset:35160
	ds_read_b32 v135, v190 offset:16768
	ds_read_b32 v132, v140 offset:35096
	ds_read_b128 v[64:67], v194 offset:6144
	ds_read_b128 v[68:71], v194 offset:6400
	ds_read_b128 v[72:75], v194 offset:6656
	ds_read_b128 v[76:79], v194 offset:6912
	s_waitcnt lgkmcnt(15)
	v_mul_f32_e32 v155, v156, v157
	v_pk_mul_f32 v[112:113], v[112:113], v[154:155] op_sel:[0,1] op_sel_hi:[1,1]
	v_add_f32_dpp v212, v212, v212 row_ror:8 row_mask:0xf bank_mask:0xf bound_ctrl:1
	v_pk_mul_f32 v[114:115], v[114:115], v[154:155] op_sel:[0,1] op_sel_hi:[1,1]
	v_pk_mul_f32 v[116:117], v[116:117], v[154:155] op_sel:[0,1] op_sel_hi:[1,1]
	v_add_f32_dpp v212, v212, v212 row_ror:4 row_mask:0xf bank_mask:0xf bound_ctrl:1
	v_pk_mul_f32 v[118:119], v[118:119], v[154:155] op_sel:[0,1] op_sel_hi:[1,1]
	v_pk_mul_f32 v[120:121], v[120:121], v[154:155] op_sel:[0,1] op_sel_hi:[1,1]
	v_add_f32_dpp v212, v212, v212 row_ror:2 row_mask:0xf bank_mask:0xf bound_ctrl:1
	v_pk_mul_f32 v[122:123], v[122:123], v[154:155] op_sel:[0,1] op_sel_hi:[1,1]
	v_pk_mul_f32 v[124:125], v[124:125], v[154:155] op_sel:[0,1] op_sel_hi:[1,1]
	v_add_f32_dpp v212, v212, v212 row_ror:1 row_mask:0xf bank_mask:0xf bound_ctrl:1
	v_pk_mul_f32 v[126:127], v[126:127], v[154:155] op_sel:[0,1] op_sel_hi:[1,1]
	v_pk_fma_f32 v[196:197], v[154:155], v[196:197], v[112:113] op_sel_hi:[0,1,1]
	ds_write_b32 v190, v212 offset:34304
	v_pk_fma_f32 v[198:199], v[154:155], v[198:199], v[114:115] op_sel_hi:[0,1,1]
	v_pk_fma_f32 v[200:201], v[154:155], v[200:201], v[116:117] op_sel_hi:[0,1,1]
	v_pk_fma_f32 v[202:203], v[154:155], v[202:203], v[118:119] op_sel_hi:[0,1,1]
	v_pk_fma_f32 v[204:205], v[154:155], v[204:205], v[120:121] op_sel_hi:[0,1,1]
	v_pk_fma_f32 v[206:207], v[154:155], v[206:207], v[122:123] op_sel_hi:[0,1,1]
	v_pk_fma_f32 v[208:209], v[154:155], v[208:209], v[124:125] op_sel_hi:[0,1,1]
	v_pk_fma_f32 v[210:211], v[154:155], v[210:211], v[126:127] op_sel_hi:[0,1,1]
	s_waitcnt lgkmcnt(15)
	v_pk_fma_f32 v[128:129], v[96:97], v[196:197], v[214:215]
	v_pk_fma_f32 v[130:131], v[98:99], v[198:199], v[214:215]
	v_pk_fma_f32 v[128:129], v[100:101], v[200:201], v[128:129]
	v_pk_fma_f32 v[130:131], v[102:103], v[202:203], v[130:131]
	s_waitcnt lgkmcnt(14)
	v_pk_fma_f32 v[128:129], v[104:105], v[204:205], v[128:129]
	v_pk_fma_f32 v[130:131], v[106:107], v[206:207], v[130:131]
	s_waitcnt lgkmcnt(13)
	v_pk_fma_f32 v[128:129], v[108:109], v[208:209], v[128:129]
	v_pk_fma_f32 v[130:131], v[110:111], v[210:211], v[130:131]
	v_add_f32_e32 v128, v128, v129
	v_add_f32_e32 v130, v130, v131
	v_add_f32_e32 v213, v128, v130
	ds_read_b128 v[112:115], v194 offset:15360
	ds_read_b128 v[116:119], v194 offset:15616
	ds_read_b128 v[120:123], v194 offset:15872
	ds_read_b128 v[124:127], v194 offset:16128
	ds_read_b32 v156, v140 offset:35164
	ds_read_b32 v157, v190 offset:16832
	ds_read_b32 v154, v140 offset:35100
	ds_read_b128 v[96:99], v194 offset:7168
	ds_read_b128 v[100:103], v194 offset:7424
	ds_read_b128 v[104:107], v194 offset:7680
	ds_read_b128 v[108:111], v194 offset:7936
	s_waitcnt lgkmcnt(15)
	v_mul_f32_e32 v133, v134, v135
	v_pk_mul_f32 v[80:81], v[80:81], v[132:133] op_sel:[0,1] op_sel_hi:[1,1]
	v_add_f32_dpp v213, v213, v213 row_ror:8 row_mask:0xf bank_mask:0xf bound_ctrl:1
	v_pk_mul_f32 v[82:83], v[82:83], v[132:133] op_sel:[0,1] op_sel_hi:[1,1]
	v_pk_mul_f32 v[84:85], v[84:85], v[132:133] op_sel:[0,1] op_sel_hi:[1,1]
	v_add_f32_dpp v213, v213, v213 row_ror:4 row_mask:0xf bank_mask:0xf bound_ctrl:1
	v_pk_mul_f32 v[86:87], v[86:87], v[132:133] op_sel:[0,1] op_sel_hi:[1,1]
	v_pk_mul_f32 v[88:89], v[88:89], v[132:133] op_sel:[0,1] op_sel_hi:[1,1]
	v_add_f32_dpp v213, v213, v213 row_ror:2 row_mask:0xf bank_mask:0xf bound_ctrl:1
	v_pk_mul_f32 v[90:91], v[90:91], v[132:133] op_sel:[0,1] op_sel_hi:[1,1]
	v_pk_mul_f32 v[92:93], v[92:93], v[132:133] op_sel:[0,1] op_sel_hi:[1,1]
	v_add_f32_dpp v213, v213, v213 row_ror:1 row_mask:0xf bank_mask:0xf bound_ctrl:1
	v_pk_mul_f32 v[94:95], v[94:95], v[132:133] op_sel:[0,1] op_sel_hi:[1,1]
	v_pk_fma_f32 v[196:197], v[132:133], v[196:197], v[80:81] op_sel_hi:[0,1,1]
	ds_write_b32 v190, v213 offset:34368
	v_pk_fma_f32 v[198:199], v[132:133], v[198:199], v[82:83] op_sel_hi:[0,1,1]
	v_pk_fma_f32 v[200:201], v[132:133], v[200:201], v[84:85] op_sel_hi:[0,1,1]
	v_pk_fma_f32 v[202:203], v[132:133], v[202:203], v[86:87] op_sel_hi:[0,1,1]
	v_pk_fma_f32 v[204:205], v[132:133], v[204:205], v[88:89] op_sel_hi:[0,1,1]
	v_pk_fma_f32 v[206:207], v[132:133], v[206:207], v[90:91] op_sel_hi:[0,1,1]
	v_pk_fma_f32 v[208:209], v[132:133], v[208:209], v[92:93] op_sel_hi:[0,1,1]
	v_pk_fma_f32 v[210:211], v[132:133], v[210:211], v[94:95] op_sel_hi:[0,1,1]
	s_waitcnt lgkmcnt(15)
	v_pk_fma_f32 v[128:129], v[64:65], v[196:197], v[214:215]
	v_pk_fma_f32 v[130:131], v[66:67], v[198:199], v[214:215]
	v_pk_fma_f32 v[128:129], v[68:69], v[200:201], v[128:129]
	v_pk_fma_f32 v[130:131], v[70:71], v[202:203], v[130:131]
	s_waitcnt lgkmcnt(14)
	v_pk_fma_f32 v[128:129], v[72:73], v[204:205], v[128:129]
	v_pk_fma_f32 v[130:131], v[74:75], v[206:207], v[130:131]
	s_waitcnt lgkmcnt(13)
	v_pk_fma_f32 v[128:129], v[76:77], v[208:209], v[128:129]
	v_pk_fma_f32 v[130:131], v[78:79], v[210:211], v[130:131]
	v_add_f32_e32 v128, v128, v129
	v_add_f32_e32 v130, v130, v131
	v_add_f32_e32 v212, v128, v130
	s_waitcnt lgkmcnt(6)
	v_mul_f32_e32 v155, v156, v157
	v_pk_mul_f32 v[112:113], v[112:113], v[154:155] op_sel:[0,1] op_sel_hi:[1,1]
	v_add_f32_dpp v212, v212, v212 row_ror:8 row_mask:0xf bank_mask:0xf bound_ctrl:1
	v_pk_mul_f32 v[114:115], v[114:115], v[154:155] op_sel:[0,1] op_sel_hi:[1,1]
	v_pk_mul_f32 v[116:117], v[116:117], v[154:155] op_sel:[0,1] op_sel_hi:[1,1]
	v_add_f32_dpp v212, v212, v212 row_ror:4 row_mask:0xf bank_mask:0xf bound_ctrl:1
	v_pk_mul_f32 v[118:119], v[118:119], v[154:155] op_sel:[0,1] op_sel_hi:[1,1]
	v_pk_mul_f32 v[120:121], v[120:121], v[154:155] op_sel:[0,1] op_sel_hi:[1,1]
	v_add_f32_dpp v212, v212, v212 row_ror:2 row_mask:0xf bank_mask:0xf bound_ctrl:1
	v_pk_mul_f32 v[122:123], v[122:123], v[154:155] op_sel:[0,1] op_sel_hi:[1,1]
	v_pk_mul_f32 v[124:125], v[124:125], v[154:155] op_sel:[0,1] op_sel_hi:[1,1]
	v_add_f32_dpp v212, v212, v212 row_ror:1 row_mask:0xf bank_mask:0xf bound_ctrl:1
	v_pk_mul_f32 v[126:127], v[126:127], v[154:155] op_sel:[0,1] op_sel_hi:[1,1]
	s_waitcnt lgkmcnt(5)
	v_pk_fma_f32 v[196:197], v[154:155], v[196:197], v[112:113] op_sel_hi:[0,1,1]
	ds_write_b32 v190, v212 offset:34432
	v_pk_fma_f32 v[198:199], v[154:155], v[198:199], v[114:115] op_sel_hi:[0,1,1]
	v_pk_fma_f32 v[200:201], v[154:155], v[200:201], v[116:117] op_sel_hi:[0,1,1]
	v_pk_fma_f32 v[202:203], v[154:155], v[202:203], v[118:119] op_sel_hi:[0,1,1]
	v_pk_fma_f32 v[204:205], v[154:155], v[204:205], v[120:121] op_sel_hi:[0,1,1]
	v_pk_fma_f32 v[206:207], v[154:155], v[206:207], v[122:123] op_sel_hi:[0,1,1]
	v_pk_fma_f32 v[208:209], v[154:155], v[208:209], v[124:125] op_sel_hi:[0,1,1]
	v_pk_fma_f32 v[210:211], v[154:155], v[210:211], v[126:127] op_sel_hi:[0,1,1]
	s_waitcnt lgkmcnt(5)
	v_pk_fma_f32 v[128:129], v[96:97], v[196:197], v[214:215]
	v_pk_fma_f32 v[130:131], v[98:99], v[198:199], v[214:215]
	s_waitcnt lgkmcnt(4)
	v_pk_fma_f32 v[128:129], v[100:101], v[200:201], v[128:129]
	v_pk_fma_f32 v[130:131], v[102:103], v[202:203], v[130:131]
	s_waitcnt lgkmcnt(3)
	v_pk_fma_f32 v[128:129], v[104:105], v[204:205], v[128:129]
	v_pk_fma_f32 v[130:131], v[106:107], v[206:207], v[130:131]
	s_waitcnt lgkmcnt(2)
	v_pk_fma_f32 v[128:129], v[108:109], v[208:209], v[128:129]
	v_pk_fma_f32 v[130:131], v[110:111], v[210:211], v[130:131]
	v_add_f32_e32 v128, v128, v129
	v_add_f32_e32 v130, v130, v131
	v_add_f32_e32 v213, v128, v130
	s_nop 1
	v_add_f32_dpp v213, v213, v213 row_ror:8 row_mask:0xf bank_mask:0xf bound_ctrl:1
	s_nop 1
	v_add_f32_dpp v213, v213, v213 row_ror:4 row_mask:0xf bank_mask:0xf bound_ctrl:1
	s_nop 1
	v_add_f32_dpp v213, v213, v213 row_ror:2 row_mask:0xf bank_mask:0xf bound_ctrl:1
	s_nop 1
	v_add_f32_dpp v213, v213, v213 row_ror:1 row_mask:0xf bank_mask:0xf bound_ctrl:1
	ds_write_b32 v190, v213 offset:34496
	s_waitcnt vmcnt(3)
	ds_write_b128 v188, v[48:51] offset:17024
	s_waitcnt vmcnt(1)
	ds_write_b128 v191, v[56:59] offset:17024
	ds_write_b128 v188, v[52:55] offset:25216
	s_waitcnt vmcnt(0)
	ds_write_b128 v191, v[60:63] offset:25216
	s_and_saveexec_b64 s[8:9], s[40:41]
	ds_write_b32 v145, v192 offset:33408
	s_or_b64 exec, exec, s[8:9]
	s_and_saveexec_b64 s[8:9], s[42:43]
	s_cbranch_execz .LBB0_1242
	v_add_f32_e32 v64, v178, v195
	v_mul_f32_e64 v65, |v64|, s62
	v_exp_f32_e32 v65, v65
	v_min_f32_e32 v64, 0, v64
	v_add_f32_e32 v65, 1.0, v65
	v_cmp_gt_f32_e32 vcc, s5, v65
	s_nop 1
	v_cndmask_b32_e64 v66, 0, 32, vcc
	v_ldexp_f32 v65, v65, v66
	v_log_f32_e32 v65, v65
	v_cndmask_b32_e32 v67, 0, v171, vcc
	v_add_f32_e32 v66, v147, v193
	v_mul_f32_e32 v68, 0x3f317217, v65
	v_fma_f32 v68, v65, s76, -v68
	v_fmac_f32_e32 v68, 0x3377d1cf, v65
	v_fmac_f32_e32 v68, 0x3f317217, v65
	v_cmp_lt_f32_e64 vcc, |v65|, s77
	s_nop 1
	v_cndmask_b32_e32 v65, v65, v68, vcc
	v_sub_f32_e32 v65, v65, v67
	v_sub_f32_e32 v64, v64, v65
	v_add_u32_e32 v65, 0x8400, v145
	ds_write2_b32 v65, v66, v64 offset0:32 offset1:48

.LBB0_1255:
	s_or_b64 exec, exec, s[8:9]
	s_waitcnt lgkmcnt(0)
	s_barrier
	v_mov_b32_e32 v214, 0
	v_mov_b32_e32 v215, 0
	ds_read_b128 v[80:83], v194 offset:25216
	ds_read_b128 v[84:87], v194 offset:25472
	ds_read_b128 v[88:91], v194 offset:25728
	ds_read_b128 v[92:95], v194 offset:25984
	ds_read_b32 v134, v140 offset:35136
	ds_read_b32 v135, v190 offset:33408
	ds_read_b32 v132, v140 offset:35072
	ds_read_b128 v[64:67], v194 offset:17024
	ds_read_b128 v[68:71], v194 offset:17280
	ds_read_b128 v[72:75], v194 offset:17536
	ds_read_b128 v[76:79], v194 offset:17792
	ds_read_b128 v[112:115], v194 offset:26240
	ds_read_b128 v[116:119], v194 offset:26496
	ds_read_b128 v[120:123], v194 offset:26752
	ds_read_b128 v[124:127], v194 offset:27008
	ds_read_b32 v156, v140 offset:35140
	ds_read_b32 v157, v190 offset:33472
	ds_read_b32 v154, v140 offset:35076
	ds_read_b128 v[96:99], v194 offset:18048
	ds_read_b128 v[100:103], v194 offset:18304
	ds_read_b128 v[104:107], v194 offset:18560
	ds_read_b128 v[108:111], v194 offset:18816
	s_waitcnt lgkmcnt(15)
	v_mul_f32_e32 v133, v134, v135
	v_pk_mul_f32 v[80:81], v[80:81], v[132:133] op_sel:[0,1] op_sel_hi:[1,1]
	v_pk_mul_f32 v[82:83], v[82:83], v[132:133] op_sel:[0,1] op_sel_hi:[1,1]
	v_pk_mul_f32 v[84:85], v[84:85], v[132:133] op_sel:[0,1] op_sel_hi:[1,1]
	v_pk_mul_f32 v[86:87], v[86:87], v[132:133] op_sel:[0,1] op_sel_hi:[1,1]
	v_pk_mul_f32 v[88:89], v[88:89], v[132:133] op_sel:[0,1] op_sel_hi:[1,1]
	v_pk_mul_f32 v[90:91], v[90:91], v[132:133] op_sel:[0,1] op_sel_hi:[1,1]
	v_pk_mul_f32 v[92:93], v[92:93], v[132:133] op_sel:[0,1] op_sel_hi:[1,1]
	v_pk_mul_f32 v[94:95], v[94:95], v[132:133] op_sel:[0,1] op_sel_hi:[1,1]
	v_pk_fma_f32 v[196:197], v[132:133], v[196:197], v[80:81] op_sel_hi:[0,1,1]
	v_pk_fma_f32 v[198:199], v[132:133], v[198:199], v[82:83] op_sel_hi:[0,1,1]
	v_pk_fma_f32 v[200:201], v[132:133], v[200:201], v[84:85] op_sel_hi:[0,1,1]
	v_pk_fma_f32 v[202:203], v[132:133], v[202:203], v[86:87] op_sel_hi:[0,1,1]
	v_pk_fma_f32 v[204:205], v[132:133], v[204:205], v[88:89] op_sel_hi:[0,1,1]
	v_pk_fma_f32 v[206:207], v[132:133], v[206:207], v[90:91] op_sel_hi:[0,1,1]
	v_pk_fma_f32 v[208:209], v[132:133], v[208:209], v[92:93] op_sel_hi:[0,1,1]
	v_pk_fma_f32 v[210:211], v[132:133], v[210:211], v[94:95] op_sel_hi:[0,1,1]
	s_waitcnt lgkmcnt(14)
	v_pk_fma_f32 v[128:129], v[64:65], v[196:197], v[214:215]
	v_pk_fma_f32 v[130:131], v[66:67], v[198:199], v[214:215]
	s_waitcnt lgkmcnt(13)
	v_pk_fma_f32 v[128:129], v[68:69], v[200:201], v[128:129]
	v_pk_fma_f32 v[130:131], v[70:71], v[202:203], v[130:131]
	s_waitcnt lgkmcnt(12)
	v_pk_fma_f32 v[128:129], v[72:73], v[204:205], v[128:129]
	v_pk_fma_f32 v[130:131], v[74:75], v[206:207], v[130:131]
	s_waitcnt lgkmcnt(11)
	v_pk_fma_f32 v[128:129], v[76:77], v[208:209], v[128:129]
	v_pk_fma_f32 v[130:131], v[78:79], v[210:211], v[130:131]
	v_add_f32_e32 v128, v128, v129
	v_add_f32_e32 v130, v130, v131
	v_add_f32_e32 v212, v128, v130
	ds_read_b128 v[80:83], v194 offset:27264
	ds_read_b128 v[84:87], v194 offset:27520
	ds_read_b128 v[88:91], v194 offset:27776
	ds_read_b128 v[92:95], v194 offset:28032
	ds_read_b32 v134, v140 offset:35144
	ds_read_b32 v135, v190 offset:33536
	ds_read_b32 v132, v140 offset:35080
	ds_read_b128 v[64:67], v194 offset:19072
	ds_read_b128 v[68:71], v194 offset:19328
	ds_read_b128 v[72:75], v194 offset:19584
	ds_read_b128 v[76:79], v194 offset:19840
	s_waitcnt lgkmcnt(15)
	v_mul_f32_e32 v155, v156, v157
	v_pk_mul_f32 v[112:113], v[112:113], v[154:155] op_sel:[0,1] op_sel_hi:[1,1]
	v_add_f32_dpp v212, v212, v212 row_ror:8 row_mask:0xf bank_mask:0xf bound_ctrl:1
	v_pk_mul_f32 v[114:115], v[114:115], v[154:155] op_sel:[0,1] op_sel_hi:[1,1]
	v_pk_mul_f32 v[116:117], v[116:117], v[154:155] op_sel:[0,1] op_sel_hi:[1,1]
	v_add_f32_dpp v212, v212, v212 row_ror:4 row_mask:0xf bank_mask:0xf bound_ctrl:1
	v_pk_mul_f32 v[118:119], v[118:119], v[154:155] op_sel:[0,1] op_sel_hi:[1,1]
	v_pk_mul_f32 v[120:121], v[120:121], v[154:155] op_sel:[0,1] op_sel_hi:[1,1]
	v_add_f32_dpp v212, v212, v212 row_ror:2 row_mask:0xf bank_mask:0xf bound_ctrl:1
	v_pk_mul_f32 v[122:123], v[122:123], v[154:155] op_sel:[0,1] op_sel_hi:[1,1]
	v_pk_mul_f32 v[124:125], v[124:125], v[154:155] op_sel:[0,1] op_sel_hi:[1,1]
	v_add_f32_dpp v212, v212, v212 row_ror:1 row_mask:0xf bank_mask:0xf bound_ctrl:1
	v_pk_mul_f32 v[126:127], v[126:127], v[154:155] op_sel:[0,1] op_sel_hi:[1,1]
	v_pk_fma_f32 v[196:197], v[154:155], v[196:197], v[112:113] op_sel_hi:[0,1,1]
	ds_write_b32 v190, v212 offset:34560
	v_pk_fma_f32 v[198:199], v[154:155], v[198:199], v[114:115] op_sel_hi:[0,1,1]
	v_pk_fma_f32 v[200:201], v[154:155], v[200:201], v[116:117] op_sel_hi:[0,1,1]
	v_pk_fma_f32 v[202:203], v[154:155], v[202:203], v[118:119] op_sel_hi:[0,1,1]
	v_pk_fma_f32 v[204:205], v[154:155], v[204:205], v[120:121] op_sel_hi:[0,1,1]
	v_pk_fma_f32 v[206:207], v[154:155], v[206:207], v[122:123] op_sel_hi:[0,1,1]
	v_pk_fma_f32 v[208:209], v[154:155], v[208:209], v[124:125] op_sel_hi:[0,1,1]
	v_pk_fma_f32 v[210:211], v[154:155], v[210:211], v[126:127] op_sel_hi:[0,1,1]
	s_waitcnt lgkmcnt(15)
	v_pk_fma_f32 v[128:129], v[96:97], v[196:197], v[214:215]
	v_pk_fma_f32 v[130:131], v[98:99], v[198:199], v[214:215]
	s_waitcnt lgkmcnt(14)
	v_pk_fma_f32 v[128:129], v[100:101], v[200:201], v[128:129]
	v_pk_fma_f32 v[130:131], v[102:103], v[202:203], v[130:131]
	s_waitcnt lgkmcnt(13)
	v_pk_fma_f32 v[128:129], v[104:105], v[204:205], v[128:129]
	v_pk_fma_f32 v[130:131], v[106:107], v[206:207], v[130:131]
	s_waitcnt lgkmcnt(12)
	v_pk_fma_f32 v[128:129], v[108:109], v[208:209], v[128:129]
	v_pk_fma_f32 v[130:131], v[110:111], v[210:211], v[130:131]
	v_add_f32_e32 v128, v128, v129
	v_add_f32_e32 v130, v130, v131
	v_add_f32_e32 v213, v128, v130
	ds_read_b128 v[112:115], v194 offset:28288
	ds_read_b128 v[116:119], v194 offset:28544
	ds_read_b128 v[120:123], v194 offset:28800
	ds_read_b128 v[124:127], v194 offset:29056
	ds_read_b32 v156, v140 offset:35148
	ds_read_b32 v157, v190 offset:33600
	ds_read_b32 v154, v140 offset:35084
	ds_read_b128 v[96:99], v194 offset:20096
	ds_read_b128 v[100:103], v194 offset:20352
	ds_read_b128 v[104:107], v194 offset:20608
	ds_read_b128 v[108:111], v194 offset:20864
	s_waitcnt lgkmcnt(15)
	v_mul_f32_e32 v133, v134, v135
	v_pk_mul_f32 v[80:81], v[80:81], v[132:133] op_sel:[0,1] op_sel_hi:[1,1]
	v_add_f32_dpp v213, v213, v213 row_ror:8 row_mask:0xf bank_mask:0xf bound_ctrl:1
	v_pk_mul_f32 v[82:83], v[82:83], v[132:133] op_sel:[0,1] op_sel_hi:[1,1]
	v_pk_mul_f32 v[84:85], v[84:85], v[132:133] op_sel:[0,1] op_sel_hi:[1,1]
	v_add_f32_dpp v213, v213, v213 row_ror:4 row_mask:0xf bank_mask:0xf bound_ctrl:1
	v_pk_mul_f32 v[86:87], v[86:87], v[132:133] op_sel:[0,1] op_sel_hi:[1,1]
	v_pk_mul_f32 v[88:89], v[88:89], v[132:133] op_sel:[0,1] op_sel_hi:[1,1]
	v_add_f32_dpp v213, v213, v213 row_ror:2 row_mask:0xf bank_mask:0xf bound_ctrl:1
	v_pk_mul_f32 v[90:91], v[90:91], v[132:133] op_sel:[0,1] op_sel_hi:[1,1]
	v_pk_mul_f32 v[92:93], v[92:93], v[132:133] op_sel:[0,1] op_sel_hi:[1,1]
	v_add_f32_dpp v213, v213, v213 row_ror:1 row_mask:0xf bank_mask:0xf bound_ctrl:1
	v_pk_mul_f32 v[94:95], v[94:95], v[132:133] op_sel:[0,1] op_sel_hi:[1,1]
	v_pk_fma_f32 v[196:197], v[132:133], v[196:197], v[80:81] op_sel_hi:[0,1,1]
	ds_write_b32 v190, v213 offset:34624
	v_pk_fma_f32 v[198:199], v[132:133], v[198:199], v[82:83] op_sel_hi:[0,1,1]
	v_pk_fma_f32 v[200:201], v[132:133], v[200:201], v[84:85] op_sel_hi:[0,1,1]
	v_pk_fma_f32 v[202:203], v[132:133], v[202:203], v[86:87] op_sel_hi:[0,1,1]
	v_pk_fma_f32 v[204:205], v[132:133], v[204:205], v[88:89] op_sel_hi:[0,1,1]
	v_pk_fma_f32 v[206:207], v[132:133], v[206:207], v[90:91] op_sel_hi:[0,1,1]
	v_pk_fma_f32 v[208:209], v[132:133], v[208:209], v[92:93] op_sel_hi:[0,1,1]
	v_pk_fma_f32 v[210:211], v[132:133], v[210:211], v[94:95] op_sel_hi:[0,1,1]
	s_waitcnt lgkmcnt(15)
	v_pk_fma_f32 v[128:129], v[64:65], v[196:197], v[214:215]
	v_pk_fma_f32 v[130:131], v[66:67], v[198:199], v[214:215]
	v_pk_fma_f32 v[128:129], v[68:69], v[200:201], v[128:129]
	v_pk_fma_f32 v[130:131], v[70:71], v[202:203], v[130:131]
	s_waitcnt lgkmcnt(14)
	v_pk_fma_f32 v[128:129], v[72:73], v[204:205], v[128:129]
	v_pk_fma_f32 v[130:131], v[74:75], v[206:207], v[130:131]
	s_waitcnt lgkmcnt(13)
	v_pk_fma_f32 v[128:129], v[76:77], v[208:209], v[128:129]
	v_pk_fma_f32 v[130:131], v[78:79], v[210:211], v[130:131]
	v_add_f32_e32 v128, v128, v129
	v_add_f32_e32 v130, v130, v131
	v_add_f32_e32 v212, v128, v130
	ds_read_b128 v[80:83], v194 offset:29312
	ds_read_b128 v[84:87], v194 offset:29568
	ds_read_b128 v[88:91], v194 offset:29824
	ds_read_b128 v[92:95], v194 offset:30080
	ds_read_b32 v134, v140 offset:35152
	ds_read_b32 v135, v190 offset:33664
	ds_read_b32 v132, v140 offset:35088
	ds_read_b128 v[64:67], v194 offset:21120
	ds_read_b128 v[68:71], v194 offset:21376
	ds_read_b128 v[72:75], v194 offset:21632
	ds_read_b128 v[76:79], v194 offset:21888
	s_waitcnt lgkmcnt(15)
	v_mul_f32_e32 v155, v156, v157
	v_pk_mul_f32 v[112:113], v[112:113], v[154:155] op_sel:[0,1] op_sel_hi:[1,1]
	v_add_f32_dpp v212, v212, v212 row_ror:8 row_mask:0xf bank_mask:0xf bound_ctrl:1
	v_pk_mul_f32 v[114:115], v[114:115], v[154:155] op_sel:[0,1] op_sel_hi:[1,1]
	v_pk_mul_f32 v[116:117], v[116:117], v[154:155] op_sel:[0,1] op_sel_hi:[1,1]
	v_add_f32_dpp v212, v212, v212 row_ror:4 row_mask:0xf bank_mask:0xf bound_ctrl:1
	v_pk_mul_f32 v[118:119], v[118:119], v[154:155] op_sel:[0,1] op_sel_hi:[1,1]
	v_pk_mul_f32 v[120:121], v[120:121], v[154:155] op_sel:[0,1] op_sel_hi:[1,1]
	v_add_f32_dpp v212, v212, v212 row_ror:2 row_mask:0xf bank_mask:0xf bound_ctrl:1
	v_pk_mul_f32 v[122:123], v[122:123], v[154:155] op_sel:[0,1] op_sel_hi:[1,1]
	v_pk_mul_f32 v[124:125], v[124:125], v[154:155] op_sel:[0,1] op_sel_hi:[1,1]
	v_add_f32_dpp v212, v212, v212 row_ror:1 row_mask:0xf bank_mask:0xf bound_ctrl:1
	v_pk_mul_f32 v[126:127], v[126:127], v[154:155] op_sel:[0,1] op_sel_hi:[1,1]
	v_pk_fma_f32 v[196:197], v[154:155], v[196:197], v[112:113] op_sel_hi:[0,1,1]
	ds_write_b32 v190, v212 offset:34688
	v_pk_fma_f32 v[198:199], v[154:155], v[198:199], v[114:115] op_sel_hi:[0,1,1]
	v_pk_fma_f32 v[200:201], v[154:155], v[200:201], v[116:117] op_sel_hi:[0,1,1]
	v_pk_fma_f32 v[202:203], v[154:155], v[202:203], v[118:119] op_sel_hi:[0,1,1]
	v_pk_fma_f32 v[204:205], v[154:155], v[204:205], v[120:121] op_sel_hi:[0,1,1]
	v_pk_fma_f32 v[206:207], v[154:155], v[206:207], v[122:123] op_sel_hi:[0,1,1]
	v_pk_fma_f32 v[208:209], v[154:155], v[208:209], v[124:125] op_sel_hi:[0,1,1]
	v_pk_fma_f32 v[210:211], v[154:155], v[210:211], v[126:127] op_sel_hi:[0,1,1]
	s_waitcnt lgkmcnt(15)
	v_pk_fma_f32 v[128:129], v[96:97], v[196:197], v[214:215]
	v_pk_fma_f32 v[130:131], v[98:99], v[198:199], v[214:215]
	v_pk_fma_f32 v[128:129], v[100:101], v[200:201], v[128:129]
	v_pk_fma_f32 v[130:131], v[102:103], v[202:203], v[130:131]
	s_waitcnt lgkmcnt(14)
	v_pk_fma_f32 v[128:129], v[104:105], v[204:205], v[128:129]
	v_pk_fma_f32 v[130:131], v[106:107], v[206:207], v[130:131]
	s_waitcnt lgkmcnt(13)
	v_pk_fma_f32 v[128:129], v[108:109], v[208:209], v[128:129]
	v_pk_fma_f32 v[130:131], v[110:111], v[210:211], v[130:131]
	v_add_f32_e32 v128, v128, v129
	v_add_f32_e32 v130, v130, v131
	v_add_f32_e32 v213, v128, v130
	ds_read_b128 v[112:115], v194 offset:30336
	ds_read_b128 v[116:119], v194 offset:30592
	ds_read_b128 v[120:123], v194 offset:30848
	ds_read_b128 v[124:127], v194 offset:31104
	ds_read_b32 v156, v140 offset:35156
	ds_read_b32 v157, v190 offset:33728
	ds_read_b32 v154, v140 offset:35092
	ds_read_b128 v[96:99], v194 offset:22144
	ds_read_b128 v[100:103], v194 offset:22400
	ds_read_b128 v[104:107], v194 offset:22656
	ds_read_b128 v[108:111], v194 offset:22912
	s_waitcnt lgkmcnt(15)
	v_mul_f32_e32 v133, v134, v135
	v_pk_mul_f32 v[80:81], v[80:81], v[132:133] op_sel:[0,1] op_sel_hi:[1,1]
	v_add_f32_dpp v213, v213, v213 row_ror:8 row_mask:0xf bank_mask:0xf bound_ctrl:1
	v_pk_mul_f32 v[82:83], v[82:83], v[132:133] op_sel:[0,1] op_sel_hi:[1,1]
	v_pk_mul_f32 v[84:85], v[84:85], v[132:133] op_sel:[0,1] op_sel_hi:[1,1]
	v_add_f32_dpp v213, v213, v213 row_ror:4 row_mask:0xf bank_mask:0xf bound_ctrl:1
	v_pk_mul_f32 v[86:87], v[86:87], v[132:133] op_sel:[0,1] op_sel_hi:[1,1]
	v_pk_mul_f32 v[88:89], v[88:89], v[132:133] op_sel:[0,1] op_sel_hi:[1,1]
	v_add_f32_dpp v213, v213, v213 row_ror:2 row_mask:0xf bank_mask:0xf bound_ctrl:1
	v_pk_mul_f32 v[90:91], v[90:91], v[132:133] op_sel:[0,1] op_sel_hi:[1,1]
	v_pk_mul_f32 v[92:93], v[92:93], v[132:133] op_sel:[0,1] op_sel_hi:[1,1]
	v_add_f32_dpp v213, v213, v213 row_ror:1 row_mask:0xf bank_mask:0xf bound_ctrl:1
	v_pk_mul_f32 v[94:95], v[94:95], v[132:133] op_sel:[0,1] op_sel_hi:[1,1]
	v_pk_fma_f32 v[196:197], v[132:133], v[196:197], v[80:81] op_sel_hi:[0,1,1]
	ds_write_b32 v190, v213 offset:34752
	v_pk_fma_f32 v[198:199], v[132:133], v[198:199], v[82:83] op_sel_hi:[0,1,1]
	v_pk_fma_f32 v[200:201], v[132:133], v[200:201], v[84:85] op_sel_hi:[0,1,1]
	v_pk_fma_f32 v[202:203], v[132:133], v[202:203], v[86:87] op_sel_hi:[0,1,1]
	v_pk_fma_f32 v[204:205], v[132:133], v[204:205], v[88:89] op_sel_hi:[0,1,1]
	v_pk_fma_f32 v[206:207], v[132:133], v[206:207], v[90:91] op_sel_hi:[0,1,1]
	v_pk_fma_f32 v[208:209], v[132:133], v[208:209], v[92:93] op_sel_hi:[0,1,1]
	v_pk_fma_f32 v[210:211], v[132:133], v[210:211], v[94:95] op_sel_hi:[0,1,1]
	s_waitcnt lgkmcnt(15)
	v_pk_fma_f32 v[128:129], v[64:65], v[196:197], v[214:215]
	v_pk_fma_f32 v[130:131], v[66:67], v[198:199], v[214:215]
	v_pk_fma_f32 v[128:129], v[68:69], v[200:201], v[128:129]
	v_pk_fma_f32 v[130:131], v[70:71], v[202:203], v[130:131]
	s_waitcnt lgkmcnt(14)
	v_pk_fma_f32 v[128:129], v[72:73], v[204:205], v[128:129]
	v_pk_fma_f32 v[130:131], v[74:75], v[206:207], v[130:131]
	s_waitcnt lgkmcnt(13)
	v_pk_fma_f32 v[128:129], v[76:77], v[208:209], v[128:129]
	v_pk_fma_f32 v[130:131], v[78:79], v[210:211], v[130:131]
	v_add_f32_e32 v128, v128, v129
	v_add_f32_e32 v130, v130, v131
	v_add_f32_e32 v212, v128, v130
	ds_read_b128 v[80:83], v194 offset:31360
	ds_read_b128 v[84:87], v194 offset:31616
	ds_read_b128 v[88:91], v194 offset:31872
	ds_read_b128 v[92:95], v194 offset:32128
	ds_read_b32 v134, v140 offset:35160
	ds_read_b32 v135, v190 offset:33792
	ds_read_b32 v132, v140 offset:35096
	ds_read_b128 v[64:67], v194 offset:23168
	ds_read_b128 v[68:71], v194 offset:23424
	ds_read_b128 v[72:75], v194 offset:23680
	ds_read_b128 v[76:79], v194 offset:23936
	s_waitcnt lgkmcnt(15)
	v_mul_f32_e32 v155, v156, v157
	v_pk_mul_f32 v[112:113], v[112:113], v[154:155] op_sel:[0,1] op_sel_hi:[1,1]
	v_add_f32_dpp v212, v212, v212 row_ror:8 row_mask:0xf bank_mask:0xf bound_ctrl:1
	v_pk_mul_f32 v[114:115], v[114:115], v[154:155] op_sel:[0,1] op_sel_hi:[1,1]
	v_pk_mul_f32 v[116:117], v[116:117], v[154:155] op_sel:[0,1] op_sel_hi:[1,1]
	v_add_f32_dpp v212, v212, v212 row_ror:4 row_mask:0xf bank_mask:0xf bound_ctrl:1
	v_pk_mul_f32 v[118:119], v[118:119], v[154:155] op_sel:[0,1] op_sel_hi:[1,1]
	v_pk_mul_f32 v[120:121], v[120:121], v[154:155] op_sel:[0,1] op_sel_hi:[1,1]
	v_add_f32_dpp v212, v212, v212 row_ror:2 row_mask:0xf bank_mask:0xf bound_ctrl:1
	v_pk_mul_f32 v[122:123], v[122:123], v[154:155] op_sel:[0,1] op_sel_hi:[1,1]
	v_pk_mul_f32 v[124:125], v[124:125], v[154:155] op_sel:[0,1] op_sel_hi:[1,1]
	v_add_f32_dpp v212, v212, v212 row_ror:1 row_mask:0xf bank_mask:0xf bound_ctrl:1
	v_pk_mul_f32 v[126:127], v[126:127], v[154:155] op_sel:[0,1] op_sel_hi:[1,1]
	v_pk_fma_f32 v[196:197], v[154:155], v[196:197], v[112:113] op_sel_hi:[0,1,1]
	ds_write_b32 v190, v212 offset:34816
	v_pk_fma_f32 v[198:199], v[154:155], v[198:199], v[114:115] op_sel_hi:[0,1,1]
	v_pk_fma_f32 v[200:201], v[154:155], v[200:201], v[116:117] op_sel_hi:[0,1,1]
	v_pk_fma_f32 v[202:203], v[154:155], v[202:203], v[118:119] op_sel_hi:[0,1,1]
	v_pk_fma_f32 v[204:205], v[154:155], v[204:205], v[120:121] op_sel_hi:[0,1,1]
	v_pk_fma_f32 v[206:207], v[154:155], v[206:207], v[122:123] op_sel_hi:[0,1,1]
	v_pk_fma_f32 v[208:209], v[154:155], v[208:209], v[124:125] op_sel_hi:[0,1,1]
	v_pk_fma_f32 v[210:211], v[154:155], v[210:211], v[126:127] op_sel_hi:[0,1,1]
	s_waitcnt lgkmcnt(15)
	v_pk_fma_f32 v[128:129], v[96:97], v[196:197], v[214:215]
	v_pk_fma_f32 v[130:131], v[98:99], v[198:199], v[214:215]
	v_pk_fma_f32 v[128:129], v[100:101], v[200:201], v[128:129]
	v_pk_fma_f32 v[130:131], v[102:103], v[202:203], v[130:131]
	s_waitcnt lgkmcnt(14)
	v_pk_fma_f32 v[128:129], v[104:105], v[204:205], v[128:129]
	v_pk_fma_f32 v[130:131], v[106:107], v[206:207], v[130:131]
	s_waitcnt lgkmcnt(13)
	v_pk_fma_f32 v[128:129], v[108:109], v[208:209], v[128:129]
	v_pk_fma_f32 v[130:131], v[110:111], v[210:211], v[130:131]
	v_add_f32_e32 v128, v128, v129
	v_add_f32_e32 v130, v130, v131
	v_add_f32_e32 v213, v128, v130
	ds_read_b128 v[112:115], v194 offset:32384
	ds_read_b128 v[116:119], v194 offset:32640
	ds_read_b128 v[120:123], v194 offset:32896
	ds_read_b128 v[124:127], v194 offset:33152
	ds_read_b32 v156, v140 offset:35164
	ds_read_b32 v157, v190 offset:33856
	ds_read_b32 v154, v140 offset:35100
	ds_read_b128 v[96:99], v194 offset:24192
	ds_read_b128 v[100:103], v194 offset:24448
	ds_read_b128 v[104:107], v194 offset:24704
	ds_read_b128 v[108:111], v194 offset:24960
	s_waitcnt lgkmcnt(15)
	v_mul_f32_e32 v133, v134, v135
	v_pk_mul_f32 v[80:81], v[80:81], v[132:133] op_sel:[0,1] op_sel_hi:[1,1]
	v_add_f32_dpp v213, v213, v213 row_ror:8 row_mask:0xf bank_mask:0xf bound_ctrl:1
	v_pk_mul_f32 v[82:83], v[82:83], v[132:133] op_sel:[0,1] op_sel_hi:[1,1]
	v_pk_mul_f32 v[84:85], v[84:85], v[132:133] op_sel:[0,1] op_sel_hi:[1,1]
	v_add_f32_dpp v213, v213, v213 row_ror:4 row_mask:0xf bank_mask:0xf bound_ctrl:1
	v_pk_mul_f32 v[86:87], v[86:87], v[132:133] op_sel:[0,1] op_sel_hi:[1,1]
	v_pk_mul_f32 v[88:89], v[88:89], v[132:133] op_sel:[0,1] op_sel_hi:[1,1]
	v_add_f32_dpp v213, v213, v213 row_ror:2 row_mask:0xf bank_mask:0xf bound_ctrl:1
	v_pk_mul_f32 v[90:91], v[90:91], v[132:133] op_sel:[0,1] op_sel_hi:[1,1]
	v_pk_mul_f32 v[92:93], v[92:93], v[132:133] op_sel:[0,1] op_sel_hi:[1,1]
	v_add_f32_dpp v213, v213, v213 row_ror:1 row_mask:0xf bank_mask:0xf bound_ctrl:1
	v_pk_mul_f32 v[94:95], v[94:95], v[132:133] op_sel:[0,1] op_sel_hi:[1,1]
	v_pk_fma_f32 v[196:197], v[132:133], v[196:197], v[80:81] op_sel_hi:[0,1,1]
	ds_write_b32 v190, v213 offset:34880
	v_pk_fma_f32 v[198:199], v[132:133], v[198:199], v[82:83] op_sel_hi:[0,1,1]
	v_pk_fma_f32 v[200:201], v[132:133], v[200:201], v[84:85] op_sel_hi:[0,1,1]
	v_pk_fma_f32 v[202:203], v[132:133], v[202:203], v[86:87] op_sel_hi:[0,1,1]
	v_pk_fma_f32 v[204:205], v[132:133], v[204:205], v[88:89] op_sel_hi:[0,1,1]
	v_pk_fma_f32 v[206:207], v[132:133], v[206:207], v[90:91] op_sel_hi:[0,1,1]
	v_pk_fma_f32 v[208:209], v[132:133], v[208:209], v[92:93] op_sel_hi:[0,1,1]
	v_pk_fma_f32 v[210:211], v[132:133], v[210:211], v[94:95] op_sel_hi:[0,1,1]
	s_waitcnt lgkmcnt(15)
	v_pk_fma_f32 v[128:129], v[64:65], v[196:197], v[214:215]
	v_pk_fma_f32 v[130:131], v[66:67], v[198:199], v[214:215]
	v_pk_fma_f32 v[128:129], v[68:69], v[200:201], v[128:129]
	v_pk_fma_f32 v[130:131], v[70:71], v[202:203], v[130:131]
	s_waitcnt lgkmcnt(14)
	v_pk_fma_f32 v[128:129], v[72:73], v[204:205], v[128:129]
	v_pk_fma_f32 v[130:131], v[74:75], v[206:207], v[130:131]
	s_waitcnt lgkmcnt(13)
	v_pk_fma_f32 v[128:129], v[76:77], v[208:209], v[128:129]
	v_pk_fma_f32 v[130:131], v[78:79], v[210:211], v[130:131]
	v_add_f32_e32 v128, v128, v129
	v_add_f32_e32 v130, v130, v131
	v_add_f32_e32 v212, v128, v130
	s_waitcnt lgkmcnt(6)
	v_mul_f32_e32 v155, v156, v157
	v_pk_mul_f32 v[112:113], v[112:113], v[154:155] op_sel:[0,1] op_sel_hi:[1,1]
	v_add_f32_dpp v212, v212, v212 row_ror:8 row_mask:0xf bank_mask:0xf bound_ctrl:1
	v_pk_mul_f32 v[114:115], v[114:115], v[154:155] op_sel:[0,1] op_sel_hi:[1,1]
	v_pk_mul_f32 v[116:117], v[116:117], v[154:155] op_sel:[0,1] op_sel_hi:[1,1]
	v_add_f32_dpp v212, v212, v212 row_ror:4 row_mask:0xf bank_mask:0xf bound_ctrl:1
	v_pk_mul_f32 v[118:119], v[118:119], v[154:155] op_sel:[0,1] op_sel_hi:[1,1]
	v_pk_mul_f32 v[120:121], v[120:121], v[154:155] op_sel:[0,1] op_sel_hi:[1,1]
	v_add_f32_dpp v212, v212, v212 row_ror:2 row_mask:0xf bank_mask:0xf bound_ctrl:1
	v_pk_mul_f32 v[122:123], v[122:123], v[154:155] op_sel:[0,1] op_sel_hi:[1,1]
	v_pk_mul_f32 v[124:125], v[124:125], v[154:155] op_sel:[0,1] op_sel_hi:[1,1]
	v_add_f32_dpp v212, v212, v212 row_ror:1 row_mask:0xf bank_mask:0xf bound_ctrl:1
	v_pk_mul_f32 v[126:127], v[126:127], v[154:155] op_sel:[0,1] op_sel_hi:[1,1]
	s_waitcnt lgkmcnt(5)
	v_pk_fma_f32 v[196:197], v[154:155], v[196:197], v[112:113] op_sel_hi:[0,1,1]
	ds_write_b32 v190, v212 offset:34944
	v_pk_fma_f32 v[198:199], v[154:155], v[198:199], v[114:115] op_sel_hi:[0,1,1]
	v_pk_fma_f32 v[200:201], v[154:155], v[200:201], v[116:117] op_sel_hi:[0,1,1]
	v_pk_fma_f32 v[202:203], v[154:155], v[202:203], v[118:119] op_sel_hi:[0,1,1]
	v_pk_fma_f32 v[204:205], v[154:155], v[204:205], v[120:121] op_sel_hi:[0,1,1]
	v_pk_fma_f32 v[206:207], v[154:155], v[206:207], v[122:123] op_sel_hi:[0,1,1]
	v_pk_fma_f32 v[208:209], v[154:155], v[208:209], v[124:125] op_sel_hi:[0,1,1]
	v_pk_fma_f32 v[210:211], v[154:155], v[210:211], v[126:127] op_sel_hi:[0,1,1]
	s_waitcnt lgkmcnt(5)
	v_pk_fma_f32 v[128:129], v[96:97], v[196:197], v[214:215]
	v_pk_fma_f32 v[130:131], v[98:99], v[198:199], v[214:215]
	s_waitcnt lgkmcnt(4)
	v_pk_fma_f32 v[128:129], v[100:101], v[200:201], v[128:129]
	v_pk_fma_f32 v[130:131], v[102:103], v[202:203], v[130:131]
	s_waitcnt lgkmcnt(3)
	v_pk_fma_f32 v[128:129], v[104:105], v[204:205], v[128:129]
	v_pk_fma_f32 v[130:131], v[106:107], v[206:207], v[130:131]
	s_waitcnt lgkmcnt(2)
	v_pk_fma_f32 v[128:129], v[108:109], v[208:209], v[128:129]
	v_pk_fma_f32 v[130:131], v[110:111], v[210:211], v[130:131]
	v_add_f32_e32 v128, v128, v129
	v_add_f32_e32 v130, v130, v131
	v_add_f32_e32 v213, v128, v130
	s_nop 1
	v_add_f32_dpp v213, v213, v213 row_ror:8 row_mask:0xf bank_mask:0xf bound_ctrl:1
	s_nop 1
	v_add_f32_dpp v213, v213, v213 row_ror:4 row_mask:0xf bank_mask:0xf bound_ctrl:1
	s_nop 1
	v_add_f32_dpp v213, v213, v213 row_ror:2 row_mask:0xf bank_mask:0xf bound_ctrl:1
	s_nop 1
	v_add_f32_dpp v213, v213, v213 row_ror:1 row_mask:0xf bank_mask:0xf bound_ctrl:1
	ds_write_b32 v190, v213 offset:35008
	s_waitcnt lgkmcnt(0)
	v_mov_b32_e32 v88, v196
	v_mov_b32_e32 v89, v197
	v_mov_b32_e32 v90, v198
	v_mov_b32_e32 v100, v199
	v_mov_b32_e32 v91, v200
	v_mov_b32_e32 v101, v201
	v_mov_b32_e32 v102, v202
	v_mov_b32_e32 v104, v203
	v_mov_b32_e32 v103, v204
	v_mov_b32_e32 v105, v205
	v_mov_b32_e32 v106, v206
	v_mov_b32_e32 v109, v207
	v_mov_b32_e32 v107, v208
	v_mov_b32_e32 v110, v209
	v_mov_b32_e32 v108, v210
	v_mov_b32_e32 v111, v211
	s_branch .LBB0_1138

.LBB0_1289:
	v_mov_b32_e32 v178, v118
	v_mov_b32_e32 v179, v119
	v_mov_b32_e32 v180, v88
	v_mov_b32_e32 v181, v89
	v_mov_b32_e32 v182, v90
	v_mov_b32_e32 v183, v80
	v_mov_b32_e32 v184, v81
	v_mov_b32_e32 v185, v82
	v_mov_b32_e32 v186, v146
	v_mov_b32_e32 v187, v120
	v_mov_b32_e32 v188, v121
	v_mov_b32_e32 v189, v91
	v_mov_b32_e32 v190, v147
	v_mov_b32_e32 v191, v148
	v_mov_b32_e32 v192, v149
	v_mov_b32_e32 v193, v83
	v_mov_b32_e32 v196, 0
	v_mov_b32_e32 v197, 0
	v_add_u32_e32 v194, 0x4000, v103
	v_add_u32_e32 v195, 0x4400, v103
	ds_read2_b32 v[118:119], v194 offset0:0 offset1:16
	ds_read_b128 v[72:75], v145 offset:8192
	ds_read_b128 v[76:79], v145 offset:8448
	ds_read_b128 v[64:67], v145
	ds_read_b128 v[68:71], v145 offset:256
	ds_read2_b32 v[120:121], v194 offset0:32 offset1:48
	ds_read_b128 v[88:91], v145 offset:8704
	ds_read_b128 v[92:95], v145 offset:8960
	ds_read_b128 v[80:83], v145 offset:512
	ds_read_b128 v[84:87], v145 offset:768
	s_waitcnt lgkmcnt(9)
	v_pk_add_f32 v[178:179], v[178:179], v[118:119] op_sel_hi:[1,0] neg_lo:[0,1] neg_hi:[0,1]
	v_pk_add_f32 v[186:187], v[186:187], v[118:119] op_sel:[0,1] op_sel_hi:[1,1] neg_lo:[0,1] neg_hi:[0,1]
	v_pk_add_f32 v[180:181], v[180:181], v[118:119] op_sel_hi:[1,0] neg_lo:[0,1] neg_hi:[0,1]
	v_pk_add_f32 v[188:189], v[188:189], v[118:119] op_sel:[0,1] op_sel_hi:[1,1] neg_lo:[0,1] neg_hi:[0,1]
	v_pk_add_f32 v[182:183], v[182:183], v[118:119] op_sel_hi:[1,0] neg_lo:[0,1] neg_hi:[0,1]
	v_pk_add_f32 v[190:191], v[190:191], v[118:119] op_sel:[0,1] op_sel_hi:[1,1] neg_lo:[0,1] neg_hi:[0,1]
	v_pk_add_f32 v[184:185], v[184:185], v[118:119] op_sel_hi:[1,0] neg_lo:[0,1] neg_hi:[0,1]
	v_pk_add_f32 v[192:193], v[192:193], v[118:119] op_sel:[0,1] op_sel_hi:[1,1] neg_lo:[0,1] neg_hi:[0,1]
	s_waitcnt lgkmcnt(8)
	v_pk_fma_f32 v[178:179], v[72:73], v[178:179], v[118:119] op_sel_hi:[1,1,0]
	v_pk_fma_f32 v[186:187], v[72:73], v[186:187], v[118:119] op_sel:[0,0,1] op_sel_hi:[1,1,1]
	v_pk_fma_f32 v[180:181], v[74:75], v[180:181], v[118:119] op_sel_hi:[1,1,0]
	v_pk_fma_f32 v[188:189], v[74:75], v[188:189], v[118:119] op_sel:[0,0,1] op_sel_hi:[1,1,1]
	s_waitcnt lgkmcnt(7)
	v_pk_fma_f32 v[182:183], v[76:77], v[182:183], v[118:119] op_sel_hi:[1,1,0]
	v_pk_fma_f32 v[190:191], v[76:77], v[190:191], v[118:119] op_sel:[0,0,1] op_sel_hi:[1,1,1]
	v_pk_fma_f32 v[184:185], v[78:79], v[184:185], v[118:119] op_sel_hi:[1,1,0]
	v_pk_fma_f32 v[192:193], v[78:79], v[192:193], v[118:119] op_sel:[0,0,1] op_sel_hi:[1,1,1]
	s_waitcnt lgkmcnt(6)
	v_pk_fma_f32 v[146:147], v[64:65], v[178:179], v[196:197]
	v_pk_fma_f32 v[150:151], v[64:65], v[186:187], v[196:197]
	v_pk_fma_f32 v[148:149], v[66:67], v[180:181], v[196:197]
	v_pk_fma_f32 v[152:153], v[66:67], v[188:189], v[196:197]
	s_waitcnt lgkmcnt(5)
	v_pk_fma_f32 v[146:147], v[68:69], v[182:183], v[146:147]
	v_pk_fma_f32 v[150:151], v[68:69], v[190:191], v[150:151]
	v_pk_fma_f32 v[148:149], v[70:71], v[184:185], v[148:149]
	v_pk_fma_f32 v[152:153], v[70:71], v[192:193], v[152:153]
	v_add_f32_e32 v146, v146, v147
	v_add_f32_e32 v148, v148, v149
	v_add_f32_e32 v150, v150, v151
	v_add_f32_e32 v152, v152, v153
	v_add_f32_e32 v154, v146, v148
	v_add_f32_e32 v155, v150, v152
	ds_read2_b32 v[118:119], v194 offset0:64 offset1:80
	ds_read_b128 v[72:75], v145 offset:9216
	ds_read_b128 v[76:79], v145 offset:9472
	ds_read_b128 v[64:67], v145 offset:1024
	ds_read_b128 v[68:71], v145 offset:1280
	s_waitcnt lgkmcnt(9)
	v_pk_add_f32 v[178:179], v[178:179], v[120:121] op_sel_hi:[1,0] neg_lo:[0,1] neg_hi:[0,1]
	v_add_f32_dpp v154, v154, v154 row_ror:8 row_mask:0xf bank_mask:0xf bound_ctrl:1
	v_pk_add_f32 v[186:187], v[186:187], v[120:121] op_sel:[0,1] op_sel_hi:[1,1] neg_lo:[0,1] neg_hi:[0,1]
	v_add_f32_dpp v155, v155, v155 row_ror:8 row_mask:0xf bank_mask:0xf bound_ctrl:1
	v_pk_add_f32 v[180:181], v[180:181], v[120:121] op_sel_hi:[1,0] neg_lo:[0,1] neg_hi:[0,1]
	v_add_f32_dpp v154, v154, v154 row_ror:4 row_mask:0xf bank_mask:0xf bound_ctrl:1
	v_pk_add_f32 v[188:189], v[188:189], v[120:121] op_sel:[0,1] op_sel_hi:[1,1] neg_lo:[0,1] neg_hi:[0,1]
	v_add_f32_dpp v155, v155, v155 row_ror:4 row_mask:0xf bank_mask:0xf bound_ctrl:1
	v_pk_add_f32 v[182:183], v[182:183], v[120:121] op_sel_hi:[1,0] neg_lo:[0,1] neg_hi:[0,1]
	v_add_f32_dpp v154, v154, v154 row_ror:2 row_mask:0xf bank_mask:0xf bound_ctrl:1
	v_pk_add_f32 v[190:191], v[190:191], v[120:121] op_sel:[0,1] op_sel_hi:[1,1] neg_lo:[0,1] neg_hi:[0,1]
	v_add_f32_dpp v155, v155, v155 row_ror:2 row_mask:0xf bank_mask:0xf bound_ctrl:1
	v_pk_add_f32 v[184:185], v[184:185], v[120:121] op_sel_hi:[1,0] neg_lo:[0,1] neg_hi:[0,1]
	v_add_f32_dpp v154, v154, v154 row_ror:1 row_mask:0xf bank_mask:0xf bound_ctrl:1
	v_pk_add_f32 v[192:193], v[192:193], v[120:121] op_sel:[0,1] op_sel_hi:[1,1] neg_lo:[0,1] neg_hi:[0,1]
	v_add_f32_dpp v155, v155, v155 row_ror:1 row_mask:0xf bank_mask:0xf bound_ctrl:1
	s_waitcnt lgkmcnt(8)
	v_pk_fma_f32 v[178:179], v[88:89], v[178:179], v[120:121] op_sel_hi:[1,1,0]
	ds_write_b32 v103, v154 offset:36864
	v_pk_fma_f32 v[186:187], v[88:89], v[186:187], v[120:121] op_sel:[0,0,1] op_sel_hi:[1,1,1]
	ds_write_b32 v103, v155 offset:36928
	v_pk_fma_f32 v[180:181], v[90:91], v[180:181], v[120:121] op_sel_hi:[1,1,0]
	v_pk_fma_f32 v[188:189], v[90:91], v[188:189], v[120:121] op_sel:[0,0,1] op_sel_hi:[1,1,1]
	s_waitcnt lgkmcnt(9)
	v_pk_fma_f32 v[182:183], v[92:93], v[182:183], v[120:121] op_sel_hi:[1,1,0]
	v_pk_fma_f32 v[190:191], v[92:93], v[190:191], v[120:121] op_sel:[0,0,1] op_sel_hi:[1,1,1]
	v_pk_fma_f32 v[184:185], v[94:95], v[184:185], v[120:121] op_sel_hi:[1,1,0]
	v_pk_fma_f32 v[192:193], v[94:95], v[192:193], v[120:121] op_sel:[0,0,1] op_sel_hi:[1,1,1]
	s_waitcnt lgkmcnt(8)
	v_pk_fma_f32 v[146:147], v[80:81], v[178:179], v[196:197]
	v_pk_fma_f32 v[150:151], v[80:81], v[186:187], v[196:197]
	v_pk_fma_f32 v[148:149], v[82:83], v[180:181], v[196:197]
	v_pk_fma_f32 v[152:153], v[82:83], v[188:189], v[196:197]
	s_waitcnt lgkmcnt(7)
	v_pk_fma_f32 v[146:147], v[84:85], v[182:183], v[146:147]
	v_pk_fma_f32 v[150:151], v[84:85], v[190:191], v[150:151]
	v_pk_fma_f32 v[148:149], v[86:87], v[184:185], v[148:149]
	v_pk_fma_f32 v[152:153], v[86:87], v[192:193], v[152:153]
	v_add_f32_e32 v146, v146, v147
	v_add_f32_e32 v148, v148, v149
	v_add_f32_e32 v150, v150, v151
	v_add_f32_e32 v152, v152, v153
	v_add_f32_e32 v156, v146, v148
	v_add_f32_e32 v157, v150, v152
	ds_read2_b32 v[120:121], v194 offset0:96 offset1:112
	ds_read_b128 v[88:91], v145 offset:9728
	ds_read_b128 v[92:95], v145 offset:9984
	ds_read_b128 v[80:83], v145 offset:1536
	ds_read_b128 v[84:87], v145 offset:1792
	s_waitcnt lgkmcnt(11)
	v_pk_add_f32 v[178:179], v[178:179], v[118:119] op_sel_hi:[1,0] neg_lo:[0,1] neg_hi:[0,1]
	v_add_f32_dpp v156, v156, v156 row_ror:8 row_mask:0xf bank_mask:0xf bound_ctrl:1
	v_pk_add_f32 v[186:187], v[186:187], v[118:119] op_sel:[0,1] op_sel_hi:[1,1] neg_lo:[0,1] neg_hi:[0,1]
	v_add_f32_dpp v157, v157, v157 row_ror:8 row_mask:0xf bank_mask:0xf bound_ctrl:1
	v_pk_add_f32 v[180:181], v[180:181], v[118:119] op_sel_hi:[1,0] neg_lo:[0,1] neg_hi:[0,1]
	v_add_f32_dpp v156, v156, v156 row_ror:4 row_mask:0xf bank_mask:0xf bound_ctrl:1
	v_pk_add_f32 v[188:189], v[188:189], v[118:119] op_sel:[0,1] op_sel_hi:[1,1] neg_lo:[0,1] neg_hi:[0,1]
	v_add_f32_dpp v157, v157, v157 row_ror:4 row_mask:0xf bank_mask:0xf bound_ctrl:1
	v_pk_add_f32 v[182:183], v[182:183], v[118:119] op_sel_hi:[1,0] neg_lo:[0,1] neg_hi:[0,1]
	v_add_f32_dpp v156, v156, v156 row_ror:2 row_mask:0xf bank_mask:0xf bound_ctrl:1
	v_pk_add_f32 v[190:191], v[190:191], v[118:119] op_sel:[0,1] op_sel_hi:[1,1] neg_lo:[0,1] neg_hi:[0,1]
	v_add_f32_dpp v157, v157, v157 row_ror:2 row_mask:0xf bank_mask:0xf bound_ctrl:1
	v_pk_add_f32 v[184:185], v[184:185], v[118:119] op_sel_hi:[1,0] neg_lo:[0,1] neg_hi:[0,1]
	v_add_f32_dpp v156, v156, v156 row_ror:1 row_mask:0xf bank_mask:0xf bound_ctrl:1
	v_pk_add_f32 v[192:193], v[192:193], v[118:119] op_sel:[0,1] op_sel_hi:[1,1] neg_lo:[0,1] neg_hi:[0,1]
	v_add_f32_dpp v157, v157, v157 row_ror:1 row_mask:0xf bank_mask:0xf bound_ctrl:1
	s_waitcnt lgkmcnt(10)
	v_pk_fma_f32 v[178:179], v[72:73], v[178:179], v[118:119] op_sel_hi:[1,1,0]
	ds_write_b32 v103, v156 offset:36992
	v_pk_fma_f32 v[186:187], v[72:73], v[186:187], v[118:119] op_sel:[0,0,1] op_sel_hi:[1,1,1]
	ds_write_b32 v103, v157 offset:37056
	v_pk_fma_f32 v[180:181], v[74:75], v[180:181], v[118:119] op_sel_hi:[1,1,0]
	v_pk_fma_f32 v[188:189], v[74:75], v[188:189], v[118:119] op_sel:[0,0,1] op_sel_hi:[1,1,1]
	s_waitcnt lgkmcnt(11)
	v_pk_fma_f32 v[182:183], v[76:77], v[182:183], v[118:119] op_sel_hi:[1,1,0]
	v_pk_fma_f32 v[190:191], v[76:77], v[190:191], v[118:119] op_sel:[0,0,1] op_sel_hi:[1,1,1]
	v_pk_fma_f32 v[184:185], v[78:79], v[184:185], v[118:119] op_sel_hi:[1,1,0]
	v_pk_fma_f32 v[192:193], v[78:79], v[192:193], v[118:119] op_sel:[0,0,1] op_sel_hi:[1,1,1]
	s_waitcnt lgkmcnt(10)
	v_pk_fma_f32 v[146:147], v[64:65], v[178:179], v[196:197]
	v_pk_fma_f32 v[150:151], v[64:65], v[186:187], v[196:197]
	v_pk_fma_f32 v[148:149], v[66:67], v[180:181], v[196:197]
	v_pk_fma_f32 v[152:153], v[66:67], v[188:189], v[196:197]
	s_waitcnt lgkmcnt(9)
	v_pk_fma_f32 v[146:147], v[68:69], v[182:183], v[146:147]
	v_pk_fma_f32 v[150:151], v[68:69], v[190:191], v[150:151]
	v_pk_fma_f32 v[148:149], v[70:71], v[184:185], v[148:149]
	v_pk_fma_f32 v[152:153], v[70:71], v[192:193], v[152:153]
	v_add_f32_e32 v146, v146, v147
	v_add_f32_e32 v148, v148, v149
	v_add_f32_e32 v150, v150, v151
	v_add_f32_e32 v152, v152, v153
	v_add_f32_e32 v154, v146, v148
	v_add_f32_e32 v155, v150, v152
	ds_read2_b32 v[118:119], v194 offset0:128 offset1:144
	ds_read_b128 v[72:75], v145 offset:10240
	ds_read_b128 v[76:79], v145 offset:10496
	ds_read_b128 v[64:67], v145 offset:2048
	ds_read_b128 v[68:71], v145 offset:2304
	s_waitcnt lgkmcnt(11)
	v_pk_add_f32 v[178:179], v[178:179], v[120:121] op_sel_hi:[1,0] neg_lo:[0,1] neg_hi:[0,1]
	v_add_f32_dpp v154, v154, v154 row_ror:8 row_mask:0xf bank_mask:0xf bound_ctrl:1
	v_pk_add_f32 v[186:187], v[186:187], v[120:121] op_sel:[0,1] op_sel_hi:[1,1] neg_lo:[0,1] neg_hi:[0,1]
	v_add_f32_dpp v155, v155, v155 row_ror:8 row_mask:0xf bank_mask:0xf bound_ctrl:1
	v_pk_add_f32 v[180:181], v[180:181], v[120:121] op_sel_hi:[1,0] neg_lo:[0,1] neg_hi:[0,1]
	v_add_f32_dpp v154, v154, v154 row_ror:4 row_mask:0xf bank_mask:0xf bound_ctrl:1
	v_pk_add_f32 v[188:189], v[188:189], v[120:121] op_sel:[0,1] op_sel_hi:[1,1] neg_lo:[0,1] neg_hi:[0,1]
	v_add_f32_dpp v155, v155, v155 row_ror:4 row_mask:0xf bank_mask:0xf bound_ctrl:1
	v_pk_add_f32 v[182:183], v[182:183], v[120:121] op_sel_hi:[1,0] neg_lo:[0,1] neg_hi:[0,1]
	v_add_f32_dpp v154, v154, v154 row_ror:2 row_mask:0xf bank_mask:0xf bound_ctrl:1
	v_pk_add_f32 v[190:191], v[190:191], v[120:121] op_sel:[0,1] op_sel_hi:[1,1] neg_lo:[0,1] neg_hi:[0,1]
	v_add_f32_dpp v155, v155, v155 row_ror:2 row_mask:0xf bank_mask:0xf bound_ctrl:1
	v_pk_add_f32 v[184:185], v[184:185], v[120:121] op_sel_hi:[1,0] neg_lo:[0,1] neg_hi:[0,1]
	v_add_f32_dpp v154, v154, v154 row_ror:1 row_mask:0xf bank_mask:0xf bound_ctrl:1
	v_pk_add_f32 v[192:193], v[192:193], v[120:121] op_sel:[0,1] op_sel_hi:[1,1] neg_lo:[0,1] neg_hi:[0,1]
	v_add_f32_dpp v155, v155, v155 row_ror:1 row_mask:0xf bank_mask:0xf bound_ctrl:1
	s_waitcnt lgkmcnt(10)
	v_pk_fma_f32 v[178:179], v[88:89], v[178:179], v[120:121] op_sel_hi:[1,1,0]
	ds_write_b32 v103, v154 offset:37120
	v_pk_fma_f32 v[186:187], v[88:89], v[186:187], v[120:121] op_sel:[0,0,1] op_sel_hi:[1,1,1]
	ds_write_b32 v103, v155 offset:37184
	v_pk_fma_f32 v[180:181], v[90:91], v[180:181], v[120:121] op_sel_hi:[1,1,0]
	v_pk_fma_f32 v[188:189], v[90:91], v[188:189], v[120:121] op_sel:[0,0,1] op_sel_hi:[1,1,1]
	s_waitcnt lgkmcnt(11)
	v_pk_fma_f32 v[182:183], v[92:93], v[182:183], v[120:121] op_sel_hi:[1,1,0]
	v_pk_fma_f32 v[190:191], v[92:93], v[190:191], v[120:121] op_sel:[0,0,1] op_sel_hi:[1,1,1]
	v_pk_fma_f32 v[184:185], v[94:95], v[184:185], v[120:121] op_sel_hi:[1,1,0]
	v_pk_fma_f32 v[192:193], v[94:95], v[192:193], v[120:121] op_sel:[0,0,1] op_sel_hi:[1,1,1]
	s_waitcnt lgkmcnt(10)
	v_pk_fma_f32 v[146:147], v[80:81], v[178:179], v[196:197]
	v_pk_fma_f32 v[150:151], v[80:81], v[186:187], v[196:197]
	v_pk_fma_f32 v[148:149], v[82:83], v[180:181], v[196:197]
	v_pk_fma_f32 v[152:153], v[82:83], v[188:189], v[196:197]
	s_waitcnt lgkmcnt(9)
	v_pk_fma_f32 v[146:147], v[84:85], v[182:183], v[146:147]
	v_pk_fma_f32 v[150:151], v[84:85], v[190:191], v[150:151]
	v_pk_fma_f32 v[148:149], v[86:87], v[184:185], v[148:149]
	v_pk_fma_f32 v[152:153], v[86:87], v[192:193], v[152:153]
	v_add_f32_e32 v146, v146, v147
	v_add_f32_e32 v148, v148, v149
	v_add_f32_e32 v150, v150, v151
	v_add_f32_e32 v152, v152, v153
	v_add_f32_e32 v156, v146, v148
	v_add_f32_e32 v157, v150, v152
	ds_read2_b32 v[120:121], v194 offset0:160 offset1:176
	ds_read_b128 v[88:91], v145 offset:10752
	ds_read_b128 v[92:95], v145 offset:11008
	ds_read_b128 v[80:83], v145 offset:2560
	ds_read_b128 v[84:87], v145 offset:2816
	s_waitcnt lgkmcnt(11)
	v_pk_add_f32 v[178:179], v[178:179], v[118:119] op_sel_hi:[1,0] neg_lo:[0,1] neg_hi:[0,1]
	v_add_f32_dpp v156, v156, v156 row_ror:8 row_mask:0xf bank_mask:0xf bound_ctrl:1
	v_pk_add_f32 v[186:187], v[186:187], v[118:119] op_sel:[0,1] op_sel_hi:[1,1] neg_lo:[0,1] neg_hi:[0,1]
	v_add_f32_dpp v157, v157, v157 row_ror:8 row_mask:0xf bank_mask:0xf bound_ctrl:1
	v_pk_add_f32 v[180:181], v[180:181], v[118:119] op_sel_hi:[1,0] neg_lo:[0,1] neg_hi:[0,1]
	v_add_f32_dpp v156, v156, v156 row_ror:4 row_mask:0xf bank_mask:0xf bound_ctrl:1
	v_pk_add_f32 v[188:189], v[188:189], v[118:119] op_sel:[0,1] op_sel_hi:[1,1] neg_lo:[0,1] neg_hi:[0,1]
	v_add_f32_dpp v157, v157, v157 row_ror:4 row_mask:0xf bank_mask:0xf bound_ctrl:1
	v_pk_add_f32 v[182:183], v[182:183], v[118:119] op_sel_hi:[1,0] neg_lo:[0,1] neg_hi:[0,1]
	v_add_f32_dpp v156, v156, v156 row_ror:2 row_mask:0xf bank_mask:0xf bound_ctrl:1
	v_pk_add_f32 v[190:191], v[190:191], v[118:119] op_sel:[0,1] op_sel_hi:[1,1] neg_lo:[0,1] neg_hi:[0,1]
	v_add_f32_dpp v157, v157, v157 row_ror:2 row_mask:0xf bank_mask:0xf bound_ctrl:1
	v_pk_add_f32 v[184:185], v[184:185], v[118:119] op_sel_hi:[1,0] neg_lo:[0,1] neg_hi:[0,1]
	v_add_f32_dpp v156, v156, v156 row_ror:1 row_mask:0xf bank_mask:0xf bound_ctrl:1
	v_pk_add_f32 v[192:193], v[192:193], v[118:119] op_sel:[0,1] op_sel_hi:[1,1] neg_lo:[0,1] neg_hi:[0,1]
	v_add_f32_dpp v157, v157, v157 row_ror:1 row_mask:0xf bank_mask:0xf bound_ctrl:1
	s_waitcnt lgkmcnt(10)
	v_pk_fma_f32 v[178:179], v[72:73], v[178:179], v[118:119] op_sel_hi:[1,1,0]
	ds_write_b32 v103, v156 offset:37248
	v_pk_fma_f32 v[186:187], v[72:73], v[186:187], v[118:119] op_sel:[0,0,1] op_sel_hi:[1,1,1]
	ds_write_b32 v103, v157 offset:37312
	v_pk_fma_f32 v[180:181], v[74:75], v[180:181], v[118:119] op_sel_hi:[1,1,0]
	v_pk_fma_f32 v[188:189], v[74:75], v[188:189], v[118:119] op_sel:[0,0,1] op_sel_hi:[1,1,1]
	s_waitcnt lgkmcnt(11)
	v_pk_fma_f32 v[182:183], v[76:77], v[182:183], v[118:119] op_sel_hi:[1,1,0]
	v_pk_fma_f32 v[190:191], v[76:77], v[190:191], v[118:119] op_sel:[0,0,1] op_sel_hi:[1,1,1]
	v_pk_fma_f32 v[184:185], v[78:79], v[184:185], v[118:119] op_sel_hi:[1,1,0]
	v_pk_fma_f32 v[192:193], v[78:79], v[192:193], v[118:119] op_sel:[0,0,1] op_sel_hi:[1,1,1]
	s_waitcnt lgkmcnt(10)
	v_pk_fma_f32 v[146:147], v[64:65], v[178:179], v[196:197]
	v_pk_fma_f32 v[150:151], v[64:65], v[186:187], v[196:197]
	v_pk_fma_f32 v[148:149], v[66:67], v[180:181], v[196:197]
	v_pk_fma_f32 v[152:153], v[66:67], v[188:189], v[196:197]
	s_waitcnt lgkmcnt(9)
	v_pk_fma_f32 v[146:147], v[68:69], v[182:183], v[146:147]
	v_pk_fma_f32 v[150:151], v[68:69], v[190:191], v[150:151]
	v_pk_fma_f32 v[148:149], v[70:71], v[184:185], v[148:149]
	v_pk_fma_f32 v[152:153], v[70:71], v[192:193], v[152:153]
	v_add_f32_e32 v146, v146, v147
	v_add_f32_e32 v148, v148, v149
	v_add_f32_e32 v150, v150, v151
	v_add_f32_e32 v152, v152, v153
	v_add_f32_e32 v154, v146, v148
	v_add_f32_e32 v155, v150, v152
	ds_read2_b32 v[118:119], v194 offset0:192 offset1:208
	ds_read_b128 v[72:75], v145 offset:11264
	ds_read_b128 v[76:79], v145 offset:11520
	ds_read_b128 v[64:67], v145 offset:3072
	ds_read_b128 v[68:71], v145 offset:3328
	s_waitcnt lgkmcnt(11)
	v_pk_add_f32 v[178:179], v[178:179], v[120:121] op_sel_hi:[1,0] neg_lo:[0,1] neg_hi:[0,1]
	v_add_f32_dpp v154, v154, v154 row_ror:8 row_mask:0xf bank_mask:0xf bound_ctrl:1
	v_pk_add_f32 v[186:187], v[186:187], v[120:121] op_sel:[0,1] op_sel_hi:[1,1] neg_lo:[0,1] neg_hi:[0,1]
	v_add_f32_dpp v155, v155, v155 row_ror:8 row_mask:0xf bank_mask:0xf bound_ctrl:1
	v_pk_add_f32 v[180:181], v[180:181], v[120:121] op_sel_hi:[1,0] neg_lo:[0,1] neg_hi:[0,1]
	v_add_f32_dpp v154, v154, v154 row_ror:4 row_mask:0xf bank_mask:0xf bound_ctrl:1
	v_pk_add_f32 v[188:189], v[188:189], v[120:121] op_sel:[0,1] op_sel_hi:[1,1] neg_lo:[0,1] neg_hi:[0,1]
	v_add_f32_dpp v155, v155, v155 row_ror:4 row_mask:0xf bank_mask:0xf bound_ctrl:1
	v_pk_add_f32 v[182:183], v[182:183], v[120:121] op_sel_hi:[1,0] neg_lo:[0,1] neg_hi:[0,1]
	v_add_f32_dpp v154, v154, v154 row_ror:2 row_mask:0xf bank_mask:0xf bound_ctrl:1
	v_pk_add_f32 v[190:191], v[190:191], v[120:121] op_sel:[0,1] op_sel_hi:[1,1] neg_lo:[0,1] neg_hi:[0,1]
	v_add_f32_dpp v155, v155, v155 row_ror:2 row_mask:0xf bank_mask:0xf bound_ctrl:1
	v_pk_add_f32 v[184:185], v[184:185], v[120:121] op_sel_hi:[1,0] neg_lo:[0,1] neg_hi:[0,1]
	v_add_f32_dpp v154, v154, v154 row_ror:1 row_mask:0xf bank_mask:0xf bound_ctrl:1
	v_pk_add_f32 v[192:193], v[192:193], v[120:121] op_sel:[0,1] op_sel_hi:[1,1] neg_lo:[0,1] neg_hi:[0,1]
	v_add_f32_dpp v155, v155, v155 row_ror:1 row_mask:0xf bank_mask:0xf bound_ctrl:1
	s_waitcnt lgkmcnt(10)
	v_pk_fma_f32 v[178:179], v[88:89], v[178:179], v[120:121] op_sel_hi:[1,1,0]
	ds_write_b32 v103, v154 offset:37376
	v_pk_fma_f32 v[186:187], v[88:89], v[186:187], v[120:121] op_sel:[0,0,1] op_sel_hi:[1,1,1]
	ds_write_b32 v103, v155 offset:37440
	v_pk_fma_f32 v[180:181], v[90:91], v[180:181], v[120:121] op_sel_hi:[1,1,0]
	v_pk_fma_f32 v[188:189], v[90:91], v[188:189], v[120:121] op_sel:[0,0,1] op_sel_hi:[1,1,1]
	s_waitcnt lgkmcnt(11)
	v_pk_fma_f32 v[182:183], v[92:93], v[182:183], v[120:121] op_sel_hi:[1,1,0]
	v_pk_fma_f32 v[190:191], v[92:93], v[190:191], v[120:121] op_sel:[0,0,1] op_sel_hi:[1,1,1]
	v_pk_fma_f32 v[184:185], v[94:95], v[184:185], v[120:121] op_sel_hi:[1,1,0]
	v_pk_fma_f32 v[192:193], v[94:95], v[192:193], v[120:121] op_sel:[0,0,1] op_sel_hi:[1,1,1]
	s_waitcnt lgkmcnt(10)
	v_pk_fma_f32 v[146:147], v[80:81], v[178:179], v[196:197]
	v_pk_fma_f32 v[150:151], v[80:81], v[186:187], v[196:197]
	v_pk_fma_f32 v[148:149], v[82:83], v[180:181], v[196:197]
	v_pk_fma_f32 v[152:153], v[82:83], v[188:189], v[196:197]
	s_waitcnt lgkmcnt(9)
	v_pk_fma_f32 v[146:147], v[84:85], v[182:183], v[146:147]
	v_pk_fma_f32 v[150:151], v[84:85], v[190:191], v[150:151]
	v_pk_fma_f32 v[148:149], v[86:87], v[184:185], v[148:149]
	v_pk_fma_f32 v[152:153], v[86:87], v[192:193], v[152:153]
	v_add_f32_e32 v146, v146, v147
	v_add_f32_e32 v148, v148, v149
	v_add_f32_e32 v150, v150, v151
	v_add_f32_e32 v152, v152, v153
	v_add_f32_e32 v156, v146, v148
	v_add_f32_e32 v157, v150, v152
	ds_read2_b32 v[120:121], v194 offset0:224 offset1:240
	ds_read_b128 v[88:91], v145 offset:11776
	ds_read_b128 v[92:95], v145 offset:12032
	ds_read_b128 v[80:83], v145 offset:3584
	ds_read_b128 v[84:87], v145 offset:3840
	s_waitcnt lgkmcnt(11)
	v_pk_add_f32 v[178:179], v[178:179], v[118:119] op_sel_hi:[1,0] neg_lo:[0,1] neg_hi:[0,1]
	v_add_f32_dpp v156, v156, v156 row_ror:8 row_mask:0xf bank_mask:0xf bound_ctrl:1
	v_pk_add_f32 v[186:187], v[186:187], v[118:119] op_sel:[0,1] op_sel_hi:[1,1] neg_lo:[0,1] neg_hi:[0,1]
	v_add_f32_dpp v157, v157, v157 row_ror:8 row_mask:0xf bank_mask:0xf bound_ctrl:1
	v_pk_add_f32 v[180:181], v[180:181], v[118:119] op_sel_hi:[1,0] neg_lo:[0,1] neg_hi:[0,1]
	v_add_f32_dpp v156, v156, v156 row_ror:4 row_mask:0xf bank_mask:0xf bound_ctrl:1
	v_pk_add_f32 v[188:189], v[188:189], v[118:119] op_sel:[0,1] op_sel_hi:[1,1] neg_lo:[0,1] neg_hi:[0,1]
	v_add_f32_dpp v157, v157, v157 row_ror:4 row_mask:0xf bank_mask:0xf bound_ctrl:1
	v_pk_add_f32 v[182:183], v[182:183], v[118:119] op_sel_hi:[1,0] neg_lo:[0,1] neg_hi:[0,1]
	v_add_f32_dpp v156, v156, v156 row_ror:2 row_mask:0xf bank_mask:0xf bound_ctrl:1
	v_pk_add_f32 v[190:191], v[190:191], v[118:119] op_sel:[0,1] op_sel_hi:[1,1] neg_lo:[0,1] neg_hi:[0,1]
	v_add_f32_dpp v157, v157, v157 row_ror:2 row_mask:0xf bank_mask:0xf bound_ctrl:1
	v_pk_add_f32 v[184:185], v[184:185], v[118:119] op_sel_hi:[1,0] neg_lo:[0,1] neg_hi:[0,1]
	v_add_f32_dpp v156, v156, v156 row_ror:1 row_mask:0xf bank_mask:0xf bound_ctrl:1
	v_pk_add_f32 v[192:193], v[192:193], v[118:119] op_sel:[0,1] op_sel_hi:[1,1] neg_lo:[0,1] neg_hi:[0,1]
	v_add_f32_dpp v157, v157, v157 row_ror:1 row_mask:0xf bank_mask:0xf bound_ctrl:1
	s_waitcnt lgkmcnt(10)
	v_pk_fma_f32 v[178:179], v[72:73], v[178:179], v[118:119] op_sel_hi:[1,1,0]
	ds_write_b32 v103, v156 offset:37504
	v_pk_fma_f32 v[186:187], v[72:73], v[186:187], v[118:119] op_sel:[0,0,1] op_sel_hi:[1,1,1]
	ds_write_b32 v103, v157 offset:37568
	v_pk_fma_f32 v[180:181], v[74:75], v[180:181], v[118:119] op_sel_hi:[1,1,0]
	v_pk_fma_f32 v[188:189], v[74:75], v[188:189], v[118:119] op_sel:[0,0,1] op_sel_hi:[1,1,1]
	s_waitcnt lgkmcnt(11)
	v_pk_fma_f32 v[182:183], v[76:77], v[182:183], v[118:119] op_sel_hi:[1,1,0]
	v_pk_fma_f32 v[190:191], v[76:77], v[190:191], v[118:119] op_sel:[0,0,1] op_sel_hi:[1,1,1]
	v_pk_fma_f32 v[184:185], v[78:79], v[184:185], v[118:119] op_sel_hi:[1,1,0]
	v_pk_fma_f32 v[192:193], v[78:79], v[192:193], v[118:119] op_sel:[0,0,1] op_sel_hi:[1,1,1]
	s_waitcnt lgkmcnt(10)
	v_pk_fma_f32 v[146:147], v[64:65], v[178:179], v[196:197]
	v_pk_fma_f32 v[150:151], v[64:65], v[186:187], v[196:197]
	v_pk_fma_f32 v[148:149], v[66:67], v[180:181], v[196:197]
	v_pk_fma_f32 v[152:153], v[66:67], v[188:189], v[196:197]
	s_waitcnt lgkmcnt(9)
	v_pk_fma_f32 v[146:147], v[68:69], v[182:183], v[146:147]
	v_pk_fma_f32 v[150:151], v[68:69], v[190:191], v[150:151]
	v_pk_fma_f32 v[148:149], v[70:71], v[184:185], v[148:149]
	v_pk_fma_f32 v[152:153], v[70:71], v[192:193], v[152:153]
	v_add_f32_e32 v146, v146, v147
	v_add_f32_e32 v148, v148, v149
	v_add_f32_e32 v150, v150, v151
	v_add_f32_e32 v152, v152, v153
	v_add_f32_e32 v154, v146, v148
	v_add_f32_e32 v155, v150, v152
	ds_read2_b32 v[118:119], v195 offset0:0 offset1:16
	ds_read_b128 v[72:75], v145 offset:12288
	ds_read_b128 v[76:79], v145 offset:12544
	ds_read_b128 v[64:67], v145 offset:4096
	ds_read_b128 v[68:71], v145 offset:4352
	s_waitcnt lgkmcnt(11)
	v_pk_add_f32 v[178:179], v[178:179], v[120:121] op_sel_hi:[1,0] neg_lo:[0,1] neg_hi:[0,1]
	v_add_f32_dpp v154, v154, v154 row_ror:8 row_mask:0xf bank_mask:0xf bound_ctrl:1
	v_pk_add_f32 v[186:187], v[186:187], v[120:121] op_sel:[0,1] op_sel_hi:[1,1] neg_lo:[0,1] neg_hi:[0,1]
	v_add_f32_dpp v155, v155, v155 row_ror:8 row_mask:0xf bank_mask:0xf bound_ctrl:1
	v_pk_add_f32 v[180:181], v[180:181], v[120:121] op_sel_hi:[1,0] neg_lo:[0,1] neg_hi:[0,1]
	v_add_f32_dpp v154, v154, v154 row_ror:4 row_mask:0xf bank_mask:0xf bound_ctrl:1
	v_pk_add_f32 v[188:189], v[188:189], v[120:121] op_sel:[0,1] op_sel_hi:[1,1] neg_lo:[0,1] neg_hi:[0,1]
	v_add_f32_dpp v155, v155, v155 row_ror:4 row_mask:0xf bank_mask:0xf bound_ctrl:1
	v_pk_add_f32 v[182:183], v[182:183], v[120:121] op_sel_hi:[1,0] neg_lo:[0,1] neg_hi:[0,1]
	v_add_f32_dpp v154, v154, v154 row_ror:2 row_mask:0xf bank_mask:0xf bound_ctrl:1
	v_pk_add_f32 v[190:191], v[190:191], v[120:121] op_sel:[0,1] op_sel_hi:[1,1] neg_lo:[0,1] neg_hi:[0,1]
	v_add_f32_dpp v155, v155, v155 row_ror:2 row_mask:0xf bank_mask:0xf bound_ctrl:1
	v_pk_add_f32 v[184:185], v[184:185], v[120:121] op_sel_hi:[1,0] neg_lo:[0,1] neg_hi:[0,1]
	v_add_f32_dpp v154, v154, v154 row_ror:1 row_mask:0xf bank_mask:0xf bound_ctrl:1
	v_pk_add_f32 v[192:193], v[192:193], v[120:121] op_sel:[0,1] op_sel_hi:[1,1] neg_lo:[0,1] neg_hi:[0,1]
	v_add_f32_dpp v155, v155, v155 row_ror:1 row_mask:0xf bank_mask:0xf bound_ctrl:1
	s_waitcnt lgkmcnt(10)
	v_pk_fma_f32 v[178:179], v[88:89], v[178:179], v[120:121] op_sel_hi:[1,1,0]
	ds_write_b32 v103, v154 offset:37632
	v_pk_fma_f32 v[186:187], v[88:89], v[186:187], v[120:121] op_sel:[0,0,1] op_sel_hi:[1,1,1]
	ds_write_b32 v103, v155 offset:37696
	v_pk_fma_f32 v[180:181], v[90:91], v[180:181], v[120:121] op_sel_hi:[1,1,0]
	v_pk_fma_f32 v[188:189], v[90:91], v[188:189], v[120:121] op_sel:[0,0,1] op_sel_hi:[1,1,1]
	s_waitcnt lgkmcnt(11)
	v_pk_fma_f32 v[182:183], v[92:93], v[182:183], v[120:121] op_sel_hi:[1,1,0]
	v_pk_fma_f32 v[190:191], v[92:93], v[190:191], v[120:121] op_sel:[0,0,1] op_sel_hi:[1,1,1]
	v_pk_fma_f32 v[184:185], v[94:95], v[184:185], v[120:121] op_sel_hi:[1,1,0]
	v_pk_fma_f32 v[192:193], v[94:95], v[192:193], v[120:121] op_sel:[0,0,1] op_sel_hi:[1,1,1]
	s_waitcnt lgkmcnt(10)
	v_pk_fma_f32 v[146:147], v[80:81], v[178:179], v[196:197]
	v_pk_fma_f32 v[150:151], v[80:81], v[186:187], v[196:197]
	v_pk_fma_f32 v[148:149], v[82:83], v[180:181], v[196:197]
	v_pk_fma_f32 v[152:153], v[82:83], v[188:189], v[196:197]
	s_waitcnt lgkmcnt(9)
	v_pk_fma_f32 v[146:147], v[84:85], v[182:183], v[146:147]
	v_pk_fma_f32 v[150:151], v[84:85], v[190:191], v[150:151]
	v_pk_fma_f32 v[148:149], v[86:87], v[184:185], v[148:149]
	v_pk_fma_f32 v[152:153], v[86:87], v[192:193], v[152:153]
	v_add_f32_e32 v146, v146, v147
	v_add_f32_e32 v148, v148, v149
	v_add_f32_e32 v150, v150, v151
	v_add_f32_e32 v152, v152, v153
	v_add_f32_e32 v156, v146, v148
	v_add_f32_e32 v157, v150, v152
	ds_read2_b32 v[120:121], v195 offset0:32 offset1:48
	ds_read_b128 v[88:91], v145 offset:12800
	ds_read_b128 v[92:95], v145 offset:13056
	ds_read_b128 v[80:83], v145 offset:4608
	ds_read_b128 v[84:87], v145 offset:4864
	s_waitcnt lgkmcnt(11)
	v_pk_add_f32 v[178:179], v[178:179], v[118:119] op_sel_hi:[1,0] neg_lo:[0,1] neg_hi:[0,1]
	v_add_f32_dpp v156, v156, v156 row_ror:8 row_mask:0xf bank_mask:0xf bound_ctrl:1
	v_pk_add_f32 v[186:187], v[186:187], v[118:119] op_sel:[0,1] op_sel_hi:[1,1] neg_lo:[0,1] neg_hi:[0,1]
	v_add_f32_dpp v157, v157, v157 row_ror:8 row_mask:0xf bank_mask:0xf bound_ctrl:1
	v_pk_add_f32 v[180:181], v[180:181], v[118:119] op_sel_hi:[1,0] neg_lo:[0,1] neg_hi:[0,1]
	v_add_f32_dpp v156, v156, v156 row_ror:4 row_mask:0xf bank_mask:0xf bound_ctrl:1
	v_pk_add_f32 v[188:189], v[188:189], v[118:119] op_sel:[0,1] op_sel_hi:[1,1] neg_lo:[0,1] neg_hi:[0,1]
	v_add_f32_dpp v157, v157, v157 row_ror:4 row_mask:0xf bank_mask:0xf bound_ctrl:1
	v_pk_add_f32 v[182:183], v[182:183], v[118:119] op_sel_hi:[1,0] neg_lo:[0,1] neg_hi:[0,1]
	v_add_f32_dpp v156, v156, v156 row_ror:2 row_mask:0xf bank_mask:0xf bound_ctrl:1
	v_pk_add_f32 v[190:191], v[190:191], v[118:119] op_sel:[0,1] op_sel_hi:[1,1] neg_lo:[0,1] neg_hi:[0,1]
	v_add_f32_dpp v157, v157, v157 row_ror:2 row_mask:0xf bank_mask:0xf bound_ctrl:1
	v_pk_add_f32 v[184:185], v[184:185], v[118:119] op_sel_hi:[1,0] neg_lo:[0,1] neg_hi:[0,1]
	v_add_f32_dpp v156, v156, v156 row_ror:1 row_mask:0xf bank_mask:0xf bound_ctrl:1
	v_pk_add_f32 v[192:193], v[192:193], v[118:119] op_sel:[0,1] op_sel_hi:[1,1] neg_lo:[0,1] neg_hi:[0,1]
	v_add_f32_dpp v157, v157, v157 row_ror:1 row_mask:0xf bank_mask:0xf bound_ctrl:1
	s_waitcnt lgkmcnt(10)
	v_pk_fma_f32 v[178:179], v[72:73], v[178:179], v[118:119] op_sel_hi:[1,1,0]
	ds_write_b32 v103, v156 offset:37760
	v_pk_fma_f32 v[186:187], v[72:73], v[186:187], v[118:119] op_sel:[0,0,1] op_sel_hi:[1,1,1]
	ds_write_b32 v103, v157 offset:37824
	v_pk_fma_f32 v[180:181], v[74:75], v[180:181], v[118:119] op_sel_hi:[1,1,0]
	v_pk_fma_f32 v[188:189], v[74:75], v[188:189], v[118:119] op_sel:[0,0,1] op_sel_hi:[1,1,1]
	s_waitcnt lgkmcnt(11)
	v_pk_fma_f32 v[182:183], v[76:77], v[182:183], v[118:119] op_sel_hi:[1,1,0]
	v_pk_fma_f32 v[190:191], v[76:77], v[190:191], v[118:119] op_sel:[0,0,1] op_sel_hi:[1,1,1]
	v_pk_fma_f32 v[184:185], v[78:79], v[184:185], v[118:119] op_sel_hi:[1,1,0]
	v_pk_fma_f32 v[192:193], v[78:79], v[192:193], v[118:119] op_sel:[0,0,1] op_sel_hi:[1,1,1]
	s_waitcnt lgkmcnt(10)
	v_pk_fma_f32 v[146:147], v[64:65], v[178:179], v[196:197]
	v_pk_fma_f32 v[150:151], v[64:65], v[186:187], v[196:197]
	v_pk_fma_f32 v[148:149], v[66:67], v[180:181], v[196:197]
	v_pk_fma_f32 v[152:153], v[66:67], v[188:189], v[196:197]
	s_waitcnt lgkmcnt(9)
	v_pk_fma_f32 v[146:147], v[68:69], v[182:183], v[146:147]
	v_pk_fma_f32 v[150:151], v[68:69], v[190:191], v[150:151]
	v_pk_fma_f32 v[148:149], v[70:71], v[184:185], v[148:149]
	v_pk_fma_f32 v[152:153], v[70:71], v[192:193], v[152:153]
	v_add_f32_e32 v146, v146, v147
	v_add_f32_e32 v148, v148, v149
	v_add_f32_e32 v150, v150, v151
	v_add_f32_e32 v152, v152, v153
	v_add_f32_e32 v154, v146, v148
	v_add_f32_e32 v155, v150, v152
	ds_read2_b32 v[118:119], v195 offset0:64 offset1:80
	ds_read_b128 v[72:75], v145 offset:13312
	ds_read_b128 v[76:79], v145 offset:13568
	ds_read_b128 v[64:67], v145 offset:5120
	ds_read_b128 v[68:71], v145 offset:5376
	s_waitcnt lgkmcnt(11)
	v_pk_add_f32 v[178:179], v[178:179], v[120:121] op_sel_hi:[1,0] neg_lo:[0,1] neg_hi:[0,1]
	v_add_f32_dpp v154, v154, v154 row_ror:8 row_mask:0xf bank_mask:0xf bound_ctrl:1
	v_pk_add_f32 v[186:187], v[186:187], v[120:121] op_sel:[0,1] op_sel_hi:[1,1] neg_lo:[0,1] neg_hi:[0,1]
	v_add_f32_dpp v155, v155, v155 row_ror:8 row_mask:0xf bank_mask:0xf bound_ctrl:1
	v_pk_add_f32 v[180:181], v[180:181], v[120:121] op_sel_hi:[1,0] neg_lo:[0,1] neg_hi:[0,1]
	v_add_f32_dpp v154, v154, v154 row_ror:4 row_mask:0xf bank_mask:0xf bound_ctrl:1
	v_pk_add_f32 v[188:189], v[188:189], v[120:121] op_sel:[0,1] op_sel_hi:[1,1] neg_lo:[0,1] neg_hi:[0,1]
	v_add_f32_dpp v155, v155, v155 row_ror:4 row_mask:0xf bank_mask:0xf bound_ctrl:1
	v_pk_add_f32 v[182:183], v[182:183], v[120:121] op_sel_hi:[1,0] neg_lo:[0,1] neg_hi:[0,1]
	v_add_f32_dpp v154, v154, v154 row_ror:2 row_mask:0xf bank_mask:0xf bound_ctrl:1
	v_pk_add_f32 v[190:191], v[190:191], v[120:121] op_sel:[0,1] op_sel_hi:[1,1] neg_lo:[0,1] neg_hi:[0,1]
	v_add_f32_dpp v155, v155, v155 row_ror:2 row_mask:0xf bank_mask:0xf bound_ctrl:1
	v_pk_add_f32 v[184:185], v[184:185], v[120:121] op_sel_hi:[1,0] neg_lo:[0,1] neg_hi:[0,1]
	v_add_f32_dpp v154, v154, v154 row_ror:1 row_mask:0xf bank_mask:0xf bound_ctrl:1
	v_pk_add_f32 v[192:193], v[192:193], v[120:121] op_sel:[0,1] op_sel_hi:[1,1] neg_lo:[0,1] neg_hi:[0,1]
	v_add_f32_dpp v155, v155, v155 row_ror:1 row_mask:0xf bank_mask:0xf bound_ctrl:1
	s_waitcnt lgkmcnt(10)
	v_pk_fma_f32 v[178:179], v[88:89], v[178:179], v[120:121] op_sel_hi:[1,1,0]
	ds_write_b32 v103, v154 offset:37888
	v_pk_fma_f32 v[186:187], v[88:89], v[186:187], v[120:121] op_sel:[0,0,1] op_sel_hi:[1,1,1]
	ds_write_b32 v103, v155 offset:37952
	v_pk_fma_f32 v[180:181], v[90:91], v[180:181], v[120:121] op_sel_hi:[1,1,0]
	v_pk_fma_f32 v[188:189], v[90:91], v[188:189], v[120:121] op_sel:[0,0,1] op_sel_hi:[1,1,1]
	s_waitcnt lgkmcnt(11)
	v_pk_fma_f32 v[182:183], v[92:93], v[182:183], v[120:121] op_sel_hi:[1,1,0]
	v_pk_fma_f32 v[190:191], v[92:93], v[190:191], v[120:121] op_sel:[0,0,1] op_sel_hi:[1,1,1]
	v_pk_fma_f32 v[184:185], v[94:95], v[184:185], v[120:121] op_sel_hi:[1,1,0]
	v_pk_fma_f32 v[192:193], v[94:95], v[192:193], v[120:121] op_sel:[0,0,1] op_sel_hi:[1,1,1]
	s_waitcnt lgkmcnt(10)
	v_pk_fma_f32 v[146:147], v[80:81], v[178:179], v[196:197]
	v_pk_fma_f32 v[150:151], v[80:81], v[186:187], v[196:197]
	v_pk_fma_f32 v[148:149], v[82:83], v[180:181], v[196:197]
	v_pk_fma_f32 v[152:153], v[82:83], v[188:189], v[196:197]
	s_waitcnt lgkmcnt(9)
	v_pk_fma_f32 v[146:147], v[84:85], v[182:183], v[146:147]
	v_pk_fma_f32 v[150:151], v[84:85], v[190:191], v[150:151]
	v_pk_fma_f32 v[148:149], v[86:87], v[184:185], v[148:149]
	v_pk_fma_f32 v[152:153], v[86:87], v[192:193], v[152:153]
	v_add_f32_e32 v146, v146, v147
	v_add_f32_e32 v148, v148, v149
	v_add_f32_e32 v150, v150, v151
	v_add_f32_e32 v152, v152, v153
	v_add_f32_e32 v156, v146, v148
	v_add_f32_e32 v157, v150, v152
	ds_read2_b32 v[120:121], v195 offset0:96 offset1:112
	ds_read_b128 v[88:91], v145 offset:13824
	ds_read_b128 v[92:95], v145 offset:14080
	ds_read_b128 v[80:83], v145 offset:5632
	ds_read_b128 v[84:87], v145 offset:5888
	s_waitcnt lgkmcnt(11)
	v_pk_add_f32 v[178:179], v[178:179], v[118:119] op_sel_hi:[1,0] neg_lo:[0,1] neg_hi:[0,1]
	v_add_f32_dpp v156, v156, v156 row_ror:8 row_mask:0xf bank_mask:0xf bound_ctrl:1
	v_pk_add_f32 v[186:187], v[186:187], v[118:119] op_sel:[0,1] op_sel_hi:[1,1] neg_lo:[0,1] neg_hi:[0,1]
	v_add_f32_dpp v157, v157, v157 row_ror:8 row_mask:0xf bank_mask:0xf bound_ctrl:1
	v_pk_add_f32 v[180:181], v[180:181], v[118:119] op_sel_hi:[1,0] neg_lo:[0,1] neg_hi:[0,1]
	v_add_f32_dpp v156, v156, v156 row_ror:4 row_mask:0xf bank_mask:0xf bound_ctrl:1
	v_pk_add_f32 v[188:189], v[188:189], v[118:119] op_sel:[0,1] op_sel_hi:[1,1] neg_lo:[0,1] neg_hi:[0,1]
	v_add_f32_dpp v157, v157, v157 row_ror:4 row_mask:0xf bank_mask:0xf bound_ctrl:1
	v_pk_add_f32 v[182:183], v[182:183], v[118:119] op_sel_hi:[1,0] neg_lo:[0,1] neg_hi:[0,1]
	v_add_f32_dpp v156, v156, v156 row_ror:2 row_mask:0xf bank_mask:0xf bound_ctrl:1
	v_pk_add_f32 v[190:191], v[190:191], v[118:119] op_sel:[0,1] op_sel_hi:[1,1] neg_lo:[0,1] neg_hi:[0,1]
	v_add_f32_dpp v157, v157, v157 row_ror:2 row_mask:0xf bank_mask:0xf bound_ctrl:1
	v_pk_add_f32 v[184:185], v[184:185], v[118:119] op_sel_hi:[1,0] neg_lo:[0,1] neg_hi:[0,1]
	v_add_f32_dpp v156, v156, v156 row_ror:1 row_mask:0xf bank_mask:0xf bound_ctrl:1
	v_pk_add_f32 v[192:193], v[192:193], v[118:119] op_sel:[0,1] op_sel_hi:[1,1] neg_lo:[0,1] neg_hi:[0,1]
	v_add_f32_dpp v157, v157, v157 row_ror:1 row_mask:0xf bank_mask:0xf bound_ctrl:1
	s_waitcnt lgkmcnt(10)
	v_pk_fma_f32 v[178:179], v[72:73], v[178:179], v[118:119] op_sel_hi:[1,1,0]
	ds_write_b32 v103, v156 offset:38016
	v_pk_fma_f32 v[186:187], v[72:73], v[186:187], v[118:119] op_sel:[0,0,1] op_sel_hi:[1,1,1]
	ds_write_b32 v103, v157 offset:38080
	v_pk_fma_f32 v[180:181], v[74:75], v[180:181], v[118:119] op_sel_hi:[1,1,0]
	v_pk_fma_f32 v[188:189], v[74:75], v[188:189], v[118:119] op_sel:[0,0,1] op_sel_hi:[1,1,1]
	s_waitcnt lgkmcnt(11)
	v_pk_fma_f32 v[182:183], v[76:77], v[182:183], v[118:119] op_sel_hi:[1,1,0]
	v_pk_fma_f32 v[190:191], v[76:77], v[190:191], v[118:119] op_sel:[0,0,1] op_sel_hi:[1,1,1]
	v_pk_fma_f32 v[184:185], v[78:79], v[184:185], v[118:119] op_sel_hi:[1,1,0]
	v_pk_fma_f32 v[192:193], v[78:79], v[192:193], v[118:119] op_sel:[0,0,1] op_sel_hi:[1,1,1]
	s_waitcnt lgkmcnt(10)
	v_pk_fma_f32 v[146:147], v[64:65], v[178:179], v[196:197]
	v_pk_fma_f32 v[150:151], v[64:65], v[186:187], v[196:197]
	v_pk_fma_f32 v[148:149], v[66:67], v[180:181], v[196:197]
	v_pk_fma_f32 v[152:153], v[66:67], v[188:189], v[196:197]
	s_waitcnt lgkmcnt(9)
	v_pk_fma_f32 v[146:147], v[68:69], v[182:183], v[146:147]
	v_pk_fma_f32 v[150:151], v[68:69], v[190:191], v[150:151]
	v_pk_fma_f32 v[148:149], v[70:71], v[184:185], v[148:149]
	v_pk_fma_f32 v[152:153], v[70:71], v[192:193], v[152:153]
	v_add_f32_e32 v146, v146, v147
	v_add_f32_e32 v148, v148, v149
	v_add_f32_e32 v150, v150, v151
	v_add_f32_e32 v152, v152, v153
	v_add_f32_e32 v154, v146, v148
	v_add_f32_e32 v155, v150, v152
	ds_read2_b32 v[118:119], v195 offset0:128 offset1:144
	ds_read_b128 v[72:75], v145 offset:14336
	ds_read_b128 v[76:79], v145 offset:14592
	ds_read_b128 v[64:67], v145 offset:6144
	ds_read_b128 v[68:71], v145 offset:6400
	s_waitcnt lgkmcnt(11)
	v_pk_add_f32 v[178:179], v[178:179], v[120:121] op_sel_hi:[1,0] neg_lo:[0,1] neg_hi:[0,1]
	v_add_f32_dpp v154, v154, v154 row_ror:8 row_mask:0xf bank_mask:0xf bound_ctrl:1
	v_pk_add_f32 v[186:187], v[186:187], v[120:121] op_sel:[0,1] op_sel_hi:[1,1] neg_lo:[0,1] neg_hi:[0,1]
	v_add_f32_dpp v155, v155, v155 row_ror:8 row_mask:0xf bank_mask:0xf bound_ctrl:1
	v_pk_add_f32 v[180:181], v[180:181], v[120:121] op_sel_hi:[1,0] neg_lo:[0,1] neg_hi:[0,1]
	v_add_f32_dpp v154, v154, v154 row_ror:4 row_mask:0xf bank_mask:0xf bound_ctrl:1
	v_pk_add_f32 v[188:189], v[188:189], v[120:121] op_sel:[0,1] op_sel_hi:[1,1] neg_lo:[0,1] neg_hi:[0,1]
	v_add_f32_dpp v155, v155, v155 row_ror:4 row_mask:0xf bank_mask:0xf bound_ctrl:1
	v_pk_add_f32 v[182:183], v[182:183], v[120:121] op_sel_hi:[1,0] neg_lo:[0,1] neg_hi:[0,1]
	v_add_f32_dpp v154, v154, v154 row_ror:2 row_mask:0xf bank_mask:0xf bound_ctrl:1
	v_pk_add_f32 v[190:191], v[190:191], v[120:121] op_sel:[0,1] op_sel_hi:[1,1] neg_lo:[0,1] neg_hi:[0,1]
	v_add_f32_dpp v155, v155, v155 row_ror:2 row_mask:0xf bank_mask:0xf bound_ctrl:1
	v_pk_add_f32 v[184:185], v[184:185], v[120:121] op_sel_hi:[1,0] neg_lo:[0,1] neg_hi:[0,1]
	v_add_f32_dpp v154, v154, v154 row_ror:1 row_mask:0xf bank_mask:0xf bound_ctrl:1
	v_pk_add_f32 v[192:193], v[192:193], v[120:121] op_sel:[0,1] op_sel_hi:[1,1] neg_lo:[0,1] neg_hi:[0,1]
	v_add_f32_dpp v155, v155, v155 row_ror:1 row_mask:0xf bank_mask:0xf bound_ctrl:1
	s_waitcnt lgkmcnt(10)
	v_pk_fma_f32 v[178:179], v[88:89], v[178:179], v[120:121] op_sel_hi:[1,1,0]
	ds_write_b32 v103, v154 offset:38144
	v_pk_fma_f32 v[186:187], v[88:89], v[186:187], v[120:121] op_sel:[0,0,1] op_sel_hi:[1,1,1]
	ds_write_b32 v103, v155 offset:38208
	v_pk_fma_f32 v[180:181], v[90:91], v[180:181], v[120:121] op_sel_hi:[1,1,0]
	v_pk_fma_f32 v[188:189], v[90:91], v[188:189], v[120:121] op_sel:[0,0,1] op_sel_hi:[1,1,1]
	s_waitcnt lgkmcnt(11)
	v_pk_fma_f32 v[182:183], v[92:93], v[182:183], v[120:121] op_sel_hi:[1,1,0]
	v_pk_fma_f32 v[190:191], v[92:93], v[190:191], v[120:121] op_sel:[0,0,1] op_sel_hi:[1,1,1]
	v_pk_fma_f32 v[184:185], v[94:95], v[184:185], v[120:121] op_sel_hi:[1,1,0]
	v_pk_fma_f32 v[192:193], v[94:95], v[192:193], v[120:121] op_sel:[0,0,1] op_sel_hi:[1,1,1]
	s_waitcnt lgkmcnt(10)
	v_pk_fma_f32 v[146:147], v[80:81], v[178:179], v[196:197]
	v_pk_fma_f32 v[150:151], v[80:81], v[186:187], v[196:197]
	v_pk_fma_f32 v[148:149], v[82:83], v[180:181], v[196:197]
	v_pk_fma_f32 v[152:153], v[82:83], v[188:189], v[196:197]
	s_waitcnt lgkmcnt(9)
	v_pk_fma_f32 v[146:147], v[84:85], v[182:183], v[146:147]
	v_pk_fma_f32 v[150:151], v[84:85], v[190:191], v[150:151]
	v_pk_fma_f32 v[148:149], v[86:87], v[184:185], v[148:149]
	v_pk_fma_f32 v[152:153], v[86:87], v[192:193], v[152:153]
	v_add_f32_e32 v146, v146, v147
	v_add_f32_e32 v148, v148, v149
	v_add_f32_e32 v150, v150, v151
	v_add_f32_e32 v152, v152, v153
	v_add_f32_e32 v156, v146, v148
	v_add_f32_e32 v157, v150, v152
	ds_read2_b32 v[120:121], v195 offset0:160 offset1:176
	ds_read_b128 v[88:91], v145 offset:14848
	ds_read_b128 v[92:95], v145 offset:15104
	ds_read_b128 v[80:83], v145 offset:6656
	ds_read_b128 v[84:87], v145 offset:6912
	s_waitcnt lgkmcnt(11)
	v_pk_add_f32 v[178:179], v[178:179], v[118:119] op_sel_hi:[1,0] neg_lo:[0,1] neg_hi:[0,1]
	v_add_f32_dpp v156, v156, v156 row_ror:8 row_mask:0xf bank_mask:0xf bound_ctrl:1
	v_pk_add_f32 v[186:187], v[186:187], v[118:119] op_sel:[0,1] op_sel_hi:[1,1] neg_lo:[0,1] neg_hi:[0,1]
	v_add_f32_dpp v157, v157, v157 row_ror:8 row_mask:0xf bank_mask:0xf bound_ctrl:1
	v_pk_add_f32 v[180:181], v[180:181], v[118:119] op_sel_hi:[1,0] neg_lo:[0,1] neg_hi:[0,1]
	v_add_f32_dpp v156, v156, v156 row_ror:4 row_mask:0xf bank_mask:0xf bound_ctrl:1
	v_pk_add_f32 v[188:189], v[188:189], v[118:119] op_sel:[0,1] op_sel_hi:[1,1] neg_lo:[0,1] neg_hi:[0,1]
	v_add_f32_dpp v157, v157, v157 row_ror:4 row_mask:0xf bank_mask:0xf bound_ctrl:1
	v_pk_add_f32 v[182:183], v[182:183], v[118:119] op_sel_hi:[1,0] neg_lo:[0,1] neg_hi:[0,1]
	v_add_f32_dpp v156, v156, v156 row_ror:2 row_mask:0xf bank_mask:0xf bound_ctrl:1
	v_pk_add_f32 v[190:191], v[190:191], v[118:119] op_sel:[0,1] op_sel_hi:[1,1] neg_lo:[0,1] neg_hi:[0,1]
	v_add_f32_dpp v157, v157, v157 row_ror:2 row_mask:0xf bank_mask:0xf bound_ctrl:1
	v_pk_add_f32 v[184:185], v[184:185], v[118:119] op_sel_hi:[1,0] neg_lo:[0,1] neg_hi:[0,1]
	v_add_f32_dpp v156, v156, v156 row_ror:1 row_mask:0xf bank_mask:0xf bound_ctrl:1
	v_pk_add_f32 v[192:193], v[192:193], v[118:119] op_sel:[0,1] op_sel_hi:[1,1] neg_lo:[0,1] neg_hi:[0,1]
	v_add_f32_dpp v157, v157, v157 row_ror:1 row_mask:0xf bank_mask:0xf bound_ctrl:1
	s_waitcnt lgkmcnt(10)
	v_pk_fma_f32 v[178:179], v[72:73], v[178:179], v[118:119] op_sel_hi:[1,1,0]
	ds_write_b32 v103, v156 offset:38272
	v_pk_fma_f32 v[186:187], v[72:73], v[186:187], v[118:119] op_sel:[0,0,1] op_sel_hi:[1,1,1]
	ds_write_b32 v103, v157 offset:38336
	v_pk_fma_f32 v[180:181], v[74:75], v[180:181], v[118:119] op_sel_hi:[1,1,0]
	v_pk_fma_f32 v[188:189], v[74:75], v[188:189], v[118:119] op_sel:[0,0,1] op_sel_hi:[1,1,1]
	s_waitcnt lgkmcnt(11)
	v_pk_fma_f32 v[182:183], v[76:77], v[182:183], v[118:119] op_sel_hi:[1,1,0]
	v_pk_fma_f32 v[190:191], v[76:77], v[190:191], v[118:119] op_sel:[0,0,1] op_sel_hi:[1,1,1]
	v_pk_fma_f32 v[184:185], v[78:79], v[184:185], v[118:119] op_sel_hi:[1,1,0]
	v_pk_fma_f32 v[192:193], v[78:79], v[192:193], v[118:119] op_sel:[0,0,1] op_sel_hi:[1,1,1]
	s_waitcnt lgkmcnt(10)
	v_pk_fma_f32 v[146:147], v[64:65], v[178:179], v[196:197]
	v_pk_fma_f32 v[150:151], v[64:65], v[186:187], v[196:197]
	v_pk_fma_f32 v[148:149], v[66:67], v[180:181], v[196:197]
	v_pk_fma_f32 v[152:153], v[66:67], v[188:189], v[196:197]
	s_waitcnt lgkmcnt(9)
	v_pk_fma_f32 v[146:147], v[68:69], v[182:183], v[146:147]
	v_pk_fma_f32 v[150:151], v[68:69], v[190:191], v[150:151]
	v_pk_fma_f32 v[148:149], v[70:71], v[184:185], v[148:149]
	v_pk_fma_f32 v[152:153], v[70:71], v[192:193], v[152:153]
	v_add_f32_e32 v146, v146, v147
	v_add_f32_e32 v148, v148, v149
	v_add_f32_e32 v150, v150, v151
	v_add_f32_e32 v152, v152, v153
	v_add_f32_e32 v154, v146, v148
	v_add_f32_e32 v155, v150, v152
	ds_read2_b32 v[118:119], v195 offset0:192 offset1:208
	ds_read_b128 v[72:75], v145 offset:15360
	ds_read_b128 v[76:79], v145 offset:15616
	ds_read_b128 v[64:67], v145 offset:7168
	ds_read_b128 v[68:71], v145 offset:7424
	s_waitcnt lgkmcnt(11)
	v_pk_add_f32 v[178:179], v[178:179], v[120:121] op_sel_hi:[1,0] neg_lo:[0,1] neg_hi:[0,1]
	v_add_f32_dpp v154, v154, v154 row_ror:8 row_mask:0xf bank_mask:0xf bound_ctrl:1
	v_pk_add_f32 v[186:187], v[186:187], v[120:121] op_sel:[0,1] op_sel_hi:[1,1] neg_lo:[0,1] neg_hi:[0,1]
	v_add_f32_dpp v155, v155, v155 row_ror:8 row_mask:0xf bank_mask:0xf bound_ctrl:1
	v_pk_add_f32 v[180:181], v[180:181], v[120:121] op_sel_hi:[1,0] neg_lo:[0,1] neg_hi:[0,1]
	v_add_f32_dpp v154, v154, v154 row_ror:4 row_mask:0xf bank_mask:0xf bound_ctrl:1
	v_pk_add_f32 v[188:189], v[188:189], v[120:121] op_sel:[0,1] op_sel_hi:[1,1] neg_lo:[0,1] neg_hi:[0,1]
	v_add_f32_dpp v155, v155, v155 row_ror:4 row_mask:0xf bank_mask:0xf bound_ctrl:1
	v_pk_add_f32 v[182:183], v[182:183], v[120:121] op_sel_hi:[1,0] neg_lo:[0,1] neg_hi:[0,1]
	v_add_f32_dpp v154, v154, v154 row_ror:2 row_mask:0xf bank_mask:0xf bound_ctrl:1
	v_pk_add_f32 v[190:191], v[190:191], v[120:121] op_sel:[0,1] op_sel_hi:[1,1] neg_lo:[0,1] neg_hi:[0,1]
	v_add_f32_dpp v155, v155, v155 row_ror:2 row_mask:0xf bank_mask:0xf bound_ctrl:1
	v_pk_add_f32 v[184:185], v[184:185], v[120:121] op_sel_hi:[1,0] neg_lo:[0,1] neg_hi:[0,1]
	v_add_f32_dpp v154, v154, v154 row_ror:1 row_mask:0xf bank_mask:0xf bound_ctrl:1
	v_pk_add_f32 v[192:193], v[192:193], v[120:121] op_sel:[0,1] op_sel_hi:[1,1] neg_lo:[0,1] neg_hi:[0,1]
	v_add_f32_dpp v155, v155, v155 row_ror:1 row_mask:0xf bank_mask:0xf bound_ctrl:1
	s_waitcnt lgkmcnt(10)
	v_pk_fma_f32 v[178:179], v[88:89], v[178:179], v[120:121] op_sel_hi:[1,1,0]
	ds_write_b32 v103, v154 offset:38400
	v_pk_fma_f32 v[186:187], v[88:89], v[186:187], v[120:121] op_sel:[0,0,1] op_sel_hi:[1,1,1]
	ds_write_b32 v103, v155 offset:38464
	v_pk_fma_f32 v[180:181], v[90:91], v[180:181], v[120:121] op_sel_hi:[1,1,0]
	v_pk_fma_f32 v[188:189], v[90:91], v[188:189], v[120:121] op_sel:[0,0,1] op_sel_hi:[1,1,1]
	s_waitcnt lgkmcnt(11)
	v_pk_fma_f32 v[182:183], v[92:93], v[182:183], v[120:121] op_sel_hi:[1,1,0]
	v_pk_fma_f32 v[190:191], v[92:93], v[190:191], v[120:121] op_sel:[0,0,1] op_sel_hi:[1,1,1]
	v_pk_fma_f32 v[184:185], v[94:95], v[184:185], v[120:121] op_sel_hi:[1,1,0]
	v_pk_fma_f32 v[192:193], v[94:95], v[192:193], v[120:121] op_sel:[0,0,1] op_sel_hi:[1,1,1]
	s_waitcnt lgkmcnt(10)
	v_pk_fma_f32 v[146:147], v[80:81], v[178:179], v[196:197]
	v_pk_fma_f32 v[150:151], v[80:81], v[186:187], v[196:197]
	v_pk_fma_f32 v[148:149], v[82:83], v[180:181], v[196:197]
	v_pk_fma_f32 v[152:153], v[82:83], v[188:189], v[196:197]
	s_waitcnt lgkmcnt(9)
	v_pk_fma_f32 v[146:147], v[84:85], v[182:183], v[146:147]
	v_pk_fma_f32 v[150:151], v[84:85], v[190:191], v[150:151]
	v_pk_fma_f32 v[148:149], v[86:87], v[184:185], v[148:149]
	v_pk_fma_f32 v[152:153], v[86:87], v[192:193], v[152:153]
	v_add_f32_e32 v146, v146, v147
	v_add_f32_e32 v148, v148, v149
	v_add_f32_e32 v150, v150, v151
	v_add_f32_e32 v152, v152, v153
	v_add_f32_e32 v156, v146, v148
	v_add_f32_e32 v157, v150, v152
	ds_read2_b32 v[120:121], v195 offset0:224 offset1:240
	ds_read_b128 v[88:91], v145 offset:15872
	ds_read_b128 v[92:95], v145 offset:16128
	ds_read_b128 v[80:83], v145 offset:7680
	ds_read_b128 v[84:87], v145 offset:7936
	s_waitcnt lgkmcnt(11)
	v_pk_add_f32 v[178:179], v[178:179], v[118:119] op_sel_hi:[1,0] neg_lo:[0,1] neg_hi:[0,1]
	v_add_f32_dpp v156, v156, v156 row_ror:8 row_mask:0xf bank_mask:0xf bound_ctrl:1
	v_pk_add_f32 v[186:187], v[186:187], v[118:119] op_sel:[0,1] op_sel_hi:[1,1] neg_lo:[0,1] neg_hi:[0,1]
	v_add_f32_dpp v157, v157, v157 row_ror:8 row_mask:0xf bank_mask:0xf bound_ctrl:1
	v_pk_add_f32 v[180:181], v[180:181], v[118:119] op_sel_hi:[1,0] neg_lo:[0,1] neg_hi:[0,1]
	v_add_f32_dpp v156, v156, v156 row_ror:4 row_mask:0xf bank_mask:0xf bound_ctrl:1
	v_pk_add_f32 v[188:189], v[188:189], v[118:119] op_sel:[0,1] op_sel_hi:[1,1] neg_lo:[0,1] neg_hi:[0,1]
	v_add_f32_dpp v157, v157, v157 row_ror:4 row_mask:0xf bank_mask:0xf bound_ctrl:1
	v_pk_add_f32 v[182:183], v[182:183], v[118:119] op_sel_hi:[1,0] neg_lo:[0,1] neg_hi:[0,1]
	v_add_f32_dpp v156, v156, v156 row_ror:2 row_mask:0xf bank_mask:0xf bound_ctrl:1
	v_pk_add_f32 v[190:191], v[190:191], v[118:119] op_sel:[0,1] op_sel_hi:[1,1] neg_lo:[0,1] neg_hi:[0,1]
	v_add_f32_dpp v157, v157, v157 row_ror:2 row_mask:0xf bank_mask:0xf bound_ctrl:1
	v_pk_add_f32 v[184:185], v[184:185], v[118:119] op_sel_hi:[1,0] neg_lo:[0,1] neg_hi:[0,1]
	v_add_f32_dpp v156, v156, v156 row_ror:1 row_mask:0xf bank_mask:0xf bound_ctrl:1
	v_pk_add_f32 v[192:193], v[192:193], v[118:119] op_sel:[0,1] op_sel_hi:[1,1] neg_lo:[0,1] neg_hi:[0,1]
	v_add_f32_dpp v157, v157, v157 row_ror:1 row_mask:0xf bank_mask:0xf bound_ctrl:1
	s_waitcnt lgkmcnt(10)
	v_pk_fma_f32 v[178:179], v[72:73], v[178:179], v[118:119] op_sel_hi:[1,1,0]
	ds_write_b32 v103, v156 offset:38528
	v_pk_fma_f32 v[186:187], v[72:73], v[186:187], v[118:119] op_sel:[0,0,1] op_sel_hi:[1,1,1]
	ds_write_b32 v103, v157 offset:38592
	v_pk_fma_f32 v[180:181], v[74:75], v[180:181], v[118:119] op_sel_hi:[1,1,0]
	v_pk_fma_f32 v[188:189], v[74:75], v[188:189], v[118:119] op_sel:[0,0,1] op_sel_hi:[1,1,1]
	s_waitcnt lgkmcnt(11)
	v_pk_fma_f32 v[182:183], v[76:77], v[182:183], v[118:119] op_sel_hi:[1,1,0]
	v_pk_fma_f32 v[190:191], v[76:77], v[190:191], v[118:119] op_sel:[0,0,1] op_sel_hi:[1,1,1]
	v_pk_fma_f32 v[184:185], v[78:79], v[184:185], v[118:119] op_sel_hi:[1,1,0]
	v_pk_fma_f32 v[192:193], v[78:79], v[192:193], v[118:119] op_sel:[0,0,1] op_sel_hi:[1,1,1]
	s_waitcnt lgkmcnt(10)
	v_pk_fma_f32 v[146:147], v[64:65], v[178:179], v[196:197]
	v_pk_fma_f32 v[150:151], v[64:65], v[186:187], v[196:197]
	v_pk_fma_f32 v[148:149], v[66:67], v[180:181], v[196:197]
	v_pk_fma_f32 v[152:153], v[66:67], v[188:189], v[196:197]
	s_waitcnt lgkmcnt(9)
	v_pk_fma_f32 v[146:147], v[68:69], v[182:183], v[146:147]
	v_pk_fma_f32 v[150:151], v[68:69], v[190:191], v[150:151]
	v_pk_fma_f32 v[148:149], v[70:71], v[184:185], v[148:149]
	v_pk_fma_f32 v[152:153], v[70:71], v[192:193], v[152:153]
	v_add_f32_e32 v146, v146, v147
	v_add_f32_e32 v148, v148, v149
	v_add_f32_e32 v150, v150, v151
	v_add_f32_e32 v152, v152, v153
	v_add_f32_e32 v154, v146, v148
	v_add_f32_e32 v155, v150, v152
	s_waitcnt lgkmcnt(6)
	v_pk_add_f32 v[178:179], v[178:179], v[120:121] op_sel_hi:[1,0] neg_lo:[0,1] neg_hi:[0,1]
	v_add_f32_dpp v154, v154, v154 row_ror:8 row_mask:0xf bank_mask:0xf bound_ctrl:1
	v_pk_add_f32 v[186:187], v[186:187], v[120:121] op_sel:[0,1] op_sel_hi:[1,1] neg_lo:[0,1] neg_hi:[0,1]
	v_add_f32_dpp v155, v155, v155 row_ror:8 row_mask:0xf bank_mask:0xf bound_ctrl:1
	v_pk_add_f32 v[180:181], v[180:181], v[120:121] op_sel_hi:[1,0] neg_lo:[0,1] neg_hi:[0,1]
	v_add_f32_dpp v154, v154, v154 row_ror:4 row_mask:0xf bank_mask:0xf bound_ctrl:1
	v_pk_add_f32 v[188:189], v[188:189], v[120:121] op_sel:[0,1] op_sel_hi:[1,1] neg_lo:[0,1] neg_hi:[0,1]
	v_add_f32_dpp v155, v155, v155 row_ror:4 row_mask:0xf bank_mask:0xf bound_ctrl:1
	v_pk_add_f32 v[182:183], v[182:183], v[120:121] op_sel_hi:[1,0] neg_lo:[0,1] neg_hi:[0,1]
	v_add_f32_dpp v154, v154, v154 row_ror:2 row_mask:0xf bank_mask:0xf bound_ctrl:1
	v_pk_add_f32 v[190:191], v[190:191], v[120:121] op_sel:[0,1] op_sel_hi:[1,1] neg_lo:[0,1] neg_hi:[0,1]
	v_add_f32_dpp v155, v155, v155 row_ror:2 row_mask:0xf bank_mask:0xf bound_ctrl:1
	v_pk_add_f32 v[184:185], v[184:185], v[120:121] op_sel_hi:[1,0] neg_lo:[0,1] neg_hi:[0,1]
	v_add_f32_dpp v154, v154, v154 row_ror:1 row_mask:0xf bank_mask:0xf bound_ctrl:1
	v_pk_add_f32 v[192:193], v[192:193], v[120:121] op_sel:[0,1] op_sel_hi:[1,1] neg_lo:[0,1] neg_hi:[0,1]
	v_add_f32_dpp v155, v155, v155 row_ror:1 row_mask:0xf bank_mask:0xf bound_ctrl:1
	s_waitcnt lgkmcnt(5)
	v_pk_fma_f32 v[178:179], v[88:89], v[178:179], v[120:121] op_sel_hi:[1,1,0]
	ds_write_b32 v103, v154 offset:38656
	v_pk_fma_f32 v[186:187], v[88:89], v[186:187], v[120:121] op_sel:[0,0,1] op_sel_hi:[1,1,1]
	ds_write_b32 v103, v155 offset:38720
	v_pk_fma_f32 v[180:181], v[90:91], v[180:181], v[120:121] op_sel_hi:[1,1,0]
	v_pk_fma_f32 v[188:189], v[90:91], v[188:189], v[120:121] op_sel:[0,0,1] op_sel_hi:[1,1,1]
	s_waitcnt lgkmcnt(6)
	v_pk_fma_f32 v[182:183], v[92:93], v[182:183], v[120:121] op_sel_hi:[1,1,0]
	v_pk_fma_f32 v[190:191], v[92:93], v[190:191], v[120:121] op_sel:[0,0,1] op_sel_hi:[1,1,1]
	v_pk_fma_f32 v[184:185], v[94:95], v[184:185], v[120:121] op_sel_hi:[1,1,0]
	v_pk_fma_f32 v[192:193], v[94:95], v[192:193], v[120:121] op_sel:[0,0,1] op_sel_hi:[1,1,1]
	s_waitcnt lgkmcnt(5)
	v_pk_fma_f32 v[146:147], v[80:81], v[178:179], v[196:197]
	v_pk_fma_f32 v[150:151], v[80:81], v[186:187], v[196:197]
	v_pk_fma_f32 v[148:149], v[82:83], v[180:181], v[196:197]
	v_pk_fma_f32 v[152:153], v[82:83], v[188:189], v[196:197]
	s_waitcnt lgkmcnt(4)
	v_pk_fma_f32 v[146:147], v[84:85], v[182:183], v[146:147]
	v_pk_fma_f32 v[150:151], v[84:85], v[190:191], v[150:151]
	v_pk_fma_f32 v[148:149], v[86:87], v[184:185], v[148:149]
	v_pk_fma_f32 v[152:153], v[86:87], v[192:193], v[152:153]
	v_add_f32_e32 v146, v146, v147
	v_add_f32_e32 v148, v148, v149
	v_add_f32_e32 v150, v150, v151
	v_add_f32_e32 v152, v152, v153
	v_add_f32_e32 v156, v146, v148
	v_add_f32_e32 v157, v150, v152
	s_nop 0
	v_add_f32_dpp v156, v156, v156 row_ror:8 row_mask:0xf bank_mask:0xf bound_ctrl:1
	v_add_f32_dpp v157, v157, v157 row_ror:8 row_mask:0xf bank_mask:0xf bound_ctrl:1
	s_nop 0
	v_add_f32_dpp v156, v156, v156 row_ror:4 row_mask:0xf bank_mask:0xf bound_ctrl:1
	v_add_f32_dpp v157, v157, v157 row_ror:4 row_mask:0xf bank_mask:0xf bound_ctrl:1
	s_nop 0
	v_add_f32_dpp v156, v156, v156 row_ror:2 row_mask:0xf bank_mask:0xf bound_ctrl:1
	v_add_f32_dpp v157, v157, v157 row_ror:2 row_mask:0xf bank_mask:0xf bound_ctrl:1
	s_nop 0
	v_add_f32_dpp v156, v156, v156 row_ror:1 row_mask:0xf bank_mask:0xf bound_ctrl:1
	v_add_f32_dpp v157, v157, v157 row_ror:1 row_mask:0xf bank_mask:0xf bound_ctrl:1
	ds_write_b32 v103, v156 offset:38784
	ds_write_b32 v103, v157 offset:38848
	s_waitcnt vmcnt(9)
	v_mul_f32_e32 v64, 0xbfb8aa3b, v16
	v_mul_f32_e32 v65, 0xbfb8aa3b, v17
	v_exp_f32_e32 v64, v64
	v_exp_f32_e32 v65, v65
	v_mul_f32_e32 v66, 0xbfb8aa3b, v18
	v_mul_f32_e32 v67, 0xbfb8aa3b, v19
	v_exp_f32_e32 v66, v66
	v_pk_add_f32 v[64:65], v[64:65], 1.0 op_sel_hi:[1,0]
	v_exp_f32_e32 v67, v67
	v_div_scale_f32 v76, s[8:9], v65, v65, v17
	v_rcp_f32_e32 v77, v76
	v_pk_add_f32 v[66:67], v[66:67], 1.0 op_sel_hi:[1,0]
	s_waitcnt vmcnt(8)
	v_mul_f32_e32 v72, 0xbfb8aa3b, v20
	v_mul_f32_e32 v73, 0xbfb8aa3b, v21
	v_fma_f32 v78, -v76, v77, 1.0
	v_fmac_f32_e32 v77, v78, v77
	v_div_scale_f32 v78, vcc, v17, v65, v17
	v_mul_f32_e32 v79, v78, v77
	v_fma_f32 v80, -v76, v79, v78
	v_fmac_f32_e32 v79, v80, v77
	v_fma_f32 v76, -v76, v79, v78
	v_div_fmas_f32 v76, v76, v77, v79
	v_div_fixup_f32 v65, v76, v65, v17
	v_div_scale_f32 v76, s[8:9], v64, v64, v16
	v_rcp_f32_e32 v77, v76
	v_exp_f32_e32 v72, v72
	v_exp_f32_e32 v73, v73
	v_mul_f32_e32 v74, 0xbfb8aa3b, v22
	v_fma_f32 v78, -v76, v77, 1.0
	v_fmac_f32_e32 v77, v78, v77
	v_div_scale_f32 v78, vcc, v16, v64, v16
	v_mul_f32_e32 v79, v78, v77
	v_fma_f32 v80, -v76, v79, v78
	v_fmac_f32_e32 v79, v80, v77
	v_fma_f32 v76, -v76, v79, v78
	v_div_fmas_f32 v76, v76, v77, v79
	v_div_fixup_f32 v64, v76, v64, v16
	v_div_scale_f32 v76, s[8:9], v67, v67, v19
	v_rcp_f32_e32 v77, v76
	v_pk_mul_f32 v[64:65], v[64:65], s[18:19] op_sel_hi:[1,0]
	v_mul_f32_e32 v75, 0xbfb8aa3b, v23
	v_exp_f32_e32 v74, v74
	v_fma_f32 v78, -v76, v77, 1.0
	v_fmac_f32_e32 v77, v78, v77
	v_div_scale_f32 v78, vcc, v19, v67, v19
	v_mul_f32_e32 v79, v78, v77
	v_fma_f32 v80, -v76, v79, v78
	v_fmac_f32_e32 v79, v80, v77
	v_fma_f32 v76, -v76, v79, v78
	v_div_fmas_f32 v76, v76, v77, v79
	v_div_fixup_f32 v67, v76, v67, v19
	v_div_scale_f32 v76, s[8:9], v66, v66, v18
	v_rcp_f32_e32 v77, v76
	v_exp_f32_e32 v75, v75
	s_cmpk_lt_u32 s48, 0x7b
	v_fma_f32 v78, -v76, v77, 1.0
	v_fmac_f32_e32 v77, v78, v77
	v_div_scale_f32 v78, vcc, v18, v66, v18
	v_mul_f32_e32 v79, v78, v77
	v_fma_f32 v80, -v76, v79, v78
	v_fmac_f32_e32 v79, v80, v77
	v_fma_f32 v76, -v76, v79, v78
	v_div_fmas_f32 v76, v76, v77, v79
	v_div_fixup_f32 v66, v76, v66, v18
	v_pk_mul_f32 v[66:67], v[66:67], s[18:19] op_sel_hi:[1,0]
	ds_write_b128 v141, v[64:67] offset:18432
	v_pk_add_f32 v[64:65], v[72:73], 1.0 op_sel_hi:[1,0]
	v_div_scale_f32 v66, s[8:9], v65, v65, 1.0
	v_rcp_f32_e32 v67, v66
	s_nop 0
	v_fma_f32 v72, -v66, v67, 1.0
	v_fmac_f32_e32 v67, v72, v67
	v_div_scale_f32 v72, vcc, 1.0, v65, 1.0
	v_mul_f32_e32 v73, v72, v67
	v_fma_f32 v76, -v66, v73, v72
	v_fmac_f32_e32 v73, v76, v67
	v_fma_f32 v66, -v66, v73, v72
	v_div_fmas_f32 v66, v66, v67, v73
	v_div_fixup_f32 v65, v66, v65, 1.0
	v_div_scale_f32 v66, s[8:9], v64, v64, 1.0
	v_rcp_f32_e32 v67, v66
	s_nop 0
	v_fma_f32 v72, -v66, v67, 1.0
	v_fmac_f32_e32 v67, v72, v67
	v_div_scale_f32 v72, vcc, 1.0, v64, 1.0
	v_mul_f32_e32 v73, v72, v67
	v_fma_f32 v76, -v66, v73, v72
	v_fmac_f32_e32 v73, v76, v67
	v_fma_f32 v66, -v66, v73, v72
	v_div_fmas_f32 v66, v66, v67, v73
	v_div_fixup_f32 v64, v66, v64, 1.0
	v_pk_add_f32 v[66:67], v[74:75], 1.0 op_sel_hi:[1,0]
	v_pk_fma_f32 v[64:65], v[110:111], v[64:65], v[104:105]
	v_div_scale_f32 v72, s[8:9], v67, v67, 1.0
	v_rcp_f32_e32 v73, v72
	s_nop 0
	v_fma_f32 v74, -v72, v73, 1.0
	v_fmac_f32_e32 v73, v74, v73
	v_div_scale_f32 v74, vcc, 1.0, v67, 1.0
	v_mul_f32_e32 v75, v74, v73
	v_fma_f32 v76, -v72, v75, v74
	v_fmac_f32_e32 v75, v76, v73
	v_fma_f32 v72, -v72, v75, v74
	v_div_fmas_f32 v72, v72, v73, v75
	v_div_fixup_f32 v67, v72, v67, 1.0
	v_div_scale_f32 v72, s[8:9], v66, v66, 1.0
	v_rcp_f32_e32 v73, v72
	s_nop 0
	v_fma_f32 v74, -v72, v73, 1.0
	v_fmac_f32_e32 v73, v74, v73
	v_div_scale_f32 v74, vcc, 1.0, v66, 1.0
	v_mul_f32_e32 v75, v74, v73
	v_fma_f32 v76, -v72, v75, v74
	v_fmac_f32_e32 v75, v76, v73
	v_fma_f32 v72, -v72, v75, v74
	v_div_fmas_f32 v72, v72, v73, v75
	v_div_fixup_f32 v66, v72, v66, 1.0
	v_pk_fma_f32 v[66:67], v[112:113], v[66:67], v[106:107]
	ds_write_b128 v141, v[64:67] offset:26624
	ds_write_b32 v134, v129 offset:34816
	v_mul_f32_e32 v64, 0xbfb8aa3b, v24
	v_mul_f32_e32 v65, 0xbfb8aa3b, v25
	v_exp_f32_e32 v64, v64
	v_exp_f32_e32 v65, v65
	v_mul_f32_e32 v66, 0xbfb8aa3b, v26
	v_mul_f32_e32 v67, 0xbfb8aa3b, v27
	v_exp_f32_e32 v66, v66
	v_pk_add_f32 v[64:65], v[64:65], 1.0 op_sel_hi:[1,0]
	v_exp_f32_e32 v67, v67
	v_div_scale_f32 v76, s[8:9], v65, v65, v25
	v_rcp_f32_e32 v77, v76
	v_pk_add_f32 v[66:67], v[66:67], 1.0 op_sel_hi:[1,0]
	v_mul_f32_e32 v72, 0xbfb8aa3b, v36
	v_mul_f32_e32 v73, 0xbfb8aa3b, v37
	v_fma_f32 v78, -v76, v77, 1.0
	v_fmac_f32_e32 v77, v78, v77
	v_div_scale_f32 v78, vcc, v25, v65, v25
	v_mul_f32_e32 v79, v78, v77
	v_fma_f32 v80, -v76, v79, v78
	v_fmac_f32_e32 v79, v80, v77
	v_fma_f32 v76, -v76, v79, v78
	v_div_fmas_f32 v76, v76, v77, v79
	v_div_fixup_f32 v65, v76, v65, v25
	v_div_scale_f32 v76, s[8:9], v64, v64, v24
	v_rcp_f32_e32 v77, v76
	v_exp_f32_e32 v72, v72
	v_exp_f32_e32 v73, v73
	v_mul_f32_e32 v74, 0xbfb8aa3b, v38
	v_fma_f32 v78, -v76, v77, 1.0
	v_fmac_f32_e32 v77, v78, v77
	v_div_scale_f32 v78, vcc, v24, v64, v24
	v_mul_f32_e32 v79, v78, v77
	v_fma_f32 v80, -v76, v79, v78
	v_fmac_f32_e32 v79, v80, v77
	v_fma_f32 v76, -v76, v79, v78
	v_div_fmas_f32 v76, v76, v77, v79
	v_div_fixup_f32 v64, v76, v64, v24
	v_div_scale_f32 v76, s[8:9], v67, v67, v27
	v_rcp_f32_e32 v77, v76
	v_pk_mul_f32 v[64:65], v[64:65], s[18:19] op_sel_hi:[1,0]
	v_mul_f32_e32 v75, 0xbfb8aa3b, v39
	v_exp_f32_e32 v74, v74
	v_fma_f32 v78, -v76, v77, 1.0
	v_fmac_f32_e32 v77, v78, v77
	v_div_scale_f32 v78, vcc, v27, v67, v27
	v_mul_f32_e32 v79, v78, v77
	v_fma_f32 v80, -v76, v79, v78
	v_fmac_f32_e32 v79, v80, v77
	v_fma_f32 v76, -v76, v79, v78
	v_div_fmas_f32 v76, v76, v77, v79
	v_div_fixup_f32 v67, v76, v67, v27
	v_div_scale_f32 v76, s[8:9], v66, v66, v26
	v_rcp_f32_e32 v77, v76
	v_exp_f32_e32 v75, v75
	v_fma_f32 v78, -v76, v77, 1.0
	v_fmac_f32_e32 v77, v78, v77
	v_div_scale_f32 v78, vcc, v26, v66, v26
	v_mul_f32_e32 v79, v78, v77
	v_fma_f32 v80, -v76, v79, v78
	v_fmac_f32_e32 v79, v80, v77
	v_fma_f32 v76, -v76, v79, v78
	v_div_fmas_f32 v76, v76, v77, v79
	v_div_fixup_f32 v66, v76, v66, v26
	v_pk_mul_f32 v[66:67], v[66:67], s[18:19] op_sel_hi:[1,0]
	ds_write_b128 v144, v[64:67] offset:18432
	v_pk_add_f32 v[64:65], v[72:73], 1.0 op_sel_hi:[1,0]
	v_div_scale_f32 v66, s[8:9], v65, v65, 1.0
	v_rcp_f32_e32 v67, v66
	s_nop 0
	v_fma_f32 v72, -v66, v67, 1.0
	v_fmac_f32_e32 v67, v72, v67
	v_div_scale_f32 v72, vcc, 1.0, v65, 1.0
	v_mul_f32_e32 v73, v72, v67
	v_fma_f32 v76, -v66, v73, v72
	v_fmac_f32_e32 v73, v76, v67
	v_fma_f32 v66, -v66, v73, v72
	v_div_fmas_f32 v66, v66, v67, v73
	v_div_fixup_f32 v65, v66, v65, 1.0
	v_div_scale_f32 v66, s[8:9], v64, v64, 1.0
	v_rcp_f32_e32 v67, v66
	s_nop 0
	v_fma_f32 v72, -v66, v67, 1.0
	v_fmac_f32_e32 v67, v72, v67
	v_div_scale_f32 v72, vcc, 1.0, v64, 1.0
	v_mul_f32_e32 v73, v72, v67
	v_fma_f32 v76, -v66, v73, v72
	v_fmac_f32_e32 v73, v76, v67
	v_fma_f32 v66, -v66, v73, v72
	v_div_fmas_f32 v66, v66, v67, v73
	v_div_fixup_f32 v64, v66, v64, 1.0
	v_pk_add_f32 v[66:67], v[74:75], 1.0 op_sel_hi:[1,0]
	v_pk_fma_f32 v[64:65], v[110:111], v[64:65], v[104:105]
	v_div_scale_f32 v72, s[8:9], v67, v67, 1.0
	v_rcp_f32_e32 v73, v72
	s_nop 0
	v_fma_f32 v74, -v72, v73, 1.0
	v_fmac_f32_e32 v73, v74, v73
	v_div_scale_f32 v74, vcc, 1.0, v67, 1.0
	v_mul_f32_e32 v75, v74, v73
	v_fma_f32 v76, -v72, v75, v74
	v_fmac_f32_e32 v75, v76, v73
	v_fma_f32 v72, -v72, v75, v74
	v_div_fmas_f32 v72, v72, v73, v75
	v_div_fixup_f32 v67, v72, v67, 1.0
	v_div_scale_f32 v72, s[8:9], v66, v66, 1.0
	v_rcp_f32_e32 v73, v72
	s_mov_b64 s[8:9], -1
	v_fma_f32 v74, -v72, v73, 1.0
	v_fmac_f32_e32 v73, v74, v73
	v_div_scale_f32 v74, vcc, 1.0, v66, 1.0
	v_mul_f32_e32 v75, v74, v73
	v_fma_f32 v76, -v72, v75, v74
	v_fmac_f32_e32 v75, v76, v73
	v_fma_f32 v72, -v72, v75, v74
	v_div_fmas_f32 v72, v72, v73, v75
	v_div_fixup_f32 v66, v72, v66, 1.0
	v_pk_fma_f32 v[66:67], v[112:113], v[66:67], v[106:107]
	ds_write_b128 v144, v[64:67] offset:26624
	ds_write_b32 v134, v130 offset:35840
	s_waitcnt lgkmcnt(0)
	s_barrier
	v_add_u32_e32 v64, s47, v124
	v_add_u32_e32 v65, s47, v126
	s_cbranch_scc1 .LBB0_1323
	v_add_u32_e32 v98, s47, v124
	v_add_u32_e32 v96, s47, v126
	s_mov_b64 s[8:9], 0

.LBB0_1325:
	ds_read2st64_b32 v[64:65], v134 offset0:144 offset1:148
	v_ashrrev_i32_e32 v99, 31, v98
	v_lshlrev_b64 v[66:67], 12, v[98:99]
	v_ashrrev_i32_e32 v97, 31, v96
	v_lshl_add_u64 v[66:67], v[108:109], 0, v[66:67]
	s_waitcnt lgkmcnt(0)
	global_store_dword v[66:67], v64, off
	v_lshlrev_b64 v[66:67], 12, v[96:97]
	v_lshl_add_u64 v[66:67], v[108:109], 0, v[66:67]
	global_store_dword v[66:67], v65, off
	v_mov_b32_e32 v196, 0
	v_mov_b32_e32 v197, 0
	v_add_u32_e32 v194, 0x8800, v103
	v_add_u32_e32 v195, 0x8c00, v103
	ds_read2_b32 v[118:119], v194 offset0:0 offset1:16
	ds_read_b128 v[72:75], v145 offset:26624
	ds_read_b128 v[76:79], v145 offset:26880
	ds_read_b128 v[64:67], v145 offset:18432
	ds_read_b128 v[68:71], v145 offset:18688
	ds_read2_b32 v[120:121], v194 offset0:32 offset1:48
	ds_read_b128 v[88:91], v145 offset:27136
	ds_read_b128 v[92:95], v145 offset:27392
	ds_read_b128 v[80:83], v145 offset:18944
	ds_read_b128 v[84:87], v145 offset:19200
	s_waitcnt lgkmcnt(9)
	v_pk_add_f32 v[178:179], v[178:179], v[118:119] op_sel_hi:[1,0] neg_lo:[0,1] neg_hi:[0,1]
	v_pk_add_f32 v[186:187], v[186:187], v[118:119] op_sel:[0,1] op_sel_hi:[1,1] neg_lo:[0,1] neg_hi:[0,1]
	v_pk_add_f32 v[180:181], v[180:181], v[118:119] op_sel_hi:[1,0] neg_lo:[0,1] neg_hi:[0,1]
	v_pk_add_f32 v[188:189], v[188:189], v[118:119] op_sel:[0,1] op_sel_hi:[1,1] neg_lo:[0,1] neg_hi:[0,1]
	v_pk_add_f32 v[182:183], v[182:183], v[118:119] op_sel_hi:[1,0] neg_lo:[0,1] neg_hi:[0,1]
	v_pk_add_f32 v[190:191], v[190:191], v[118:119] op_sel:[0,1] op_sel_hi:[1,1] neg_lo:[0,1] neg_hi:[0,1]
	v_pk_add_f32 v[184:185], v[184:185], v[118:119] op_sel_hi:[1,0] neg_lo:[0,1] neg_hi:[0,1]
	v_pk_add_f32 v[192:193], v[192:193], v[118:119] op_sel:[0,1] op_sel_hi:[1,1] neg_lo:[0,1] neg_hi:[0,1]
	s_waitcnt lgkmcnt(8)
	v_pk_fma_f32 v[178:179], v[72:73], v[178:179], v[118:119] op_sel_hi:[1,1,0]
	v_pk_fma_f32 v[186:187], v[72:73], v[186:187], v[118:119] op_sel:[0,0,1] op_sel_hi:[1,1,1]
	v_pk_fma_f32 v[180:181], v[74:75], v[180:181], v[118:119] op_sel_hi:[1,1,0]
	v_pk_fma_f32 v[188:189], v[74:75], v[188:189], v[118:119] op_sel:[0,0,1] op_sel_hi:[1,1,1]
	s_waitcnt lgkmcnt(7)
	v_pk_fma_f32 v[182:183], v[76:77], v[182:183], v[118:119] op_sel_hi:[1,1,0]
	v_pk_fma_f32 v[190:191], v[76:77], v[190:191], v[118:119] op_sel:[0,0,1] op_sel_hi:[1,1,1]
	v_pk_fma_f32 v[184:185], v[78:79], v[184:185], v[118:119] op_sel_hi:[1,1,0]
	v_pk_fma_f32 v[192:193], v[78:79], v[192:193], v[118:119] op_sel:[0,0,1] op_sel_hi:[1,1,1]
	s_waitcnt lgkmcnt(6)
	v_pk_fma_f32 v[146:147], v[64:65], v[178:179], v[196:197]
	v_pk_fma_f32 v[150:151], v[64:65], v[186:187], v[196:197]
	v_pk_fma_f32 v[148:149], v[66:67], v[180:181], v[196:197]
	v_pk_fma_f32 v[152:153], v[66:67], v[188:189], v[196:197]
	s_waitcnt lgkmcnt(5)
	v_pk_fma_f32 v[146:147], v[68:69], v[182:183], v[146:147]
	v_pk_fma_f32 v[150:151], v[68:69], v[190:191], v[150:151]
	v_pk_fma_f32 v[148:149], v[70:71], v[184:185], v[148:149]
	v_pk_fma_f32 v[152:153], v[70:71], v[192:193], v[152:153]
	v_add_f32_e32 v146, v146, v147
	v_add_f32_e32 v148, v148, v149
	v_add_f32_e32 v150, v150, v151
	v_add_f32_e32 v152, v152, v153
	v_add_f32_e32 v154, v146, v148
	v_add_f32_e32 v155, v150, v152
	ds_read2_b32 v[118:119], v194 offset0:64 offset1:80
	ds_read_b128 v[72:75], v145 offset:27648
	ds_read_b128 v[76:79], v145 offset:27904
	ds_read_b128 v[64:67], v145 offset:19456
	ds_read_b128 v[68:71], v145 offset:19712
	s_waitcnt lgkmcnt(9)
	v_pk_add_f32 v[178:179], v[178:179], v[120:121] op_sel_hi:[1,0] neg_lo:[0,1] neg_hi:[0,1]
	v_add_f32_dpp v154, v154, v154 row_ror:8 row_mask:0xf bank_mask:0xf bound_ctrl:1
	v_pk_add_f32 v[186:187], v[186:187], v[120:121] op_sel:[0,1] op_sel_hi:[1,1] neg_lo:[0,1] neg_hi:[0,1]
	v_add_f32_dpp v155, v155, v155 row_ror:8 row_mask:0xf bank_mask:0xf bound_ctrl:1
	v_pk_add_f32 v[180:181], v[180:181], v[120:121] op_sel_hi:[1,0] neg_lo:[0,1] neg_hi:[0,1]
	v_add_f32_dpp v154, v154, v154 row_ror:4 row_mask:0xf bank_mask:0xf bound_ctrl:1
	v_pk_add_f32 v[188:189], v[188:189], v[120:121] op_sel:[0,1] op_sel_hi:[1,1] neg_lo:[0,1] neg_hi:[0,1]
	v_add_f32_dpp v155, v155, v155 row_ror:4 row_mask:0xf bank_mask:0xf bound_ctrl:1
	v_pk_add_f32 v[182:183], v[182:183], v[120:121] op_sel_hi:[1,0] neg_lo:[0,1] neg_hi:[0,1]
	v_add_f32_dpp v154, v154, v154 row_ror:2 row_mask:0xf bank_mask:0xf bound_ctrl:1
	v_pk_add_f32 v[190:191], v[190:191], v[120:121] op_sel:[0,1] op_sel_hi:[1,1] neg_lo:[0,1] neg_hi:[0,1]
	v_add_f32_dpp v155, v155, v155 row_ror:2 row_mask:0xf bank_mask:0xf bound_ctrl:1
	v_pk_add_f32 v[184:185], v[184:185], v[120:121] op_sel_hi:[1,0] neg_lo:[0,1] neg_hi:[0,1]
	v_add_f32_dpp v154, v154, v154 row_ror:1 row_mask:0xf bank_mask:0xf bound_ctrl:1
	v_pk_add_f32 v[192:193], v[192:193], v[120:121] op_sel:[0,1] op_sel_hi:[1,1] neg_lo:[0,1] neg_hi:[0,1]
	v_add_f32_dpp v155, v155, v155 row_ror:1 row_mask:0xf bank_mask:0xf bound_ctrl:1
	s_waitcnt lgkmcnt(8)
	v_pk_fma_f32 v[178:179], v[88:89], v[178:179], v[120:121] op_sel_hi:[1,1,0]
	ds_write_b32 v103, v154 offset:38912
	v_pk_fma_f32 v[186:187], v[88:89], v[186:187], v[120:121] op_sel:[0,0,1] op_sel_hi:[1,1,1]
	ds_write_b32 v103, v155 offset:38976
	v_pk_fma_f32 v[180:181], v[90:91], v[180:181], v[120:121] op_sel_hi:[1,1,0]
	v_pk_fma_f32 v[188:189], v[90:91], v[188:189], v[120:121] op_sel:[0,0,1] op_sel_hi:[1,1,1]
	s_waitcnt lgkmcnt(9)
	v_pk_fma_f32 v[182:183], v[92:93], v[182:183], v[120:121] op_sel_hi:[1,1,0]
	v_pk_fma_f32 v[190:191], v[92:93], v[190:191], v[120:121] op_sel:[0,0,1] op_sel_hi:[1,1,1]
	v_pk_fma_f32 v[184:185], v[94:95], v[184:185], v[120:121] op_sel_hi:[1,1,0]
	v_pk_fma_f32 v[192:193], v[94:95], v[192:193], v[120:121] op_sel:[0,0,1] op_sel_hi:[1,1,1]
	s_waitcnt lgkmcnt(8)
	v_pk_fma_f32 v[146:147], v[80:81], v[178:179], v[196:197]
	v_pk_fma_f32 v[150:151], v[80:81], v[186:187], v[196:197]
	v_pk_fma_f32 v[148:149], v[82:83], v[180:181], v[196:197]
	v_pk_fma_f32 v[152:153], v[82:83], v[188:189], v[196:197]
	s_waitcnt lgkmcnt(7)
	v_pk_fma_f32 v[146:147], v[84:85], v[182:183], v[146:147]
	v_pk_fma_f32 v[150:151], v[84:85], v[190:191], v[150:151]
	v_pk_fma_f32 v[148:149], v[86:87], v[184:185], v[148:149]
	v_pk_fma_f32 v[152:153], v[86:87], v[192:193], v[152:153]
	v_add_f32_e32 v146, v146, v147
	v_add_f32_e32 v148, v148, v149
	v_add_f32_e32 v150, v150, v151
	v_add_f32_e32 v152, v152, v153
	v_add_f32_e32 v156, v146, v148
	v_add_f32_e32 v157, v150, v152
	ds_read2_b32 v[120:121], v194 offset0:96 offset1:112
	ds_read_b128 v[88:91], v145 offset:28160
	ds_read_b128 v[92:95], v145 offset:28416
	ds_read_b128 v[80:83], v145 offset:19968
	ds_read_b128 v[84:87], v145 offset:20224
	s_waitcnt lgkmcnt(11)
	v_pk_add_f32 v[178:179], v[178:179], v[118:119] op_sel_hi:[1,0] neg_lo:[0,1] neg_hi:[0,1]
	v_add_f32_dpp v156, v156, v156 row_ror:8 row_mask:0xf bank_mask:0xf bound_ctrl:1
	v_pk_add_f32 v[186:187], v[186:187], v[118:119] op_sel:[0,1] op_sel_hi:[1,1] neg_lo:[0,1] neg_hi:[0,1]
	v_add_f32_dpp v157, v157, v157 row_ror:8 row_mask:0xf bank_mask:0xf bound_ctrl:1
	v_pk_add_f32 v[180:181], v[180:181], v[118:119] op_sel_hi:[1,0] neg_lo:[0,1] neg_hi:[0,1]
	v_add_f32_dpp v156, v156, v156 row_ror:4 row_mask:0xf bank_mask:0xf bound_ctrl:1
	v_pk_add_f32 v[188:189], v[188:189], v[118:119] op_sel:[0,1] op_sel_hi:[1,1] neg_lo:[0,1] neg_hi:[0,1]
	v_add_f32_dpp v157, v157, v157 row_ror:4 row_mask:0xf bank_mask:0xf bound_ctrl:1
	v_pk_add_f32 v[182:183], v[182:183], v[118:119] op_sel_hi:[1,0] neg_lo:[0,1] neg_hi:[0,1]
	v_add_f32_dpp v156, v156, v156 row_ror:2 row_mask:0xf bank_mask:0xf bound_ctrl:1
	v_pk_add_f32 v[190:191], v[190:191], v[118:119] op_sel:[0,1] op_sel_hi:[1,1] neg_lo:[0,1] neg_hi:[0,1]
	v_add_f32_dpp v157, v157, v157 row_ror:2 row_mask:0xf bank_mask:0xf bound_ctrl:1
	v_pk_add_f32 v[184:185], v[184:185], v[118:119] op_sel_hi:[1,0] neg_lo:[0,1] neg_hi:[0,1]
	v_add_f32_dpp v156, v156, v156 row_ror:1 row_mask:0xf bank_mask:0xf bound_ctrl:1
	v_pk_add_f32 v[192:193], v[192:193], v[118:119] op_sel:[0,1] op_sel_hi:[1,1] neg_lo:[0,1] neg_hi:[0,1]
	v_add_f32_dpp v157, v157, v157 row_ror:1 row_mask:0xf bank_mask:0xf bound_ctrl:1
	s_waitcnt lgkmcnt(10)
	v_pk_fma_f32 v[178:179], v[72:73], v[178:179], v[118:119] op_sel_hi:[1,1,0]
	ds_write_b32 v103, v156 offset:39040
	v_pk_fma_f32 v[186:187], v[72:73], v[186:187], v[118:119] op_sel:[0,0,1] op_sel_hi:[1,1,1]
	ds_write_b32 v103, v157 offset:39104
	v_pk_fma_f32 v[180:181], v[74:75], v[180:181], v[118:119] op_sel_hi:[1,1,0]
	v_pk_fma_f32 v[188:189], v[74:75], v[188:189], v[118:119] op_sel:[0,0,1] op_sel_hi:[1,1,1]
	s_waitcnt lgkmcnt(11)
	v_pk_fma_f32 v[182:183], v[76:77], v[182:183], v[118:119] op_sel_hi:[1,1,0]
	v_pk_fma_f32 v[190:191], v[76:77], v[190:191], v[118:119] op_sel:[0,0,1] op_sel_hi:[1,1,1]
	v_pk_fma_f32 v[184:185], v[78:79], v[184:185], v[118:119] op_sel_hi:[1,1,0]
	v_pk_fma_f32 v[192:193], v[78:79], v[192:193], v[118:119] op_sel:[0,0,1] op_sel_hi:[1,1,1]
	s_waitcnt lgkmcnt(10)
	v_pk_fma_f32 v[146:147], v[64:65], v[178:179], v[196:197]
	v_pk_fma_f32 v[150:151], v[64:65], v[186:187], v[196:197]
	v_pk_fma_f32 v[148:149], v[66:67], v[180:181], v[196:197]
	v_pk_fma_f32 v[152:153], v[66:67], v[188:189], v[196:197]
	s_waitcnt lgkmcnt(9)
	v_pk_fma_f32 v[146:147], v[68:69], v[182:183], v[146:147]
	v_pk_fma_f32 v[150:151], v[68:69], v[190:191], v[150:151]
	v_pk_fma_f32 v[148:149], v[70:71], v[184:185], v[148:149]
	v_pk_fma_f32 v[152:153], v[70:71], v[192:193], v[152:153]
	v_add_f32_e32 v146, v146, v147
	v_add_f32_e32 v148, v148, v149
	v_add_f32_e32 v150, v150, v151
	v_add_f32_e32 v152, v152, v153
	v_add_f32_e32 v154, v146, v148
	v_add_f32_e32 v155, v150, v152
	ds_read2_b32 v[118:119], v194 offset0:128 offset1:144
	ds_read_b128 v[72:75], v145 offset:28672
	ds_read_b128 v[76:79], v145 offset:28928
	ds_read_b128 v[64:67], v145 offset:20480
	ds_read_b128 v[68:71], v145 offset:20736
	s_waitcnt lgkmcnt(11)
	v_pk_add_f32 v[178:179], v[178:179], v[120:121] op_sel_hi:[1,0] neg_lo:[0,1] neg_hi:[0,1]
	v_add_f32_dpp v154, v154, v154 row_ror:8 row_mask:0xf bank_mask:0xf bound_ctrl:1
	v_pk_add_f32 v[186:187], v[186:187], v[120:121] op_sel:[0,1] op_sel_hi:[1,1] neg_lo:[0,1] neg_hi:[0,1]
	v_add_f32_dpp v155, v155, v155 row_ror:8 row_mask:0xf bank_mask:0xf bound_ctrl:1
	v_pk_add_f32 v[180:181], v[180:181], v[120:121] op_sel_hi:[1,0] neg_lo:[0,1] neg_hi:[0,1]
	v_add_f32_dpp v154, v154, v154 row_ror:4 row_mask:0xf bank_mask:0xf bound_ctrl:1
	v_pk_add_f32 v[188:189], v[188:189], v[120:121] op_sel:[0,1] op_sel_hi:[1,1] neg_lo:[0,1] neg_hi:[0,1]
	v_add_f32_dpp v155, v155, v155 row_ror:4 row_mask:0xf bank_mask:0xf bound_ctrl:1
	v_pk_add_f32 v[182:183], v[182:183], v[120:121] op_sel_hi:[1,0] neg_lo:[0,1] neg_hi:[0,1]
	v_add_f32_dpp v154, v154, v154 row_ror:2 row_mask:0xf bank_mask:0xf bound_ctrl:1
	v_pk_add_f32 v[190:191], v[190:191], v[120:121] op_sel:[0,1] op_sel_hi:[1,1] neg_lo:[0,1] neg_hi:[0,1]
	v_add_f32_dpp v155, v155, v155 row_ror:2 row_mask:0xf bank_mask:0xf bound_ctrl:1
	v_pk_add_f32 v[184:185], v[184:185], v[120:121] op_sel_hi:[1,0] neg_lo:[0,1] neg_hi:[0,1]
	v_add_f32_dpp v154, v154, v154 row_ror:1 row_mask:0xf bank_mask:0xf bound_ctrl:1
	v_pk_add_f32 v[192:193], v[192:193], v[120:121] op_sel:[0,1] op_sel_hi:[1,1] neg_lo:[0,1] neg_hi:[0,1]
	v_add_f32_dpp v155, v155, v155 row_ror:1 row_mask:0xf bank_mask:0xf bound_ctrl:1
	s_waitcnt lgkmcnt(10)
	v_pk_fma_f32 v[178:179], v[88:89], v[178:179], v[120:121] op_sel_hi:[1,1,0]
	ds_write_b32 v103, v154 offset:39168
	v_pk_fma_f32 v[186:187], v[88:89], v[186:187], v[120:121] op_sel:[0,0,1] op_sel_hi:[1,1,1]
	ds_write_b32 v103, v155 offset:39232
	v_pk_fma_f32 v[180:181], v[90:91], v[180:181], v[120:121] op_sel_hi:[1,1,0]
	v_pk_fma_f32 v[188:189], v[90:91], v[188:189], v[120:121] op_sel:[0,0,1] op_sel_hi:[1,1,1]
	s_waitcnt lgkmcnt(11)
	v_pk_fma_f32 v[182:183], v[92:93], v[182:183], v[120:121] op_sel_hi:[1,1,0]
	v_pk_fma_f32 v[190:191], v[92:93], v[190:191], v[120:121] op_sel:[0,0,1] op_sel_hi:[1,1,1]
	v_pk_fma_f32 v[184:185], v[94:95], v[184:185], v[120:121] op_sel_hi:[1,1,0]
	v_pk_fma_f32 v[192:193], v[94:95], v[192:193], v[120:121] op_sel:[0,0,1] op_sel_hi:[1,1,1]
	s_waitcnt lgkmcnt(10)
	v_pk_fma_f32 v[146:147], v[80:81], v[178:179], v[196:197]
	v_pk_fma_f32 v[150:151], v[80:81], v[186:187], v[196:197]
	v_pk_fma_f32 v[148:149], v[82:83], v[180:181], v[196:197]
	v_pk_fma_f32 v[152:153], v[82:83], v[188:189], v[196:197]
	s_waitcnt lgkmcnt(9)
	v_pk_fma_f32 v[146:147], v[84:85], v[182:183], v[146:147]
	v_pk_fma_f32 v[150:151], v[84:85], v[190:191], v[150:151]
	v_pk_fma_f32 v[148:149], v[86:87], v[184:185], v[148:149]
	v_pk_fma_f32 v[152:153], v[86:87], v[192:193], v[152:153]
	v_add_f32_e32 v146, v146, v147
	v_add_f32_e32 v148, v148, v149
	v_add_f32_e32 v150, v150, v151
	v_add_f32_e32 v152, v152, v153
	v_add_f32_e32 v156, v146, v148
	v_add_f32_e32 v157, v150, v152
	ds_read2_b32 v[120:121], v194 offset0:160 offset1:176
	ds_read_b128 v[88:91], v145 offset:29184
	ds_read_b128 v[92:95], v145 offset:29440
	ds_read_b128 v[80:83], v145 offset:20992
	ds_read_b128 v[84:87], v145 offset:21248
	s_waitcnt lgkmcnt(11)
	v_pk_add_f32 v[178:179], v[178:179], v[118:119] op_sel_hi:[1,0] neg_lo:[0,1] neg_hi:[0,1]
	v_add_f32_dpp v156, v156, v156 row_ror:8 row_mask:0xf bank_mask:0xf bound_ctrl:1
	v_pk_add_f32 v[186:187], v[186:187], v[118:119] op_sel:[0,1] op_sel_hi:[1,1] neg_lo:[0,1] neg_hi:[0,1]
	v_add_f32_dpp v157, v157, v157 row_ror:8 row_mask:0xf bank_mask:0xf bound_ctrl:1
	v_pk_add_f32 v[180:181], v[180:181], v[118:119] op_sel_hi:[1,0] neg_lo:[0,1] neg_hi:[0,1]
	v_add_f32_dpp v156, v156, v156 row_ror:4 row_mask:0xf bank_mask:0xf bound_ctrl:1
	v_pk_add_f32 v[188:189], v[188:189], v[118:119] op_sel:[0,1] op_sel_hi:[1,1] neg_lo:[0,1] neg_hi:[0,1]
	v_add_f32_dpp v157, v157, v157 row_ror:4 row_mask:0xf bank_mask:0xf bound_ctrl:1
	v_pk_add_f32 v[182:183], v[182:183], v[118:119] op_sel_hi:[1,0] neg_lo:[0,1] neg_hi:[0,1]
	v_add_f32_dpp v156, v156, v156 row_ror:2 row_mask:0xf bank_mask:0xf bound_ctrl:1
	v_pk_add_f32 v[190:191], v[190:191], v[118:119] op_sel:[0,1] op_sel_hi:[1,1] neg_lo:[0,1] neg_hi:[0,1]
	v_add_f32_dpp v157, v157, v157 row_ror:2 row_mask:0xf bank_mask:0xf bound_ctrl:1
	v_pk_add_f32 v[184:185], v[184:185], v[118:119] op_sel_hi:[1,0] neg_lo:[0,1] neg_hi:[0,1]
	v_add_f32_dpp v156, v156, v156 row_ror:1 row_mask:0xf bank_mask:0xf bound_ctrl:1
	v_pk_add_f32 v[192:193], v[192:193], v[118:119] op_sel:[0,1] op_sel_hi:[1,1] neg_lo:[0,1] neg_hi:[0,1]
	v_add_f32_dpp v157, v157, v157 row_ror:1 row_mask:0xf bank_mask:0xf bound_ctrl:1
	s_waitcnt lgkmcnt(10)
	v_pk_fma_f32 v[178:179], v[72:73], v[178:179], v[118:119] op_sel_hi:[1,1,0]
	ds_write_b32 v103, v156 offset:39296
	v_pk_fma_f32 v[186:187], v[72:73], v[186:187], v[118:119] op_sel:[0,0,1] op_sel_hi:[1,1,1]
	ds_write_b32 v103, v157 offset:39360
	v_pk_fma_f32 v[180:181], v[74:75], v[180:181], v[118:119] op_sel_hi:[1,1,0]
	v_pk_fma_f32 v[188:189], v[74:75], v[188:189], v[118:119] op_sel:[0,0,1] op_sel_hi:[1,1,1]
	s_waitcnt lgkmcnt(11)
	v_pk_fma_f32 v[182:183], v[76:77], v[182:183], v[118:119] op_sel_hi:[1,1,0]
	v_pk_fma_f32 v[190:191], v[76:77], v[190:191], v[118:119] op_sel:[0,0,1] op_sel_hi:[1,1,1]
	v_pk_fma_f32 v[184:185], v[78:79], v[184:185], v[118:119] op_sel_hi:[1,1,0]
	v_pk_fma_f32 v[192:193], v[78:79], v[192:193], v[118:119] op_sel:[0,0,1] op_sel_hi:[1,1,1]
	s_waitcnt lgkmcnt(10)
	v_pk_fma_f32 v[146:147], v[64:65], v[178:179], v[196:197]
	v_pk_fma_f32 v[150:151], v[64:65], v[186:187], v[196:197]
	v_pk_fma_f32 v[148:149], v[66:67], v[180:181], v[196:197]
	v_pk_fma_f32 v[152:153], v[66:67], v[188:189], v[196:197]
	s_waitcnt lgkmcnt(9)
	v_pk_fma_f32 v[146:147], v[68:69], v[182:183], v[146:147]
	v_pk_fma_f32 v[150:151], v[68:69], v[190:191], v[150:151]
	v_pk_fma_f32 v[148:149], v[70:71], v[184:185], v[148:149]
	v_pk_fma_f32 v[152:153], v[70:71], v[192:193], v[152:153]
	v_add_f32_e32 v146, v146, v147
	v_add_f32_e32 v148, v148, v149
	v_add_f32_e32 v150, v150, v151
	v_add_f32_e32 v152, v152, v153
	v_add_f32_e32 v154, v146, v148
	v_add_f32_e32 v155, v150, v152
	ds_read2_b32 v[118:119], v194 offset0:192 offset1:208
	ds_read_b128 v[72:75], v145 offset:29696
	ds_read_b128 v[76:79], v145 offset:29952
	ds_read_b128 v[64:67], v145 offset:21504
	ds_read_b128 v[68:71], v145 offset:21760
	s_waitcnt lgkmcnt(11)
	v_pk_add_f32 v[178:179], v[178:179], v[120:121] op_sel_hi:[1,0] neg_lo:[0,1] neg_hi:[0,1]
	v_add_f32_dpp v154, v154, v154 row_ror:8 row_mask:0xf bank_mask:0xf bound_ctrl:1
	v_pk_add_f32 v[186:187], v[186:187], v[120:121] op_sel:[0,1] op_sel_hi:[1,1] neg_lo:[0,1] neg_hi:[0,1]
	v_add_f32_dpp v155, v155, v155 row_ror:8 row_mask:0xf bank_mask:0xf bound_ctrl:1
	v_pk_add_f32 v[180:181], v[180:181], v[120:121] op_sel_hi:[1,0] neg_lo:[0,1] neg_hi:[0,1]
	v_add_f32_dpp v154, v154, v154 row_ror:4 row_mask:0xf bank_mask:0xf bound_ctrl:1
	v_pk_add_f32 v[188:189], v[188:189], v[120:121] op_sel:[0,1] op_sel_hi:[1,1] neg_lo:[0,1] neg_hi:[0,1]
	v_add_f32_dpp v155, v155, v155 row_ror:4 row_mask:0xf bank_mask:0xf bound_ctrl:1
	v_pk_add_f32 v[182:183], v[182:183], v[120:121] op_sel_hi:[1,0] neg_lo:[0,1] neg_hi:[0,1]
	v_add_f32_dpp v154, v154, v154 row_ror:2 row_mask:0xf bank_mask:0xf bound_ctrl:1
	v_pk_add_f32 v[190:191], v[190:191], v[120:121] op_sel:[0,1] op_sel_hi:[1,1] neg_lo:[0,1] neg_hi:[0,1]
	v_add_f32_dpp v155, v155, v155 row_ror:2 row_mask:0xf bank_mask:0xf bound_ctrl:1
	v_pk_add_f32 v[184:185], v[184:185], v[120:121] op_sel_hi:[1,0] neg_lo:[0,1] neg_hi:[0,1]
	v_add_f32_dpp v154, v154, v154 row_ror:1 row_mask:0xf bank_mask:0xf bound_ctrl:1
	v_pk_add_f32 v[192:193], v[192:193], v[120:121] op_sel:[0,1] op_sel_hi:[1,1] neg_lo:[0,1] neg_hi:[0,1]
	v_add_f32_dpp v155, v155, v155 row_ror:1 row_mask:0xf bank_mask:0xf bound_ctrl:1
	s_waitcnt lgkmcnt(10)
	v_pk_fma_f32 v[178:179], v[88:89], v[178:179], v[120:121] op_sel_hi:[1,1,0]
	ds_write_b32 v103, v154 offset:39424
	v_pk_fma_f32 v[186:187], v[88:89], v[186:187], v[120:121] op_sel:[0,0,1] op_sel_hi:[1,1,1]
	ds_write_b32 v103, v155 offset:39488
	v_pk_fma_f32 v[180:181], v[90:91], v[180:181], v[120:121] op_sel_hi:[1,1,0]
	v_pk_fma_f32 v[188:189], v[90:91], v[188:189], v[120:121] op_sel:[0,0,1] op_sel_hi:[1,1,1]
	s_waitcnt lgkmcnt(11)
	v_pk_fma_f32 v[182:183], v[92:93], v[182:183], v[120:121] op_sel_hi:[1,1,0]
	v_pk_fma_f32 v[190:191], v[92:93], v[190:191], v[120:121] op_sel:[0,0,1] op_sel_hi:[1,1,1]
	v_pk_fma_f32 v[184:185], v[94:95], v[184:185], v[120:121] op_sel_hi:[1,1,0]
	v_pk_fma_f32 v[192:193], v[94:95], v[192:193], v[120:121] op_sel:[0,0,1] op_sel_hi:[1,1,1]
	s_waitcnt lgkmcnt(10)
	v_pk_fma_f32 v[146:147], v[80:81], v[178:179], v[196:197]
	v_pk_fma_f32 v[150:151], v[80:81], v[186:187], v[196:197]
	v_pk_fma_f32 v[148:149], v[82:83], v[180:181], v[196:197]
	v_pk_fma_f32 v[152:153], v[82:83], v[188:189], v[196:197]
	s_waitcnt lgkmcnt(9)
	v_pk_fma_f32 v[146:147], v[84:85], v[182:183], v[146:147]
	v_pk_fma_f32 v[150:151], v[84:85], v[190:191], v[150:151]
	v_pk_fma_f32 v[148:149], v[86:87], v[184:185], v[148:149]
	v_pk_fma_f32 v[152:153], v[86:87], v[192:193], v[152:153]
	v_add_f32_e32 v146, v146, v147
	v_add_f32_e32 v148, v148, v149
	v_add_f32_e32 v150, v150, v151
	v_add_f32_e32 v152, v152, v153
	v_add_f32_e32 v156, v146, v148
	v_add_f32_e32 v157, v150, v152
	ds_read2_b32 v[120:121], v194 offset0:224 offset1:240
	ds_read_b128 v[88:91], v145 offset:30208
	ds_read_b128 v[92:95], v145 offset:30464
	ds_read_b128 v[80:83], v145 offset:22016
	ds_read_b128 v[84:87], v145 offset:22272
	s_waitcnt lgkmcnt(11)
	v_pk_add_f32 v[178:179], v[178:179], v[118:119] op_sel_hi:[1,0] neg_lo:[0,1] neg_hi:[0,1]
	v_add_f32_dpp v156, v156, v156 row_ror:8 row_mask:0xf bank_mask:0xf bound_ctrl:1
	v_pk_add_f32 v[186:187], v[186:187], v[118:119] op_sel:[0,1] op_sel_hi:[1,1] neg_lo:[0,1] neg_hi:[0,1]
	v_add_f32_dpp v157, v157, v157 row_ror:8 row_mask:0xf bank_mask:0xf bound_ctrl:1
	v_pk_add_f32 v[180:181], v[180:181], v[118:119] op_sel_hi:[1,0] neg_lo:[0,1] neg_hi:[0,1]
	v_add_f32_dpp v156, v156, v156 row_ror:4 row_mask:0xf bank_mask:0xf bound_ctrl:1
	v_pk_add_f32 v[188:189], v[188:189], v[118:119] op_sel:[0,1] op_sel_hi:[1,1] neg_lo:[0,1] neg_hi:[0,1]
	v_add_f32_dpp v157, v157, v157 row_ror:4 row_mask:0xf bank_mask:0xf bound_ctrl:1
	v_pk_add_f32 v[182:183], v[182:183], v[118:119] op_sel_hi:[1,0] neg_lo:[0,1] neg_hi:[0,1]
	v_add_f32_dpp v156, v156, v156 row_ror:2 row_mask:0xf bank_mask:0xf bound_ctrl:1
	v_pk_add_f32 v[190:191], v[190:191], v[118:119] op_sel:[0,1] op_sel_hi:[1,1] neg_lo:[0,1] neg_hi:[0,1]
	v_add_f32_dpp v157, v157, v157 row_ror:2 row_mask:0xf bank_mask:0xf bound_ctrl:1
	v_pk_add_f32 v[184:185], v[184:185], v[118:119] op_sel_hi:[1,0] neg_lo:[0,1] neg_hi:[0,1]
	v_add_f32_dpp v156, v156, v156 row_ror:1 row_mask:0xf bank_mask:0xf bound_ctrl:1
	v_pk_add_f32 v[192:193], v[192:193], v[118:119] op_sel:[0,1] op_sel_hi:[1,1] neg_lo:[0,1] neg_hi:[0,1]
	v_add_f32_dpp v157, v157, v157 row_ror:1 row_mask:0xf bank_mask:0xf bound_ctrl:1
	s_waitcnt lgkmcnt(10)
	v_pk_fma_f32 v[178:179], v[72:73], v[178:179], v[118:119] op_sel_hi:[1,1,0]
	ds_write_b32 v103, v156 offset:39552
	v_pk_fma_f32 v[186:187], v[72:73], v[186:187], v[118:119] op_sel:[0,0,1] op_sel_hi:[1,1,1]
	ds_write_b32 v103, v157 offset:39616
	v_pk_fma_f32 v[180:181], v[74:75], v[180:181], v[118:119] op_sel_hi:[1,1,0]
	v_pk_fma_f32 v[188:189], v[74:75], v[188:189], v[118:119] op_sel:[0,0,1] op_sel_hi:[1,1,1]
	s_waitcnt lgkmcnt(11)
	v_pk_fma_f32 v[182:183], v[76:77], v[182:183], v[118:119] op_sel_hi:[1,1,0]
	v_pk_fma_f32 v[190:191], v[76:77], v[190:191], v[118:119] op_sel:[0,0,1] op_sel_hi:[1,1,1]
	v_pk_fma_f32 v[184:185], v[78:79], v[184:185], v[118:119] op_sel_hi:[1,1,0]
	v_pk_fma_f32 v[192:193], v[78:79], v[192:193], v[118:119] op_sel:[0,0,1] op_sel_hi:[1,1,1]
	s_waitcnt lgkmcnt(10)
	v_pk_fma_f32 v[146:147], v[64:65], v[178:179], v[196:197]
	v_pk_fma_f32 v[150:151], v[64:65], v[186:187], v[196:197]
	v_pk_fma_f32 v[148:149], v[66:67], v[180:181], v[196:197]
	v_pk_fma_f32 v[152:153], v[66:67], v[188:189], v[196:197]
	s_waitcnt lgkmcnt(9)
	v_pk_fma_f32 v[146:147], v[68:69], v[182:183], v[146:147]
	v_pk_fma_f32 v[150:151], v[68:69], v[190:191], v[150:151]
	v_pk_fma_f32 v[148:149], v[70:71], v[184:185], v[148:149]
	v_pk_fma_f32 v[152:153], v[70:71], v[192:193], v[152:153]
	v_add_f32_e32 v146, v146, v147
	v_add_f32_e32 v148, v148, v149
	v_add_f32_e32 v150, v150, v151
	v_add_f32_e32 v152, v152, v153
	v_add_f32_e32 v154, v146, v148
	v_add_f32_e32 v155, v150, v152
	ds_read2_b32 v[118:119], v195 offset0:0 offset1:16
	ds_read_b128 v[72:75], v145 offset:30720
	ds_read_b128 v[76:79], v145 offset:30976
	ds_read_b128 v[64:67], v145 offset:22528
	ds_read_b128 v[68:71], v145 offset:22784
	s_waitcnt lgkmcnt(11)
	v_pk_add_f32 v[178:179], v[178:179], v[120:121] op_sel_hi:[1,0] neg_lo:[0,1] neg_hi:[0,1]
	v_add_f32_dpp v154, v154, v154 row_ror:8 row_mask:0xf bank_mask:0xf bound_ctrl:1
	v_pk_add_f32 v[186:187], v[186:187], v[120:121] op_sel:[0,1] op_sel_hi:[1,1] neg_lo:[0,1] neg_hi:[0,1]
	v_add_f32_dpp v155, v155, v155 row_ror:8 row_mask:0xf bank_mask:0xf bound_ctrl:1
	v_pk_add_f32 v[180:181], v[180:181], v[120:121] op_sel_hi:[1,0] neg_lo:[0,1] neg_hi:[0,1]
	v_add_f32_dpp v154, v154, v154 row_ror:4 row_mask:0xf bank_mask:0xf bound_ctrl:1
	v_pk_add_f32 v[188:189], v[188:189], v[120:121] op_sel:[0,1] op_sel_hi:[1,1] neg_lo:[0,1] neg_hi:[0,1]
	v_add_f32_dpp v155, v155, v155 row_ror:4 row_mask:0xf bank_mask:0xf bound_ctrl:1
	v_pk_add_f32 v[182:183], v[182:183], v[120:121] op_sel_hi:[1,0] neg_lo:[0,1] neg_hi:[0,1]
	v_add_f32_dpp v154, v154, v154 row_ror:2 row_mask:0xf bank_mask:0xf bound_ctrl:1
	v_pk_add_f32 v[190:191], v[190:191], v[120:121] op_sel:[0,1] op_sel_hi:[1,1] neg_lo:[0,1] neg_hi:[0,1]
	v_add_f32_dpp v155, v155, v155 row_ror:2 row_mask:0xf bank_mask:0xf bound_ctrl:1
	v_pk_add_f32 v[184:185], v[184:185], v[120:121] op_sel_hi:[1,0] neg_lo:[0,1] neg_hi:[0,1]
	v_add_f32_dpp v154, v154, v154 row_ror:1 row_mask:0xf bank_mask:0xf bound_ctrl:1
	v_pk_add_f32 v[192:193], v[192:193], v[120:121] op_sel:[0,1] op_sel_hi:[1,1] neg_lo:[0,1] neg_hi:[0,1]
	v_add_f32_dpp v155, v155, v155 row_ror:1 row_mask:0xf bank_mask:0xf bound_ctrl:1
	s_waitcnt lgkmcnt(10)
	v_pk_fma_f32 v[178:179], v[88:89], v[178:179], v[120:121] op_sel_hi:[1,1,0]
	ds_write_b32 v103, v154 offset:39680
	v_pk_fma_f32 v[186:187], v[88:89], v[186:187], v[120:121] op_sel:[0,0,1] op_sel_hi:[1,1,1]
	ds_write_b32 v103, v155 offset:39744
	v_pk_fma_f32 v[180:181], v[90:91], v[180:181], v[120:121] op_sel_hi:[1,1,0]
	v_pk_fma_f32 v[188:189], v[90:91], v[188:189], v[120:121] op_sel:[0,0,1] op_sel_hi:[1,1,1]
	s_waitcnt lgkmcnt(11)
	v_pk_fma_f32 v[182:183], v[92:93], v[182:183], v[120:121] op_sel_hi:[1,1,0]
	v_pk_fma_f32 v[190:191], v[92:93], v[190:191], v[120:121] op_sel:[0,0,1] op_sel_hi:[1,1,1]
	v_pk_fma_f32 v[184:185], v[94:95], v[184:185], v[120:121] op_sel_hi:[1,1,0]
	v_pk_fma_f32 v[192:193], v[94:95], v[192:193], v[120:121] op_sel:[0,0,1] op_sel_hi:[1,1,1]
	s_waitcnt lgkmcnt(10)
	v_pk_fma_f32 v[146:147], v[80:81], v[178:179], v[196:197]
	v_pk_fma_f32 v[150:151], v[80:81], v[186:187], v[196:197]
	v_pk_fma_f32 v[148:149], v[82:83], v[180:181], v[196:197]
	v_pk_fma_f32 v[152:153], v[82:83], v[188:189], v[196:197]
	s_waitcnt lgkmcnt(9)
	v_pk_fma_f32 v[146:147], v[84:85], v[182:183], v[146:147]
	v_pk_fma_f32 v[150:151], v[84:85], v[190:191], v[150:151]
	v_pk_fma_f32 v[148:149], v[86:87], v[184:185], v[148:149]
	v_pk_fma_f32 v[152:153], v[86:87], v[192:193], v[152:153]
	v_add_f32_e32 v146, v146, v147
	v_add_f32_e32 v148, v148, v149
	v_add_f32_e32 v150, v150, v151
	v_add_f32_e32 v152, v152, v153
	v_add_f32_e32 v156, v146, v148
	v_add_f32_e32 v157, v150, v152
	ds_read2_b32 v[120:121], v195 offset0:32 offset1:48
	ds_read_b128 v[88:91], v145 offset:31232
	ds_read_b128 v[92:95], v145 offset:31488
	ds_read_b128 v[80:83], v145 offset:23040
	ds_read_b128 v[84:87], v145 offset:23296
	s_waitcnt lgkmcnt(11)
	v_pk_add_f32 v[178:179], v[178:179], v[118:119] op_sel_hi:[1,0] neg_lo:[0,1] neg_hi:[0,1]
	v_add_f32_dpp v156, v156, v156 row_ror:8 row_mask:0xf bank_mask:0xf bound_ctrl:1
	v_pk_add_f32 v[186:187], v[186:187], v[118:119] op_sel:[0,1] op_sel_hi:[1,1] neg_lo:[0,1] neg_hi:[0,1]
	v_add_f32_dpp v157, v157, v157 row_ror:8 row_mask:0xf bank_mask:0xf bound_ctrl:1
	v_pk_add_f32 v[180:181], v[180:181], v[118:119] op_sel_hi:[1,0] neg_lo:[0,1] neg_hi:[0,1]
	v_add_f32_dpp v156, v156, v156 row_ror:4 row_mask:0xf bank_mask:0xf bound_ctrl:1
	v_pk_add_f32 v[188:189], v[188:189], v[118:119] op_sel:[0,1] op_sel_hi:[1,1] neg_lo:[0,1] neg_hi:[0,1]
	v_add_f32_dpp v157, v157, v157 row_ror:4 row_mask:0xf bank_mask:0xf bound_ctrl:1
	v_pk_add_f32 v[182:183], v[182:183], v[118:119] op_sel_hi:[1,0] neg_lo:[0,1] neg_hi:[0,1]
	v_add_f32_dpp v156, v156, v156 row_ror:2 row_mask:0xf bank_mask:0xf bound_ctrl:1
	v_pk_add_f32 v[190:191], v[190:191], v[118:119] op_sel:[0,1] op_sel_hi:[1,1] neg_lo:[0,1] neg_hi:[0,1]
	v_add_f32_dpp v157, v157, v157 row_ror:2 row_mask:0xf bank_mask:0xf bound_ctrl:1
	v_pk_add_f32 v[184:185], v[184:185], v[118:119] op_sel_hi:[1,0] neg_lo:[0,1] neg_hi:[0,1]
	v_add_f32_dpp v156, v156, v156 row_ror:1 row_mask:0xf bank_mask:0xf bound_ctrl:1
	v_pk_add_f32 v[192:193], v[192:193], v[118:119] op_sel:[0,1] op_sel_hi:[1,1] neg_lo:[0,1] neg_hi:[0,1]
	v_add_f32_dpp v157, v157, v157 row_ror:1 row_mask:0xf bank_mask:0xf bound_ctrl:1
	s_waitcnt lgkmcnt(10)
	v_pk_fma_f32 v[178:179], v[72:73], v[178:179], v[118:119] op_sel_hi:[1,1,0]
	ds_write_b32 v103, v156 offset:39808
	v_pk_fma_f32 v[186:187], v[72:73], v[186:187], v[118:119] op_sel:[0,0,1] op_sel_hi:[1,1,1]
	ds_write_b32 v103, v157 offset:39872
	v_pk_fma_f32 v[180:181], v[74:75], v[180:181], v[118:119] op_sel_hi:[1,1,0]
	v_pk_fma_f32 v[188:189], v[74:75], v[188:189], v[118:119] op_sel:[0,0,1] op_sel_hi:[1,1,1]
	s_waitcnt lgkmcnt(11)
	v_pk_fma_f32 v[182:183], v[76:77], v[182:183], v[118:119] op_sel_hi:[1,1,0]
	v_pk_fma_f32 v[190:191], v[76:77], v[190:191], v[118:119] op_sel:[0,0,1] op_sel_hi:[1,1,1]
	v_pk_fma_f32 v[184:185], v[78:79], v[184:185], v[118:119] op_sel_hi:[1,1,0]
	v_pk_fma_f32 v[192:193], v[78:79], v[192:193], v[118:119] op_sel:[0,0,1] op_sel_hi:[1,1,1]
	s_waitcnt lgkmcnt(10)
	v_pk_fma_f32 v[146:147], v[64:65], v[178:179], v[196:197]
	v_pk_fma_f32 v[150:151], v[64:65], v[186:187], v[196:197]
	v_pk_fma_f32 v[148:149], v[66:67], v[180:181], v[196:197]
	v_pk_fma_f32 v[152:153], v[66:67], v[188:189], v[196:197]
	s_waitcnt lgkmcnt(9)
	v_pk_fma_f32 v[146:147], v[68:69], v[182:183], v[146:147]
	v_pk_fma_f32 v[150:151], v[68:69], v[190:191], v[150:151]
	v_pk_fma_f32 v[148:149], v[70:71], v[184:185], v[148:149]
	v_pk_fma_f32 v[152:153], v[70:71], v[192:193], v[152:153]
	v_add_f32_e32 v146, v146, v147
	v_add_f32_e32 v148, v148, v149
	v_add_f32_e32 v150, v150, v151
	v_add_f32_e32 v152, v152, v153
	v_add_f32_e32 v154, v146, v148
	v_add_f32_e32 v155, v150, v152
	ds_read2_b32 v[118:119], v195 offset0:64 offset1:80
	ds_read_b128 v[72:75], v145 offset:31744
	ds_read_b128 v[76:79], v145 offset:32000
	ds_read_b128 v[64:67], v145 offset:23552
	ds_read_b128 v[68:71], v145 offset:23808
	s_waitcnt lgkmcnt(11)
	v_pk_add_f32 v[178:179], v[178:179], v[120:121] op_sel_hi:[1,0] neg_lo:[0,1] neg_hi:[0,1]
	v_add_f32_dpp v154, v154, v154 row_ror:8 row_mask:0xf bank_mask:0xf bound_ctrl:1
	v_pk_add_f32 v[186:187], v[186:187], v[120:121] op_sel:[0,1] op_sel_hi:[1,1] neg_lo:[0,1] neg_hi:[0,1]
	v_add_f32_dpp v155, v155, v155 row_ror:8 row_mask:0xf bank_mask:0xf bound_ctrl:1
	v_pk_add_f32 v[180:181], v[180:181], v[120:121] op_sel_hi:[1,0] neg_lo:[0,1] neg_hi:[0,1]
	v_add_f32_dpp v154, v154, v154 row_ror:4 row_mask:0xf bank_mask:0xf bound_ctrl:1
	v_pk_add_f32 v[188:189], v[188:189], v[120:121] op_sel:[0,1] op_sel_hi:[1,1] neg_lo:[0,1] neg_hi:[0,1]
	v_add_f32_dpp v155, v155, v155 row_ror:4 row_mask:0xf bank_mask:0xf bound_ctrl:1
	v_pk_add_f32 v[182:183], v[182:183], v[120:121] op_sel_hi:[1,0] neg_lo:[0,1] neg_hi:[0,1]
	v_add_f32_dpp v154, v154, v154 row_ror:2 row_mask:0xf bank_mask:0xf bound_ctrl:1
	v_pk_add_f32 v[190:191], v[190:191], v[120:121] op_sel:[0,1] op_sel_hi:[1,1] neg_lo:[0,1] neg_hi:[0,1]
	v_add_f32_dpp v155, v155, v155 row_ror:2 row_mask:0xf bank_mask:0xf bound_ctrl:1
	v_pk_add_f32 v[184:185], v[184:185], v[120:121] op_sel_hi:[1,0] neg_lo:[0,1] neg_hi:[0,1]
	v_add_f32_dpp v154, v154, v154 row_ror:1 row_mask:0xf bank_mask:0xf bound_ctrl:1
	v_pk_add_f32 v[192:193], v[192:193], v[120:121] op_sel:[0,1] op_sel_hi:[1,1] neg_lo:[0,1] neg_hi:[0,1]
	v_add_f32_dpp v155, v155, v155 row_ror:1 row_mask:0xf bank_mask:0xf bound_ctrl:1
	s_waitcnt lgkmcnt(10)
	v_pk_fma_f32 v[178:179], v[88:89], v[178:179], v[120:121] op_sel_hi:[1,1,0]
	ds_write_b32 v103, v154 offset:39936
	v_pk_fma_f32 v[186:187], v[88:89], v[186:187], v[120:121] op_sel:[0,0,1] op_sel_hi:[1,1,1]
	ds_write_b32 v103, v155 offset:40000
	v_pk_fma_f32 v[180:181], v[90:91], v[180:181], v[120:121] op_sel_hi:[1,1,0]
	v_pk_fma_f32 v[188:189], v[90:91], v[188:189], v[120:121] op_sel:[0,0,1] op_sel_hi:[1,1,1]
	s_waitcnt lgkmcnt(11)
	v_pk_fma_f32 v[182:183], v[92:93], v[182:183], v[120:121] op_sel_hi:[1,1,0]
	v_pk_fma_f32 v[190:191], v[92:93], v[190:191], v[120:121] op_sel:[0,0,1] op_sel_hi:[1,1,1]
	v_pk_fma_f32 v[184:185], v[94:95], v[184:185], v[120:121] op_sel_hi:[1,1,0]
	v_pk_fma_f32 v[192:193], v[94:95], v[192:193], v[120:121] op_sel:[0,0,1] op_sel_hi:[1,1,1]
	s_waitcnt lgkmcnt(10)
	v_pk_fma_f32 v[146:147], v[80:81], v[178:179], v[196:197]
	v_pk_fma_f32 v[150:151], v[80:81], v[186:187], v[196:197]
	v_pk_fma_f32 v[148:149], v[82:83], v[180:181], v[196:197]
	v_pk_fma_f32 v[152:153], v[82:83], v[188:189], v[196:197]
	s_waitcnt lgkmcnt(9)
	v_pk_fma_f32 v[146:147], v[84:85], v[182:183], v[146:147]
	v_pk_fma_f32 v[150:151], v[84:85], v[190:191], v[150:151]
	v_pk_fma_f32 v[148:149], v[86:87], v[184:185], v[148:149]
	v_pk_fma_f32 v[152:153], v[86:87], v[192:193], v[152:153]
	v_add_f32_e32 v146, v146, v147
	v_add_f32_e32 v148, v148, v149
	v_add_f32_e32 v150, v150, v151
	v_add_f32_e32 v152, v152, v153
	v_add_f32_e32 v156, v146, v148
	v_add_f32_e32 v157, v150, v152
	ds_read2_b32 v[120:121], v195 offset0:96 offset1:112
	ds_read_b128 v[88:91], v145 offset:32256
	ds_read_b128 v[92:95], v145 offset:32512
	ds_read_b128 v[80:83], v145 offset:24064
	ds_read_b128 v[84:87], v145 offset:24320
	s_waitcnt lgkmcnt(11)
	v_pk_add_f32 v[178:179], v[178:179], v[118:119] op_sel_hi:[1,0] neg_lo:[0,1] neg_hi:[0,1]
	v_add_f32_dpp v156, v156, v156 row_ror:8 row_mask:0xf bank_mask:0xf bound_ctrl:1
	v_pk_add_f32 v[186:187], v[186:187], v[118:119] op_sel:[0,1] op_sel_hi:[1,1] neg_lo:[0,1] neg_hi:[0,1]
	v_add_f32_dpp v157, v157, v157 row_ror:8 row_mask:0xf bank_mask:0xf bound_ctrl:1
	v_pk_add_f32 v[180:181], v[180:181], v[118:119] op_sel_hi:[1,0] neg_lo:[0,1] neg_hi:[0,1]
	v_add_f32_dpp v156, v156, v156 row_ror:4 row_mask:0xf bank_mask:0xf bound_ctrl:1
	v_pk_add_f32 v[188:189], v[188:189], v[118:119] op_sel:[0,1] op_sel_hi:[1,1] neg_lo:[0,1] neg_hi:[0,1]
	v_add_f32_dpp v157, v157, v157 row_ror:4 row_mask:0xf bank_mask:0xf bound_ctrl:1
	v_pk_add_f32 v[182:183], v[182:183], v[118:119] op_sel_hi:[1,0] neg_lo:[0,1] neg_hi:[0,1]
	v_add_f32_dpp v156, v156, v156 row_ror:2 row_mask:0xf bank_mask:0xf bound_ctrl:1
	v_pk_add_f32 v[190:191], v[190:191], v[118:119] op_sel:[0,1] op_sel_hi:[1,1] neg_lo:[0,1] neg_hi:[0,1]
	v_add_f32_dpp v157, v157, v157 row_ror:2 row_mask:0xf bank_mask:0xf bound_ctrl:1
	v_pk_add_f32 v[184:185], v[184:185], v[118:119] op_sel_hi:[1,0] neg_lo:[0,1] neg_hi:[0,1]
	v_add_f32_dpp v156, v156, v156 row_ror:1 row_mask:0xf bank_mask:0xf bound_ctrl:1
	v_pk_add_f32 v[192:193], v[192:193], v[118:119] op_sel:[0,1] op_sel_hi:[1,1] neg_lo:[0,1] neg_hi:[0,1]
	v_add_f32_dpp v157, v157, v157 row_ror:1 row_mask:0xf bank_mask:0xf bound_ctrl:1
	s_waitcnt lgkmcnt(10)
	v_pk_fma_f32 v[178:179], v[72:73], v[178:179], v[118:119] op_sel_hi:[1,1,0]
	ds_write_b32 v103, v156 offset:40064
	v_pk_fma_f32 v[186:187], v[72:73], v[186:187], v[118:119] op_sel:[0,0,1] op_sel_hi:[1,1,1]
	ds_write_b32 v103, v157 offset:40128
	v_pk_fma_f32 v[180:181], v[74:75], v[180:181], v[118:119] op_sel_hi:[1,1,0]
	v_pk_fma_f32 v[188:189], v[74:75], v[188:189], v[118:119] op_sel:[0,0,1] op_sel_hi:[1,1,1]
	s_waitcnt lgkmcnt(11)
	v_pk_fma_f32 v[182:183], v[76:77], v[182:183], v[118:119] op_sel_hi:[1,1,0]
	v_pk_fma_f32 v[190:191], v[76:77], v[190:191], v[118:119] op_sel:[0,0,1] op_sel_hi:[1,1,1]
	v_pk_fma_f32 v[184:185], v[78:79], v[184:185], v[118:119] op_sel_hi:[1,1,0]
	v_pk_fma_f32 v[192:193], v[78:79], v[192:193], v[118:119] op_sel:[0,0,1] op_sel_hi:[1,1,1]
	s_waitcnt lgkmcnt(10)
	v_pk_fma_f32 v[146:147], v[64:65], v[178:179], v[196:197]
	v_pk_fma_f32 v[150:151], v[64:65], v[186:187], v[196:197]
	v_pk_fma_f32 v[148:149], v[66:67], v[180:181], v[196:197]
	v_pk_fma_f32 v[152:153], v[66:67], v[188:189], v[196:197]
	s_waitcnt lgkmcnt(9)
	v_pk_fma_f32 v[146:147], v[68:69], v[182:183], v[146:147]
	v_pk_fma_f32 v[150:151], v[68:69], v[190:191], v[150:151]
	v_pk_fma_f32 v[148:149], v[70:71], v[184:185], v[148:149]
	v_pk_fma_f32 v[152:153], v[70:71], v[192:193], v[152:153]
	v_add_f32_e32 v146, v146, v147
	v_add_f32_e32 v148, v148, v149
	v_add_f32_e32 v150, v150, v151
	v_add_f32_e32 v152, v152, v153
	v_add_f32_e32 v154, v146, v148
	v_add_f32_e32 v155, v150, v152
	ds_read2_b32 v[118:119], v195 offset0:128 offset1:144
	ds_read_b128 v[72:75], v145 offset:32768
	ds_read_b128 v[76:79], v145 offset:33024
	ds_read_b128 v[64:67], v145 offset:24576
	ds_read_b128 v[68:71], v145 offset:24832
	s_waitcnt lgkmcnt(11)
	v_pk_add_f32 v[178:179], v[178:179], v[120:121] op_sel_hi:[1,0] neg_lo:[0,1] neg_hi:[0,1]
	v_add_f32_dpp v154, v154, v154 row_ror:8 row_mask:0xf bank_mask:0xf bound_ctrl:1
	v_pk_add_f32 v[186:187], v[186:187], v[120:121] op_sel:[0,1] op_sel_hi:[1,1] neg_lo:[0,1] neg_hi:[0,1]
	v_add_f32_dpp v155, v155, v155 row_ror:8 row_mask:0xf bank_mask:0xf bound_ctrl:1
	v_pk_add_f32 v[180:181], v[180:181], v[120:121] op_sel_hi:[1,0] neg_lo:[0,1] neg_hi:[0,1]
	v_add_f32_dpp v154, v154, v154 row_ror:4 row_mask:0xf bank_mask:0xf bound_ctrl:1
	v_pk_add_f32 v[188:189], v[188:189], v[120:121] op_sel:[0,1] op_sel_hi:[1,1] neg_lo:[0,1] neg_hi:[0,1]
	v_add_f32_dpp v155, v155, v155 row_ror:4 row_mask:0xf bank_mask:0xf bound_ctrl:1
	v_pk_add_f32 v[182:183], v[182:183], v[120:121] op_sel_hi:[1,0] neg_lo:[0,1] neg_hi:[0,1]
	v_add_f32_dpp v154, v154, v154 row_ror:2 row_mask:0xf bank_mask:0xf bound_ctrl:1
	v_pk_add_f32 v[190:191], v[190:191], v[120:121] op_sel:[0,1] op_sel_hi:[1,1] neg_lo:[0,1] neg_hi:[0,1]
	v_add_f32_dpp v155, v155, v155 row_ror:2 row_mask:0xf bank_mask:0xf bound_ctrl:1
	v_pk_add_f32 v[184:185], v[184:185], v[120:121] op_sel_hi:[1,0] neg_lo:[0,1] neg_hi:[0,1]
	v_add_f32_dpp v154, v154, v154 row_ror:1 row_mask:0xf bank_mask:0xf bound_ctrl:1
	v_pk_add_f32 v[192:193], v[192:193], v[120:121] op_sel:[0,1] op_sel_hi:[1,1] neg_lo:[0,1] neg_hi:[0,1]
	v_add_f32_dpp v155, v155, v155 row_ror:1 row_mask:0xf bank_mask:0xf bound_ctrl:1
	s_waitcnt lgkmcnt(10)
	v_pk_fma_f32 v[178:179], v[88:89], v[178:179], v[120:121] op_sel_hi:[1,1,0]
	ds_write_b32 v103, v154 offset:40192
	v_pk_fma_f32 v[186:187], v[88:89], v[186:187], v[120:121] op_sel:[0,0,1] op_sel_hi:[1,1,1]
	ds_write_b32 v103, v155 offset:40256
	v_pk_fma_f32 v[180:181], v[90:91], v[180:181], v[120:121] op_sel_hi:[1,1,0]
	v_pk_fma_f32 v[188:189], v[90:91], v[188:189], v[120:121] op_sel:[0,0,1] op_sel_hi:[1,1,1]
	s_waitcnt lgkmcnt(11)
	v_pk_fma_f32 v[182:183], v[92:93], v[182:183], v[120:121] op_sel_hi:[1,1,0]
	v_pk_fma_f32 v[190:191], v[92:93], v[190:191], v[120:121] op_sel:[0,0,1] op_sel_hi:[1,1,1]
	v_pk_fma_f32 v[184:185], v[94:95], v[184:185], v[120:121] op_sel_hi:[1,1,0]
	v_pk_fma_f32 v[192:193], v[94:95], v[192:193], v[120:121] op_sel:[0,0,1] op_sel_hi:[1,1,1]
	s_waitcnt lgkmcnt(10)
	v_pk_fma_f32 v[146:147], v[80:81], v[178:179], v[196:197]
	v_pk_fma_f32 v[150:151], v[80:81], v[186:187], v[196:197]
	v_pk_fma_f32 v[148:149], v[82:83], v[180:181], v[196:197]
	v_pk_fma_f32 v[152:153], v[82:83], v[188:189], v[196:197]
	s_waitcnt lgkmcnt(9)
	v_pk_fma_f32 v[146:147], v[84:85], v[182:183], v[146:147]
	v_pk_fma_f32 v[150:151], v[84:85], v[190:191], v[150:151]
	v_pk_fma_f32 v[148:149], v[86:87], v[184:185], v[148:149]
	v_pk_fma_f32 v[152:153], v[86:87], v[192:193], v[152:153]
	v_add_f32_e32 v146, v146, v147
	v_add_f32_e32 v148, v148, v149
	v_add_f32_e32 v150, v150, v151
	v_add_f32_e32 v152, v152, v153
	v_add_f32_e32 v156, v146, v148
	v_add_f32_e32 v157, v150, v152
	ds_read2_b32 v[120:121], v195 offset0:160 offset1:176
	ds_read_b128 v[88:91], v145 offset:33280
	ds_read_b128 v[92:95], v145 offset:33536
	ds_read_b128 v[80:83], v145 offset:25088
	ds_read_b128 v[84:87], v145 offset:25344
	s_waitcnt lgkmcnt(11)
	v_pk_add_f32 v[178:179], v[178:179], v[118:119] op_sel_hi:[1,0] neg_lo:[0,1] neg_hi:[0,1]
	v_add_f32_dpp v156, v156, v156 row_ror:8 row_mask:0xf bank_mask:0xf bound_ctrl:1
	v_pk_add_f32 v[186:187], v[186:187], v[118:119] op_sel:[0,1] op_sel_hi:[1,1] neg_lo:[0,1] neg_hi:[0,1]
	v_add_f32_dpp v157, v157, v157 row_ror:8 row_mask:0xf bank_mask:0xf bound_ctrl:1
	v_pk_add_f32 v[180:181], v[180:181], v[118:119] op_sel_hi:[1,0] neg_lo:[0,1] neg_hi:[0,1]
	v_add_f32_dpp v156, v156, v156 row_ror:4 row_mask:0xf bank_mask:0xf bound_ctrl:1
	v_pk_add_f32 v[188:189], v[188:189], v[118:119] op_sel:[0,1] op_sel_hi:[1,1] neg_lo:[0,1] neg_hi:[0,1]
	v_add_f32_dpp v157, v157, v157 row_ror:4 row_mask:0xf bank_mask:0xf bound_ctrl:1
	v_pk_add_f32 v[182:183], v[182:183], v[118:119] op_sel_hi:[1,0] neg_lo:[0,1] neg_hi:[0,1]
	v_add_f32_dpp v156, v156, v156 row_ror:2 row_mask:0xf bank_mask:0xf bound_ctrl:1
	v_pk_add_f32 v[190:191], v[190:191], v[118:119] op_sel:[0,1] op_sel_hi:[1,1] neg_lo:[0,1] neg_hi:[0,1]
	v_add_f32_dpp v157, v157, v157 row_ror:2 row_mask:0xf bank_mask:0xf bound_ctrl:1
	v_pk_add_f32 v[184:185], v[184:185], v[118:119] op_sel_hi:[1,0] neg_lo:[0,1] neg_hi:[0,1]
	v_add_f32_dpp v156, v156, v156 row_ror:1 row_mask:0xf bank_mask:0xf bound_ctrl:1
	v_pk_add_f32 v[192:193], v[192:193], v[118:119] op_sel:[0,1] op_sel_hi:[1,1] neg_lo:[0,1] neg_hi:[0,1]
	v_add_f32_dpp v157, v157, v157 row_ror:1 row_mask:0xf bank_mask:0xf bound_ctrl:1
	s_waitcnt lgkmcnt(10)
	v_pk_fma_f32 v[178:179], v[72:73], v[178:179], v[118:119] op_sel_hi:[1,1,0]
	ds_write_b32 v103, v156 offset:40320
	v_pk_fma_f32 v[186:187], v[72:73], v[186:187], v[118:119] op_sel:[0,0,1] op_sel_hi:[1,1,1]
	ds_write_b32 v103, v157 offset:40384
	v_pk_fma_f32 v[180:181], v[74:75], v[180:181], v[118:119] op_sel_hi:[1,1,0]
	v_pk_fma_f32 v[188:189], v[74:75], v[188:189], v[118:119] op_sel:[0,0,1] op_sel_hi:[1,1,1]
	s_waitcnt lgkmcnt(11)
	v_pk_fma_f32 v[182:183], v[76:77], v[182:183], v[118:119] op_sel_hi:[1,1,0]
	v_pk_fma_f32 v[190:191], v[76:77], v[190:191], v[118:119] op_sel:[0,0,1] op_sel_hi:[1,1,1]
	v_pk_fma_f32 v[184:185], v[78:79], v[184:185], v[118:119] op_sel_hi:[1,1,0]
	v_pk_fma_f32 v[192:193], v[78:79], v[192:193], v[118:119] op_sel:[0,0,1] op_sel_hi:[1,1,1]
	s_waitcnt lgkmcnt(10)
	v_pk_fma_f32 v[146:147], v[64:65], v[178:179], v[196:197]
	v_pk_fma_f32 v[150:151], v[64:65], v[186:187], v[196:197]
	v_pk_fma_f32 v[148:149], v[66:67], v[180:181], v[196:197]
	v_pk_fma_f32 v[152:153], v[66:67], v[188:189], v[196:197]
	s_waitcnt lgkmcnt(9)
	v_pk_fma_f32 v[146:147], v[68:69], v[182:183], v[146:147]
	v_pk_fma_f32 v[150:151], v[68:69], v[190:191], v[150:151]
	v_pk_fma_f32 v[148:149], v[70:71], v[184:185], v[148:149]
	v_pk_fma_f32 v[152:153], v[70:71], v[192:193], v[152:153]
	v_add_f32_e32 v146, v146, v147
	v_add_f32_e32 v148, v148, v149
	v_add_f32_e32 v150, v150, v151
	v_add_f32_e32 v152, v152, v153
	v_add_f32_e32 v154, v146, v148
	v_add_f32_e32 v155, v150, v152
	ds_read2_b32 v[118:119], v195 offset0:192 offset1:208
	ds_read_b128 v[72:75], v145 offset:33792
	ds_read_b128 v[76:79], v145 offset:34048
	ds_read_b128 v[64:67], v145 offset:25600
	ds_read_b128 v[68:71], v145 offset:25856
	s_waitcnt lgkmcnt(11)
	v_pk_add_f32 v[178:179], v[178:179], v[120:121] op_sel_hi:[1,0] neg_lo:[0,1] neg_hi:[0,1]
	v_add_f32_dpp v154, v154, v154 row_ror:8 row_mask:0xf bank_mask:0xf bound_ctrl:1
	v_pk_add_f32 v[186:187], v[186:187], v[120:121] op_sel:[0,1] op_sel_hi:[1,1] neg_lo:[0,1] neg_hi:[0,1]
	v_add_f32_dpp v155, v155, v155 row_ror:8 row_mask:0xf bank_mask:0xf bound_ctrl:1
	v_pk_add_f32 v[180:181], v[180:181], v[120:121] op_sel_hi:[1,0] neg_lo:[0,1] neg_hi:[0,1]
	v_add_f32_dpp v154, v154, v154 row_ror:4 row_mask:0xf bank_mask:0xf bound_ctrl:1
	v_pk_add_f32 v[188:189], v[188:189], v[120:121] op_sel:[0,1] op_sel_hi:[1,1] neg_lo:[0,1] neg_hi:[0,1]
	v_add_f32_dpp v155, v155, v155 row_ror:4 row_mask:0xf bank_mask:0xf bound_ctrl:1
	v_pk_add_f32 v[182:183], v[182:183], v[120:121] op_sel_hi:[1,0] neg_lo:[0,1] neg_hi:[0,1]
	v_add_f32_dpp v154, v154, v154 row_ror:2 row_mask:0xf bank_mask:0xf bound_ctrl:1
	v_pk_add_f32 v[190:191], v[190:191], v[120:121] op_sel:[0,1] op_sel_hi:[1,1] neg_lo:[0,1] neg_hi:[0,1]
	v_add_f32_dpp v155, v155, v155 row_ror:2 row_mask:0xf bank_mask:0xf bound_ctrl:1
	v_pk_add_f32 v[184:185], v[184:185], v[120:121] op_sel_hi:[1,0] neg_lo:[0,1] neg_hi:[0,1]
	v_add_f32_dpp v154, v154, v154 row_ror:1 row_mask:0xf bank_mask:0xf bound_ctrl:1
	v_pk_add_f32 v[192:193], v[192:193], v[120:121] op_sel:[0,1] op_sel_hi:[1,1] neg_lo:[0,1] neg_hi:[0,1]
	v_add_f32_dpp v155, v155, v155 row_ror:1 row_mask:0xf bank_mask:0xf bound_ctrl:1
	s_waitcnt lgkmcnt(10)
	v_pk_fma_f32 v[178:179], v[88:89], v[178:179], v[120:121] op_sel_hi:[1,1,0]
	ds_write_b32 v103, v154 offset:40448
	v_pk_fma_f32 v[186:187], v[88:89], v[186:187], v[120:121] op_sel:[0,0,1] op_sel_hi:[1,1,1]
	ds_write_b32 v103, v155 offset:40512
	v_pk_fma_f32 v[180:181], v[90:91], v[180:181], v[120:121] op_sel_hi:[1,1,0]
	v_pk_fma_f32 v[188:189], v[90:91], v[188:189], v[120:121] op_sel:[0,0,1] op_sel_hi:[1,1,1]
	s_waitcnt lgkmcnt(11)
	v_pk_fma_f32 v[182:183], v[92:93], v[182:183], v[120:121] op_sel_hi:[1,1,0]
	v_pk_fma_f32 v[190:191], v[92:93], v[190:191], v[120:121] op_sel:[0,0,1] op_sel_hi:[1,1,1]
	v_pk_fma_f32 v[184:185], v[94:95], v[184:185], v[120:121] op_sel_hi:[1,1,0]
	v_pk_fma_f32 v[192:193], v[94:95], v[192:193], v[120:121] op_sel:[0,0,1] op_sel_hi:[1,1,1]
	s_waitcnt lgkmcnt(10)
	v_pk_fma_f32 v[146:147], v[80:81], v[178:179], v[196:197]
	v_pk_fma_f32 v[150:151], v[80:81], v[186:187], v[196:197]
	v_pk_fma_f32 v[148:149], v[82:83], v[180:181], v[196:197]
	v_pk_fma_f32 v[152:153], v[82:83], v[188:189], v[196:197]
	s_waitcnt lgkmcnt(9)
	v_pk_fma_f32 v[146:147], v[84:85], v[182:183], v[146:147]
	v_pk_fma_f32 v[150:151], v[84:85], v[190:191], v[150:151]
	v_pk_fma_f32 v[148:149], v[86:87], v[184:185], v[148:149]
	v_pk_fma_f32 v[152:153], v[86:87], v[192:193], v[152:153]
	v_add_f32_e32 v146, v146, v147
	v_add_f32_e32 v148, v148, v149
	v_add_f32_e32 v150, v150, v151
	v_add_f32_e32 v152, v152, v153
	v_add_f32_e32 v156, v146, v148
	v_add_f32_e32 v157, v150, v152
	ds_read2_b32 v[120:121], v195 offset0:224 offset1:240
	ds_read_b128 v[88:91], v145 offset:34304
	ds_read_b128 v[92:95], v145 offset:34560
	ds_read_b128 v[80:83], v145 offset:26112
	ds_read_b128 v[84:87], v145 offset:26368
	s_waitcnt lgkmcnt(11)
	v_pk_add_f32 v[178:179], v[178:179], v[118:119] op_sel_hi:[1,0] neg_lo:[0,1] neg_hi:[0,1]
	v_add_f32_dpp v156, v156, v156 row_ror:8 row_mask:0xf bank_mask:0xf bound_ctrl:1
	v_pk_add_f32 v[186:187], v[186:187], v[118:119] op_sel:[0,1] op_sel_hi:[1,1] neg_lo:[0,1] neg_hi:[0,1]
	v_add_f32_dpp v157, v157, v157 row_ror:8 row_mask:0xf bank_mask:0xf bound_ctrl:1
	v_pk_add_f32 v[180:181], v[180:181], v[118:119] op_sel_hi:[1,0] neg_lo:[0,1] neg_hi:[0,1]
	v_add_f32_dpp v156, v156, v156 row_ror:4 row_mask:0xf bank_mask:0xf bound_ctrl:1
	v_pk_add_f32 v[188:189], v[188:189], v[118:119] op_sel:[0,1] op_sel_hi:[1,1] neg_lo:[0,1] neg_hi:[0,1]
	v_add_f32_dpp v157, v157, v157 row_ror:4 row_mask:0xf bank_mask:0xf bound_ctrl:1
	v_pk_add_f32 v[182:183], v[182:183], v[118:119] op_sel_hi:[1,0] neg_lo:[0,1] neg_hi:[0,1]
	v_add_f32_dpp v156, v156, v156 row_ror:2 row_mask:0xf bank_mask:0xf bound_ctrl:1
	v_pk_add_f32 v[190:191], v[190:191], v[118:119] op_sel:[0,1] op_sel_hi:[1,1] neg_lo:[0,1] neg_hi:[0,1]
	v_add_f32_dpp v157, v157, v157 row_ror:2 row_mask:0xf bank_mask:0xf bound_ctrl:1
	v_pk_add_f32 v[184:185], v[184:185], v[118:119] op_sel_hi:[1,0] neg_lo:[0,1] neg_hi:[0,1]
	v_add_f32_dpp v156, v156, v156 row_ror:1 row_mask:0xf bank_mask:0xf bound_ctrl:1
	v_pk_add_f32 v[192:193], v[192:193], v[118:119] op_sel:[0,1] op_sel_hi:[1,1] neg_lo:[0,1] neg_hi:[0,1]
	v_add_f32_dpp v157, v157, v157 row_ror:1 row_mask:0xf bank_mask:0xf bound_ctrl:1
	s_waitcnt lgkmcnt(10)
	v_pk_fma_f32 v[178:179], v[72:73], v[178:179], v[118:119] op_sel_hi:[1,1,0]
	ds_write_b32 v103, v156 offset:40576
	v_pk_fma_f32 v[186:187], v[72:73], v[186:187], v[118:119] op_sel:[0,0,1] op_sel_hi:[1,1,1]
	ds_write_b32 v103, v157 offset:40640
	v_pk_fma_f32 v[180:181], v[74:75], v[180:181], v[118:119] op_sel_hi:[1,1,0]
	v_pk_fma_f32 v[188:189], v[74:75], v[188:189], v[118:119] op_sel:[0,0,1] op_sel_hi:[1,1,1]
	s_waitcnt lgkmcnt(11)
	v_pk_fma_f32 v[182:183], v[76:77], v[182:183], v[118:119] op_sel_hi:[1,1,0]
	v_pk_fma_f32 v[190:191], v[76:77], v[190:191], v[118:119] op_sel:[0,0,1] op_sel_hi:[1,1,1]
	v_pk_fma_f32 v[184:185], v[78:79], v[184:185], v[118:119] op_sel_hi:[1,1,0]
	v_pk_fma_f32 v[192:193], v[78:79], v[192:193], v[118:119] op_sel:[0,0,1] op_sel_hi:[1,1,1]
	s_waitcnt lgkmcnt(10)
	v_pk_fma_f32 v[146:147], v[64:65], v[178:179], v[196:197]
	v_pk_fma_f32 v[150:151], v[64:65], v[186:187], v[196:197]
	v_pk_fma_f32 v[148:149], v[66:67], v[180:181], v[196:197]
	v_pk_fma_f32 v[152:153], v[66:67], v[188:189], v[196:197]
	s_waitcnt lgkmcnt(9)
	v_pk_fma_f32 v[146:147], v[68:69], v[182:183], v[146:147]
	v_pk_fma_f32 v[150:151], v[68:69], v[190:191], v[150:151]
	v_pk_fma_f32 v[148:149], v[70:71], v[184:185], v[148:149]
	v_pk_fma_f32 v[152:153], v[70:71], v[192:193], v[152:153]
	v_add_f32_e32 v146, v146, v147
	v_add_f32_e32 v148, v148, v149
	v_add_f32_e32 v150, v150, v151
	v_add_f32_e32 v152, v152, v153
	v_add_f32_e32 v154, v146, v148
	v_add_f32_e32 v155, v150, v152
	s_waitcnt lgkmcnt(6)
	v_pk_add_f32 v[178:179], v[178:179], v[120:121] op_sel_hi:[1,0] neg_lo:[0,1] neg_hi:[0,1]
	v_add_f32_dpp v154, v154, v154 row_ror:8 row_mask:0xf bank_mask:0xf bound_ctrl:1
	v_pk_add_f32 v[186:187], v[186:187], v[120:121] op_sel:[0,1] op_sel_hi:[1,1] neg_lo:[0,1] neg_hi:[0,1]
	v_add_f32_dpp v155, v155, v155 row_ror:8 row_mask:0xf bank_mask:0xf bound_ctrl:1
	v_pk_add_f32 v[180:181], v[180:181], v[120:121] op_sel_hi:[1,0] neg_lo:[0,1] neg_hi:[0,1]
	v_add_f32_dpp v154, v154, v154 row_ror:4 row_mask:0xf bank_mask:0xf bound_ctrl:1
	v_pk_add_f32 v[188:189], v[188:189], v[120:121] op_sel:[0,1] op_sel_hi:[1,1] neg_lo:[0,1] neg_hi:[0,1]
	v_add_f32_dpp v155, v155, v155 row_ror:4 row_mask:0xf bank_mask:0xf bound_ctrl:1
	v_pk_add_f32 v[182:183], v[182:183], v[120:121] op_sel_hi:[1,0] neg_lo:[0,1] neg_hi:[0,1]
	v_add_f32_dpp v154, v154, v154 row_ror:2 row_mask:0xf bank_mask:0xf bound_ctrl:1
	v_pk_add_f32 v[190:191], v[190:191], v[120:121] op_sel:[0,1] op_sel_hi:[1,1] neg_lo:[0,1] neg_hi:[0,1]
	v_add_f32_dpp v155, v155, v155 row_ror:2 row_mask:0xf bank_mask:0xf bound_ctrl:1
	v_pk_add_f32 v[184:185], v[184:185], v[120:121] op_sel_hi:[1,0] neg_lo:[0,1] neg_hi:[0,1]
	v_add_f32_dpp v154, v154, v154 row_ror:1 row_mask:0xf bank_mask:0xf bound_ctrl:1
	v_pk_add_f32 v[192:193], v[192:193], v[120:121] op_sel:[0,1] op_sel_hi:[1,1] neg_lo:[0,1] neg_hi:[0,1]
	v_add_f32_dpp v155, v155, v155 row_ror:1 row_mask:0xf bank_mask:0xf bound_ctrl:1
	s_waitcnt lgkmcnt(5)
	v_pk_fma_f32 v[178:179], v[88:89], v[178:179], v[120:121] op_sel_hi:[1,1,0]
	ds_write_b32 v103, v154 offset:40704
	v_pk_fma_f32 v[186:187], v[88:89], v[186:187], v[120:121] op_sel:[0,0,1] op_sel_hi:[1,1,1]
	ds_write_b32 v103, v155 offset:40768
	v_pk_fma_f32 v[180:181], v[90:91], v[180:181], v[120:121] op_sel_hi:[1,1,0]
	v_pk_fma_f32 v[188:189], v[90:91], v[188:189], v[120:121] op_sel:[0,0,1] op_sel_hi:[1,1,1]
	s_waitcnt lgkmcnt(6)
	v_pk_fma_f32 v[182:183], v[92:93], v[182:183], v[120:121] op_sel_hi:[1,1,0]
	v_pk_fma_f32 v[190:191], v[92:93], v[190:191], v[120:121] op_sel:[0,0,1] op_sel_hi:[1,1,1]
	v_pk_fma_f32 v[184:185], v[94:95], v[184:185], v[120:121] op_sel_hi:[1,1,0]
	v_pk_fma_f32 v[192:193], v[94:95], v[192:193], v[120:121] op_sel:[0,0,1] op_sel_hi:[1,1,1]
	s_waitcnt lgkmcnt(5)
	v_pk_fma_f32 v[146:147], v[80:81], v[178:179], v[196:197]
	v_pk_fma_f32 v[150:151], v[80:81], v[186:187], v[196:197]
	v_pk_fma_f32 v[148:149], v[82:83], v[180:181], v[196:197]
	v_pk_fma_f32 v[152:153], v[82:83], v[188:189], v[196:197]
	s_waitcnt lgkmcnt(4)
	v_pk_fma_f32 v[146:147], v[84:85], v[182:183], v[146:147]
	v_pk_fma_f32 v[150:151], v[84:85], v[190:191], v[150:151]
	v_pk_fma_f32 v[148:149], v[86:87], v[184:185], v[148:149]
	v_pk_fma_f32 v[152:153], v[86:87], v[192:193], v[152:153]
	v_add_f32_e32 v146, v146, v147
	v_add_f32_e32 v148, v148, v149
	v_add_f32_e32 v150, v150, v151
	v_add_f32_e32 v152, v152, v153
	v_add_f32_e32 v156, v146, v148
	v_add_f32_e32 v157, v150, v152
	s_nop 0
	v_add_f32_dpp v156, v156, v156 row_ror:8 row_mask:0xf bank_mask:0xf bound_ctrl:1
	v_add_f32_dpp v157, v157, v157 row_ror:8 row_mask:0xf bank_mask:0xf bound_ctrl:1
	s_nop 0
	v_add_f32_dpp v156, v156, v156 row_ror:4 row_mask:0xf bank_mask:0xf bound_ctrl:1
	v_add_f32_dpp v157, v157, v157 row_ror:4 row_mask:0xf bank_mask:0xf bound_ctrl:1
	s_nop 0
	v_add_f32_dpp v156, v156, v156 row_ror:2 row_mask:0xf bank_mask:0xf bound_ctrl:1
	v_add_f32_dpp v157, v157, v157 row_ror:2 row_mask:0xf bank_mask:0xf bound_ctrl:1
	s_nop 0
	v_add_f32_dpp v156, v156, v156 row_ror:1 row_mask:0xf bank_mask:0xf bound_ctrl:1
	v_add_f32_dpp v157, v157, v157 row_ror:1 row_mask:0xf bank_mask:0xf bound_ctrl:1
	ds_write_b32 v103, v156 offset:40832
	ds_write_b32 v103, v157 offset:40896
	s_waitcnt vmcnt(9)
	v_mul_f32_e32 v64, 0xbfb8aa3b, v28
	v_mul_f32_e32 v65, 0xbfb8aa3b, v29
	v_exp_f32_e32 v64, v64
	v_exp_f32_e32 v65, v65
	v_mul_f32_e32 v66, 0xbfb8aa3b, v30
	v_mul_f32_e32 v67, 0xbfb8aa3b, v31
	v_exp_f32_e32 v66, v66
	v_pk_add_f32 v[64:65], v[64:65], 1.0 op_sel_hi:[1,0]
	v_exp_f32_e32 v67, v67
	v_div_scale_f32 v80, s[8:9], v65, v65, v29
	v_rcp_f32_e32 v81, v80
	v_pk_add_f32 v[66:67], v[66:67], 1.0 op_sel_hi:[1,0]
	s_waitcnt vmcnt(8)
	v_mul_f32_e32 v72, 0xbfb8aa3b, v32
	v_mul_f32_e32 v73, 0xbfb8aa3b, v33
	v_fma_f32 v82, -v80, v81, 1.0
	v_fmac_f32_e32 v81, v82, v81
	v_div_scale_f32 v82, vcc, v29, v65, v29
	v_mul_f32_e32 v83, v82, v81
	v_fma_f32 v88, -v80, v83, v82
	v_fmac_f32_e32 v83, v88, v81
	v_fma_f32 v80, -v80, v83, v82
	v_div_fmas_f32 v80, v80, v81, v83
	v_div_fixup_f32 v65, v80, v65, v29
	v_div_scale_f32 v80, s[8:9], v64, v64, v28
	v_rcp_f32_e32 v81, v80
	v_exp_f32_e32 v72, v72
	v_exp_f32_e32 v73, v73
	v_mul_f32_e32 v74, 0xbfb8aa3b, v34
	v_fma_f32 v82, -v80, v81, 1.0
	v_fmac_f32_e32 v81, v82, v81
	v_div_scale_f32 v82, vcc, v28, v64, v28
	v_mul_f32_e32 v83, v82, v81
	v_fma_f32 v88, -v80, v83, v82
	v_fmac_f32_e32 v83, v88, v81
	v_fma_f32 v80, -v80, v83, v82
	v_div_fmas_f32 v80, v80, v81, v83
	v_div_fixup_f32 v64, v80, v64, v28
	v_div_scale_f32 v80, s[8:9], v67, v67, v31
	v_rcp_f32_e32 v81, v80
	v_pk_mul_f32 v[64:65], v[64:65], s[18:19] op_sel_hi:[1,0]
	v_mul_f32_e32 v75, 0xbfb8aa3b, v35
	v_exp_f32_e32 v74, v74
	v_fma_f32 v82, -v80, v81, 1.0
	v_fmac_f32_e32 v81, v82, v81
	v_div_scale_f32 v82, vcc, v31, v67, v31
	v_mul_f32_e32 v83, v82, v81
	v_fma_f32 v88, -v80, v83, v82
	v_fmac_f32_e32 v83, v88, v81
	v_fma_f32 v80, -v80, v83, v82
	v_div_fmas_f32 v80, v80, v81, v83
	v_div_fixup_f32 v67, v80, v67, v31
	v_div_scale_f32 v80, s[8:9], v66, v66, v30
	v_rcp_f32_e32 v81, v80
	v_exp_f32_e32 v75, v75
	s_cmpk_gt_u32 s48, 0x79
	v_fma_f32 v82, -v80, v81, 1.0
	v_fmac_f32_e32 v81, v82, v81
	v_div_scale_f32 v82, vcc, v30, v66, v30
	v_mul_f32_e32 v83, v82, v81
	v_fma_f32 v88, -v80, v83, v82
	v_fmac_f32_e32 v83, v88, v81
	v_fma_f32 v80, -v80, v83, v82
	v_div_fmas_f32 v80, v80, v81, v83
	v_div_fixup_f32 v66, v80, v66, v30
	v_pk_mul_f32 v[66:67], v[66:67], s[18:19] op_sel_hi:[1,0]
	ds_write_b128 v141, v[64:67]
	v_pk_add_f32 v[64:65], v[72:73], 1.0 op_sel_hi:[1,0]
	v_div_scale_f32 v66, s[8:9], v65, v65, 1.0
	v_rcp_f32_e32 v67, v66
	s_nop 0
	v_fma_f32 v72, -v66, v67, 1.0
	v_fmac_f32_e32 v67, v72, v67
	v_div_scale_f32 v72, vcc, 1.0, v65, 1.0
	v_mul_f32_e32 v73, v72, v67
	v_fma_f32 v80, -v66, v73, v72
	v_fmac_f32_e32 v73, v80, v67
	v_fma_f32 v66, -v66, v73, v72
	v_div_fmas_f32 v66, v66, v67, v73
	v_div_fixup_f32 v65, v66, v65, 1.0
	v_div_scale_f32 v66, s[8:9], v64, v64, 1.0
	v_rcp_f32_e32 v67, v66
	s_nop 0
	v_fma_f32 v72, -v66, v67, 1.0
	v_fmac_f32_e32 v67, v72, v67
	v_div_scale_f32 v72, vcc, 1.0, v64, 1.0
	v_mul_f32_e32 v73, v72, v67
	v_fma_f32 v80, -v66, v73, v72
	v_fmac_f32_e32 v73, v80, v67
	v_fma_f32 v66, -v66, v73, v72
	v_div_fmas_f32 v66, v66, v67, v73
	v_div_fixup_f32 v64, v66, v64, 1.0
	v_pk_add_f32 v[66:67], v[74:75], 1.0 op_sel_hi:[1,0]
	v_pk_fma_f32 v[64:65], v[110:111], v[64:65], v[104:105]
	v_div_scale_f32 v72, s[8:9], v67, v67, 1.0
	v_rcp_f32_e32 v73, v72
	s_nop 0
	v_fma_f32 v74, -v72, v73, 1.0
	v_fmac_f32_e32 v73, v74, v73
	v_div_scale_f32 v74, vcc, 1.0, v67, 1.0
	v_mul_f32_e32 v75, v74, v73
	v_fma_f32 v80, -v72, v75, v74
	v_fmac_f32_e32 v75, v80, v73
	v_fma_f32 v72, -v72, v75, v74
	v_div_fmas_f32 v72, v72, v73, v75
	v_div_fixup_f32 v67, v72, v67, 1.0
	v_div_scale_f32 v72, s[8:9], v66, v66, 1.0
	v_rcp_f32_e32 v73, v72
	s_nop 0
	v_fma_f32 v74, -v72, v73, 1.0
	v_fmac_f32_e32 v73, v74, v73
	v_div_scale_f32 v74, vcc, 1.0, v66, 1.0
	v_mul_f32_e32 v75, v74, v73
	v_fma_f32 v80, -v72, v75, v74
	v_fmac_f32_e32 v75, v80, v73
	v_fma_f32 v72, -v72, v75, v74
	v_div_fmas_f32 v72, v72, v73, v75
	v_div_fixup_f32 v66, v72, v66, 1.0
	v_pk_fma_f32 v[66:67], v[112:113], v[66:67], v[106:107]
	ds_write_b128 v141, v[64:67] offset:8192
	ds_write_b32 v134, v131 offset:16384
	v_mul_f32_e32 v64, 0xbfb8aa3b, v40
	v_mul_f32_e32 v65, 0xbfb8aa3b, v41
	v_exp_f32_e32 v64, v64
	v_exp_f32_e32 v65, v65
	v_mul_f32_e32 v66, 0xbfb8aa3b, v42
	v_mul_f32_e32 v67, 0xbfb8aa3b, v43
	v_exp_f32_e32 v66, v66
	v_pk_add_f32 v[64:65], v[64:65], 1.0 op_sel_hi:[1,0]
	v_exp_f32_e32 v67, v67
	v_div_scale_f32 v80, s[8:9], v65, v65, v41
	v_rcp_f32_e32 v81, v80
	v_pk_add_f32 v[66:67], v[66:67], 1.0 op_sel_hi:[1,0]
	s_waitcnt vmcnt(7)
	v_mul_f32_e32 v72, 0xbfb8aa3b, v52
	v_mul_f32_e32 v73, 0xbfb8aa3b, v53
	v_fma_f32 v82, -v80, v81, 1.0
	v_fmac_f32_e32 v81, v82, v81
	v_div_scale_f32 v82, vcc, v41, v65, v41
	v_mul_f32_e32 v83, v82, v81
	v_fma_f32 v88, -v80, v83, v82
	v_fmac_f32_e32 v83, v88, v81
	v_fma_f32 v80, -v80, v83, v82
	v_div_fmas_f32 v80, v80, v81, v83
	v_div_fixup_f32 v65, v80, v65, v41
	v_div_scale_f32 v80, s[8:9], v64, v64, v40
	v_rcp_f32_e32 v81, v80
	v_exp_f32_e32 v72, v72
	v_exp_f32_e32 v73, v73
	v_mul_f32_e32 v74, 0xbfb8aa3b, v54
	v_fma_f32 v82, -v80, v81, 1.0
	v_fmac_f32_e32 v81, v82, v81
	v_div_scale_f32 v82, vcc, v40, v64, v40
	v_mul_f32_e32 v83, v82, v81
	v_fma_f32 v88, -v80, v83, v82
	v_fmac_f32_e32 v83, v88, v81
	v_fma_f32 v80, -v80, v83, v82
	v_div_fmas_f32 v80, v80, v81, v83
	v_div_fixup_f32 v64, v80, v64, v40
	v_div_scale_f32 v80, s[8:9], v67, v67, v43
	v_rcp_f32_e32 v81, v80
	v_pk_mul_f32 v[64:65], v[64:65], s[18:19] op_sel_hi:[1,0]
	v_mul_f32_e32 v75, 0xbfb8aa3b, v55
	v_exp_f32_e32 v74, v74
	v_fma_f32 v82, -v80, v81, 1.0
	v_fmac_f32_e32 v81, v82, v81
	v_div_scale_f32 v82, vcc, v43, v67, v43
	v_mul_f32_e32 v83, v82, v81
	v_fma_f32 v88, -v80, v83, v82
	v_fmac_f32_e32 v83, v88, v81
	v_fma_f32 v80, -v80, v83, v82
	v_div_fmas_f32 v80, v80, v81, v83
	v_div_fixup_f32 v67, v80, v67, v43
	v_div_scale_f32 v80, s[8:9], v66, v66, v42
	v_rcp_f32_e32 v81, v80
	v_exp_f32_e32 v75, v75
	v_fma_f32 v82, -v80, v81, 1.0
	v_fmac_f32_e32 v81, v82, v81
	v_div_scale_f32 v82, vcc, v42, v66, v42
	v_mul_f32_e32 v83, v82, v81
	v_fma_f32 v88, -v80, v83, v82
	v_fmac_f32_e32 v83, v88, v81
	v_fma_f32 v80, -v80, v83, v82
	v_div_fmas_f32 v80, v80, v81, v83
	v_div_fixup_f32 v66, v80, v66, v42
	v_pk_mul_f32 v[66:67], v[66:67], s[18:19] op_sel_hi:[1,0]
	ds_write_b128 v144, v[64:67]
	v_pk_add_f32 v[64:65], v[72:73], 1.0 op_sel_hi:[1,0]
	v_div_scale_f32 v66, s[8:9], v65, v65, 1.0
	v_rcp_f32_e32 v67, v66
	s_nop 0
	v_fma_f32 v72, -v66, v67, 1.0
	v_fmac_f32_e32 v67, v72, v67
	v_div_scale_f32 v72, vcc, 1.0, v65, 1.0
	v_mul_f32_e32 v73, v72, v67
	v_fma_f32 v80, -v66, v73, v72
	v_fmac_f32_e32 v73, v80, v67
	v_fma_f32 v66, -v66, v73, v72
	v_div_fmas_f32 v66, v66, v67, v73
	v_div_fixup_f32 v65, v66, v65, 1.0
	v_div_scale_f32 v66, s[8:9], v64, v64, 1.0
	v_rcp_f32_e32 v67, v66
	s_nop 0
	v_fma_f32 v72, -v66, v67, 1.0
	v_fmac_f32_e32 v67, v72, v67
	v_div_scale_f32 v72, vcc, 1.0, v64, 1.0
	v_mul_f32_e32 v73, v72, v67
	v_fma_f32 v80, -v66, v73, v72
	v_fmac_f32_e32 v73, v80, v67
	v_fma_f32 v66, -v66, v73, v72
	v_div_fmas_f32 v66, v66, v67, v73
	v_div_fixup_f32 v64, v66, v64, 1.0
	v_pk_add_f32 v[66:67], v[74:75], 1.0 op_sel_hi:[1,0]
	v_pk_fma_f32 v[64:65], v[110:111], v[64:65], v[104:105]
	v_div_scale_f32 v72, s[8:9], v67, v67, 1.0
	v_rcp_f32_e32 v73, v72
	s_nop 0
	v_fma_f32 v74, -v72, v73, 1.0
	v_fmac_f32_e32 v73, v74, v73
	v_div_scale_f32 v74, vcc, 1.0, v67, 1.0
	v_mul_f32_e32 v75, v74, v73
	v_fma_f32 v80, -v72, v75, v74
	v_fmac_f32_e32 v75, v80, v73
	v_fma_f32 v72, -v72, v75, v74
	v_div_fmas_f32 v72, v72, v73, v75
	v_div_fixup_f32 v67, v72, v67, 1.0
	v_div_scale_f32 v72, s[8:9], v66, v66, 1.0
	v_rcp_f32_e32 v73, v72
	s_nop 0
	v_fma_f32 v74, -v72, v73, 1.0
	v_fmac_f32_e32 v73, v74, v73
	v_div_scale_f32 v74, vcc, 1.0, v66, 1.0
	v_mul_f32_e32 v75, v74, v73
	v_fma_f32 v80, -v72, v75, v74
	v_fmac_f32_e32 v75, v80, v73
	v_fma_f32 v72, -v72, v75, v74
	v_div_fmas_f32 v72, v72, v73, v75
	v_div_fixup_f32 v66, v72, v66, 1.0
	v_pk_fma_f32 v[66:67], v[112:113], v[66:67], v[106:107]
	ds_write_b128 v144, v[64:67] offset:8192
	s_waitcnt vmcnt(6)
	ds_write_b32 v134, v132 offset:17408
	s_waitcnt lgkmcnt(0)
	s_barrier
	s_cbranch_scc1 .LBB0_1359
	v_add_u32_e32 v28, 0x60, v98
	v_mov_b64_e32 v[40:41], s[30:31]
	v_mad_i64_i32 v[28:29], s[8:9], v28, s25, v[40:41]
	s_lshl_b32 s94, s46, 2
	v_lshl_add_u64 v[42:43], v[28:29], 0, s[94:95]
	v_mov_b32_e32 v117, v140
	v_lshl_add_u64 v[28:29], v[42:43], 0, v[116:117]
	v_add_co_u32_e32 v30, vcc, 0x4000, v28
	s_lshl_b32 s8, s42, 2
	s_nop 0
	v_addc_co_u32_e32 v31, vcc, 0, v29, vcc
	s_mov_b32 s9, s95
	v_add_co_u32_e32 v32, vcc, 0x5000, v28
	v_lshl_add_u64 v[42:43], v[42:43], 0, s[8:9]
	v_mov_b32_e32 v115, v140
	v_add_u32_e32 v52, 0x60, v96
	v_addc_co_u32_e32 v33, vcc, 0, v29, vcc
	v_lshl_add_u64 v[42:43], v[42:43], 0, v[114:115]
	v_mad_i64_i32 v[40:41], s[22:23], v52, s25, v[40:41]
	v_add_co_u32_e32 v42, vcc, s81, v42
	v_lshl_add_u64 v[52:53], v[40:41], 0, s[94:95]
	s_nop 0
	v_addc_co_u32_e32 v43, vcc, 0, v43, vcc
	v_lshl_add_u64 v[54:55], v[52:53], 0, v[116:117]
	v_add_co_u32_e32 v40, vcc, s80, v54
	v_lshl_add_u64 v[52:53], v[52:53], 0, s[8:9]
	s_nop 0
	v_addc_co_u32_e32 v41, vcc, 0, v55, vcc
	v_add_co_u32_e32 v54, vcc, 0x5000, v54
	v_lshl_add_u64 v[52:53], v[52:53], 0, v[114:115]
	s_nop 0
	v_addc_co_u32_e32 v55, vcc, 0, v55, vcc
	v_add_co_u32_e32 v64, vcc, 0x6000, v52
	global_load_dwordx4 v[28:31], v[30:31], off offset:32
	s_nop 0
	global_load_dwordx4 v[32:35], v[32:33], off offset:32
	s_nop 0
	global_load_dword v131, v[42:43], off offset:32
	s_nop 0
	global_load_dwordx4 v[40:43], v[40:41], off offset:32
	v_addc_co_u32_e32 v65, vcc, 0, v53, vcc
	global_load_dwordx4 v[52:55], v[54:55], off offset:32
	s_nop 0
	global_load_dword v132, v[64:65], off offset:32
.LBB0_1359:
	ds_read2st64_b32 v[64:65], v134 offset0:152 offset1:156
	v_add_u32_e32 v66, 16, v98
	v_ashrrev_i32_e32 v67, 31, v66
	v_lshlrev_b64 v[66:67], 12, v[66:67]
	v_lshl_add_u64 v[66:67], v[108:109], 0, v[66:67]
	s_waitcnt lgkmcnt(0)
	global_store_dword v[66:67], v64, off
	v_add_u32_e32 v66, 16, v96
	v_ashrrev_i32_e32 v67, 31, v66
	v_lshlrev_b64 v[66:67], 12, v[66:67]
	v_lshl_add_u64 v[66:67], v[108:109], 0, v[66:67]
	global_store_dword v[66:67], v65, off
	v_mov_b32_e32 v196, 0
	v_mov_b32_e32 v197, 0
	v_add_u32_e32 v194, 0x4000, v103
	v_add_u32_e32 v195, 0x4400, v103
	ds_read2_b32 v[118:119], v194 offset0:0 offset1:16
	ds_read_b128 v[72:75], v145 offset:8192
	ds_read_b128 v[76:79], v145 offset:8448
	ds_read_b128 v[64:67], v145
	ds_read_b128 v[68:71], v145 offset:256
	ds_read2_b32 v[120:121], v194 offset0:32 offset1:48
	ds_read_b128 v[88:91], v145 offset:8704
	ds_read_b128 v[92:95], v145 offset:8960
	ds_read_b128 v[80:83], v145 offset:512
	ds_read_b128 v[84:87], v145 offset:768
	s_waitcnt lgkmcnt(9)
	v_pk_add_f32 v[178:179], v[178:179], v[118:119] op_sel_hi:[1,0] neg_lo:[0,1] neg_hi:[0,1]
	v_pk_add_f32 v[186:187], v[186:187], v[118:119] op_sel:[0,1] op_sel_hi:[1,1] neg_lo:[0,1] neg_hi:[0,1]
	v_pk_add_f32 v[180:181], v[180:181], v[118:119] op_sel_hi:[1,0] neg_lo:[0,1] neg_hi:[0,1]
	v_pk_add_f32 v[188:189], v[188:189], v[118:119] op_sel:[0,1] op_sel_hi:[1,1] neg_lo:[0,1] neg_hi:[0,1]
	v_pk_add_f32 v[182:183], v[182:183], v[118:119] op_sel_hi:[1,0] neg_lo:[0,1] neg_hi:[0,1]
	v_pk_add_f32 v[190:191], v[190:191], v[118:119] op_sel:[0,1] op_sel_hi:[1,1] neg_lo:[0,1] neg_hi:[0,1]
	v_pk_add_f32 v[184:185], v[184:185], v[118:119] op_sel_hi:[1,0] neg_lo:[0,1] neg_hi:[0,1]
	v_pk_add_f32 v[192:193], v[192:193], v[118:119] op_sel:[0,1] op_sel_hi:[1,1] neg_lo:[0,1] neg_hi:[0,1]
	s_waitcnt lgkmcnt(8)
	v_pk_fma_f32 v[178:179], v[72:73], v[178:179], v[118:119] op_sel_hi:[1,1,0]
	v_pk_fma_f32 v[186:187], v[72:73], v[186:187], v[118:119] op_sel:[0,0,1] op_sel_hi:[1,1,1]
	v_pk_fma_f32 v[180:181], v[74:75], v[180:181], v[118:119] op_sel_hi:[1,1,0]
	v_pk_fma_f32 v[188:189], v[74:75], v[188:189], v[118:119] op_sel:[0,0,1] op_sel_hi:[1,1,1]
	s_waitcnt lgkmcnt(7)
	v_pk_fma_f32 v[182:183], v[76:77], v[182:183], v[118:119] op_sel_hi:[1,1,0]
	v_pk_fma_f32 v[190:191], v[76:77], v[190:191], v[118:119] op_sel:[0,0,1] op_sel_hi:[1,1,1]
	v_pk_fma_f32 v[184:185], v[78:79], v[184:185], v[118:119] op_sel_hi:[1,1,0]
	v_pk_fma_f32 v[192:193], v[78:79], v[192:193], v[118:119] op_sel:[0,0,1] op_sel_hi:[1,1,1]
	s_waitcnt lgkmcnt(6)
	v_pk_fma_f32 v[146:147], v[64:65], v[178:179], v[196:197]
	v_pk_fma_f32 v[150:151], v[64:65], v[186:187], v[196:197]
	v_pk_fma_f32 v[148:149], v[66:67], v[180:181], v[196:197]
	v_pk_fma_f32 v[152:153], v[66:67], v[188:189], v[196:197]
	s_waitcnt lgkmcnt(5)
	v_pk_fma_f32 v[146:147], v[68:69], v[182:183], v[146:147]
	v_pk_fma_f32 v[150:151], v[68:69], v[190:191], v[150:151]
	v_pk_fma_f32 v[148:149], v[70:71], v[184:185], v[148:149]
	v_pk_fma_f32 v[152:153], v[70:71], v[192:193], v[152:153]
	v_add_f32_e32 v146, v146, v147
	v_add_f32_e32 v148, v148, v149
	v_add_f32_e32 v150, v150, v151
	v_add_f32_e32 v152, v152, v153
	v_add_f32_e32 v154, v146, v148
	v_add_f32_e32 v155, v150, v152
	ds_read2_b32 v[118:119], v194 offset0:64 offset1:80
	ds_read_b128 v[72:75], v145 offset:9216
	ds_read_b128 v[76:79], v145 offset:9472
	ds_read_b128 v[64:67], v145 offset:1024
	ds_read_b128 v[68:71], v145 offset:1280
	s_waitcnt lgkmcnt(9)
	v_pk_add_f32 v[178:179], v[178:179], v[120:121] op_sel_hi:[1,0] neg_lo:[0,1] neg_hi:[0,1]
	v_add_f32_dpp v154, v154, v154 row_ror:8 row_mask:0xf bank_mask:0xf bound_ctrl:1
	v_pk_add_f32 v[186:187], v[186:187], v[120:121] op_sel:[0,1] op_sel_hi:[1,1] neg_lo:[0,1] neg_hi:[0,1]
	v_add_f32_dpp v155, v155, v155 row_ror:8 row_mask:0xf bank_mask:0xf bound_ctrl:1
	v_pk_add_f32 v[180:181], v[180:181], v[120:121] op_sel_hi:[1,0] neg_lo:[0,1] neg_hi:[0,1]
	v_add_f32_dpp v154, v154, v154 row_ror:4 row_mask:0xf bank_mask:0xf bound_ctrl:1
	v_pk_add_f32 v[188:189], v[188:189], v[120:121] op_sel:[0,1] op_sel_hi:[1,1] neg_lo:[0,1] neg_hi:[0,1]
	v_add_f32_dpp v155, v155, v155 row_ror:4 row_mask:0xf bank_mask:0xf bound_ctrl:1
	v_pk_add_f32 v[182:183], v[182:183], v[120:121] op_sel_hi:[1,0] neg_lo:[0,1] neg_hi:[0,1]
	v_add_f32_dpp v154, v154, v154 row_ror:2 row_mask:0xf bank_mask:0xf bound_ctrl:1
	v_pk_add_f32 v[190:191], v[190:191], v[120:121] op_sel:[0,1] op_sel_hi:[1,1] neg_lo:[0,1] neg_hi:[0,1]
	v_add_f32_dpp v155, v155, v155 row_ror:2 row_mask:0xf bank_mask:0xf bound_ctrl:1
	v_pk_add_f32 v[184:185], v[184:185], v[120:121] op_sel_hi:[1,0] neg_lo:[0,1] neg_hi:[0,1]
	v_add_f32_dpp v154, v154, v154 row_ror:1 row_mask:0xf bank_mask:0xf bound_ctrl:1
	v_pk_add_f32 v[192:193], v[192:193], v[120:121] op_sel:[0,1] op_sel_hi:[1,1] neg_lo:[0,1] neg_hi:[0,1]
	v_add_f32_dpp v155, v155, v155 row_ror:1 row_mask:0xf bank_mask:0xf bound_ctrl:1
	s_waitcnt lgkmcnt(8)
	v_pk_fma_f32 v[178:179], v[88:89], v[178:179], v[120:121] op_sel_hi:[1,1,0]
	ds_write_b32 v103, v154 offset:36864
	v_pk_fma_f32 v[186:187], v[88:89], v[186:187], v[120:121] op_sel:[0,0,1] op_sel_hi:[1,1,1]
	ds_write_b32 v103, v155 offset:36928
	v_pk_fma_f32 v[180:181], v[90:91], v[180:181], v[120:121] op_sel_hi:[1,1,0]
	v_pk_fma_f32 v[188:189], v[90:91], v[188:189], v[120:121] op_sel:[0,0,1] op_sel_hi:[1,1,1]
	s_waitcnt lgkmcnt(9)
	v_pk_fma_f32 v[182:183], v[92:93], v[182:183], v[120:121] op_sel_hi:[1,1,0]
	v_pk_fma_f32 v[190:191], v[92:93], v[190:191], v[120:121] op_sel:[0,0,1] op_sel_hi:[1,1,1]
	v_pk_fma_f32 v[184:185], v[94:95], v[184:185], v[120:121] op_sel_hi:[1,1,0]
	v_pk_fma_f32 v[192:193], v[94:95], v[192:193], v[120:121] op_sel:[0,0,1] op_sel_hi:[1,1,1]
	s_waitcnt lgkmcnt(8)
	v_pk_fma_f32 v[146:147], v[80:81], v[178:179], v[196:197]
	v_pk_fma_f32 v[150:151], v[80:81], v[186:187], v[196:197]
	v_pk_fma_f32 v[148:149], v[82:83], v[180:181], v[196:197]
	v_pk_fma_f32 v[152:153], v[82:83], v[188:189], v[196:197]
	s_waitcnt lgkmcnt(7)
	v_pk_fma_f32 v[146:147], v[84:85], v[182:183], v[146:147]
	v_pk_fma_f32 v[150:151], v[84:85], v[190:191], v[150:151]
	v_pk_fma_f32 v[148:149], v[86:87], v[184:185], v[148:149]
	v_pk_fma_f32 v[152:153], v[86:87], v[192:193], v[152:153]
	v_add_f32_e32 v146, v146, v147
	v_add_f32_e32 v148, v148, v149
	v_add_f32_e32 v150, v150, v151
	v_add_f32_e32 v152, v152, v153
	v_add_f32_e32 v156, v146, v148
	v_add_f32_e32 v157, v150, v152
	ds_read2_b32 v[120:121], v194 offset0:96 offset1:112
	ds_read_b128 v[88:91], v145 offset:9728
	ds_read_b128 v[92:95], v145 offset:9984
	ds_read_b128 v[80:83], v145 offset:1536
	ds_read_b128 v[84:87], v145 offset:1792
	s_waitcnt lgkmcnt(11)
	v_pk_add_f32 v[178:179], v[178:179], v[118:119] op_sel_hi:[1,0] neg_lo:[0,1] neg_hi:[0,1]
	v_add_f32_dpp v156, v156, v156 row_ror:8 row_mask:0xf bank_mask:0xf bound_ctrl:1
	v_pk_add_f32 v[186:187], v[186:187], v[118:119] op_sel:[0,1] op_sel_hi:[1,1] neg_lo:[0,1] neg_hi:[0,1]
	v_add_f32_dpp v157, v157, v157 row_ror:8 row_mask:0xf bank_mask:0xf bound_ctrl:1
	v_pk_add_f32 v[180:181], v[180:181], v[118:119] op_sel_hi:[1,0] neg_lo:[0,1] neg_hi:[0,1]
	v_add_f32_dpp v156, v156, v156 row_ror:4 row_mask:0xf bank_mask:0xf bound_ctrl:1
	v_pk_add_f32 v[188:189], v[188:189], v[118:119] op_sel:[0,1] op_sel_hi:[1,1] neg_lo:[0,1] neg_hi:[0,1]
	v_add_f32_dpp v157, v157, v157 row_ror:4 row_mask:0xf bank_mask:0xf bound_ctrl:1
	v_pk_add_f32 v[182:183], v[182:183], v[118:119] op_sel_hi:[1,0] neg_lo:[0,1] neg_hi:[0,1]
	v_add_f32_dpp v156, v156, v156 row_ror:2 row_mask:0xf bank_mask:0xf bound_ctrl:1
	v_pk_add_f32 v[190:191], v[190:191], v[118:119] op_sel:[0,1] op_sel_hi:[1,1] neg_lo:[0,1] neg_hi:[0,1]
	v_add_f32_dpp v157, v157, v157 row_ror:2 row_mask:0xf bank_mask:0xf bound_ctrl:1
	v_pk_add_f32 v[184:185], v[184:185], v[118:119] op_sel_hi:[1,0] neg_lo:[0,1] neg_hi:[0,1]
	v_add_f32_dpp v156, v156, v156 row_ror:1 row_mask:0xf bank_mask:0xf bound_ctrl:1
	v_pk_add_f32 v[192:193], v[192:193], v[118:119] op_sel:[0,1] op_sel_hi:[1,1] neg_lo:[0,1] neg_hi:[0,1]
	v_add_f32_dpp v157, v157, v157 row_ror:1 row_mask:0xf bank_mask:0xf bound_ctrl:1
	s_waitcnt lgkmcnt(10)
	v_pk_fma_f32 v[178:179], v[72:73], v[178:179], v[118:119] op_sel_hi:[1,1,0]
	ds_write_b32 v103, v156 offset:36992
	v_pk_fma_f32 v[186:187], v[72:73], v[186:187], v[118:119] op_sel:[0,0,1] op_sel_hi:[1,1,1]
	ds_write_b32 v103, v157 offset:37056
	v_pk_fma_f32 v[180:181], v[74:75], v[180:181], v[118:119] op_sel_hi:[1,1,0]
	v_pk_fma_f32 v[188:189], v[74:75], v[188:189], v[118:119] op_sel:[0,0,1] op_sel_hi:[1,1,1]
	s_waitcnt lgkmcnt(11)
	v_pk_fma_f32 v[182:183], v[76:77], v[182:183], v[118:119] op_sel_hi:[1,1,0]
	v_pk_fma_f32 v[190:191], v[76:77], v[190:191], v[118:119] op_sel:[0,0,1] op_sel_hi:[1,1,1]
	v_pk_fma_f32 v[184:185], v[78:79], v[184:185], v[118:119] op_sel_hi:[1,1,0]
	v_pk_fma_f32 v[192:193], v[78:79], v[192:193], v[118:119] op_sel:[0,0,1] op_sel_hi:[1,1,1]
	s_waitcnt lgkmcnt(10)
	v_pk_fma_f32 v[146:147], v[64:65], v[178:179], v[196:197]
	v_pk_fma_f32 v[150:151], v[64:65], v[186:187], v[196:197]
	v_pk_fma_f32 v[148:149], v[66:67], v[180:181], v[196:197]
	v_pk_fma_f32 v[152:153], v[66:67], v[188:189], v[196:197]
	s_waitcnt lgkmcnt(9)
	v_pk_fma_f32 v[146:147], v[68:69], v[182:183], v[146:147]
	v_pk_fma_f32 v[150:151], v[68:69], v[190:191], v[150:151]
	v_pk_fma_f32 v[148:149], v[70:71], v[184:185], v[148:149]
	v_pk_fma_f32 v[152:153], v[70:71], v[192:193], v[152:153]
	v_add_f32_e32 v146, v146, v147
	v_add_f32_e32 v148, v148, v149
	v_add_f32_e32 v150, v150, v151
	v_add_f32_e32 v152, v152, v153
	v_add_f32_e32 v154, v146, v148
	v_add_f32_e32 v155, v150, v152
	ds_read2_b32 v[118:119], v194 offset0:128 offset1:144
	ds_read_b128 v[72:75], v145 offset:10240
	ds_read_b128 v[76:79], v145 offset:10496
	ds_read_b128 v[64:67], v145 offset:2048
	ds_read_b128 v[68:71], v145 offset:2304
	s_waitcnt lgkmcnt(11)
	v_pk_add_f32 v[178:179], v[178:179], v[120:121] op_sel_hi:[1,0] neg_lo:[0,1] neg_hi:[0,1]
	v_add_f32_dpp v154, v154, v154 row_ror:8 row_mask:0xf bank_mask:0xf bound_ctrl:1
	v_pk_add_f32 v[186:187], v[186:187], v[120:121] op_sel:[0,1] op_sel_hi:[1,1] neg_lo:[0,1] neg_hi:[0,1]
	v_add_f32_dpp v155, v155, v155 row_ror:8 row_mask:0xf bank_mask:0xf bound_ctrl:1
	v_pk_add_f32 v[180:181], v[180:181], v[120:121] op_sel_hi:[1,0] neg_lo:[0,1] neg_hi:[0,1]
	v_add_f32_dpp v154, v154, v154 row_ror:4 row_mask:0xf bank_mask:0xf bound_ctrl:1
	v_pk_add_f32 v[188:189], v[188:189], v[120:121] op_sel:[0,1] op_sel_hi:[1,1] neg_lo:[0,1] neg_hi:[0,1]
	v_add_f32_dpp v155, v155, v155 row_ror:4 row_mask:0xf bank_mask:0xf bound_ctrl:1
	v_pk_add_f32 v[182:183], v[182:183], v[120:121] op_sel_hi:[1,0] neg_lo:[0,1] neg_hi:[0,1]
	v_add_f32_dpp v154, v154, v154 row_ror:2 row_mask:0xf bank_mask:0xf bound_ctrl:1
	v_pk_add_f32 v[190:191], v[190:191], v[120:121] op_sel:[0,1] op_sel_hi:[1,1] neg_lo:[0,1] neg_hi:[0,1]
	v_add_f32_dpp v155, v155, v155 row_ror:2 row_mask:0xf bank_mask:0xf bound_ctrl:1
	v_pk_add_f32 v[184:185], v[184:185], v[120:121] op_sel_hi:[1,0] neg_lo:[0,1] neg_hi:[0,1]
	v_add_f32_dpp v154, v154, v154 row_ror:1 row_mask:0xf bank_mask:0xf bound_ctrl:1
	v_pk_add_f32 v[192:193], v[192:193], v[120:121] op_sel:[0,1] op_sel_hi:[1,1] neg_lo:[0,1] neg_hi:[0,1]
	v_add_f32_dpp v155, v155, v155 row_ror:1 row_mask:0xf bank_mask:0xf bound_ctrl:1
	s_waitcnt lgkmcnt(10)
	v_pk_fma_f32 v[178:179], v[88:89], v[178:179], v[120:121] op_sel_hi:[1,1,0]
	ds_write_b32 v103, v154 offset:37120
	v_pk_fma_f32 v[186:187], v[88:89], v[186:187], v[120:121] op_sel:[0,0,1] op_sel_hi:[1,1,1]
	ds_write_b32 v103, v155 offset:37184
	v_pk_fma_f32 v[180:181], v[90:91], v[180:181], v[120:121] op_sel_hi:[1,1,0]
	v_pk_fma_f32 v[188:189], v[90:91], v[188:189], v[120:121] op_sel:[0,0,1] op_sel_hi:[1,1,1]
	s_waitcnt lgkmcnt(11)
	v_pk_fma_f32 v[182:183], v[92:93], v[182:183], v[120:121] op_sel_hi:[1,1,0]
	v_pk_fma_f32 v[190:191], v[92:93], v[190:191], v[120:121] op_sel:[0,0,1] op_sel_hi:[1,1,1]
	v_pk_fma_f32 v[184:185], v[94:95], v[184:185], v[120:121] op_sel_hi:[1,1,0]
	v_pk_fma_f32 v[192:193], v[94:95], v[192:193], v[120:121] op_sel:[0,0,1] op_sel_hi:[1,1,1]
	s_waitcnt lgkmcnt(10)
	v_pk_fma_f32 v[146:147], v[80:81], v[178:179], v[196:197]
	v_pk_fma_f32 v[150:151], v[80:81], v[186:187], v[196:197]
	v_pk_fma_f32 v[148:149], v[82:83], v[180:181], v[196:197]
	v_pk_fma_f32 v[152:153], v[82:83], v[188:189], v[196:197]
	s_waitcnt lgkmcnt(9)
	v_pk_fma_f32 v[146:147], v[84:85], v[182:183], v[146:147]
	v_pk_fma_f32 v[150:151], v[84:85], v[190:191], v[150:151]
	v_pk_fma_f32 v[148:149], v[86:87], v[184:185], v[148:149]
	v_pk_fma_f32 v[152:153], v[86:87], v[192:193], v[152:153]
	v_add_f32_e32 v146, v146, v147
	v_add_f32_e32 v148, v148, v149
	v_add_f32_e32 v150, v150, v151
	v_add_f32_e32 v152, v152, v153
	v_add_f32_e32 v156, v146, v148
	v_add_f32_e32 v157, v150, v152
	ds_read2_b32 v[120:121], v194 offset0:160 offset1:176
	ds_read_b128 v[88:91], v145 offset:10752
	ds_read_b128 v[92:95], v145 offset:11008
	ds_read_b128 v[80:83], v145 offset:2560
	ds_read_b128 v[84:87], v145 offset:2816
	s_waitcnt lgkmcnt(11)
	v_pk_add_f32 v[178:179], v[178:179], v[118:119] op_sel_hi:[1,0] neg_lo:[0,1] neg_hi:[0,1]
	v_add_f32_dpp v156, v156, v156 row_ror:8 row_mask:0xf bank_mask:0xf bound_ctrl:1
	v_pk_add_f32 v[186:187], v[186:187], v[118:119] op_sel:[0,1] op_sel_hi:[1,1] neg_lo:[0,1] neg_hi:[0,1]
	v_add_f32_dpp v157, v157, v157 row_ror:8 row_mask:0xf bank_mask:0xf bound_ctrl:1
	v_pk_add_f32 v[180:181], v[180:181], v[118:119] op_sel_hi:[1,0] neg_lo:[0,1] neg_hi:[0,1]
	v_add_f32_dpp v156, v156, v156 row_ror:4 row_mask:0xf bank_mask:0xf bound_ctrl:1
	v_pk_add_f32 v[188:189], v[188:189], v[118:119] op_sel:[0,1] op_sel_hi:[1,1] neg_lo:[0,1] neg_hi:[0,1]
	v_add_f32_dpp v157, v157, v157 row_ror:4 row_mask:0xf bank_mask:0xf bound_ctrl:1
	v_pk_add_f32 v[182:183], v[182:183], v[118:119] op_sel_hi:[1,0] neg_lo:[0,1] neg_hi:[0,1]
	v_add_f32_dpp v156, v156, v156 row_ror:2 row_mask:0xf bank_mask:0xf bound_ctrl:1
	v_pk_add_f32 v[190:191], v[190:191], v[118:119] op_sel:[0,1] op_sel_hi:[1,1] neg_lo:[0,1] neg_hi:[0,1]
	v_add_f32_dpp v157, v157, v157 row_ror:2 row_mask:0xf bank_mask:0xf bound_ctrl:1
	v_pk_add_f32 v[184:185], v[184:185], v[118:119] op_sel_hi:[1,0] neg_lo:[0,1] neg_hi:[0,1]
	v_add_f32_dpp v156, v156, v156 row_ror:1 row_mask:0xf bank_mask:0xf bound_ctrl:1
	v_pk_add_f32 v[192:193], v[192:193], v[118:119] op_sel:[0,1] op_sel_hi:[1,1] neg_lo:[0,1] neg_hi:[0,1]
	v_add_f32_dpp v157, v157, v157 row_ror:1 row_mask:0xf bank_mask:0xf bound_ctrl:1
	s_waitcnt lgkmcnt(10)
	v_pk_fma_f32 v[178:179], v[72:73], v[178:179], v[118:119] op_sel_hi:[1,1,0]
	ds_write_b32 v103, v156 offset:37248
	v_pk_fma_f32 v[186:187], v[72:73], v[186:187], v[118:119] op_sel:[0,0,1] op_sel_hi:[1,1,1]
	ds_write_b32 v103, v157 offset:37312
	v_pk_fma_f32 v[180:181], v[74:75], v[180:181], v[118:119] op_sel_hi:[1,1,0]
	v_pk_fma_f32 v[188:189], v[74:75], v[188:189], v[118:119] op_sel:[0,0,1] op_sel_hi:[1,1,1]
	s_waitcnt lgkmcnt(11)
	v_pk_fma_f32 v[182:183], v[76:77], v[182:183], v[118:119] op_sel_hi:[1,1,0]
	v_pk_fma_f32 v[190:191], v[76:77], v[190:191], v[118:119] op_sel:[0,0,1] op_sel_hi:[1,1,1]
	v_pk_fma_f32 v[184:185], v[78:79], v[184:185], v[118:119] op_sel_hi:[1,1,0]
	v_pk_fma_f32 v[192:193], v[78:79], v[192:193], v[118:119] op_sel:[0,0,1] op_sel_hi:[1,1,1]
	s_waitcnt lgkmcnt(10)
	v_pk_fma_f32 v[146:147], v[64:65], v[178:179], v[196:197]
	v_pk_fma_f32 v[150:151], v[64:65], v[186:187], v[196:197]
	v_pk_fma_f32 v[148:149], v[66:67], v[180:181], v[196:197]
	v_pk_fma_f32 v[152:153], v[66:67], v[188:189], v[196:197]
	s_waitcnt lgkmcnt(9)
	v_pk_fma_f32 v[146:147], v[68:69], v[182:183], v[146:147]
	v_pk_fma_f32 v[150:151], v[68:69], v[190:191], v[150:151]
	v_pk_fma_f32 v[148:149], v[70:71], v[184:185], v[148:149]
	v_pk_fma_f32 v[152:153], v[70:71], v[192:193], v[152:153]
	v_add_f32_e32 v146, v146, v147
	v_add_f32_e32 v148, v148, v149
	v_add_f32_e32 v150, v150, v151
	v_add_f32_e32 v152, v152, v153
	v_add_f32_e32 v154, v146, v148
	v_add_f32_e32 v155, v150, v152
	ds_read2_b32 v[118:119], v194 offset0:192 offset1:208
	ds_read_b128 v[72:75], v145 offset:11264
	ds_read_b128 v[76:79], v145 offset:11520
	ds_read_b128 v[64:67], v145 offset:3072
	ds_read_b128 v[68:71], v145 offset:3328
	s_waitcnt lgkmcnt(11)
	v_pk_add_f32 v[178:179], v[178:179], v[120:121] op_sel_hi:[1,0] neg_lo:[0,1] neg_hi:[0,1]
	v_add_f32_dpp v154, v154, v154 row_ror:8 row_mask:0xf bank_mask:0xf bound_ctrl:1
	v_pk_add_f32 v[186:187], v[186:187], v[120:121] op_sel:[0,1] op_sel_hi:[1,1] neg_lo:[0,1] neg_hi:[0,1]
	v_add_f32_dpp v155, v155, v155 row_ror:8 row_mask:0xf bank_mask:0xf bound_ctrl:1
	v_pk_add_f32 v[180:181], v[180:181], v[120:121] op_sel_hi:[1,0] neg_lo:[0,1] neg_hi:[0,1]
	v_add_f32_dpp v154, v154, v154 row_ror:4 row_mask:0xf bank_mask:0xf bound_ctrl:1
	v_pk_add_f32 v[188:189], v[188:189], v[120:121] op_sel:[0,1] op_sel_hi:[1,1] neg_lo:[0,1] neg_hi:[0,1]
	v_add_f32_dpp v155, v155, v155 row_ror:4 row_mask:0xf bank_mask:0xf bound_ctrl:1
	v_pk_add_f32 v[182:183], v[182:183], v[120:121] op_sel_hi:[1,0] neg_lo:[0,1] neg_hi:[0,1]
	v_add_f32_dpp v154, v154, v154 row_ror:2 row_mask:0xf bank_mask:0xf bound_ctrl:1
	v_pk_add_f32 v[190:191], v[190:191], v[120:121] op_sel:[0,1] op_sel_hi:[1,1] neg_lo:[0,1] neg_hi:[0,1]
	v_add_f32_dpp v155, v155, v155 row_ror:2 row_mask:0xf bank_mask:0xf bound_ctrl:1
	v_pk_add_f32 v[184:185], v[184:185], v[120:121] op_sel_hi:[1,0] neg_lo:[0,1] neg_hi:[0,1]
	v_add_f32_dpp v154, v154, v154 row_ror:1 row_mask:0xf bank_mask:0xf bound_ctrl:1
	v_pk_add_f32 v[192:193], v[192:193], v[120:121] op_sel:[0,1] op_sel_hi:[1,1] neg_lo:[0,1] neg_hi:[0,1]
	v_add_f32_dpp v155, v155, v155 row_ror:1 row_mask:0xf bank_mask:0xf bound_ctrl:1
	s_waitcnt lgkmcnt(10)
	v_pk_fma_f32 v[178:179], v[88:89], v[178:179], v[120:121] op_sel_hi:[1,1,0]
	ds_write_b32 v103, v154 offset:37376
	v_pk_fma_f32 v[186:187], v[88:89], v[186:187], v[120:121] op_sel:[0,0,1] op_sel_hi:[1,1,1]
	ds_write_b32 v103, v155 offset:37440
	v_pk_fma_f32 v[180:181], v[90:91], v[180:181], v[120:121] op_sel_hi:[1,1,0]
	v_pk_fma_f32 v[188:189], v[90:91], v[188:189], v[120:121] op_sel:[0,0,1] op_sel_hi:[1,1,1]
	s_waitcnt lgkmcnt(11)
	v_pk_fma_f32 v[182:183], v[92:93], v[182:183], v[120:121] op_sel_hi:[1,1,0]
	v_pk_fma_f32 v[190:191], v[92:93], v[190:191], v[120:121] op_sel:[0,0,1] op_sel_hi:[1,1,1]
	v_pk_fma_f32 v[184:185], v[94:95], v[184:185], v[120:121] op_sel_hi:[1,1,0]
	v_pk_fma_f32 v[192:193], v[94:95], v[192:193], v[120:121] op_sel:[0,0,1] op_sel_hi:[1,1,1]
	s_waitcnt lgkmcnt(10)
	v_pk_fma_f32 v[146:147], v[80:81], v[178:179], v[196:197]
	v_pk_fma_f32 v[150:151], v[80:81], v[186:187], v[196:197]
	v_pk_fma_f32 v[148:149], v[82:83], v[180:181], v[196:197]
	v_pk_fma_f32 v[152:153], v[82:83], v[188:189], v[196:197]
	s_waitcnt lgkmcnt(9)
	v_pk_fma_f32 v[146:147], v[84:85], v[182:183], v[146:147]
	v_pk_fma_f32 v[150:151], v[84:85], v[190:191], v[150:151]
	v_pk_fma_f32 v[148:149], v[86:87], v[184:185], v[148:149]
	v_pk_fma_f32 v[152:153], v[86:87], v[192:193], v[152:153]
	v_add_f32_e32 v146, v146, v147
	v_add_f32_e32 v148, v148, v149
	v_add_f32_e32 v150, v150, v151
	v_add_f32_e32 v152, v152, v153
	v_add_f32_e32 v156, v146, v148
	v_add_f32_e32 v157, v150, v152
	ds_read2_b32 v[120:121], v194 offset0:224 offset1:240
	ds_read_b128 v[88:91], v145 offset:11776
	ds_read_b128 v[92:95], v145 offset:12032
	ds_read_b128 v[80:83], v145 offset:3584
	ds_read_b128 v[84:87], v145 offset:3840
	s_waitcnt lgkmcnt(11)
	v_pk_add_f32 v[178:179], v[178:179], v[118:119] op_sel_hi:[1,0] neg_lo:[0,1] neg_hi:[0,1]
	v_add_f32_dpp v156, v156, v156 row_ror:8 row_mask:0xf bank_mask:0xf bound_ctrl:1
	v_pk_add_f32 v[186:187], v[186:187], v[118:119] op_sel:[0,1] op_sel_hi:[1,1] neg_lo:[0,1] neg_hi:[0,1]
	v_add_f32_dpp v157, v157, v157 row_ror:8 row_mask:0xf bank_mask:0xf bound_ctrl:1
	v_pk_add_f32 v[180:181], v[180:181], v[118:119] op_sel_hi:[1,0] neg_lo:[0,1] neg_hi:[0,1]
	v_add_f32_dpp v156, v156, v156 row_ror:4 row_mask:0xf bank_mask:0xf bound_ctrl:1
	v_pk_add_f32 v[188:189], v[188:189], v[118:119] op_sel:[0,1] op_sel_hi:[1,1] neg_lo:[0,1] neg_hi:[0,1]
	v_add_f32_dpp v157, v157, v157 row_ror:4 row_mask:0xf bank_mask:0xf bound_ctrl:1
	v_pk_add_f32 v[182:183], v[182:183], v[118:119] op_sel_hi:[1,0] neg_lo:[0,1] neg_hi:[0,1]
	v_add_f32_dpp v156, v156, v156 row_ror:2 row_mask:0xf bank_mask:0xf bound_ctrl:1
	v_pk_add_f32 v[190:191], v[190:191], v[118:119] op_sel:[0,1] op_sel_hi:[1,1] neg_lo:[0,1] neg_hi:[0,1]
	v_add_f32_dpp v157, v157, v157 row_ror:2 row_mask:0xf bank_mask:0xf bound_ctrl:1
	v_pk_add_f32 v[184:185], v[184:185], v[118:119] op_sel_hi:[1,0] neg_lo:[0,1] neg_hi:[0,1]
	v_add_f32_dpp v156, v156, v156 row_ror:1 row_mask:0xf bank_mask:0xf bound_ctrl:1
	v_pk_add_f32 v[192:193], v[192:193], v[118:119] op_sel:[0,1] op_sel_hi:[1,1] neg_lo:[0,1] neg_hi:[0,1]
	v_add_f32_dpp v157, v157, v157 row_ror:1 row_mask:0xf bank_mask:0xf bound_ctrl:1
	s_waitcnt lgkmcnt(10)
	v_pk_fma_f32 v[178:179], v[72:73], v[178:179], v[118:119] op_sel_hi:[1,1,0]
	ds_write_b32 v103, v156 offset:37504
	v_pk_fma_f32 v[186:187], v[72:73], v[186:187], v[118:119] op_sel:[0,0,1] op_sel_hi:[1,1,1]
	ds_write_b32 v103, v157 offset:37568
	v_pk_fma_f32 v[180:181], v[74:75], v[180:181], v[118:119] op_sel_hi:[1,1,0]
	v_pk_fma_f32 v[188:189], v[74:75], v[188:189], v[118:119] op_sel:[0,0,1] op_sel_hi:[1,1,1]
	s_waitcnt lgkmcnt(11)
	v_pk_fma_f32 v[182:183], v[76:77], v[182:183], v[118:119] op_sel_hi:[1,1,0]
	v_pk_fma_f32 v[190:191], v[76:77], v[190:191], v[118:119] op_sel:[0,0,1] op_sel_hi:[1,1,1]
	v_pk_fma_f32 v[184:185], v[78:79], v[184:185], v[118:119] op_sel_hi:[1,1,0]
	v_pk_fma_f32 v[192:193], v[78:79], v[192:193], v[118:119] op_sel:[0,0,1] op_sel_hi:[1,1,1]
	s_waitcnt lgkmcnt(10)
	v_pk_fma_f32 v[146:147], v[64:65], v[178:179], v[196:197]
	v_pk_fma_f32 v[150:151], v[64:65], v[186:187], v[196:197]
	v_pk_fma_f32 v[148:149], v[66:67], v[180:181], v[196:197]
	v_pk_fma_f32 v[152:153], v[66:67], v[188:189], v[196:197]
	s_waitcnt lgkmcnt(9)
	v_pk_fma_f32 v[146:147], v[68:69], v[182:183], v[146:147]
	v_pk_fma_f32 v[150:151], v[68:69], v[190:191], v[150:151]
	v_pk_fma_f32 v[148:149], v[70:71], v[184:185], v[148:149]
	v_pk_fma_f32 v[152:153], v[70:71], v[192:193], v[152:153]
	v_add_f32_e32 v146, v146, v147
	v_add_f32_e32 v148, v148, v149
	v_add_f32_e32 v150, v150, v151
	v_add_f32_e32 v152, v152, v153
	v_add_f32_e32 v154, v146, v148
	v_add_f32_e32 v155, v150, v152
	ds_read2_b32 v[118:119], v195 offset0:0 offset1:16
	ds_read_b128 v[72:75], v145 offset:12288
	ds_read_b128 v[76:79], v145 offset:12544
	ds_read_b128 v[64:67], v145 offset:4096
	ds_read_b128 v[68:71], v145 offset:4352
	s_waitcnt lgkmcnt(11)
	v_pk_add_f32 v[178:179], v[178:179], v[120:121] op_sel_hi:[1,0] neg_lo:[0,1] neg_hi:[0,1]
	v_add_f32_dpp v154, v154, v154 row_ror:8 row_mask:0xf bank_mask:0xf bound_ctrl:1
	v_pk_add_f32 v[186:187], v[186:187], v[120:121] op_sel:[0,1] op_sel_hi:[1,1] neg_lo:[0,1] neg_hi:[0,1]
	v_add_f32_dpp v155, v155, v155 row_ror:8 row_mask:0xf bank_mask:0xf bound_ctrl:1
	v_pk_add_f32 v[180:181], v[180:181], v[120:121] op_sel_hi:[1,0] neg_lo:[0,1] neg_hi:[0,1]
	v_add_f32_dpp v154, v154, v154 row_ror:4 row_mask:0xf bank_mask:0xf bound_ctrl:1
	v_pk_add_f32 v[188:189], v[188:189], v[120:121] op_sel:[0,1] op_sel_hi:[1,1] neg_lo:[0,1] neg_hi:[0,1]
	v_add_f32_dpp v155, v155, v155 row_ror:4 row_mask:0xf bank_mask:0xf bound_ctrl:1
	v_pk_add_f32 v[182:183], v[182:183], v[120:121] op_sel_hi:[1,0] neg_lo:[0,1] neg_hi:[0,1]
	v_add_f32_dpp v154, v154, v154 row_ror:2 row_mask:0xf bank_mask:0xf bound_ctrl:1
	v_pk_add_f32 v[190:191], v[190:191], v[120:121] op_sel:[0,1] op_sel_hi:[1,1] neg_lo:[0,1] neg_hi:[0,1]
	v_add_f32_dpp v155, v155, v155 row_ror:2 row_mask:0xf bank_mask:0xf bound_ctrl:1
	v_pk_add_f32 v[184:185], v[184:185], v[120:121] op_sel_hi:[1,0] neg_lo:[0,1] neg_hi:[0,1]
	v_add_f32_dpp v154, v154, v154 row_ror:1 row_mask:0xf bank_mask:0xf bound_ctrl:1
	v_pk_add_f32 v[192:193], v[192:193], v[120:121] op_sel:[0,1] op_sel_hi:[1,1] neg_lo:[0,1] neg_hi:[0,1]
	v_add_f32_dpp v155, v155, v155 row_ror:1 row_mask:0xf bank_mask:0xf bound_ctrl:1
	s_waitcnt lgkmcnt(10)
	v_pk_fma_f32 v[178:179], v[88:89], v[178:179], v[120:121] op_sel_hi:[1,1,0]
	ds_write_b32 v103, v154 offset:37632
	v_pk_fma_f32 v[186:187], v[88:89], v[186:187], v[120:121] op_sel:[0,0,1] op_sel_hi:[1,1,1]
	ds_write_b32 v103, v155 offset:37696
	v_pk_fma_f32 v[180:181], v[90:91], v[180:181], v[120:121] op_sel_hi:[1,1,0]
	v_pk_fma_f32 v[188:189], v[90:91], v[188:189], v[120:121] op_sel:[0,0,1] op_sel_hi:[1,1,1]
	s_waitcnt lgkmcnt(11)
	v_pk_fma_f32 v[182:183], v[92:93], v[182:183], v[120:121] op_sel_hi:[1,1,0]
	v_pk_fma_f32 v[190:191], v[92:93], v[190:191], v[120:121] op_sel:[0,0,1] op_sel_hi:[1,1,1]
	v_pk_fma_f32 v[184:185], v[94:95], v[184:185], v[120:121] op_sel_hi:[1,1,0]
	v_pk_fma_f32 v[192:193], v[94:95], v[192:193], v[120:121] op_sel:[0,0,1] op_sel_hi:[1,1,1]
	s_waitcnt lgkmcnt(10)
	v_pk_fma_f32 v[146:147], v[80:81], v[178:179], v[196:197]
	v_pk_fma_f32 v[150:151], v[80:81], v[186:187], v[196:197]
	v_pk_fma_f32 v[148:149], v[82:83], v[180:181], v[196:197]
	v_pk_fma_f32 v[152:153], v[82:83], v[188:189], v[196:197]
	s_waitcnt lgkmcnt(9)
	v_pk_fma_f32 v[146:147], v[84:85], v[182:183], v[146:147]
	v_pk_fma_f32 v[150:151], v[84:85], v[190:191], v[150:151]
	v_pk_fma_f32 v[148:149], v[86:87], v[184:185], v[148:149]
	v_pk_fma_f32 v[152:153], v[86:87], v[192:193], v[152:153]
	v_add_f32_e32 v146, v146, v147
	v_add_f32_e32 v148, v148, v149
	v_add_f32_e32 v150, v150, v151
	v_add_f32_e32 v152, v152, v153
	v_add_f32_e32 v156, v146, v148
	v_add_f32_e32 v157, v150, v152
	ds_read2_b32 v[120:121], v195 offset0:32 offset1:48
	ds_read_b128 v[88:91], v145 offset:12800
	ds_read_b128 v[92:95], v145 offset:13056
	ds_read_b128 v[80:83], v145 offset:4608
	ds_read_b128 v[84:87], v145 offset:4864
	s_waitcnt lgkmcnt(11)
	v_pk_add_f32 v[178:179], v[178:179], v[118:119] op_sel_hi:[1,0] neg_lo:[0,1] neg_hi:[0,1]
	v_add_f32_dpp v156, v156, v156 row_ror:8 row_mask:0xf bank_mask:0xf bound_ctrl:1
	v_pk_add_f32 v[186:187], v[186:187], v[118:119] op_sel:[0,1] op_sel_hi:[1,1] neg_lo:[0,1] neg_hi:[0,1]
	v_add_f32_dpp v157, v157, v157 row_ror:8 row_mask:0xf bank_mask:0xf bound_ctrl:1
	v_pk_add_f32 v[180:181], v[180:181], v[118:119] op_sel_hi:[1,0] neg_lo:[0,1] neg_hi:[0,1]
	v_add_f32_dpp v156, v156, v156 row_ror:4 row_mask:0xf bank_mask:0xf bound_ctrl:1
	v_pk_add_f32 v[188:189], v[188:189], v[118:119] op_sel:[0,1] op_sel_hi:[1,1] neg_lo:[0,1] neg_hi:[0,1]
	v_add_f32_dpp v157, v157, v157 row_ror:4 row_mask:0xf bank_mask:0xf bound_ctrl:1
	v_pk_add_f32 v[182:183], v[182:183], v[118:119] op_sel_hi:[1,0] neg_lo:[0,1] neg_hi:[0,1]
	v_add_f32_dpp v156, v156, v156 row_ror:2 row_mask:0xf bank_mask:0xf bound_ctrl:1
	v_pk_add_f32 v[190:191], v[190:191], v[118:119] op_sel:[0,1] op_sel_hi:[1,1] neg_lo:[0,1] neg_hi:[0,1]
	v_add_f32_dpp v157, v157, v157 row_ror:2 row_mask:0xf bank_mask:0xf bound_ctrl:1
	v_pk_add_f32 v[184:185], v[184:185], v[118:119] op_sel_hi:[1,0] neg_lo:[0,1] neg_hi:[0,1]
	v_add_f32_dpp v156, v156, v156 row_ror:1 row_mask:0xf bank_mask:0xf bound_ctrl:1
	v_pk_add_f32 v[192:193], v[192:193], v[118:119] op_sel:[0,1] op_sel_hi:[1,1] neg_lo:[0,1] neg_hi:[0,1]
	v_add_f32_dpp v157, v157, v157 row_ror:1 row_mask:0xf bank_mask:0xf bound_ctrl:1
	s_waitcnt lgkmcnt(10)
	v_pk_fma_f32 v[178:179], v[72:73], v[178:179], v[118:119] op_sel_hi:[1,1,0]
	ds_write_b32 v103, v156 offset:37760
	v_pk_fma_f32 v[186:187], v[72:73], v[186:187], v[118:119] op_sel:[0,0,1] op_sel_hi:[1,1,1]
	ds_write_b32 v103, v157 offset:37824
	v_pk_fma_f32 v[180:181], v[74:75], v[180:181], v[118:119] op_sel_hi:[1,1,0]
	v_pk_fma_f32 v[188:189], v[74:75], v[188:189], v[118:119] op_sel:[0,0,1] op_sel_hi:[1,1,1]
	s_waitcnt lgkmcnt(11)
	v_pk_fma_f32 v[182:183], v[76:77], v[182:183], v[118:119] op_sel_hi:[1,1,0]
	v_pk_fma_f32 v[190:191], v[76:77], v[190:191], v[118:119] op_sel:[0,0,1] op_sel_hi:[1,1,1]
	v_pk_fma_f32 v[184:185], v[78:79], v[184:185], v[118:119] op_sel_hi:[1,1,0]
	v_pk_fma_f32 v[192:193], v[78:79], v[192:193], v[118:119] op_sel:[0,0,1] op_sel_hi:[1,1,1]
	s_waitcnt lgkmcnt(10)
	v_pk_fma_f32 v[146:147], v[64:65], v[178:179], v[196:197]
	v_pk_fma_f32 v[150:151], v[64:65], v[186:187], v[196:197]
	v_pk_fma_f32 v[148:149], v[66:67], v[180:181], v[196:197]
	v_pk_fma_f32 v[152:153], v[66:67], v[188:189], v[196:197]
	s_waitcnt lgkmcnt(9)
	v_pk_fma_f32 v[146:147], v[68:69], v[182:183], v[146:147]
	v_pk_fma_f32 v[150:151], v[68:69], v[190:191], v[150:151]
	v_pk_fma_f32 v[148:149], v[70:71], v[184:185], v[148:149]
	v_pk_fma_f32 v[152:153], v[70:71], v[192:193], v[152:153]
	v_add_f32_e32 v146, v146, v147
	v_add_f32_e32 v148, v148, v149
	v_add_f32_e32 v150, v150, v151
	v_add_f32_e32 v152, v152, v153
	v_add_f32_e32 v154, v146, v148
	v_add_f32_e32 v155, v150, v152
	ds_read2_b32 v[118:119], v195 offset0:64 offset1:80
	ds_read_b128 v[72:75], v145 offset:13312
	ds_read_b128 v[76:79], v145 offset:13568
	ds_read_b128 v[64:67], v145 offset:5120
	ds_read_b128 v[68:71], v145 offset:5376
	s_waitcnt lgkmcnt(11)
	v_pk_add_f32 v[178:179], v[178:179], v[120:121] op_sel_hi:[1,0] neg_lo:[0,1] neg_hi:[0,1]
	v_add_f32_dpp v154, v154, v154 row_ror:8 row_mask:0xf bank_mask:0xf bound_ctrl:1
	v_pk_add_f32 v[186:187], v[186:187], v[120:121] op_sel:[0,1] op_sel_hi:[1,1] neg_lo:[0,1] neg_hi:[0,1]
	v_add_f32_dpp v155, v155, v155 row_ror:8 row_mask:0xf bank_mask:0xf bound_ctrl:1
	v_pk_add_f32 v[180:181], v[180:181], v[120:121] op_sel_hi:[1,0] neg_lo:[0,1] neg_hi:[0,1]
	v_add_f32_dpp v154, v154, v154 row_ror:4 row_mask:0xf bank_mask:0xf bound_ctrl:1
	v_pk_add_f32 v[188:189], v[188:189], v[120:121] op_sel:[0,1] op_sel_hi:[1,1] neg_lo:[0,1] neg_hi:[0,1]
	v_add_f32_dpp v155, v155, v155 row_ror:4 row_mask:0xf bank_mask:0xf bound_ctrl:1
	v_pk_add_f32 v[182:183], v[182:183], v[120:121] op_sel_hi:[1,0] neg_lo:[0,1] neg_hi:[0,1]
	v_add_f32_dpp v154, v154, v154 row_ror:2 row_mask:0xf bank_mask:0xf bound_ctrl:1
	v_pk_add_f32 v[190:191], v[190:191], v[120:121] op_sel:[0,1] op_sel_hi:[1,1] neg_lo:[0,1] neg_hi:[0,1]
	v_add_f32_dpp v155, v155, v155 row_ror:2 row_mask:0xf bank_mask:0xf bound_ctrl:1
	v_pk_add_f32 v[184:185], v[184:185], v[120:121] op_sel_hi:[1,0] neg_lo:[0,1] neg_hi:[0,1]
	v_add_f32_dpp v154, v154, v154 row_ror:1 row_mask:0xf bank_mask:0xf bound_ctrl:1
	v_pk_add_f32 v[192:193], v[192:193], v[120:121] op_sel:[0,1] op_sel_hi:[1,1] neg_lo:[0,1] neg_hi:[0,1]
	v_add_f32_dpp v155, v155, v155 row_ror:1 row_mask:0xf bank_mask:0xf bound_ctrl:1
	s_waitcnt lgkmcnt(10)
	v_pk_fma_f32 v[178:179], v[88:89], v[178:179], v[120:121] op_sel_hi:[1,1,0]
	ds_write_b32 v103, v154 offset:37888
	v_pk_fma_f32 v[186:187], v[88:89], v[186:187], v[120:121] op_sel:[0,0,1] op_sel_hi:[1,1,1]
	ds_write_b32 v103, v155 offset:37952
	v_pk_fma_f32 v[180:181], v[90:91], v[180:181], v[120:121] op_sel_hi:[1,1,0]
	v_pk_fma_f32 v[188:189], v[90:91], v[188:189], v[120:121] op_sel:[0,0,1] op_sel_hi:[1,1,1]
	s_waitcnt lgkmcnt(11)
	v_pk_fma_f32 v[182:183], v[92:93], v[182:183], v[120:121] op_sel_hi:[1,1,0]
	v_pk_fma_f32 v[190:191], v[92:93], v[190:191], v[120:121] op_sel:[0,0,1] op_sel_hi:[1,1,1]
	v_pk_fma_f32 v[184:185], v[94:95], v[184:185], v[120:121] op_sel_hi:[1,1,0]
	v_pk_fma_f32 v[192:193], v[94:95], v[192:193], v[120:121] op_sel:[0,0,1] op_sel_hi:[1,1,1]
	s_waitcnt lgkmcnt(10)
	v_pk_fma_f32 v[146:147], v[80:81], v[178:179], v[196:197]
	v_pk_fma_f32 v[150:151], v[80:81], v[186:187], v[196:197]
	v_pk_fma_f32 v[148:149], v[82:83], v[180:181], v[196:197]
	v_pk_fma_f32 v[152:153], v[82:83], v[188:189], v[196:197]
	s_waitcnt lgkmcnt(9)
	v_pk_fma_f32 v[146:147], v[84:85], v[182:183], v[146:147]
	v_pk_fma_f32 v[150:151], v[84:85], v[190:191], v[150:151]
	v_pk_fma_f32 v[148:149], v[86:87], v[184:185], v[148:149]
	v_pk_fma_f32 v[152:153], v[86:87], v[192:193], v[152:153]
	v_add_f32_e32 v146, v146, v147
	v_add_f32_e32 v148, v148, v149
	v_add_f32_e32 v150, v150, v151
	v_add_f32_e32 v152, v152, v153
	v_add_f32_e32 v156, v146, v148
	v_add_f32_e32 v157, v150, v152
	ds_read2_b32 v[120:121], v195 offset0:96 offset1:112
	ds_read_b128 v[88:91], v145 offset:13824
	ds_read_b128 v[92:95], v145 offset:14080
	ds_read_b128 v[80:83], v145 offset:5632
	ds_read_b128 v[84:87], v145 offset:5888
	s_waitcnt lgkmcnt(11)
	v_pk_add_f32 v[178:179], v[178:179], v[118:119] op_sel_hi:[1,0] neg_lo:[0,1] neg_hi:[0,1]
	v_add_f32_dpp v156, v156, v156 row_ror:8 row_mask:0xf bank_mask:0xf bound_ctrl:1
	v_pk_add_f32 v[186:187], v[186:187], v[118:119] op_sel:[0,1] op_sel_hi:[1,1] neg_lo:[0,1] neg_hi:[0,1]
	v_add_f32_dpp v157, v157, v157 row_ror:8 row_mask:0xf bank_mask:0xf bound_ctrl:1
	v_pk_add_f32 v[180:181], v[180:181], v[118:119] op_sel_hi:[1,0] neg_lo:[0,1] neg_hi:[0,1]
	v_add_f32_dpp v156, v156, v156 row_ror:4 row_mask:0xf bank_mask:0xf bound_ctrl:1
	v_pk_add_f32 v[188:189], v[188:189], v[118:119] op_sel:[0,1] op_sel_hi:[1,1] neg_lo:[0,1] neg_hi:[0,1]
	v_add_f32_dpp v157, v157, v157 row_ror:4 row_mask:0xf bank_mask:0xf bound_ctrl:1
	v_pk_add_f32 v[182:183], v[182:183], v[118:119] op_sel_hi:[1,0] neg_lo:[0,1] neg_hi:[0,1]
	v_add_f32_dpp v156, v156, v156 row_ror:2 row_mask:0xf bank_mask:0xf bound_ctrl:1
	v_pk_add_f32 v[190:191], v[190:191], v[118:119] op_sel:[0,1] op_sel_hi:[1,1] neg_lo:[0,1] neg_hi:[0,1]
	v_add_f32_dpp v157, v157, v157 row_ror:2 row_mask:0xf bank_mask:0xf bound_ctrl:1
	v_pk_add_f32 v[184:185], v[184:185], v[118:119] op_sel_hi:[1,0] neg_lo:[0,1] neg_hi:[0,1]
	v_add_f32_dpp v156, v156, v156 row_ror:1 row_mask:0xf bank_mask:0xf bound_ctrl:1
	v_pk_add_f32 v[192:193], v[192:193], v[118:119] op_sel:[0,1] op_sel_hi:[1,1] neg_lo:[0,1] neg_hi:[0,1]
	v_add_f32_dpp v157, v157, v157 row_ror:1 row_mask:0xf bank_mask:0xf bound_ctrl:1
	s_waitcnt lgkmcnt(10)
	v_pk_fma_f32 v[178:179], v[72:73], v[178:179], v[118:119] op_sel_hi:[1,1,0]
	ds_write_b32 v103, v156 offset:38016
	v_pk_fma_f32 v[186:187], v[72:73], v[186:187], v[118:119] op_sel:[0,0,1] op_sel_hi:[1,1,1]
	ds_write_b32 v103, v157 offset:38080
	v_pk_fma_f32 v[180:181], v[74:75], v[180:181], v[118:119] op_sel_hi:[1,1,0]
	v_pk_fma_f32 v[188:189], v[74:75], v[188:189], v[118:119] op_sel:[0,0,1] op_sel_hi:[1,1,1]
	s_waitcnt lgkmcnt(11)
	v_pk_fma_f32 v[182:183], v[76:77], v[182:183], v[118:119] op_sel_hi:[1,1,0]
	v_pk_fma_f32 v[190:191], v[76:77], v[190:191], v[118:119] op_sel:[0,0,1] op_sel_hi:[1,1,1]
	v_pk_fma_f32 v[184:185], v[78:79], v[184:185], v[118:119] op_sel_hi:[1,1,0]
	v_pk_fma_f32 v[192:193], v[78:79], v[192:193], v[118:119] op_sel:[0,0,1] op_sel_hi:[1,1,1]
	s_waitcnt lgkmcnt(10)
	v_pk_fma_f32 v[146:147], v[64:65], v[178:179], v[196:197]
	v_pk_fma_f32 v[150:151], v[64:65], v[186:187], v[196:197]
	v_pk_fma_f32 v[148:149], v[66:67], v[180:181], v[196:197]
	v_pk_fma_f32 v[152:153], v[66:67], v[188:189], v[196:197]
	s_waitcnt lgkmcnt(9)
	v_pk_fma_f32 v[146:147], v[68:69], v[182:183], v[146:147]
	v_pk_fma_f32 v[150:151], v[68:69], v[190:191], v[150:151]
	v_pk_fma_f32 v[148:149], v[70:71], v[184:185], v[148:149]
	v_pk_fma_f32 v[152:153], v[70:71], v[192:193], v[152:153]
	v_add_f32_e32 v146, v146, v147
	v_add_f32_e32 v148, v148, v149
	v_add_f32_e32 v150, v150, v151
	v_add_f32_e32 v152, v152, v153
	v_add_f32_e32 v154, v146, v148
	v_add_f32_e32 v155, v150, v152
	ds_read2_b32 v[118:119], v195 offset0:128 offset1:144
	ds_read_b128 v[72:75], v145 offset:14336
	ds_read_b128 v[76:79], v145 offset:14592
	ds_read_b128 v[64:67], v145 offset:6144
	ds_read_b128 v[68:71], v145 offset:6400
	s_waitcnt lgkmcnt(11)
	v_pk_add_f32 v[178:179], v[178:179], v[120:121] op_sel_hi:[1,0] neg_lo:[0,1] neg_hi:[0,1]
	v_add_f32_dpp v154, v154, v154 row_ror:8 row_mask:0xf bank_mask:0xf bound_ctrl:1
	v_pk_add_f32 v[186:187], v[186:187], v[120:121] op_sel:[0,1] op_sel_hi:[1,1] neg_lo:[0,1] neg_hi:[0,1]
	v_add_f32_dpp v155, v155, v155 row_ror:8 row_mask:0xf bank_mask:0xf bound_ctrl:1
	v_pk_add_f32 v[180:181], v[180:181], v[120:121] op_sel_hi:[1,0] neg_lo:[0,1] neg_hi:[0,1]
	v_add_f32_dpp v154, v154, v154 row_ror:4 row_mask:0xf bank_mask:0xf bound_ctrl:1
	v_pk_add_f32 v[188:189], v[188:189], v[120:121] op_sel:[0,1] op_sel_hi:[1,1] neg_lo:[0,1] neg_hi:[0,1]
	v_add_f32_dpp v155, v155, v155 row_ror:4 row_mask:0xf bank_mask:0xf bound_ctrl:1
	v_pk_add_f32 v[182:183], v[182:183], v[120:121] op_sel_hi:[1,0] neg_lo:[0,1] neg_hi:[0,1]
	v_add_f32_dpp v154, v154, v154 row_ror:2 row_mask:0xf bank_mask:0xf bound_ctrl:1
	v_pk_add_f32 v[190:191], v[190:191], v[120:121] op_sel:[0,1] op_sel_hi:[1,1] neg_lo:[0,1] neg_hi:[0,1]
	v_add_f32_dpp v155, v155, v155 row_ror:2 row_mask:0xf bank_mask:0xf bound_ctrl:1
	v_pk_add_f32 v[184:185], v[184:185], v[120:121] op_sel_hi:[1,0] neg_lo:[0,1] neg_hi:[0,1]
	v_add_f32_dpp v154, v154, v154 row_ror:1 row_mask:0xf bank_mask:0xf bound_ctrl:1
	v_pk_add_f32 v[192:193], v[192:193], v[120:121] op_sel:[0,1] op_sel_hi:[1,1] neg_lo:[0,1] neg_hi:[0,1]
	v_add_f32_dpp v155, v155, v155 row_ror:1 row_mask:0xf bank_mask:0xf bound_ctrl:1
	s_waitcnt lgkmcnt(10)
	v_pk_fma_f32 v[178:179], v[88:89], v[178:179], v[120:121] op_sel_hi:[1,1,0]
	ds_write_b32 v103, v154 offset:38144
	v_pk_fma_f32 v[186:187], v[88:89], v[186:187], v[120:121] op_sel:[0,0,1] op_sel_hi:[1,1,1]
	ds_write_b32 v103, v155 offset:38208
	v_pk_fma_f32 v[180:181], v[90:91], v[180:181], v[120:121] op_sel_hi:[1,1,0]
	v_pk_fma_f32 v[188:189], v[90:91], v[188:189], v[120:121] op_sel:[0,0,1] op_sel_hi:[1,1,1]
	s_waitcnt lgkmcnt(11)
	v_pk_fma_f32 v[182:183], v[92:93], v[182:183], v[120:121] op_sel_hi:[1,1,0]
	v_pk_fma_f32 v[190:191], v[92:93], v[190:191], v[120:121] op_sel:[0,0,1] op_sel_hi:[1,1,1]
	v_pk_fma_f32 v[184:185], v[94:95], v[184:185], v[120:121] op_sel_hi:[1,1,0]
	v_pk_fma_f32 v[192:193], v[94:95], v[192:193], v[120:121] op_sel:[0,0,1] op_sel_hi:[1,1,1]
	s_waitcnt lgkmcnt(10)
	v_pk_fma_f32 v[146:147], v[80:81], v[178:179], v[196:197]
	v_pk_fma_f32 v[150:151], v[80:81], v[186:187], v[196:197]
	v_pk_fma_f32 v[148:149], v[82:83], v[180:181], v[196:197]
	v_pk_fma_f32 v[152:153], v[82:83], v[188:189], v[196:197]
	s_waitcnt lgkmcnt(9)
	v_pk_fma_f32 v[146:147], v[84:85], v[182:183], v[146:147]
	v_pk_fma_f32 v[150:151], v[84:85], v[190:191], v[150:151]
	v_pk_fma_f32 v[148:149], v[86:87], v[184:185], v[148:149]
	v_pk_fma_f32 v[152:153], v[86:87], v[192:193], v[152:153]
	v_add_f32_e32 v146, v146, v147
	v_add_f32_e32 v148, v148, v149
	v_add_f32_e32 v150, v150, v151
	v_add_f32_e32 v152, v152, v153
	v_add_f32_e32 v156, v146, v148
	v_add_f32_e32 v157, v150, v152
	ds_read2_b32 v[120:121], v195 offset0:160 offset1:176
	ds_read_b128 v[88:91], v145 offset:14848
	ds_read_b128 v[92:95], v145 offset:15104
	ds_read_b128 v[80:83], v145 offset:6656
	ds_read_b128 v[84:87], v145 offset:6912
	s_waitcnt lgkmcnt(11)
	v_pk_add_f32 v[178:179], v[178:179], v[118:119] op_sel_hi:[1,0] neg_lo:[0,1] neg_hi:[0,1]
	v_add_f32_dpp v156, v156, v156 row_ror:8 row_mask:0xf bank_mask:0xf bound_ctrl:1
	v_pk_add_f32 v[186:187], v[186:187], v[118:119] op_sel:[0,1] op_sel_hi:[1,1] neg_lo:[0,1] neg_hi:[0,1]
	v_add_f32_dpp v157, v157, v157 row_ror:8 row_mask:0xf bank_mask:0xf bound_ctrl:1
	v_pk_add_f32 v[180:181], v[180:181], v[118:119] op_sel_hi:[1,0] neg_lo:[0,1] neg_hi:[0,1]
	v_add_f32_dpp v156, v156, v156 row_ror:4 row_mask:0xf bank_mask:0xf bound_ctrl:1
	v_pk_add_f32 v[188:189], v[188:189], v[118:119] op_sel:[0,1] op_sel_hi:[1,1] neg_lo:[0,1] neg_hi:[0,1]
	v_add_f32_dpp v157, v157, v157 row_ror:4 row_mask:0xf bank_mask:0xf bound_ctrl:1
	v_pk_add_f32 v[182:183], v[182:183], v[118:119] op_sel_hi:[1,0] neg_lo:[0,1] neg_hi:[0,1]
	v_add_f32_dpp v156, v156, v156 row_ror:2 row_mask:0xf bank_mask:0xf bound_ctrl:1
	v_pk_add_f32 v[190:191], v[190:191], v[118:119] op_sel:[0,1] op_sel_hi:[1,1] neg_lo:[0,1] neg_hi:[0,1]
	v_add_f32_dpp v157, v157, v157 row_ror:2 row_mask:0xf bank_mask:0xf bound_ctrl:1
	v_pk_add_f32 v[184:185], v[184:185], v[118:119] op_sel_hi:[1,0] neg_lo:[0,1] neg_hi:[0,1]
	v_add_f32_dpp v156, v156, v156 row_ror:1 row_mask:0xf bank_mask:0xf bound_ctrl:1
	v_pk_add_f32 v[192:193], v[192:193], v[118:119] op_sel:[0,1] op_sel_hi:[1,1] neg_lo:[0,1] neg_hi:[0,1]
	v_add_f32_dpp v157, v157, v157 row_ror:1 row_mask:0xf bank_mask:0xf bound_ctrl:1
	s_waitcnt lgkmcnt(10)
	v_pk_fma_f32 v[178:179], v[72:73], v[178:179], v[118:119] op_sel_hi:[1,1,0]
	ds_write_b32 v103, v156 offset:38272
	v_pk_fma_f32 v[186:187], v[72:73], v[186:187], v[118:119] op_sel:[0,0,1] op_sel_hi:[1,1,1]
	ds_write_b32 v103, v157 offset:38336
	v_pk_fma_f32 v[180:181], v[74:75], v[180:181], v[118:119] op_sel_hi:[1,1,0]
	v_pk_fma_f32 v[188:189], v[74:75], v[188:189], v[118:119] op_sel:[0,0,1] op_sel_hi:[1,1,1]
	s_waitcnt lgkmcnt(11)
	v_pk_fma_f32 v[182:183], v[76:77], v[182:183], v[118:119] op_sel_hi:[1,1,0]
	v_pk_fma_f32 v[190:191], v[76:77], v[190:191], v[118:119] op_sel:[0,0,1] op_sel_hi:[1,1,1]
	v_pk_fma_f32 v[184:185], v[78:79], v[184:185], v[118:119] op_sel_hi:[1,1,0]
	v_pk_fma_f32 v[192:193], v[78:79], v[192:193], v[118:119] op_sel:[0,0,1] op_sel_hi:[1,1,1]
	s_waitcnt lgkmcnt(10)
	v_pk_fma_f32 v[146:147], v[64:65], v[178:179], v[196:197]
	v_pk_fma_f32 v[150:151], v[64:65], v[186:187], v[196:197]
	v_pk_fma_f32 v[148:149], v[66:67], v[180:181], v[196:197]
	v_pk_fma_f32 v[152:153], v[66:67], v[188:189], v[196:197]
	s_waitcnt lgkmcnt(9)
	v_pk_fma_f32 v[146:147], v[68:69], v[182:183], v[146:147]
	v_pk_fma_f32 v[150:151], v[68:69], v[190:191], v[150:151]
	v_pk_fma_f32 v[148:149], v[70:71], v[184:185], v[148:149]
	v_pk_fma_f32 v[152:153], v[70:71], v[192:193], v[152:153]
	v_add_f32_e32 v146, v146, v147
	v_add_f32_e32 v148, v148, v149
	v_add_f32_e32 v150, v150, v151
	v_add_f32_e32 v152, v152, v153
	v_add_f32_e32 v154, v146, v148
	v_add_f32_e32 v155, v150, v152
	ds_read2_b32 v[118:119], v195 offset0:192 offset1:208
	ds_read_b128 v[72:75], v145 offset:15360
	ds_read_b128 v[76:79], v145 offset:15616
	ds_read_b128 v[64:67], v145 offset:7168
	ds_read_b128 v[68:71], v145 offset:7424
	s_waitcnt lgkmcnt(11)
	v_pk_add_f32 v[178:179], v[178:179], v[120:121] op_sel_hi:[1,0] neg_lo:[0,1] neg_hi:[0,1]
	v_add_f32_dpp v154, v154, v154 row_ror:8 row_mask:0xf bank_mask:0xf bound_ctrl:1
	v_pk_add_f32 v[186:187], v[186:187], v[120:121] op_sel:[0,1] op_sel_hi:[1,1] neg_lo:[0,1] neg_hi:[0,1]
	v_add_f32_dpp v155, v155, v155 row_ror:8 row_mask:0xf bank_mask:0xf bound_ctrl:1
	v_pk_add_f32 v[180:181], v[180:181], v[120:121] op_sel_hi:[1,0] neg_lo:[0,1] neg_hi:[0,1]
	v_add_f32_dpp v154, v154, v154 row_ror:4 row_mask:0xf bank_mask:0xf bound_ctrl:1
	v_pk_add_f32 v[188:189], v[188:189], v[120:121] op_sel:[0,1] op_sel_hi:[1,1] neg_lo:[0,1] neg_hi:[0,1]
	v_add_f32_dpp v155, v155, v155 row_ror:4 row_mask:0xf bank_mask:0xf bound_ctrl:1
	v_pk_add_f32 v[182:183], v[182:183], v[120:121] op_sel_hi:[1,0] neg_lo:[0,1] neg_hi:[0,1]
	v_add_f32_dpp v154, v154, v154 row_ror:2 row_mask:0xf bank_mask:0xf bound_ctrl:1
	v_pk_add_f32 v[190:191], v[190:191], v[120:121] op_sel:[0,1] op_sel_hi:[1,1] neg_lo:[0,1] neg_hi:[0,1]
	v_add_f32_dpp v155, v155, v155 row_ror:2 row_mask:0xf bank_mask:0xf bound_ctrl:1
	v_pk_add_f32 v[184:185], v[184:185], v[120:121] op_sel_hi:[1,0] neg_lo:[0,1] neg_hi:[0,1]
	v_add_f32_dpp v154, v154, v154 row_ror:1 row_mask:0xf bank_mask:0xf bound_ctrl:1
	v_pk_add_f32 v[192:193], v[192:193], v[120:121] op_sel:[0,1] op_sel_hi:[1,1] neg_lo:[0,1] neg_hi:[0,1]
	v_add_f32_dpp v155, v155, v155 row_ror:1 row_mask:0xf bank_mask:0xf bound_ctrl:1
	s_waitcnt lgkmcnt(10)
	v_pk_fma_f32 v[178:179], v[88:89], v[178:179], v[120:121] op_sel_hi:[1,1,0]
	ds_write_b32 v103, v154 offset:38400
	v_pk_fma_f32 v[186:187], v[88:89], v[186:187], v[120:121] op_sel:[0,0,1] op_sel_hi:[1,1,1]
	ds_write_b32 v103, v155 offset:38464
	v_pk_fma_f32 v[180:181], v[90:91], v[180:181], v[120:121] op_sel_hi:[1,1,0]
	v_pk_fma_f32 v[188:189], v[90:91], v[188:189], v[120:121] op_sel:[0,0,1] op_sel_hi:[1,1,1]
	s_waitcnt lgkmcnt(11)
	v_pk_fma_f32 v[182:183], v[92:93], v[182:183], v[120:121] op_sel_hi:[1,1,0]
	v_pk_fma_f32 v[190:191], v[92:93], v[190:191], v[120:121] op_sel:[0,0,1] op_sel_hi:[1,1,1]
	v_pk_fma_f32 v[184:185], v[94:95], v[184:185], v[120:121] op_sel_hi:[1,1,0]
	v_pk_fma_f32 v[192:193], v[94:95], v[192:193], v[120:121] op_sel:[0,0,1] op_sel_hi:[1,1,1]
	s_waitcnt lgkmcnt(10)
	v_pk_fma_f32 v[146:147], v[80:81], v[178:179], v[196:197]
	v_pk_fma_f32 v[150:151], v[80:81], v[186:187], v[196:197]
	v_pk_fma_f32 v[148:149], v[82:83], v[180:181], v[196:197]
	v_pk_fma_f32 v[152:153], v[82:83], v[188:189], v[196:197]
	s_waitcnt lgkmcnt(9)
	v_pk_fma_f32 v[146:147], v[84:85], v[182:183], v[146:147]
	v_pk_fma_f32 v[150:151], v[84:85], v[190:191], v[150:151]
	v_pk_fma_f32 v[148:149], v[86:87], v[184:185], v[148:149]
	v_pk_fma_f32 v[152:153], v[86:87], v[192:193], v[152:153]
	v_add_f32_e32 v146, v146, v147
	v_add_f32_e32 v148, v148, v149
	v_add_f32_e32 v150, v150, v151
	v_add_f32_e32 v152, v152, v153
	v_add_f32_e32 v156, v146, v148
	v_add_f32_e32 v157, v150, v152
	ds_read2_b32 v[120:121], v195 offset0:224 offset1:240
	ds_read_b128 v[88:91], v145 offset:15872
	ds_read_b128 v[92:95], v145 offset:16128
	ds_read_b128 v[80:83], v145 offset:7680
	ds_read_b128 v[84:87], v145 offset:7936
	s_waitcnt lgkmcnt(11)
	v_pk_add_f32 v[178:179], v[178:179], v[118:119] op_sel_hi:[1,0] neg_lo:[0,1] neg_hi:[0,1]
	v_add_f32_dpp v156, v156, v156 row_ror:8 row_mask:0xf bank_mask:0xf bound_ctrl:1
	v_pk_add_f32 v[186:187], v[186:187], v[118:119] op_sel:[0,1] op_sel_hi:[1,1] neg_lo:[0,1] neg_hi:[0,1]
	v_add_f32_dpp v157, v157, v157 row_ror:8 row_mask:0xf bank_mask:0xf bound_ctrl:1
	v_pk_add_f32 v[180:181], v[180:181], v[118:119] op_sel_hi:[1,0] neg_lo:[0,1] neg_hi:[0,1]
	v_add_f32_dpp v156, v156, v156 row_ror:4 row_mask:0xf bank_mask:0xf bound_ctrl:1
	v_pk_add_f32 v[188:189], v[188:189], v[118:119] op_sel:[0,1] op_sel_hi:[1,1] neg_lo:[0,1] neg_hi:[0,1]
	v_add_f32_dpp v157, v157, v157 row_ror:4 row_mask:0xf bank_mask:0xf bound_ctrl:1
	v_pk_add_f32 v[182:183], v[182:183], v[118:119] op_sel_hi:[1,0] neg_lo:[0,1] neg_hi:[0,1]
	v_add_f32_dpp v156, v156, v156 row_ror:2 row_mask:0xf bank_mask:0xf bound_ctrl:1
	v_pk_add_f32 v[190:191], v[190:191], v[118:119] op_sel:[0,1] op_sel_hi:[1,1] neg_lo:[0,1] neg_hi:[0,1]
	v_add_f32_dpp v157, v157, v157 row_ror:2 row_mask:0xf bank_mask:0xf bound_ctrl:1
	v_pk_add_f32 v[184:185], v[184:185], v[118:119] op_sel_hi:[1,0] neg_lo:[0,1] neg_hi:[0,1]
	v_add_f32_dpp v156, v156, v156 row_ror:1 row_mask:0xf bank_mask:0xf bound_ctrl:1
	v_pk_add_f32 v[192:193], v[192:193], v[118:119] op_sel:[0,1] op_sel_hi:[1,1] neg_lo:[0,1] neg_hi:[0,1]
	v_add_f32_dpp v157, v157, v157 row_ror:1 row_mask:0xf bank_mask:0xf bound_ctrl:1
	s_waitcnt lgkmcnt(10)
	v_pk_fma_f32 v[178:179], v[72:73], v[178:179], v[118:119] op_sel_hi:[1,1,0]
	ds_write_b32 v103, v156 offset:38528
	v_pk_fma_f32 v[186:187], v[72:73], v[186:187], v[118:119] op_sel:[0,0,1] op_sel_hi:[1,1,1]
	ds_write_b32 v103, v157 offset:38592
	v_pk_fma_f32 v[180:181], v[74:75], v[180:181], v[118:119] op_sel_hi:[1,1,0]
	v_pk_fma_f32 v[188:189], v[74:75], v[188:189], v[118:119] op_sel:[0,0,1] op_sel_hi:[1,1,1]
	s_waitcnt lgkmcnt(11)
	v_pk_fma_f32 v[182:183], v[76:77], v[182:183], v[118:119] op_sel_hi:[1,1,0]
	v_pk_fma_f32 v[190:191], v[76:77], v[190:191], v[118:119] op_sel:[0,0,1] op_sel_hi:[1,1,1]
	v_pk_fma_f32 v[184:185], v[78:79], v[184:185], v[118:119] op_sel_hi:[1,1,0]
	v_pk_fma_f32 v[192:193], v[78:79], v[192:193], v[118:119] op_sel:[0,0,1] op_sel_hi:[1,1,1]
	s_waitcnt lgkmcnt(10)
	v_pk_fma_f32 v[146:147], v[64:65], v[178:179], v[196:197]
	v_pk_fma_f32 v[150:151], v[64:65], v[186:187], v[196:197]
	v_pk_fma_f32 v[148:149], v[66:67], v[180:181], v[196:197]
	v_pk_fma_f32 v[152:153], v[66:67], v[188:189], v[196:197]
	s_waitcnt lgkmcnt(9)
	v_pk_fma_f32 v[146:147], v[68:69], v[182:183], v[146:147]
	v_pk_fma_f32 v[150:151], v[68:69], v[190:191], v[150:151]
	v_pk_fma_f32 v[148:149], v[70:71], v[184:185], v[148:149]
	v_pk_fma_f32 v[152:153], v[70:71], v[192:193], v[152:153]
	v_add_f32_e32 v146, v146, v147
	v_add_f32_e32 v148, v148, v149
	v_add_f32_e32 v150, v150, v151
	v_add_f32_e32 v152, v152, v153
	v_add_f32_e32 v154, v146, v148
	v_add_f32_e32 v155, v150, v152
	s_waitcnt lgkmcnt(6)
	v_pk_add_f32 v[178:179], v[178:179], v[120:121] op_sel_hi:[1,0] neg_lo:[0,1] neg_hi:[0,1]
	v_add_f32_dpp v154, v154, v154 row_ror:8 row_mask:0xf bank_mask:0xf bound_ctrl:1
	v_pk_add_f32 v[186:187], v[186:187], v[120:121] op_sel:[0,1] op_sel_hi:[1,1] neg_lo:[0,1] neg_hi:[0,1]
	v_add_f32_dpp v155, v155, v155 row_ror:8 row_mask:0xf bank_mask:0xf bound_ctrl:1
	v_pk_add_f32 v[180:181], v[180:181], v[120:121] op_sel_hi:[1,0] neg_lo:[0,1] neg_hi:[0,1]
	v_add_f32_dpp v154, v154, v154 row_ror:4 row_mask:0xf bank_mask:0xf bound_ctrl:1
	v_pk_add_f32 v[188:189], v[188:189], v[120:121] op_sel:[0,1] op_sel_hi:[1,1] neg_lo:[0,1] neg_hi:[0,1]
	v_add_f32_dpp v155, v155, v155 row_ror:4 row_mask:0xf bank_mask:0xf bound_ctrl:1
	v_pk_add_f32 v[182:183], v[182:183], v[120:121] op_sel_hi:[1,0] neg_lo:[0,1] neg_hi:[0,1]
	v_add_f32_dpp v154, v154, v154 row_ror:2 row_mask:0xf bank_mask:0xf bound_ctrl:1
	v_pk_add_f32 v[190:191], v[190:191], v[120:121] op_sel:[0,1] op_sel_hi:[1,1] neg_lo:[0,1] neg_hi:[0,1]
	v_add_f32_dpp v155, v155, v155 row_ror:2 row_mask:0xf bank_mask:0xf bound_ctrl:1
	v_pk_add_f32 v[184:185], v[184:185], v[120:121] op_sel_hi:[1,0] neg_lo:[0,1] neg_hi:[0,1]
	v_add_f32_dpp v154, v154, v154 row_ror:1 row_mask:0xf bank_mask:0xf bound_ctrl:1
	v_pk_add_f32 v[192:193], v[192:193], v[120:121] op_sel:[0,1] op_sel_hi:[1,1] neg_lo:[0,1] neg_hi:[0,1]
	v_add_f32_dpp v155, v155, v155 row_ror:1 row_mask:0xf bank_mask:0xf bound_ctrl:1
	s_waitcnt lgkmcnt(5)
	v_pk_fma_f32 v[178:179], v[88:89], v[178:179], v[120:121] op_sel_hi:[1,1,0]
	ds_write_b32 v103, v154 offset:38656
	v_pk_fma_f32 v[186:187], v[88:89], v[186:187], v[120:121] op_sel:[0,0,1] op_sel_hi:[1,1,1]
	ds_write_b32 v103, v155 offset:38720
	v_pk_fma_f32 v[180:181], v[90:91], v[180:181], v[120:121] op_sel_hi:[1,1,0]
	v_pk_fma_f32 v[188:189], v[90:91], v[188:189], v[120:121] op_sel:[0,0,1] op_sel_hi:[1,1,1]
	s_waitcnt lgkmcnt(6)
	v_pk_fma_f32 v[182:183], v[92:93], v[182:183], v[120:121] op_sel_hi:[1,1,0]
	v_pk_fma_f32 v[190:191], v[92:93], v[190:191], v[120:121] op_sel:[0,0,1] op_sel_hi:[1,1,1]
	v_pk_fma_f32 v[184:185], v[94:95], v[184:185], v[120:121] op_sel_hi:[1,1,0]
	v_pk_fma_f32 v[192:193], v[94:95], v[192:193], v[120:121] op_sel:[0,0,1] op_sel_hi:[1,1,1]
	s_waitcnt lgkmcnt(5)
	v_pk_fma_f32 v[146:147], v[80:81], v[178:179], v[196:197]
	v_pk_fma_f32 v[150:151], v[80:81], v[186:187], v[196:197]
	v_pk_fma_f32 v[148:149], v[82:83], v[180:181], v[196:197]
	v_pk_fma_f32 v[152:153], v[82:83], v[188:189], v[196:197]
	s_waitcnt lgkmcnt(4)
	v_pk_fma_f32 v[146:147], v[84:85], v[182:183], v[146:147]
	v_pk_fma_f32 v[150:151], v[84:85], v[190:191], v[150:151]
	v_pk_fma_f32 v[148:149], v[86:87], v[184:185], v[148:149]
	v_pk_fma_f32 v[152:153], v[86:87], v[192:193], v[152:153]
	v_add_f32_e32 v146, v146, v147
	v_add_f32_e32 v148, v148, v149
	v_add_f32_e32 v150, v150, v151
	v_add_f32_e32 v152, v152, v153
	v_add_f32_e32 v156, v146, v148
	v_add_f32_e32 v157, v150, v152
	s_nop 0
	v_add_f32_dpp v156, v156, v156 row_ror:8 row_mask:0xf bank_mask:0xf bound_ctrl:1
	v_add_f32_dpp v157, v157, v157 row_ror:8 row_mask:0xf bank_mask:0xf bound_ctrl:1
	s_nop 0
	v_add_f32_dpp v156, v156, v156 row_ror:4 row_mask:0xf bank_mask:0xf bound_ctrl:1
	v_add_f32_dpp v157, v157, v157 row_ror:4 row_mask:0xf bank_mask:0xf bound_ctrl:1
	s_nop 0
	v_add_f32_dpp v156, v156, v156 row_ror:2 row_mask:0xf bank_mask:0xf bound_ctrl:1
	v_add_f32_dpp v157, v157, v157 row_ror:2 row_mask:0xf bank_mask:0xf bound_ctrl:1
	s_nop 0
	v_add_f32_dpp v156, v156, v156 row_ror:1 row_mask:0xf bank_mask:0xf bound_ctrl:1
	v_add_f32_dpp v157, v157, v157 row_ror:1 row_mask:0xf bank_mask:0xf bound_ctrl:1
	ds_write_b32 v103, v156 offset:38784
	ds_write_b32 v103, v157 offset:38848
	s_waitcnt vmcnt(5)
	v_mul_f32_e32 v64, 0xbfb8aa3b, v44
	v_mul_f32_e32 v65, 0xbfb8aa3b, v45
	v_exp_f32_e32 v64, v64
	v_exp_f32_e32 v65, v65
	v_mul_f32_e32 v66, 0xbfb8aa3b, v46
	v_mul_f32_e32 v67, 0xbfb8aa3b, v47
	v_exp_f32_e32 v66, v66
	v_pk_add_f32 v[64:65], v[64:65], 1.0 op_sel_hi:[1,0]
	v_exp_f32_e32 v67, v67
	v_div_scale_f32 v80, s[8:9], v65, v65, v45
	v_rcp_f32_e32 v81, v80
	v_pk_add_f32 v[66:67], v[66:67], 1.0 op_sel_hi:[1,0]
	v_mul_f32_e32 v72, 0xbfb8aa3b, v48
	v_mul_f32_e32 v73, 0xbfb8aa3b, v49
	v_fma_f32 v82, -v80, v81, 1.0
	v_fmac_f32_e32 v81, v82, v81
	v_div_scale_f32 v82, vcc, v45, v65, v45
	v_mul_f32_e32 v83, v82, v81
	v_fma_f32 v88, -v80, v83, v82
	v_fmac_f32_e32 v83, v88, v81
	v_fma_f32 v80, -v80, v83, v82
	v_div_fmas_f32 v80, v80, v81, v83
	v_div_fixup_f32 v65, v80, v65, v45
	v_div_scale_f32 v80, s[8:9], v64, v64, v44
	v_rcp_f32_e32 v81, v80
	v_exp_f32_e32 v72, v72
	v_exp_f32_e32 v73, v73
	v_mul_f32_e32 v74, 0xbfb8aa3b, v50
	v_fma_f32 v82, -v80, v81, 1.0
	v_fmac_f32_e32 v81, v82, v81
	v_div_scale_f32 v82, vcc, v44, v64, v44
	v_mul_f32_e32 v83, v82, v81
	v_fma_f32 v88, -v80, v83, v82
	v_fmac_f32_e32 v83, v88, v81
	v_fma_f32 v80, -v80, v83, v82
	v_div_fmas_f32 v80, v80, v81, v83
	v_div_fixup_f32 v64, v80, v64, v44
	v_div_scale_f32 v80, s[8:9], v67, v67, v47
	v_rcp_f32_e32 v81, v80
	v_pk_mul_f32 v[64:65], v[64:65], s[18:19] op_sel_hi:[1,0]
	v_mul_f32_e32 v75, 0xbfb8aa3b, v51
	v_exp_f32_e32 v74, v74
	v_fma_f32 v82, -v80, v81, 1.0
	v_fmac_f32_e32 v81, v82, v81
	v_div_scale_f32 v82, vcc, v47, v67, v47
	v_mul_f32_e32 v83, v82, v81
	v_fma_f32 v88, -v80, v83, v82
	v_fmac_f32_e32 v83, v88, v81
	v_fma_f32 v80, -v80, v83, v82
	v_div_fmas_f32 v80, v80, v81, v83
	v_div_fixup_f32 v67, v80, v67, v47
	v_div_scale_f32 v80, s[8:9], v66, v66, v46
	v_rcp_f32_e32 v81, v80
	v_exp_f32_e32 v75, v75
	s_cmpk_gt_u32 s48, 0x78
	v_fma_f32 v82, -v80, v81, 1.0
	v_fmac_f32_e32 v81, v82, v81
	v_div_scale_f32 v82, vcc, v46, v66, v46
	v_mul_f32_e32 v83, v82, v81
	v_fma_f32 v88, -v80, v83, v82
	v_fmac_f32_e32 v83, v88, v81
	v_fma_f32 v80, -v80, v83, v82
	v_div_fmas_f32 v80, v80, v81, v83
	v_div_fixup_f32 v66, v80, v66, v46
	v_pk_mul_f32 v[66:67], v[66:67], s[18:19] op_sel_hi:[1,0]
	ds_write_b128 v141, v[64:67] offset:18432
	v_pk_add_f32 v[64:65], v[72:73], 1.0 op_sel_hi:[1,0]
	v_div_scale_f32 v66, s[8:9], v65, v65, 1.0
	v_rcp_f32_e32 v67, v66
	s_nop 0
	v_fma_f32 v72, -v66, v67, 1.0
	v_fmac_f32_e32 v67, v72, v67
	v_div_scale_f32 v72, vcc, 1.0, v65, 1.0
	v_mul_f32_e32 v73, v72, v67
	v_fma_f32 v80, -v66, v73, v72
	v_fmac_f32_e32 v73, v80, v67
	v_fma_f32 v66, -v66, v73, v72
	v_div_fmas_f32 v66, v66, v67, v73
	v_div_fixup_f32 v65, v66, v65, 1.0
	v_div_scale_f32 v66, s[8:9], v64, v64, 1.0
	v_rcp_f32_e32 v67, v66
	s_nop 0
	v_fma_f32 v72, -v66, v67, 1.0
	v_fmac_f32_e32 v67, v72, v67
	v_div_scale_f32 v72, vcc, 1.0, v64, 1.0
	v_mul_f32_e32 v73, v72, v67
	v_fma_f32 v80, -v66, v73, v72
	v_fmac_f32_e32 v73, v80, v67
	v_fma_f32 v66, -v66, v73, v72
	v_div_fmas_f32 v66, v66, v67, v73
	v_div_fixup_f32 v64, v66, v64, 1.0
	v_pk_add_f32 v[66:67], v[74:75], 1.0 op_sel_hi:[1,0]
	v_pk_fma_f32 v[64:65], v[110:111], v[64:65], v[104:105]
	v_div_scale_f32 v72, s[8:9], v67, v67, 1.0
	v_rcp_f32_e32 v73, v72
	s_nop 0
	v_fma_f32 v74, -v72, v73, 1.0
	v_fmac_f32_e32 v73, v74, v73
	v_div_scale_f32 v74, vcc, 1.0, v67, 1.0
	v_mul_f32_e32 v75, v74, v73
	v_fma_f32 v80, -v72, v75, v74
	v_fmac_f32_e32 v75, v80, v73
	v_fma_f32 v72, -v72, v75, v74
	v_div_fmas_f32 v72, v72, v73, v75
	v_div_fixup_f32 v67, v72, v67, 1.0
	v_div_scale_f32 v72, s[8:9], v66, v66, 1.0
	v_rcp_f32_e32 v73, v72
	s_nop 0
	v_fma_f32 v74, -v72, v73, 1.0
	v_fmac_f32_e32 v73, v74, v73
	v_div_scale_f32 v74, vcc, 1.0, v66, 1.0
	v_mul_f32_e32 v75, v74, v73
	v_fma_f32 v80, -v72, v75, v74
	v_fmac_f32_e32 v75, v80, v73
	v_fma_f32 v72, -v72, v75, v74
	v_div_fmas_f32 v72, v72, v73, v75
	v_div_fixup_f32 v66, v72, v66, 1.0
	v_pk_fma_f32 v[66:67], v[112:113], v[66:67], v[106:107]
	ds_write_b128 v141, v[64:67] offset:26624
	ds_write_b32 v134, v133 offset:34816
	v_mul_f32_e32 v64, 0xbfb8aa3b, v56
	v_mul_f32_e32 v65, 0xbfb8aa3b, v57
	v_exp_f32_e32 v64, v64
	v_exp_f32_e32 v65, v65
	v_mul_f32_e32 v66, 0xbfb8aa3b, v58
	v_mul_f32_e32 v67, 0xbfb8aa3b, v59
	v_exp_f32_e32 v66, v66
	v_pk_add_f32 v[64:65], v[64:65], 1.0 op_sel_hi:[1,0]
	v_exp_f32_e32 v67, v67
	v_div_scale_f32 v80, s[8:9], v65, v65, v57
	v_rcp_f32_e32 v81, v80
	v_pk_add_f32 v[66:67], v[66:67], 1.0 op_sel_hi:[1,0]
	s_waitcnt vmcnt(4)
	v_mul_f32_e32 v72, 0xbfb8aa3b, v60
	v_mul_f32_e32 v73, 0xbfb8aa3b, v61
	v_fma_f32 v82, -v80, v81, 1.0
	v_fmac_f32_e32 v81, v82, v81
	v_div_scale_f32 v82, vcc, v57, v65, v57
	v_mul_f32_e32 v83, v82, v81
	v_fma_f32 v88, -v80, v83, v82
	v_fmac_f32_e32 v83, v88, v81
	v_fma_f32 v80, -v80, v83, v82
	v_div_fmas_f32 v80, v80, v81, v83
	v_div_fixup_f32 v65, v80, v65, v57
	v_div_scale_f32 v80, s[8:9], v64, v64, v56
	v_rcp_f32_e32 v81, v80
	v_exp_f32_e32 v72, v72
	v_exp_f32_e32 v73, v73
	v_mul_f32_e32 v74, 0xbfb8aa3b, v62
	v_fma_f32 v82, -v80, v81, 1.0
	v_fmac_f32_e32 v81, v82, v81
	v_div_scale_f32 v82, vcc, v56, v64, v56
	v_mul_f32_e32 v83, v82, v81
	v_fma_f32 v88, -v80, v83, v82
	v_fmac_f32_e32 v83, v88, v81
	v_fma_f32 v80, -v80, v83, v82
	v_div_fmas_f32 v80, v80, v81, v83
	v_div_fixup_f32 v64, v80, v64, v56
	v_div_scale_f32 v80, s[8:9], v67, v67, v59
	v_rcp_f32_e32 v81, v80
	v_pk_mul_f32 v[64:65], v[64:65], s[18:19] op_sel_hi:[1,0]
	v_mul_f32_e32 v75, 0xbfb8aa3b, v63
	v_exp_f32_e32 v74, v74
	v_fma_f32 v82, -v80, v81, 1.0
	v_fmac_f32_e32 v81, v82, v81
	v_div_scale_f32 v82, vcc, v59, v67, v59
	v_mul_f32_e32 v83, v82, v81
	v_fma_f32 v88, -v80, v83, v82
	v_fmac_f32_e32 v83, v88, v81
	v_fma_f32 v80, -v80, v83, v82
	v_div_fmas_f32 v80, v80, v81, v83
	v_div_fixup_f32 v67, v80, v67, v59
	v_div_scale_f32 v80, s[8:9], v66, v66, v58
	v_rcp_f32_e32 v81, v80
	v_exp_f32_e32 v75, v75
	v_fma_f32 v82, -v80, v81, 1.0
	v_fmac_f32_e32 v81, v82, v81
	v_div_scale_f32 v82, vcc, v58, v66, v58
	v_mul_f32_e32 v83, v82, v81
	v_fma_f32 v88, -v80, v83, v82
	v_fmac_f32_e32 v83, v88, v81
	v_fma_f32 v80, -v80, v83, v82
	v_div_fmas_f32 v80, v80, v81, v83
	v_div_fixup_f32 v66, v80, v66, v58
	v_pk_mul_f32 v[66:67], v[66:67], s[18:19] op_sel_hi:[1,0]
	ds_write_b128 v144, v[64:67] offset:18432
	v_pk_add_f32 v[64:65], v[72:73], 1.0 op_sel_hi:[1,0]
	v_div_scale_f32 v66, s[8:9], v65, v65, 1.0
	v_rcp_f32_e32 v67, v66
	s_nop 0
	v_fma_f32 v72, -v66, v67, 1.0
	v_fmac_f32_e32 v67, v72, v67
	v_div_scale_f32 v72, vcc, 1.0, v65, 1.0
	v_mul_f32_e32 v73, v72, v67
	v_fma_f32 v80, -v66, v73, v72
	v_fmac_f32_e32 v73, v80, v67
	v_fma_f32 v66, -v66, v73, v72
	v_div_fmas_f32 v66, v66, v67, v73
	v_div_fixup_f32 v65, v66, v65, 1.0
	v_div_scale_f32 v66, s[8:9], v64, v64, 1.0
	v_rcp_f32_e32 v67, v66
	s_nop 0
	v_fma_f32 v72, -v66, v67, 1.0
	v_fmac_f32_e32 v67, v72, v67
	v_div_scale_f32 v72, vcc, 1.0, v64, 1.0
	v_mul_f32_e32 v73, v72, v67
	v_fma_f32 v80, -v66, v73, v72
	v_fmac_f32_e32 v73, v80, v67
	v_fma_f32 v66, -v66, v73, v72
	v_div_fmas_f32 v66, v66, v67, v73
	v_div_fixup_f32 v64, v66, v64, 1.0
	v_pk_add_f32 v[66:67], v[74:75], 1.0 op_sel_hi:[1,0]
	v_pk_fma_f32 v[64:65], v[110:111], v[64:65], v[104:105]
	v_div_scale_f32 v72, s[8:9], v67, v67, 1.0
	v_rcp_f32_e32 v73, v72
	s_nop 0
	v_fma_f32 v74, -v72, v73, 1.0
	v_fmac_f32_e32 v73, v74, v73
	v_div_scale_f32 v74, vcc, 1.0, v67, 1.0
	v_mul_f32_e32 v75, v74, v73
	v_fma_f32 v80, -v72, v75, v74
	v_fmac_f32_e32 v75, v80, v73
	v_fma_f32 v72, -v72, v75, v74
	v_div_fmas_f32 v72, v72, v73, v75
	v_div_fixup_f32 v67, v72, v67, 1.0
	v_div_scale_f32 v72, s[8:9], v66, v66, 1.0
	v_rcp_f32_e32 v73, v72
	s_nop 0
	v_fma_f32 v74, -v72, v73, 1.0
	v_fmac_f32_e32 v73, v74, v73
	v_div_scale_f32 v74, vcc, 1.0, v66, 1.0
	v_mul_f32_e32 v75, v74, v73
	v_fma_f32 v80, -v72, v75, v74
	v_fmac_f32_e32 v75, v80, v73
	v_fma_f32 v72, -v72, v75, v74
	v_div_fmas_f32 v72, v72, v73, v75
	v_div_fixup_f32 v66, v72, v66, 1.0
	v_pk_fma_f32 v[66:67], v[112:113], v[66:67], v[106:107]
	ds_write_b128 v144, v[64:67] offset:26624
	ds_write_b32 v134, v135 offset:35840
	s_waitcnt lgkmcnt(0)
	s_barrier
	s_cbranch_scc1 .LBB0_1393
	v_add_u32_e32 v44, 0x70, v98
	v_mov_b64_e32 v[56:57], s[30:31]
	v_mad_i64_i32 v[44:45], s[8:9], v44, s25, v[56:57]
	s_lshl_b32 s94, s46, 2
	v_lshl_add_u64 v[58:59], v[44:45], 0, s[94:95]
	v_mov_b32_e32 v117, v140
	v_lshl_add_u64 v[44:45], v[58:59], 0, v[116:117]
	v_add_co_u32_e32 v46, vcc, 0x4000, v44
	s_lshl_b32 s8, s42, 2
	s_nop 0
	v_addc_co_u32_e32 v47, vcc, 0, v45, vcc
	s_mov_b32 s9, s95
	v_add_co_u32_e32 v48, vcc, 0x5000, v44
	v_lshl_add_u64 v[58:59], v[58:59], 0, s[8:9]
	v_mov_b32_e32 v115, v140
	v_add_u32_e32 v60, 0x70, v96
	v_addc_co_u32_e32 v49, vcc, 0, v45, vcc
	v_lshl_add_u64 v[58:59], v[58:59], 0, v[114:115]
	v_mad_i64_i32 v[56:57], s[22:23], v60, s25, v[56:57]
	v_add_co_u32_e32 v58, vcc, s81, v58
	v_lshl_add_u64 v[60:61], v[56:57], 0, s[94:95]
	s_nop 0
	v_addc_co_u32_e32 v59, vcc, 0, v59, vcc
	v_lshl_add_u64 v[62:63], v[60:61], 0, v[116:117]
	v_add_co_u32_e32 v56, vcc, s80, v62
	v_lshl_add_u64 v[60:61], v[60:61], 0, s[8:9]
	s_nop 0
	v_addc_co_u32_e32 v57, vcc, 0, v63, vcc
	v_add_co_u32_e32 v62, vcc, 0x5000, v62
	v_lshl_add_u64 v[60:61], v[60:61], 0, v[114:115]
	s_nop 0
	v_addc_co_u32_e32 v63, vcc, 0, v63, vcc
	v_add_co_u32_e32 v64, vcc, 0x6000, v60
	global_load_dwordx4 v[44:47], v[46:47], off offset:32
	s_nop 0
	global_load_dwordx4 v[48:51], v[48:49], off offset:32
	s_nop 0
	global_load_dword v133, v[58:59], off offset:32
	s_nop 0
	global_load_dwordx4 v[56:59], v[56:57], off offset:32
	v_addc_co_u32_e32 v65, vcc, 0, v61, vcc
	global_load_dwordx4 v[60:63], v[62:63], off offset:32
	s_nop 0
	global_load_dword v135, v[64:65], off offset:32
.LBB0_1393:
	ds_read2st64_b32 v[64:65], v134 offset0:144 offset1:148
	v_add_u32_e32 v66, 32, v98
	v_ashrrev_i32_e32 v67, 31, v66
	v_lshlrev_b64 v[66:67], 12, v[66:67]
	v_lshl_add_u64 v[66:67], v[108:109], 0, v[66:67]
	s_waitcnt lgkmcnt(0)
	global_store_dword v[66:67], v64, off
	v_add_u32_e32 v66, 32, v96
	v_ashrrev_i32_e32 v67, 31, v66
	v_lshlrev_b64 v[66:67], 12, v[66:67]
	v_lshl_add_u64 v[66:67], v[108:109], 0, v[66:67]
	global_store_dword v[66:67], v65, off
	v_mov_b32_e32 v196, 0
	v_mov_b32_e32 v197, 0
	v_add_u32_e32 v194, 0x8800, v103
	v_add_u32_e32 v195, 0x8c00, v103
	ds_read2_b32 v[118:119], v194 offset0:0 offset1:16
	ds_read_b128 v[72:75], v145 offset:26624
	ds_read_b128 v[76:79], v145 offset:26880
	ds_read_b128 v[64:67], v145 offset:18432
	ds_read_b128 v[68:71], v145 offset:18688
	ds_read2_b32 v[120:121], v194 offset0:32 offset1:48
	ds_read_b128 v[88:91], v145 offset:27136
	ds_read_b128 v[92:95], v145 offset:27392
	ds_read_b128 v[80:83], v145 offset:18944
	ds_read_b128 v[84:87], v145 offset:19200
	s_waitcnt lgkmcnt(9)
	v_pk_add_f32 v[178:179], v[178:179], v[118:119] op_sel_hi:[1,0] neg_lo:[0,1] neg_hi:[0,1]
	v_pk_add_f32 v[186:187], v[186:187], v[118:119] op_sel:[0,1] op_sel_hi:[1,1] neg_lo:[0,1] neg_hi:[0,1]
	v_pk_add_f32 v[180:181], v[180:181], v[118:119] op_sel_hi:[1,0] neg_lo:[0,1] neg_hi:[0,1]
	v_pk_add_f32 v[188:189], v[188:189], v[118:119] op_sel:[0,1] op_sel_hi:[1,1] neg_lo:[0,1] neg_hi:[0,1]
	v_pk_add_f32 v[182:183], v[182:183], v[118:119] op_sel_hi:[1,0] neg_lo:[0,1] neg_hi:[0,1]
	v_pk_add_f32 v[190:191], v[190:191], v[118:119] op_sel:[0,1] op_sel_hi:[1,1] neg_lo:[0,1] neg_hi:[0,1]
	v_pk_add_f32 v[184:185], v[184:185], v[118:119] op_sel_hi:[1,0] neg_lo:[0,1] neg_hi:[0,1]
	v_pk_add_f32 v[192:193], v[192:193], v[118:119] op_sel:[0,1] op_sel_hi:[1,1] neg_lo:[0,1] neg_hi:[0,1]
	s_waitcnt lgkmcnt(8)
	v_pk_fma_f32 v[178:179], v[72:73], v[178:179], v[118:119] op_sel_hi:[1,1,0]
	v_pk_fma_f32 v[186:187], v[72:73], v[186:187], v[118:119] op_sel:[0,0,1] op_sel_hi:[1,1,1]
	v_pk_fma_f32 v[180:181], v[74:75], v[180:181], v[118:119] op_sel_hi:[1,1,0]
	v_pk_fma_f32 v[188:189], v[74:75], v[188:189], v[118:119] op_sel:[0,0,1] op_sel_hi:[1,1,1]
	s_waitcnt lgkmcnt(7)
	v_pk_fma_f32 v[182:183], v[76:77], v[182:183], v[118:119] op_sel_hi:[1,1,0]
	v_pk_fma_f32 v[190:191], v[76:77], v[190:191], v[118:119] op_sel:[0,0,1] op_sel_hi:[1,1,1]
	v_pk_fma_f32 v[184:185], v[78:79], v[184:185], v[118:119] op_sel_hi:[1,1,0]
	v_pk_fma_f32 v[192:193], v[78:79], v[192:193], v[118:119] op_sel:[0,0,1] op_sel_hi:[1,1,1]
	s_waitcnt lgkmcnt(6)
	v_pk_fma_f32 v[146:147], v[64:65], v[178:179], v[196:197]
	v_pk_fma_f32 v[150:151], v[64:65], v[186:187], v[196:197]
	v_pk_fma_f32 v[148:149], v[66:67], v[180:181], v[196:197]
	v_pk_fma_f32 v[152:153], v[66:67], v[188:189], v[196:197]
	s_waitcnt lgkmcnt(5)
	v_pk_fma_f32 v[146:147], v[68:69], v[182:183], v[146:147]
	v_pk_fma_f32 v[150:151], v[68:69], v[190:191], v[150:151]
	v_pk_fma_f32 v[148:149], v[70:71], v[184:185], v[148:149]
	v_pk_fma_f32 v[152:153], v[70:71], v[192:193], v[152:153]
	v_add_f32_e32 v146, v146, v147
	v_add_f32_e32 v148, v148, v149
	v_add_f32_e32 v150, v150, v151
	v_add_f32_e32 v152, v152, v153
	v_add_f32_e32 v154, v146, v148
	v_add_f32_e32 v155, v150, v152
	ds_read2_b32 v[118:119], v194 offset0:64 offset1:80
	ds_read_b128 v[72:75], v145 offset:27648
	ds_read_b128 v[76:79], v145 offset:27904
	ds_read_b128 v[64:67], v145 offset:19456
	ds_read_b128 v[68:71], v145 offset:19712
	s_waitcnt lgkmcnt(9)
	v_pk_add_f32 v[178:179], v[178:179], v[120:121] op_sel_hi:[1,0] neg_lo:[0,1] neg_hi:[0,1]
	v_add_f32_dpp v154, v154, v154 row_ror:8 row_mask:0xf bank_mask:0xf bound_ctrl:1
	v_pk_add_f32 v[186:187], v[186:187], v[120:121] op_sel:[0,1] op_sel_hi:[1,1] neg_lo:[0,1] neg_hi:[0,1]
	v_add_f32_dpp v155, v155, v155 row_ror:8 row_mask:0xf bank_mask:0xf bound_ctrl:1
	v_pk_add_f32 v[180:181], v[180:181], v[120:121] op_sel_hi:[1,0] neg_lo:[0,1] neg_hi:[0,1]
	v_add_f32_dpp v154, v154, v154 row_ror:4 row_mask:0xf bank_mask:0xf bound_ctrl:1
	v_pk_add_f32 v[188:189], v[188:189], v[120:121] op_sel:[0,1] op_sel_hi:[1,1] neg_lo:[0,1] neg_hi:[0,1]
	v_add_f32_dpp v155, v155, v155 row_ror:4 row_mask:0xf bank_mask:0xf bound_ctrl:1
	v_pk_add_f32 v[182:183], v[182:183], v[120:121] op_sel_hi:[1,0] neg_lo:[0,1] neg_hi:[0,1]
	v_add_f32_dpp v154, v154, v154 row_ror:2 row_mask:0xf bank_mask:0xf bound_ctrl:1
	v_pk_add_f32 v[190:191], v[190:191], v[120:121] op_sel:[0,1] op_sel_hi:[1,1] neg_lo:[0,1] neg_hi:[0,1]
	v_add_f32_dpp v155, v155, v155 row_ror:2 row_mask:0xf bank_mask:0xf bound_ctrl:1
	v_pk_add_f32 v[184:185], v[184:185], v[120:121] op_sel_hi:[1,0] neg_lo:[0,1] neg_hi:[0,1]
	v_add_f32_dpp v154, v154, v154 row_ror:1 row_mask:0xf bank_mask:0xf bound_ctrl:1
	v_pk_add_f32 v[192:193], v[192:193], v[120:121] op_sel:[0,1] op_sel_hi:[1,1] neg_lo:[0,1] neg_hi:[0,1]
	v_add_f32_dpp v155, v155, v155 row_ror:1 row_mask:0xf bank_mask:0xf bound_ctrl:1
	s_waitcnt lgkmcnt(8)
	v_pk_fma_f32 v[178:179], v[88:89], v[178:179], v[120:121] op_sel_hi:[1,1,0]
	ds_write_b32 v103, v154 offset:38912
	v_pk_fma_f32 v[186:187], v[88:89], v[186:187], v[120:121] op_sel:[0,0,1] op_sel_hi:[1,1,1]
	ds_write_b32 v103, v155 offset:38976
	v_pk_fma_f32 v[180:181], v[90:91], v[180:181], v[120:121] op_sel_hi:[1,1,0]
	v_pk_fma_f32 v[188:189], v[90:91], v[188:189], v[120:121] op_sel:[0,0,1] op_sel_hi:[1,1,1]
	s_waitcnt lgkmcnt(9)
	v_pk_fma_f32 v[182:183], v[92:93], v[182:183], v[120:121] op_sel_hi:[1,1,0]
	v_pk_fma_f32 v[190:191], v[92:93], v[190:191], v[120:121] op_sel:[0,0,1] op_sel_hi:[1,1,1]
	v_pk_fma_f32 v[184:185], v[94:95], v[184:185], v[120:121] op_sel_hi:[1,1,0]
	v_pk_fma_f32 v[192:193], v[94:95], v[192:193], v[120:121] op_sel:[0,0,1] op_sel_hi:[1,1,1]
	s_waitcnt lgkmcnt(8)
	v_pk_fma_f32 v[146:147], v[80:81], v[178:179], v[196:197]
	v_pk_fma_f32 v[150:151], v[80:81], v[186:187], v[196:197]
	v_pk_fma_f32 v[148:149], v[82:83], v[180:181], v[196:197]
	v_pk_fma_f32 v[152:153], v[82:83], v[188:189], v[196:197]
	s_waitcnt lgkmcnt(7)
	v_pk_fma_f32 v[146:147], v[84:85], v[182:183], v[146:147]
	v_pk_fma_f32 v[150:151], v[84:85], v[190:191], v[150:151]
	v_pk_fma_f32 v[148:149], v[86:87], v[184:185], v[148:149]
	v_pk_fma_f32 v[152:153], v[86:87], v[192:193], v[152:153]
	v_add_f32_e32 v146, v146, v147
	v_add_f32_e32 v148, v148, v149
	v_add_f32_e32 v150, v150, v151
	v_add_f32_e32 v152, v152, v153
	v_add_f32_e32 v156, v146, v148
	v_add_f32_e32 v157, v150, v152
	ds_read2_b32 v[120:121], v194 offset0:96 offset1:112
	ds_read_b128 v[88:91], v145 offset:28160
	ds_read_b128 v[92:95], v145 offset:28416
	ds_read_b128 v[80:83], v145 offset:19968
	ds_read_b128 v[84:87], v145 offset:20224
	s_waitcnt lgkmcnt(11)
	v_pk_add_f32 v[178:179], v[178:179], v[118:119] op_sel_hi:[1,0] neg_lo:[0,1] neg_hi:[0,1]
	v_add_f32_dpp v156, v156, v156 row_ror:8 row_mask:0xf bank_mask:0xf bound_ctrl:1
	v_pk_add_f32 v[186:187], v[186:187], v[118:119] op_sel:[0,1] op_sel_hi:[1,1] neg_lo:[0,1] neg_hi:[0,1]
	v_add_f32_dpp v157, v157, v157 row_ror:8 row_mask:0xf bank_mask:0xf bound_ctrl:1
	v_pk_add_f32 v[180:181], v[180:181], v[118:119] op_sel_hi:[1,0] neg_lo:[0,1] neg_hi:[0,1]
	v_add_f32_dpp v156, v156, v156 row_ror:4 row_mask:0xf bank_mask:0xf bound_ctrl:1
	v_pk_add_f32 v[188:189], v[188:189], v[118:119] op_sel:[0,1] op_sel_hi:[1,1] neg_lo:[0,1] neg_hi:[0,1]
	v_add_f32_dpp v157, v157, v157 row_ror:4 row_mask:0xf bank_mask:0xf bound_ctrl:1
	v_pk_add_f32 v[182:183], v[182:183], v[118:119] op_sel_hi:[1,0] neg_lo:[0,1] neg_hi:[0,1]
	v_add_f32_dpp v156, v156, v156 row_ror:2 row_mask:0xf bank_mask:0xf bound_ctrl:1
	v_pk_add_f32 v[190:191], v[190:191], v[118:119] op_sel:[0,1] op_sel_hi:[1,1] neg_lo:[0,1] neg_hi:[0,1]
	v_add_f32_dpp v157, v157, v157 row_ror:2 row_mask:0xf bank_mask:0xf bound_ctrl:1
	v_pk_add_f32 v[184:185], v[184:185], v[118:119] op_sel_hi:[1,0] neg_lo:[0,1] neg_hi:[0,1]
	v_add_f32_dpp v156, v156, v156 row_ror:1 row_mask:0xf bank_mask:0xf bound_ctrl:1
	v_pk_add_f32 v[192:193], v[192:193], v[118:119] op_sel:[0,1] op_sel_hi:[1,1] neg_lo:[0,1] neg_hi:[0,1]
	v_add_f32_dpp v157, v157, v157 row_ror:1 row_mask:0xf bank_mask:0xf bound_ctrl:1
	s_waitcnt lgkmcnt(10)
	v_pk_fma_f32 v[178:179], v[72:73], v[178:179], v[118:119] op_sel_hi:[1,1,0]
	ds_write_b32 v103, v156 offset:39040
	v_pk_fma_f32 v[186:187], v[72:73], v[186:187], v[118:119] op_sel:[0,0,1] op_sel_hi:[1,1,1]
	ds_write_b32 v103, v157 offset:39104
	v_pk_fma_f32 v[180:181], v[74:75], v[180:181], v[118:119] op_sel_hi:[1,1,0]
	v_pk_fma_f32 v[188:189], v[74:75], v[188:189], v[118:119] op_sel:[0,0,1] op_sel_hi:[1,1,1]
	s_waitcnt lgkmcnt(11)
	v_pk_fma_f32 v[182:183], v[76:77], v[182:183], v[118:119] op_sel_hi:[1,1,0]
	v_pk_fma_f32 v[190:191], v[76:77], v[190:191], v[118:119] op_sel:[0,0,1] op_sel_hi:[1,1,1]
	v_pk_fma_f32 v[184:185], v[78:79], v[184:185], v[118:119] op_sel_hi:[1,1,0]
	v_pk_fma_f32 v[192:193], v[78:79], v[192:193], v[118:119] op_sel:[0,0,1] op_sel_hi:[1,1,1]
	s_waitcnt lgkmcnt(10)
	v_pk_fma_f32 v[146:147], v[64:65], v[178:179], v[196:197]
	v_pk_fma_f32 v[150:151], v[64:65], v[186:187], v[196:197]
	v_pk_fma_f32 v[148:149], v[66:67], v[180:181], v[196:197]
	v_pk_fma_f32 v[152:153], v[66:67], v[188:189], v[196:197]
	s_waitcnt lgkmcnt(9)
	v_pk_fma_f32 v[146:147], v[68:69], v[182:183], v[146:147]
	v_pk_fma_f32 v[150:151], v[68:69], v[190:191], v[150:151]
	v_pk_fma_f32 v[148:149], v[70:71], v[184:185], v[148:149]
	v_pk_fma_f32 v[152:153], v[70:71], v[192:193], v[152:153]
	v_add_f32_e32 v146, v146, v147
	v_add_f32_e32 v148, v148, v149
	v_add_f32_e32 v150, v150, v151
	v_add_f32_e32 v152, v152, v153
	v_add_f32_e32 v154, v146, v148
	v_add_f32_e32 v155, v150, v152
	ds_read2_b32 v[118:119], v194 offset0:128 offset1:144
	ds_read_b128 v[72:75], v145 offset:28672
	ds_read_b128 v[76:79], v145 offset:28928
	ds_read_b128 v[64:67], v145 offset:20480
	ds_read_b128 v[68:71], v145 offset:20736
	s_waitcnt lgkmcnt(11)
	v_pk_add_f32 v[178:179], v[178:179], v[120:121] op_sel_hi:[1,0] neg_lo:[0,1] neg_hi:[0,1]
	v_add_f32_dpp v154, v154, v154 row_ror:8 row_mask:0xf bank_mask:0xf bound_ctrl:1
	v_pk_add_f32 v[186:187], v[186:187], v[120:121] op_sel:[0,1] op_sel_hi:[1,1] neg_lo:[0,1] neg_hi:[0,1]
	v_add_f32_dpp v155, v155, v155 row_ror:8 row_mask:0xf bank_mask:0xf bound_ctrl:1
	v_pk_add_f32 v[180:181], v[180:181], v[120:121] op_sel_hi:[1,0] neg_lo:[0,1] neg_hi:[0,1]
	v_add_f32_dpp v154, v154, v154 row_ror:4 row_mask:0xf bank_mask:0xf bound_ctrl:1
	v_pk_add_f32 v[188:189], v[188:189], v[120:121] op_sel:[0,1] op_sel_hi:[1,1] neg_lo:[0,1] neg_hi:[0,1]
	v_add_f32_dpp v155, v155, v155 row_ror:4 row_mask:0xf bank_mask:0xf bound_ctrl:1
	v_pk_add_f32 v[182:183], v[182:183], v[120:121] op_sel_hi:[1,0] neg_lo:[0,1] neg_hi:[0,1]
	v_add_f32_dpp v154, v154, v154 row_ror:2 row_mask:0xf bank_mask:0xf bound_ctrl:1
	v_pk_add_f32 v[190:191], v[190:191], v[120:121] op_sel:[0,1] op_sel_hi:[1,1] neg_lo:[0,1] neg_hi:[0,1]
	v_add_f32_dpp v155, v155, v155 row_ror:2 row_mask:0xf bank_mask:0xf bound_ctrl:1
	v_pk_add_f32 v[184:185], v[184:185], v[120:121] op_sel_hi:[1,0] neg_lo:[0,1] neg_hi:[0,1]
	v_add_f32_dpp v154, v154, v154 row_ror:1 row_mask:0xf bank_mask:0xf bound_ctrl:1
	v_pk_add_f32 v[192:193], v[192:193], v[120:121] op_sel:[0,1] op_sel_hi:[1,1] neg_lo:[0,1] neg_hi:[0,1]
	v_add_f32_dpp v155, v155, v155 row_ror:1 row_mask:0xf bank_mask:0xf bound_ctrl:1
	s_waitcnt lgkmcnt(10)
	v_pk_fma_f32 v[178:179], v[88:89], v[178:179], v[120:121] op_sel_hi:[1,1,0]
	ds_write_b32 v103, v154 offset:39168
	v_pk_fma_f32 v[186:187], v[88:89], v[186:187], v[120:121] op_sel:[0,0,1] op_sel_hi:[1,1,1]
	ds_write_b32 v103, v155 offset:39232
	v_pk_fma_f32 v[180:181], v[90:91], v[180:181], v[120:121] op_sel_hi:[1,1,0]
	v_pk_fma_f32 v[188:189], v[90:91], v[188:189], v[120:121] op_sel:[0,0,1] op_sel_hi:[1,1,1]
	s_waitcnt lgkmcnt(11)
	v_pk_fma_f32 v[182:183], v[92:93], v[182:183], v[120:121] op_sel_hi:[1,1,0]
	v_pk_fma_f32 v[190:191], v[92:93], v[190:191], v[120:121] op_sel:[0,0,1] op_sel_hi:[1,1,1]
	v_pk_fma_f32 v[184:185], v[94:95], v[184:185], v[120:121] op_sel_hi:[1,1,0]
	v_pk_fma_f32 v[192:193], v[94:95], v[192:193], v[120:121] op_sel:[0,0,1] op_sel_hi:[1,1,1]
	s_waitcnt lgkmcnt(10)
	v_pk_fma_f32 v[146:147], v[80:81], v[178:179], v[196:197]
	v_pk_fma_f32 v[150:151], v[80:81], v[186:187], v[196:197]
	v_pk_fma_f32 v[148:149], v[82:83], v[180:181], v[196:197]
	v_pk_fma_f32 v[152:153], v[82:83], v[188:189], v[196:197]
	s_waitcnt lgkmcnt(9)
	v_pk_fma_f32 v[146:147], v[84:85], v[182:183], v[146:147]
	v_pk_fma_f32 v[150:151], v[84:85], v[190:191], v[150:151]
	v_pk_fma_f32 v[148:149], v[86:87], v[184:185], v[148:149]
	v_pk_fma_f32 v[152:153], v[86:87], v[192:193], v[152:153]
	v_add_f32_e32 v146, v146, v147
	v_add_f32_e32 v148, v148, v149
	v_add_f32_e32 v150, v150, v151
	v_add_f32_e32 v152, v152, v153
	v_add_f32_e32 v156, v146, v148
	v_add_f32_e32 v157, v150, v152
	ds_read2_b32 v[120:121], v194 offset0:160 offset1:176
	ds_read_b128 v[88:91], v145 offset:29184
	ds_read_b128 v[92:95], v145 offset:29440
	ds_read_b128 v[80:83], v145 offset:20992
	ds_read_b128 v[84:87], v145 offset:21248
	s_waitcnt lgkmcnt(11)
	v_pk_add_f32 v[178:179], v[178:179], v[118:119] op_sel_hi:[1,0] neg_lo:[0,1] neg_hi:[0,1]
	v_add_f32_dpp v156, v156, v156 row_ror:8 row_mask:0xf bank_mask:0xf bound_ctrl:1
	v_pk_add_f32 v[186:187], v[186:187], v[118:119] op_sel:[0,1] op_sel_hi:[1,1] neg_lo:[0,1] neg_hi:[0,1]
	v_add_f32_dpp v157, v157, v157 row_ror:8 row_mask:0xf bank_mask:0xf bound_ctrl:1
	v_pk_add_f32 v[180:181], v[180:181], v[118:119] op_sel_hi:[1,0] neg_lo:[0,1] neg_hi:[0,1]
	v_add_f32_dpp v156, v156, v156 row_ror:4 row_mask:0xf bank_mask:0xf bound_ctrl:1
	v_pk_add_f32 v[188:189], v[188:189], v[118:119] op_sel:[0,1] op_sel_hi:[1,1] neg_lo:[0,1] neg_hi:[0,1]
	v_add_f32_dpp v157, v157, v157 row_ror:4 row_mask:0xf bank_mask:0xf bound_ctrl:1
	v_pk_add_f32 v[182:183], v[182:183], v[118:119] op_sel_hi:[1,0] neg_lo:[0,1] neg_hi:[0,1]
	v_add_f32_dpp v156, v156, v156 row_ror:2 row_mask:0xf bank_mask:0xf bound_ctrl:1
	v_pk_add_f32 v[190:191], v[190:191], v[118:119] op_sel:[0,1] op_sel_hi:[1,1] neg_lo:[0,1] neg_hi:[0,1]
	v_add_f32_dpp v157, v157, v157 row_ror:2 row_mask:0xf bank_mask:0xf bound_ctrl:1
	v_pk_add_f32 v[184:185], v[184:185], v[118:119] op_sel_hi:[1,0] neg_lo:[0,1] neg_hi:[0,1]
	v_add_f32_dpp v156, v156, v156 row_ror:1 row_mask:0xf bank_mask:0xf bound_ctrl:1
	v_pk_add_f32 v[192:193], v[192:193], v[118:119] op_sel:[0,1] op_sel_hi:[1,1] neg_lo:[0,1] neg_hi:[0,1]
	v_add_f32_dpp v157, v157, v157 row_ror:1 row_mask:0xf bank_mask:0xf bound_ctrl:1
	s_waitcnt lgkmcnt(10)
	v_pk_fma_f32 v[178:179], v[72:73], v[178:179], v[118:119] op_sel_hi:[1,1,0]
	ds_write_b32 v103, v156 offset:39296
	v_pk_fma_f32 v[186:187], v[72:73], v[186:187], v[118:119] op_sel:[0,0,1] op_sel_hi:[1,1,1]
	ds_write_b32 v103, v157 offset:39360
	v_pk_fma_f32 v[180:181], v[74:75], v[180:181], v[118:119] op_sel_hi:[1,1,0]
	v_pk_fma_f32 v[188:189], v[74:75], v[188:189], v[118:119] op_sel:[0,0,1] op_sel_hi:[1,1,1]
	s_waitcnt lgkmcnt(11)
	v_pk_fma_f32 v[182:183], v[76:77], v[182:183], v[118:119] op_sel_hi:[1,1,0]
	v_pk_fma_f32 v[190:191], v[76:77], v[190:191], v[118:119] op_sel:[0,0,1] op_sel_hi:[1,1,1]
	v_pk_fma_f32 v[184:185], v[78:79], v[184:185], v[118:119] op_sel_hi:[1,1,0]
	v_pk_fma_f32 v[192:193], v[78:79], v[192:193], v[118:119] op_sel:[0,0,1] op_sel_hi:[1,1,1]
	s_waitcnt lgkmcnt(10)
	v_pk_fma_f32 v[146:147], v[64:65], v[178:179], v[196:197]
	v_pk_fma_f32 v[150:151], v[64:65], v[186:187], v[196:197]
	v_pk_fma_f32 v[148:149], v[66:67], v[180:181], v[196:197]
	v_pk_fma_f32 v[152:153], v[66:67], v[188:189], v[196:197]
	s_waitcnt lgkmcnt(9)
	v_pk_fma_f32 v[146:147], v[68:69], v[182:183], v[146:147]
	v_pk_fma_f32 v[150:151], v[68:69], v[190:191], v[150:151]
	v_pk_fma_f32 v[148:149], v[70:71], v[184:185], v[148:149]
	v_pk_fma_f32 v[152:153], v[70:71], v[192:193], v[152:153]
	v_add_f32_e32 v146, v146, v147
	v_add_f32_e32 v148, v148, v149
	v_add_f32_e32 v150, v150, v151
	v_add_f32_e32 v152, v152, v153
	v_add_f32_e32 v154, v146, v148
	v_add_f32_e32 v155, v150, v152
	ds_read2_b32 v[118:119], v194 offset0:192 offset1:208
	ds_read_b128 v[72:75], v145 offset:29696
	ds_read_b128 v[76:79], v145 offset:29952
	ds_read_b128 v[64:67], v145 offset:21504
	ds_read_b128 v[68:71], v145 offset:21760
	s_waitcnt lgkmcnt(11)
	v_pk_add_f32 v[178:179], v[178:179], v[120:121] op_sel_hi:[1,0] neg_lo:[0,1] neg_hi:[0,1]
	v_add_f32_dpp v154, v154, v154 row_ror:8 row_mask:0xf bank_mask:0xf bound_ctrl:1
	v_pk_add_f32 v[186:187], v[186:187], v[120:121] op_sel:[0,1] op_sel_hi:[1,1] neg_lo:[0,1] neg_hi:[0,1]
	v_add_f32_dpp v155, v155, v155 row_ror:8 row_mask:0xf bank_mask:0xf bound_ctrl:1
	v_pk_add_f32 v[180:181], v[180:181], v[120:121] op_sel_hi:[1,0] neg_lo:[0,1] neg_hi:[0,1]
	v_add_f32_dpp v154, v154, v154 row_ror:4 row_mask:0xf bank_mask:0xf bound_ctrl:1
	v_pk_add_f32 v[188:189], v[188:189], v[120:121] op_sel:[0,1] op_sel_hi:[1,1] neg_lo:[0,1] neg_hi:[0,1]
	v_add_f32_dpp v155, v155, v155 row_ror:4 row_mask:0xf bank_mask:0xf bound_ctrl:1
	v_pk_add_f32 v[182:183], v[182:183], v[120:121] op_sel_hi:[1,0] neg_lo:[0,1] neg_hi:[0,1]
	v_add_f32_dpp v154, v154, v154 row_ror:2 row_mask:0xf bank_mask:0xf bound_ctrl:1
	v_pk_add_f32 v[190:191], v[190:191], v[120:121] op_sel:[0,1] op_sel_hi:[1,1] neg_lo:[0,1] neg_hi:[0,1]
	v_add_f32_dpp v155, v155, v155 row_ror:2 row_mask:0xf bank_mask:0xf bound_ctrl:1
	v_pk_add_f32 v[184:185], v[184:185], v[120:121] op_sel_hi:[1,0] neg_lo:[0,1] neg_hi:[0,1]
	v_add_f32_dpp v154, v154, v154 row_ror:1 row_mask:0xf bank_mask:0xf bound_ctrl:1
	v_pk_add_f32 v[192:193], v[192:193], v[120:121] op_sel:[0,1] op_sel_hi:[1,1] neg_lo:[0,1] neg_hi:[0,1]
	v_add_f32_dpp v155, v155, v155 row_ror:1 row_mask:0xf bank_mask:0xf bound_ctrl:1
	s_waitcnt lgkmcnt(10)
	v_pk_fma_f32 v[178:179], v[88:89], v[178:179], v[120:121] op_sel_hi:[1,1,0]
	ds_write_b32 v103, v154 offset:39424
	v_pk_fma_f32 v[186:187], v[88:89], v[186:187], v[120:121] op_sel:[0,0,1] op_sel_hi:[1,1,1]
	ds_write_b32 v103, v155 offset:39488
	v_pk_fma_f32 v[180:181], v[90:91], v[180:181], v[120:121] op_sel_hi:[1,1,0]
	v_pk_fma_f32 v[188:189], v[90:91], v[188:189], v[120:121] op_sel:[0,0,1] op_sel_hi:[1,1,1]
	s_waitcnt lgkmcnt(11)
	v_pk_fma_f32 v[182:183], v[92:93], v[182:183], v[120:121] op_sel_hi:[1,1,0]
	v_pk_fma_f32 v[190:191], v[92:93], v[190:191], v[120:121] op_sel:[0,0,1] op_sel_hi:[1,1,1]
	v_pk_fma_f32 v[184:185], v[94:95], v[184:185], v[120:121] op_sel_hi:[1,1,0]
	v_pk_fma_f32 v[192:193], v[94:95], v[192:193], v[120:121] op_sel:[0,0,1] op_sel_hi:[1,1,1]
	s_waitcnt lgkmcnt(10)
	v_pk_fma_f32 v[146:147], v[80:81], v[178:179], v[196:197]
	v_pk_fma_f32 v[150:151], v[80:81], v[186:187], v[196:197]
	v_pk_fma_f32 v[148:149], v[82:83], v[180:181], v[196:197]
	v_pk_fma_f32 v[152:153], v[82:83], v[188:189], v[196:197]
	s_waitcnt lgkmcnt(9)
	v_pk_fma_f32 v[146:147], v[84:85], v[182:183], v[146:147]
	v_pk_fma_f32 v[150:151], v[84:85], v[190:191], v[150:151]
	v_pk_fma_f32 v[148:149], v[86:87], v[184:185], v[148:149]
	v_pk_fma_f32 v[152:153], v[86:87], v[192:193], v[152:153]
	v_add_f32_e32 v146, v146, v147
	v_add_f32_e32 v148, v148, v149
	v_add_f32_e32 v150, v150, v151
	v_add_f32_e32 v152, v152, v153
	v_add_f32_e32 v156, v146, v148
	v_add_f32_e32 v157, v150, v152
	ds_read2_b32 v[120:121], v194 offset0:224 offset1:240
	ds_read_b128 v[88:91], v145 offset:30208
	ds_read_b128 v[92:95], v145 offset:30464
	ds_read_b128 v[80:83], v145 offset:22016
	ds_read_b128 v[84:87], v145 offset:22272
	s_waitcnt lgkmcnt(11)
	v_pk_add_f32 v[178:179], v[178:179], v[118:119] op_sel_hi:[1,0] neg_lo:[0,1] neg_hi:[0,1]
	v_add_f32_dpp v156, v156, v156 row_ror:8 row_mask:0xf bank_mask:0xf bound_ctrl:1
	v_pk_add_f32 v[186:187], v[186:187], v[118:119] op_sel:[0,1] op_sel_hi:[1,1] neg_lo:[0,1] neg_hi:[0,1]
	v_add_f32_dpp v157, v157, v157 row_ror:8 row_mask:0xf bank_mask:0xf bound_ctrl:1
	v_pk_add_f32 v[180:181], v[180:181], v[118:119] op_sel_hi:[1,0] neg_lo:[0,1] neg_hi:[0,1]
	v_add_f32_dpp v156, v156, v156 row_ror:4 row_mask:0xf bank_mask:0xf bound_ctrl:1
	v_pk_add_f32 v[188:189], v[188:189], v[118:119] op_sel:[0,1] op_sel_hi:[1,1] neg_lo:[0,1] neg_hi:[0,1]
	v_add_f32_dpp v157, v157, v157 row_ror:4 row_mask:0xf bank_mask:0xf bound_ctrl:1
	v_pk_add_f32 v[182:183], v[182:183], v[118:119] op_sel_hi:[1,0] neg_lo:[0,1] neg_hi:[0,1]
	v_add_f32_dpp v156, v156, v156 row_ror:2 row_mask:0xf bank_mask:0xf bound_ctrl:1
	v_pk_add_f32 v[190:191], v[190:191], v[118:119] op_sel:[0,1] op_sel_hi:[1,1] neg_lo:[0,1] neg_hi:[0,1]
	v_add_f32_dpp v157, v157, v157 row_ror:2 row_mask:0xf bank_mask:0xf bound_ctrl:1
	v_pk_add_f32 v[184:185], v[184:185], v[118:119] op_sel_hi:[1,0] neg_lo:[0,1] neg_hi:[0,1]
	v_add_f32_dpp v156, v156, v156 row_ror:1 row_mask:0xf bank_mask:0xf bound_ctrl:1
	v_pk_add_f32 v[192:193], v[192:193], v[118:119] op_sel:[0,1] op_sel_hi:[1,1] neg_lo:[0,1] neg_hi:[0,1]
	v_add_f32_dpp v157, v157, v157 row_ror:1 row_mask:0xf bank_mask:0xf bound_ctrl:1
	s_waitcnt lgkmcnt(10)
	v_pk_fma_f32 v[178:179], v[72:73], v[178:179], v[118:119] op_sel_hi:[1,1,0]
	ds_write_b32 v103, v156 offset:39552
	v_pk_fma_f32 v[186:187], v[72:73], v[186:187], v[118:119] op_sel:[0,0,1] op_sel_hi:[1,1,1]
	ds_write_b32 v103, v157 offset:39616
	v_pk_fma_f32 v[180:181], v[74:75], v[180:181], v[118:119] op_sel_hi:[1,1,0]
	v_pk_fma_f32 v[188:189], v[74:75], v[188:189], v[118:119] op_sel:[0,0,1] op_sel_hi:[1,1,1]
	s_waitcnt lgkmcnt(11)
	v_pk_fma_f32 v[182:183], v[76:77], v[182:183], v[118:119] op_sel_hi:[1,1,0]
	v_pk_fma_f32 v[190:191], v[76:77], v[190:191], v[118:119] op_sel:[0,0,1] op_sel_hi:[1,1,1]
	v_pk_fma_f32 v[184:185], v[78:79], v[184:185], v[118:119] op_sel_hi:[1,1,0]
	v_pk_fma_f32 v[192:193], v[78:79], v[192:193], v[118:119] op_sel:[0,0,1] op_sel_hi:[1,1,1]
	s_waitcnt lgkmcnt(10)
	v_pk_fma_f32 v[146:147], v[64:65], v[178:179], v[196:197]
	v_pk_fma_f32 v[150:151], v[64:65], v[186:187], v[196:197]
	v_pk_fma_f32 v[148:149], v[66:67], v[180:181], v[196:197]
	v_pk_fma_f32 v[152:153], v[66:67], v[188:189], v[196:197]
	s_waitcnt lgkmcnt(9)
	v_pk_fma_f32 v[146:147], v[68:69], v[182:183], v[146:147]
	v_pk_fma_f32 v[150:151], v[68:69], v[190:191], v[150:151]
	v_pk_fma_f32 v[148:149], v[70:71], v[184:185], v[148:149]
	v_pk_fma_f32 v[152:153], v[70:71], v[192:193], v[152:153]
	v_add_f32_e32 v146, v146, v147
	v_add_f32_e32 v148, v148, v149
	v_add_f32_e32 v150, v150, v151
	v_add_f32_e32 v152, v152, v153
	v_add_f32_e32 v154, v146, v148
	v_add_f32_e32 v155, v150, v152
	ds_read2_b32 v[118:119], v195 offset0:0 offset1:16
	ds_read_b128 v[72:75], v145 offset:30720
	ds_read_b128 v[76:79], v145 offset:30976
	ds_read_b128 v[64:67], v145 offset:22528
	ds_read_b128 v[68:71], v145 offset:22784
	s_waitcnt lgkmcnt(11)
	v_pk_add_f32 v[178:179], v[178:179], v[120:121] op_sel_hi:[1,0] neg_lo:[0,1] neg_hi:[0,1]
	v_add_f32_dpp v154, v154, v154 row_ror:8 row_mask:0xf bank_mask:0xf bound_ctrl:1
	v_pk_add_f32 v[186:187], v[186:187], v[120:121] op_sel:[0,1] op_sel_hi:[1,1] neg_lo:[0,1] neg_hi:[0,1]
	v_add_f32_dpp v155, v155, v155 row_ror:8 row_mask:0xf bank_mask:0xf bound_ctrl:1
	v_pk_add_f32 v[180:181], v[180:181], v[120:121] op_sel_hi:[1,0] neg_lo:[0,1] neg_hi:[0,1]
	v_add_f32_dpp v154, v154, v154 row_ror:4 row_mask:0xf bank_mask:0xf bound_ctrl:1
	v_pk_add_f32 v[188:189], v[188:189], v[120:121] op_sel:[0,1] op_sel_hi:[1,1] neg_lo:[0,1] neg_hi:[0,1]
	v_add_f32_dpp v155, v155, v155 row_ror:4 row_mask:0xf bank_mask:0xf bound_ctrl:1
	v_pk_add_f32 v[182:183], v[182:183], v[120:121] op_sel_hi:[1,0] neg_lo:[0,1] neg_hi:[0,1]
	v_add_f32_dpp v154, v154, v154 row_ror:2 row_mask:0xf bank_mask:0xf bound_ctrl:1
	v_pk_add_f32 v[190:191], v[190:191], v[120:121] op_sel:[0,1] op_sel_hi:[1,1] neg_lo:[0,1] neg_hi:[0,1]
	v_add_f32_dpp v155, v155, v155 row_ror:2 row_mask:0xf bank_mask:0xf bound_ctrl:1
	v_pk_add_f32 v[184:185], v[184:185], v[120:121] op_sel_hi:[1,0] neg_lo:[0,1] neg_hi:[0,1]
	v_add_f32_dpp v154, v154, v154 row_ror:1 row_mask:0xf bank_mask:0xf bound_ctrl:1
	v_pk_add_f32 v[192:193], v[192:193], v[120:121] op_sel:[0,1] op_sel_hi:[1,1] neg_lo:[0,1] neg_hi:[0,1]
	v_add_f32_dpp v155, v155, v155 row_ror:1 row_mask:0xf bank_mask:0xf bound_ctrl:1
	s_waitcnt lgkmcnt(10)
	v_pk_fma_f32 v[178:179], v[88:89], v[178:179], v[120:121] op_sel_hi:[1,1,0]
	ds_write_b32 v103, v154 offset:39680
	v_pk_fma_f32 v[186:187], v[88:89], v[186:187], v[120:121] op_sel:[0,0,1] op_sel_hi:[1,1,1]
	ds_write_b32 v103, v155 offset:39744
	v_pk_fma_f32 v[180:181], v[90:91], v[180:181], v[120:121] op_sel_hi:[1,1,0]
	v_pk_fma_f32 v[188:189], v[90:91], v[188:189], v[120:121] op_sel:[0,0,1] op_sel_hi:[1,1,1]
	s_waitcnt lgkmcnt(11)
	v_pk_fma_f32 v[182:183], v[92:93], v[182:183], v[120:121] op_sel_hi:[1,1,0]
	v_pk_fma_f32 v[190:191], v[92:93], v[190:191], v[120:121] op_sel:[0,0,1] op_sel_hi:[1,1,1]
	v_pk_fma_f32 v[184:185], v[94:95], v[184:185], v[120:121] op_sel_hi:[1,1,0]
	v_pk_fma_f32 v[192:193], v[94:95], v[192:193], v[120:121] op_sel:[0,0,1] op_sel_hi:[1,1,1]
	s_waitcnt lgkmcnt(10)
	v_pk_fma_f32 v[146:147], v[80:81], v[178:179], v[196:197]
	v_pk_fma_f32 v[150:151], v[80:81], v[186:187], v[196:197]
	v_pk_fma_f32 v[148:149], v[82:83], v[180:181], v[196:197]
	v_pk_fma_f32 v[152:153], v[82:83], v[188:189], v[196:197]
	s_waitcnt lgkmcnt(9)
	v_pk_fma_f32 v[146:147], v[84:85], v[182:183], v[146:147]
	v_pk_fma_f32 v[150:151], v[84:85], v[190:191], v[150:151]
	v_pk_fma_f32 v[148:149], v[86:87], v[184:185], v[148:149]
	v_pk_fma_f32 v[152:153], v[86:87], v[192:193], v[152:153]
	v_add_f32_e32 v146, v146, v147
	v_add_f32_e32 v148, v148, v149
	v_add_f32_e32 v150, v150, v151
	v_add_f32_e32 v152, v152, v153
	v_add_f32_e32 v156, v146, v148
	v_add_f32_e32 v157, v150, v152
	ds_read2_b32 v[120:121], v195 offset0:32 offset1:48
	ds_read_b128 v[88:91], v145 offset:31232
	ds_read_b128 v[92:95], v145 offset:31488
	ds_read_b128 v[80:83], v145 offset:23040
	ds_read_b128 v[84:87], v145 offset:23296
	s_waitcnt lgkmcnt(11)
	v_pk_add_f32 v[178:179], v[178:179], v[118:119] op_sel_hi:[1,0] neg_lo:[0,1] neg_hi:[0,1]
	v_add_f32_dpp v156, v156, v156 row_ror:8 row_mask:0xf bank_mask:0xf bound_ctrl:1
	v_pk_add_f32 v[186:187], v[186:187], v[118:119] op_sel:[0,1] op_sel_hi:[1,1] neg_lo:[0,1] neg_hi:[0,1]
	v_add_f32_dpp v157, v157, v157 row_ror:8 row_mask:0xf bank_mask:0xf bound_ctrl:1
	v_pk_add_f32 v[180:181], v[180:181], v[118:119] op_sel_hi:[1,0] neg_lo:[0,1] neg_hi:[0,1]
	v_add_f32_dpp v156, v156, v156 row_ror:4 row_mask:0xf bank_mask:0xf bound_ctrl:1
	v_pk_add_f32 v[188:189], v[188:189], v[118:119] op_sel:[0,1] op_sel_hi:[1,1] neg_lo:[0,1] neg_hi:[0,1]
	v_add_f32_dpp v157, v157, v157 row_ror:4 row_mask:0xf bank_mask:0xf bound_ctrl:1
	v_pk_add_f32 v[182:183], v[182:183], v[118:119] op_sel_hi:[1,0] neg_lo:[0,1] neg_hi:[0,1]
	v_add_f32_dpp v156, v156, v156 row_ror:2 row_mask:0xf bank_mask:0xf bound_ctrl:1
	v_pk_add_f32 v[190:191], v[190:191], v[118:119] op_sel:[0,1] op_sel_hi:[1,1] neg_lo:[0,1] neg_hi:[0,1]
	v_add_f32_dpp v157, v157, v157 row_ror:2 row_mask:0xf bank_mask:0xf bound_ctrl:1
	v_pk_add_f32 v[184:185], v[184:185], v[118:119] op_sel_hi:[1,0] neg_lo:[0,1] neg_hi:[0,1]
	v_add_f32_dpp v156, v156, v156 row_ror:1 row_mask:0xf bank_mask:0xf bound_ctrl:1
	v_pk_add_f32 v[192:193], v[192:193], v[118:119] op_sel:[0,1] op_sel_hi:[1,1] neg_lo:[0,1] neg_hi:[0,1]
	v_add_f32_dpp v157, v157, v157 row_ror:1 row_mask:0xf bank_mask:0xf bound_ctrl:1
	s_waitcnt lgkmcnt(10)
	v_pk_fma_f32 v[178:179], v[72:73], v[178:179], v[118:119] op_sel_hi:[1,1,0]
	ds_write_b32 v103, v156 offset:39808
	v_pk_fma_f32 v[186:187], v[72:73], v[186:187], v[118:119] op_sel:[0,0,1] op_sel_hi:[1,1,1]
	ds_write_b32 v103, v157 offset:39872
	v_pk_fma_f32 v[180:181], v[74:75], v[180:181], v[118:119] op_sel_hi:[1,1,0]
	v_pk_fma_f32 v[188:189], v[74:75], v[188:189], v[118:119] op_sel:[0,0,1] op_sel_hi:[1,1,1]
	s_waitcnt lgkmcnt(11)
	v_pk_fma_f32 v[182:183], v[76:77], v[182:183], v[118:119] op_sel_hi:[1,1,0]
	v_pk_fma_f32 v[190:191], v[76:77], v[190:191], v[118:119] op_sel:[0,0,1] op_sel_hi:[1,1,1]
	v_pk_fma_f32 v[184:185], v[78:79], v[184:185], v[118:119] op_sel_hi:[1,1,0]
	v_pk_fma_f32 v[192:193], v[78:79], v[192:193], v[118:119] op_sel:[0,0,1] op_sel_hi:[1,1,1]
	s_waitcnt lgkmcnt(10)
	v_pk_fma_f32 v[146:147], v[64:65], v[178:179], v[196:197]
	v_pk_fma_f32 v[150:151], v[64:65], v[186:187], v[196:197]
	v_pk_fma_f32 v[148:149], v[66:67], v[180:181], v[196:197]
	v_pk_fma_f32 v[152:153], v[66:67], v[188:189], v[196:197]
	s_waitcnt lgkmcnt(9)
	v_pk_fma_f32 v[146:147], v[68:69], v[182:183], v[146:147]
	v_pk_fma_f32 v[150:151], v[68:69], v[190:191], v[150:151]
	v_pk_fma_f32 v[148:149], v[70:71], v[184:185], v[148:149]
	v_pk_fma_f32 v[152:153], v[70:71], v[192:193], v[152:153]
	v_add_f32_e32 v146, v146, v147
	v_add_f32_e32 v148, v148, v149
	v_add_f32_e32 v150, v150, v151
	v_add_f32_e32 v152, v152, v153
	v_add_f32_e32 v154, v146, v148
	v_add_f32_e32 v155, v150, v152
	ds_read2_b32 v[118:119], v195 offset0:64 offset1:80
	ds_read_b128 v[72:75], v145 offset:31744
	ds_read_b128 v[76:79], v145 offset:32000
	ds_read_b128 v[64:67], v145 offset:23552
	ds_read_b128 v[68:71], v145 offset:23808
	s_waitcnt lgkmcnt(11)
	v_pk_add_f32 v[178:179], v[178:179], v[120:121] op_sel_hi:[1,0] neg_lo:[0,1] neg_hi:[0,1]
	v_add_f32_dpp v154, v154, v154 row_ror:8 row_mask:0xf bank_mask:0xf bound_ctrl:1
	v_pk_add_f32 v[186:187], v[186:187], v[120:121] op_sel:[0,1] op_sel_hi:[1,1] neg_lo:[0,1] neg_hi:[0,1]
	v_add_f32_dpp v155, v155, v155 row_ror:8 row_mask:0xf bank_mask:0xf bound_ctrl:1
	v_pk_add_f32 v[180:181], v[180:181], v[120:121] op_sel_hi:[1,0] neg_lo:[0,1] neg_hi:[0,1]
	v_add_f32_dpp v154, v154, v154 row_ror:4 row_mask:0xf bank_mask:0xf bound_ctrl:1
	v_pk_add_f32 v[188:189], v[188:189], v[120:121] op_sel:[0,1] op_sel_hi:[1,1] neg_lo:[0,1] neg_hi:[0,1]
	v_add_f32_dpp v155, v155, v155 row_ror:4 row_mask:0xf bank_mask:0xf bound_ctrl:1
	v_pk_add_f32 v[182:183], v[182:183], v[120:121] op_sel_hi:[1,0] neg_lo:[0,1] neg_hi:[0,1]
	v_add_f32_dpp v154, v154, v154 row_ror:2 row_mask:0xf bank_mask:0xf bound_ctrl:1
	v_pk_add_f32 v[190:191], v[190:191], v[120:121] op_sel:[0,1] op_sel_hi:[1,1] neg_lo:[0,1] neg_hi:[0,1]
	v_add_f32_dpp v155, v155, v155 row_ror:2 row_mask:0xf bank_mask:0xf bound_ctrl:1
	v_pk_add_f32 v[184:185], v[184:185], v[120:121] op_sel_hi:[1,0] neg_lo:[0,1] neg_hi:[0,1]
	v_add_f32_dpp v154, v154, v154 row_ror:1 row_mask:0xf bank_mask:0xf bound_ctrl:1
	v_pk_add_f32 v[192:193], v[192:193], v[120:121] op_sel:[0,1] op_sel_hi:[1,1] neg_lo:[0,1] neg_hi:[0,1]
	v_add_f32_dpp v155, v155, v155 row_ror:1 row_mask:0xf bank_mask:0xf bound_ctrl:1
	s_waitcnt lgkmcnt(10)
	v_pk_fma_f32 v[178:179], v[88:89], v[178:179], v[120:121] op_sel_hi:[1,1,0]
	ds_write_b32 v103, v154 offset:39936
	v_pk_fma_f32 v[186:187], v[88:89], v[186:187], v[120:121] op_sel:[0,0,1] op_sel_hi:[1,1,1]
	ds_write_b32 v103, v155 offset:40000
	v_pk_fma_f32 v[180:181], v[90:91], v[180:181], v[120:121] op_sel_hi:[1,1,0]
	v_pk_fma_f32 v[188:189], v[90:91], v[188:189], v[120:121] op_sel:[0,0,1] op_sel_hi:[1,1,1]
	s_waitcnt lgkmcnt(11)
	v_pk_fma_f32 v[182:183], v[92:93], v[182:183], v[120:121] op_sel_hi:[1,1,0]
	v_pk_fma_f32 v[190:191], v[92:93], v[190:191], v[120:121] op_sel:[0,0,1] op_sel_hi:[1,1,1]
	v_pk_fma_f32 v[184:185], v[94:95], v[184:185], v[120:121] op_sel_hi:[1,1,0]
	v_pk_fma_f32 v[192:193], v[94:95], v[192:193], v[120:121] op_sel:[0,0,1] op_sel_hi:[1,1,1]
	s_waitcnt lgkmcnt(10)
	v_pk_fma_f32 v[146:147], v[80:81], v[178:179], v[196:197]
	v_pk_fma_f32 v[150:151], v[80:81], v[186:187], v[196:197]
	v_pk_fma_f32 v[148:149], v[82:83], v[180:181], v[196:197]
	v_pk_fma_f32 v[152:153], v[82:83], v[188:189], v[196:197]
	s_waitcnt lgkmcnt(9)
	v_pk_fma_f32 v[146:147], v[84:85], v[182:183], v[146:147]
	v_pk_fma_f32 v[150:151], v[84:85], v[190:191], v[150:151]
	v_pk_fma_f32 v[148:149], v[86:87], v[184:185], v[148:149]
	v_pk_fma_f32 v[152:153], v[86:87], v[192:193], v[152:153]
	v_add_f32_e32 v146, v146, v147
	v_add_f32_e32 v148, v148, v149
	v_add_f32_e32 v150, v150, v151
	v_add_f32_e32 v152, v152, v153
	v_add_f32_e32 v156, v146, v148
	v_add_f32_e32 v157, v150, v152
	ds_read2_b32 v[120:121], v195 offset0:96 offset1:112
	ds_read_b128 v[88:91], v145 offset:32256
	ds_read_b128 v[92:95], v145 offset:32512
	ds_read_b128 v[80:83], v145 offset:24064
	ds_read_b128 v[84:87], v145 offset:24320
	s_waitcnt lgkmcnt(11)
	v_pk_add_f32 v[178:179], v[178:179], v[118:119] op_sel_hi:[1,0] neg_lo:[0,1] neg_hi:[0,1]
	v_add_f32_dpp v156, v156, v156 row_ror:8 row_mask:0xf bank_mask:0xf bound_ctrl:1
	v_pk_add_f32 v[186:187], v[186:187], v[118:119] op_sel:[0,1] op_sel_hi:[1,1] neg_lo:[0,1] neg_hi:[0,1]
	v_add_f32_dpp v157, v157, v157 row_ror:8 row_mask:0xf bank_mask:0xf bound_ctrl:1
	v_pk_add_f32 v[180:181], v[180:181], v[118:119] op_sel_hi:[1,0] neg_lo:[0,1] neg_hi:[0,1]
	v_add_f32_dpp v156, v156, v156 row_ror:4 row_mask:0xf bank_mask:0xf bound_ctrl:1
	v_pk_add_f32 v[188:189], v[188:189], v[118:119] op_sel:[0,1] op_sel_hi:[1,1] neg_lo:[0,1] neg_hi:[0,1]
	v_add_f32_dpp v157, v157, v157 row_ror:4 row_mask:0xf bank_mask:0xf bound_ctrl:1
	v_pk_add_f32 v[182:183], v[182:183], v[118:119] op_sel_hi:[1,0] neg_lo:[0,1] neg_hi:[0,1]
	v_add_f32_dpp v156, v156, v156 row_ror:2 row_mask:0xf bank_mask:0xf bound_ctrl:1
	v_pk_add_f32 v[190:191], v[190:191], v[118:119] op_sel:[0,1] op_sel_hi:[1,1] neg_lo:[0,1] neg_hi:[0,1]
	v_add_f32_dpp v157, v157, v157 row_ror:2 row_mask:0xf bank_mask:0xf bound_ctrl:1
	v_pk_add_f32 v[184:185], v[184:185], v[118:119] op_sel_hi:[1,0] neg_lo:[0,1] neg_hi:[0,1]
	v_add_f32_dpp v156, v156, v156 row_ror:1 row_mask:0xf bank_mask:0xf bound_ctrl:1
	v_pk_add_f32 v[192:193], v[192:193], v[118:119] op_sel:[0,1] op_sel_hi:[1,1] neg_lo:[0,1] neg_hi:[0,1]
	v_add_f32_dpp v157, v157, v157 row_ror:1 row_mask:0xf bank_mask:0xf bound_ctrl:1
	s_waitcnt lgkmcnt(10)
	v_pk_fma_f32 v[178:179], v[72:73], v[178:179], v[118:119] op_sel_hi:[1,1,0]
	ds_write_b32 v103, v156 offset:40064
	v_pk_fma_f32 v[186:187], v[72:73], v[186:187], v[118:119] op_sel:[0,0,1] op_sel_hi:[1,1,1]
	ds_write_b32 v103, v157 offset:40128
	v_pk_fma_f32 v[180:181], v[74:75], v[180:181], v[118:119] op_sel_hi:[1,1,0]
	v_pk_fma_f32 v[188:189], v[74:75], v[188:189], v[118:119] op_sel:[0,0,1] op_sel_hi:[1,1,1]
	s_waitcnt lgkmcnt(11)
	v_pk_fma_f32 v[182:183], v[76:77], v[182:183], v[118:119] op_sel_hi:[1,1,0]
	v_pk_fma_f32 v[190:191], v[76:77], v[190:191], v[118:119] op_sel:[0,0,1] op_sel_hi:[1,1,1]
	v_pk_fma_f32 v[184:185], v[78:79], v[184:185], v[118:119] op_sel_hi:[1,1,0]
	v_pk_fma_f32 v[192:193], v[78:79], v[192:193], v[118:119] op_sel:[0,0,1] op_sel_hi:[1,1,1]
	s_waitcnt lgkmcnt(10)
	v_pk_fma_f32 v[146:147], v[64:65], v[178:179], v[196:197]
	v_pk_fma_f32 v[150:151], v[64:65], v[186:187], v[196:197]
	v_pk_fma_f32 v[148:149], v[66:67], v[180:181], v[196:197]
	v_pk_fma_f32 v[152:153], v[66:67], v[188:189], v[196:197]
	s_waitcnt lgkmcnt(9)
	v_pk_fma_f32 v[146:147], v[68:69], v[182:183], v[146:147]
	v_pk_fma_f32 v[150:151], v[68:69], v[190:191], v[150:151]
	v_pk_fma_f32 v[148:149], v[70:71], v[184:185], v[148:149]
	v_pk_fma_f32 v[152:153], v[70:71], v[192:193], v[152:153]
	v_add_f32_e32 v146, v146, v147
	v_add_f32_e32 v148, v148, v149
	v_add_f32_e32 v150, v150, v151
	v_add_f32_e32 v152, v152, v153
	v_add_f32_e32 v154, v146, v148
	v_add_f32_e32 v155, v150, v152
	ds_read2_b32 v[118:119], v195 offset0:128 offset1:144
	ds_read_b128 v[72:75], v145 offset:32768
	ds_read_b128 v[76:79], v145 offset:33024
	ds_read_b128 v[64:67], v145 offset:24576
	ds_read_b128 v[68:71], v145 offset:24832
	s_waitcnt lgkmcnt(11)
	v_pk_add_f32 v[178:179], v[178:179], v[120:121] op_sel_hi:[1,0] neg_lo:[0,1] neg_hi:[0,1]
	v_add_f32_dpp v154, v154, v154 row_ror:8 row_mask:0xf bank_mask:0xf bound_ctrl:1
	v_pk_add_f32 v[186:187], v[186:187], v[120:121] op_sel:[0,1] op_sel_hi:[1,1] neg_lo:[0,1] neg_hi:[0,1]
	v_add_f32_dpp v155, v155, v155 row_ror:8 row_mask:0xf bank_mask:0xf bound_ctrl:1
	v_pk_add_f32 v[180:181], v[180:181], v[120:121] op_sel_hi:[1,0] neg_lo:[0,1] neg_hi:[0,1]
	v_add_f32_dpp v154, v154, v154 row_ror:4 row_mask:0xf bank_mask:0xf bound_ctrl:1
	v_pk_add_f32 v[188:189], v[188:189], v[120:121] op_sel:[0,1] op_sel_hi:[1,1] neg_lo:[0,1] neg_hi:[0,1]
	v_add_f32_dpp v155, v155, v155 row_ror:4 row_mask:0xf bank_mask:0xf bound_ctrl:1
	v_pk_add_f32 v[182:183], v[182:183], v[120:121] op_sel_hi:[1,0] neg_lo:[0,1] neg_hi:[0,1]
	v_add_f32_dpp v154, v154, v154 row_ror:2 row_mask:0xf bank_mask:0xf bound_ctrl:1
	v_pk_add_f32 v[190:191], v[190:191], v[120:121] op_sel:[0,1] op_sel_hi:[1,1] neg_lo:[0,1] neg_hi:[0,1]
	v_add_f32_dpp v155, v155, v155 row_ror:2 row_mask:0xf bank_mask:0xf bound_ctrl:1
	v_pk_add_f32 v[184:185], v[184:185], v[120:121] op_sel_hi:[1,0] neg_lo:[0,1] neg_hi:[0,1]
	v_add_f32_dpp v154, v154, v154 row_ror:1 row_mask:0xf bank_mask:0xf bound_ctrl:1
	v_pk_add_f32 v[192:193], v[192:193], v[120:121] op_sel:[0,1] op_sel_hi:[1,1] neg_lo:[0,1] neg_hi:[0,1]
	v_add_f32_dpp v155, v155, v155 row_ror:1 row_mask:0xf bank_mask:0xf bound_ctrl:1
	s_waitcnt lgkmcnt(10)
	v_pk_fma_f32 v[178:179], v[88:89], v[178:179], v[120:121] op_sel_hi:[1,1,0]
	ds_write_b32 v103, v154 offset:40192
	v_pk_fma_f32 v[186:187], v[88:89], v[186:187], v[120:121] op_sel:[0,0,1] op_sel_hi:[1,1,1]
	ds_write_b32 v103, v155 offset:40256
	v_pk_fma_f32 v[180:181], v[90:91], v[180:181], v[120:121] op_sel_hi:[1,1,0]
	v_pk_fma_f32 v[188:189], v[90:91], v[188:189], v[120:121] op_sel:[0,0,1] op_sel_hi:[1,1,1]
	s_waitcnt lgkmcnt(11)
	v_pk_fma_f32 v[182:183], v[92:93], v[182:183], v[120:121] op_sel_hi:[1,1,0]
	v_pk_fma_f32 v[190:191], v[92:93], v[190:191], v[120:121] op_sel:[0,0,1] op_sel_hi:[1,1,1]
	v_pk_fma_f32 v[184:185], v[94:95], v[184:185], v[120:121] op_sel_hi:[1,1,0]
	v_pk_fma_f32 v[192:193], v[94:95], v[192:193], v[120:121] op_sel:[0,0,1] op_sel_hi:[1,1,1]
	s_waitcnt lgkmcnt(10)
	v_pk_fma_f32 v[146:147], v[80:81], v[178:179], v[196:197]
	v_pk_fma_f32 v[150:151], v[80:81], v[186:187], v[196:197]
	v_pk_fma_f32 v[148:149], v[82:83], v[180:181], v[196:197]
	v_pk_fma_f32 v[152:153], v[82:83], v[188:189], v[196:197]
	s_waitcnt lgkmcnt(9)
	v_pk_fma_f32 v[146:147], v[84:85], v[182:183], v[146:147]
	v_pk_fma_f32 v[150:151], v[84:85], v[190:191], v[150:151]
	v_pk_fma_f32 v[148:149], v[86:87], v[184:185], v[148:149]
	v_pk_fma_f32 v[152:153], v[86:87], v[192:193], v[152:153]
	v_add_f32_e32 v146, v146, v147
	v_add_f32_e32 v148, v148, v149
	v_add_f32_e32 v150, v150, v151
	v_add_f32_e32 v152, v152, v153
	v_add_f32_e32 v156, v146, v148
	v_add_f32_e32 v157, v150, v152
	ds_read2_b32 v[120:121], v195 offset0:160 offset1:176
	ds_read_b128 v[88:91], v145 offset:33280
	ds_read_b128 v[92:95], v145 offset:33536
	ds_read_b128 v[80:83], v145 offset:25088
	ds_read_b128 v[84:87], v145 offset:25344
	s_waitcnt lgkmcnt(11)
	v_pk_add_f32 v[178:179], v[178:179], v[118:119] op_sel_hi:[1,0] neg_lo:[0,1] neg_hi:[0,1]
	v_add_f32_dpp v156, v156, v156 row_ror:8 row_mask:0xf bank_mask:0xf bound_ctrl:1
	v_pk_add_f32 v[186:187], v[186:187], v[118:119] op_sel:[0,1] op_sel_hi:[1,1] neg_lo:[0,1] neg_hi:[0,1]
	v_add_f32_dpp v157, v157, v157 row_ror:8 row_mask:0xf bank_mask:0xf bound_ctrl:1
	v_pk_add_f32 v[180:181], v[180:181], v[118:119] op_sel_hi:[1,0] neg_lo:[0,1] neg_hi:[0,1]
	v_add_f32_dpp v156, v156, v156 row_ror:4 row_mask:0xf bank_mask:0xf bound_ctrl:1
	v_pk_add_f32 v[188:189], v[188:189], v[118:119] op_sel:[0,1] op_sel_hi:[1,1] neg_lo:[0,1] neg_hi:[0,1]
	v_add_f32_dpp v157, v157, v157 row_ror:4 row_mask:0xf bank_mask:0xf bound_ctrl:1
	v_pk_add_f32 v[182:183], v[182:183], v[118:119] op_sel_hi:[1,0] neg_lo:[0,1] neg_hi:[0,1]
	v_add_f32_dpp v156, v156, v156 row_ror:2 row_mask:0xf bank_mask:0xf bound_ctrl:1
	v_pk_add_f32 v[190:191], v[190:191], v[118:119] op_sel:[0,1] op_sel_hi:[1,1] neg_lo:[0,1] neg_hi:[0,1]
	v_add_f32_dpp v157, v157, v157 row_ror:2 row_mask:0xf bank_mask:0xf bound_ctrl:1
	v_pk_add_f32 v[184:185], v[184:185], v[118:119] op_sel_hi:[1,0] neg_lo:[0,1] neg_hi:[0,1]
	v_add_f32_dpp v156, v156, v156 row_ror:1 row_mask:0xf bank_mask:0xf bound_ctrl:1
	v_pk_add_f32 v[192:193], v[192:193], v[118:119] op_sel:[0,1] op_sel_hi:[1,1] neg_lo:[0,1] neg_hi:[0,1]
	v_add_f32_dpp v157, v157, v157 row_ror:1 row_mask:0xf bank_mask:0xf bound_ctrl:1
	s_waitcnt lgkmcnt(10)
	v_pk_fma_f32 v[178:179], v[72:73], v[178:179], v[118:119] op_sel_hi:[1,1,0]
	ds_write_b32 v103, v156 offset:40320
	v_pk_fma_f32 v[186:187], v[72:73], v[186:187], v[118:119] op_sel:[0,0,1] op_sel_hi:[1,1,1]
	ds_write_b32 v103, v157 offset:40384
	v_pk_fma_f32 v[180:181], v[74:75], v[180:181], v[118:119] op_sel_hi:[1,1,0]
	v_pk_fma_f32 v[188:189], v[74:75], v[188:189], v[118:119] op_sel:[0,0,1] op_sel_hi:[1,1,1]
	s_waitcnt lgkmcnt(11)
	v_pk_fma_f32 v[182:183], v[76:77], v[182:183], v[118:119] op_sel_hi:[1,1,0]
	v_pk_fma_f32 v[190:191], v[76:77], v[190:191], v[118:119] op_sel:[0,0,1] op_sel_hi:[1,1,1]
	v_pk_fma_f32 v[184:185], v[78:79], v[184:185], v[118:119] op_sel_hi:[1,1,0]
	v_pk_fma_f32 v[192:193], v[78:79], v[192:193], v[118:119] op_sel:[0,0,1] op_sel_hi:[1,1,1]
	s_waitcnt lgkmcnt(10)
	v_pk_fma_f32 v[146:147], v[64:65], v[178:179], v[196:197]
	v_pk_fma_f32 v[150:151], v[64:65], v[186:187], v[196:197]
	v_pk_fma_f32 v[148:149], v[66:67], v[180:181], v[196:197]
	v_pk_fma_f32 v[152:153], v[66:67], v[188:189], v[196:197]
	s_waitcnt lgkmcnt(9)
	v_pk_fma_f32 v[146:147], v[68:69], v[182:183], v[146:147]
	v_pk_fma_f32 v[150:151], v[68:69], v[190:191], v[150:151]
	v_pk_fma_f32 v[148:149], v[70:71], v[184:185], v[148:149]
	v_pk_fma_f32 v[152:153], v[70:71], v[192:193], v[152:153]
	v_add_f32_e32 v146, v146, v147
	v_add_f32_e32 v148, v148, v149
	v_add_f32_e32 v150, v150, v151
	v_add_f32_e32 v152, v152, v153
	v_add_f32_e32 v154, v146, v148
	v_add_f32_e32 v155, v150, v152
	ds_read2_b32 v[118:119], v195 offset0:192 offset1:208
	ds_read_b128 v[72:75], v145 offset:33792
	ds_read_b128 v[76:79], v145 offset:34048
	ds_read_b128 v[64:67], v145 offset:25600
	ds_read_b128 v[68:71], v145 offset:25856
	s_waitcnt lgkmcnt(11)
	v_pk_add_f32 v[178:179], v[178:179], v[120:121] op_sel_hi:[1,0] neg_lo:[0,1] neg_hi:[0,1]
	v_add_f32_dpp v154, v154, v154 row_ror:8 row_mask:0xf bank_mask:0xf bound_ctrl:1
	v_pk_add_f32 v[186:187], v[186:187], v[120:121] op_sel:[0,1] op_sel_hi:[1,1] neg_lo:[0,1] neg_hi:[0,1]
	v_add_f32_dpp v155, v155, v155 row_ror:8 row_mask:0xf bank_mask:0xf bound_ctrl:1
	v_pk_add_f32 v[180:181], v[180:181], v[120:121] op_sel_hi:[1,0] neg_lo:[0,1] neg_hi:[0,1]
	v_add_f32_dpp v154, v154, v154 row_ror:4 row_mask:0xf bank_mask:0xf bound_ctrl:1
	v_pk_add_f32 v[188:189], v[188:189], v[120:121] op_sel:[0,1] op_sel_hi:[1,1] neg_lo:[0,1] neg_hi:[0,1]
	v_add_f32_dpp v155, v155, v155 row_ror:4 row_mask:0xf bank_mask:0xf bound_ctrl:1
	v_pk_add_f32 v[182:183], v[182:183], v[120:121] op_sel_hi:[1,0] neg_lo:[0,1] neg_hi:[0,1]
	v_add_f32_dpp v154, v154, v154 row_ror:2 row_mask:0xf bank_mask:0xf bound_ctrl:1
	v_pk_add_f32 v[190:191], v[190:191], v[120:121] op_sel:[0,1] op_sel_hi:[1,1] neg_lo:[0,1] neg_hi:[0,1]
	v_add_f32_dpp v155, v155, v155 row_ror:2 row_mask:0xf bank_mask:0xf bound_ctrl:1
	v_pk_add_f32 v[184:185], v[184:185], v[120:121] op_sel_hi:[1,0] neg_lo:[0,1] neg_hi:[0,1]
	v_add_f32_dpp v154, v154, v154 row_ror:1 row_mask:0xf bank_mask:0xf bound_ctrl:1
	v_pk_add_f32 v[192:193], v[192:193], v[120:121] op_sel:[0,1] op_sel_hi:[1,1] neg_lo:[0,1] neg_hi:[0,1]
	v_add_f32_dpp v155, v155, v155 row_ror:1 row_mask:0xf bank_mask:0xf bound_ctrl:1
	s_waitcnt lgkmcnt(10)
	v_pk_fma_f32 v[178:179], v[88:89], v[178:179], v[120:121] op_sel_hi:[1,1,0]
	ds_write_b32 v103, v154 offset:40448
	v_pk_fma_f32 v[186:187], v[88:89], v[186:187], v[120:121] op_sel:[0,0,1] op_sel_hi:[1,1,1]
	ds_write_b32 v103, v155 offset:40512
	v_pk_fma_f32 v[180:181], v[90:91], v[180:181], v[120:121] op_sel_hi:[1,1,0]
	v_pk_fma_f32 v[188:189], v[90:91], v[188:189], v[120:121] op_sel:[0,0,1] op_sel_hi:[1,1,1]
	s_waitcnt lgkmcnt(11)
	v_pk_fma_f32 v[182:183], v[92:93], v[182:183], v[120:121] op_sel_hi:[1,1,0]
	v_pk_fma_f32 v[190:191], v[92:93], v[190:191], v[120:121] op_sel:[0,0,1] op_sel_hi:[1,1,1]
	v_pk_fma_f32 v[184:185], v[94:95], v[184:185], v[120:121] op_sel_hi:[1,1,0]
	v_pk_fma_f32 v[192:193], v[94:95], v[192:193], v[120:121] op_sel:[0,0,1] op_sel_hi:[1,1,1]
	s_waitcnt lgkmcnt(10)
	v_pk_fma_f32 v[146:147], v[80:81], v[178:179], v[196:197]
	v_pk_fma_f32 v[150:151], v[80:81], v[186:187], v[196:197]
	v_pk_fma_f32 v[148:149], v[82:83], v[180:181], v[196:197]
	v_pk_fma_f32 v[152:153], v[82:83], v[188:189], v[196:197]
	s_waitcnt lgkmcnt(9)
	v_pk_fma_f32 v[146:147], v[84:85], v[182:183], v[146:147]
	v_pk_fma_f32 v[150:151], v[84:85], v[190:191], v[150:151]
	v_pk_fma_f32 v[148:149], v[86:87], v[184:185], v[148:149]
	v_pk_fma_f32 v[152:153], v[86:87], v[192:193], v[152:153]
	v_add_f32_e32 v146, v146, v147
	v_add_f32_e32 v148, v148, v149
	v_add_f32_e32 v150, v150, v151
	v_add_f32_e32 v152, v152, v153
	v_add_f32_e32 v156, v146, v148
	v_add_f32_e32 v157, v150, v152
	ds_read2_b32 v[120:121], v195 offset0:224 offset1:240
	ds_read_b128 v[88:91], v145 offset:34304
	ds_read_b128 v[92:95], v145 offset:34560
	ds_read_b128 v[80:83], v145 offset:26112
	ds_read_b128 v[84:87], v145 offset:26368
	s_waitcnt lgkmcnt(11)
	v_pk_add_f32 v[178:179], v[178:179], v[118:119] op_sel_hi:[1,0] neg_lo:[0,1] neg_hi:[0,1]
	v_add_f32_dpp v156, v156, v156 row_ror:8 row_mask:0xf bank_mask:0xf bound_ctrl:1
	v_pk_add_f32 v[186:187], v[186:187], v[118:119] op_sel:[0,1] op_sel_hi:[1,1] neg_lo:[0,1] neg_hi:[0,1]
	v_add_f32_dpp v157, v157, v157 row_ror:8 row_mask:0xf bank_mask:0xf bound_ctrl:1
	v_pk_add_f32 v[180:181], v[180:181], v[118:119] op_sel_hi:[1,0] neg_lo:[0,1] neg_hi:[0,1]
	v_add_f32_dpp v156, v156, v156 row_ror:4 row_mask:0xf bank_mask:0xf bound_ctrl:1
	v_pk_add_f32 v[188:189], v[188:189], v[118:119] op_sel:[0,1] op_sel_hi:[1,1] neg_lo:[0,1] neg_hi:[0,1]
	v_add_f32_dpp v157, v157, v157 row_ror:4 row_mask:0xf bank_mask:0xf bound_ctrl:1
	v_pk_add_f32 v[182:183], v[182:183], v[118:119] op_sel_hi:[1,0] neg_lo:[0,1] neg_hi:[0,1]
	v_add_f32_dpp v156, v156, v156 row_ror:2 row_mask:0xf bank_mask:0xf bound_ctrl:1
	v_pk_add_f32 v[190:191], v[190:191], v[118:119] op_sel:[0,1] op_sel_hi:[1,1] neg_lo:[0,1] neg_hi:[0,1]
	v_add_f32_dpp v157, v157, v157 row_ror:2 row_mask:0xf bank_mask:0xf bound_ctrl:1
	v_pk_add_f32 v[184:185], v[184:185], v[118:119] op_sel_hi:[1,0] neg_lo:[0,1] neg_hi:[0,1]
	v_add_f32_dpp v156, v156, v156 row_ror:1 row_mask:0xf bank_mask:0xf bound_ctrl:1
	v_pk_add_f32 v[192:193], v[192:193], v[118:119] op_sel:[0,1] op_sel_hi:[1,1] neg_lo:[0,1] neg_hi:[0,1]
	v_add_f32_dpp v157, v157, v157 row_ror:1 row_mask:0xf bank_mask:0xf bound_ctrl:1
	s_waitcnt lgkmcnt(10)
	v_pk_fma_f32 v[178:179], v[72:73], v[178:179], v[118:119] op_sel_hi:[1,1,0]
	ds_write_b32 v103, v156 offset:40576
	v_pk_fma_f32 v[186:187], v[72:73], v[186:187], v[118:119] op_sel:[0,0,1] op_sel_hi:[1,1,1]
	ds_write_b32 v103, v157 offset:40640
	v_pk_fma_f32 v[180:181], v[74:75], v[180:181], v[118:119] op_sel_hi:[1,1,0]
	v_pk_fma_f32 v[188:189], v[74:75], v[188:189], v[118:119] op_sel:[0,0,1] op_sel_hi:[1,1,1]
	s_waitcnt lgkmcnt(11)
	v_pk_fma_f32 v[182:183], v[76:77], v[182:183], v[118:119] op_sel_hi:[1,1,0]
	v_pk_fma_f32 v[190:191], v[76:77], v[190:191], v[118:119] op_sel:[0,0,1] op_sel_hi:[1,1,1]
	v_pk_fma_f32 v[184:185], v[78:79], v[184:185], v[118:119] op_sel_hi:[1,1,0]
	v_pk_fma_f32 v[192:193], v[78:79], v[192:193], v[118:119] op_sel:[0,0,1] op_sel_hi:[1,1,1]
	s_waitcnt lgkmcnt(10)
	v_pk_fma_f32 v[146:147], v[64:65], v[178:179], v[196:197]
	v_pk_fma_f32 v[150:151], v[64:65], v[186:187], v[196:197]
	v_pk_fma_f32 v[148:149], v[66:67], v[180:181], v[196:197]
	v_pk_fma_f32 v[152:153], v[66:67], v[188:189], v[196:197]
	s_waitcnt lgkmcnt(9)
	v_pk_fma_f32 v[146:147], v[68:69], v[182:183], v[146:147]
	v_pk_fma_f32 v[150:151], v[68:69], v[190:191], v[150:151]
	v_pk_fma_f32 v[148:149], v[70:71], v[184:185], v[148:149]
	v_pk_fma_f32 v[152:153], v[70:71], v[192:193], v[152:153]
	v_add_f32_e32 v146, v146, v147
	v_add_f32_e32 v148, v148, v149
	v_add_f32_e32 v150, v150, v151
	v_add_f32_e32 v152, v152, v153
	v_add_f32_e32 v154, v146, v148
	v_add_f32_e32 v155, v150, v152
	s_waitcnt lgkmcnt(6)
	v_pk_add_f32 v[178:179], v[178:179], v[120:121] op_sel_hi:[1,0] neg_lo:[0,1] neg_hi:[0,1]
	v_add_f32_dpp v154, v154, v154 row_ror:8 row_mask:0xf bank_mask:0xf bound_ctrl:1
	v_pk_add_f32 v[186:187], v[186:187], v[120:121] op_sel:[0,1] op_sel_hi:[1,1] neg_lo:[0,1] neg_hi:[0,1]
	v_add_f32_dpp v155, v155, v155 row_ror:8 row_mask:0xf bank_mask:0xf bound_ctrl:1
	v_pk_add_f32 v[180:181], v[180:181], v[120:121] op_sel_hi:[1,0] neg_lo:[0,1] neg_hi:[0,1]
	v_add_f32_dpp v154, v154, v154 row_ror:4 row_mask:0xf bank_mask:0xf bound_ctrl:1
	v_pk_add_f32 v[188:189], v[188:189], v[120:121] op_sel:[0,1] op_sel_hi:[1,1] neg_lo:[0,1] neg_hi:[0,1]
	v_add_f32_dpp v155, v155, v155 row_ror:4 row_mask:0xf bank_mask:0xf bound_ctrl:1
	v_pk_add_f32 v[182:183], v[182:183], v[120:121] op_sel_hi:[1,0] neg_lo:[0,1] neg_hi:[0,1]
	v_add_f32_dpp v154, v154, v154 row_ror:2 row_mask:0xf bank_mask:0xf bound_ctrl:1
	v_pk_add_f32 v[190:191], v[190:191], v[120:121] op_sel:[0,1] op_sel_hi:[1,1] neg_lo:[0,1] neg_hi:[0,1]
	v_add_f32_dpp v155, v155, v155 row_ror:2 row_mask:0xf bank_mask:0xf bound_ctrl:1
	v_pk_add_f32 v[184:185], v[184:185], v[120:121] op_sel_hi:[1,0] neg_lo:[0,1] neg_hi:[0,1]
	v_add_f32_dpp v154, v154, v154 row_ror:1 row_mask:0xf bank_mask:0xf bound_ctrl:1
	v_pk_add_f32 v[192:193], v[192:193], v[120:121] op_sel:[0,1] op_sel_hi:[1,1] neg_lo:[0,1] neg_hi:[0,1]
	v_add_f32_dpp v155, v155, v155 row_ror:1 row_mask:0xf bank_mask:0xf bound_ctrl:1
	s_waitcnt lgkmcnt(5)
	v_pk_fma_f32 v[178:179], v[88:89], v[178:179], v[120:121] op_sel_hi:[1,1,0]
	ds_write_b32 v103, v154 offset:40704
	v_pk_fma_f32 v[186:187], v[88:89], v[186:187], v[120:121] op_sel:[0,0,1] op_sel_hi:[1,1,1]
	ds_write_b32 v103, v155 offset:40768
	v_pk_fma_f32 v[180:181], v[90:91], v[180:181], v[120:121] op_sel_hi:[1,1,0]
	v_pk_fma_f32 v[188:189], v[90:91], v[188:189], v[120:121] op_sel:[0,0,1] op_sel_hi:[1,1,1]
	s_waitcnt lgkmcnt(6)
	v_pk_fma_f32 v[182:183], v[92:93], v[182:183], v[120:121] op_sel_hi:[1,1,0]
	v_pk_fma_f32 v[190:191], v[92:93], v[190:191], v[120:121] op_sel:[0,0,1] op_sel_hi:[1,1,1]
	v_pk_fma_f32 v[184:185], v[94:95], v[184:185], v[120:121] op_sel_hi:[1,1,0]
	v_pk_fma_f32 v[192:193], v[94:95], v[192:193], v[120:121] op_sel:[0,0,1] op_sel_hi:[1,1,1]
	s_waitcnt lgkmcnt(5)
	v_pk_fma_f32 v[146:147], v[80:81], v[178:179], v[196:197]
	v_pk_fma_f32 v[150:151], v[80:81], v[186:187], v[196:197]
	v_pk_fma_f32 v[148:149], v[82:83], v[180:181], v[196:197]
	v_pk_fma_f32 v[152:153], v[82:83], v[188:189], v[196:197]
	s_waitcnt lgkmcnt(4)
	v_pk_fma_f32 v[146:147], v[84:85], v[182:183], v[146:147]
	v_pk_fma_f32 v[150:151], v[84:85], v[190:191], v[150:151]
	v_pk_fma_f32 v[148:149], v[86:87], v[184:185], v[148:149]
	v_pk_fma_f32 v[152:153], v[86:87], v[192:193], v[152:153]
	v_add_f32_e32 v146, v146, v147
	v_add_f32_e32 v148, v148, v149
	v_add_f32_e32 v150, v150, v151
	v_add_f32_e32 v152, v152, v153
	v_add_f32_e32 v156, v146, v148
	v_add_f32_e32 v157, v150, v152
	s_nop 0
	v_add_f32_dpp v156, v156, v156 row_ror:8 row_mask:0xf bank_mask:0xf bound_ctrl:1
	v_add_f32_dpp v157, v157, v157 row_ror:8 row_mask:0xf bank_mask:0xf bound_ctrl:1
	s_nop 0
	v_add_f32_dpp v156, v156, v156 row_ror:4 row_mask:0xf bank_mask:0xf bound_ctrl:1
	v_add_f32_dpp v157, v157, v157 row_ror:4 row_mask:0xf bank_mask:0xf bound_ctrl:1
	s_nop 0
	v_add_f32_dpp v156, v156, v156 row_ror:2 row_mask:0xf bank_mask:0xf bound_ctrl:1
	v_add_f32_dpp v157, v157, v157 row_ror:2 row_mask:0xf bank_mask:0xf bound_ctrl:1
	s_nop 0
	v_add_f32_dpp v156, v156, v156 row_ror:1 row_mask:0xf bank_mask:0xf bound_ctrl:1
	v_add_f32_dpp v157, v157, v157 row_ror:1 row_mask:0xf bank_mask:0xf bound_ctrl:1
	ds_write_b32 v103, v156 offset:40832
	ds_write_b32 v103, v157 offset:40896
	s_waitcnt lgkmcnt(0)
	v_mov_b32_e32 v118, v178
	v_mov_b32_e32 v119, v179
	v_mov_b32_e32 v88, v180
	v_mov_b32_e32 v89, v181
	v_mov_b32_e32 v90, v182
	v_mov_b32_e32 v80, v183
	v_mov_b32_e32 v81, v184
	v_mov_b32_e32 v82, v185
	v_mov_b32_e32 v146, v186
	v_mov_b32_e32 v120, v187
	v_mov_b32_e32 v121, v188
	v_mov_b32_e32 v91, v189
	v_mov_b32_e32 v147, v190
	v_mov_b32_e32 v148, v191
	v_mov_b32_e32 v149, v192
	v_mov_b32_e32 v83, v193
	s_branch .LBB0_1284

.LBB0_1454:
	s_or_b64 exec, exec, s[8:9]
	s_waitcnt lgkmcnt(0)
	s_barrier
	v_mov_b32_e32 v196, v64
	v_mov_b32_e32 v197, v65
	v_mov_b32_e32 v198, v66
	v_mov_b32_e32 v199, v67
	v_mov_b32_e32 v200, v76
	v_mov_b32_e32 v201, v77
	v_mov_b32_e32 v202, v78
	v_mov_b32_e32 v203, v79
	v_mov_b32_e32 v204, v72
	v_mov_b32_e32 v205, v73
	v_mov_b32_e32 v206, v74
	v_mov_b32_e32 v207, v75
	v_mov_b32_e32 v208, v68
	v_mov_b32_e32 v209, v69
	v_mov_b32_e32 v210, v70
	v_mov_b32_e32 v211, v71
	v_mov_b32_e32 v192, 0
	v_mov_b32_e32 v193, 0
	ds_read_b128 v[80:83], v188 offset:8192
	ds_read_b128 v[84:87], v188 offset:8448
	ds_read_b128 v[88:91], v188 offset:8704
	ds_read_b128 v[92:95], v188 offset:8960
	ds_read_b32 v134, v140 offset:35136
	ds_read_b32 v135, v189 offset:16384
	ds_read_b32 v132, v140 offset:35072
	ds_read_b128 v[64:67], v188
	ds_read_b128 v[68:71], v188 offset:256
	ds_read_b128 v[72:75], v188 offset:512
	ds_read_b128 v[76:79], v188 offset:768
	ds_read_b128 v[112:115], v188 offset:9216
	ds_read_b128 v[116:119], v188 offset:9472
	ds_read_b128 v[120:123], v188 offset:9728
	ds_read_b128 v[124:127], v188 offset:9984
	ds_read_b32 v154, v140 offset:35140
	ds_read_b32 v155, v189 offset:16448
	ds_read_b32 v152, v140 offset:35076
	ds_read_b128 v[96:99], v188 offset:1024
	ds_read_b128 v[100:103], v188 offset:1280
	ds_read_b128 v[104:107], v188 offset:1536
	ds_read_b128 v[108:111], v188 offset:1792
	s_waitcnt lgkmcnt(15)
	v_mul_f32_e32 v133, v134, v135
	v_pk_mul_f32 v[80:81], v[80:81], v[132:133] op_sel:[0,1] op_sel_hi:[1,1]
	v_pk_mul_f32 v[82:83], v[82:83], v[132:133] op_sel:[0,1] op_sel_hi:[1,1]
	v_pk_mul_f32 v[84:85], v[84:85], v[132:133] op_sel:[0,1] op_sel_hi:[1,1]
	v_pk_mul_f32 v[86:87], v[86:87], v[132:133] op_sel:[0,1] op_sel_hi:[1,1]
	v_pk_mul_f32 v[88:89], v[88:89], v[132:133] op_sel:[0,1] op_sel_hi:[1,1]
	v_pk_mul_f32 v[90:91], v[90:91], v[132:133] op_sel:[0,1] op_sel_hi:[1,1]
	v_pk_mul_f32 v[92:93], v[92:93], v[132:133] op_sel:[0,1] op_sel_hi:[1,1]
	v_pk_mul_f32 v[94:95], v[94:95], v[132:133] op_sel:[0,1] op_sel_hi:[1,1]
	v_pk_fma_f32 v[196:197], v[132:133], v[196:197], v[80:81] op_sel_hi:[0,1,1]
	v_pk_fma_f32 v[198:199], v[132:133], v[198:199], v[82:83] op_sel_hi:[0,1,1]
	v_pk_fma_f32 v[200:201], v[132:133], v[200:201], v[84:85] op_sel_hi:[0,1,1]
	v_pk_fma_f32 v[202:203], v[132:133], v[202:203], v[86:87] op_sel_hi:[0,1,1]
	v_pk_fma_f32 v[204:205], v[132:133], v[204:205], v[88:89] op_sel_hi:[0,1,1]
	v_pk_fma_f32 v[206:207], v[132:133], v[206:207], v[90:91] op_sel_hi:[0,1,1]
	v_pk_fma_f32 v[208:209], v[132:133], v[208:209], v[92:93] op_sel_hi:[0,1,1]
	v_pk_fma_f32 v[210:211], v[132:133], v[210:211], v[94:95] op_sel_hi:[0,1,1]
	s_waitcnt lgkmcnt(14)
	v_pk_fma_f32 v[128:129], v[64:65], v[196:197], v[192:193]
	v_pk_fma_f32 v[130:131], v[66:67], v[198:199], v[192:193]
	s_waitcnt lgkmcnt(13)
	v_pk_fma_f32 v[128:129], v[68:69], v[200:201], v[128:129]
	v_pk_fma_f32 v[130:131], v[70:71], v[202:203], v[130:131]
	s_waitcnt lgkmcnt(12)
	v_pk_fma_f32 v[128:129], v[72:73], v[204:205], v[128:129]
	v_pk_fma_f32 v[130:131], v[74:75], v[206:207], v[130:131]
	s_waitcnt lgkmcnt(11)
	v_pk_fma_f32 v[128:129], v[76:77], v[208:209], v[128:129]
	v_pk_fma_f32 v[130:131], v[78:79], v[210:211], v[130:131]
	v_add_f32_e32 v128, v128, v129
	v_add_f32_e32 v130, v130, v131
	v_add_f32_e32 v190, v128, v130
	ds_read_b128 v[80:83], v188 offset:10240
	ds_read_b128 v[84:87], v188 offset:10496
	ds_read_b128 v[88:91], v188 offset:10752
	ds_read_b128 v[92:95], v188 offset:11008
	ds_read_b32 v134, v140 offset:35144
	ds_read_b32 v135, v189 offset:16512
	ds_read_b32 v132, v140 offset:35080
	ds_read_b128 v[64:67], v188 offset:2048
	ds_read_b128 v[68:71], v188 offset:2304
	ds_read_b128 v[72:75], v188 offset:2560
	ds_read_b128 v[76:79], v188 offset:2816
	s_waitcnt lgkmcnt(15)
	v_mul_f32_e32 v153, v154, v155
	v_pk_mul_f32 v[112:113], v[112:113], v[152:153] op_sel:[0,1] op_sel_hi:[1,1]
	v_add_f32_dpp v190, v190, v190 row_ror:8 row_mask:0xf bank_mask:0xf bound_ctrl:1
	v_pk_mul_f32 v[114:115], v[114:115], v[152:153] op_sel:[0,1] op_sel_hi:[1,1]
	v_pk_mul_f32 v[116:117], v[116:117], v[152:153] op_sel:[0,1] op_sel_hi:[1,1]
	v_add_f32_dpp v190, v190, v190 row_ror:4 row_mask:0xf bank_mask:0xf bound_ctrl:1
	v_pk_mul_f32 v[118:119], v[118:119], v[152:153] op_sel:[0,1] op_sel_hi:[1,1]
	v_pk_mul_f32 v[120:121], v[120:121], v[152:153] op_sel:[0,1] op_sel_hi:[1,1]
	v_add_f32_dpp v190, v190, v190 row_ror:2 row_mask:0xf bank_mask:0xf bound_ctrl:1
	v_pk_mul_f32 v[122:123], v[122:123], v[152:153] op_sel:[0,1] op_sel_hi:[1,1]
	v_pk_mul_f32 v[124:125], v[124:125], v[152:153] op_sel:[0,1] op_sel_hi:[1,1]
	v_add_f32_dpp v190, v190, v190 row_ror:1 row_mask:0xf bank_mask:0xf bound_ctrl:1
	v_pk_mul_f32 v[126:127], v[126:127], v[152:153] op_sel:[0,1] op_sel_hi:[1,1]
	v_pk_fma_f32 v[196:197], v[152:153], v[196:197], v[112:113] op_sel_hi:[0,1,1]
	ds_write_b32 v189, v190 offset:34048
	v_pk_fma_f32 v[198:199], v[152:153], v[198:199], v[114:115] op_sel_hi:[0,1,1]
	v_pk_fma_f32 v[200:201], v[152:153], v[200:201], v[116:117] op_sel_hi:[0,1,1]
	v_pk_fma_f32 v[202:203], v[152:153], v[202:203], v[118:119] op_sel_hi:[0,1,1]
	v_pk_fma_f32 v[204:205], v[152:153], v[204:205], v[120:121] op_sel_hi:[0,1,1]
	v_pk_fma_f32 v[206:207], v[152:153], v[206:207], v[122:123] op_sel_hi:[0,1,1]
	v_pk_fma_f32 v[208:209], v[152:153], v[208:209], v[124:125] op_sel_hi:[0,1,1]
	v_pk_fma_f32 v[210:211], v[152:153], v[210:211], v[126:127] op_sel_hi:[0,1,1]
	s_waitcnt lgkmcnt(15)
	v_pk_fma_f32 v[128:129], v[96:97], v[196:197], v[192:193]
	v_pk_fma_f32 v[130:131], v[98:99], v[198:199], v[192:193]
	s_waitcnt lgkmcnt(14)
	v_pk_fma_f32 v[128:129], v[100:101], v[200:201], v[128:129]
	v_pk_fma_f32 v[130:131], v[102:103], v[202:203], v[130:131]
	s_waitcnt lgkmcnt(13)
	v_pk_fma_f32 v[128:129], v[104:105], v[204:205], v[128:129]
	v_pk_fma_f32 v[130:131], v[106:107], v[206:207], v[130:131]
	s_waitcnt lgkmcnt(12)
	v_pk_fma_f32 v[128:129], v[108:109], v[208:209], v[128:129]
	v_pk_fma_f32 v[130:131], v[110:111], v[210:211], v[130:131]
	v_add_f32_e32 v128, v128, v129
	v_add_f32_e32 v130, v130, v131
	v_add_f32_e32 v191, v128, v130
	ds_read_b128 v[112:115], v188 offset:11264
	ds_read_b128 v[116:119], v188 offset:11520
	ds_read_b128 v[120:123], v188 offset:11776
	ds_read_b128 v[124:127], v188 offset:12032
	ds_read_b32 v154, v140 offset:35148
	ds_read_b32 v155, v189 offset:16576
	ds_read_b32 v152, v140 offset:35084
	ds_read_b128 v[96:99], v188 offset:3072
	ds_read_b128 v[100:103], v188 offset:3328
	ds_read_b128 v[104:107], v188 offset:3584
	ds_read_b128 v[108:111], v188 offset:3840
	s_waitcnt lgkmcnt(15)
	v_mul_f32_e32 v133, v134, v135
	v_pk_mul_f32 v[80:81], v[80:81], v[132:133] op_sel:[0,1] op_sel_hi:[1,1]
	v_add_f32_dpp v191, v191, v191 row_ror:8 row_mask:0xf bank_mask:0xf bound_ctrl:1
	v_pk_mul_f32 v[82:83], v[82:83], v[132:133] op_sel:[0,1] op_sel_hi:[1,1]
	v_pk_mul_f32 v[84:85], v[84:85], v[132:133] op_sel:[0,1] op_sel_hi:[1,1]
	v_add_f32_dpp v191, v191, v191 row_ror:4 row_mask:0xf bank_mask:0xf bound_ctrl:1
	v_pk_mul_f32 v[86:87], v[86:87], v[132:133] op_sel:[0,1] op_sel_hi:[1,1]
	v_pk_mul_f32 v[88:89], v[88:89], v[132:133] op_sel:[0,1] op_sel_hi:[1,1]
	v_add_f32_dpp v191, v191, v191 row_ror:2 row_mask:0xf bank_mask:0xf bound_ctrl:1
	v_pk_mul_f32 v[90:91], v[90:91], v[132:133] op_sel:[0,1] op_sel_hi:[1,1]
	v_pk_mul_f32 v[92:93], v[92:93], v[132:133] op_sel:[0,1] op_sel_hi:[1,1]
	v_add_f32_dpp v191, v191, v191 row_ror:1 row_mask:0xf bank_mask:0xf bound_ctrl:1
	v_pk_mul_f32 v[94:95], v[94:95], v[132:133] op_sel:[0,1] op_sel_hi:[1,1]
	v_pk_fma_f32 v[196:197], v[132:133], v[196:197], v[80:81] op_sel_hi:[0,1,1]
	ds_write_b32 v189, v191 offset:34112
	v_pk_fma_f32 v[198:199], v[132:133], v[198:199], v[82:83] op_sel_hi:[0,1,1]
	v_pk_fma_f32 v[200:201], v[132:133], v[200:201], v[84:85] op_sel_hi:[0,1,1]
	v_pk_fma_f32 v[202:203], v[132:133], v[202:203], v[86:87] op_sel_hi:[0,1,1]
	v_pk_fma_f32 v[204:205], v[132:133], v[204:205], v[88:89] op_sel_hi:[0,1,1]
	v_pk_fma_f32 v[206:207], v[132:133], v[206:207], v[90:91] op_sel_hi:[0,1,1]
	v_pk_fma_f32 v[208:209], v[132:133], v[208:209], v[92:93] op_sel_hi:[0,1,1]
	v_pk_fma_f32 v[210:211], v[132:133], v[210:211], v[94:95] op_sel_hi:[0,1,1]
	s_waitcnt lgkmcnt(15)
	v_pk_fma_f32 v[128:129], v[64:65], v[196:197], v[192:193]
	v_pk_fma_f32 v[130:131], v[66:67], v[198:199], v[192:193]
	v_pk_fma_f32 v[128:129], v[68:69], v[200:201], v[128:129]
	v_pk_fma_f32 v[130:131], v[70:71], v[202:203], v[130:131]
	s_waitcnt lgkmcnt(14)
	v_pk_fma_f32 v[128:129], v[72:73], v[204:205], v[128:129]
	v_pk_fma_f32 v[130:131], v[74:75], v[206:207], v[130:131]
	s_waitcnt lgkmcnt(13)
	v_pk_fma_f32 v[128:129], v[76:77], v[208:209], v[128:129]
	v_pk_fma_f32 v[130:131], v[78:79], v[210:211], v[130:131]
	v_add_f32_e32 v128, v128, v129
	v_add_f32_e32 v130, v130, v131
	v_add_f32_e32 v190, v128, v130
	ds_read_b128 v[80:83], v188 offset:12288
	ds_read_b128 v[84:87], v188 offset:12544
	ds_read_b128 v[88:91], v188 offset:12800
	ds_read_b128 v[92:95], v188 offset:13056
	ds_read_b32 v134, v140 offset:35152
	ds_read_b32 v135, v189 offset:16640
	ds_read_b32 v132, v140 offset:35088
	ds_read_b128 v[64:67], v188 offset:4096
	ds_read_b128 v[68:71], v188 offset:4352
	ds_read_b128 v[72:75], v188 offset:4608
	ds_read_b128 v[76:79], v188 offset:4864
	s_waitcnt lgkmcnt(15)
	v_mul_f32_e32 v153, v154, v155
	v_pk_mul_f32 v[112:113], v[112:113], v[152:153] op_sel:[0,1] op_sel_hi:[1,1]
	v_add_f32_dpp v190, v190, v190 row_ror:8 row_mask:0xf bank_mask:0xf bound_ctrl:1
	v_pk_mul_f32 v[114:115], v[114:115], v[152:153] op_sel:[0,1] op_sel_hi:[1,1]
	v_pk_mul_f32 v[116:117], v[116:117], v[152:153] op_sel:[0,1] op_sel_hi:[1,1]
	v_add_f32_dpp v190, v190, v190 row_ror:4 row_mask:0xf bank_mask:0xf bound_ctrl:1
	v_pk_mul_f32 v[118:119], v[118:119], v[152:153] op_sel:[0,1] op_sel_hi:[1,1]
	v_pk_mul_f32 v[120:121], v[120:121], v[152:153] op_sel:[0,1] op_sel_hi:[1,1]
	v_add_f32_dpp v190, v190, v190 row_ror:2 row_mask:0xf bank_mask:0xf bound_ctrl:1
	v_pk_mul_f32 v[122:123], v[122:123], v[152:153] op_sel:[0,1] op_sel_hi:[1,1]
	v_pk_mul_f32 v[124:125], v[124:125], v[152:153] op_sel:[0,1] op_sel_hi:[1,1]
	v_add_f32_dpp v190, v190, v190 row_ror:1 row_mask:0xf bank_mask:0xf bound_ctrl:1
	v_pk_mul_f32 v[126:127], v[126:127], v[152:153] op_sel:[0,1] op_sel_hi:[1,1]
	v_pk_fma_f32 v[196:197], v[152:153], v[196:197], v[112:113] op_sel_hi:[0,1,1]
	ds_write_b32 v189, v190 offset:34176
	v_pk_fma_f32 v[198:199], v[152:153], v[198:199], v[114:115] op_sel_hi:[0,1,1]
	v_pk_fma_f32 v[200:201], v[152:153], v[200:201], v[116:117] op_sel_hi:[0,1,1]
	v_pk_fma_f32 v[202:203], v[152:153], v[202:203], v[118:119] op_sel_hi:[0,1,1]
	v_pk_fma_f32 v[204:205], v[152:153], v[204:205], v[120:121] op_sel_hi:[0,1,1]
	v_pk_fma_f32 v[206:207], v[152:153], v[206:207], v[122:123] op_sel_hi:[0,1,1]
	v_pk_fma_f32 v[208:209], v[152:153], v[208:209], v[124:125] op_sel_hi:[0,1,1]
	v_pk_fma_f32 v[210:211], v[152:153], v[210:211], v[126:127] op_sel_hi:[0,1,1]
	s_waitcnt lgkmcnt(15)
	v_pk_fma_f32 v[128:129], v[96:97], v[196:197], v[192:193]
	v_pk_fma_f32 v[130:131], v[98:99], v[198:199], v[192:193]
	v_pk_fma_f32 v[128:129], v[100:101], v[200:201], v[128:129]
	v_pk_fma_f32 v[130:131], v[102:103], v[202:203], v[130:131]
	s_waitcnt lgkmcnt(14)
	v_pk_fma_f32 v[128:129], v[104:105], v[204:205], v[128:129]
	v_pk_fma_f32 v[130:131], v[106:107], v[206:207], v[130:131]
	s_waitcnt lgkmcnt(13)
	v_pk_fma_f32 v[128:129], v[108:109], v[208:209], v[128:129]
	v_pk_fma_f32 v[130:131], v[110:111], v[210:211], v[130:131]
	v_add_f32_e32 v128, v128, v129
	v_add_f32_e32 v130, v130, v131
	v_add_f32_e32 v191, v128, v130
	ds_read_b128 v[112:115], v188 offset:13312
	ds_read_b128 v[116:119], v188 offset:13568
	ds_read_b128 v[120:123], v188 offset:13824
	ds_read_b128 v[124:127], v188 offset:14080
	ds_read_b32 v154, v140 offset:35156
	ds_read_b32 v155, v189 offset:16704
	ds_read_b32 v152, v140 offset:35092
	ds_read_b128 v[96:99], v188 offset:5120
	ds_read_b128 v[100:103], v188 offset:5376
	ds_read_b128 v[104:107], v188 offset:5632
	ds_read_b128 v[108:111], v188 offset:5888
	s_waitcnt lgkmcnt(15)
	v_mul_f32_e32 v133, v134, v135
	v_pk_mul_f32 v[80:81], v[80:81], v[132:133] op_sel:[0,1] op_sel_hi:[1,1]
	v_add_f32_dpp v191, v191, v191 row_ror:8 row_mask:0xf bank_mask:0xf bound_ctrl:1
	v_pk_mul_f32 v[82:83], v[82:83], v[132:133] op_sel:[0,1] op_sel_hi:[1,1]
	v_pk_mul_f32 v[84:85], v[84:85], v[132:133] op_sel:[0,1] op_sel_hi:[1,1]
	v_add_f32_dpp v191, v191, v191 row_ror:4 row_mask:0xf bank_mask:0xf bound_ctrl:1
	v_pk_mul_f32 v[86:87], v[86:87], v[132:133] op_sel:[0,1] op_sel_hi:[1,1]
	v_pk_mul_f32 v[88:89], v[88:89], v[132:133] op_sel:[0,1] op_sel_hi:[1,1]
	v_add_f32_dpp v191, v191, v191 row_ror:2 row_mask:0xf bank_mask:0xf bound_ctrl:1
	v_pk_mul_f32 v[90:91], v[90:91], v[132:133] op_sel:[0,1] op_sel_hi:[1,1]
	v_pk_mul_f32 v[92:93], v[92:93], v[132:133] op_sel:[0,1] op_sel_hi:[1,1]
	v_add_f32_dpp v191, v191, v191 row_ror:1 row_mask:0xf bank_mask:0xf bound_ctrl:1
	v_pk_mul_f32 v[94:95], v[94:95], v[132:133] op_sel:[0,1] op_sel_hi:[1,1]
	v_pk_fma_f32 v[196:197], v[132:133], v[196:197], v[80:81] op_sel_hi:[0,1,1]
	ds_write_b32 v189, v191 offset:34240
	v_pk_fma_f32 v[198:199], v[132:133], v[198:199], v[82:83] op_sel_hi:[0,1,1]
	v_pk_fma_f32 v[200:201], v[132:133], v[200:201], v[84:85] op_sel_hi:[0,1,1]
	v_pk_fma_f32 v[202:203], v[132:133], v[202:203], v[86:87] op_sel_hi:[0,1,1]
	v_pk_fma_f32 v[204:205], v[132:133], v[204:205], v[88:89] op_sel_hi:[0,1,1]
	v_pk_fma_f32 v[206:207], v[132:133], v[206:207], v[90:91] op_sel_hi:[0,1,1]
	v_pk_fma_f32 v[208:209], v[132:133], v[208:209], v[92:93] op_sel_hi:[0,1,1]
	v_pk_fma_f32 v[210:211], v[132:133], v[210:211], v[94:95] op_sel_hi:[0,1,1]
	s_waitcnt lgkmcnt(15)
	v_pk_fma_f32 v[128:129], v[64:65], v[196:197], v[192:193]
	v_pk_fma_f32 v[130:131], v[66:67], v[198:199], v[192:193]
	v_pk_fma_f32 v[128:129], v[68:69], v[200:201], v[128:129]
	v_pk_fma_f32 v[130:131], v[70:71], v[202:203], v[130:131]
	s_waitcnt lgkmcnt(14)
	v_pk_fma_f32 v[128:129], v[72:73], v[204:205], v[128:129]
	v_pk_fma_f32 v[130:131], v[74:75], v[206:207], v[130:131]
	s_waitcnt lgkmcnt(13)
	v_pk_fma_f32 v[128:129], v[76:77], v[208:209], v[128:129]
	v_pk_fma_f32 v[130:131], v[78:79], v[210:211], v[130:131]
	v_add_f32_e32 v128, v128, v129
	v_add_f32_e32 v130, v130, v131
	v_add_f32_e32 v190, v128, v130
	ds_read_b128 v[80:83], v188 offset:14336
	ds_read_b128 v[84:87], v188 offset:14592
	ds_read_b128 v[88:91], v188 offset:14848
	ds_read_b128 v[92:95], v188 offset:15104
	ds_read_b32 v134, v140 offset:35160
	ds_read_b32 v135, v189 offset:16768
	ds_read_b32 v132, v140 offset:35096
	ds_read_b128 v[64:67], v188 offset:6144
	ds_read_b128 v[68:71], v188 offset:6400
	ds_read_b128 v[72:75], v188 offset:6656
	ds_read_b128 v[76:79], v188 offset:6912
	s_waitcnt lgkmcnt(15)
	v_mul_f32_e32 v153, v154, v155
	v_pk_mul_f32 v[112:113], v[112:113], v[152:153] op_sel:[0,1] op_sel_hi:[1,1]
	v_add_f32_dpp v190, v190, v190 row_ror:8 row_mask:0xf bank_mask:0xf bound_ctrl:1
	v_pk_mul_f32 v[114:115], v[114:115], v[152:153] op_sel:[0,1] op_sel_hi:[1,1]
	v_pk_mul_f32 v[116:117], v[116:117], v[152:153] op_sel:[0,1] op_sel_hi:[1,1]
	v_add_f32_dpp v190, v190, v190 row_ror:4 row_mask:0xf bank_mask:0xf bound_ctrl:1
	v_pk_mul_f32 v[118:119], v[118:119], v[152:153] op_sel:[0,1] op_sel_hi:[1,1]
	v_pk_mul_f32 v[120:121], v[120:121], v[152:153] op_sel:[0,1] op_sel_hi:[1,1]
	v_add_f32_dpp v190, v190, v190 row_ror:2 row_mask:0xf bank_mask:0xf bound_ctrl:1
	v_pk_mul_f32 v[122:123], v[122:123], v[152:153] op_sel:[0,1] op_sel_hi:[1,1]
	v_pk_mul_f32 v[124:125], v[124:125], v[152:153] op_sel:[0,1] op_sel_hi:[1,1]
	v_add_f32_dpp v190, v190, v190 row_ror:1 row_mask:0xf bank_mask:0xf bound_ctrl:1
	v_pk_mul_f32 v[126:127], v[126:127], v[152:153] op_sel:[0,1] op_sel_hi:[1,1]
	v_pk_fma_f32 v[196:197], v[152:153], v[196:197], v[112:113] op_sel_hi:[0,1,1]
	ds_write_b32 v189, v190 offset:34304
	v_pk_fma_f32 v[198:199], v[152:153], v[198:199], v[114:115] op_sel_hi:[0,1,1]
	v_pk_fma_f32 v[200:201], v[152:153], v[200:201], v[116:117] op_sel_hi:[0,1,1]
	v_pk_fma_f32 v[202:203], v[152:153], v[202:203], v[118:119] op_sel_hi:[0,1,1]
	v_pk_fma_f32 v[204:205], v[152:153], v[204:205], v[120:121] op_sel_hi:[0,1,1]
	v_pk_fma_f32 v[206:207], v[152:153], v[206:207], v[122:123] op_sel_hi:[0,1,1]
	v_pk_fma_f32 v[208:209], v[152:153], v[208:209], v[124:125] op_sel_hi:[0,1,1]
	v_pk_fma_f32 v[210:211], v[152:153], v[210:211], v[126:127] op_sel_hi:[0,1,1]
	s_waitcnt lgkmcnt(15)
	v_pk_fma_f32 v[128:129], v[96:97], v[196:197], v[192:193]
	v_pk_fma_f32 v[130:131], v[98:99], v[198:199], v[192:193]
	v_pk_fma_f32 v[128:129], v[100:101], v[200:201], v[128:129]
	v_pk_fma_f32 v[130:131], v[102:103], v[202:203], v[130:131]
	s_waitcnt lgkmcnt(14)
	v_pk_fma_f32 v[128:129], v[104:105], v[204:205], v[128:129]
	v_pk_fma_f32 v[130:131], v[106:107], v[206:207], v[130:131]
	s_waitcnt lgkmcnt(13)
	v_pk_fma_f32 v[128:129], v[108:109], v[208:209], v[128:129]
	v_pk_fma_f32 v[130:131], v[110:111], v[210:211], v[130:131]
	v_add_f32_e32 v128, v128, v129
	v_add_f32_e32 v130, v130, v131
	v_add_f32_e32 v191, v128, v130
	ds_read_b128 v[112:115], v188 offset:15360
	ds_read_b128 v[116:119], v188 offset:15616
	ds_read_b128 v[120:123], v188 offset:15872
	ds_read_b128 v[124:127], v188 offset:16128
	ds_read_b32 v154, v140 offset:35164
	ds_read_b32 v155, v189 offset:16832
	ds_read_b32 v152, v140 offset:35100
	ds_read_b128 v[96:99], v188 offset:7168
	ds_read_b128 v[100:103], v188 offset:7424
	ds_read_b128 v[104:107], v188 offset:7680
	ds_read_b128 v[108:111], v188 offset:7936
	s_waitcnt lgkmcnt(15)
	v_mul_f32_e32 v133, v134, v135
	v_pk_mul_f32 v[80:81], v[80:81], v[132:133] op_sel:[0,1] op_sel_hi:[1,1]
	v_add_f32_dpp v191, v191, v191 row_ror:8 row_mask:0xf bank_mask:0xf bound_ctrl:1
	v_pk_mul_f32 v[82:83], v[82:83], v[132:133] op_sel:[0,1] op_sel_hi:[1,1]
	v_pk_mul_f32 v[84:85], v[84:85], v[132:133] op_sel:[0,1] op_sel_hi:[1,1]
	v_add_f32_dpp v191, v191, v191 row_ror:4 row_mask:0xf bank_mask:0xf bound_ctrl:1
	v_pk_mul_f32 v[86:87], v[86:87], v[132:133] op_sel:[0,1] op_sel_hi:[1,1]
	v_pk_mul_f32 v[88:89], v[88:89], v[132:133] op_sel:[0,1] op_sel_hi:[1,1]
	v_add_f32_dpp v191, v191, v191 row_ror:2 row_mask:0xf bank_mask:0xf bound_ctrl:1
	v_pk_mul_f32 v[90:91], v[90:91], v[132:133] op_sel:[0,1] op_sel_hi:[1,1]
	v_pk_mul_f32 v[92:93], v[92:93], v[132:133] op_sel:[0,1] op_sel_hi:[1,1]
	v_add_f32_dpp v191, v191, v191 row_ror:1 row_mask:0xf bank_mask:0xf bound_ctrl:1
	v_pk_mul_f32 v[94:95], v[94:95], v[132:133] op_sel:[0,1] op_sel_hi:[1,1]
	v_pk_fma_f32 v[196:197], v[132:133], v[196:197], v[80:81] op_sel_hi:[0,1,1]
	ds_write_b32 v189, v191 offset:34368
	v_pk_fma_f32 v[198:199], v[132:133], v[198:199], v[82:83] op_sel_hi:[0,1,1]
	v_pk_fma_f32 v[200:201], v[132:133], v[200:201], v[84:85] op_sel_hi:[0,1,1]
	v_pk_fma_f32 v[202:203], v[132:133], v[202:203], v[86:87] op_sel_hi:[0,1,1]
	v_pk_fma_f32 v[204:205], v[132:133], v[204:205], v[88:89] op_sel_hi:[0,1,1]
	v_pk_fma_f32 v[206:207], v[132:133], v[206:207], v[90:91] op_sel_hi:[0,1,1]
	v_pk_fma_f32 v[208:209], v[132:133], v[208:209], v[92:93] op_sel_hi:[0,1,1]
	v_pk_fma_f32 v[210:211], v[132:133], v[210:211], v[94:95] op_sel_hi:[0,1,1]
	s_waitcnt lgkmcnt(15)
	v_pk_fma_f32 v[128:129], v[64:65], v[196:197], v[192:193]
	v_pk_fma_f32 v[130:131], v[66:67], v[198:199], v[192:193]
	v_pk_fma_f32 v[128:129], v[68:69], v[200:201], v[128:129]
	v_pk_fma_f32 v[130:131], v[70:71], v[202:203], v[130:131]
	s_waitcnt lgkmcnt(14)
	v_pk_fma_f32 v[128:129], v[72:73], v[204:205], v[128:129]
	v_pk_fma_f32 v[130:131], v[74:75], v[206:207], v[130:131]
	s_waitcnt lgkmcnt(13)
	v_pk_fma_f32 v[128:129], v[76:77], v[208:209], v[128:129]
	v_pk_fma_f32 v[130:131], v[78:79], v[210:211], v[130:131]
	v_add_f32_e32 v128, v128, v129
	v_add_f32_e32 v130, v130, v131
	v_add_f32_e32 v190, v128, v130
	s_waitcnt lgkmcnt(6)
	v_mul_f32_e32 v153, v154, v155
	v_pk_mul_f32 v[112:113], v[112:113], v[152:153] op_sel:[0,1] op_sel_hi:[1,1]
	v_add_f32_dpp v190, v190, v190 row_ror:8 row_mask:0xf bank_mask:0xf bound_ctrl:1
	v_pk_mul_f32 v[114:115], v[114:115], v[152:153] op_sel:[0,1] op_sel_hi:[1,1]
	v_pk_mul_f32 v[116:117], v[116:117], v[152:153] op_sel:[0,1] op_sel_hi:[1,1]
	v_add_f32_dpp v190, v190, v190 row_ror:4 row_mask:0xf bank_mask:0xf bound_ctrl:1
	v_pk_mul_f32 v[118:119], v[118:119], v[152:153] op_sel:[0,1] op_sel_hi:[1,1]
	v_pk_mul_f32 v[120:121], v[120:121], v[152:153] op_sel:[0,1] op_sel_hi:[1,1]
	v_add_f32_dpp v190, v190, v190 row_ror:2 row_mask:0xf bank_mask:0xf bound_ctrl:1
	v_pk_mul_f32 v[122:123], v[122:123], v[152:153] op_sel:[0,1] op_sel_hi:[1,1]
	v_pk_mul_f32 v[124:125], v[124:125], v[152:153] op_sel:[0,1] op_sel_hi:[1,1]
	v_add_f32_dpp v190, v190, v190 row_ror:1 row_mask:0xf bank_mask:0xf bound_ctrl:1
	v_pk_mul_f32 v[126:127], v[126:127], v[152:153] op_sel:[0,1] op_sel_hi:[1,1]
	s_waitcnt lgkmcnt(5)
	v_pk_fma_f32 v[196:197], v[152:153], v[196:197], v[112:113] op_sel_hi:[0,1,1]
	ds_write_b32 v189, v190 offset:34432
	v_pk_fma_f32 v[198:199], v[152:153], v[198:199], v[114:115] op_sel_hi:[0,1,1]
	v_pk_fma_f32 v[200:201], v[152:153], v[200:201], v[116:117] op_sel_hi:[0,1,1]
	v_pk_fma_f32 v[202:203], v[152:153], v[202:203], v[118:119] op_sel_hi:[0,1,1]
	v_pk_fma_f32 v[204:205], v[152:153], v[204:205], v[120:121] op_sel_hi:[0,1,1]
	v_pk_fma_f32 v[206:207], v[152:153], v[206:207], v[122:123] op_sel_hi:[0,1,1]
	v_pk_fma_f32 v[208:209], v[152:153], v[208:209], v[124:125] op_sel_hi:[0,1,1]
	v_pk_fma_f32 v[210:211], v[152:153], v[210:211], v[126:127] op_sel_hi:[0,1,1]
	s_waitcnt lgkmcnt(5)
	v_pk_fma_f32 v[128:129], v[96:97], v[196:197], v[192:193]
	v_pk_fma_f32 v[130:131], v[98:99], v[198:199], v[192:193]
	s_waitcnt lgkmcnt(4)
	v_pk_fma_f32 v[128:129], v[100:101], v[200:201], v[128:129]
	v_pk_fma_f32 v[130:131], v[102:103], v[202:203], v[130:131]
	s_waitcnt lgkmcnt(3)
	v_pk_fma_f32 v[128:129], v[104:105], v[204:205], v[128:129]
	v_pk_fma_f32 v[130:131], v[106:107], v[206:207], v[130:131]
	s_waitcnt lgkmcnt(2)
	v_pk_fma_f32 v[128:129], v[108:109], v[208:209], v[128:129]
	v_pk_fma_f32 v[130:131], v[110:111], v[210:211], v[130:131]
	v_add_f32_e32 v128, v128, v129
	v_add_f32_e32 v130, v130, v131
	v_add_f32_e32 v191, v128, v130
	s_nop 1
	v_add_f32_dpp v191, v191, v191 row_ror:8 row_mask:0xf bank_mask:0xf bound_ctrl:1
	s_nop 1
	v_add_f32_dpp v191, v191, v191 row_ror:4 row_mask:0xf bank_mask:0xf bound_ctrl:1
	s_nop 1
	v_add_f32_dpp v191, v191, v191 row_ror:2 row_mask:0xf bank_mask:0xf bound_ctrl:1
	s_nop 1
	v_add_f32_dpp v191, v191, v191 row_ror:1 row_mask:0xf bank_mask:0xf bound_ctrl:1
	ds_write_b32 v189, v191 offset:34496
	s_waitcnt vmcnt(11)
	ds_write_b128 v185, v[16:19] offset:17024
	s_waitcnt vmcnt(9)
	ds_write_b128 v186, v[24:27] offset:17024
	ds_write_b128 v185, v[20:23] offset:25216
	s_waitcnt vmcnt(8)
	ds_write_b128 v186, v[28:31] offset:25216
	s_and_saveexec_b64 s[8:9], s[42:43]
	ds_write_b32 v144, v184 offset:33408
	s_or_b64 exec, exec, s[8:9]
	s_and_saveexec_b64 s[8:9], s[40:41]
	s_cbranch_execz .LBB0_1474
	v_add_f32_e32 v64, v156, v157
	v_mul_f32_e64 v65, |v64|, s62
	v_exp_f32_e32 v65, v65
	v_min_f32_e32 v64, 0, v64
	v_add_f32_e32 v65, 1.0, v65
	v_cmp_gt_f32_e32 vcc, s5, v65
	s_nop 1
	v_cndmask_b32_e64 v66, 0, 32, vcc
	v_ldexp_f32 v65, v65, v66
	v_log_f32_e32 v65, v65
	v_cndmask_b32_e32 v67, 0, v171, vcc
	v_add_f32_e32 v66, v145, v179
	v_mul_f32_e32 v68, 0x3f317217, v65
	v_fma_f32 v68, v65, s76, -v68
	v_fmac_f32_e32 v68, 0x3377d1cf, v65
	v_fmac_f32_e32 v68, 0x3f317217, v65
	v_cmp_lt_f32_e64 vcc, |v65|, s77
	s_nop 1
	v_cndmask_b32_e32 v65, v65, v68, vcc
	v_sub_f32_e32 v65, v65, v67
	v_sub_f32_e32 v64, v64, v65
	v_add_u32_e32 v65, 0x8400, v144
	ds_write2_b32 v65, v66, v64 offset0:32 offset1:48

.LBB0_1485:
	s_or_b64 exec, exec, s[8:9]
	s_waitcnt lgkmcnt(0)
	s_barrier
	v_mov_b32_e32 v192, 0
	v_mov_b32_e32 v193, 0
	ds_read_b128 v[80:83], v188 offset:25216
	ds_read_b128 v[84:87], v188 offset:25472
	ds_read_b128 v[88:91], v188 offset:25728
	ds_read_b128 v[92:95], v188 offset:25984
	ds_read_b32 v134, v140 offset:35136
	ds_read_b32 v135, v189 offset:33408
	ds_read_b32 v132, v140 offset:35072
	ds_read_b128 v[64:67], v188 offset:17024
	ds_read_b128 v[68:71], v188 offset:17280
	ds_read_b128 v[72:75], v188 offset:17536
	ds_read_b128 v[76:79], v188 offset:17792
	ds_read_b128 v[112:115], v188 offset:26240
	ds_read_b128 v[116:119], v188 offset:26496
	ds_read_b128 v[120:123], v188 offset:26752
	ds_read_b128 v[124:127], v188 offset:27008
	ds_read_b32 v154, v140 offset:35140
	ds_read_b32 v155, v189 offset:33472
	ds_read_b32 v152, v140 offset:35076
	ds_read_b128 v[96:99], v188 offset:18048
	ds_read_b128 v[100:103], v188 offset:18304
	ds_read_b128 v[104:107], v188 offset:18560
	ds_read_b128 v[108:111], v188 offset:18816
	s_waitcnt lgkmcnt(15)
	v_mul_f32_e32 v133, v134, v135
	v_pk_mul_f32 v[80:81], v[80:81], v[132:133] op_sel:[0,1] op_sel_hi:[1,1]
	v_pk_mul_f32 v[82:83], v[82:83], v[132:133] op_sel:[0,1] op_sel_hi:[1,1]
	v_pk_mul_f32 v[84:85], v[84:85], v[132:133] op_sel:[0,1] op_sel_hi:[1,1]
	v_pk_mul_f32 v[86:87], v[86:87], v[132:133] op_sel:[0,1] op_sel_hi:[1,1]
	v_pk_mul_f32 v[88:89], v[88:89], v[132:133] op_sel:[0,1] op_sel_hi:[1,1]
	v_pk_mul_f32 v[90:91], v[90:91], v[132:133] op_sel:[0,1] op_sel_hi:[1,1]
	v_pk_mul_f32 v[92:93], v[92:93], v[132:133] op_sel:[0,1] op_sel_hi:[1,1]
	v_pk_mul_f32 v[94:95], v[94:95], v[132:133] op_sel:[0,1] op_sel_hi:[1,1]
	v_pk_fma_f32 v[196:197], v[132:133], v[196:197], v[80:81] op_sel_hi:[0,1,1]
	v_pk_fma_f32 v[198:199], v[132:133], v[198:199], v[82:83] op_sel_hi:[0,1,1]
	v_pk_fma_f32 v[200:201], v[132:133], v[200:201], v[84:85] op_sel_hi:[0,1,1]
	v_pk_fma_f32 v[202:203], v[132:133], v[202:203], v[86:87] op_sel_hi:[0,1,1]
	v_pk_fma_f32 v[204:205], v[132:133], v[204:205], v[88:89] op_sel_hi:[0,1,1]
	v_pk_fma_f32 v[206:207], v[132:133], v[206:207], v[90:91] op_sel_hi:[0,1,1]
	v_pk_fma_f32 v[208:209], v[132:133], v[208:209], v[92:93] op_sel_hi:[0,1,1]
	v_pk_fma_f32 v[210:211], v[132:133], v[210:211], v[94:95] op_sel_hi:[0,1,1]
	s_waitcnt lgkmcnt(14)
	v_pk_fma_f32 v[128:129], v[64:65], v[196:197], v[192:193]
	v_pk_fma_f32 v[130:131], v[66:67], v[198:199], v[192:193]
	s_waitcnt lgkmcnt(13)
	v_pk_fma_f32 v[128:129], v[68:69], v[200:201], v[128:129]
	v_pk_fma_f32 v[130:131], v[70:71], v[202:203], v[130:131]
	s_waitcnt lgkmcnt(12)
	v_pk_fma_f32 v[128:129], v[72:73], v[204:205], v[128:129]
	v_pk_fma_f32 v[130:131], v[74:75], v[206:207], v[130:131]
	s_waitcnt lgkmcnt(11)
	v_pk_fma_f32 v[128:129], v[76:77], v[208:209], v[128:129]
	v_pk_fma_f32 v[130:131], v[78:79], v[210:211], v[130:131]
	v_add_f32_e32 v128, v128, v129
	v_add_f32_e32 v130, v130, v131
	v_add_f32_e32 v190, v128, v130
	ds_read_b128 v[80:83], v188 offset:27264
	ds_read_b128 v[84:87], v188 offset:27520
	ds_read_b128 v[88:91], v188 offset:27776
	ds_read_b128 v[92:95], v188 offset:28032
	ds_read_b32 v134, v140 offset:35144
	ds_read_b32 v135, v189 offset:33536
	ds_read_b32 v132, v140 offset:35080
	ds_read_b128 v[64:67], v188 offset:19072
	ds_read_b128 v[68:71], v188 offset:19328
	ds_read_b128 v[72:75], v188 offset:19584
	ds_read_b128 v[76:79], v188 offset:19840
	s_waitcnt lgkmcnt(15)
	v_mul_f32_e32 v153, v154, v155
	v_pk_mul_f32 v[112:113], v[112:113], v[152:153] op_sel:[0,1] op_sel_hi:[1,1]
	v_add_f32_dpp v190, v190, v190 row_ror:8 row_mask:0xf bank_mask:0xf bound_ctrl:1
	v_pk_mul_f32 v[114:115], v[114:115], v[152:153] op_sel:[0,1] op_sel_hi:[1,1]
	v_pk_mul_f32 v[116:117], v[116:117], v[152:153] op_sel:[0,1] op_sel_hi:[1,1]
	v_add_f32_dpp v190, v190, v190 row_ror:4 row_mask:0xf bank_mask:0xf bound_ctrl:1
	v_pk_mul_f32 v[118:119], v[118:119], v[152:153] op_sel:[0,1] op_sel_hi:[1,1]
	v_pk_mul_f32 v[120:121], v[120:121], v[152:153] op_sel:[0,1] op_sel_hi:[1,1]
	v_add_f32_dpp v190, v190, v190 row_ror:2 row_mask:0xf bank_mask:0xf bound_ctrl:1
	v_pk_mul_f32 v[122:123], v[122:123], v[152:153] op_sel:[0,1] op_sel_hi:[1,1]
	v_pk_mul_f32 v[124:125], v[124:125], v[152:153] op_sel:[0,1] op_sel_hi:[1,1]
	v_add_f32_dpp v190, v190, v190 row_ror:1 row_mask:0xf bank_mask:0xf bound_ctrl:1
	v_pk_mul_f32 v[126:127], v[126:127], v[152:153] op_sel:[0,1] op_sel_hi:[1,1]
	v_pk_fma_f32 v[196:197], v[152:153], v[196:197], v[112:113] op_sel_hi:[0,1,1]
	ds_write_b32 v189, v190 offset:34560
	v_pk_fma_f32 v[198:199], v[152:153], v[198:199], v[114:115] op_sel_hi:[0,1,1]
	v_pk_fma_f32 v[200:201], v[152:153], v[200:201], v[116:117] op_sel_hi:[0,1,1]
	v_pk_fma_f32 v[202:203], v[152:153], v[202:203], v[118:119] op_sel_hi:[0,1,1]
	v_pk_fma_f32 v[204:205], v[152:153], v[204:205], v[120:121] op_sel_hi:[0,1,1]
	v_pk_fma_f32 v[206:207], v[152:153], v[206:207], v[122:123] op_sel_hi:[0,1,1]
	v_pk_fma_f32 v[208:209], v[152:153], v[208:209], v[124:125] op_sel_hi:[0,1,1]
	v_pk_fma_f32 v[210:211], v[152:153], v[210:211], v[126:127] op_sel_hi:[0,1,1]
	s_waitcnt lgkmcnt(15)
	v_pk_fma_f32 v[128:129], v[96:97], v[196:197], v[192:193]
	v_pk_fma_f32 v[130:131], v[98:99], v[198:199], v[192:193]
	s_waitcnt lgkmcnt(14)
	v_pk_fma_f32 v[128:129], v[100:101], v[200:201], v[128:129]
	v_pk_fma_f32 v[130:131], v[102:103], v[202:203], v[130:131]
	s_waitcnt lgkmcnt(13)
	v_pk_fma_f32 v[128:129], v[104:105], v[204:205], v[128:129]
	v_pk_fma_f32 v[130:131], v[106:107], v[206:207], v[130:131]
	s_waitcnt lgkmcnt(12)
	v_pk_fma_f32 v[128:129], v[108:109], v[208:209], v[128:129]
	v_pk_fma_f32 v[130:131], v[110:111], v[210:211], v[130:131]
	v_add_f32_e32 v128, v128, v129
	v_add_f32_e32 v130, v130, v131
	v_add_f32_e32 v191, v128, v130
	ds_read_b128 v[112:115], v188 offset:28288
	ds_read_b128 v[116:119], v188 offset:28544
	ds_read_b128 v[120:123], v188 offset:28800
	ds_read_b128 v[124:127], v188 offset:29056
	ds_read_b32 v154, v140 offset:35148
	ds_read_b32 v155, v189 offset:33600
	ds_read_b32 v152, v140 offset:35084
	ds_read_b128 v[96:99], v188 offset:20096
	ds_read_b128 v[100:103], v188 offset:20352
	ds_read_b128 v[104:107], v188 offset:20608
	ds_read_b128 v[108:111], v188 offset:20864
	s_waitcnt lgkmcnt(15)
	v_mul_f32_e32 v133, v134, v135
	v_pk_mul_f32 v[80:81], v[80:81], v[132:133] op_sel:[0,1] op_sel_hi:[1,1]
	v_add_f32_dpp v191, v191, v191 row_ror:8 row_mask:0xf bank_mask:0xf bound_ctrl:1
	v_pk_mul_f32 v[82:83], v[82:83], v[132:133] op_sel:[0,1] op_sel_hi:[1,1]
	v_pk_mul_f32 v[84:85], v[84:85], v[132:133] op_sel:[0,1] op_sel_hi:[1,1]
	v_add_f32_dpp v191, v191, v191 row_ror:4 row_mask:0xf bank_mask:0xf bound_ctrl:1
	v_pk_mul_f32 v[86:87], v[86:87], v[132:133] op_sel:[0,1] op_sel_hi:[1,1]
	v_pk_mul_f32 v[88:89], v[88:89], v[132:133] op_sel:[0,1] op_sel_hi:[1,1]
	v_add_f32_dpp v191, v191, v191 row_ror:2 row_mask:0xf bank_mask:0xf bound_ctrl:1
	v_pk_mul_f32 v[90:91], v[90:91], v[132:133] op_sel:[0,1] op_sel_hi:[1,1]
	v_pk_mul_f32 v[92:93], v[92:93], v[132:133] op_sel:[0,1] op_sel_hi:[1,1]
	v_add_f32_dpp v191, v191, v191 row_ror:1 row_mask:0xf bank_mask:0xf bound_ctrl:1
	v_pk_mul_f32 v[94:95], v[94:95], v[132:133] op_sel:[0,1] op_sel_hi:[1,1]
	v_pk_fma_f32 v[196:197], v[132:133], v[196:197], v[80:81] op_sel_hi:[0,1,1]
	ds_write_b32 v189, v191 offset:34624
	v_pk_fma_f32 v[198:199], v[132:133], v[198:199], v[82:83] op_sel_hi:[0,1,1]
	v_pk_fma_f32 v[200:201], v[132:133], v[200:201], v[84:85] op_sel_hi:[0,1,1]
	v_pk_fma_f32 v[202:203], v[132:133], v[202:203], v[86:87] op_sel_hi:[0,1,1]
	v_pk_fma_f32 v[204:205], v[132:133], v[204:205], v[88:89] op_sel_hi:[0,1,1]
	v_pk_fma_f32 v[206:207], v[132:133], v[206:207], v[90:91] op_sel_hi:[0,1,1]
	v_pk_fma_f32 v[208:209], v[132:133], v[208:209], v[92:93] op_sel_hi:[0,1,1]
	v_pk_fma_f32 v[210:211], v[132:133], v[210:211], v[94:95] op_sel_hi:[0,1,1]
	s_waitcnt lgkmcnt(15)
	v_pk_fma_f32 v[128:129], v[64:65], v[196:197], v[192:193]
	v_pk_fma_f32 v[130:131], v[66:67], v[198:199], v[192:193]
	v_pk_fma_f32 v[128:129], v[68:69], v[200:201], v[128:129]
	v_pk_fma_f32 v[130:131], v[70:71], v[202:203], v[130:131]
	s_waitcnt lgkmcnt(14)
	v_pk_fma_f32 v[128:129], v[72:73], v[204:205], v[128:129]
	v_pk_fma_f32 v[130:131], v[74:75], v[206:207], v[130:131]
	s_waitcnt lgkmcnt(13)
	v_pk_fma_f32 v[128:129], v[76:77], v[208:209], v[128:129]
	v_pk_fma_f32 v[130:131], v[78:79], v[210:211], v[130:131]
	v_add_f32_e32 v128, v128, v129
	v_add_f32_e32 v130, v130, v131
	v_add_f32_e32 v190, v128, v130
	ds_read_b128 v[80:83], v188 offset:29312
	ds_read_b128 v[84:87], v188 offset:29568
	ds_read_b128 v[88:91], v188 offset:29824
	ds_read_b128 v[92:95], v188 offset:30080
	ds_read_b32 v134, v140 offset:35152
	ds_read_b32 v135, v189 offset:33664
	ds_read_b32 v132, v140 offset:35088
	ds_read_b128 v[64:67], v188 offset:21120
	ds_read_b128 v[68:71], v188 offset:21376
	ds_read_b128 v[72:75], v188 offset:21632
	ds_read_b128 v[76:79], v188 offset:21888
	s_waitcnt lgkmcnt(15)
	v_mul_f32_e32 v153, v154, v155
	v_pk_mul_f32 v[112:113], v[112:113], v[152:153] op_sel:[0,1] op_sel_hi:[1,1]
	v_add_f32_dpp v190, v190, v190 row_ror:8 row_mask:0xf bank_mask:0xf bound_ctrl:1
	v_pk_mul_f32 v[114:115], v[114:115], v[152:153] op_sel:[0,1] op_sel_hi:[1,1]
	v_pk_mul_f32 v[116:117], v[116:117], v[152:153] op_sel:[0,1] op_sel_hi:[1,1]
	v_add_f32_dpp v190, v190, v190 row_ror:4 row_mask:0xf bank_mask:0xf bound_ctrl:1
	v_pk_mul_f32 v[118:119], v[118:119], v[152:153] op_sel:[0,1] op_sel_hi:[1,1]
	v_pk_mul_f32 v[120:121], v[120:121], v[152:153] op_sel:[0,1] op_sel_hi:[1,1]
	v_add_f32_dpp v190, v190, v190 row_ror:2 row_mask:0xf bank_mask:0xf bound_ctrl:1
	v_pk_mul_f32 v[122:123], v[122:123], v[152:153] op_sel:[0,1] op_sel_hi:[1,1]
	v_pk_mul_f32 v[124:125], v[124:125], v[152:153] op_sel:[0,1] op_sel_hi:[1,1]
	v_add_f32_dpp v190, v190, v190 row_ror:1 row_mask:0xf bank_mask:0xf bound_ctrl:1
	v_pk_mul_f32 v[126:127], v[126:127], v[152:153] op_sel:[0,1] op_sel_hi:[1,1]
	v_pk_fma_f32 v[196:197], v[152:153], v[196:197], v[112:113] op_sel_hi:[0,1,1]
	ds_write_b32 v189, v190 offset:34688
	v_pk_fma_f32 v[198:199], v[152:153], v[198:199], v[114:115] op_sel_hi:[0,1,1]
	v_pk_fma_f32 v[200:201], v[152:153], v[200:201], v[116:117] op_sel_hi:[0,1,1]
	v_pk_fma_f32 v[202:203], v[152:153], v[202:203], v[118:119] op_sel_hi:[0,1,1]
	v_pk_fma_f32 v[204:205], v[152:153], v[204:205], v[120:121] op_sel_hi:[0,1,1]
	v_pk_fma_f32 v[206:207], v[152:153], v[206:207], v[122:123] op_sel_hi:[0,1,1]
	v_pk_fma_f32 v[208:209], v[152:153], v[208:209], v[124:125] op_sel_hi:[0,1,1]
	v_pk_fma_f32 v[210:211], v[152:153], v[210:211], v[126:127] op_sel_hi:[0,1,1]
	s_waitcnt lgkmcnt(15)
	v_pk_fma_f32 v[128:129], v[96:97], v[196:197], v[192:193]
	v_pk_fma_f32 v[130:131], v[98:99], v[198:199], v[192:193]
	v_pk_fma_f32 v[128:129], v[100:101], v[200:201], v[128:129]
	v_pk_fma_f32 v[130:131], v[102:103], v[202:203], v[130:131]
	s_waitcnt lgkmcnt(14)
	v_pk_fma_f32 v[128:129], v[104:105], v[204:205], v[128:129]
	v_pk_fma_f32 v[130:131], v[106:107], v[206:207], v[130:131]
	s_waitcnt lgkmcnt(13)
	v_pk_fma_f32 v[128:129], v[108:109], v[208:209], v[128:129]
	v_pk_fma_f32 v[130:131], v[110:111], v[210:211], v[130:131]
	v_add_f32_e32 v128, v128, v129
	v_add_f32_e32 v130, v130, v131
	v_add_f32_e32 v191, v128, v130
	ds_read_b128 v[112:115], v188 offset:30336
	ds_read_b128 v[116:119], v188 offset:30592
	ds_read_b128 v[120:123], v188 offset:30848
	ds_read_b128 v[124:127], v188 offset:31104
	ds_read_b32 v154, v140 offset:35156
	ds_read_b32 v155, v189 offset:33728
	ds_read_b32 v152, v140 offset:35092
	ds_read_b128 v[96:99], v188 offset:22144
	ds_read_b128 v[100:103], v188 offset:22400
	ds_read_b128 v[104:107], v188 offset:22656
	ds_read_b128 v[108:111], v188 offset:22912
	s_waitcnt lgkmcnt(15)
	v_mul_f32_e32 v133, v134, v135
	v_pk_mul_f32 v[80:81], v[80:81], v[132:133] op_sel:[0,1] op_sel_hi:[1,1]
	v_add_f32_dpp v191, v191, v191 row_ror:8 row_mask:0xf bank_mask:0xf bound_ctrl:1
	v_pk_mul_f32 v[82:83], v[82:83], v[132:133] op_sel:[0,1] op_sel_hi:[1,1]
	v_pk_mul_f32 v[84:85], v[84:85], v[132:133] op_sel:[0,1] op_sel_hi:[1,1]
	v_add_f32_dpp v191, v191, v191 row_ror:4 row_mask:0xf bank_mask:0xf bound_ctrl:1
	v_pk_mul_f32 v[86:87], v[86:87], v[132:133] op_sel:[0,1] op_sel_hi:[1,1]
	v_pk_mul_f32 v[88:89], v[88:89], v[132:133] op_sel:[0,1] op_sel_hi:[1,1]
	v_add_f32_dpp v191, v191, v191 row_ror:2 row_mask:0xf bank_mask:0xf bound_ctrl:1
	v_pk_mul_f32 v[90:91], v[90:91], v[132:133] op_sel:[0,1] op_sel_hi:[1,1]
	v_pk_mul_f32 v[92:93], v[92:93], v[132:133] op_sel:[0,1] op_sel_hi:[1,1]
	v_add_f32_dpp v191, v191, v191 row_ror:1 row_mask:0xf bank_mask:0xf bound_ctrl:1
	v_pk_mul_f32 v[94:95], v[94:95], v[132:133] op_sel:[0,1] op_sel_hi:[1,1]
	v_pk_fma_f32 v[196:197], v[132:133], v[196:197], v[80:81] op_sel_hi:[0,1,1]
	ds_write_b32 v189, v191 offset:34752
	v_pk_fma_f32 v[198:199], v[132:133], v[198:199], v[82:83] op_sel_hi:[0,1,1]
	v_pk_fma_f32 v[200:201], v[132:133], v[200:201], v[84:85] op_sel_hi:[0,1,1]
	v_pk_fma_f32 v[202:203], v[132:133], v[202:203], v[86:87] op_sel_hi:[0,1,1]
	v_pk_fma_f32 v[204:205], v[132:133], v[204:205], v[88:89] op_sel_hi:[0,1,1]
	v_pk_fma_f32 v[206:207], v[132:133], v[206:207], v[90:91] op_sel_hi:[0,1,1]
	v_pk_fma_f32 v[208:209], v[132:133], v[208:209], v[92:93] op_sel_hi:[0,1,1]
	v_pk_fma_f32 v[210:211], v[132:133], v[210:211], v[94:95] op_sel_hi:[0,1,1]
	s_waitcnt lgkmcnt(15)
	v_pk_fma_f32 v[128:129], v[64:65], v[196:197], v[192:193]
	v_pk_fma_f32 v[130:131], v[66:67], v[198:199], v[192:193]
	v_pk_fma_f32 v[128:129], v[68:69], v[200:201], v[128:129]
	v_pk_fma_f32 v[130:131], v[70:71], v[202:203], v[130:131]
	s_waitcnt lgkmcnt(14)
	v_pk_fma_f32 v[128:129], v[72:73], v[204:205], v[128:129]
	v_pk_fma_f32 v[130:131], v[74:75], v[206:207], v[130:131]
	s_waitcnt lgkmcnt(13)
	v_pk_fma_f32 v[128:129], v[76:77], v[208:209], v[128:129]
	v_pk_fma_f32 v[130:131], v[78:79], v[210:211], v[130:131]
	v_add_f32_e32 v128, v128, v129
	v_add_f32_e32 v130, v130, v131
	v_add_f32_e32 v190, v128, v130
	ds_read_b128 v[80:83], v188 offset:31360
	ds_read_b128 v[84:87], v188 offset:31616
	ds_read_b128 v[88:91], v188 offset:31872
	ds_read_b128 v[92:95], v188 offset:32128
	ds_read_b32 v134, v140 offset:35160
	ds_read_b32 v135, v189 offset:33792
	ds_read_b32 v132, v140 offset:35096
	ds_read_b128 v[64:67], v188 offset:23168
	ds_read_b128 v[68:71], v188 offset:23424
	ds_read_b128 v[72:75], v188 offset:23680
	ds_read_b128 v[76:79], v188 offset:23936
	s_waitcnt lgkmcnt(15)
	v_mul_f32_e32 v153, v154, v155
	v_pk_mul_f32 v[112:113], v[112:113], v[152:153] op_sel:[0,1] op_sel_hi:[1,1]
	v_add_f32_dpp v190, v190, v190 row_ror:8 row_mask:0xf bank_mask:0xf bound_ctrl:1
	v_pk_mul_f32 v[114:115], v[114:115], v[152:153] op_sel:[0,1] op_sel_hi:[1,1]
	v_pk_mul_f32 v[116:117], v[116:117], v[152:153] op_sel:[0,1] op_sel_hi:[1,1]
	v_add_f32_dpp v190, v190, v190 row_ror:4 row_mask:0xf bank_mask:0xf bound_ctrl:1
	v_pk_mul_f32 v[118:119], v[118:119], v[152:153] op_sel:[0,1] op_sel_hi:[1,1]
	v_pk_mul_f32 v[120:121], v[120:121], v[152:153] op_sel:[0,1] op_sel_hi:[1,1]
	v_add_f32_dpp v190, v190, v190 row_ror:2 row_mask:0xf bank_mask:0xf bound_ctrl:1
	v_pk_mul_f32 v[122:123], v[122:123], v[152:153] op_sel:[0,1] op_sel_hi:[1,1]
	v_pk_mul_f32 v[124:125], v[124:125], v[152:153] op_sel:[0,1] op_sel_hi:[1,1]
	v_add_f32_dpp v190, v190, v190 row_ror:1 row_mask:0xf bank_mask:0xf bound_ctrl:1
	v_pk_mul_f32 v[126:127], v[126:127], v[152:153] op_sel:[0,1] op_sel_hi:[1,1]
	v_pk_fma_f32 v[196:197], v[152:153], v[196:197], v[112:113] op_sel_hi:[0,1,1]
	ds_write_b32 v189, v190 offset:34816
	v_pk_fma_f32 v[198:199], v[152:153], v[198:199], v[114:115] op_sel_hi:[0,1,1]
	v_pk_fma_f32 v[200:201], v[152:153], v[200:201], v[116:117] op_sel_hi:[0,1,1]
	v_pk_fma_f32 v[202:203], v[152:153], v[202:203], v[118:119] op_sel_hi:[0,1,1]
	v_pk_fma_f32 v[204:205], v[152:153], v[204:205], v[120:121] op_sel_hi:[0,1,1]
	v_pk_fma_f32 v[206:207], v[152:153], v[206:207], v[122:123] op_sel_hi:[0,1,1]
	v_pk_fma_f32 v[208:209], v[152:153], v[208:209], v[124:125] op_sel_hi:[0,1,1]
	v_pk_fma_f32 v[210:211], v[152:153], v[210:211], v[126:127] op_sel_hi:[0,1,1]
	s_waitcnt lgkmcnt(15)
	v_pk_fma_f32 v[128:129], v[96:97], v[196:197], v[192:193]
	v_pk_fma_f32 v[130:131], v[98:99], v[198:199], v[192:193]
	v_pk_fma_f32 v[128:129], v[100:101], v[200:201], v[128:129]
	v_pk_fma_f32 v[130:131], v[102:103], v[202:203], v[130:131]
	s_waitcnt lgkmcnt(14)
	v_pk_fma_f32 v[128:129], v[104:105], v[204:205], v[128:129]
	v_pk_fma_f32 v[130:131], v[106:107], v[206:207], v[130:131]
	s_waitcnt lgkmcnt(13)
	v_pk_fma_f32 v[128:129], v[108:109], v[208:209], v[128:129]
	v_pk_fma_f32 v[130:131], v[110:111], v[210:211], v[130:131]
	v_add_f32_e32 v128, v128, v129
	v_add_f32_e32 v130, v130, v131
	v_add_f32_e32 v191, v128, v130
	ds_read_b128 v[112:115], v188 offset:32384
	ds_read_b128 v[116:119], v188 offset:32640
	ds_read_b128 v[120:123], v188 offset:32896
	ds_read_b128 v[124:127], v188 offset:33152
	ds_read_b32 v154, v140 offset:35164
	ds_read_b32 v155, v189 offset:33856
	ds_read_b32 v152, v140 offset:35100
	ds_read_b128 v[96:99], v188 offset:24192
	ds_read_b128 v[100:103], v188 offset:24448
	ds_read_b128 v[104:107], v188 offset:24704
	ds_read_b128 v[108:111], v188 offset:24960
	s_waitcnt lgkmcnt(15)
	v_mul_f32_e32 v133, v134, v135
	v_pk_mul_f32 v[80:81], v[80:81], v[132:133] op_sel:[0,1] op_sel_hi:[1,1]
	v_add_f32_dpp v191, v191, v191 row_ror:8 row_mask:0xf bank_mask:0xf bound_ctrl:1
	v_pk_mul_f32 v[82:83], v[82:83], v[132:133] op_sel:[0,1] op_sel_hi:[1,1]
	v_pk_mul_f32 v[84:85], v[84:85], v[132:133] op_sel:[0,1] op_sel_hi:[1,1]
	v_add_f32_dpp v191, v191, v191 row_ror:4 row_mask:0xf bank_mask:0xf bound_ctrl:1
	v_pk_mul_f32 v[86:87], v[86:87], v[132:133] op_sel:[0,1] op_sel_hi:[1,1]
	v_pk_mul_f32 v[88:89], v[88:89], v[132:133] op_sel:[0,1] op_sel_hi:[1,1]
	v_add_f32_dpp v191, v191, v191 row_ror:2 row_mask:0xf bank_mask:0xf bound_ctrl:1
	v_pk_mul_f32 v[90:91], v[90:91], v[132:133] op_sel:[0,1] op_sel_hi:[1,1]
	v_pk_mul_f32 v[92:93], v[92:93], v[132:133] op_sel:[0,1] op_sel_hi:[1,1]
	v_add_f32_dpp v191, v191, v191 row_ror:1 row_mask:0xf bank_mask:0xf bound_ctrl:1
	v_pk_mul_f32 v[94:95], v[94:95], v[132:133] op_sel:[0,1] op_sel_hi:[1,1]
	v_pk_fma_f32 v[196:197], v[132:133], v[196:197], v[80:81] op_sel_hi:[0,1,1]
	ds_write_b32 v189, v191 offset:34880
	v_pk_fma_f32 v[198:199], v[132:133], v[198:199], v[82:83] op_sel_hi:[0,1,1]
	v_pk_fma_f32 v[200:201], v[132:133], v[200:201], v[84:85] op_sel_hi:[0,1,1]
	v_pk_fma_f32 v[202:203], v[132:133], v[202:203], v[86:87] op_sel_hi:[0,1,1]
	v_pk_fma_f32 v[204:205], v[132:133], v[204:205], v[88:89] op_sel_hi:[0,1,1]
	v_pk_fma_f32 v[206:207], v[132:133], v[206:207], v[90:91] op_sel_hi:[0,1,1]
	v_pk_fma_f32 v[208:209], v[132:133], v[208:209], v[92:93] op_sel_hi:[0,1,1]
	v_pk_fma_f32 v[210:211], v[132:133], v[210:211], v[94:95] op_sel_hi:[0,1,1]
	s_waitcnt lgkmcnt(15)
	v_pk_fma_f32 v[128:129], v[64:65], v[196:197], v[192:193]
	v_pk_fma_f32 v[130:131], v[66:67], v[198:199], v[192:193]
	v_pk_fma_f32 v[128:129], v[68:69], v[200:201], v[128:129]
	v_pk_fma_f32 v[130:131], v[70:71], v[202:203], v[130:131]
	s_waitcnt lgkmcnt(14)
	v_pk_fma_f32 v[128:129], v[72:73], v[204:205], v[128:129]
	v_pk_fma_f32 v[130:131], v[74:75], v[206:207], v[130:131]
	s_waitcnt lgkmcnt(13)
	v_pk_fma_f32 v[128:129], v[76:77], v[208:209], v[128:129]
	v_pk_fma_f32 v[130:131], v[78:79], v[210:211], v[130:131]
	v_add_f32_e32 v128, v128, v129
	v_add_f32_e32 v130, v130, v131
	v_add_f32_e32 v190, v128, v130
	s_waitcnt lgkmcnt(6)
	v_mul_f32_e32 v153, v154, v155
	v_pk_mul_f32 v[112:113], v[112:113], v[152:153] op_sel:[0,1] op_sel_hi:[1,1]
	v_add_f32_dpp v190, v190, v190 row_ror:8 row_mask:0xf bank_mask:0xf bound_ctrl:1
	v_pk_mul_f32 v[114:115], v[114:115], v[152:153] op_sel:[0,1] op_sel_hi:[1,1]
	v_pk_mul_f32 v[116:117], v[116:117], v[152:153] op_sel:[0,1] op_sel_hi:[1,1]
	v_add_f32_dpp v190, v190, v190 row_ror:4 row_mask:0xf bank_mask:0xf bound_ctrl:1
	v_pk_mul_f32 v[118:119], v[118:119], v[152:153] op_sel:[0,1] op_sel_hi:[1,1]
	v_pk_mul_f32 v[120:121], v[120:121], v[152:153] op_sel:[0,1] op_sel_hi:[1,1]
	v_add_f32_dpp v190, v190, v190 row_ror:2 row_mask:0xf bank_mask:0xf bound_ctrl:1
	v_pk_mul_f32 v[122:123], v[122:123], v[152:153] op_sel:[0,1] op_sel_hi:[1,1]
	v_pk_mul_f32 v[124:125], v[124:125], v[152:153] op_sel:[0,1] op_sel_hi:[1,1]
	v_add_f32_dpp v190, v190, v190 row_ror:1 row_mask:0xf bank_mask:0xf bound_ctrl:1
	v_pk_mul_f32 v[126:127], v[126:127], v[152:153] op_sel:[0,1] op_sel_hi:[1,1]
	s_waitcnt lgkmcnt(5)
	v_pk_fma_f32 v[196:197], v[152:153], v[196:197], v[112:113] op_sel_hi:[0,1,1]
	ds_write_b32 v189, v190 offset:34944
	v_pk_fma_f32 v[198:199], v[152:153], v[198:199], v[114:115] op_sel_hi:[0,1,1]
	v_pk_fma_f32 v[200:201], v[152:153], v[200:201], v[116:117] op_sel_hi:[0,1,1]
	v_pk_fma_f32 v[202:203], v[152:153], v[202:203], v[118:119] op_sel_hi:[0,1,1]
	v_pk_fma_f32 v[204:205], v[152:153], v[204:205], v[120:121] op_sel_hi:[0,1,1]
	v_pk_fma_f32 v[206:207], v[152:153], v[206:207], v[122:123] op_sel_hi:[0,1,1]
	v_pk_fma_f32 v[208:209], v[152:153], v[208:209], v[124:125] op_sel_hi:[0,1,1]
	v_pk_fma_f32 v[210:211], v[152:153], v[210:211], v[126:127] op_sel_hi:[0,1,1]
	s_waitcnt lgkmcnt(5)
	v_pk_fma_f32 v[128:129], v[96:97], v[196:197], v[192:193]
	v_pk_fma_f32 v[130:131], v[98:99], v[198:199], v[192:193]
	s_waitcnt lgkmcnt(4)
	v_pk_fma_f32 v[128:129], v[100:101], v[200:201], v[128:129]
	v_pk_fma_f32 v[130:131], v[102:103], v[202:203], v[130:131]
	s_waitcnt lgkmcnt(3)
	v_pk_fma_f32 v[128:129], v[104:105], v[204:205], v[128:129]
	v_pk_fma_f32 v[130:131], v[106:107], v[206:207], v[130:131]
	s_waitcnt lgkmcnt(2)
	v_pk_fma_f32 v[128:129], v[108:109], v[208:209], v[128:129]
	v_pk_fma_f32 v[130:131], v[110:111], v[210:211], v[130:131]
	v_add_f32_e32 v128, v128, v129
	v_add_f32_e32 v130, v130, v131
	v_add_f32_e32 v191, v128, v130
	s_nop 1
	v_add_f32_dpp v191, v191, v191 row_ror:8 row_mask:0xf bank_mask:0xf bound_ctrl:1
	s_nop 1
	v_add_f32_dpp v191, v191, v191 row_ror:4 row_mask:0xf bank_mask:0xf bound_ctrl:1
	s_nop 1
	v_add_f32_dpp v191, v191, v191 row_ror:2 row_mask:0xf bank_mask:0xf bound_ctrl:1
	s_nop 1
	v_add_f32_dpp v191, v191, v191 row_ror:1 row_mask:0xf bank_mask:0xf bound_ctrl:1
	ds_write_b32 v189, v191 offset:35008
	s_waitcnt vmcnt(7)
	ds_write_b128 v185, v[32:35]
	s_waitcnt vmcnt(5)
	ds_write_b128 v186, v[40:43]
	ds_write_b128 v185, v[36:39] offset:8192
	s_waitcnt vmcnt(4)
	ds_write_b128 v186, v[44:47] offset:8192
	s_and_saveexec_b64 s[8:9], s[42:43]
	ds_write_b32 v144, v184 offset:16384
	s_or_b64 exec, exec, s[8:9]
	s_and_saveexec_b64 s[8:9], s[40:41]
	s_cbranch_execz .LBB0_1505
	v_add_f32_e32 v64, v156, v182
	v_mul_f32_e64 v65, |v64|, s62
	v_exp_f32_e32 v65, v65
	v_min_f32_e32 v64, 0, v64
	v_add_f32_e32 v65, 1.0, v65
	v_cmp_gt_f32_e32 vcc, s5, v65
	s_nop 1
	v_cndmask_b32_e64 v66, 0, 32, vcc
	v_ldexp_f32 v65, v65, v66
	v_log_f32_e32 v65, v65
	v_cndmask_b32_e32 v67, 0, v171, vcc
	v_add_f32_e32 v66, v145, v180
	v_mul_f32_e32 v68, 0x3f317217, v65
	v_fma_f32 v68, v65, s76, -v68
	v_fmac_f32_e32 v68, 0x3377d1cf, v65
	v_fmac_f32_e32 v68, 0x3f317217, v65
	v_cmp_lt_f32_e64 vcc, |v65|, s77
	s_nop 1
	v_cndmask_b32_e32 v65, v65, v68, vcc
	v_sub_f32_e32 v65, v65, v67
	v_sub_f32_e32 v64, v64, v65
	v_add_u32_e32 v65, 0x4000, v144
	ds_write2_b32 v65, v66, v64 offset0:128 offset1:144

.LBB0_1516:
	s_or_b64 exec, exec, s[8:9]
	s_waitcnt lgkmcnt(0)
	s_barrier
	v_mov_b32_e32 v192, 0
	v_mov_b32_e32 v193, 0
	ds_read_b128 v[80:83], v188 offset:8192
	ds_read_b128 v[84:87], v188 offset:8448
	ds_read_b128 v[88:91], v188 offset:8704
	ds_read_b128 v[92:95], v188 offset:8960
	ds_read_b32 v134, v140 offset:35136
	ds_read_b32 v135, v189 offset:16384
	ds_read_b32 v132, v140 offset:35072
	ds_read_b128 v[64:67], v188
	ds_read_b128 v[68:71], v188 offset:256
	ds_read_b128 v[72:75], v188 offset:512
	ds_read_b128 v[76:79], v188 offset:768
	ds_read_b128 v[112:115], v188 offset:9216
	ds_read_b128 v[116:119], v188 offset:9472
	ds_read_b128 v[120:123], v188 offset:9728
	ds_read_b128 v[124:127], v188 offset:9984
	ds_read_b32 v154, v140 offset:35140
	ds_read_b32 v155, v189 offset:16448
	ds_read_b32 v152, v140 offset:35076
	ds_read_b128 v[96:99], v188 offset:1024
	ds_read_b128 v[100:103], v188 offset:1280
	ds_read_b128 v[104:107], v188 offset:1536
	ds_read_b128 v[108:111], v188 offset:1792
	s_waitcnt lgkmcnt(15)
	v_mul_f32_e32 v133, v134, v135
	v_pk_mul_f32 v[80:81], v[80:81], v[132:133] op_sel:[0,1] op_sel_hi:[1,1]
	v_pk_mul_f32 v[82:83], v[82:83], v[132:133] op_sel:[0,1] op_sel_hi:[1,1]
	v_pk_mul_f32 v[84:85], v[84:85], v[132:133] op_sel:[0,1] op_sel_hi:[1,1]
	v_pk_mul_f32 v[86:87], v[86:87], v[132:133] op_sel:[0,1] op_sel_hi:[1,1]
	v_pk_mul_f32 v[88:89], v[88:89], v[132:133] op_sel:[0,1] op_sel_hi:[1,1]
	v_pk_mul_f32 v[90:91], v[90:91], v[132:133] op_sel:[0,1] op_sel_hi:[1,1]
	v_pk_mul_f32 v[92:93], v[92:93], v[132:133] op_sel:[0,1] op_sel_hi:[1,1]
	v_pk_mul_f32 v[94:95], v[94:95], v[132:133] op_sel:[0,1] op_sel_hi:[1,1]
	v_pk_fma_f32 v[196:197], v[132:133], v[196:197], v[80:81] op_sel_hi:[0,1,1]
	v_pk_fma_f32 v[198:199], v[132:133], v[198:199], v[82:83] op_sel_hi:[0,1,1]
	v_pk_fma_f32 v[200:201], v[132:133], v[200:201], v[84:85] op_sel_hi:[0,1,1]
	v_pk_fma_f32 v[202:203], v[132:133], v[202:203], v[86:87] op_sel_hi:[0,1,1]
	v_pk_fma_f32 v[204:205], v[132:133], v[204:205], v[88:89] op_sel_hi:[0,1,1]
	v_pk_fma_f32 v[206:207], v[132:133], v[206:207], v[90:91] op_sel_hi:[0,1,1]
	v_pk_fma_f32 v[208:209], v[132:133], v[208:209], v[92:93] op_sel_hi:[0,1,1]
	v_pk_fma_f32 v[210:211], v[132:133], v[210:211], v[94:95] op_sel_hi:[0,1,1]
	s_waitcnt lgkmcnt(14)
	v_pk_fma_f32 v[128:129], v[64:65], v[196:197], v[192:193]
	v_pk_fma_f32 v[130:131], v[66:67], v[198:199], v[192:193]
	s_waitcnt lgkmcnt(13)
	v_pk_fma_f32 v[128:129], v[68:69], v[200:201], v[128:129]
	v_pk_fma_f32 v[130:131], v[70:71], v[202:203], v[130:131]
	s_waitcnt lgkmcnt(12)
	v_pk_fma_f32 v[128:129], v[72:73], v[204:205], v[128:129]
	v_pk_fma_f32 v[130:131], v[74:75], v[206:207], v[130:131]
	s_waitcnt lgkmcnt(11)
	v_pk_fma_f32 v[128:129], v[76:77], v[208:209], v[128:129]
	v_pk_fma_f32 v[130:131], v[78:79], v[210:211], v[130:131]
	v_add_f32_e32 v128, v128, v129
	v_add_f32_e32 v130, v130, v131
	v_add_f32_e32 v190, v128, v130
	ds_read_b128 v[80:83], v188 offset:10240
	ds_read_b128 v[84:87], v188 offset:10496
	ds_read_b128 v[88:91], v188 offset:10752
	ds_read_b128 v[92:95], v188 offset:11008
	ds_read_b32 v134, v140 offset:35144
	ds_read_b32 v135, v189 offset:16512
	ds_read_b32 v132, v140 offset:35080
	ds_read_b128 v[64:67], v188 offset:2048
	ds_read_b128 v[68:71], v188 offset:2304
	ds_read_b128 v[72:75], v188 offset:2560
	ds_read_b128 v[76:79], v188 offset:2816
	s_waitcnt lgkmcnt(15)
	v_mul_f32_e32 v153, v154, v155
	v_pk_mul_f32 v[112:113], v[112:113], v[152:153] op_sel:[0,1] op_sel_hi:[1,1]
	v_add_f32_dpp v190, v190, v190 row_ror:8 row_mask:0xf bank_mask:0xf bound_ctrl:1
	v_pk_mul_f32 v[114:115], v[114:115], v[152:153] op_sel:[0,1] op_sel_hi:[1,1]
	v_pk_mul_f32 v[116:117], v[116:117], v[152:153] op_sel:[0,1] op_sel_hi:[1,1]
	v_add_f32_dpp v190, v190, v190 row_ror:4 row_mask:0xf bank_mask:0xf bound_ctrl:1
	v_pk_mul_f32 v[118:119], v[118:119], v[152:153] op_sel:[0,1] op_sel_hi:[1,1]
	v_pk_mul_f32 v[120:121], v[120:121], v[152:153] op_sel:[0,1] op_sel_hi:[1,1]
	v_add_f32_dpp v190, v190, v190 row_ror:2 row_mask:0xf bank_mask:0xf bound_ctrl:1
	v_pk_mul_f32 v[122:123], v[122:123], v[152:153] op_sel:[0,1] op_sel_hi:[1,1]
	v_pk_mul_f32 v[124:125], v[124:125], v[152:153] op_sel:[0,1] op_sel_hi:[1,1]
	v_add_f32_dpp v190, v190, v190 row_ror:1 row_mask:0xf bank_mask:0xf bound_ctrl:1
	v_pk_mul_f32 v[126:127], v[126:127], v[152:153] op_sel:[0,1] op_sel_hi:[1,1]
	v_pk_fma_f32 v[196:197], v[152:153], v[196:197], v[112:113] op_sel_hi:[0,1,1]
	ds_write_b32 v189, v190 offset:34048
	v_pk_fma_f32 v[198:199], v[152:153], v[198:199], v[114:115] op_sel_hi:[0,1,1]
	v_pk_fma_f32 v[200:201], v[152:153], v[200:201], v[116:117] op_sel_hi:[0,1,1]
	v_pk_fma_f32 v[202:203], v[152:153], v[202:203], v[118:119] op_sel_hi:[0,1,1]
	v_pk_fma_f32 v[204:205], v[152:153], v[204:205], v[120:121] op_sel_hi:[0,1,1]
	v_pk_fma_f32 v[206:207], v[152:153], v[206:207], v[122:123] op_sel_hi:[0,1,1]
	v_pk_fma_f32 v[208:209], v[152:153], v[208:209], v[124:125] op_sel_hi:[0,1,1]
	v_pk_fma_f32 v[210:211], v[152:153], v[210:211], v[126:127] op_sel_hi:[0,1,1]
	s_waitcnt lgkmcnt(15)
	v_pk_fma_f32 v[128:129], v[96:97], v[196:197], v[192:193]
	v_pk_fma_f32 v[130:131], v[98:99], v[198:199], v[192:193]
	s_waitcnt lgkmcnt(14)
	v_pk_fma_f32 v[128:129], v[100:101], v[200:201], v[128:129]
	v_pk_fma_f32 v[130:131], v[102:103], v[202:203], v[130:131]
	s_waitcnt lgkmcnt(13)
	v_pk_fma_f32 v[128:129], v[104:105], v[204:205], v[128:129]
	v_pk_fma_f32 v[130:131], v[106:107], v[206:207], v[130:131]
	s_waitcnt lgkmcnt(12)
	v_pk_fma_f32 v[128:129], v[108:109], v[208:209], v[128:129]
	v_pk_fma_f32 v[130:131], v[110:111], v[210:211], v[130:131]
	v_add_f32_e32 v128, v128, v129
	v_add_f32_e32 v130, v130, v131
	v_add_f32_e32 v191, v128, v130
	ds_read_b128 v[112:115], v188 offset:11264
	ds_read_b128 v[116:119], v188 offset:11520
	ds_read_b128 v[120:123], v188 offset:11776
	ds_read_b128 v[124:127], v188 offset:12032
	ds_read_b32 v154, v140 offset:35148
	ds_read_b32 v155, v189 offset:16576
	ds_read_b32 v152, v140 offset:35084
	ds_read_b128 v[96:99], v188 offset:3072
	ds_read_b128 v[100:103], v188 offset:3328
	ds_read_b128 v[104:107], v188 offset:3584
	ds_read_b128 v[108:111], v188 offset:3840
	s_waitcnt lgkmcnt(15)
	v_mul_f32_e32 v133, v134, v135
	v_pk_mul_f32 v[80:81], v[80:81], v[132:133] op_sel:[0,1] op_sel_hi:[1,1]
	v_add_f32_dpp v191, v191, v191 row_ror:8 row_mask:0xf bank_mask:0xf bound_ctrl:1
	v_pk_mul_f32 v[82:83], v[82:83], v[132:133] op_sel:[0,1] op_sel_hi:[1,1]
	v_pk_mul_f32 v[84:85], v[84:85], v[132:133] op_sel:[0,1] op_sel_hi:[1,1]
	v_add_f32_dpp v191, v191, v191 row_ror:4 row_mask:0xf bank_mask:0xf bound_ctrl:1
	v_pk_mul_f32 v[86:87], v[86:87], v[132:133] op_sel:[0,1] op_sel_hi:[1,1]
	v_pk_mul_f32 v[88:89], v[88:89], v[132:133] op_sel:[0,1] op_sel_hi:[1,1]
	v_add_f32_dpp v191, v191, v191 row_ror:2 row_mask:0xf bank_mask:0xf bound_ctrl:1
	v_pk_mul_f32 v[90:91], v[90:91], v[132:133] op_sel:[0,1] op_sel_hi:[1,1]
	v_pk_mul_f32 v[92:93], v[92:93], v[132:133] op_sel:[0,1] op_sel_hi:[1,1]
	v_add_f32_dpp v191, v191, v191 row_ror:1 row_mask:0xf bank_mask:0xf bound_ctrl:1
	v_pk_mul_f32 v[94:95], v[94:95], v[132:133] op_sel:[0,1] op_sel_hi:[1,1]
	v_pk_fma_f32 v[196:197], v[132:133], v[196:197], v[80:81] op_sel_hi:[0,1,1]
	ds_write_b32 v189, v191 offset:34112
	v_pk_fma_f32 v[198:199], v[132:133], v[198:199], v[82:83] op_sel_hi:[0,1,1]
	v_pk_fma_f32 v[200:201], v[132:133], v[200:201], v[84:85] op_sel_hi:[0,1,1]
	v_pk_fma_f32 v[202:203], v[132:133], v[202:203], v[86:87] op_sel_hi:[0,1,1]
	v_pk_fma_f32 v[204:205], v[132:133], v[204:205], v[88:89] op_sel_hi:[0,1,1]
	v_pk_fma_f32 v[206:207], v[132:133], v[206:207], v[90:91] op_sel_hi:[0,1,1]
	v_pk_fma_f32 v[208:209], v[132:133], v[208:209], v[92:93] op_sel_hi:[0,1,1]
	v_pk_fma_f32 v[210:211], v[132:133], v[210:211], v[94:95] op_sel_hi:[0,1,1]
	s_waitcnt lgkmcnt(15)
	v_pk_fma_f32 v[128:129], v[64:65], v[196:197], v[192:193]
	v_pk_fma_f32 v[130:131], v[66:67], v[198:199], v[192:193]
	v_pk_fma_f32 v[128:129], v[68:69], v[200:201], v[128:129]
	v_pk_fma_f32 v[130:131], v[70:71], v[202:203], v[130:131]
	s_waitcnt lgkmcnt(14)
	v_pk_fma_f32 v[128:129], v[72:73], v[204:205], v[128:129]
	v_pk_fma_f32 v[130:131], v[74:75], v[206:207], v[130:131]
	s_waitcnt lgkmcnt(13)
	v_pk_fma_f32 v[128:129], v[76:77], v[208:209], v[128:129]
	v_pk_fma_f32 v[130:131], v[78:79], v[210:211], v[130:131]
	v_add_f32_e32 v128, v128, v129
	v_add_f32_e32 v130, v130, v131
	v_add_f32_e32 v190, v128, v130
	ds_read_b128 v[80:83], v188 offset:12288
	ds_read_b128 v[84:87], v188 offset:12544
	ds_read_b128 v[88:91], v188 offset:12800
	ds_read_b128 v[92:95], v188 offset:13056
	ds_read_b32 v134, v140 offset:35152
	ds_read_b32 v135, v189 offset:16640
	ds_read_b32 v132, v140 offset:35088
	ds_read_b128 v[64:67], v188 offset:4096
	ds_read_b128 v[68:71], v188 offset:4352
	ds_read_b128 v[72:75], v188 offset:4608
	ds_read_b128 v[76:79], v188 offset:4864
	s_waitcnt lgkmcnt(15)
	v_mul_f32_e32 v153, v154, v155
	v_pk_mul_f32 v[112:113], v[112:113], v[152:153] op_sel:[0,1] op_sel_hi:[1,1]
	v_add_f32_dpp v190, v190, v190 row_ror:8 row_mask:0xf bank_mask:0xf bound_ctrl:1
	v_pk_mul_f32 v[114:115], v[114:115], v[152:153] op_sel:[0,1] op_sel_hi:[1,1]
	v_pk_mul_f32 v[116:117], v[116:117], v[152:153] op_sel:[0,1] op_sel_hi:[1,1]
	v_add_f32_dpp v190, v190, v190 row_ror:4 row_mask:0xf bank_mask:0xf bound_ctrl:1
	v_pk_mul_f32 v[118:119], v[118:119], v[152:153] op_sel:[0,1] op_sel_hi:[1,1]
	v_pk_mul_f32 v[120:121], v[120:121], v[152:153] op_sel:[0,1] op_sel_hi:[1,1]
	v_add_f32_dpp v190, v190, v190 row_ror:2 row_mask:0xf bank_mask:0xf bound_ctrl:1
	v_pk_mul_f32 v[122:123], v[122:123], v[152:153] op_sel:[0,1] op_sel_hi:[1,1]
	v_pk_mul_f32 v[124:125], v[124:125], v[152:153] op_sel:[0,1] op_sel_hi:[1,1]
	v_add_f32_dpp v190, v190, v190 row_ror:1 row_mask:0xf bank_mask:0xf bound_ctrl:1
	v_pk_mul_f32 v[126:127], v[126:127], v[152:153] op_sel:[0,1] op_sel_hi:[1,1]
	v_pk_fma_f32 v[196:197], v[152:153], v[196:197], v[112:113] op_sel_hi:[0,1,1]
	ds_write_b32 v189, v190 offset:34176
	v_pk_fma_f32 v[198:199], v[152:153], v[198:199], v[114:115] op_sel_hi:[0,1,1]
	v_pk_fma_f32 v[200:201], v[152:153], v[200:201], v[116:117] op_sel_hi:[0,1,1]
	v_pk_fma_f32 v[202:203], v[152:153], v[202:203], v[118:119] op_sel_hi:[0,1,1]
	v_pk_fma_f32 v[204:205], v[152:153], v[204:205], v[120:121] op_sel_hi:[0,1,1]
	v_pk_fma_f32 v[206:207], v[152:153], v[206:207], v[122:123] op_sel_hi:[0,1,1]
	v_pk_fma_f32 v[208:209], v[152:153], v[208:209], v[124:125] op_sel_hi:[0,1,1]
	v_pk_fma_f32 v[210:211], v[152:153], v[210:211], v[126:127] op_sel_hi:[0,1,1]
	s_waitcnt lgkmcnt(15)
	v_pk_fma_f32 v[128:129], v[96:97], v[196:197], v[192:193]
	v_pk_fma_f32 v[130:131], v[98:99], v[198:199], v[192:193]
	v_pk_fma_f32 v[128:129], v[100:101], v[200:201], v[128:129]
	v_pk_fma_f32 v[130:131], v[102:103], v[202:203], v[130:131]
	s_waitcnt lgkmcnt(14)
	v_pk_fma_f32 v[128:129], v[104:105], v[204:205], v[128:129]
	v_pk_fma_f32 v[130:131], v[106:107], v[206:207], v[130:131]
	s_waitcnt lgkmcnt(13)
	v_pk_fma_f32 v[128:129], v[108:109], v[208:209], v[128:129]
	v_pk_fma_f32 v[130:131], v[110:111], v[210:211], v[130:131]
	v_add_f32_e32 v128, v128, v129
	v_add_f32_e32 v130, v130, v131
	v_add_f32_e32 v191, v128, v130
	ds_read_b128 v[112:115], v188 offset:13312
	ds_read_b128 v[116:119], v188 offset:13568
	ds_read_b128 v[120:123], v188 offset:13824
	ds_read_b128 v[124:127], v188 offset:14080
	ds_read_b32 v154, v140 offset:35156
	ds_read_b32 v155, v189 offset:16704
	ds_read_b32 v152, v140 offset:35092
	ds_read_b128 v[96:99], v188 offset:5120
	ds_read_b128 v[100:103], v188 offset:5376
	ds_read_b128 v[104:107], v188 offset:5632
	ds_read_b128 v[108:111], v188 offset:5888
	s_waitcnt lgkmcnt(15)
	v_mul_f32_e32 v133, v134, v135
	v_pk_mul_f32 v[80:81], v[80:81], v[132:133] op_sel:[0,1] op_sel_hi:[1,1]
	v_add_f32_dpp v191, v191, v191 row_ror:8 row_mask:0xf bank_mask:0xf bound_ctrl:1
	v_pk_mul_f32 v[82:83], v[82:83], v[132:133] op_sel:[0,1] op_sel_hi:[1,1]
	v_pk_mul_f32 v[84:85], v[84:85], v[132:133] op_sel:[0,1] op_sel_hi:[1,1]
	v_add_f32_dpp v191, v191, v191 row_ror:4 row_mask:0xf bank_mask:0xf bound_ctrl:1
	v_pk_mul_f32 v[86:87], v[86:87], v[132:133] op_sel:[0,1] op_sel_hi:[1,1]
	v_pk_mul_f32 v[88:89], v[88:89], v[132:133] op_sel:[0,1] op_sel_hi:[1,1]
	v_add_f32_dpp v191, v191, v191 row_ror:2 row_mask:0xf bank_mask:0xf bound_ctrl:1
	v_pk_mul_f32 v[90:91], v[90:91], v[132:133] op_sel:[0,1] op_sel_hi:[1,1]
	v_pk_mul_f32 v[92:93], v[92:93], v[132:133] op_sel:[0,1] op_sel_hi:[1,1]
	v_add_f32_dpp v191, v191, v191 row_ror:1 row_mask:0xf bank_mask:0xf bound_ctrl:1
	v_pk_mul_f32 v[94:95], v[94:95], v[132:133] op_sel:[0,1] op_sel_hi:[1,1]
	v_pk_fma_f32 v[196:197], v[132:133], v[196:197], v[80:81] op_sel_hi:[0,1,1]
	ds_write_b32 v189, v191 offset:34240
	v_pk_fma_f32 v[198:199], v[132:133], v[198:199], v[82:83] op_sel_hi:[0,1,1]
	v_pk_fma_f32 v[200:201], v[132:133], v[200:201], v[84:85] op_sel_hi:[0,1,1]
	v_pk_fma_f32 v[202:203], v[132:133], v[202:203], v[86:87] op_sel_hi:[0,1,1]
	v_pk_fma_f32 v[204:205], v[132:133], v[204:205], v[88:89] op_sel_hi:[0,1,1]
	v_pk_fma_f32 v[206:207], v[132:133], v[206:207], v[90:91] op_sel_hi:[0,1,1]
	v_pk_fma_f32 v[208:209], v[132:133], v[208:209], v[92:93] op_sel_hi:[0,1,1]
	v_pk_fma_f32 v[210:211], v[132:133], v[210:211], v[94:95] op_sel_hi:[0,1,1]
	s_waitcnt lgkmcnt(15)
	v_pk_fma_f32 v[128:129], v[64:65], v[196:197], v[192:193]
	v_pk_fma_f32 v[130:131], v[66:67], v[198:199], v[192:193]
	v_pk_fma_f32 v[128:129], v[68:69], v[200:201], v[128:129]
	v_pk_fma_f32 v[130:131], v[70:71], v[202:203], v[130:131]
	s_waitcnt lgkmcnt(14)
	v_pk_fma_f32 v[128:129], v[72:73], v[204:205], v[128:129]
	v_pk_fma_f32 v[130:131], v[74:75], v[206:207], v[130:131]
	s_waitcnt lgkmcnt(13)
	v_pk_fma_f32 v[128:129], v[76:77], v[208:209], v[128:129]
	v_pk_fma_f32 v[130:131], v[78:79], v[210:211], v[130:131]
	v_add_f32_e32 v128, v128, v129
	v_add_f32_e32 v130, v130, v131
	v_add_f32_e32 v190, v128, v130
	ds_read_b128 v[80:83], v188 offset:14336
	ds_read_b128 v[84:87], v188 offset:14592
	ds_read_b128 v[88:91], v188 offset:14848
	ds_read_b128 v[92:95], v188 offset:15104
	ds_read_b32 v134, v140 offset:35160
	ds_read_b32 v135, v189 offset:16768
	ds_read_b32 v132, v140 offset:35096
	ds_read_b128 v[64:67], v188 offset:6144
	ds_read_b128 v[68:71], v188 offset:6400
	ds_read_b128 v[72:75], v188 offset:6656
	ds_read_b128 v[76:79], v188 offset:6912
	s_waitcnt lgkmcnt(15)
	v_mul_f32_e32 v153, v154, v155
	v_pk_mul_f32 v[112:113], v[112:113], v[152:153] op_sel:[0,1] op_sel_hi:[1,1]
	v_add_f32_dpp v190, v190, v190 row_ror:8 row_mask:0xf bank_mask:0xf bound_ctrl:1
	v_pk_mul_f32 v[114:115], v[114:115], v[152:153] op_sel:[0,1] op_sel_hi:[1,1]
	v_pk_mul_f32 v[116:117], v[116:117], v[152:153] op_sel:[0,1] op_sel_hi:[1,1]
	v_add_f32_dpp v190, v190, v190 row_ror:4 row_mask:0xf bank_mask:0xf bound_ctrl:1
	v_pk_mul_f32 v[118:119], v[118:119], v[152:153] op_sel:[0,1] op_sel_hi:[1,1]
	v_pk_mul_f32 v[120:121], v[120:121], v[152:153] op_sel:[0,1] op_sel_hi:[1,1]
	v_add_f32_dpp v190, v190, v190 row_ror:2 row_mask:0xf bank_mask:0xf bound_ctrl:1
	v_pk_mul_f32 v[122:123], v[122:123], v[152:153] op_sel:[0,1] op_sel_hi:[1,1]
	v_pk_mul_f32 v[124:125], v[124:125], v[152:153] op_sel:[0,1] op_sel_hi:[1,1]
	v_add_f32_dpp v190, v190, v190 row_ror:1 row_mask:0xf bank_mask:0xf bound_ctrl:1
	v_pk_mul_f32 v[126:127], v[126:127], v[152:153] op_sel:[0,1] op_sel_hi:[1,1]
	v_pk_fma_f32 v[196:197], v[152:153], v[196:197], v[112:113] op_sel_hi:[0,1,1]
	ds_write_b32 v189, v190 offset:34304
	v_pk_fma_f32 v[198:199], v[152:153], v[198:199], v[114:115] op_sel_hi:[0,1,1]
	v_pk_fma_f32 v[200:201], v[152:153], v[200:201], v[116:117] op_sel_hi:[0,1,1]
	v_pk_fma_f32 v[202:203], v[152:153], v[202:203], v[118:119] op_sel_hi:[0,1,1]
	v_pk_fma_f32 v[204:205], v[152:153], v[204:205], v[120:121] op_sel_hi:[0,1,1]
	v_pk_fma_f32 v[206:207], v[152:153], v[206:207], v[122:123] op_sel_hi:[0,1,1]
	v_pk_fma_f32 v[208:209], v[152:153], v[208:209], v[124:125] op_sel_hi:[0,1,1]
	v_pk_fma_f32 v[210:211], v[152:153], v[210:211], v[126:127] op_sel_hi:[0,1,1]
	s_waitcnt lgkmcnt(15)
	v_pk_fma_f32 v[128:129], v[96:97], v[196:197], v[192:193]
	v_pk_fma_f32 v[130:131], v[98:99], v[198:199], v[192:193]
	v_pk_fma_f32 v[128:129], v[100:101], v[200:201], v[128:129]
	v_pk_fma_f32 v[130:131], v[102:103], v[202:203], v[130:131]
	s_waitcnt lgkmcnt(14)
	v_pk_fma_f32 v[128:129], v[104:105], v[204:205], v[128:129]
	v_pk_fma_f32 v[130:131], v[106:107], v[206:207], v[130:131]
	s_waitcnt lgkmcnt(13)
	v_pk_fma_f32 v[128:129], v[108:109], v[208:209], v[128:129]
	v_pk_fma_f32 v[130:131], v[110:111], v[210:211], v[130:131]
	v_add_f32_e32 v128, v128, v129
	v_add_f32_e32 v130, v130, v131
	v_add_f32_e32 v191, v128, v130
	ds_read_b128 v[112:115], v188 offset:15360
	ds_read_b128 v[116:119], v188 offset:15616
	ds_read_b128 v[120:123], v188 offset:15872
	ds_read_b128 v[124:127], v188 offset:16128
	ds_read_b32 v154, v140 offset:35164
	ds_read_b32 v155, v189 offset:16832
	ds_read_b32 v152, v140 offset:35100
	ds_read_b128 v[96:99], v188 offset:7168
	ds_read_b128 v[100:103], v188 offset:7424
	ds_read_b128 v[104:107], v188 offset:7680
	ds_read_b128 v[108:111], v188 offset:7936
	s_waitcnt lgkmcnt(15)
	v_mul_f32_e32 v133, v134, v135
	v_pk_mul_f32 v[80:81], v[80:81], v[132:133] op_sel:[0,1] op_sel_hi:[1,1]
	v_add_f32_dpp v191, v191, v191 row_ror:8 row_mask:0xf bank_mask:0xf bound_ctrl:1
	v_pk_mul_f32 v[82:83], v[82:83], v[132:133] op_sel:[0,1] op_sel_hi:[1,1]
	v_pk_mul_f32 v[84:85], v[84:85], v[132:133] op_sel:[0,1] op_sel_hi:[1,1]
	v_add_f32_dpp v191, v191, v191 row_ror:4 row_mask:0xf bank_mask:0xf bound_ctrl:1
	v_pk_mul_f32 v[86:87], v[86:87], v[132:133] op_sel:[0,1] op_sel_hi:[1,1]
	v_pk_mul_f32 v[88:89], v[88:89], v[132:133] op_sel:[0,1] op_sel_hi:[1,1]
	v_add_f32_dpp v191, v191, v191 row_ror:2 row_mask:0xf bank_mask:0xf bound_ctrl:1
	v_pk_mul_f32 v[90:91], v[90:91], v[132:133] op_sel:[0,1] op_sel_hi:[1,1]
	v_pk_mul_f32 v[92:93], v[92:93], v[132:133] op_sel:[0,1] op_sel_hi:[1,1]
	v_add_f32_dpp v191, v191, v191 row_ror:1 row_mask:0xf bank_mask:0xf bound_ctrl:1
	v_pk_mul_f32 v[94:95], v[94:95], v[132:133] op_sel:[0,1] op_sel_hi:[1,1]
	v_pk_fma_f32 v[196:197], v[132:133], v[196:197], v[80:81] op_sel_hi:[0,1,1]
	ds_write_b32 v189, v191 offset:34368
	v_pk_fma_f32 v[198:199], v[132:133], v[198:199], v[82:83] op_sel_hi:[0,1,1]
	v_pk_fma_f32 v[200:201], v[132:133], v[200:201], v[84:85] op_sel_hi:[0,1,1]
	v_pk_fma_f32 v[202:203], v[132:133], v[202:203], v[86:87] op_sel_hi:[0,1,1]
	v_pk_fma_f32 v[204:205], v[132:133], v[204:205], v[88:89] op_sel_hi:[0,1,1]
	v_pk_fma_f32 v[206:207], v[132:133], v[206:207], v[90:91] op_sel_hi:[0,1,1]
	v_pk_fma_f32 v[208:209], v[132:133], v[208:209], v[92:93] op_sel_hi:[0,1,1]
	v_pk_fma_f32 v[210:211], v[132:133], v[210:211], v[94:95] op_sel_hi:[0,1,1]
	s_waitcnt lgkmcnt(15)
	v_pk_fma_f32 v[128:129], v[64:65], v[196:197], v[192:193]
	v_pk_fma_f32 v[130:131], v[66:67], v[198:199], v[192:193]
	v_pk_fma_f32 v[128:129], v[68:69], v[200:201], v[128:129]
	v_pk_fma_f32 v[130:131], v[70:71], v[202:203], v[130:131]
	s_waitcnt lgkmcnt(14)
	v_pk_fma_f32 v[128:129], v[72:73], v[204:205], v[128:129]
	v_pk_fma_f32 v[130:131], v[74:75], v[206:207], v[130:131]
	s_waitcnt lgkmcnt(13)
	v_pk_fma_f32 v[128:129], v[76:77], v[208:209], v[128:129]
	v_pk_fma_f32 v[130:131], v[78:79], v[210:211], v[130:131]
	v_add_f32_e32 v128, v128, v129
	v_add_f32_e32 v130, v130, v131
	v_add_f32_e32 v190, v128, v130
	s_waitcnt lgkmcnt(6)
	v_mul_f32_e32 v153, v154, v155
	v_pk_mul_f32 v[112:113], v[112:113], v[152:153] op_sel:[0,1] op_sel_hi:[1,1]
	v_add_f32_dpp v190, v190, v190 row_ror:8 row_mask:0xf bank_mask:0xf bound_ctrl:1
	v_pk_mul_f32 v[114:115], v[114:115], v[152:153] op_sel:[0,1] op_sel_hi:[1,1]
	v_pk_mul_f32 v[116:117], v[116:117], v[152:153] op_sel:[0,1] op_sel_hi:[1,1]
	v_add_f32_dpp v190, v190, v190 row_ror:4 row_mask:0xf bank_mask:0xf bound_ctrl:1
	v_pk_mul_f32 v[118:119], v[118:119], v[152:153] op_sel:[0,1] op_sel_hi:[1,1]
	v_pk_mul_f32 v[120:121], v[120:121], v[152:153] op_sel:[0,1] op_sel_hi:[1,1]
	v_add_f32_dpp v190, v190, v190 row_ror:2 row_mask:0xf bank_mask:0xf bound_ctrl:1
	v_pk_mul_f32 v[122:123], v[122:123], v[152:153] op_sel:[0,1] op_sel_hi:[1,1]
	v_pk_mul_f32 v[124:125], v[124:125], v[152:153] op_sel:[0,1] op_sel_hi:[1,1]
	v_add_f32_dpp v190, v190, v190 row_ror:1 row_mask:0xf bank_mask:0xf bound_ctrl:1
	v_pk_mul_f32 v[126:127], v[126:127], v[152:153] op_sel:[0,1] op_sel_hi:[1,1]
	s_waitcnt lgkmcnt(5)
	v_pk_fma_f32 v[196:197], v[152:153], v[196:197], v[112:113] op_sel_hi:[0,1,1]
	ds_write_b32 v189, v190 offset:34432
	v_pk_fma_f32 v[198:199], v[152:153], v[198:199], v[114:115] op_sel_hi:[0,1,1]
	v_pk_fma_f32 v[200:201], v[152:153], v[200:201], v[116:117] op_sel_hi:[0,1,1]
	v_pk_fma_f32 v[202:203], v[152:153], v[202:203], v[118:119] op_sel_hi:[0,1,1]
	v_pk_fma_f32 v[204:205], v[152:153], v[204:205], v[120:121] op_sel_hi:[0,1,1]
	v_pk_fma_f32 v[206:207], v[152:153], v[206:207], v[122:123] op_sel_hi:[0,1,1]
	v_pk_fma_f32 v[208:209], v[152:153], v[208:209], v[124:125] op_sel_hi:[0,1,1]
	v_pk_fma_f32 v[210:211], v[152:153], v[210:211], v[126:127] op_sel_hi:[0,1,1]
	s_waitcnt lgkmcnt(5)
	v_pk_fma_f32 v[128:129], v[96:97], v[196:197], v[192:193]
	v_pk_fma_f32 v[130:131], v[98:99], v[198:199], v[192:193]
	s_waitcnt lgkmcnt(4)
	v_pk_fma_f32 v[128:129], v[100:101], v[200:201], v[128:129]
	v_pk_fma_f32 v[130:131], v[102:103], v[202:203], v[130:131]
	s_waitcnt lgkmcnt(3)
	v_pk_fma_f32 v[128:129], v[104:105], v[204:205], v[128:129]
	v_pk_fma_f32 v[130:131], v[106:107], v[206:207], v[130:131]
	s_waitcnt lgkmcnt(2)
	v_pk_fma_f32 v[128:129], v[108:109], v[208:209], v[128:129]
	v_pk_fma_f32 v[130:131], v[110:111], v[210:211], v[130:131]
	v_add_f32_e32 v128, v128, v129
	v_add_f32_e32 v130, v130, v131
	v_add_f32_e32 v191, v128, v130
	s_nop 1
	v_add_f32_dpp v191, v191, v191 row_ror:8 row_mask:0xf bank_mask:0xf bound_ctrl:1
	s_nop 1
	v_add_f32_dpp v191, v191, v191 row_ror:4 row_mask:0xf bank_mask:0xf bound_ctrl:1
	s_nop 1
	v_add_f32_dpp v191, v191, v191 row_ror:2 row_mask:0xf bank_mask:0xf bound_ctrl:1
	s_nop 1
	v_add_f32_dpp v191, v191, v191 row_ror:1 row_mask:0xf bank_mask:0xf bound_ctrl:1
	ds_write_b32 v189, v191 offset:34496
	s_waitcnt vmcnt(3)
	ds_write_b128 v185, v[48:51] offset:17024
	s_waitcnt vmcnt(1)
	ds_write_b128 v186, v[56:59] offset:17024
	ds_write_b128 v185, v[52:55] offset:25216
	s_waitcnt vmcnt(0)
	ds_write_b128 v186, v[60:63] offset:25216
	s_and_saveexec_b64 s[8:9], s[42:43]
	ds_write_b32 v144, v184 offset:33408
	s_or_b64 exec, exec, s[8:9]
	s_and_saveexec_b64 s[8:9], s[40:41]
	s_cbranch_execz .LBB0_1536
	v_add_f32_e32 v64, v156, v181
	v_mul_f32_e64 v65, |v64|, s62
	v_exp_f32_e32 v65, v65
	v_min_f32_e32 v64, 0, v64
	v_add_f32_e32 v65, 1.0, v65
	v_cmp_gt_f32_e32 vcc, s5, v65
	s_nop 1
	v_cndmask_b32_e64 v66, 0, 32, vcc
	v_ldexp_f32 v65, v65, v66
	v_log_f32_e32 v65, v65
	v_cndmask_b32_e32 v67, 0, v171, vcc
	v_add_f32_e32 v66, v145, v187
	v_mul_f32_e32 v68, 0x3f317217, v65
	v_fma_f32 v68, v65, s76, -v68
	v_fmac_f32_e32 v68, 0x3377d1cf, v65
	v_fmac_f32_e32 v68, 0x3f317217, v65
	v_cmp_lt_f32_e64 vcc, |v65|, s77
	s_nop 1
	v_cndmask_b32_e32 v65, v65, v68, vcc
	v_sub_f32_e32 v65, v65, v67
	v_sub_f32_e32 v64, v64, v65
	v_add_u32_e32 v65, 0x8400, v144
	ds_write2_b32 v65, v66, v64 offset0:32 offset1:48

.LBB0_1547:
	s_or_b64 exec, exec, s[8:9]
	s_waitcnt lgkmcnt(0)
	s_barrier
	v_mov_b32_e32 v192, 0
	v_mov_b32_e32 v193, 0
	ds_read_b128 v[80:83], v188 offset:25216
	ds_read_b128 v[84:87], v188 offset:25472
	ds_read_b128 v[88:91], v188 offset:25728
	ds_read_b128 v[92:95], v188 offset:25984
	ds_read_b32 v134, v140 offset:35136
	ds_read_b32 v135, v189 offset:33408
	ds_read_b32 v132, v140 offset:35072
	ds_read_b128 v[64:67], v188 offset:17024
	ds_read_b128 v[68:71], v188 offset:17280
	ds_read_b128 v[72:75], v188 offset:17536
	ds_read_b128 v[76:79], v188 offset:17792
	ds_read_b128 v[112:115], v188 offset:26240
	ds_read_b128 v[116:119], v188 offset:26496
	ds_read_b128 v[120:123], v188 offset:26752
	ds_read_b128 v[124:127], v188 offset:27008
	ds_read_b32 v154, v140 offset:35140
	ds_read_b32 v155, v189 offset:33472
	ds_read_b32 v152, v140 offset:35076
	ds_read_b128 v[96:99], v188 offset:18048
	ds_read_b128 v[100:103], v188 offset:18304
	ds_read_b128 v[104:107], v188 offset:18560
	ds_read_b128 v[108:111], v188 offset:18816
	s_waitcnt lgkmcnt(15)
	v_mul_f32_e32 v133, v134, v135
	v_pk_mul_f32 v[80:81], v[80:81], v[132:133] op_sel:[0,1] op_sel_hi:[1,1]
	v_pk_mul_f32 v[82:83], v[82:83], v[132:133] op_sel:[0,1] op_sel_hi:[1,1]
	v_pk_mul_f32 v[84:85], v[84:85], v[132:133] op_sel:[0,1] op_sel_hi:[1,1]
	v_pk_mul_f32 v[86:87], v[86:87], v[132:133] op_sel:[0,1] op_sel_hi:[1,1]
	v_pk_mul_f32 v[88:89], v[88:89], v[132:133] op_sel:[0,1] op_sel_hi:[1,1]
	v_pk_mul_f32 v[90:91], v[90:91], v[132:133] op_sel:[0,1] op_sel_hi:[1,1]
	v_pk_mul_f32 v[92:93], v[92:93], v[132:133] op_sel:[0,1] op_sel_hi:[1,1]
	v_pk_mul_f32 v[94:95], v[94:95], v[132:133] op_sel:[0,1] op_sel_hi:[1,1]
	v_pk_fma_f32 v[196:197], v[132:133], v[196:197], v[80:81] op_sel_hi:[0,1,1]
	v_pk_fma_f32 v[198:199], v[132:133], v[198:199], v[82:83] op_sel_hi:[0,1,1]
	v_pk_fma_f32 v[200:201], v[132:133], v[200:201], v[84:85] op_sel_hi:[0,1,1]
	v_pk_fma_f32 v[202:203], v[132:133], v[202:203], v[86:87] op_sel_hi:[0,1,1]
	v_pk_fma_f32 v[204:205], v[132:133], v[204:205], v[88:89] op_sel_hi:[0,1,1]
	v_pk_fma_f32 v[206:207], v[132:133], v[206:207], v[90:91] op_sel_hi:[0,1,1]
	v_pk_fma_f32 v[208:209], v[132:133], v[208:209], v[92:93] op_sel_hi:[0,1,1]
	v_pk_fma_f32 v[210:211], v[132:133], v[210:211], v[94:95] op_sel_hi:[0,1,1]
	s_waitcnt lgkmcnt(14)
	v_pk_fma_f32 v[128:129], v[64:65], v[196:197], v[192:193]
	v_pk_fma_f32 v[130:131], v[66:67], v[198:199], v[192:193]
	s_waitcnt lgkmcnt(13)
	v_pk_fma_f32 v[128:129], v[68:69], v[200:201], v[128:129]
	v_pk_fma_f32 v[130:131], v[70:71], v[202:203], v[130:131]
	s_waitcnt lgkmcnt(12)
	v_pk_fma_f32 v[128:129], v[72:73], v[204:205], v[128:129]
	v_pk_fma_f32 v[130:131], v[74:75], v[206:207], v[130:131]
	s_waitcnt lgkmcnt(11)
	v_pk_fma_f32 v[128:129], v[76:77], v[208:209], v[128:129]
	v_pk_fma_f32 v[130:131], v[78:79], v[210:211], v[130:131]
	v_add_f32_e32 v128, v128, v129
	v_add_f32_e32 v130, v130, v131
	v_add_f32_e32 v190, v128, v130
	ds_read_b128 v[80:83], v188 offset:27264
	ds_read_b128 v[84:87], v188 offset:27520
	ds_read_b128 v[88:91], v188 offset:27776
	ds_read_b128 v[92:95], v188 offset:28032
	ds_read_b32 v134, v140 offset:35144
	ds_read_b32 v135, v189 offset:33536
	ds_read_b32 v132, v140 offset:35080
	ds_read_b128 v[64:67], v188 offset:19072
	ds_read_b128 v[68:71], v188 offset:19328
	ds_read_b128 v[72:75], v188 offset:19584
	ds_read_b128 v[76:79], v188 offset:19840
	s_waitcnt lgkmcnt(15)
	v_mul_f32_e32 v153, v154, v155
	v_pk_mul_f32 v[112:113], v[112:113], v[152:153] op_sel:[0,1] op_sel_hi:[1,1]
	v_add_f32_dpp v190, v190, v190 row_ror:8 row_mask:0xf bank_mask:0xf bound_ctrl:1
	v_pk_mul_f32 v[114:115], v[114:115], v[152:153] op_sel:[0,1] op_sel_hi:[1,1]
	v_pk_mul_f32 v[116:117], v[116:117], v[152:153] op_sel:[0,1] op_sel_hi:[1,1]
	v_add_f32_dpp v190, v190, v190 row_ror:4 row_mask:0xf bank_mask:0xf bound_ctrl:1
	v_pk_mul_f32 v[118:119], v[118:119], v[152:153] op_sel:[0,1] op_sel_hi:[1,1]
	v_pk_mul_f32 v[120:121], v[120:121], v[152:153] op_sel:[0,1] op_sel_hi:[1,1]
	v_add_f32_dpp v190, v190, v190 row_ror:2 row_mask:0xf bank_mask:0xf bound_ctrl:1
	v_pk_mul_f32 v[122:123], v[122:123], v[152:153] op_sel:[0,1] op_sel_hi:[1,1]
	v_pk_mul_f32 v[124:125], v[124:125], v[152:153] op_sel:[0,1] op_sel_hi:[1,1]
	v_add_f32_dpp v190, v190, v190 row_ror:1 row_mask:0xf bank_mask:0xf bound_ctrl:1
	v_pk_mul_f32 v[126:127], v[126:127], v[152:153] op_sel:[0,1] op_sel_hi:[1,1]
	v_pk_fma_f32 v[196:197], v[152:153], v[196:197], v[112:113] op_sel_hi:[0,1,1]
	ds_write_b32 v189, v190 offset:34560
	v_pk_fma_f32 v[198:199], v[152:153], v[198:199], v[114:115] op_sel_hi:[0,1,1]
	v_pk_fma_f32 v[200:201], v[152:153], v[200:201], v[116:117] op_sel_hi:[0,1,1]
	v_pk_fma_f32 v[202:203], v[152:153], v[202:203], v[118:119] op_sel_hi:[0,1,1]
	v_pk_fma_f32 v[204:205], v[152:153], v[204:205], v[120:121] op_sel_hi:[0,1,1]
	v_pk_fma_f32 v[206:207], v[152:153], v[206:207], v[122:123] op_sel_hi:[0,1,1]
	v_pk_fma_f32 v[208:209], v[152:153], v[208:209], v[124:125] op_sel_hi:[0,1,1]
	v_pk_fma_f32 v[210:211], v[152:153], v[210:211], v[126:127] op_sel_hi:[0,1,1]
	s_waitcnt lgkmcnt(15)
	v_pk_fma_f32 v[128:129], v[96:97], v[196:197], v[192:193]
	v_pk_fma_f32 v[130:131], v[98:99], v[198:199], v[192:193]
	s_waitcnt lgkmcnt(14)
	v_pk_fma_f32 v[128:129], v[100:101], v[200:201], v[128:129]
	v_pk_fma_f32 v[130:131], v[102:103], v[202:203], v[130:131]
	s_waitcnt lgkmcnt(13)
	v_pk_fma_f32 v[128:129], v[104:105], v[204:205], v[128:129]
	v_pk_fma_f32 v[130:131], v[106:107], v[206:207], v[130:131]
	s_waitcnt lgkmcnt(12)
	v_pk_fma_f32 v[128:129], v[108:109], v[208:209], v[128:129]
	v_pk_fma_f32 v[130:131], v[110:111], v[210:211], v[130:131]
	v_add_f32_e32 v128, v128, v129
	v_add_f32_e32 v130, v130, v131
	v_add_f32_e32 v191, v128, v130
	ds_read_b128 v[112:115], v188 offset:28288
	ds_read_b128 v[116:119], v188 offset:28544
	ds_read_b128 v[120:123], v188 offset:28800
	ds_read_b128 v[124:127], v188 offset:29056
	ds_read_b32 v154, v140 offset:35148
	ds_read_b32 v155, v189 offset:33600
	ds_read_b32 v152, v140 offset:35084
	ds_read_b128 v[96:99], v188 offset:20096
	ds_read_b128 v[100:103], v188 offset:20352
	ds_read_b128 v[104:107], v188 offset:20608
	ds_read_b128 v[108:111], v188 offset:20864
	s_waitcnt lgkmcnt(15)
	v_mul_f32_e32 v133, v134, v135
	v_pk_mul_f32 v[80:81], v[80:81], v[132:133] op_sel:[0,1] op_sel_hi:[1,1]
	v_add_f32_dpp v191, v191, v191 row_ror:8 row_mask:0xf bank_mask:0xf bound_ctrl:1
	v_pk_mul_f32 v[82:83], v[82:83], v[132:133] op_sel:[0,1] op_sel_hi:[1,1]
	v_pk_mul_f32 v[84:85], v[84:85], v[132:133] op_sel:[0,1] op_sel_hi:[1,1]
	v_add_f32_dpp v191, v191, v191 row_ror:4 row_mask:0xf bank_mask:0xf bound_ctrl:1
	v_pk_mul_f32 v[86:87], v[86:87], v[132:133] op_sel:[0,1] op_sel_hi:[1,1]
	v_pk_mul_f32 v[88:89], v[88:89], v[132:133] op_sel:[0,1] op_sel_hi:[1,1]
	v_add_f32_dpp v191, v191, v191 row_ror:2 row_mask:0xf bank_mask:0xf bound_ctrl:1
	v_pk_mul_f32 v[90:91], v[90:91], v[132:133] op_sel:[0,1] op_sel_hi:[1,1]
	v_pk_mul_f32 v[92:93], v[92:93], v[132:133] op_sel:[0,1] op_sel_hi:[1,1]
	v_add_f32_dpp v191, v191, v191 row_ror:1 row_mask:0xf bank_mask:0xf bound_ctrl:1
	v_pk_mul_f32 v[94:95], v[94:95], v[132:133] op_sel:[0,1] op_sel_hi:[1,1]
	v_pk_fma_f32 v[196:197], v[132:133], v[196:197], v[80:81] op_sel_hi:[0,1,1]
	ds_write_b32 v189, v191 offset:34624
	v_pk_fma_f32 v[198:199], v[132:133], v[198:199], v[82:83] op_sel_hi:[0,1,1]
	v_pk_fma_f32 v[200:201], v[132:133], v[200:201], v[84:85] op_sel_hi:[0,1,1]
	v_pk_fma_f32 v[202:203], v[132:133], v[202:203], v[86:87] op_sel_hi:[0,1,1]
	v_pk_fma_f32 v[204:205], v[132:133], v[204:205], v[88:89] op_sel_hi:[0,1,1]
	v_pk_fma_f32 v[206:207], v[132:133], v[206:207], v[90:91] op_sel_hi:[0,1,1]
	v_pk_fma_f32 v[208:209], v[132:133], v[208:209], v[92:93] op_sel_hi:[0,1,1]
	v_pk_fma_f32 v[210:211], v[132:133], v[210:211], v[94:95] op_sel_hi:[0,1,1]
	s_waitcnt lgkmcnt(15)
	v_pk_fma_f32 v[128:129], v[64:65], v[196:197], v[192:193]
	v_pk_fma_f32 v[130:131], v[66:67], v[198:199], v[192:193]
	v_pk_fma_f32 v[128:129], v[68:69], v[200:201], v[128:129]
	v_pk_fma_f32 v[130:131], v[70:71], v[202:203], v[130:131]
	s_waitcnt lgkmcnt(14)
	v_pk_fma_f32 v[128:129], v[72:73], v[204:205], v[128:129]
	v_pk_fma_f32 v[130:131], v[74:75], v[206:207], v[130:131]
	s_waitcnt lgkmcnt(13)
	v_pk_fma_f32 v[128:129], v[76:77], v[208:209], v[128:129]
	v_pk_fma_f32 v[130:131], v[78:79], v[210:211], v[130:131]
	v_add_f32_e32 v128, v128, v129
	v_add_f32_e32 v130, v130, v131
	v_add_f32_e32 v190, v128, v130
	ds_read_b128 v[80:83], v188 offset:29312
	ds_read_b128 v[84:87], v188 offset:29568
	ds_read_b128 v[88:91], v188 offset:29824
	ds_read_b128 v[92:95], v188 offset:30080
	ds_read_b32 v134, v140 offset:35152
	ds_read_b32 v135, v189 offset:33664
	ds_read_b32 v132, v140 offset:35088
	ds_read_b128 v[64:67], v188 offset:21120
	ds_read_b128 v[68:71], v188 offset:21376
	ds_read_b128 v[72:75], v188 offset:21632
	ds_read_b128 v[76:79], v188 offset:21888
	s_waitcnt lgkmcnt(15)
	v_mul_f32_e32 v153, v154, v155
	v_pk_mul_f32 v[112:113], v[112:113], v[152:153] op_sel:[0,1] op_sel_hi:[1,1]
	v_add_f32_dpp v190, v190, v190 row_ror:8 row_mask:0xf bank_mask:0xf bound_ctrl:1
	v_pk_mul_f32 v[114:115], v[114:115], v[152:153] op_sel:[0,1] op_sel_hi:[1,1]
	v_pk_mul_f32 v[116:117], v[116:117], v[152:153] op_sel:[0,1] op_sel_hi:[1,1]
	v_add_f32_dpp v190, v190, v190 row_ror:4 row_mask:0xf bank_mask:0xf bound_ctrl:1
	v_pk_mul_f32 v[118:119], v[118:119], v[152:153] op_sel:[0,1] op_sel_hi:[1,1]
	v_pk_mul_f32 v[120:121], v[120:121], v[152:153] op_sel:[0,1] op_sel_hi:[1,1]
	v_add_f32_dpp v190, v190, v190 row_ror:2 row_mask:0xf bank_mask:0xf bound_ctrl:1
	v_pk_mul_f32 v[122:123], v[122:123], v[152:153] op_sel:[0,1] op_sel_hi:[1,1]
	v_pk_mul_f32 v[124:125], v[124:125], v[152:153] op_sel:[0,1] op_sel_hi:[1,1]
	v_add_f32_dpp v190, v190, v190 row_ror:1 row_mask:0xf bank_mask:0xf bound_ctrl:1
	v_pk_mul_f32 v[126:127], v[126:127], v[152:153] op_sel:[0,1] op_sel_hi:[1,1]
	v_pk_fma_f32 v[196:197], v[152:153], v[196:197], v[112:113] op_sel_hi:[0,1,1]
	ds_write_b32 v189, v190 offset:34688
	v_pk_fma_f32 v[198:199], v[152:153], v[198:199], v[114:115] op_sel_hi:[0,1,1]
	v_pk_fma_f32 v[200:201], v[152:153], v[200:201], v[116:117] op_sel_hi:[0,1,1]
	v_pk_fma_f32 v[202:203], v[152:153], v[202:203], v[118:119] op_sel_hi:[0,1,1]
	v_pk_fma_f32 v[204:205], v[152:153], v[204:205], v[120:121] op_sel_hi:[0,1,1]
	v_pk_fma_f32 v[206:207], v[152:153], v[206:207], v[122:123] op_sel_hi:[0,1,1]
	v_pk_fma_f32 v[208:209], v[152:153], v[208:209], v[124:125] op_sel_hi:[0,1,1]
	v_pk_fma_f32 v[210:211], v[152:153], v[210:211], v[126:127] op_sel_hi:[0,1,1]
	s_waitcnt lgkmcnt(15)
	v_pk_fma_f32 v[128:129], v[96:97], v[196:197], v[192:193]
	v_pk_fma_f32 v[130:131], v[98:99], v[198:199], v[192:193]
	v_pk_fma_f32 v[128:129], v[100:101], v[200:201], v[128:129]
	v_pk_fma_f32 v[130:131], v[102:103], v[202:203], v[130:131]
	s_waitcnt lgkmcnt(14)
	v_pk_fma_f32 v[128:129], v[104:105], v[204:205], v[128:129]
	v_pk_fma_f32 v[130:131], v[106:107], v[206:207], v[130:131]
	s_waitcnt lgkmcnt(13)
	v_pk_fma_f32 v[128:129], v[108:109], v[208:209], v[128:129]
	v_pk_fma_f32 v[130:131], v[110:111], v[210:211], v[130:131]
	v_add_f32_e32 v128, v128, v129
	v_add_f32_e32 v130, v130, v131
	v_add_f32_e32 v191, v128, v130
	ds_read_b128 v[112:115], v188 offset:30336
	ds_read_b128 v[116:119], v188 offset:30592
	ds_read_b128 v[120:123], v188 offset:30848
	ds_read_b128 v[124:127], v188 offset:31104
	ds_read_b32 v154, v140 offset:35156
	ds_read_b32 v155, v189 offset:33728
	ds_read_b32 v152, v140 offset:35092
	ds_read_b128 v[96:99], v188 offset:22144
	ds_read_b128 v[100:103], v188 offset:22400
	ds_read_b128 v[104:107], v188 offset:22656
	ds_read_b128 v[108:111], v188 offset:22912
	s_waitcnt lgkmcnt(15)
	v_mul_f32_e32 v133, v134, v135
	v_pk_mul_f32 v[80:81], v[80:81], v[132:133] op_sel:[0,1] op_sel_hi:[1,1]
	v_add_f32_dpp v191, v191, v191 row_ror:8 row_mask:0xf bank_mask:0xf bound_ctrl:1
	v_pk_mul_f32 v[82:83], v[82:83], v[132:133] op_sel:[0,1] op_sel_hi:[1,1]
	v_pk_mul_f32 v[84:85], v[84:85], v[132:133] op_sel:[0,1] op_sel_hi:[1,1]
	v_add_f32_dpp v191, v191, v191 row_ror:4 row_mask:0xf bank_mask:0xf bound_ctrl:1
	v_pk_mul_f32 v[86:87], v[86:87], v[132:133] op_sel:[0,1] op_sel_hi:[1,1]
	v_pk_mul_f32 v[88:89], v[88:89], v[132:133] op_sel:[0,1] op_sel_hi:[1,1]
	v_add_f32_dpp v191, v191, v191 row_ror:2 row_mask:0xf bank_mask:0xf bound_ctrl:1
	v_pk_mul_f32 v[90:91], v[90:91], v[132:133] op_sel:[0,1] op_sel_hi:[1,1]
	v_pk_mul_f32 v[92:93], v[92:93], v[132:133] op_sel:[0,1] op_sel_hi:[1,1]
	v_add_f32_dpp v191, v191, v191 row_ror:1 row_mask:0xf bank_mask:0xf bound_ctrl:1
	v_pk_mul_f32 v[94:95], v[94:95], v[132:133] op_sel:[0,1] op_sel_hi:[1,1]
	v_pk_fma_f32 v[196:197], v[132:133], v[196:197], v[80:81] op_sel_hi:[0,1,1]
	ds_write_b32 v189, v191 offset:34752
	v_pk_fma_f32 v[198:199], v[132:133], v[198:199], v[82:83] op_sel_hi:[0,1,1]
	v_pk_fma_f32 v[200:201], v[132:133], v[200:201], v[84:85] op_sel_hi:[0,1,1]
	v_pk_fma_f32 v[202:203], v[132:133], v[202:203], v[86:87] op_sel_hi:[0,1,1]
	v_pk_fma_f32 v[204:205], v[132:133], v[204:205], v[88:89] op_sel_hi:[0,1,1]
	v_pk_fma_f32 v[206:207], v[132:133], v[206:207], v[90:91] op_sel_hi:[0,1,1]
	v_pk_fma_f32 v[208:209], v[132:133], v[208:209], v[92:93] op_sel_hi:[0,1,1]
	v_pk_fma_f32 v[210:211], v[132:133], v[210:211], v[94:95] op_sel_hi:[0,1,1]
	s_waitcnt lgkmcnt(15)
	v_pk_fma_f32 v[128:129], v[64:65], v[196:197], v[192:193]
	v_pk_fma_f32 v[130:131], v[66:67], v[198:199], v[192:193]
	v_pk_fma_f32 v[128:129], v[68:69], v[200:201], v[128:129]
	v_pk_fma_f32 v[130:131], v[70:71], v[202:203], v[130:131]
	s_waitcnt lgkmcnt(14)
	v_pk_fma_f32 v[128:129], v[72:73], v[204:205], v[128:129]
	v_pk_fma_f32 v[130:131], v[74:75], v[206:207], v[130:131]
	s_waitcnt lgkmcnt(13)
	v_pk_fma_f32 v[128:129], v[76:77], v[208:209], v[128:129]
	v_pk_fma_f32 v[130:131], v[78:79], v[210:211], v[130:131]
	v_add_f32_e32 v128, v128, v129
	v_add_f32_e32 v130, v130, v131
	v_add_f32_e32 v190, v128, v130
	ds_read_b128 v[80:83], v188 offset:31360
	ds_read_b128 v[84:87], v188 offset:31616
	ds_read_b128 v[88:91], v188 offset:31872
	ds_read_b128 v[92:95], v188 offset:32128
	ds_read_b32 v134, v140 offset:35160
	ds_read_b32 v135, v189 offset:33792
	ds_read_b32 v132, v140 offset:35096
	ds_read_b128 v[64:67], v188 offset:23168
	ds_read_b128 v[68:71], v188 offset:23424
	ds_read_b128 v[72:75], v188 offset:23680
	ds_read_b128 v[76:79], v188 offset:23936
	s_waitcnt lgkmcnt(15)
	v_mul_f32_e32 v153, v154, v155
	v_pk_mul_f32 v[112:113], v[112:113], v[152:153] op_sel:[0,1] op_sel_hi:[1,1]
	v_add_f32_dpp v190, v190, v190 row_ror:8 row_mask:0xf bank_mask:0xf bound_ctrl:1
	v_pk_mul_f32 v[114:115], v[114:115], v[152:153] op_sel:[0,1] op_sel_hi:[1,1]
	v_pk_mul_f32 v[116:117], v[116:117], v[152:153] op_sel:[0,1] op_sel_hi:[1,1]
	v_add_f32_dpp v190, v190, v190 row_ror:4 row_mask:0xf bank_mask:0xf bound_ctrl:1
	v_pk_mul_f32 v[118:119], v[118:119], v[152:153] op_sel:[0,1] op_sel_hi:[1,1]
	v_pk_mul_f32 v[120:121], v[120:121], v[152:153] op_sel:[0,1] op_sel_hi:[1,1]
	v_add_f32_dpp v190, v190, v190 row_ror:2 row_mask:0xf bank_mask:0xf bound_ctrl:1
	v_pk_mul_f32 v[122:123], v[122:123], v[152:153] op_sel:[0,1] op_sel_hi:[1,1]
	v_pk_mul_f32 v[124:125], v[124:125], v[152:153] op_sel:[0,1] op_sel_hi:[1,1]
	v_add_f32_dpp v190, v190, v190 row_ror:1 row_mask:0xf bank_mask:0xf bound_ctrl:1
	v_pk_mul_f32 v[126:127], v[126:127], v[152:153] op_sel:[0,1] op_sel_hi:[1,1]
	v_pk_fma_f32 v[196:197], v[152:153], v[196:197], v[112:113] op_sel_hi:[0,1,1]
	ds_write_b32 v189, v190 offset:34816
	v_pk_fma_f32 v[198:199], v[152:153], v[198:199], v[114:115] op_sel_hi:[0,1,1]
	v_pk_fma_f32 v[200:201], v[152:153], v[200:201], v[116:117] op_sel_hi:[0,1,1]
	v_pk_fma_f32 v[202:203], v[152:153], v[202:203], v[118:119] op_sel_hi:[0,1,1]
	v_pk_fma_f32 v[204:205], v[152:153], v[204:205], v[120:121] op_sel_hi:[0,1,1]
	v_pk_fma_f32 v[206:207], v[152:153], v[206:207], v[122:123] op_sel_hi:[0,1,1]
	v_pk_fma_f32 v[208:209], v[152:153], v[208:209], v[124:125] op_sel_hi:[0,1,1]
	v_pk_fma_f32 v[210:211], v[152:153], v[210:211], v[126:127] op_sel_hi:[0,1,1]
	s_waitcnt lgkmcnt(15)
	v_pk_fma_f32 v[128:129], v[96:97], v[196:197], v[192:193]
	v_pk_fma_f32 v[130:131], v[98:99], v[198:199], v[192:193]
	v_pk_fma_f32 v[128:129], v[100:101], v[200:201], v[128:129]
	v_pk_fma_f32 v[130:131], v[102:103], v[202:203], v[130:131]
	s_waitcnt lgkmcnt(14)
	v_pk_fma_f32 v[128:129], v[104:105], v[204:205], v[128:129]
	v_pk_fma_f32 v[130:131], v[106:107], v[206:207], v[130:131]
	s_waitcnt lgkmcnt(13)
	v_pk_fma_f32 v[128:129], v[108:109], v[208:209], v[128:129]
	v_pk_fma_f32 v[130:131], v[110:111], v[210:211], v[130:131]
	v_add_f32_e32 v128, v128, v129
	v_add_f32_e32 v130, v130, v131
	v_add_f32_e32 v191, v128, v130
	ds_read_b128 v[112:115], v188 offset:32384
	ds_read_b128 v[116:119], v188 offset:32640
	ds_read_b128 v[120:123], v188 offset:32896
	ds_read_b128 v[124:127], v188 offset:33152
	ds_read_b32 v154, v140 offset:35164
	ds_read_b32 v155, v189 offset:33856
	ds_read_b32 v152, v140 offset:35100
	ds_read_b128 v[96:99], v188 offset:24192
	ds_read_b128 v[100:103], v188 offset:24448
	ds_read_b128 v[104:107], v188 offset:24704
	ds_read_b128 v[108:111], v188 offset:24960
	s_waitcnt lgkmcnt(15)
	v_mul_f32_e32 v133, v134, v135
	v_pk_mul_f32 v[80:81], v[80:81], v[132:133] op_sel:[0,1] op_sel_hi:[1,1]
	v_add_f32_dpp v191, v191, v191 row_ror:8 row_mask:0xf bank_mask:0xf bound_ctrl:1
	v_pk_mul_f32 v[82:83], v[82:83], v[132:133] op_sel:[0,1] op_sel_hi:[1,1]
	v_pk_mul_f32 v[84:85], v[84:85], v[132:133] op_sel:[0,1] op_sel_hi:[1,1]
	v_add_f32_dpp v191, v191, v191 row_ror:4 row_mask:0xf bank_mask:0xf bound_ctrl:1
	v_pk_mul_f32 v[86:87], v[86:87], v[132:133] op_sel:[0,1] op_sel_hi:[1,1]
	v_pk_mul_f32 v[88:89], v[88:89], v[132:133] op_sel:[0,1] op_sel_hi:[1,1]
	v_add_f32_dpp v191, v191, v191 row_ror:2 row_mask:0xf bank_mask:0xf bound_ctrl:1
	v_pk_mul_f32 v[90:91], v[90:91], v[132:133] op_sel:[0,1] op_sel_hi:[1,1]
	v_pk_mul_f32 v[92:93], v[92:93], v[132:133] op_sel:[0,1] op_sel_hi:[1,1]
	v_add_f32_dpp v191, v191, v191 row_ror:1 row_mask:0xf bank_mask:0xf bound_ctrl:1
	v_pk_mul_f32 v[94:95], v[94:95], v[132:133] op_sel:[0,1] op_sel_hi:[1,1]
	v_pk_fma_f32 v[196:197], v[132:133], v[196:197], v[80:81] op_sel_hi:[0,1,1]
	ds_write_b32 v189, v191 offset:34880
	v_pk_fma_f32 v[198:199], v[132:133], v[198:199], v[82:83] op_sel_hi:[0,1,1]
	v_pk_fma_f32 v[200:201], v[132:133], v[200:201], v[84:85] op_sel_hi:[0,1,1]
	v_pk_fma_f32 v[202:203], v[132:133], v[202:203], v[86:87] op_sel_hi:[0,1,1]
	v_pk_fma_f32 v[204:205], v[132:133], v[204:205], v[88:89] op_sel_hi:[0,1,1]
	v_pk_fma_f32 v[206:207], v[132:133], v[206:207], v[90:91] op_sel_hi:[0,1,1]
	v_pk_fma_f32 v[208:209], v[132:133], v[208:209], v[92:93] op_sel_hi:[0,1,1]
	v_pk_fma_f32 v[210:211], v[132:133], v[210:211], v[94:95] op_sel_hi:[0,1,1]
	s_waitcnt lgkmcnt(15)
	v_pk_fma_f32 v[128:129], v[64:65], v[196:197], v[192:193]
	v_pk_fma_f32 v[130:131], v[66:67], v[198:199], v[192:193]
	v_pk_fma_f32 v[128:129], v[68:69], v[200:201], v[128:129]
	v_pk_fma_f32 v[130:131], v[70:71], v[202:203], v[130:131]
	s_waitcnt lgkmcnt(14)
	v_pk_fma_f32 v[128:129], v[72:73], v[204:205], v[128:129]
	v_pk_fma_f32 v[130:131], v[74:75], v[206:207], v[130:131]
	s_waitcnt lgkmcnt(13)
	v_pk_fma_f32 v[128:129], v[76:77], v[208:209], v[128:129]
	v_pk_fma_f32 v[130:131], v[78:79], v[210:211], v[130:131]
	v_add_f32_e32 v128, v128, v129
	v_add_f32_e32 v130, v130, v131
	v_add_f32_e32 v190, v128, v130
	s_waitcnt lgkmcnt(6)
	v_mul_f32_e32 v153, v154, v155
	v_pk_mul_f32 v[112:113], v[112:113], v[152:153] op_sel:[0,1] op_sel_hi:[1,1]
	v_add_f32_dpp v190, v190, v190 row_ror:8 row_mask:0xf bank_mask:0xf bound_ctrl:1
	v_pk_mul_f32 v[114:115], v[114:115], v[152:153] op_sel:[0,1] op_sel_hi:[1,1]
	v_pk_mul_f32 v[116:117], v[116:117], v[152:153] op_sel:[0,1] op_sel_hi:[1,1]
	v_add_f32_dpp v190, v190, v190 row_ror:4 row_mask:0xf bank_mask:0xf bound_ctrl:1
	v_pk_mul_f32 v[118:119], v[118:119], v[152:153] op_sel:[0,1] op_sel_hi:[1,1]
	v_pk_mul_f32 v[120:121], v[120:121], v[152:153] op_sel:[0,1] op_sel_hi:[1,1]
	v_add_f32_dpp v190, v190, v190 row_ror:2 row_mask:0xf bank_mask:0xf bound_ctrl:1
	v_pk_mul_f32 v[122:123], v[122:123], v[152:153] op_sel:[0,1] op_sel_hi:[1,1]
	v_pk_mul_f32 v[124:125], v[124:125], v[152:153] op_sel:[0,1] op_sel_hi:[1,1]
	v_add_f32_dpp v190, v190, v190 row_ror:1 row_mask:0xf bank_mask:0xf bound_ctrl:1
	v_pk_mul_f32 v[126:127], v[126:127], v[152:153] op_sel:[0,1] op_sel_hi:[1,1]
	s_waitcnt lgkmcnt(5)
	v_pk_fma_f32 v[196:197], v[152:153], v[196:197], v[112:113] op_sel_hi:[0,1,1]
	ds_write_b32 v189, v190 offset:34944
	v_pk_fma_f32 v[198:199], v[152:153], v[198:199], v[114:115] op_sel_hi:[0,1,1]
	v_pk_fma_f32 v[200:201], v[152:153], v[200:201], v[116:117] op_sel_hi:[0,1,1]
	v_pk_fma_f32 v[202:203], v[152:153], v[202:203], v[118:119] op_sel_hi:[0,1,1]
	v_pk_fma_f32 v[204:205], v[152:153], v[204:205], v[120:121] op_sel_hi:[0,1,1]
	v_pk_fma_f32 v[206:207], v[152:153], v[206:207], v[122:123] op_sel_hi:[0,1,1]
	v_pk_fma_f32 v[208:209], v[152:153], v[208:209], v[124:125] op_sel_hi:[0,1,1]
	v_pk_fma_f32 v[210:211], v[152:153], v[210:211], v[126:127] op_sel_hi:[0,1,1]
	s_waitcnt lgkmcnt(5)
	v_pk_fma_f32 v[128:129], v[96:97], v[196:197], v[192:193]
	v_pk_fma_f32 v[130:131], v[98:99], v[198:199], v[192:193]
	s_waitcnt lgkmcnt(4)
	v_pk_fma_f32 v[128:129], v[100:101], v[200:201], v[128:129]
	v_pk_fma_f32 v[130:131], v[102:103], v[202:203], v[130:131]
	s_waitcnt lgkmcnt(3)
	v_pk_fma_f32 v[128:129], v[104:105], v[204:205], v[128:129]
	v_pk_fma_f32 v[130:131], v[106:107], v[206:207], v[130:131]
	s_waitcnt lgkmcnt(2)
	v_pk_fma_f32 v[128:129], v[108:109], v[208:209], v[128:129]
	v_pk_fma_f32 v[130:131], v[110:111], v[210:211], v[130:131]
	v_add_f32_e32 v128, v128, v129
	v_add_f32_e32 v130, v130, v131
	v_add_f32_e32 v191, v128, v130
	s_nop 1
	v_add_f32_dpp v191, v191, v191 row_ror:8 row_mask:0xf bank_mask:0xf bound_ctrl:1
	s_nop 1
	v_add_f32_dpp v191, v191, v191 row_ror:4 row_mask:0xf bank_mask:0xf bound_ctrl:1
	s_nop 1
	v_add_f32_dpp v191, v191, v191 row_ror:2 row_mask:0xf bank_mask:0xf bound_ctrl:1
	s_nop 1
	v_add_f32_dpp v191, v191, v191 row_ror:1 row_mask:0xf bank_mask:0xf bound_ctrl:1
	ds_write_b32 v189, v191 offset:35008
	s_waitcnt lgkmcnt(0)
	v_mov_b32_e32 v64, v196
	v_mov_b32_e32 v65, v197
	v_mov_b32_e32 v66, v198
	v_mov_b32_e32 v67, v199
	v_mov_b32_e32 v76, v200
	v_mov_b32_e32 v77, v201
	v_mov_b32_e32 v78, v202
	v_mov_b32_e32 v79, v203
	v_mov_b32_e32 v72, v204
	v_mov_b32_e32 v73, v205
	v_mov_b32_e32 v74, v206
	v_mov_b32_e32 v75, v207
	v_mov_b32_e32 v68, v208
	v_mov_b32_e32 v69, v209
	v_mov_b32_e32 v70, v210
	v_mov_b32_e32 v71, v211
	s_branch .LBB0_1438
